# plus: non-temporal hint on P1 epilogue stores (write-once outputs and streamed bf16 intermediates) and P4 y stores
# speedup vs baseline: 1.1833x; 1.0215x over previous
.LBB0_205:
	v_mov_b32_e32 v128, v132
	s_mov_b64 s[8:9], -1
	v_ashrrev_i32_e32 v130, 1, v128
	v_and_b32_e32 v129, 0xc0, v128
	v_and_b32_e32 v130, 0xffffff80, v130
	v_and_b32_e32 v210, 63, v128
	v_add_u32_e32 v211, s78, v130
	v_or_b32_e32 v212, s94, v129
	s_and_b64 vcc, exec, s[92:93]
	s_cbranch_vccz .LBB0_263
	s_and_b64 vcc, exec, s[0:1]
	s_cbranch_vccz .LBB0_208
	s_movk_i32 s0, 0xff
	v_mov_b32_e32 v130, s29
	v_mov_b32_e32 v131, s31
	v_cmp_lt_i32_e32 vcc, s0, v212
	v_mov_b32_e32 v134, s30
	s_nop 0
	v_cndmask_b32_e32 v131, v130, v131, vcc
	v_mov_b32_e32 v130, s28
	v_cndmask_b32_e32 v130, v130, v134, vcc
	v_cndmask_b32_e32 v134, v250, v251, vcc
	v_lshl_add_u64 v[138:139], s[4:5], 0, v[134:135]
	v_lshlrev_b32_e32 v134, 2, v128
	v_and_or_b32 v129, v134, 60, v129
	v_lshlrev_b32_e32 v134, 1, v129
	v_lshrrev_b32_e32 v128, 2, v128
	v_lshl_add_u64 v[130:131], v[130:131], 0, v[134:135]
	v_lshlrev_b32_e32 v134, 2, v129
	v_and_or_b32 v136, v128, 12, v211
	v_lshl_add_u64 v[128:129], v[138:139], 0, v[134:135]
	v_ashrrev_i32_e32 v137, 31, v136
	v_lshlrev_b64 v[138:139], 9, v[136:137]
	v_lshl_add_u64 v[138:139], v[130:131], 0, v[138:139]
	v_cvt_pk_bf16_f32 v140, v124, v120
	v_cvt_pk_bf16_f32 v141, v116, v112
	global_store_dwordx2 v[138:139], v[140:141], off nt
	v_lshlrev_b64 v[138:139], 10, v[136:137]
	v_lshl_add_u64 v[142:143], v[128:129], 0, v[138:139]
	v_mov_b32_e32 v138, v124
	v_mov_b32_e32 v139, v120
	v_mov_b32_e32 v140, v116
	v_mov_b32_e32 v141, v112
	global_store_dwordx4 v[142:143], v[138:141], off nt
	s_nop 1
	v_or_b32_e32 v138, 1, v136
	v_ashrrev_i32_e32 v139, 31, v138
	v_lshlrev_b64 v[140:141], 9, v[138:139]
	v_lshl_add_u64 v[140:141], v[130:131], 0, v[140:141]
	v_cvt_pk_bf16_f32 v142, v125, v121
	v_cvt_pk_bf16_f32 v143, v117, v113
	v_lshlrev_b64 v[138:139], 10, v[138:139]
	global_store_dwordx2 v[140:141], v[142:143], off nt
	v_lshl_add_u64 v[142:143], v[128:129], 0, v[138:139]
	v_mov_b32_e32 v138, v125
	v_mov_b32_e32 v139, v121
	v_mov_b32_e32 v140, v117
	v_mov_b32_e32 v141, v113
	global_store_dwordx4 v[142:143], v[138:141], off nt
	s_nop 1
	v_or_b32_e32 v138, 2, v136
	v_ashrrev_i32_e32 v139, 31, v138
	v_lshlrev_b64 v[140:141], 9, v[138:139]
	v_lshl_add_u64 v[140:141], v[130:131], 0, v[140:141]
	v_cvt_pk_bf16_f32 v142, v126, v122
	v_cvt_pk_bf16_f32 v143, v118, v114
	v_lshlrev_b64 v[138:139], 10, v[138:139]
	global_store_dwordx2 v[140:141], v[142:143], off nt
	v_lshl_add_u64 v[142:143], v[128:129], 0, v[138:139]
	v_mov_b32_e32 v138, v126
	v_mov_b32_e32 v139, v122
	v_mov_b32_e32 v140, v118
	v_mov_b32_e32 v141, v114
	global_store_dwordx4 v[142:143], v[138:141], off nt
	s_nop 1
	v_or_b32_e32 v138, 3, v136
	v_ashrrev_i32_e32 v139, 31, v138
	v_lshlrev_b64 v[140:141], 9, v[138:139]
	v_lshl_add_u64 v[140:141], v[130:131], 0, v[140:141]
	v_cvt_pk_bf16_f32 v142, v127, v123
	v_cvt_pk_bf16_f32 v143, v119, v115
	v_lshlrev_b64 v[138:139], 10, v[138:139]
	global_store_dwordx2 v[140:141], v[142:143], off nt
	v_lshl_add_u64 v[142:143], v[128:129], 0, v[138:139]
	v_mov_b32_e32 v138, v127
	v_mov_b32_e32 v139, v123
	v_mov_b32_e32 v140, v119
	v_mov_b32_e32 v141, v115
	global_store_dwordx4 v[142:143], v[138:141], off nt
	s_nop 1
	v_or_b32_e32 v138, 16, v136
	v_ashrrev_i32_e32 v139, 31, v138
	v_lshlrev_b64 v[140:141], 9, v[138:139]
	v_lshl_add_u64 v[140:141], v[130:131], 0, v[140:141]
	v_cvt_pk_bf16_f32 v142, v108, v104
	v_cvt_pk_bf16_f32 v143, v100, v96
	v_lshlrev_b64 v[138:139], 10, v[138:139]
	global_store_dwordx2 v[140:141], v[142:143], off nt
	v_lshl_add_u64 v[142:143], v[128:129], 0, v[138:139]
	v_mov_b32_e32 v138, v108
	v_mov_b32_e32 v139, v104
	v_mov_b32_e32 v140, v100
	v_mov_b32_e32 v141, v96
	global_store_dwordx4 v[142:143], v[138:141], off nt
	s_nop 1
	v_or_b32_e32 v138, 17, v136
	v_ashrrev_i32_e32 v139, 31, v138
	v_lshlrev_b64 v[140:141], 9, v[138:139]
	v_lshl_add_u64 v[140:141], v[130:131], 0, v[140:141]
	v_cvt_pk_bf16_f32 v142, v109, v105
	v_cvt_pk_bf16_f32 v143, v101, v97
	v_lshlrev_b64 v[138:139], 10, v[138:139]
	global_store_dwordx2 v[140:141], v[142:143], off nt
	v_lshl_add_u64 v[142:143], v[128:129], 0, v[138:139]
	v_mov_b32_e32 v138, v109
	v_mov_b32_e32 v139, v105
	v_mov_b32_e32 v140, v101
	v_mov_b32_e32 v141, v97
	global_store_dwordx4 v[142:143], v[138:141], off nt
	s_nop 1
	v_or_b32_e32 v138, 18, v136
	v_ashrrev_i32_e32 v139, 31, v138
	v_lshlrev_b64 v[140:141], 9, v[138:139]
	v_lshl_add_u64 v[140:141], v[130:131], 0, v[140:141]
	v_cvt_pk_bf16_f32 v142, v110, v106
	v_cvt_pk_bf16_f32 v143, v102, v98
	v_lshlrev_b64 v[138:139], 10, v[138:139]
	global_store_dwordx2 v[140:141], v[142:143], off nt
	v_lshl_add_u64 v[142:143], v[128:129], 0, v[138:139]
	v_mov_b32_e32 v138, v110
	v_mov_b32_e32 v139, v106
	v_mov_b32_e32 v140, v102
	v_mov_b32_e32 v141, v98
	global_store_dwordx4 v[142:143], v[138:141], off nt
	s_nop 1
	v_or_b32_e32 v138, 19, v136
	v_ashrrev_i32_e32 v139, 31, v138
	v_lshlrev_b64 v[140:141], 9, v[138:139]
	v_lshl_add_u64 v[140:141], v[130:131], 0, v[140:141]
	v_cvt_pk_bf16_f32 v142, v111, v107
	v_cvt_pk_bf16_f32 v143, v103, v99
	v_lshlrev_b64 v[138:139], 10, v[138:139]
	global_store_dwordx2 v[140:141], v[142:143], off nt
	v_lshl_add_u64 v[142:143], v[128:129], 0, v[138:139]
	v_mov_b32_e32 v138, v111
	v_mov_b32_e32 v139, v107
	v_mov_b32_e32 v140, v103
	v_mov_b32_e32 v141, v99
	global_store_dwordx4 v[142:143], v[138:141], off nt
	s_nop 1
	v_or_b32_e32 v138, 32, v136
	v_ashrrev_i32_e32 v139, 31, v138
	v_lshlrev_b64 v[140:141], 9, v[138:139]
	v_lshl_add_u64 v[140:141], v[130:131], 0, v[140:141]
	v_cvt_pk_bf16_f32 v142, v92, v88
	v_cvt_pk_bf16_f32 v143, v84, v80
	v_lshlrev_b64 v[138:139], 10, v[138:139]
	global_store_dwordx2 v[140:141], v[142:143], off nt
	v_lshl_add_u64 v[142:143], v[128:129], 0, v[138:139]
	v_mov_b32_e32 v138, v92
	v_mov_b32_e32 v139, v88
	v_mov_b32_e32 v140, v84
	v_mov_b32_e32 v141, v80
	global_store_dwordx4 v[142:143], v[138:141], off nt
	s_nop 1
	v_or_b32_e32 v138, 33, v136
	v_ashrrev_i32_e32 v139, 31, v138
	v_lshlrev_b64 v[140:141], 9, v[138:139]
	v_lshl_add_u64 v[140:141], v[130:131], 0, v[140:141]
	v_cvt_pk_bf16_f32 v142, v93, v89
	v_cvt_pk_bf16_f32 v143, v85, v81
	v_lshlrev_b64 v[138:139], 10, v[138:139]
	global_store_dwordx2 v[140:141], v[142:143], off nt
	v_lshl_add_u64 v[142:143], v[128:129], 0, v[138:139]
	v_mov_b32_e32 v138, v93
	v_mov_b32_e32 v139, v89
	v_mov_b32_e32 v140, v85
	v_mov_b32_e32 v141, v81
	global_store_dwordx4 v[142:143], v[138:141], off nt
	s_nop 1
	v_or_b32_e32 v138, 34, v136
	v_ashrrev_i32_e32 v139, 31, v138
	v_lshlrev_b64 v[140:141], 9, v[138:139]
	v_lshl_add_u64 v[140:141], v[130:131], 0, v[140:141]
	v_cvt_pk_bf16_f32 v142, v94, v90
	v_cvt_pk_bf16_f32 v143, v86, v82
	v_lshlrev_b64 v[138:139], 10, v[138:139]
	global_store_dwordx2 v[140:141], v[142:143], off nt
	v_lshl_add_u64 v[142:143], v[128:129], 0, v[138:139]
	v_mov_b32_e32 v138, v94
	v_mov_b32_e32 v139, v90
	v_mov_b32_e32 v140, v86
	v_mov_b32_e32 v141, v82
	global_store_dwordx4 v[142:143], v[138:141], off nt
	s_nop 1
	v_or_b32_e32 v138, 35, v136
	v_ashrrev_i32_e32 v139, 31, v138
	v_lshlrev_b64 v[140:141], 9, v[138:139]
	v_lshl_add_u64 v[140:141], v[130:131], 0, v[140:141]
	v_cvt_pk_bf16_f32 v142, v95, v91
	v_cvt_pk_bf16_f32 v143, v87, v83
	v_lshlrev_b64 v[138:139], 10, v[138:139]
	global_store_dwordx2 v[140:141], v[142:143], off nt
	v_lshl_add_u64 v[142:143], v[128:129], 0, v[138:139]
	v_mov_b32_e32 v138, v95
	v_mov_b32_e32 v139, v91
	v_mov_b32_e32 v140, v87
	v_mov_b32_e32 v141, v83
	global_store_dwordx4 v[142:143], v[138:141], off nt
	s_nop 1
	v_or_b32_e32 v138, 48, v136
	v_ashrrev_i32_e32 v139, 31, v138
	v_lshlrev_b64 v[140:141], 9, v[138:139]
	v_lshl_add_u64 v[140:141], v[130:131], 0, v[140:141]
	v_cvt_pk_bf16_f32 v142, v76, v72
	v_cvt_pk_bf16_f32 v143, v68, v64
	v_lshlrev_b64 v[138:139], 10, v[138:139]
	global_store_dwordx2 v[140:141], v[142:143], off nt
	v_lshl_add_u64 v[142:143], v[128:129], 0, v[138:139]
	v_mov_b32_e32 v138, v76
	v_mov_b32_e32 v139, v72
	v_mov_b32_e32 v140, v68
	v_mov_b32_e32 v141, v64
	global_store_dwordx4 v[142:143], v[138:141], off nt
	s_nop 1
	v_or_b32_e32 v138, 49, v136
	v_ashrrev_i32_e32 v139, 31, v138
	v_lshlrev_b64 v[140:141], 9, v[138:139]
	v_lshl_add_u64 v[140:141], v[130:131], 0, v[140:141]
	v_cvt_pk_bf16_f32 v142, v77, v73
	v_cvt_pk_bf16_f32 v143, v69, v65
	v_lshlrev_b64 v[138:139], 10, v[138:139]
	global_store_dwordx2 v[140:141], v[142:143], off nt
	v_lshl_add_u64 v[142:143], v[128:129], 0, v[138:139]
	v_mov_b32_e32 v138, v77
	v_mov_b32_e32 v139, v73
	v_mov_b32_e32 v140, v69
	v_mov_b32_e32 v141, v65
	global_store_dwordx4 v[142:143], v[138:141], off nt
	s_nop 1
	v_or_b32_e32 v138, 50, v136
	v_ashrrev_i32_e32 v139, 31, v138
	v_lshlrev_b64 v[140:141], 9, v[138:139]
	v_lshl_add_u64 v[140:141], v[130:131], 0, v[140:141]
	v_cvt_pk_bf16_f32 v142, v78, v74
	v_cvt_pk_bf16_f32 v143, v70, v66
	v_lshlrev_b64 v[138:139], 10, v[138:139]
	global_store_dwordx2 v[140:141], v[142:143], off nt
	v_lshl_add_u64 v[142:143], v[128:129], 0, v[138:139]
	v_mov_b32_e32 v138, v78
	v_mov_b32_e32 v139, v74
	v_mov_b32_e32 v140, v70
	v_mov_b32_e32 v141, v66
	global_store_dwordx4 v[142:143], v[138:141], off nt
	s_nop 1
	v_or_b32_e32 v138, 51, v136
	v_ashrrev_i32_e32 v139, 31, v138
	v_lshlrev_b64 v[140:141], 9, v[138:139]
	v_lshl_add_u64 v[140:141], v[130:131], 0, v[140:141]
	v_cvt_pk_bf16_f32 v142, v79, v75
	v_cvt_pk_bf16_f32 v143, v71, v67
	v_lshlrev_b64 v[138:139], 10, v[138:139]
	global_store_dwordx2 v[140:141], v[142:143], off nt
	v_lshl_add_u64 v[142:143], v[128:129], 0, v[138:139]
	v_mov_b32_e32 v138, v79
	v_mov_b32_e32 v139, v75
	v_mov_b32_e32 v140, v71
	v_mov_b32_e32 v141, v67
	global_store_dwordx4 v[142:143], v[138:141], off nt
	s_nop 1
	v_or_b32_e32 v138, 64, v136
	v_ashrrev_i32_e32 v139, 31, v138
	v_lshlrev_b64 v[140:141], 9, v[138:139]
	v_lshl_add_u64 v[140:141], v[130:131], 0, v[140:141]
	v_cvt_pk_bf16_f32 v142, v60, v56
	v_cvt_pk_bf16_f32 v143, v52, v48
	v_lshlrev_b64 v[138:139], 10, v[138:139]
	global_store_dwordx2 v[140:141], v[142:143], off nt
	v_lshl_add_u64 v[142:143], v[128:129], 0, v[138:139]
	v_mov_b32_e32 v138, v60
	v_mov_b32_e32 v139, v56
	v_mov_b32_e32 v140, v52
	v_mov_b32_e32 v141, v48
	global_store_dwordx4 v[142:143], v[138:141], off nt
	s_nop 1
	v_or_b32_e32 v138, 0x41, v136
	v_ashrrev_i32_e32 v139, 31, v138
	v_lshlrev_b64 v[140:141], 9, v[138:139]
	v_lshl_add_u64 v[140:141], v[130:131], 0, v[140:141]
	v_cvt_pk_bf16_f32 v142, v61, v57
	v_cvt_pk_bf16_f32 v143, v53, v49
	v_lshlrev_b64 v[138:139], 10, v[138:139]
	global_store_dwordx2 v[140:141], v[142:143], off nt
	v_lshl_add_u64 v[142:143], v[128:129], 0, v[138:139]
	v_mov_b32_e32 v138, v61
	v_mov_b32_e32 v139, v57
	v_mov_b32_e32 v140, v53
	v_mov_b32_e32 v141, v49
	global_store_dwordx4 v[142:143], v[138:141], off nt
	s_nop 1
	v_or_b32_e32 v138, 0x42, v136
	v_ashrrev_i32_e32 v139, 31, v138
	v_lshlrev_b64 v[140:141], 9, v[138:139]
	v_lshl_add_u64 v[140:141], v[130:131], 0, v[140:141]
	v_cvt_pk_bf16_f32 v142, v62, v58
	v_cvt_pk_bf16_f32 v143, v54, v50
	v_lshlrev_b64 v[138:139], 10, v[138:139]
	global_store_dwordx2 v[140:141], v[142:143], off nt
	v_lshl_add_u64 v[142:143], v[128:129], 0, v[138:139]
	v_mov_b32_e32 v138, v62
	v_mov_b32_e32 v139, v58
	v_mov_b32_e32 v140, v54
	v_mov_b32_e32 v141, v50
	global_store_dwordx4 v[142:143], v[138:141], off nt
	s_nop 1
	v_or_b32_e32 v138, 0x43, v136
	v_ashrrev_i32_e32 v139, 31, v138
	v_lshlrev_b64 v[140:141], 9, v[138:139]
	v_lshl_add_u64 v[140:141], v[130:131], 0, v[140:141]
	v_cvt_pk_bf16_f32 v142, v63, v59
	v_cvt_pk_bf16_f32 v143, v55, v51
	v_lshlrev_b64 v[138:139], 10, v[138:139]
	global_store_dwordx2 v[140:141], v[142:143], off nt
	v_lshl_add_u64 v[142:143], v[128:129], 0, v[138:139]
	v_mov_b32_e32 v138, v63
	v_mov_b32_e32 v139, v59
	v_mov_b32_e32 v140, v55
	v_mov_b32_e32 v141, v51
	global_store_dwordx4 v[142:143], v[138:141], off nt
	s_nop 1
	v_or_b32_e32 v138, 0x50, v136
	v_ashrrev_i32_e32 v139, 31, v138
	v_lshlrev_b64 v[140:141], 9, v[138:139]
	v_lshl_add_u64 v[140:141], v[130:131], 0, v[140:141]
	v_cvt_pk_bf16_f32 v142, v44, v40
	v_cvt_pk_bf16_f32 v143, v36, v32
	v_lshlrev_b64 v[138:139], 10, v[138:139]
	global_store_dwordx2 v[140:141], v[142:143], off nt
	v_lshl_add_u64 v[142:143], v[128:129], 0, v[138:139]
	v_mov_b32_e32 v138, v44
	v_mov_b32_e32 v139, v40
	v_mov_b32_e32 v140, v36
	v_mov_b32_e32 v141, v32
	global_store_dwordx4 v[142:143], v[138:141], off nt
	s_nop 1
	v_or_b32_e32 v138, 0x51, v136
	v_ashrrev_i32_e32 v139, 31, v138
	v_lshlrev_b64 v[140:141], 9, v[138:139]
	v_lshl_add_u64 v[140:141], v[130:131], 0, v[140:141]
	v_cvt_pk_bf16_f32 v142, v45, v41
	v_cvt_pk_bf16_f32 v143, v37, v33
	v_lshlrev_b64 v[138:139], 10, v[138:139]
	global_store_dwordx2 v[140:141], v[142:143], off nt
	v_lshl_add_u64 v[142:143], v[128:129], 0, v[138:139]
	v_mov_b32_e32 v138, v45
	v_mov_b32_e32 v139, v41
	v_mov_b32_e32 v140, v37
	v_mov_b32_e32 v141, v33
	global_store_dwordx4 v[142:143], v[138:141], off nt
	s_nop 1
	v_or_b32_e32 v138, 0x52, v136
	v_ashrrev_i32_e32 v139, 31, v138
	v_lshlrev_b64 v[140:141], 9, v[138:139]
	v_lshl_add_u64 v[140:141], v[130:131], 0, v[140:141]
	v_cvt_pk_bf16_f32 v142, v46, v42
	v_cvt_pk_bf16_f32 v143, v38, v34
	v_lshlrev_b64 v[138:139], 10, v[138:139]
	global_store_dwordx2 v[140:141], v[142:143], off nt
	v_lshl_add_u64 v[142:143], v[128:129], 0, v[138:139]
	v_mov_b32_e32 v138, v46
	v_mov_b32_e32 v139, v42
	v_mov_b32_e32 v140, v38
	v_mov_b32_e32 v141, v34
	global_store_dwordx4 v[142:143], v[138:141], off nt
	s_nop 1
	v_or_b32_e32 v138, 0x53, v136
	v_ashrrev_i32_e32 v139, 31, v138
	v_lshlrev_b64 v[140:141], 9, v[138:139]
	v_lshl_add_u64 v[140:141], v[130:131], 0, v[140:141]
	v_cvt_pk_bf16_f32 v142, v47, v43
	v_cvt_pk_bf16_f32 v143, v39, v35
	v_lshlrev_b64 v[138:139], 10, v[138:139]
	global_store_dwordx2 v[140:141], v[142:143], off nt
	v_lshl_add_u64 v[142:143], v[128:129], 0, v[138:139]
	v_mov_b32_e32 v138, v47
	v_mov_b32_e32 v139, v43
	v_mov_b32_e32 v140, v39
	v_mov_b32_e32 v141, v35
	global_store_dwordx4 v[142:143], v[138:141], off nt
	s_nop 1
	v_or_b32_e32 v138, 0x60, v136
	v_ashrrev_i32_e32 v139, 31, v138
	v_lshlrev_b64 v[140:141], 9, v[138:139]
	v_lshl_add_u64 v[140:141], v[130:131], 0, v[140:141]
	v_cvt_pk_bf16_f32 v142, v28, v24
	v_cvt_pk_bf16_f32 v143, v20, v16
	v_lshlrev_b64 v[138:139], 10, v[138:139]
	global_store_dwordx2 v[140:141], v[142:143], off nt
	v_lshl_add_u64 v[142:143], v[128:129], 0, v[138:139]
	v_mov_b32_e32 v138, v28
	v_mov_b32_e32 v139, v24
	v_mov_b32_e32 v140, v20
	v_mov_b32_e32 v141, v16
	global_store_dwordx4 v[142:143], v[138:141], off nt
	s_nop 1
	v_or_b32_e32 v138, 0x61, v136
	v_ashrrev_i32_e32 v139, 31, v138
	v_lshlrev_b64 v[140:141], 9, v[138:139]
	v_lshl_add_u64 v[140:141], v[130:131], 0, v[140:141]
	v_cvt_pk_bf16_f32 v142, v29, v25
	v_cvt_pk_bf16_f32 v143, v21, v17
	v_lshlrev_b64 v[138:139], 10, v[138:139]
	global_store_dwordx2 v[140:141], v[142:143], off nt
	v_lshl_add_u64 v[142:143], v[128:129], 0, v[138:139]
	v_mov_b32_e32 v138, v29
	v_mov_b32_e32 v139, v25
	v_mov_b32_e32 v140, v21
	v_mov_b32_e32 v141, v17
	global_store_dwordx4 v[142:143], v[138:141], off nt
	s_nop 1
	v_or_b32_e32 v138, 0x62, v136
	v_ashrrev_i32_e32 v139, 31, v138
	v_lshlrev_b64 v[140:141], 9, v[138:139]
	v_lshl_add_u64 v[140:141], v[130:131], 0, v[140:141]
	v_cvt_pk_bf16_f32 v142, v30, v26
	v_cvt_pk_bf16_f32 v143, v22, v18
	v_lshlrev_b64 v[138:139], 10, v[138:139]
	global_store_dwordx2 v[140:141], v[142:143], off nt
	v_lshl_add_u64 v[142:143], v[128:129], 0, v[138:139]
	v_mov_b32_e32 v138, v30
	v_mov_b32_e32 v139, v26
	v_mov_b32_e32 v140, v22
	v_mov_b32_e32 v141, v18
	global_store_dwordx4 v[142:143], v[138:141], off nt
	s_nop 1
	v_or_b32_e32 v138, 0x63, v136
	v_ashrrev_i32_e32 v139, 31, v138
	v_lshlrev_b64 v[140:141], 9, v[138:139]
	v_lshl_add_u64 v[140:141], v[130:131], 0, v[140:141]
	v_cvt_pk_bf16_f32 v142, v31, v27
	v_cvt_pk_bf16_f32 v143, v23, v19
	v_lshlrev_b64 v[138:139], 10, v[138:139]
	global_store_dwordx2 v[140:141], v[142:143], off nt
	v_lshl_add_u64 v[142:143], v[128:129], 0, v[138:139]
	v_mov_b32_e32 v138, v31
	v_mov_b32_e32 v139, v27
	v_mov_b32_e32 v140, v23
	v_mov_b32_e32 v141, v19
	global_store_dwordx4 v[142:143], v[138:141], off nt
	s_nop 1
	v_or_b32_e32 v138, 0x70, v136
	v_ashrrev_i32_e32 v139, 31, v138
	v_lshlrev_b64 v[140:141], 9, v[138:139]
	v_lshl_add_u64 v[140:141], v[130:131], 0, v[140:141]
	v_cvt_pk_bf16_f32 v142, v12, v8
	v_cvt_pk_bf16_f32 v143, v4, v0
	v_lshlrev_b64 v[138:139], 10, v[138:139]
	global_store_dwordx2 v[140:141], v[142:143], off nt
	v_lshl_add_u64 v[142:143], v[128:129], 0, v[138:139]
	v_mov_b32_e32 v138, v12
	v_mov_b32_e32 v139, v8
	v_mov_b32_e32 v140, v4
	v_mov_b32_e32 v141, v0
	global_store_dwordx4 v[142:143], v[138:141], off nt
	s_nop 1
	v_or_b32_e32 v138, 0x71, v136
	v_ashrrev_i32_e32 v139, 31, v138
	v_lshlrev_b64 v[140:141], 9, v[138:139]
	v_lshl_add_u64 v[140:141], v[130:131], 0, v[140:141]
	v_cvt_pk_bf16_f32 v142, v13, v9
	v_cvt_pk_bf16_f32 v143, v5, v1
	v_lshlrev_b64 v[138:139], 10, v[138:139]
	global_store_dwordx2 v[140:141], v[142:143], off nt
	v_lshl_add_u64 v[142:143], v[128:129], 0, v[138:139]
	v_mov_b32_e32 v138, v13
	v_mov_b32_e32 v139, v9
	v_mov_b32_e32 v140, v5
	v_mov_b32_e32 v141, v1
	global_store_dwordx4 v[142:143], v[138:141], off nt
	s_nop 1
	v_or_b32_e32 v138, 0x72, v136
	v_ashrrev_i32_e32 v139, 31, v138
	v_lshlrev_b64 v[140:141], 9, v[138:139]
	v_lshl_add_u64 v[140:141], v[130:131], 0, v[140:141]
	v_cvt_pk_bf16_f32 v142, v14, v10
	v_cvt_pk_bf16_f32 v143, v6, v2
	v_lshlrev_b64 v[138:139], 10, v[138:139]
	global_store_dwordx2 v[140:141], v[142:143], off nt
	v_lshl_add_u64 v[142:143], v[128:129], 0, v[138:139]
	v_mov_b32_e32 v138, v14
	v_mov_b32_e32 v139, v10
	v_mov_b32_e32 v140, v6
	v_mov_b32_e32 v141, v2
	global_store_dwordx4 v[142:143], v[138:141], off nt
	v_or_b32_e32 v136, 0x73, v136
	v_ashrrev_i32_e32 v137, 31, v136
	v_lshlrev_b64 v[138:139], 9, v[136:137]
	v_lshl_add_u64 v[130:131], v[130:131], 0, v[138:139]
	v_cvt_pk_bf16_f32 v138, v15, v11
	v_cvt_pk_bf16_f32 v139, v7, v3
	global_store_dwordx2 v[130:131], v[138:139], off nt
	v_lshlrev_b64 v[130:131], 10, v[136:137]
	v_lshl_add_u64 v[136:137], v[128:129], 0, v[130:131]
	v_mov_b32_e32 v128, v15
	v_mov_b32_e32 v129, v11
	v_mov_b32_e32 v130, v7
	v_mov_b32_e32 v131, v3
	global_store_dwordx4 v[136:137], v[128:131], off nt
	s_mov_b64 s[8:9], 0

.LBB0_220:
	s_or_saveexec_b64 s[0:1], s[0:1]
	v_mov_b32_e32 v177, s10
	s_xor_b64 exec, exec, s[0:1]
	s_mov_b32 s8, 0x2aaaaaab
	v_mul_hi_i32 v128, v212, s8
	v_lshrrev_b32_e32 v129, 31, v128
	v_ashrrev_i32_e32 v128, 6, v128
	v_add_u32_e32 v177, v128, v129
	s_movk_i32 s8, 0xfe80
	v_mad_i32_i24 v128, v177, s8, v212
	s_or_b64 exec, exec, s[0:1]
	v_and_b32_e32 v176, 15, v174
	v_lshlrev_b32_e32 v175, 2, v176
	v_add_u32_e32 v136, v128, v175
	v_ashrrev_i32_e32 v178, 4, v174
	v_cmp_lt_i32_e32 vcc, 4, v177
	s_mov_b64 s[0:1], 0
	s_mov_b64 s[66:67], 0
	s_mov_b64 s[10:11], 0
	s_and_saveexec_b64 s[8:9], vcc
	s_xor_b64 s[8:9], exec, s[8:9]
	s_cbranch_execz .LBB0_242
	v_cmp_lt_i32_e32 vcc, 7, v177
	s_and_saveexec_b64 s[24:25], vcc
	s_xor_b64 s[68:69], exec, s[24:25]
	s_cbranch_execz .LBB0_233
	v_cmp_lt_i32_e32 vcc, 8, v177
	s_mov_b64 s[72:73], 0
	s_and_saveexec_b64 s[10:11], vcc
	s_xor_b64 s[10:11], exec, s[10:11]
	s_cbranch_execz .LBB0_230
	v_cmp_lt_i32_e32 vcc, 9, v177
	s_mov_b64 s[74:75], -1
	s_and_saveexec_b64 s[66:67], vcc
	s_cbranch_execz .LBB0_229
	v_cmp_eq_u32_e32 vcc, 10, v177
	s_mov_b64 s[34:35], -1
	s_and_saveexec_b64 s[72:73], vcc
	s_cbranch_execz .LBB0_228
	v_and_b32_e32 v129, 64, v133
	v_xor_b32_e32 v128, 4, v133
	v_add_u32_e32 v129, 64, v129
	v_cmp_lt_i32_e32 vcc, v128, v129
	v_readlane_b32 s36, v253, 26
	v_ashrrev_i32_e32 v137, 31, v136
	v_cndmask_b32_e32 v128, v133, v128, vcc
	v_lshlrev_b32_e32 v141, 2, v128
	v_and_b32_e32 v128, 4, v174
	v_cmp_eq_u32_e32 vcc, 0, v128
	v_readlane_b32 s46, v253, 36
	v_readlane_b32 s47, v253, 37
	v_lshlrev_b32_e32 v131, 3, v174
	v_lshl_add_u32 v130, v178, 2, v211
	v_cndmask_b32_e64 v140, 1.0, -1.0, vcc
	v_readlane_b32 s37, v253, 27
	v_readlane_b32 s38, v253, 28
	v_readlane_b32 s39, v253, 29
	v_readlane_b32 s40, v253, 30
	v_readlane_b32 s41, v253, 31
	v_readlane_b32 s42, v253, 32
	v_readlane_b32 s43, v253, 33
	v_readlane_b32 s44, v253, 34
	v_readlane_b32 s45, v253, 35
	v_readlane_b32 s48, v253, 38
	v_readlane_b32 s49, v253, 39
	v_readlane_b32 s50, v253, 40
	v_readlane_b32 s51, v253, 41
	v_lshl_add_u64 v[128:129], v[136:137], 1, s[46:47]
	v_and_b32_e32 v137, 24, v131
	v_lshlrev_b32_e32 v131, 7, v178
	s_movk_i32 s24, 0x380
	v_and_or_b32 v131, v131, s24, v137
	v_lshlrev_b32_e32 v134, 3, v131
	v_lshl_add_u64 v[138:139], s[58:59], 0, v[134:135]
	v_add_co_u32_e32 v138, vcc, s33, v138
	ds_bpermute_b32 v131, v141, v124
	s_nop 0
	v_addc_co_u32_e32 v139, vcc, 0, v139, vcc
	global_load_dwordx2 v[144:145], v[138:139], off
	global_load_dwordx2 v[150:151], v[138:139], off offset:256
	s_waitcnt lgkmcnt(0)
	v_mul_f32_e32 v143, v140, v131
	v_mov_b32_e32 v142, v124
	ds_bpermute_b32 v134, v141, v120
	ds_bpermute_b32 v146, v141, v116
	ds_bpermute_b32 v147, v141, v112
	v_ashrrev_i32_e32 v131, 31, v130
	ds_bpermute_b32 v152, v141, v113
	s_waitcnt vmcnt(1)
	v_pk_mul_f32 v[142:143], v[142:143], v[144:145]
	global_load_dwordx2 v[144:145], v[138:139], off offset:16
	v_add_f32_e32 v148, v142, v143
	s_waitcnt lgkmcnt(3)
	v_mul_f32_e32 v143, v140, v134
	v_mov_b32_e32 v142, v120
	s_waitcnt vmcnt(0)
	v_pk_mul_f32 v[142:143], v[142:143], v[144:145]
	global_load_dwordx2 v[144:145], v[138:139], off offset:32
	v_add_f32_e32 v134, v142, v143
	s_waitcnt lgkmcnt(2)
	v_mul_f32_e32 v143, v140, v146
	v_mov_b32_e32 v142, v116
	s_waitcnt vmcnt(0)
	v_pk_mul_f32 v[142:143], v[142:143], v[144:145]
	global_load_dwordx2 v[144:145], v[138:139], off offset:48
	v_add_f32_e32 v146, v142, v143
	s_waitcnt lgkmcnt(1)
	v_mul_f32_e32 v143, v140, v147
	v_mov_b32_e32 v142, v112
	ds_bpermute_b32 v147, v141, v117
	s_waitcnt vmcnt(0)
	v_pk_mul_f32 v[142:143], v[142:143], v[144:145]
	s_nop 0
	v_add_f32_e32 v145, v142, v143
	v_lshlrev_b64 v[142:143], 9, v[130:131]
	ds_bpermute_b32 v131, v141, v125
	v_cvt_pk_bf16_f32 v144, v148, v134
	v_mov_b32_e32 v148, v125
	ds_bpermute_b32 v134, v141, v121
	v_lshl_add_u64 v[142:143], v[128:129], 0, v[142:143]
	s_waitcnt lgkmcnt(1)
	v_mul_f32_e32 v149, v140, v131
	v_pk_mul_f32 v[148:149], v[148:149], v[150:151]
	global_load_dwordx2 v[150:151], v[138:139], off offset:272
	v_add_f32_e32 v131, v148, v149
	s_waitcnt lgkmcnt(0)
	v_mul_f32_e32 v149, v140, v134
	v_mov_b32_e32 v148, v121
	v_cvt_pk_bf16_f32 v145, v146, v145
	v_or_b32_e32 v146, 1, v130
	s_waitcnt vmcnt(0)
	v_pk_mul_f32 v[148:149], v[148:149], v[150:151]
	global_load_dwordx2 v[150:151], v[138:139], off offset:288
	v_add_f32_e32 v134, v148, v149
	v_mul_f32_e32 v149, v140, v147
	v_mov_b32_e32 v148, v117
	s_waitcnt vmcnt(0)
	v_pk_mul_f32 v[148:149], v[148:149], v[150:151]
	global_load_dwordx2 v[150:151], v[138:139], off offset:304
	v_add_f32_e32 v153, v148, v149
	v_mul_f32_e32 v149, v140, v152
	global_store_dwordx2 v[142:143], v[144:145], off nt
	v_mov_b32_e32 v148, v113
	s_waitcnt vmcnt(1)
	v_pk_mul_f32 v[142:143], v[148:149], v[150:151]
	v_ashrrev_i32_e32 v147, 31, v146
	v_add_f32_e32 v145, v142, v143
	v_lshlrev_b64 v[142:143], 9, v[146:147]
	v_lshl_add_u64 v[142:143], v[128:129], 0, v[142:143]
	v_cvt_pk_bf16_f32 v144, v131, v134
	v_cvt_pk_bf16_f32 v145, v153, v145
	global_store_dwordx2 v[142:143], v[144:145], off nt
	v_or_b32_e32 v142, 2, v130
	v_lshlrev_b32_e32 v131, 5, v142
	s_movk_i32 s23, 0x3c0
	v_and_or_b32 v131, v131, s23, v137
	v_lshlrev_b32_e32 v134, 3, v131
	v_lshl_add_u64 v[144:145], s[58:59], 0, v[134:135]
	v_add_co_u32_e32 v144, vcc, s33, v144
	ds_bpermute_b32 v131, v141, v126
	s_nop 0
	v_addc_co_u32_e32 v145, vcc, 0, v145, vcc
	global_load_dwordx2 v[148:149], v[144:145], off
	global_load_dwordx2 v[152:153], v[144:145], off offset:256
	s_waitcnt lgkmcnt(0)
	v_mul_f32_e32 v147, v140, v131
	v_mov_b32_e32 v146, v126
	ds_bpermute_b32 v134, v141, v122
	ds_bpermute_b32 v143, v141, v118
	ds_bpermute_b32 v150, v141, v114
	ds_bpermute_b32 v154, v141, v115
	s_waitcnt vmcnt(1)
	v_pk_mul_f32 v[146:147], v[146:147], v[148:149]
	global_load_dwordx2 v[148:149], v[144:145], off offset:16
	v_add_f32_e32 v131, v146, v147
	s_waitcnt lgkmcnt(3)
	v_mul_f32_e32 v147, v140, v134
	v_mov_b32_e32 v146, v122
	s_waitcnt vmcnt(0)
	v_pk_mul_f32 v[146:147], v[146:147], v[148:149]
	global_load_dwordx2 v[148:149], v[144:145], off offset:32
	v_add_f32_e32 v134, v146, v147
	s_waitcnt lgkmcnt(2)
	v_mul_f32_e32 v147, v140, v143
	v_mov_b32_e32 v146, v118
	v_ashrrev_i32_e32 v143, 31, v142
	v_lshlrev_b64 v[142:143], 9, v[142:143]
	v_lshl_add_u64 v[142:143], v[128:129], 0, v[142:143]
	s_waitcnt vmcnt(0)
	v_pk_mul_f32 v[146:147], v[146:147], v[148:149]
	global_load_dwordx2 v[148:149], v[144:145], off offset:48
	v_add_f32_e32 v151, v146, v147
	s_waitcnt lgkmcnt(1)
	v_mul_f32_e32 v147, v140, v150
	v_mov_b32_e32 v146, v114
	v_mov_b32_e32 v150, v127
	s_waitcnt vmcnt(0)
	v_pk_mul_f32 v[146:147], v[146:147], v[148:149]
	s_nop 0
	v_add_f32_e32 v147, v146, v147
	v_cvt_pk_bf16_f32 v146, v131, v134
	ds_bpermute_b32 v131, v141, v127
	v_cvt_pk_bf16_f32 v147, v151, v147
	ds_bpermute_b32 v134, v141, v123
	ds_bpermute_b32 v149, v141, v119
	v_or_b32_e32 v148, 3, v130
	s_waitcnt lgkmcnt(2)
	v_mul_f32_e32 v151, v140, v131
	v_pk_mul_f32 v[150:151], v[150:151], v[152:153]
	global_load_dwordx2 v[152:153], v[144:145], off offset:272
	v_add_f32_e32 v131, v150, v151
	s_waitcnt lgkmcnt(1)
	v_mul_f32_e32 v151, v140, v134
	v_mov_b32_e32 v150, v123
	s_waitcnt vmcnt(0)
	v_pk_mul_f32 v[150:151], v[150:151], v[152:153]
	global_load_dwordx2 v[152:153], v[144:145], off offset:288
	v_add_f32_e32 v134, v150, v151
	global_load_dwordx2 v[144:145], v[144:145], off offset:304
	s_waitcnt lgkmcnt(0)
	v_mul_f32_e32 v151, v140, v149
	v_mov_b32_e32 v150, v119
	global_store_dwordx2 v[142:143], v[146:147], off nt
	s_waitcnt vmcnt(2)
	v_pk_mul_f32 v[150:151], v[150:151], v[152:153]
	s_nop 0
	v_add_f32_e32 v152, v150, v151
	v_mul_f32_e32 v151, v140, v154
	v_mov_b32_e32 v150, v115
	s_waitcnt vmcnt(1)
	v_pk_mul_f32 v[142:143], v[150:151], v[144:145]
	v_ashrrev_i32_e32 v149, 31, v148
	v_add_f32_e32 v145, v142, v143
	v_lshlrev_b64 v[142:143], 9, v[148:149]
	v_lshl_add_u64 v[142:143], v[128:129], 0, v[142:143]
	v_cvt_pk_bf16_f32 v144, v131, v134
	v_cvt_pk_bf16_f32 v145, v152, v145
	global_store_dwordx2 v[142:143], v[144:145], off nt
	v_add_u32_e32 v142, 16, v130
	v_lshlrev_b32_e32 v131, 5, v142
	v_and_or_b32 v131, v131, s24, v137
	v_lshlrev_b32_e32 v134, 3, v131
	v_lshl_add_u64 v[144:145], s[58:59], 0, v[134:135]
	v_add_co_u32_e32 v144, vcc, s33, v144
	ds_bpermute_b32 v131, v141, v108
	s_nop 0
	v_addc_co_u32_e32 v145, vcc, 0, v145, vcc
	global_load_dwordx2 v[148:149], v[144:145], off
	global_load_dwordx2 v[152:153], v[144:145], off offset:256
	s_waitcnt lgkmcnt(0)
	v_mul_f32_e32 v147, v140, v131
	v_mov_b32_e32 v146, v108
	ds_bpermute_b32 v134, v141, v104
	ds_bpermute_b32 v143, v141, v100
	ds_bpermute_b32 v150, v141, v96
	ds_bpermute_b32 v154, v141, v97
	s_waitcnt vmcnt(1)
	v_pk_mul_f32 v[146:147], v[146:147], v[148:149]
	global_load_dwordx2 v[148:149], v[144:145], off offset:16
	v_add_f32_e32 v131, v146, v147
	s_waitcnt lgkmcnt(3)
	v_mul_f32_e32 v147, v140, v134
	v_mov_b32_e32 v146, v104
	s_waitcnt vmcnt(0)
	v_pk_mul_f32 v[146:147], v[146:147], v[148:149]
	global_load_dwordx2 v[148:149], v[144:145], off offset:32
	v_add_f32_e32 v134, v146, v147
	s_waitcnt lgkmcnt(2)
	v_mul_f32_e32 v147, v140, v143
	v_mov_b32_e32 v146, v100
	v_ashrrev_i32_e32 v143, 31, v142
	v_lshlrev_b64 v[142:143], 9, v[142:143]
	v_lshl_add_u64 v[142:143], v[128:129], 0, v[142:143]
	s_waitcnt vmcnt(0)
	v_pk_mul_f32 v[146:147], v[146:147], v[148:149]
	global_load_dwordx2 v[148:149], v[144:145], off offset:48
	v_add_f32_e32 v151, v146, v147
	s_waitcnt lgkmcnt(1)
	v_mul_f32_e32 v147, v140, v150
	v_mov_b32_e32 v146, v96
	v_mov_b32_e32 v150, v109
	s_waitcnt vmcnt(0)
	v_pk_mul_f32 v[146:147], v[146:147], v[148:149]
	s_nop 0
	v_add_f32_e32 v147, v146, v147
	v_cvt_pk_bf16_f32 v146, v131, v134
	ds_bpermute_b32 v131, v141, v109
	v_cvt_pk_bf16_f32 v147, v151, v147
	ds_bpermute_b32 v134, v141, v105
	ds_bpermute_b32 v149, v141, v101
	v_add_u32_e32 v148, 17, v130
	s_waitcnt lgkmcnt(2)
	v_mul_f32_e32 v151, v140, v131
	v_pk_mul_f32 v[150:151], v[150:151], v[152:153]
	global_load_dwordx2 v[152:153], v[144:145], off offset:272
	v_add_f32_e32 v131, v150, v151
	s_waitcnt lgkmcnt(1)
	v_mul_f32_e32 v151, v140, v134
	v_mov_b32_e32 v150, v105
	s_waitcnt vmcnt(0)
	v_pk_mul_f32 v[150:151], v[150:151], v[152:153]
	global_load_dwordx2 v[152:153], v[144:145], off offset:288
	v_add_f32_e32 v134, v150, v151
	global_load_dwordx2 v[144:145], v[144:145], off offset:304
	s_waitcnt lgkmcnt(0)
	v_mul_f32_e32 v151, v140, v149
	v_mov_b32_e32 v150, v101
	global_store_dwordx2 v[142:143], v[146:147], off nt
	s_waitcnt vmcnt(2)
	v_pk_mul_f32 v[150:151], v[150:151], v[152:153]
	s_nop 0
	v_add_f32_e32 v152, v150, v151
	v_mul_f32_e32 v151, v140, v154
	v_mov_b32_e32 v150, v97
	s_waitcnt vmcnt(1)
	v_pk_mul_f32 v[142:143], v[150:151], v[144:145]
	v_ashrrev_i32_e32 v149, 31, v148
	v_add_f32_e32 v145, v142, v143
	v_lshlrev_b64 v[142:143], 9, v[148:149]
	v_lshl_add_u64 v[142:143], v[128:129], 0, v[142:143]
	v_cvt_pk_bf16_f32 v144, v131, v134
	v_cvt_pk_bf16_f32 v145, v152, v145
	global_store_dwordx2 v[142:143], v[144:145], off nt
	v_add_u32_e32 v142, 18, v130
	v_lshlrev_b32_e32 v131, 5, v142
	v_and_or_b32 v131, v131, s23, v137
	v_lshlrev_b32_e32 v134, 3, v131
	v_lshl_add_u64 v[144:145], s[58:59], 0, v[134:135]
	v_add_co_u32_e32 v144, vcc, s33, v144
	ds_bpermute_b32 v131, v141, v110
	s_nop 0
	v_addc_co_u32_e32 v145, vcc, 0, v145, vcc
	global_load_dwordx2 v[148:149], v[144:145], off
	global_load_dwordx2 v[152:153], v[144:145], off offset:256
	s_waitcnt lgkmcnt(0)
	v_mul_f32_e32 v147, v140, v131
	v_mov_b32_e32 v146, v110
	ds_bpermute_b32 v134, v141, v106
	ds_bpermute_b32 v143, v141, v102
	ds_bpermute_b32 v150, v141, v98
	ds_bpermute_b32 v154, v141, v99
	s_waitcnt vmcnt(1)
	v_pk_mul_f32 v[146:147], v[146:147], v[148:149]
	global_load_dwordx2 v[148:149], v[144:145], off offset:16
	v_add_f32_e32 v131, v146, v147
	s_waitcnt lgkmcnt(3)
	v_mul_f32_e32 v147, v140, v134
	v_mov_b32_e32 v146, v106
	s_waitcnt vmcnt(0)
	v_pk_mul_f32 v[146:147], v[146:147], v[148:149]
	global_load_dwordx2 v[148:149], v[144:145], off offset:32
	v_add_f32_e32 v134, v146, v147
	s_waitcnt lgkmcnt(2)
	v_mul_f32_e32 v147, v140, v143
	v_mov_b32_e32 v146, v102
	v_ashrrev_i32_e32 v143, 31, v142
	v_lshlrev_b64 v[142:143], 9, v[142:143]
	v_lshl_add_u64 v[142:143], v[128:129], 0, v[142:143]
	s_waitcnt vmcnt(0)
	v_pk_mul_f32 v[146:147], v[146:147], v[148:149]
	global_load_dwordx2 v[148:149], v[144:145], off offset:48
	v_add_f32_e32 v151, v146, v147
	s_waitcnt lgkmcnt(1)
	v_mul_f32_e32 v147, v140, v150
	v_mov_b32_e32 v146, v98
	v_mov_b32_e32 v150, v111
	s_waitcnt vmcnt(0)
	v_pk_mul_f32 v[146:147], v[146:147], v[148:149]
	s_nop 0
	v_add_f32_e32 v147, v146, v147
	v_cvt_pk_bf16_f32 v146, v131, v134
	ds_bpermute_b32 v131, v141, v111
	v_cvt_pk_bf16_f32 v147, v151, v147
	ds_bpermute_b32 v134, v141, v107
	ds_bpermute_b32 v149, v141, v103
	v_add_u32_e32 v148, 19, v130
	s_waitcnt lgkmcnt(2)
	v_mul_f32_e32 v151, v140, v131
	v_pk_mul_f32 v[150:151], v[150:151], v[152:153]
	global_load_dwordx2 v[152:153], v[144:145], off offset:272
	v_add_f32_e32 v131, v150, v151
	s_waitcnt lgkmcnt(1)
	v_mul_f32_e32 v151, v140, v134
	v_mov_b32_e32 v150, v107
	s_waitcnt vmcnt(0)
	v_pk_mul_f32 v[150:151], v[150:151], v[152:153]
	global_load_dwordx2 v[152:153], v[144:145], off offset:288
	v_add_f32_e32 v134, v150, v151
	global_load_dwordx2 v[144:145], v[144:145], off offset:304
	s_waitcnt lgkmcnt(0)
	v_mul_f32_e32 v151, v140, v149
	v_mov_b32_e32 v150, v103
	global_store_dwordx2 v[142:143], v[146:147], off nt
	s_waitcnt vmcnt(2)
	v_pk_mul_f32 v[150:151], v[150:151], v[152:153]
	s_nop 0
	v_add_f32_e32 v152, v150, v151
	v_mul_f32_e32 v151, v140, v154
	v_mov_b32_e32 v150, v99
	s_waitcnt vmcnt(1)
	v_pk_mul_f32 v[142:143], v[150:151], v[144:145]
	v_ashrrev_i32_e32 v149, 31, v148
	v_add_f32_e32 v145, v142, v143
	v_lshlrev_b64 v[142:143], 9, v[148:149]
	v_lshl_add_u64 v[142:143], v[128:129], 0, v[142:143]
	v_cvt_pk_bf16_f32 v144, v131, v134
	v_cvt_pk_bf16_f32 v145, v152, v145
	global_store_dwordx2 v[142:143], v[144:145], off nt
	v_add_u32_e32 v142, 32, v130
	global_load_dwordx2 v[146:147], v[138:139], off
	global_load_dwordx2 v[150:151], v[138:139], off offset:256
	ds_bpermute_b32 v131, v141, v92
	v_mov_b32_e32 v144, v92
	ds_bpermute_b32 v134, v141, v88
	ds_bpermute_b32 v143, v141, v84
	ds_bpermute_b32 v148, v141, v80
	s_waitcnt lgkmcnt(3)
	v_mul_f32_e32 v145, v140, v131
	ds_bpermute_b32 v152, v141, v81
	s_waitcnt vmcnt(1)
	v_pk_mul_f32 v[144:145], v[144:145], v[146:147]
	global_load_dwordx2 v[146:147], v[138:139], off offset:16
	v_add_f32_e32 v131, v144, v145
	s_waitcnt lgkmcnt(3)
	v_mul_f32_e32 v145, v140, v134
	v_mov_b32_e32 v144, v88
	s_waitcnt vmcnt(0)
	v_pk_mul_f32 v[144:145], v[144:145], v[146:147]
	global_load_dwordx2 v[146:147], v[138:139], off offset:32
	v_add_f32_e32 v134, v144, v145
	s_waitcnt lgkmcnt(2)
	v_mul_f32_e32 v145, v140, v143
	v_mov_b32_e32 v144, v84
	v_ashrrev_i32_e32 v143, 31, v142
	v_lshlrev_b64 v[142:143], 9, v[142:143]
	v_lshl_add_u64 v[142:143], v[128:129], 0, v[142:143]
	s_waitcnt vmcnt(0)
	v_pk_mul_f32 v[144:145], v[144:145], v[146:147]
	global_load_dwordx2 v[146:147], v[138:139], off offset:48
	v_add_f32_e32 v149, v144, v145
	s_waitcnt lgkmcnt(1)
	v_mul_f32_e32 v145, v140, v148
	v_mov_b32_e32 v144, v80
	v_mov_b32_e32 v148, v93
	s_waitcnt vmcnt(0)
	v_pk_mul_f32 v[144:145], v[144:145], v[146:147]
	s_nop 0
	v_add_f32_e32 v145, v144, v145
	v_cvt_pk_bf16_f32 v144, v131, v134
	ds_bpermute_b32 v131, v141, v93
	v_cvt_pk_bf16_f32 v145, v149, v145
	ds_bpermute_b32 v134, v141, v89
	ds_bpermute_b32 v147, v141, v85
	v_add_u32_e32 v146, 33, v130
	s_waitcnt lgkmcnt(2)
	v_mul_f32_e32 v149, v140, v131
	v_pk_mul_f32 v[148:149], v[148:149], v[150:151]
	global_load_dwordx2 v[150:151], v[138:139], off offset:272
	v_add_f32_e32 v131, v148, v149
	s_waitcnt lgkmcnt(1)
	v_mul_f32_e32 v149, v140, v134
	v_mov_b32_e32 v148, v89
	s_waitcnt vmcnt(0)
	v_pk_mul_f32 v[148:149], v[148:149], v[150:151]
	global_load_dwordx2 v[150:151], v[138:139], off offset:288
	v_add_f32_e32 v134, v148, v149
	s_waitcnt lgkmcnt(0)
	v_mul_f32_e32 v149, v140, v147
	v_mov_b32_e32 v148, v85
	s_waitcnt vmcnt(0)
	v_pk_mul_f32 v[148:149], v[148:149], v[150:151]
	global_load_dwordx2 v[150:151], v[138:139], off offset:304
	v_add_f32_e32 v153, v148, v149
	v_mul_f32_e32 v149, v140, v152
	global_store_dwordx2 v[142:143], v[144:145], off nt
	v_mov_b32_e32 v148, v81
	s_waitcnt vmcnt(1)
	v_pk_mul_f32 v[142:143], v[148:149], v[150:151]
	v_ashrrev_i32_e32 v147, 31, v146
	v_add_f32_e32 v145, v142, v143
	v_lshlrev_b64 v[142:143], 9, v[146:147]
	v_lshl_add_u64 v[142:143], v[128:129], 0, v[142:143]
	v_cvt_pk_bf16_f32 v144, v131, v134
	v_cvt_pk_bf16_f32 v145, v153, v145
	global_store_dwordx2 v[142:143], v[144:145], off nt
	v_add_u32_e32 v142, 34, v130
	v_lshlrev_b32_e32 v131, 5, v142
	v_and_or_b32 v131, v131, s23, v137
	v_lshlrev_b32_e32 v134, 3, v131
	v_lshl_add_u64 v[144:145], s[58:59], 0, v[134:135]
	v_add_co_u32_e32 v144, vcc, s33, v144
	ds_bpermute_b32 v131, v141, v94
	s_nop 0
	v_addc_co_u32_e32 v145, vcc, 0, v145, vcc
	global_load_dwordx2 v[148:149], v[144:145], off
	global_load_dwordx2 v[152:153], v[144:145], off offset:256
	s_waitcnt lgkmcnt(0)
	v_mul_f32_e32 v147, v140, v131
	v_mov_b32_e32 v146, v94
	ds_bpermute_b32 v134, v141, v90
	ds_bpermute_b32 v143, v141, v86
	ds_bpermute_b32 v150, v141, v82
	ds_bpermute_b32 v154, v141, v83
	s_waitcnt vmcnt(1)
	v_pk_mul_f32 v[146:147], v[146:147], v[148:149]
	global_load_dwordx2 v[148:149], v[144:145], off offset:16
	v_add_f32_e32 v131, v146, v147
	s_waitcnt lgkmcnt(3)
	v_mul_f32_e32 v147, v140, v134
	v_mov_b32_e32 v146, v90
	s_waitcnt vmcnt(0)
	v_pk_mul_f32 v[146:147], v[146:147], v[148:149]
	global_load_dwordx2 v[148:149], v[144:145], off offset:32
	v_add_f32_e32 v134, v146, v147
	s_waitcnt lgkmcnt(2)
	v_mul_f32_e32 v147, v140, v143
	v_mov_b32_e32 v146, v86
	v_ashrrev_i32_e32 v143, 31, v142
	v_lshlrev_b64 v[142:143], 9, v[142:143]
	v_lshl_add_u64 v[142:143], v[128:129], 0, v[142:143]
	s_waitcnt vmcnt(0)
	v_pk_mul_f32 v[146:147], v[146:147], v[148:149]
	global_load_dwordx2 v[148:149], v[144:145], off offset:48
	v_add_f32_e32 v151, v146, v147
	s_waitcnt lgkmcnt(1)
	v_mul_f32_e32 v147, v140, v150
	v_mov_b32_e32 v146, v82
	v_mov_b32_e32 v150, v95
	s_waitcnt vmcnt(0)
	v_pk_mul_f32 v[146:147], v[146:147], v[148:149]
	s_nop 0
	v_add_f32_e32 v147, v146, v147
	v_cvt_pk_bf16_f32 v146, v131, v134
	ds_bpermute_b32 v131, v141, v95
	v_cvt_pk_bf16_f32 v147, v151, v147
	ds_bpermute_b32 v134, v141, v91
	ds_bpermute_b32 v149, v141, v87
	v_add_u32_e32 v148, 35, v130
	s_waitcnt lgkmcnt(2)
	v_mul_f32_e32 v151, v140, v131
	v_pk_mul_f32 v[150:151], v[150:151], v[152:153]
	global_load_dwordx2 v[152:153], v[144:145], off offset:272
	v_add_f32_e32 v131, v150, v151
	s_waitcnt lgkmcnt(1)
	v_mul_f32_e32 v151, v140, v134
	v_mov_b32_e32 v150, v91
	s_waitcnt vmcnt(0)
	v_pk_mul_f32 v[150:151], v[150:151], v[152:153]
	global_load_dwordx2 v[152:153], v[144:145], off offset:288
	v_add_f32_e32 v134, v150, v151
	global_load_dwordx2 v[144:145], v[144:145], off offset:304
	s_waitcnt lgkmcnt(0)
	v_mul_f32_e32 v151, v140, v149
	v_mov_b32_e32 v150, v87
	global_store_dwordx2 v[142:143], v[146:147], off nt
	s_waitcnt vmcnt(2)
	v_pk_mul_f32 v[150:151], v[150:151], v[152:153]
	s_nop 0
	v_add_f32_e32 v152, v150, v151
	v_mul_f32_e32 v151, v140, v154
	v_mov_b32_e32 v150, v83
	s_waitcnt vmcnt(1)
	v_pk_mul_f32 v[142:143], v[150:151], v[144:145]
	v_ashrrev_i32_e32 v149, 31, v148
	v_add_f32_e32 v145, v142, v143
	v_lshlrev_b64 v[142:143], 9, v[148:149]
	v_lshl_add_u64 v[142:143], v[128:129], 0, v[142:143]
	v_cvt_pk_bf16_f32 v144, v131, v134
	v_cvt_pk_bf16_f32 v145, v152, v145
	global_store_dwordx2 v[142:143], v[144:145], off nt
	v_add_u32_e32 v142, 48, v130
	v_lshlrev_b32_e32 v131, 5, v142
	v_and_or_b32 v131, v131, s24, v137
	v_lshlrev_b32_e32 v134, 3, v131
	v_lshl_add_u64 v[144:145], s[58:59], 0, v[134:135]
	v_add_co_u32_e32 v144, vcc, s33, v144
	ds_bpermute_b32 v131, v141, v76
	s_nop 0
	v_addc_co_u32_e32 v145, vcc, 0, v145, vcc
	global_load_dwordx2 v[148:149], v[144:145], off
	global_load_dwordx2 v[152:153], v[144:145], off offset:256
	s_waitcnt lgkmcnt(0)
	v_mul_f32_e32 v147, v140, v131
	v_mov_b32_e32 v146, v76
	ds_bpermute_b32 v134, v141, v72
	ds_bpermute_b32 v143, v141, v68
	ds_bpermute_b32 v150, v141, v64
	ds_bpermute_b32 v154, v141, v65
	s_waitcnt vmcnt(1)
	v_pk_mul_f32 v[146:147], v[146:147], v[148:149]
	global_load_dwordx2 v[148:149], v[144:145], off offset:16
	v_add_f32_e32 v131, v146, v147
	s_waitcnt lgkmcnt(3)
	v_mul_f32_e32 v147, v140, v134
	v_mov_b32_e32 v146, v72
	s_waitcnt vmcnt(0)
	v_pk_mul_f32 v[146:147], v[146:147], v[148:149]
	global_load_dwordx2 v[148:149], v[144:145], off offset:32
	v_add_f32_e32 v134, v146, v147
	s_waitcnt lgkmcnt(2)
	v_mul_f32_e32 v147, v140, v143
	v_mov_b32_e32 v146, v68
	v_ashrrev_i32_e32 v143, 31, v142
	v_lshlrev_b64 v[142:143], 9, v[142:143]
	v_lshl_add_u64 v[142:143], v[128:129], 0, v[142:143]
	s_waitcnt vmcnt(0)
	v_pk_mul_f32 v[146:147], v[146:147], v[148:149]
	global_load_dwordx2 v[148:149], v[144:145], off offset:48
	v_add_f32_e32 v151, v146, v147
	s_waitcnt lgkmcnt(1)
	v_mul_f32_e32 v147, v140, v150
	v_mov_b32_e32 v146, v64
	v_mov_b32_e32 v150, v77
	s_waitcnt vmcnt(0)
	v_pk_mul_f32 v[146:147], v[146:147], v[148:149]
	s_nop 0
	v_add_f32_e32 v147, v146, v147
	v_cvt_pk_bf16_f32 v146, v131, v134
	ds_bpermute_b32 v131, v141, v77
	v_cvt_pk_bf16_f32 v147, v151, v147
	ds_bpermute_b32 v134, v141, v73
	ds_bpermute_b32 v149, v141, v69
	v_add_u32_e32 v148, 49, v130
	s_waitcnt lgkmcnt(2)
	v_mul_f32_e32 v151, v140, v131
	v_pk_mul_f32 v[150:151], v[150:151], v[152:153]
	global_load_dwordx2 v[152:153], v[144:145], off offset:272
	v_add_f32_e32 v131, v150, v151
	s_waitcnt lgkmcnt(1)
	v_mul_f32_e32 v151, v140, v134
	v_mov_b32_e32 v150, v73
	s_waitcnt vmcnt(0)
	v_pk_mul_f32 v[150:151], v[150:151], v[152:153]
	global_load_dwordx2 v[152:153], v[144:145], off offset:288
	v_add_f32_e32 v134, v150, v151
	global_load_dwordx2 v[144:145], v[144:145], off offset:304
	s_waitcnt lgkmcnt(0)
	v_mul_f32_e32 v151, v140, v149
	v_mov_b32_e32 v150, v69
	global_store_dwordx2 v[142:143], v[146:147], off nt
	s_waitcnt vmcnt(2)
	v_pk_mul_f32 v[150:151], v[150:151], v[152:153]
	s_nop 0
	v_add_f32_e32 v152, v150, v151
	v_mul_f32_e32 v151, v140, v154
	v_mov_b32_e32 v150, v65
	s_waitcnt vmcnt(1)
	v_pk_mul_f32 v[142:143], v[150:151], v[144:145]
	v_ashrrev_i32_e32 v149, 31, v148
	v_add_f32_e32 v145, v142, v143
	v_lshlrev_b64 v[142:143], 9, v[148:149]
	v_lshl_add_u64 v[142:143], v[128:129], 0, v[142:143]
	v_cvt_pk_bf16_f32 v144, v131, v134
	v_cvt_pk_bf16_f32 v145, v152, v145
	global_store_dwordx2 v[142:143], v[144:145], off nt
	v_add_u32_e32 v142, 50, v130
	v_lshlrev_b32_e32 v131, 5, v142
	v_and_or_b32 v131, v131, s23, v137
	v_lshlrev_b32_e32 v134, 3, v131
	v_lshl_add_u64 v[144:145], s[58:59], 0, v[134:135]
	v_add_co_u32_e32 v144, vcc, s33, v144
	ds_bpermute_b32 v131, v141, v78
	s_nop 0
	v_addc_co_u32_e32 v145, vcc, 0, v145, vcc
	global_load_dwordx2 v[148:149], v[144:145], off
	global_load_dwordx2 v[152:153], v[144:145], off offset:256
	s_waitcnt lgkmcnt(0)
	v_mul_f32_e32 v147, v140, v131
	v_mov_b32_e32 v146, v78
	ds_bpermute_b32 v134, v141, v74
	ds_bpermute_b32 v143, v141, v70
	ds_bpermute_b32 v150, v141, v66
	ds_bpermute_b32 v154, v141, v67
	s_waitcnt vmcnt(1)
	v_pk_mul_f32 v[146:147], v[146:147], v[148:149]
	global_load_dwordx2 v[148:149], v[144:145], off offset:16
	v_add_f32_e32 v131, v146, v147
	s_waitcnt lgkmcnt(3)
	v_mul_f32_e32 v147, v140, v134
	v_mov_b32_e32 v146, v74
	s_waitcnt vmcnt(0)
	v_pk_mul_f32 v[146:147], v[146:147], v[148:149]
	global_load_dwordx2 v[148:149], v[144:145], off offset:32
	v_add_f32_e32 v134, v146, v147
	s_waitcnt lgkmcnt(2)
	v_mul_f32_e32 v147, v140, v143
	v_mov_b32_e32 v146, v70
	v_ashrrev_i32_e32 v143, 31, v142
	v_lshlrev_b64 v[142:143], 9, v[142:143]
	v_lshl_add_u64 v[142:143], v[128:129], 0, v[142:143]
	s_waitcnt vmcnt(0)
	v_pk_mul_f32 v[146:147], v[146:147], v[148:149]
	global_load_dwordx2 v[148:149], v[144:145], off offset:48
	v_add_f32_e32 v151, v146, v147
	s_waitcnt lgkmcnt(1)
	v_mul_f32_e32 v147, v140, v150
	v_mov_b32_e32 v146, v66
	v_mov_b32_e32 v150, v79
	s_waitcnt vmcnt(0)
	v_pk_mul_f32 v[146:147], v[146:147], v[148:149]
	s_nop 0
	v_add_f32_e32 v147, v146, v147
	v_cvt_pk_bf16_f32 v146, v131, v134
	ds_bpermute_b32 v131, v141, v79
	v_cvt_pk_bf16_f32 v147, v151, v147
	ds_bpermute_b32 v134, v141, v75
	ds_bpermute_b32 v149, v141, v71
	v_add_u32_e32 v148, 51, v130
	s_waitcnt lgkmcnt(2)
	v_mul_f32_e32 v151, v140, v131
	v_pk_mul_f32 v[150:151], v[150:151], v[152:153]
	global_load_dwordx2 v[152:153], v[144:145], off offset:272
	v_add_f32_e32 v131, v150, v151
	s_waitcnt lgkmcnt(1)
	v_mul_f32_e32 v151, v140, v134
	v_mov_b32_e32 v150, v75
	s_waitcnt vmcnt(0)
	v_pk_mul_f32 v[150:151], v[150:151], v[152:153]
	global_load_dwordx2 v[152:153], v[144:145], off offset:288
	v_add_f32_e32 v134, v150, v151
	global_load_dwordx2 v[144:145], v[144:145], off offset:304
	s_waitcnt lgkmcnt(0)
	v_mul_f32_e32 v151, v140, v149
	v_mov_b32_e32 v150, v71
	global_store_dwordx2 v[142:143], v[146:147], off nt
	s_waitcnt vmcnt(2)
	v_pk_mul_f32 v[150:151], v[150:151], v[152:153]
	s_nop 0
	v_add_f32_e32 v152, v150, v151
	v_mul_f32_e32 v151, v140, v154
	v_mov_b32_e32 v150, v67
	s_waitcnt vmcnt(1)
	v_pk_mul_f32 v[142:143], v[150:151], v[144:145]
	v_ashrrev_i32_e32 v149, 31, v148
	v_add_f32_e32 v145, v142, v143
	v_lshlrev_b64 v[142:143], 9, v[148:149]
	v_lshl_add_u64 v[142:143], v[128:129], 0, v[142:143]
	v_cvt_pk_bf16_f32 v144, v131, v134
	v_cvt_pk_bf16_f32 v145, v152, v145
	global_store_dwordx2 v[142:143], v[144:145], off nt
	v_add_u32_e32 v142, 64, v130
	global_load_dwordx2 v[146:147], v[138:139], off
	global_load_dwordx2 v[150:151], v[138:139], off offset:256
	ds_bpermute_b32 v131, v141, v60
	v_mov_b32_e32 v144, v60
	ds_bpermute_b32 v134, v141, v56
	ds_bpermute_b32 v143, v141, v52
	ds_bpermute_b32 v148, v141, v48
	s_waitcnt lgkmcnt(3)
	v_mul_f32_e32 v145, v140, v131
	ds_bpermute_b32 v152, v141, v49
	s_waitcnt vmcnt(1)
	v_pk_mul_f32 v[144:145], v[144:145], v[146:147]
	global_load_dwordx2 v[146:147], v[138:139], off offset:16
	v_add_f32_e32 v131, v144, v145
	s_waitcnt lgkmcnt(3)
	v_mul_f32_e32 v145, v140, v134
	v_mov_b32_e32 v144, v56
	s_waitcnt vmcnt(0)
	v_pk_mul_f32 v[144:145], v[144:145], v[146:147]
	global_load_dwordx2 v[146:147], v[138:139], off offset:32
	v_add_f32_e32 v134, v144, v145
	s_waitcnt lgkmcnt(2)
	v_mul_f32_e32 v145, v140, v143
	v_mov_b32_e32 v144, v52
	v_ashrrev_i32_e32 v143, 31, v142
	v_lshlrev_b64 v[142:143], 9, v[142:143]
	v_lshl_add_u64 v[142:143], v[128:129], 0, v[142:143]
	s_waitcnt vmcnt(0)
	v_pk_mul_f32 v[144:145], v[144:145], v[146:147]
	global_load_dwordx2 v[146:147], v[138:139], off offset:48
	v_add_f32_e32 v149, v144, v145
	s_waitcnt lgkmcnt(1)
	v_mul_f32_e32 v145, v140, v148
	v_mov_b32_e32 v144, v48
	v_mov_b32_e32 v148, v61
	s_waitcnt vmcnt(0)
	v_pk_mul_f32 v[144:145], v[144:145], v[146:147]
	s_nop 0
	v_add_f32_e32 v145, v144, v145
	v_cvt_pk_bf16_f32 v144, v131, v134
	ds_bpermute_b32 v131, v141, v61
	v_cvt_pk_bf16_f32 v145, v149, v145
	ds_bpermute_b32 v134, v141, v57
	ds_bpermute_b32 v147, v141, v53
	v_add_u32_e32 v146, 0x41, v130
	s_waitcnt lgkmcnt(2)
	v_mul_f32_e32 v149, v140, v131
	v_pk_mul_f32 v[148:149], v[148:149], v[150:151]
	global_load_dwordx2 v[150:151], v[138:139], off offset:272
	v_add_f32_e32 v131, v148, v149
	s_waitcnt lgkmcnt(1)
	v_mul_f32_e32 v149, v140, v134
	v_mov_b32_e32 v148, v57
	s_waitcnt vmcnt(0)
	v_pk_mul_f32 v[148:149], v[148:149], v[150:151]
	global_load_dwordx2 v[150:151], v[138:139], off offset:288
	v_add_f32_e32 v134, v148, v149
	s_waitcnt lgkmcnt(0)
	v_mul_f32_e32 v149, v140, v147
	v_mov_b32_e32 v148, v53
	s_waitcnt vmcnt(0)
	v_pk_mul_f32 v[148:149], v[148:149], v[150:151]
	global_load_dwordx2 v[150:151], v[138:139], off offset:304
	v_add_f32_e32 v153, v148, v149
	v_mul_f32_e32 v149, v140, v152
	global_store_dwordx2 v[142:143], v[144:145], off nt
	v_mov_b32_e32 v148, v49
	s_waitcnt vmcnt(1)
	v_pk_mul_f32 v[142:143], v[148:149], v[150:151]
	v_ashrrev_i32_e32 v147, 31, v146
	v_add_f32_e32 v145, v142, v143
	v_lshlrev_b64 v[142:143], 9, v[146:147]
	v_lshl_add_u64 v[142:143], v[128:129], 0, v[142:143]
	v_cvt_pk_bf16_f32 v144, v131, v134
	v_cvt_pk_bf16_f32 v145, v153, v145
	global_store_dwordx2 v[142:143], v[144:145], off nt
	v_add_u32_e32 v142, 0x42, v130
	v_lshlrev_b32_e32 v131, 5, v142
	v_and_or_b32 v131, v131, s23, v137
	v_lshlrev_b32_e32 v134, 3, v131
	v_lshl_add_u64 v[144:145], s[58:59], 0, v[134:135]
	v_add_co_u32_e32 v144, vcc, s33, v144
	ds_bpermute_b32 v131, v141, v62
	s_nop 0
	v_addc_co_u32_e32 v145, vcc, 0, v145, vcc
	global_load_dwordx2 v[148:149], v[144:145], off
	global_load_dwordx2 v[152:153], v[144:145], off offset:256
	s_waitcnt lgkmcnt(0)
	v_mul_f32_e32 v147, v140, v131
	v_mov_b32_e32 v146, v62
	ds_bpermute_b32 v134, v141, v58
	ds_bpermute_b32 v143, v141, v54
	ds_bpermute_b32 v150, v141, v50
	ds_bpermute_b32 v154, v141, v51
	s_waitcnt vmcnt(1)
	v_pk_mul_f32 v[146:147], v[146:147], v[148:149]
	global_load_dwordx2 v[148:149], v[144:145], off offset:16
	v_add_f32_e32 v131, v146, v147
	s_waitcnt lgkmcnt(3)
	v_mul_f32_e32 v147, v140, v134
	v_mov_b32_e32 v146, v58
	s_waitcnt vmcnt(0)
	v_pk_mul_f32 v[146:147], v[146:147], v[148:149]
	global_load_dwordx2 v[148:149], v[144:145], off offset:32
	v_add_f32_e32 v134, v146, v147
	s_waitcnt lgkmcnt(2)
	v_mul_f32_e32 v147, v140, v143
	v_mov_b32_e32 v146, v54
	v_ashrrev_i32_e32 v143, 31, v142
	v_lshlrev_b64 v[142:143], 9, v[142:143]
	v_lshl_add_u64 v[142:143], v[128:129], 0, v[142:143]
	s_waitcnt vmcnt(0)
	v_pk_mul_f32 v[146:147], v[146:147], v[148:149]
	global_load_dwordx2 v[148:149], v[144:145], off offset:48
	v_add_f32_e32 v151, v146, v147
	s_waitcnt lgkmcnt(1)
	v_mul_f32_e32 v147, v140, v150
	v_mov_b32_e32 v146, v50
	v_mov_b32_e32 v150, v63
	s_waitcnt vmcnt(0)
	v_pk_mul_f32 v[146:147], v[146:147], v[148:149]
	s_nop 0
	v_add_f32_e32 v147, v146, v147
	v_cvt_pk_bf16_f32 v146, v131, v134
	ds_bpermute_b32 v131, v141, v63
	v_cvt_pk_bf16_f32 v147, v151, v147
	ds_bpermute_b32 v134, v141, v59
	ds_bpermute_b32 v149, v141, v55
	v_add_u32_e32 v148, 0x43, v130
	s_waitcnt lgkmcnt(2)
	v_mul_f32_e32 v151, v140, v131
	v_pk_mul_f32 v[150:151], v[150:151], v[152:153]
	global_load_dwordx2 v[152:153], v[144:145], off offset:272
	v_add_f32_e32 v131, v150, v151
	s_waitcnt lgkmcnt(1)
	v_mul_f32_e32 v151, v140, v134
	v_mov_b32_e32 v150, v59
	s_waitcnt vmcnt(0)
	v_pk_mul_f32 v[150:151], v[150:151], v[152:153]
	global_load_dwordx2 v[152:153], v[144:145], off offset:288
	v_add_f32_e32 v134, v150, v151
	global_load_dwordx2 v[144:145], v[144:145], off offset:304
	s_waitcnt lgkmcnt(0)
	v_mul_f32_e32 v151, v140, v149
	v_mov_b32_e32 v150, v55
	global_store_dwordx2 v[142:143], v[146:147], off nt
	s_waitcnt vmcnt(2)
	v_pk_mul_f32 v[150:151], v[150:151], v[152:153]
	s_nop 0
	v_add_f32_e32 v152, v150, v151
	v_mul_f32_e32 v151, v140, v154
	v_mov_b32_e32 v150, v51
	s_waitcnt vmcnt(1)
	v_pk_mul_f32 v[142:143], v[150:151], v[144:145]
	v_ashrrev_i32_e32 v149, 31, v148
	v_add_f32_e32 v145, v142, v143
	v_lshlrev_b64 v[142:143], 9, v[148:149]
	v_lshl_add_u64 v[142:143], v[128:129], 0, v[142:143]
	v_cvt_pk_bf16_f32 v144, v131, v134
	v_cvt_pk_bf16_f32 v145, v152, v145
	global_store_dwordx2 v[142:143], v[144:145], off nt
	v_add_u32_e32 v142, 0x50, v130
	v_lshlrev_b32_e32 v131, 5, v142
	v_and_or_b32 v131, v131, s24, v137
	v_lshlrev_b32_e32 v134, 3, v131
	v_lshl_add_u64 v[144:145], s[58:59], 0, v[134:135]
	v_add_co_u32_e32 v144, vcc, s33, v144
	ds_bpermute_b32 v131, v141, v44
	s_nop 0
	v_addc_co_u32_e32 v145, vcc, 0, v145, vcc
	global_load_dwordx2 v[148:149], v[144:145], off
	global_load_dwordx2 v[152:153], v[144:145], off offset:256
	s_waitcnt lgkmcnt(0)
	v_mul_f32_e32 v147, v140, v131
	v_mov_b32_e32 v146, v44
	ds_bpermute_b32 v134, v141, v40
	ds_bpermute_b32 v143, v141, v36
	ds_bpermute_b32 v150, v141, v32
	ds_bpermute_b32 v154, v141, v33
	s_waitcnt vmcnt(1)
	v_pk_mul_f32 v[146:147], v[146:147], v[148:149]
	global_load_dwordx2 v[148:149], v[144:145], off offset:16
	v_add_f32_e32 v131, v146, v147
	s_waitcnt lgkmcnt(3)
	v_mul_f32_e32 v147, v140, v134
	v_mov_b32_e32 v146, v40
	s_waitcnt vmcnt(0)
	v_pk_mul_f32 v[146:147], v[146:147], v[148:149]
	global_load_dwordx2 v[148:149], v[144:145], off offset:32
	v_add_f32_e32 v134, v146, v147
	s_waitcnt lgkmcnt(2)
	v_mul_f32_e32 v147, v140, v143
	v_mov_b32_e32 v146, v36
	v_ashrrev_i32_e32 v143, 31, v142
	v_lshlrev_b64 v[142:143], 9, v[142:143]
	v_lshl_add_u64 v[142:143], v[128:129], 0, v[142:143]
	s_waitcnt vmcnt(0)
	v_pk_mul_f32 v[146:147], v[146:147], v[148:149]
	global_load_dwordx2 v[148:149], v[144:145], off offset:48
	v_add_f32_e32 v151, v146, v147
	s_waitcnt lgkmcnt(1)
	v_mul_f32_e32 v147, v140, v150
	v_mov_b32_e32 v146, v32
	v_mov_b32_e32 v150, v45
	s_waitcnt vmcnt(0)
	v_pk_mul_f32 v[146:147], v[146:147], v[148:149]
	s_nop 0
	v_add_f32_e32 v147, v146, v147
	v_cvt_pk_bf16_f32 v146, v131, v134
	ds_bpermute_b32 v131, v141, v45
	v_cvt_pk_bf16_f32 v147, v151, v147
	ds_bpermute_b32 v134, v141, v41
	ds_bpermute_b32 v149, v141, v37
	v_add_u32_e32 v148, 0x51, v130
	s_waitcnt lgkmcnt(2)
	v_mul_f32_e32 v151, v140, v131
	v_pk_mul_f32 v[150:151], v[150:151], v[152:153]
	global_load_dwordx2 v[152:153], v[144:145], off offset:272
	v_add_f32_e32 v131, v150, v151
	s_waitcnt lgkmcnt(1)
	v_mul_f32_e32 v151, v140, v134
	v_mov_b32_e32 v150, v41
	s_waitcnt vmcnt(0)
	v_pk_mul_f32 v[150:151], v[150:151], v[152:153]
	global_load_dwordx2 v[152:153], v[144:145], off offset:288
	v_add_f32_e32 v134, v150, v151
	global_load_dwordx2 v[144:145], v[144:145], off offset:304
	s_waitcnt lgkmcnt(0)
	v_mul_f32_e32 v151, v140, v149
	v_mov_b32_e32 v150, v37
	global_store_dwordx2 v[142:143], v[146:147], off nt
	s_waitcnt vmcnt(2)
	v_pk_mul_f32 v[150:151], v[150:151], v[152:153]
	s_nop 0
	v_add_f32_e32 v152, v150, v151
	v_mul_f32_e32 v151, v140, v154
	v_mov_b32_e32 v150, v33
	s_waitcnt vmcnt(1)
	v_pk_mul_f32 v[142:143], v[150:151], v[144:145]
	v_ashrrev_i32_e32 v149, 31, v148
	v_add_f32_e32 v145, v142, v143
	v_lshlrev_b64 v[142:143], 9, v[148:149]
	v_lshl_add_u64 v[142:143], v[128:129], 0, v[142:143]
	v_cvt_pk_bf16_f32 v144, v131, v134
	v_cvt_pk_bf16_f32 v145, v152, v145
	global_store_dwordx2 v[142:143], v[144:145], off nt
	v_add_u32_e32 v142, 0x52, v130
	v_lshlrev_b32_e32 v131, 5, v142
	v_and_or_b32 v131, v131, s23, v137
	v_lshlrev_b32_e32 v134, 3, v131
	v_lshl_add_u64 v[144:145], s[58:59], 0, v[134:135]
	v_add_co_u32_e32 v144, vcc, s33, v144
	ds_bpermute_b32 v131, v141, v46
	s_nop 0
	v_addc_co_u32_e32 v145, vcc, 0, v145, vcc
	global_load_dwordx2 v[148:149], v[144:145], off
	global_load_dwordx2 v[152:153], v[144:145], off offset:256
	s_waitcnt lgkmcnt(0)
	v_mul_f32_e32 v147, v140, v131
	v_mov_b32_e32 v146, v46
	ds_bpermute_b32 v134, v141, v42
	ds_bpermute_b32 v143, v141, v38
	ds_bpermute_b32 v150, v141, v34
	ds_bpermute_b32 v154, v141, v35
	s_waitcnt vmcnt(1)
	v_pk_mul_f32 v[146:147], v[146:147], v[148:149]
	global_load_dwordx2 v[148:149], v[144:145], off offset:16
	v_add_f32_e32 v131, v146, v147
	s_waitcnt lgkmcnt(3)
	v_mul_f32_e32 v147, v140, v134
	v_mov_b32_e32 v146, v42
	s_waitcnt vmcnt(0)
	v_pk_mul_f32 v[146:147], v[146:147], v[148:149]
	global_load_dwordx2 v[148:149], v[144:145], off offset:32
	v_add_f32_e32 v134, v146, v147
	s_waitcnt lgkmcnt(2)
	v_mul_f32_e32 v147, v140, v143
	v_mov_b32_e32 v146, v38
	v_ashrrev_i32_e32 v143, 31, v142
	v_lshlrev_b64 v[142:143], 9, v[142:143]
	v_lshl_add_u64 v[142:143], v[128:129], 0, v[142:143]
	s_waitcnt vmcnt(0)
	v_pk_mul_f32 v[146:147], v[146:147], v[148:149]
	global_load_dwordx2 v[148:149], v[144:145], off offset:48
	v_add_f32_e32 v151, v146, v147
	s_waitcnt lgkmcnt(1)
	v_mul_f32_e32 v147, v140, v150
	v_mov_b32_e32 v146, v34
	v_mov_b32_e32 v150, v47
	s_waitcnt vmcnt(0)
	v_pk_mul_f32 v[146:147], v[146:147], v[148:149]
	s_nop 0
	v_add_f32_e32 v147, v146, v147
	v_cvt_pk_bf16_f32 v146, v131, v134
	ds_bpermute_b32 v131, v141, v47
	v_cvt_pk_bf16_f32 v147, v151, v147
	ds_bpermute_b32 v134, v141, v43
	ds_bpermute_b32 v149, v141, v39
	v_add_u32_e32 v148, 0x53, v130
	s_waitcnt lgkmcnt(2)
	v_mul_f32_e32 v151, v140, v131
	v_pk_mul_f32 v[150:151], v[150:151], v[152:153]
	global_load_dwordx2 v[152:153], v[144:145], off offset:272
	v_add_f32_e32 v131, v150, v151
	s_waitcnt lgkmcnt(1)
	v_mul_f32_e32 v151, v140, v134
	v_mov_b32_e32 v150, v43
	s_waitcnt vmcnt(0)
	v_pk_mul_f32 v[150:151], v[150:151], v[152:153]
	global_load_dwordx2 v[152:153], v[144:145], off offset:288
	v_add_f32_e32 v134, v150, v151
	global_load_dwordx2 v[144:145], v[144:145], off offset:304
	s_waitcnt lgkmcnt(0)
	v_mul_f32_e32 v151, v140, v149
	v_mov_b32_e32 v150, v39
	global_store_dwordx2 v[142:143], v[146:147], off nt
	s_waitcnt vmcnt(2)
	v_pk_mul_f32 v[150:151], v[150:151], v[152:153]
	s_nop 0
	v_add_f32_e32 v152, v150, v151
	v_mul_f32_e32 v151, v140, v154
	v_mov_b32_e32 v150, v35
	s_waitcnt vmcnt(1)
	v_pk_mul_f32 v[142:143], v[150:151], v[144:145]
	v_ashrrev_i32_e32 v149, 31, v148
	v_add_f32_e32 v145, v142, v143
	v_lshlrev_b64 v[142:143], 9, v[148:149]
	v_lshl_add_u64 v[142:143], v[128:129], 0, v[142:143]
	v_cvt_pk_bf16_f32 v144, v131, v134
	v_cvt_pk_bf16_f32 v145, v152, v145
	global_store_dwordx2 v[142:143], v[144:145], off nt
	v_add_u32_e32 v142, 0x60, v130
	global_load_dwordx2 v[146:147], v[138:139], off
	global_load_dwordx2 v[150:151], v[138:139], off offset:256
	ds_bpermute_b32 v131, v141, v28
	v_mov_b32_e32 v144, v28
	ds_bpermute_b32 v134, v141, v24
	ds_bpermute_b32 v143, v141, v20
	ds_bpermute_b32 v148, v141, v16
	s_waitcnt lgkmcnt(3)
	v_mul_f32_e32 v145, v140, v131
	ds_bpermute_b32 v152, v141, v17
	s_waitcnt vmcnt(1)
	v_pk_mul_f32 v[144:145], v[144:145], v[146:147]
	global_load_dwordx2 v[146:147], v[138:139], off offset:16
	v_add_f32_e32 v131, v144, v145
	s_waitcnt lgkmcnt(3)
	v_mul_f32_e32 v145, v140, v134
	v_mov_b32_e32 v144, v24
	s_waitcnt vmcnt(0)
	v_pk_mul_f32 v[144:145], v[144:145], v[146:147]
	global_load_dwordx2 v[146:147], v[138:139], off offset:32
	v_add_f32_e32 v134, v144, v145
	s_waitcnt lgkmcnt(2)
	v_mul_f32_e32 v145, v140, v143
	v_mov_b32_e32 v144, v20
	v_ashrrev_i32_e32 v143, 31, v142
	v_lshlrev_b64 v[142:143], 9, v[142:143]
	v_lshl_add_u64 v[142:143], v[128:129], 0, v[142:143]
	s_waitcnt vmcnt(0)
	v_pk_mul_f32 v[144:145], v[144:145], v[146:147]
	global_load_dwordx2 v[146:147], v[138:139], off offset:48
	v_add_f32_e32 v149, v144, v145
	s_waitcnt lgkmcnt(1)
	v_mul_f32_e32 v145, v140, v148
	v_mov_b32_e32 v144, v16
	v_mov_b32_e32 v148, v29
	s_waitcnt vmcnt(0)
	v_pk_mul_f32 v[144:145], v[144:145], v[146:147]
	s_nop 0
	v_add_f32_e32 v145, v144, v145
	v_cvt_pk_bf16_f32 v144, v131, v134
	ds_bpermute_b32 v131, v141, v29
	v_cvt_pk_bf16_f32 v145, v149, v145
	ds_bpermute_b32 v134, v141, v25
	ds_bpermute_b32 v147, v141, v21
	v_add_u32_e32 v146, 0x61, v130
	s_waitcnt lgkmcnt(2)
	v_mul_f32_e32 v149, v140, v131
	v_pk_mul_f32 v[148:149], v[148:149], v[150:151]
	global_load_dwordx2 v[150:151], v[138:139], off offset:272
	v_add_f32_e32 v131, v148, v149
	s_waitcnt lgkmcnt(1)
	v_mul_f32_e32 v149, v140, v134
	v_mov_b32_e32 v148, v25
	s_waitcnt vmcnt(0)
	v_pk_mul_f32 v[148:149], v[148:149], v[150:151]
	global_load_dwordx2 v[150:151], v[138:139], off offset:288
	v_add_f32_e32 v134, v148, v149
	global_load_dwordx2 v[138:139], v[138:139], off offset:304
	s_waitcnt lgkmcnt(0)
	v_mul_f32_e32 v149, v140, v147
	v_mov_b32_e32 v148, v21
	global_store_dwordx2 v[142:143], v[144:145], off nt
	s_waitcnt vmcnt(2)
	v_pk_mul_f32 v[148:149], v[148:149], v[150:151]
	s_nop 0
	v_add_f32_e32 v150, v148, v149
	v_mul_f32_e32 v149, v140, v152
	v_mov_b32_e32 v148, v17
	s_waitcnt vmcnt(1)
	v_pk_mul_f32 v[138:139], v[148:149], v[138:139]
	v_ashrrev_i32_e32 v147, 31, v146
	v_add_f32_e32 v143, v138, v139
	v_lshlrev_b64 v[138:139], 9, v[146:147]
	v_lshl_add_u64 v[138:139], v[128:129], 0, v[138:139]
	v_cvt_pk_bf16_f32 v142, v131, v134
	v_cvt_pk_bf16_f32 v143, v150, v143
	global_store_dwordx2 v[138:139], v[142:143], off nt
	v_add_u32_e32 v138, 0x62, v130
	v_lshlrev_b32_e32 v131, 5, v138
	v_and_or_b32 v131, v131, s23, v137
	v_lshlrev_b32_e32 v134, 3, v131
	v_lshl_add_u64 v[142:143], s[58:59], 0, v[134:135]
	v_add_co_u32_e32 v142, vcc, s33, v142
	ds_bpermute_b32 v131, v141, v30
	s_nop 0
	v_addc_co_u32_e32 v143, vcc, 0, v143, vcc
	global_load_dwordx2 v[146:147], v[142:143], off
	global_load_dwordx2 v[150:151], v[142:143], off offset:256
	s_waitcnt lgkmcnt(0)
	v_mul_f32_e32 v145, v140, v131
	v_mov_b32_e32 v144, v30
	ds_bpermute_b32 v134, v141, v26
	ds_bpermute_b32 v139, v141, v22
	ds_bpermute_b32 v148, v141, v18
	ds_bpermute_b32 v152, v141, v19
	s_waitcnt vmcnt(1)
	v_pk_mul_f32 v[144:145], v[144:145], v[146:147]
	global_load_dwordx2 v[146:147], v[142:143], off offset:16
	v_add_f32_e32 v131, v144, v145
	s_waitcnt lgkmcnt(3)
	v_mul_f32_e32 v145, v140, v134
	v_mov_b32_e32 v144, v26
	s_waitcnt vmcnt(0)
	v_pk_mul_f32 v[144:145], v[144:145], v[146:147]
	global_load_dwordx2 v[146:147], v[142:143], off offset:32
	v_add_f32_e32 v134, v144, v145
	s_waitcnt lgkmcnt(2)
	v_mul_f32_e32 v145, v140, v139
	v_mov_b32_e32 v144, v22
	v_ashrrev_i32_e32 v139, 31, v138
	v_lshlrev_b64 v[138:139], 9, v[138:139]
	v_lshl_add_u64 v[138:139], v[128:129], 0, v[138:139]
	s_waitcnt vmcnt(0)
	v_pk_mul_f32 v[144:145], v[144:145], v[146:147]
	global_load_dwordx2 v[146:147], v[142:143], off offset:48
	v_add_f32_e32 v149, v144, v145
	s_waitcnt lgkmcnt(1)
	v_mul_f32_e32 v145, v140, v148
	v_mov_b32_e32 v144, v18
	v_mov_b32_e32 v148, v31
	s_waitcnt vmcnt(0)
	v_pk_mul_f32 v[144:145], v[144:145], v[146:147]
	s_nop 0
	v_add_f32_e32 v145, v144, v145
	v_cvt_pk_bf16_f32 v144, v131, v134
	ds_bpermute_b32 v131, v141, v31
	v_cvt_pk_bf16_f32 v145, v149, v145
	ds_bpermute_b32 v134, v141, v27
	ds_bpermute_b32 v147, v141, v23
	v_add_u32_e32 v146, 0x63, v130
	s_waitcnt lgkmcnt(2)
	v_mul_f32_e32 v149, v140, v131
	v_pk_mul_f32 v[148:149], v[148:149], v[150:151]
	global_load_dwordx2 v[150:151], v[142:143], off offset:272
	v_add_f32_e32 v131, v148, v149
	s_waitcnt lgkmcnt(1)
	v_mul_f32_e32 v149, v140, v134
	v_mov_b32_e32 v148, v27
	s_waitcnt vmcnt(0)
	v_pk_mul_f32 v[148:149], v[148:149], v[150:151]
	global_load_dwordx2 v[150:151], v[142:143], off offset:288
	v_add_f32_e32 v134, v148, v149
	global_load_dwordx2 v[142:143], v[142:143], off offset:304
	s_waitcnt lgkmcnt(0)
	v_mul_f32_e32 v149, v140, v147
	v_mov_b32_e32 v148, v23
	global_store_dwordx2 v[138:139], v[144:145], off nt
	s_waitcnt vmcnt(2)
	v_pk_mul_f32 v[148:149], v[148:149], v[150:151]
	s_nop 0
	v_add_f32_e32 v150, v148, v149
	v_mul_f32_e32 v149, v140, v152
	v_mov_b32_e32 v148, v19
	s_waitcnt vmcnt(1)
	v_pk_mul_f32 v[138:139], v[148:149], v[142:143]
	v_ashrrev_i32_e32 v147, 31, v146
	v_add_f32_e32 v143, v138, v139
	v_lshlrev_b64 v[138:139], 9, v[146:147]
	v_lshl_add_u64 v[138:139], v[128:129], 0, v[138:139]
	v_cvt_pk_bf16_f32 v142, v131, v134
	v_cvt_pk_bf16_f32 v143, v150, v143
	global_store_dwordx2 v[138:139], v[142:143], off nt
	v_add_u32_e32 v138, 0x70, v130
	v_lshlrev_b32_e32 v131, 5, v138
	v_and_or_b32 v131, v131, s24, v137
	v_lshlrev_b32_e32 v134, 3, v131
	v_lshl_add_u64 v[142:143], s[58:59], 0, v[134:135]
	v_add_co_u32_e32 v142, vcc, s33, v142
	ds_bpermute_b32 v131, v141, v12
	s_nop 0
	v_addc_co_u32_e32 v143, vcc, 0, v143, vcc
	global_load_dwordx2 v[146:147], v[142:143], off
	global_load_dwordx2 v[150:151], v[142:143], off offset:256
	s_waitcnt lgkmcnt(0)
	v_mul_f32_e32 v145, v140, v131
	v_mov_b32_e32 v144, v12
	ds_bpermute_b32 v134, v141, v8
	ds_bpermute_b32 v139, v141, v4
	ds_bpermute_b32 v148, v141, v0
	ds_bpermute_b32 v152, v141, v1
	s_waitcnt vmcnt(1)
	v_pk_mul_f32 v[144:145], v[144:145], v[146:147]
	global_load_dwordx2 v[146:147], v[142:143], off offset:16
	v_add_f32_e32 v131, v144, v145
	s_waitcnt lgkmcnt(3)
	v_mul_f32_e32 v145, v140, v134
	v_mov_b32_e32 v144, v8
	s_waitcnt vmcnt(0)
	v_pk_mul_f32 v[144:145], v[144:145], v[146:147]
	global_load_dwordx2 v[146:147], v[142:143], off offset:32
	v_add_f32_e32 v134, v144, v145
	s_waitcnt lgkmcnt(2)
	v_mul_f32_e32 v145, v140, v139
	v_mov_b32_e32 v144, v4
	v_ashrrev_i32_e32 v139, 31, v138
	v_lshlrev_b64 v[138:139], 9, v[138:139]
	v_lshl_add_u64 v[138:139], v[128:129], 0, v[138:139]
	s_waitcnt vmcnt(0)
	v_pk_mul_f32 v[144:145], v[144:145], v[146:147]
	global_load_dwordx2 v[146:147], v[142:143], off offset:48
	v_add_f32_e32 v149, v144, v145
	s_waitcnt lgkmcnt(1)
	v_mul_f32_e32 v145, v140, v148
	v_mov_b32_e32 v144, v0
	v_mov_b32_e32 v148, v13
	s_waitcnt vmcnt(0)
	v_pk_mul_f32 v[144:145], v[144:145], v[146:147]
	s_nop 0
	v_add_f32_e32 v145, v144, v145
	v_cvt_pk_bf16_f32 v144, v131, v134
	ds_bpermute_b32 v131, v141, v13
	v_cvt_pk_bf16_f32 v145, v149, v145
	ds_bpermute_b32 v134, v141, v9
	ds_bpermute_b32 v147, v141, v5
	v_add_u32_e32 v146, 0x71, v130
	s_waitcnt lgkmcnt(2)
	v_mul_f32_e32 v149, v140, v131
	v_pk_mul_f32 v[148:149], v[148:149], v[150:151]
	global_load_dwordx2 v[150:151], v[142:143], off offset:272
	v_add_f32_e32 v131, v148, v149
	s_waitcnt lgkmcnt(1)
	v_mul_f32_e32 v149, v140, v134
	v_mov_b32_e32 v148, v9
	s_waitcnt vmcnt(0)
	v_pk_mul_f32 v[148:149], v[148:149], v[150:151]
	global_load_dwordx2 v[150:151], v[142:143], off offset:288
	v_add_f32_e32 v134, v148, v149
	global_load_dwordx2 v[142:143], v[142:143], off offset:304
	s_waitcnt lgkmcnt(0)
	v_mul_f32_e32 v149, v140, v147
	v_mov_b32_e32 v148, v5
	global_store_dwordx2 v[138:139], v[144:145], off nt
	s_waitcnt vmcnt(2)
	v_pk_mul_f32 v[148:149], v[148:149], v[150:151]
	s_nop 0
	v_add_f32_e32 v150, v148, v149
	v_mul_f32_e32 v149, v140, v152
	v_mov_b32_e32 v148, v1
	s_waitcnt vmcnt(1)
	v_pk_mul_f32 v[138:139], v[148:149], v[142:143]
	v_ashrrev_i32_e32 v147, 31, v146
	v_add_f32_e32 v143, v138, v139
	v_lshlrev_b64 v[138:139], 9, v[146:147]
	v_lshl_add_u64 v[138:139], v[128:129], 0, v[138:139]
	v_cvt_pk_bf16_f32 v142, v131, v134
	v_cvt_pk_bf16_f32 v143, v150, v143
	global_store_dwordx2 v[138:139], v[142:143], off nt
	v_add_u32_e32 v138, 0x72, v130
	v_lshlrev_b32_e32 v131, 5, v138
	v_and_or_b32 v131, v131, s23, v137
	v_lshlrev_b32_e32 v134, 3, v131
	v_lshl_add_u64 v[142:143], s[58:59], 0, v[134:135]
	v_add_co_u32_e32 v142, vcc, s33, v142
	ds_bpermute_b32 v131, v141, v14
	s_nop 0
	v_addc_co_u32_e32 v143, vcc, 0, v143, vcc
	global_load_dwordx2 v[146:147], v[142:143], off
	global_load_dwordx2 v[148:149], v[142:143], off offset:256
	s_waitcnt lgkmcnt(0)
	v_mul_f32_e32 v145, v140, v131
	v_mov_b32_e32 v144, v14
	ds_bpermute_b32 v134, v141, v10
	ds_bpermute_b32 v137, v141, v6
	ds_bpermute_b32 v139, v141, v2
	v_add_u32_e32 v130, 0x73, v130
	s_waitcnt vmcnt(1)
	v_pk_mul_f32 v[144:145], v[144:145], v[146:147]
	global_load_dwordx2 v[146:147], v[142:143], off offset:16
	v_add_f32_e32 v131, v144, v145
	s_waitcnt lgkmcnt(2)
	v_mul_f32_e32 v145, v140, v134
	v_mov_b32_e32 v144, v10
	s_waitcnt vmcnt(0)
	v_pk_mul_f32 v[144:145], v[144:145], v[146:147]
	global_load_dwordx2 v[146:147], v[142:143], off offset:32
	v_add_f32_e32 v134, v144, v145
	s_waitcnt lgkmcnt(1)
	v_mul_f32_e32 v145, v140, v137
	v_mov_b32_e32 v144, v6
	s_waitcnt vmcnt(0)
	v_pk_mul_f32 v[144:145], v[144:145], v[146:147]
	global_load_dwordx2 v[146:147], v[142:143], off offset:48
	v_add_f32_e32 v137, v144, v145
	s_waitcnt lgkmcnt(0)
	v_mul_f32_e32 v145, v140, v139
	v_mov_b32_e32 v144, v2
	v_ashrrev_i32_e32 v139, 31, v138
	v_lshlrev_b64 v[138:139], 9, v[138:139]
	v_lshl_add_u64 v[138:139], v[128:129], 0, v[138:139]
	s_waitcnt vmcnt(0)
	v_pk_mul_f32 v[144:145], v[144:145], v[146:147]
	s_nop 0
	v_add_f32_e32 v145, v144, v145
	v_cvt_pk_bf16_f32 v144, v131, v134
	ds_bpermute_b32 v131, v141, v15
	v_mov_b32_e32 v146, v15
	ds_bpermute_b32 v134, v141, v11
	v_cvt_pk_bf16_f32 v145, v137, v145
	ds_bpermute_b32 v137, v141, v7
	s_waitcnt lgkmcnt(2)
	v_mul_f32_e32 v147, v140, v131
	v_pk_mul_f32 v[146:147], v[146:147], v[148:149]
	global_load_dwordx2 v[148:149], v[142:143], off offset:272
	v_add_f32_e32 v150, v146, v147
	s_waitcnt lgkmcnt(1)
	v_mul_f32_e32 v147, v140, v134
	v_mov_b32_e32 v146, v11
	ds_bpermute_b32 v141, v141, v3
	s_waitcnt lgkmcnt(0)
	v_mul_f32_e32 v141, v140, v141
	s_waitcnt vmcnt(0)
	v_pk_mul_f32 v[146:147], v[146:147], v[148:149]
	global_load_dwordx2 v[148:149], v[142:143], off offset:288
	v_add_f32_e32 v134, v146, v147
	global_load_dwordx2 v[142:143], v[142:143], off offset:304
	v_mul_f32_e32 v147, v140, v137
	v_mov_b32_e32 v146, v7
	global_store_dwordx2 v[138:139], v[144:145], off nt
	s_waitcnt vmcnt(2)
	v_pk_mul_f32 v[146:147], v[146:147], v[148:149]
	s_nop 0
	v_add_f32_e32 v137, v146, v147
	v_ashrrev_i32_e32 v131, 31, v130
	v_mov_b32_e32 v140, v3
	v_lshlrev_b64 v[130:131], 9, v[130:131]
	s_waitcnt vmcnt(1)
	v_pk_mul_f32 v[138:139], v[140:141], v[142:143]
	v_lshl_add_u64 v[128:129], v[128:129], 0, v[130:131]
	v_add_f32_e32 v138, v138, v139
	v_cvt_pk_bf16_f32 v130, v150, v134
	v_cvt_pk_bf16_f32 v131, v137, v138
	global_store_dwordx2 v[128:129], v[130:131], off nt
	s_xor_b64 s[34:35], exec, -1

.LBB0_230:
	s_andn2_saveexec_b64 s[10:11], s[10:11]
	s_cbranch_execz .LBB0_232
	v_readlane_b32 s36, v253, 26
	v_ashrrev_i32_e32 v137, 31, v136
	v_readlane_b32 s44, v253, 34
	v_readlane_b32 s45, v253, 35
	v_lshl_add_u32 v128, v178, 2, v211
	v_readlane_b32 s37, v253, 27
	v_readlane_b32 s38, v253, 28
	v_readlane_b32 s39, v253, 29
	v_readlane_b32 s40, v253, 30
	v_readlane_b32 s41, v253, 31
	v_readlane_b32 s42, v253, 32
	v_readlane_b32 s43, v253, 33
	v_readlane_b32 s46, v253, 36
	v_readlane_b32 s47, v253, 37
	v_readlane_b32 s48, v253, 38
	v_readlane_b32 s49, v253, 39
	v_readlane_b32 s50, v253, 40
	v_readlane_b32 s51, v253, 41
	v_lshl_add_u64 v[130:131], v[136:137], 1, s[44:45]
	v_ashrrev_i32_e32 v129, 31, v128
	v_lshlrev_b64 v[138:139], 9, v[128:129]
	v_lshl_add_u64 v[138:139], v[130:131], 0, v[138:139]
	v_mul_f32_e32 v141, 0x3e38aa3b, v112
	v_mul_f32_e32 v129, 0x3e38aa3b, v124
	v_mul_f32_e32 v134, 0x3e38aa3b, v120
	v_mul_f32_e32 v137, 0x3e38aa3b, v116
	v_cvt_pk_bf16_f32 v140, v129, v134
	v_cvt_pk_bf16_f32 v141, v137, v141
	global_store_dwordx2 v[138:139], v[140:141], off nt
	v_or_b32_e32 v138, 1, v128
	v_ashrrev_i32_e32 v139, 31, v138
	v_lshlrev_b64 v[138:139], 9, v[138:139]
	v_lshl_add_u64 v[138:139], v[130:131], 0, v[138:139]
	v_mul_f32_e32 v141, 0x3e38aa3b, v113
	v_mul_f32_e32 v129, 0x3e38aa3b, v125
	v_mul_f32_e32 v134, 0x3e38aa3b, v121
	v_mul_f32_e32 v137, 0x3e38aa3b, v117
	v_cvt_pk_bf16_f32 v140, v129, v134
	v_cvt_pk_bf16_f32 v141, v137, v141
	global_store_dwordx2 v[138:139], v[140:141], off nt
	v_or_b32_e32 v138, 2, v128
	v_ashrrev_i32_e32 v139, 31, v138
	v_lshlrev_b64 v[138:139], 9, v[138:139]
	v_lshl_add_u64 v[138:139], v[130:131], 0, v[138:139]
	v_mul_f32_e32 v141, 0x3e38aa3b, v114
	v_mul_f32_e32 v129, 0x3e38aa3b, v126
	v_mul_f32_e32 v134, 0x3e38aa3b, v122
	v_mul_f32_e32 v137, 0x3e38aa3b, v118
	v_cvt_pk_bf16_f32 v140, v129, v134
	v_cvt_pk_bf16_f32 v141, v137, v141
	global_store_dwordx2 v[138:139], v[140:141], off nt
	v_or_b32_e32 v138, 3, v128
	v_ashrrev_i32_e32 v139, 31, v138
	v_lshlrev_b64 v[138:139], 9, v[138:139]
	v_lshl_add_u64 v[138:139], v[130:131], 0, v[138:139]
	v_mul_f32_e32 v141, 0x3e38aa3b, v115
	v_mul_f32_e32 v129, 0x3e38aa3b, v127
	v_mul_f32_e32 v134, 0x3e38aa3b, v123
	v_mul_f32_e32 v137, 0x3e38aa3b, v119
	v_cvt_pk_bf16_f32 v140, v129, v134
	v_cvt_pk_bf16_f32 v141, v137, v141
	global_store_dwordx2 v[138:139], v[140:141], off nt
	v_add_u32_e32 v138, 16, v128
	v_ashrrev_i32_e32 v139, 31, v138
	v_lshlrev_b64 v[138:139], 9, v[138:139]
	v_lshl_add_u64 v[138:139], v[130:131], 0, v[138:139]
	v_mul_f32_e32 v141, 0x3e38aa3b, v96
	v_mul_f32_e32 v129, 0x3e38aa3b, v108
	v_mul_f32_e32 v134, 0x3e38aa3b, v104
	v_mul_f32_e32 v137, 0x3e38aa3b, v100
	v_cvt_pk_bf16_f32 v140, v129, v134
	v_cvt_pk_bf16_f32 v141, v137, v141
	global_store_dwordx2 v[138:139], v[140:141], off nt
	v_add_u32_e32 v138, 17, v128
	v_ashrrev_i32_e32 v139, 31, v138
	v_lshlrev_b64 v[138:139], 9, v[138:139]
	v_lshl_add_u64 v[138:139], v[130:131], 0, v[138:139]
	v_mul_f32_e32 v141, 0x3e38aa3b, v97
	v_mul_f32_e32 v129, 0x3e38aa3b, v109
	v_mul_f32_e32 v134, 0x3e38aa3b, v105
	v_mul_f32_e32 v137, 0x3e38aa3b, v101
	v_cvt_pk_bf16_f32 v140, v129, v134
	v_cvt_pk_bf16_f32 v141, v137, v141
	global_store_dwordx2 v[138:139], v[140:141], off nt
	v_add_u32_e32 v138, 18, v128
	v_ashrrev_i32_e32 v139, 31, v138
	v_lshlrev_b64 v[138:139], 9, v[138:139]
	v_lshl_add_u64 v[138:139], v[130:131], 0, v[138:139]
	v_mul_f32_e32 v141, 0x3e38aa3b, v98
	v_mul_f32_e32 v129, 0x3e38aa3b, v110
	v_mul_f32_e32 v134, 0x3e38aa3b, v106
	v_mul_f32_e32 v137, 0x3e38aa3b, v102
	v_cvt_pk_bf16_f32 v140, v129, v134
	v_cvt_pk_bf16_f32 v141, v137, v141
	global_store_dwordx2 v[138:139], v[140:141], off nt
	v_add_u32_e32 v138, 19, v128
	v_ashrrev_i32_e32 v139, 31, v138
	v_lshlrev_b64 v[138:139], 9, v[138:139]
	v_lshl_add_u64 v[138:139], v[130:131], 0, v[138:139]
	v_mul_f32_e32 v141, 0x3e38aa3b, v99
	v_mul_f32_e32 v129, 0x3e38aa3b, v111
	v_mul_f32_e32 v134, 0x3e38aa3b, v107
	v_mul_f32_e32 v137, 0x3e38aa3b, v103
	v_cvt_pk_bf16_f32 v140, v129, v134
	v_cvt_pk_bf16_f32 v141, v137, v141
	global_store_dwordx2 v[138:139], v[140:141], off nt
	v_add_u32_e32 v138, 32, v128
	v_ashrrev_i32_e32 v139, 31, v138
	v_lshlrev_b64 v[138:139], 9, v[138:139]
	v_lshl_add_u64 v[138:139], v[130:131], 0, v[138:139]
	v_mul_f32_e32 v141, 0x3e38aa3b, v80
	v_mul_f32_e32 v129, 0x3e38aa3b, v92
	v_mul_f32_e32 v134, 0x3e38aa3b, v88
	v_mul_f32_e32 v137, 0x3e38aa3b, v84
	v_cvt_pk_bf16_f32 v140, v129, v134
	v_cvt_pk_bf16_f32 v141, v137, v141
	global_store_dwordx2 v[138:139], v[140:141], off nt
	v_add_u32_e32 v138, 33, v128
	v_ashrrev_i32_e32 v139, 31, v138
	v_lshlrev_b64 v[138:139], 9, v[138:139]
	v_lshl_add_u64 v[138:139], v[130:131], 0, v[138:139]
	v_mul_f32_e32 v141, 0x3e38aa3b, v81
	v_mul_f32_e32 v129, 0x3e38aa3b, v93
	v_mul_f32_e32 v134, 0x3e38aa3b, v89
	v_mul_f32_e32 v137, 0x3e38aa3b, v85
	v_cvt_pk_bf16_f32 v140, v129, v134
	v_cvt_pk_bf16_f32 v141, v137, v141
	global_store_dwordx2 v[138:139], v[140:141], off nt
	v_add_u32_e32 v138, 34, v128
	v_ashrrev_i32_e32 v139, 31, v138
	v_lshlrev_b64 v[138:139], 9, v[138:139]
	v_lshl_add_u64 v[138:139], v[130:131], 0, v[138:139]
	v_mul_f32_e32 v141, 0x3e38aa3b, v82
	v_mul_f32_e32 v129, 0x3e38aa3b, v94
	v_mul_f32_e32 v134, 0x3e38aa3b, v90
	v_mul_f32_e32 v137, 0x3e38aa3b, v86
	v_cvt_pk_bf16_f32 v140, v129, v134
	v_cvt_pk_bf16_f32 v141, v137, v141
	global_store_dwordx2 v[138:139], v[140:141], off nt
	v_add_u32_e32 v138, 35, v128
	v_ashrrev_i32_e32 v139, 31, v138
	v_lshlrev_b64 v[138:139], 9, v[138:139]
	v_lshl_add_u64 v[138:139], v[130:131], 0, v[138:139]
	v_mul_f32_e32 v141, 0x3e38aa3b, v83
	v_mul_f32_e32 v129, 0x3e38aa3b, v95
	v_mul_f32_e32 v134, 0x3e38aa3b, v91
	v_mul_f32_e32 v137, 0x3e38aa3b, v87
	v_cvt_pk_bf16_f32 v140, v129, v134
	v_cvt_pk_bf16_f32 v141, v137, v141
	global_store_dwordx2 v[138:139], v[140:141], off nt
	v_add_u32_e32 v138, 48, v128
	v_ashrrev_i32_e32 v139, 31, v138
	v_lshlrev_b64 v[138:139], 9, v[138:139]
	v_lshl_add_u64 v[138:139], v[130:131], 0, v[138:139]
	v_mul_f32_e32 v141, 0x3e38aa3b, v64
	v_mul_f32_e32 v129, 0x3e38aa3b, v76
	v_mul_f32_e32 v134, 0x3e38aa3b, v72
	v_mul_f32_e32 v137, 0x3e38aa3b, v68
	v_cvt_pk_bf16_f32 v140, v129, v134
	v_cvt_pk_bf16_f32 v141, v137, v141
	global_store_dwordx2 v[138:139], v[140:141], off nt
	v_add_u32_e32 v138, 49, v128
	v_ashrrev_i32_e32 v139, 31, v138
	v_lshlrev_b64 v[138:139], 9, v[138:139]
	v_lshl_add_u64 v[138:139], v[130:131], 0, v[138:139]
	v_mul_f32_e32 v141, 0x3e38aa3b, v65
	v_mul_f32_e32 v129, 0x3e38aa3b, v77
	v_mul_f32_e32 v134, 0x3e38aa3b, v73
	v_mul_f32_e32 v137, 0x3e38aa3b, v69
	v_cvt_pk_bf16_f32 v140, v129, v134
	v_cvt_pk_bf16_f32 v141, v137, v141
	global_store_dwordx2 v[138:139], v[140:141], off nt
	v_add_u32_e32 v138, 50, v128
	v_ashrrev_i32_e32 v139, 31, v138
	v_lshlrev_b64 v[138:139], 9, v[138:139]
	v_lshl_add_u64 v[138:139], v[130:131], 0, v[138:139]
	v_mul_f32_e32 v141, 0x3e38aa3b, v66
	v_mul_f32_e32 v129, 0x3e38aa3b, v78
	v_mul_f32_e32 v134, 0x3e38aa3b, v74
	v_mul_f32_e32 v137, 0x3e38aa3b, v70
	v_cvt_pk_bf16_f32 v140, v129, v134
	v_cvt_pk_bf16_f32 v141, v137, v141
	global_store_dwordx2 v[138:139], v[140:141], off nt
	v_add_u32_e32 v138, 51, v128
	v_ashrrev_i32_e32 v139, 31, v138
	v_lshlrev_b64 v[138:139], 9, v[138:139]
	v_lshl_add_u64 v[138:139], v[130:131], 0, v[138:139]
	v_mul_f32_e32 v141, 0x3e38aa3b, v67
	v_mul_f32_e32 v129, 0x3e38aa3b, v79
	v_mul_f32_e32 v134, 0x3e38aa3b, v75
	v_mul_f32_e32 v137, 0x3e38aa3b, v71
	v_cvt_pk_bf16_f32 v140, v129, v134
	v_cvt_pk_bf16_f32 v141, v137, v141
	global_store_dwordx2 v[138:139], v[140:141], off nt
	v_add_u32_e32 v138, 64, v128
	v_ashrrev_i32_e32 v139, 31, v138
	v_lshlrev_b64 v[138:139], 9, v[138:139]
	v_lshl_add_u64 v[138:139], v[130:131], 0, v[138:139]
	v_mul_f32_e32 v141, 0x3e38aa3b, v48
	v_mul_f32_e32 v129, 0x3e38aa3b, v60
	v_mul_f32_e32 v134, 0x3e38aa3b, v56
	v_mul_f32_e32 v137, 0x3e38aa3b, v52
	v_cvt_pk_bf16_f32 v140, v129, v134
	v_cvt_pk_bf16_f32 v141, v137, v141
	global_store_dwordx2 v[138:139], v[140:141], off nt
	v_add_u32_e32 v138, 0x41, v128
	v_ashrrev_i32_e32 v139, 31, v138
	v_lshlrev_b64 v[138:139], 9, v[138:139]
	v_lshl_add_u64 v[138:139], v[130:131], 0, v[138:139]
	v_mul_f32_e32 v141, 0x3e38aa3b, v49
	v_mul_f32_e32 v129, 0x3e38aa3b, v61
	v_mul_f32_e32 v134, 0x3e38aa3b, v57
	v_mul_f32_e32 v137, 0x3e38aa3b, v53
	v_cvt_pk_bf16_f32 v140, v129, v134
	v_cvt_pk_bf16_f32 v141, v137, v141
	global_store_dwordx2 v[138:139], v[140:141], off nt
	v_add_u32_e32 v138, 0x42, v128
	v_ashrrev_i32_e32 v139, 31, v138
	v_lshlrev_b64 v[138:139], 9, v[138:139]
	v_lshl_add_u64 v[138:139], v[130:131], 0, v[138:139]
	v_mul_f32_e32 v141, 0x3e38aa3b, v50
	v_mul_f32_e32 v129, 0x3e38aa3b, v62
	v_mul_f32_e32 v134, 0x3e38aa3b, v58
	v_mul_f32_e32 v137, 0x3e38aa3b, v54
	v_cvt_pk_bf16_f32 v140, v129, v134
	v_cvt_pk_bf16_f32 v141, v137, v141
	global_store_dwordx2 v[138:139], v[140:141], off nt
	v_add_u32_e32 v138, 0x43, v128
	v_ashrrev_i32_e32 v139, 31, v138
	v_lshlrev_b64 v[138:139], 9, v[138:139]
	v_lshl_add_u64 v[138:139], v[130:131], 0, v[138:139]
	v_mul_f32_e32 v141, 0x3e38aa3b, v51
	v_mul_f32_e32 v129, 0x3e38aa3b, v63
	v_mul_f32_e32 v134, 0x3e38aa3b, v59
	v_mul_f32_e32 v137, 0x3e38aa3b, v55
	v_cvt_pk_bf16_f32 v140, v129, v134
	v_cvt_pk_bf16_f32 v141, v137, v141
	global_store_dwordx2 v[138:139], v[140:141], off nt
	v_add_u32_e32 v138, 0x50, v128
	v_ashrrev_i32_e32 v139, 31, v138
	v_lshlrev_b64 v[138:139], 9, v[138:139]
	v_lshl_add_u64 v[138:139], v[130:131], 0, v[138:139]
	v_mul_f32_e32 v141, 0x3e38aa3b, v32
	v_mul_f32_e32 v129, 0x3e38aa3b, v44
	v_mul_f32_e32 v134, 0x3e38aa3b, v40
	v_mul_f32_e32 v137, 0x3e38aa3b, v36
	v_cvt_pk_bf16_f32 v140, v129, v134
	v_cvt_pk_bf16_f32 v141, v137, v141
	global_store_dwordx2 v[138:139], v[140:141], off nt
	v_add_u32_e32 v138, 0x51, v128
	v_ashrrev_i32_e32 v139, 31, v138
	v_lshlrev_b64 v[138:139], 9, v[138:139]
	v_lshl_add_u64 v[138:139], v[130:131], 0, v[138:139]
	v_mul_f32_e32 v141, 0x3e38aa3b, v33
	v_mul_f32_e32 v129, 0x3e38aa3b, v45
	v_mul_f32_e32 v134, 0x3e38aa3b, v41
	v_mul_f32_e32 v137, 0x3e38aa3b, v37
	v_cvt_pk_bf16_f32 v140, v129, v134
	v_cvt_pk_bf16_f32 v141, v137, v141
	global_store_dwordx2 v[138:139], v[140:141], off nt
	v_add_u32_e32 v138, 0x52, v128
	v_ashrrev_i32_e32 v139, 31, v138
	v_lshlrev_b64 v[138:139], 9, v[138:139]
	v_lshl_add_u64 v[138:139], v[130:131], 0, v[138:139]
	v_mul_f32_e32 v141, 0x3e38aa3b, v34
	v_mul_f32_e32 v129, 0x3e38aa3b, v46
	v_mul_f32_e32 v134, 0x3e38aa3b, v42
	v_mul_f32_e32 v137, 0x3e38aa3b, v38
	v_cvt_pk_bf16_f32 v140, v129, v134
	v_cvt_pk_bf16_f32 v141, v137, v141
	global_store_dwordx2 v[138:139], v[140:141], off nt
	v_add_u32_e32 v138, 0x53, v128
	v_ashrrev_i32_e32 v139, 31, v138
	v_lshlrev_b64 v[138:139], 9, v[138:139]
	v_lshl_add_u64 v[138:139], v[130:131], 0, v[138:139]
	v_mul_f32_e32 v141, 0x3e38aa3b, v35
	v_mul_f32_e32 v129, 0x3e38aa3b, v47
	v_mul_f32_e32 v134, 0x3e38aa3b, v43
	v_mul_f32_e32 v137, 0x3e38aa3b, v39
	v_cvt_pk_bf16_f32 v140, v129, v134
	v_cvt_pk_bf16_f32 v141, v137, v141
	global_store_dwordx2 v[138:139], v[140:141], off nt
	v_add_u32_e32 v138, 0x60, v128
	v_ashrrev_i32_e32 v139, 31, v138
	v_lshlrev_b64 v[138:139], 9, v[138:139]
	v_lshl_add_u64 v[138:139], v[130:131], 0, v[138:139]
	v_mul_f32_e32 v141, 0x3e38aa3b, v16
	v_mul_f32_e32 v129, 0x3e38aa3b, v28
	v_mul_f32_e32 v134, 0x3e38aa3b, v24
	v_mul_f32_e32 v137, 0x3e38aa3b, v20
	v_cvt_pk_bf16_f32 v140, v129, v134
	v_cvt_pk_bf16_f32 v141, v137, v141
	global_store_dwordx2 v[138:139], v[140:141], off nt
	v_add_u32_e32 v138, 0x61, v128
	v_ashrrev_i32_e32 v139, 31, v138
	v_lshlrev_b64 v[138:139], 9, v[138:139]
	v_lshl_add_u64 v[138:139], v[130:131], 0, v[138:139]
	v_mul_f32_e32 v141, 0x3e38aa3b, v17
	v_mul_f32_e32 v129, 0x3e38aa3b, v29
	v_mul_f32_e32 v134, 0x3e38aa3b, v25
	v_mul_f32_e32 v137, 0x3e38aa3b, v21
	v_cvt_pk_bf16_f32 v140, v129, v134
	v_cvt_pk_bf16_f32 v141, v137, v141
	global_store_dwordx2 v[138:139], v[140:141], off nt
	v_add_u32_e32 v138, 0x62, v128
	v_ashrrev_i32_e32 v139, 31, v138
	v_lshlrev_b64 v[138:139], 9, v[138:139]
	v_lshl_add_u64 v[138:139], v[130:131], 0, v[138:139]
	v_mul_f32_e32 v141, 0x3e38aa3b, v18
	v_mul_f32_e32 v129, 0x3e38aa3b, v30
	v_mul_f32_e32 v134, 0x3e38aa3b, v26
	v_mul_f32_e32 v137, 0x3e38aa3b, v22
	v_cvt_pk_bf16_f32 v140, v129, v134
	v_cvt_pk_bf16_f32 v141, v137, v141
	global_store_dwordx2 v[138:139], v[140:141], off nt
	v_add_u32_e32 v138, 0x63, v128
	v_ashrrev_i32_e32 v139, 31, v138
	v_lshlrev_b64 v[138:139], 9, v[138:139]
	v_lshl_add_u64 v[138:139], v[130:131], 0, v[138:139]
	v_mul_f32_e32 v141, 0x3e38aa3b, v19
	v_mul_f32_e32 v129, 0x3e38aa3b, v31
	v_mul_f32_e32 v134, 0x3e38aa3b, v27
	v_mul_f32_e32 v137, 0x3e38aa3b, v23
	v_cvt_pk_bf16_f32 v140, v129, v134
	v_cvt_pk_bf16_f32 v141, v137, v141
	global_store_dwordx2 v[138:139], v[140:141], off nt
	v_add_u32_e32 v138, 0x70, v128
	v_ashrrev_i32_e32 v139, 31, v138
	v_lshlrev_b64 v[138:139], 9, v[138:139]
	v_lshl_add_u64 v[138:139], v[130:131], 0, v[138:139]
	v_mul_f32_e32 v141, 0x3e38aa3b, v0
	v_mul_f32_e32 v129, 0x3e38aa3b, v12
	v_mul_f32_e32 v134, 0x3e38aa3b, v8
	v_mul_f32_e32 v137, 0x3e38aa3b, v4
	v_cvt_pk_bf16_f32 v140, v129, v134
	v_cvt_pk_bf16_f32 v141, v137, v141
	global_store_dwordx2 v[138:139], v[140:141], off nt
	v_add_u32_e32 v138, 0x71, v128
	v_ashrrev_i32_e32 v139, 31, v138
	v_lshlrev_b64 v[138:139], 9, v[138:139]
	v_lshl_add_u64 v[138:139], v[130:131], 0, v[138:139]
	v_mul_f32_e32 v141, 0x3e38aa3b, v1
	v_mul_f32_e32 v129, 0x3e38aa3b, v13
	v_mul_f32_e32 v134, 0x3e38aa3b, v9
	v_mul_f32_e32 v137, 0x3e38aa3b, v5
	v_cvt_pk_bf16_f32 v140, v129, v134
	v_cvt_pk_bf16_f32 v141, v137, v141
	global_store_dwordx2 v[138:139], v[140:141], off nt
	v_add_u32_e32 v138, 0x72, v128
	v_ashrrev_i32_e32 v139, 31, v138
	v_lshlrev_b64 v[138:139], 9, v[138:139]
	v_lshl_add_u64 v[138:139], v[130:131], 0, v[138:139]
	v_mul_f32_e32 v141, 0x3e38aa3b, v2
	v_mul_f32_e32 v129, 0x3e38aa3b, v14
	v_mul_f32_e32 v134, 0x3e38aa3b, v10
	v_mul_f32_e32 v137, 0x3e38aa3b, v6
	v_cvt_pk_bf16_f32 v140, v129, v134
	v_cvt_pk_bf16_f32 v141, v137, v141
	global_store_dwordx2 v[138:139], v[140:141], off nt
	v_add_u32_e32 v128, 0x73, v128
	v_ashrrev_i32_e32 v129, 31, v128
	v_lshlrev_b64 v[128:129], 9, v[128:129]
	v_lshl_add_u64 v[128:129], v[130:131], 0, v[128:129]
	v_mul_f32_e32 v130, 0x3e38aa3b, v15
	v_mul_f32_e32 v131, 0x3e38aa3b, v11
	v_mul_f32_e32 v134, 0x3e38aa3b, v7
	v_mul_f32_e32 v137, 0x3e38aa3b, v3
	v_cvt_pk_bf16_f32 v130, v130, v131
	v_cvt_pk_bf16_f32 v131, v134, v137
	global_store_dwordx2 v[128:129], v[130:131], off nt

.LBB0_233:
	s_andn2_saveexec_b64 s[68:69], s[68:69]
	s_cbranch_execz .LBB0_241
	v_cmp_lt_i32_e32 vcc, 5, v177
	s_mov_b64 s[72:73], s[66:67]
	s_and_saveexec_b64 s[24:25], vcc
	s_xor_b64 s[74:75], exec, s[24:25]
	s_cbranch_execz .LBB0_238
	v_cmp_gt_i32_e32 vcc, 7, v177
	s_mov_b64 s[34:35], -1
	s_and_saveexec_b64 s[72:73], vcc
	s_cbranch_execz .LBB0_237
	v_readlane_b32 s36, v253, 26
	v_readlane_b32 s24, v253, 16
	v_lshlrev_b32_e32 v138, 2, v178
	v_ashrrev_i32_e32 v137, 31, v136
	v_readlane_b32 s40, v253, 30
	v_readlane_b32 s41, v253, 31
	v_readlane_b32 s25, v253, 17
	v_add_u32_e32 v134, v138, v211
	v_readlane_b32 s37, v253, 27
	v_readlane_b32 s38, v253, 28
	v_readlane_b32 s39, v253, 29
	v_readlane_b32 s42, v253, 32
	v_readlane_b32 s43, v253, 33
	v_readlane_b32 s44, v253, 34
	v_readlane_b32 s45, v253, 35
	v_readlane_b32 s46, v253, 36
	v_readlane_b32 s47, v253, 37
	v_readlane_b32 s48, v253, 38
	v_readlane_b32 s49, v253, 39
	v_readlane_b32 s50, v253, 40
	v_readlane_b32 s51, v253, 41
	v_lshl_add_u64 v[130:131], v[136:137], 1, s[40:41]
	v_lshl_add_u64 v[128:129], v[136:137], 2, s[24:25]
	v_lshrrev_b32_e32 v139, 5, v134
	v_and_b32_e32 v137, 28, v138
	v_mul_lo_u32 v138, v139, s12
	v_add_u32_e32 v144, 0x1000, v138
	v_or_b32_e32 v138, v144, v137
	v_mad_i64_i32 v[138:139], s[24:25], v138, s13, v[130:131]
	v_cvt_pk_bf16_f32 v140, v124, v120
	v_cvt_pk_bf16_f32 v141, v116, v112
	global_store_dwordx2 v[138:139], v[140:141], off nt
	v_mad_i64_i32 v[142:143], s[24:25], v134, s14, v[128:129]
	v_mov_b32_e32 v138, v124
	v_mov_b32_e32 v139, v120
	v_mov_b32_e32 v140, v116
	v_mov_b32_e32 v141, v112
	global_store_dwordx4 v[142:143], v[138:141], off nt
	v_or_b32_e32 v142, 1, v134
	s_nop 0
	v_and_or_b32 v138, v142, 29, v144
	v_mad_i64_i32 v[138:139], s[24:25], v138, s13, v[130:131]
	v_cvt_pk_bf16_f32 v140, v125, v121
	v_cvt_pk_bf16_f32 v141, v117, v113
	global_store_dwordx2 v[138:139], v[140:141], off nt
	v_mad_i64_i32 v[142:143], s[24:25], v142, s14, v[128:129]
	v_mov_b32_e32 v138, v125
	v_mov_b32_e32 v139, v121
	v_mov_b32_e32 v140, v117
	v_mov_b32_e32 v141, v113
	global_store_dwordx4 v[142:143], v[138:141], off nt
	v_or_b32_e32 v142, 2, v134
	s_nop 0
	v_and_or_b32 v138, v142, 30, v144
	v_mad_i64_i32 v[138:139], s[24:25], v138, s13, v[130:131]
	v_cvt_pk_bf16_f32 v140, v126, v122
	v_cvt_pk_bf16_f32 v141, v118, v114
	global_store_dwordx2 v[138:139], v[140:141], off nt
	v_mad_i64_i32 v[142:143], s[24:25], v142, s14, v[128:129]
	v_mov_b32_e32 v138, v126
	v_mov_b32_e32 v139, v122
	v_mov_b32_e32 v140, v118
	v_mov_b32_e32 v141, v114
	global_store_dwordx4 v[142:143], v[138:141], off nt
	v_or_b32_e32 v142, 3, v134
	s_nop 0
	v_and_or_b32 v138, v142, 31, v144
	v_mad_i64_i32 v[138:139], s[24:25], v138, s13, v[130:131]
	v_cvt_pk_bf16_f32 v140, v127, v123
	v_cvt_pk_bf16_f32 v141, v119, v115
	global_store_dwordx2 v[138:139], v[140:141], off nt
	v_mad_i64_i32 v[142:143], s[24:25], v142, s14, v[128:129]
	v_mov_b32_e32 v138, v127
	v_mov_b32_e32 v139, v123
	v_mov_b32_e32 v140, v119
	v_mov_b32_e32 v141, v115
	global_store_dwordx4 v[142:143], v[138:141], off nt
	v_add_u32_e32 v142, 16, v134
	s_nop 0
	v_lshrrev_b32_e32 v138, 5, v142
	v_mul_lo_u32 v138, v138, s12
	v_and_or_b32 v138, v142, 28, v138
	v_add_u32_e32 v138, 0x1000, v138
	v_mad_i64_i32 v[138:139], s[24:25], v138, s13, v[130:131]
	v_cvt_pk_bf16_f32 v140, v108, v104
	v_cvt_pk_bf16_f32 v141, v100, v96
	global_store_dwordx2 v[138:139], v[140:141], off nt
	v_mad_i64_i32 v[142:143], s[24:25], v142, s14, v[128:129]
	v_mov_b32_e32 v138, v108
	v_mov_b32_e32 v139, v104
	v_mov_b32_e32 v140, v100
	v_mov_b32_e32 v141, v96
	global_store_dwordx4 v[142:143], v[138:141], off nt
	v_add_u32_e32 v142, 17, v134
	s_nop 0
	v_lshrrev_b32_e32 v138, 5, v142
	v_mul_lo_u32 v138, v138, s12
	v_and_or_b32 v138, v142, 29, v138
	v_add_u32_e32 v138, 0x1000, v138
	v_mad_i64_i32 v[138:139], s[24:25], v138, s13, v[130:131]
	v_cvt_pk_bf16_f32 v140, v109, v105
	v_cvt_pk_bf16_f32 v141, v101, v97
	global_store_dwordx2 v[138:139], v[140:141], off nt
	v_mad_i64_i32 v[142:143], s[24:25], v142, s14, v[128:129]
	v_mov_b32_e32 v138, v109
	v_mov_b32_e32 v139, v105
	v_mov_b32_e32 v140, v101
	v_mov_b32_e32 v141, v97
	global_store_dwordx4 v[142:143], v[138:141], off nt
	v_add_u32_e32 v142, 18, v134
	s_nop 0
	v_lshrrev_b32_e32 v138, 5, v142
	v_mul_lo_u32 v138, v138, s12
	v_and_or_b32 v138, v142, 30, v138
	v_add_u32_e32 v138, 0x1000, v138
	v_mad_i64_i32 v[138:139], s[24:25], v138, s13, v[130:131]
	v_cvt_pk_bf16_f32 v140, v110, v106
	v_cvt_pk_bf16_f32 v141, v102, v98
	global_store_dwordx2 v[138:139], v[140:141], off nt
	v_mad_i64_i32 v[142:143], s[24:25], v142, s14, v[128:129]
	v_mov_b32_e32 v138, v110
	v_mov_b32_e32 v139, v106
	v_mov_b32_e32 v140, v102
	v_mov_b32_e32 v141, v98
	global_store_dwordx4 v[142:143], v[138:141], off nt
	v_add_u32_e32 v142, 19, v134
	s_nop 0
	v_lshrrev_b32_e32 v138, 5, v142
	v_mul_lo_u32 v138, v138, s12
	v_and_or_b32 v138, v142, 31, v138
	v_add_u32_e32 v138, 0x1000, v138
	v_mad_i64_i32 v[138:139], s[24:25], v138, s13, v[130:131]
	v_cvt_pk_bf16_f32 v140, v111, v107
	v_cvt_pk_bf16_f32 v141, v103, v99
	global_store_dwordx2 v[138:139], v[140:141], off nt
	v_mad_i64_i32 v[142:143], s[24:25], v142, s14, v[128:129]
	v_mov_b32_e32 v138, v111
	v_mov_b32_e32 v139, v107
	v_mov_b32_e32 v140, v103
	v_mov_b32_e32 v141, v99
	global_store_dwordx4 v[142:143], v[138:141], off nt
	v_add_u32_e32 v142, 32, v134
	s_nop 0
	v_lshrrev_b32_e32 v138, 5, v142
	v_mul_lo_u32 v138, v138, s12
	v_or_b32_e32 v138, v138, v137
	v_add_u32_e32 v138, 0x1000, v138
	v_mad_i64_i32 v[138:139], s[24:25], v138, s13, v[130:131]
	v_cvt_pk_bf16_f32 v140, v92, v88
	v_cvt_pk_bf16_f32 v141, v84, v80
	global_store_dwordx2 v[138:139], v[140:141], off nt
	v_mad_i64_i32 v[142:143], s[24:25], v142, s14, v[128:129]
	v_mov_b32_e32 v138, v92
	v_mov_b32_e32 v139, v88
	v_mov_b32_e32 v140, v84
	v_mov_b32_e32 v141, v80
	global_store_dwordx4 v[142:143], v[138:141], off nt
	v_add_u32_e32 v142, 33, v134
	s_nop 0
	v_lshrrev_b32_e32 v138, 5, v142
	v_mul_lo_u32 v138, v138, s12
	v_and_or_b32 v138, v142, 29, v138
	v_add_u32_e32 v138, 0x1000, v138
	v_mad_i64_i32 v[138:139], s[24:25], v138, s13, v[130:131]
	v_cvt_pk_bf16_f32 v140, v93, v89
	v_cvt_pk_bf16_f32 v141, v85, v81
	global_store_dwordx2 v[138:139], v[140:141], off nt
	v_mad_i64_i32 v[142:143], s[24:25], v142, s14, v[128:129]
	v_mov_b32_e32 v138, v93
	v_mov_b32_e32 v139, v89
	v_mov_b32_e32 v140, v85
	v_mov_b32_e32 v141, v81
	global_store_dwordx4 v[142:143], v[138:141], off nt
	v_add_u32_e32 v142, 34, v134
	s_nop 0
	v_lshrrev_b32_e32 v138, 5, v142
	v_mul_lo_u32 v138, v138, s12
	v_and_or_b32 v138, v142, 30, v138
	v_add_u32_e32 v138, 0x1000, v138
	v_mad_i64_i32 v[138:139], s[24:25], v138, s13, v[130:131]
	v_cvt_pk_bf16_f32 v140, v94, v90
	v_cvt_pk_bf16_f32 v141, v86, v82
	global_store_dwordx2 v[138:139], v[140:141], off nt
	v_mad_i64_i32 v[142:143], s[24:25], v142, s14, v[128:129]
	v_mov_b32_e32 v138, v94
	v_mov_b32_e32 v139, v90
	v_mov_b32_e32 v140, v86
	v_mov_b32_e32 v141, v82
	global_store_dwordx4 v[142:143], v[138:141], off nt
	v_add_u32_e32 v142, 35, v134
	s_nop 0
	v_lshrrev_b32_e32 v138, 5, v142
	v_mul_lo_u32 v138, v138, s12
	v_and_or_b32 v138, v142, 31, v138
	v_add_u32_e32 v138, 0x1000, v138
	v_mad_i64_i32 v[138:139], s[24:25], v138, s13, v[130:131]
	v_cvt_pk_bf16_f32 v140, v95, v91
	v_cvt_pk_bf16_f32 v141, v87, v83
	global_store_dwordx2 v[138:139], v[140:141], off nt
	v_mad_i64_i32 v[142:143], s[24:25], v142, s14, v[128:129]
	v_mov_b32_e32 v138, v95
	v_mov_b32_e32 v139, v91
	v_mov_b32_e32 v140, v87
	v_mov_b32_e32 v141, v83
	global_store_dwordx4 v[142:143], v[138:141], off nt
	v_add_u32_e32 v142, 48, v134
	s_nop 0
	v_lshrrev_b32_e32 v138, 5, v142
	v_mul_lo_u32 v138, v138, s12
	v_and_or_b32 v138, v142, 28, v138
	v_add_u32_e32 v138, 0x1000, v138
	v_mad_i64_i32 v[138:139], s[24:25], v138, s13, v[130:131]
	v_cvt_pk_bf16_f32 v140, v76, v72
	v_cvt_pk_bf16_f32 v141, v68, v64
	global_store_dwordx2 v[138:139], v[140:141], off nt
	v_mad_i64_i32 v[142:143], s[24:25], v142, s14, v[128:129]
	v_mov_b32_e32 v138, v76
	v_mov_b32_e32 v139, v72
	v_mov_b32_e32 v140, v68
	v_mov_b32_e32 v141, v64
	global_store_dwordx4 v[142:143], v[138:141], off nt
	v_add_u32_e32 v142, 49, v134
	s_nop 0
	v_lshrrev_b32_e32 v138, 5, v142
	v_mul_lo_u32 v138, v138, s12
	v_and_or_b32 v138, v142, 29, v138
	v_add_u32_e32 v138, 0x1000, v138
	v_mad_i64_i32 v[138:139], s[24:25], v138, s13, v[130:131]
	v_cvt_pk_bf16_f32 v140, v77, v73
	v_cvt_pk_bf16_f32 v141, v69, v65
	global_store_dwordx2 v[138:139], v[140:141], off nt
	v_mad_i64_i32 v[142:143], s[24:25], v142, s14, v[128:129]
	v_mov_b32_e32 v138, v77
	v_mov_b32_e32 v139, v73
	v_mov_b32_e32 v140, v69
	v_mov_b32_e32 v141, v65
	global_store_dwordx4 v[142:143], v[138:141], off nt
	v_add_u32_e32 v142, 50, v134
	s_nop 0
	v_lshrrev_b32_e32 v138, 5, v142
	v_mul_lo_u32 v138, v138, s12
	v_and_or_b32 v138, v142, 30, v138
	v_add_u32_e32 v138, 0x1000, v138
	v_mad_i64_i32 v[138:139], s[24:25], v138, s13, v[130:131]
	v_cvt_pk_bf16_f32 v140, v78, v74
	v_cvt_pk_bf16_f32 v141, v70, v66
	global_store_dwordx2 v[138:139], v[140:141], off nt
	v_mad_i64_i32 v[142:143], s[24:25], v142, s14, v[128:129]
	v_mov_b32_e32 v138, v78
	v_mov_b32_e32 v139, v74
	v_mov_b32_e32 v140, v70
	v_mov_b32_e32 v141, v66
	global_store_dwordx4 v[142:143], v[138:141], off nt
	v_add_u32_e32 v142, 51, v134
	s_nop 0
	v_lshrrev_b32_e32 v138, 5, v142
	v_mul_lo_u32 v138, v138, s12
	v_and_or_b32 v138, v142, 31, v138
	v_add_u32_e32 v138, 0x1000, v138
	v_mad_i64_i32 v[138:139], s[24:25], v138, s13, v[130:131]
	v_cvt_pk_bf16_f32 v140, v79, v75
	v_cvt_pk_bf16_f32 v141, v71, v67
	global_store_dwordx2 v[138:139], v[140:141], off nt
	v_mad_i64_i32 v[142:143], s[24:25], v142, s14, v[128:129]
	v_mov_b32_e32 v138, v79
	v_mov_b32_e32 v139, v75
	v_mov_b32_e32 v140, v71
	v_mov_b32_e32 v141, v67
	global_store_dwordx4 v[142:143], v[138:141], off nt
	v_add_u32_e32 v142, 64, v134
	s_nop 0
	v_lshrrev_b32_e32 v138, 5, v142
	v_mul_lo_u32 v138, v138, s12
	v_or_b32_e32 v138, v138, v137
	v_add_u32_e32 v138, 0x1000, v138
	v_mad_i64_i32 v[138:139], s[24:25], v138, s13, v[130:131]
	v_cvt_pk_bf16_f32 v140, v60, v56
	v_cvt_pk_bf16_f32 v141, v52, v48
	global_store_dwordx2 v[138:139], v[140:141], off nt
	v_mad_i64_i32 v[142:143], s[24:25], v142, s14, v[128:129]
	v_mov_b32_e32 v138, v60
	v_mov_b32_e32 v139, v56
	v_mov_b32_e32 v140, v52
	v_mov_b32_e32 v141, v48
	global_store_dwordx4 v[142:143], v[138:141], off nt
	v_add_u32_e32 v142, 0x41, v134
	s_nop 0
	v_lshrrev_b32_e32 v138, 5, v142
	v_mul_lo_u32 v138, v138, s12
	v_and_or_b32 v138, v142, 29, v138
	v_add_u32_e32 v138, 0x1000, v138
	v_mad_i64_i32 v[138:139], s[24:25], v138, s13, v[130:131]
	v_cvt_pk_bf16_f32 v140, v61, v57
	v_cvt_pk_bf16_f32 v141, v53, v49
	global_store_dwordx2 v[138:139], v[140:141], off nt
	v_mad_i64_i32 v[142:143], s[24:25], v142, s14, v[128:129]
	v_mov_b32_e32 v138, v61
	v_mov_b32_e32 v139, v57
	v_mov_b32_e32 v140, v53
	v_mov_b32_e32 v141, v49
	global_store_dwordx4 v[142:143], v[138:141], off nt
	v_add_u32_e32 v142, 0x42, v134
	s_nop 0
	v_lshrrev_b32_e32 v138, 5, v142
	v_mul_lo_u32 v138, v138, s12
	v_and_or_b32 v138, v142, 30, v138
	v_add_u32_e32 v138, 0x1000, v138
	v_mad_i64_i32 v[138:139], s[24:25], v138, s13, v[130:131]
	v_cvt_pk_bf16_f32 v140, v62, v58
	v_cvt_pk_bf16_f32 v141, v54, v50
	global_store_dwordx2 v[138:139], v[140:141], off nt
	v_mad_i64_i32 v[142:143], s[24:25], v142, s14, v[128:129]
	v_mov_b32_e32 v138, v62
	v_mov_b32_e32 v139, v58
	v_mov_b32_e32 v140, v54
	v_mov_b32_e32 v141, v50
	global_store_dwordx4 v[142:143], v[138:141], off nt
	v_add_u32_e32 v142, 0x43, v134
	s_nop 0
	v_lshrrev_b32_e32 v138, 5, v142
	v_mul_lo_u32 v138, v138, s12
	v_and_or_b32 v138, v142, 31, v138
	v_add_u32_e32 v138, 0x1000, v138
	v_mad_i64_i32 v[138:139], s[24:25], v138, s13, v[130:131]
	v_cvt_pk_bf16_f32 v140, v63, v59
	v_cvt_pk_bf16_f32 v141, v55, v51
	global_store_dwordx2 v[138:139], v[140:141], off nt
	v_mad_i64_i32 v[142:143], s[24:25], v142, s14, v[128:129]
	v_mov_b32_e32 v138, v63
	v_mov_b32_e32 v139, v59
	v_mov_b32_e32 v140, v55
	v_mov_b32_e32 v141, v51
	global_store_dwordx4 v[142:143], v[138:141], off nt
	v_add_u32_e32 v142, 0x50, v134
	s_nop 0
	v_lshrrev_b32_e32 v138, 5, v142
	v_mul_lo_u32 v138, v138, s12
	v_and_or_b32 v138, v142, 28, v138
	v_add_u32_e32 v138, 0x1000, v138
	v_mad_i64_i32 v[138:139], s[24:25], v138, s13, v[130:131]
	v_cvt_pk_bf16_f32 v140, v44, v40
	v_cvt_pk_bf16_f32 v141, v36, v32
	global_store_dwordx2 v[138:139], v[140:141], off nt
	v_mad_i64_i32 v[142:143], s[24:25], v142, s14, v[128:129]
	v_mov_b32_e32 v138, v44
	v_mov_b32_e32 v139, v40
	v_mov_b32_e32 v140, v36
	v_mov_b32_e32 v141, v32
	global_store_dwordx4 v[142:143], v[138:141], off nt
	v_add_u32_e32 v142, 0x51, v134
	s_nop 0
	v_lshrrev_b32_e32 v138, 5, v142
	v_mul_lo_u32 v138, v138, s12
	v_and_or_b32 v138, v142, 29, v138
	v_add_u32_e32 v138, 0x1000, v138
	v_mad_i64_i32 v[138:139], s[24:25], v138, s13, v[130:131]
	v_cvt_pk_bf16_f32 v140, v45, v41
	v_cvt_pk_bf16_f32 v141, v37, v33
	global_store_dwordx2 v[138:139], v[140:141], off nt
	v_mad_i64_i32 v[142:143], s[24:25], v142, s14, v[128:129]
	v_mov_b32_e32 v138, v45
	v_mov_b32_e32 v139, v41
	v_mov_b32_e32 v140, v37
	v_mov_b32_e32 v141, v33
	global_store_dwordx4 v[142:143], v[138:141], off nt
	v_add_u32_e32 v142, 0x52, v134
	s_nop 0
	v_lshrrev_b32_e32 v138, 5, v142
	v_mul_lo_u32 v138, v138, s12
	v_and_or_b32 v138, v142, 30, v138
	v_add_u32_e32 v138, 0x1000, v138
	v_mad_i64_i32 v[138:139], s[24:25], v138, s13, v[130:131]
	v_cvt_pk_bf16_f32 v140, v46, v42
	v_cvt_pk_bf16_f32 v141, v38, v34
	global_store_dwordx2 v[138:139], v[140:141], off nt
	v_mad_i64_i32 v[142:143], s[24:25], v142, s14, v[128:129]
	v_mov_b32_e32 v138, v46
	v_mov_b32_e32 v139, v42
	v_mov_b32_e32 v140, v38
	v_mov_b32_e32 v141, v34
	global_store_dwordx4 v[142:143], v[138:141], off nt
	v_add_u32_e32 v142, 0x53, v134
	s_nop 0
	v_lshrrev_b32_e32 v138, 5, v142
	v_mul_lo_u32 v138, v138, s12
	v_and_or_b32 v138, v142, 31, v138
	v_add_u32_e32 v138, 0x1000, v138
	v_mad_i64_i32 v[138:139], s[24:25], v138, s13, v[130:131]
	v_cvt_pk_bf16_f32 v140, v47, v43
	v_cvt_pk_bf16_f32 v141, v39, v35
	global_store_dwordx2 v[138:139], v[140:141], off nt
	v_mad_i64_i32 v[142:143], s[24:25], v142, s14, v[128:129]
	v_mov_b32_e32 v138, v47
	v_mov_b32_e32 v139, v43
	v_mov_b32_e32 v140, v39
	v_mov_b32_e32 v141, v35
	global_store_dwordx4 v[142:143], v[138:141], off nt
	v_add_u32_e32 v142, 0x60, v134
	s_nop 0
	v_lshrrev_b32_e32 v138, 5, v142
	v_mul_lo_u32 v138, v138, s12
	v_or_b32_e32 v137, v138, v137
	v_add_u32_e32 v137, 0x1000, v137
	v_mad_i64_i32 v[138:139], s[24:25], v137, s13, v[130:131]
	v_cvt_pk_bf16_f32 v140, v28, v24
	v_cvt_pk_bf16_f32 v141, v20, v16
	global_store_dwordx2 v[138:139], v[140:141], off nt
	v_mad_i64_i32 v[142:143], s[24:25], v142, s14, v[128:129]
	v_mov_b32_e32 v138, v28
	v_mov_b32_e32 v139, v24
	v_mov_b32_e32 v140, v20
	v_mov_b32_e32 v141, v16
	global_store_dwordx4 v[142:143], v[138:141], off nt
	v_add_u32_e32 v137, 0x61, v134
	s_nop 0
	v_lshrrev_b32_e32 v138, 5, v137
	v_mul_lo_u32 v138, v138, s12
	v_and_or_b32 v138, v137, 29, v138
	v_add_u32_e32 v138, 0x1000, v138
	v_mad_i64_i32 v[138:139], s[24:25], v138, s13, v[130:131]
	v_cvt_pk_bf16_f32 v140, v29, v25
	v_cvt_pk_bf16_f32 v141, v21, v17
	global_store_dwordx2 v[138:139], v[140:141], off nt
	v_mad_i64_i32 v[142:143], s[24:25], v137, s14, v[128:129]
	v_mov_b32_e32 v138, v29
	v_mov_b32_e32 v139, v25
	v_mov_b32_e32 v140, v21
	v_mov_b32_e32 v141, v17
	global_store_dwordx4 v[142:143], v[138:141], off nt
	v_add_u32_e32 v137, 0x62, v134
	s_nop 0
	v_lshrrev_b32_e32 v138, 5, v137
	v_mul_lo_u32 v138, v138, s12
	v_and_or_b32 v138, v137, 30, v138
	v_add_u32_e32 v138, 0x1000, v138
	v_mad_i64_i32 v[138:139], s[24:25], v138, s13, v[130:131]
	v_cvt_pk_bf16_f32 v140, v30, v26
	v_cvt_pk_bf16_f32 v141, v22, v18
	global_store_dwordx2 v[138:139], v[140:141], off nt
	v_mad_i64_i32 v[142:143], s[24:25], v137, s14, v[128:129]
	v_mov_b32_e32 v138, v30
	v_mov_b32_e32 v139, v26
	v_mov_b32_e32 v140, v22
	v_mov_b32_e32 v141, v18
	global_store_dwordx4 v[142:143], v[138:141], off nt
	v_add_u32_e32 v137, 0x63, v134
	s_nop 0
	v_lshrrev_b32_e32 v138, 5, v137
	v_mul_lo_u32 v138, v138, s12
	v_and_or_b32 v138, v137, 31, v138
	v_add_u32_e32 v138, 0x1000, v138
	v_mad_i64_i32 v[138:139], s[24:25], v138, s13, v[130:131]
	v_cvt_pk_bf16_f32 v140, v31, v27
	v_cvt_pk_bf16_f32 v141, v23, v19
	global_store_dwordx2 v[138:139], v[140:141], off nt
	v_mad_i64_i32 v[142:143], s[24:25], v137, s14, v[128:129]
	v_mov_b32_e32 v138, v31
	v_mov_b32_e32 v139, v27
	v_mov_b32_e32 v140, v23
	v_mov_b32_e32 v141, v19
	global_store_dwordx4 v[142:143], v[138:141], off nt
	v_add_u32_e32 v137, 0x70, v134
	s_nop 0
	v_lshrrev_b32_e32 v138, 5, v137
	v_mul_lo_u32 v138, v138, s12
	v_and_or_b32 v138, v137, 28, v138
	v_add_u32_e32 v138, 0x1000, v138
	v_mad_i64_i32 v[138:139], s[24:25], v138, s13, v[130:131]
	v_cvt_pk_bf16_f32 v140, v12, v8
	v_cvt_pk_bf16_f32 v141, v4, v0
	global_store_dwordx2 v[138:139], v[140:141], off nt
	v_mad_i64_i32 v[142:143], s[24:25], v137, s14, v[128:129]
	v_mov_b32_e32 v138, v12
	v_mov_b32_e32 v139, v8
	v_mov_b32_e32 v140, v4
	v_mov_b32_e32 v141, v0
	global_store_dwordx4 v[142:143], v[138:141], off nt
	v_add_u32_e32 v137, 0x71, v134
	s_nop 0
	v_lshrrev_b32_e32 v138, 5, v137
	v_mul_lo_u32 v138, v138, s12
	v_and_or_b32 v138, v137, 29, v138
	v_add_u32_e32 v138, 0x1000, v138
	v_mad_i64_i32 v[138:139], s[24:25], v138, s13, v[130:131]
	v_cvt_pk_bf16_f32 v140, v13, v9
	v_cvt_pk_bf16_f32 v141, v5, v1
	global_store_dwordx2 v[138:139], v[140:141], off nt
	v_mad_i64_i32 v[142:143], s[24:25], v137, s14, v[128:129]
	v_mov_b32_e32 v138, v13
	v_mov_b32_e32 v139, v9
	v_mov_b32_e32 v140, v5
	v_mov_b32_e32 v141, v1
	global_store_dwordx4 v[142:143], v[138:141], off nt
	v_add_u32_e32 v137, 0x72, v134
	s_nop 0
	v_lshrrev_b32_e32 v138, 5, v137
	v_mul_lo_u32 v138, v138, s12
	v_and_or_b32 v138, v137, 30, v138
	v_add_u32_e32 v138, 0x1000, v138
	v_mad_i64_i32 v[138:139], s[24:25], v138, s13, v[130:131]
	v_cvt_pk_bf16_f32 v140, v14, v10
	v_cvt_pk_bf16_f32 v141, v6, v2
	global_store_dwordx2 v[138:139], v[140:141], off nt
	v_mad_i64_i32 v[142:143], s[24:25], v137, s14, v[128:129]
	v_mov_b32_e32 v138, v14
	v_mov_b32_e32 v139, v10
	v_mov_b32_e32 v140, v6
	v_mov_b32_e32 v141, v2
	global_store_dwordx4 v[142:143], v[138:141], off nt
	v_add_u32_e32 v134, 0x73, v134
	v_lshrrev_b32_e32 v137, 5, v134
	v_mul_lo_u32 v137, v137, s12
	v_and_or_b32 v137, v134, 31, v137
	v_add_u32_e32 v137, 0x1000, v137
	v_mad_i64_i32 v[130:131], s[24:25], v137, s13, v[130:131]
	v_cvt_pk_bf16_f32 v138, v15, v11
	v_cvt_pk_bf16_f32 v139, v7, v3
	global_store_dwordx2 v[130:131], v[138:139], off nt
	v_mad_i64_i32 v[138:139], s[24:25], v134, s14, v[128:129]
	v_mov_b32_e32 v128, v15
	v_mov_b32_e32 v129, v11
	v_mov_b32_e32 v130, v7
	v_mov_b32_e32 v131, v3
	global_store_dwordx4 v[138:139], v[128:131], off nt
	s_xor_b64 s[34:35], exec, -1

.LBB0_238:
	s_andn2_saveexec_b64 s[74:75], s[74:75]
	s_cbranch_execz .LBB0_240
	v_mbcnt_hi_u32_b32 v129, -1, v204
	v_and_b32_e32 v131, 64, v129
	v_xor_b32_e32 v130, 8, v129
	v_add_u32_e32 v131, 64, v131
	v_cmp_lt_i32_e32 vcc, v130, v131
	v_readlane_b32 s36, v253, 26
	v_readlane_b32 s24, v253, 18
	v_lshlrev_b32_e32 v128, 2, v178
	v_cndmask_b32_e32 v129, v129, v130, vcc
	v_cmp_gt_u32_e32 vcc, 8, v176
	v_ashrrev_i32_e32 v137, 31, v136
	v_readlane_b32 s38, v253, 28
	v_readlane_b32 s39, v253, 29
	v_readlane_b32 s25, v253, 19
	v_add_u32_e32 v154, v128, v211
	v_lshlrev_b32_e32 v153, 2, v129
	v_cndmask_b32_e64 v152, 1.0, -1.0, vcc
	v_readlane_b32 s37, v253, 27
	v_readlane_b32 s40, v253, 30
	v_readlane_b32 s41, v253, 31
	v_readlane_b32 s42, v253, 32
	v_readlane_b32 s43, v253, 33
	v_readlane_b32 s44, v253, 34
	v_readlane_b32 s45, v253, 35
	v_readlane_b32 s46, v253, 36
	v_readlane_b32 s47, v253, 37
	v_readlane_b32 s48, v253, 38
	v_readlane_b32 s49, v253, 39
	v_readlane_b32 s50, v253, 40
	v_readlane_b32 s51, v253, 41
	v_lshl_add_u64 v[138:139], v[136:137], 1, s[38:39]
	v_lshl_add_u64 v[140:141], v[136:137], 2, s[24:25]
	v_lshrrev_b32_e32 v129, 5, v154
	v_and_b32_e32 v137, 28, v128
	v_mul_lo_u32 v128, v129, s12
	v_add_u32_e32 v155, 0x1000, v128
	v_lshlrev_b32_e32 v128, 5, v174
	v_and_b32_e32 v134, 0xe0, v128
	v_lshl_add_u64 v[142:143], s[58:59], 0, v[134:135]
	v_lshlrev_b32_e32 v134, 8, v137
	v_lshl_add_u64 v[144:145], v[142:143], 0, v[134:135]
	v_add_co_u32_e32 v146, vcc, s33, v144
	ds_bpermute_b32 v134, v153, v124
	s_nop 0
	v_addc_co_u32_e32 v147, vcc, 0, v145, vcc
	global_load_dwordx3 v[160:162], v[146:147], off offset:256
	global_load_dwordx4 v[128:131], v[146:147], off offset:268
	global_load_dword v149, v[146:147], off offset:284
	v_lshl_add_u64 v[144:145], v[144:145], 0, s[84:85]
	v_mov_b32_e32 v180, v116
	v_or_b32_e32 v148, v155, v137
	s_waitcnt lgkmcnt(0)
	v_mul_f32_e32 v170, v152, v134
	v_mov_b32_e32 v172, v124
	v_or_b32_e32 v134, 1, v154
	v_mad_i64_i32 v[182:183], s[24:25], v148, s13, v[138:139]
	v_mov_b32_e32 v171, v120
	v_and_or_b32 v148, v134, 29, v155
	v_mad_i64_i32 v[184:185], s[24:25], v154, s14, v[140:141]
	s_waitcnt vmcnt(2)
	v_mov_b32_e32 v150, v161
	v_mov_b32_e32 v151, v162
	global_load_dwordx3 v[162:164], v[146:147], off offset:20
	global_load_dwordx4 v[156:159], v[146:147], off
	global_load_dword v166, v[144:145], off offset:16
	ds_bpermute_b32 v161, v153, v112
	s_waitcnt lgkmcnt(0)
	v_mul_f32_e32 v181, v152, v161
	ds_bpermute_b32 v161, v153, v125
	s_waitcnt vmcnt(2)
	v_mov_b32_e32 v167, v164
	s_waitcnt vmcnt(1)
	v_mov_b32_e32 v168, v157
	v_mov_b32_e32 v169, v158
	ds_bpermute_b32 v157, v153, v120
	ds_bpermute_b32 v158, v153, v116
	s_waitcnt vmcnt(0)
	v_pk_mul_f32 v[164:165], v[180:181], v[166:167]
	ds_bpermute_b32 v167, v153, v113
	v_mad_i64_i32 v[180:181], s[24:25], v134, s14, v[140:141]
	s_waitcnt lgkmcnt(2)
	v_mul_f32_e32 v173, v152, v157
	s_waitcnt lgkmcnt(1)
	v_mul_f32_e32 v158, v152, v158
	v_mov_b32_e32 v157, v159
	v_mov_b32_e32 v159, v112
	v_pk_fma_f32 v[158:159], v[162:163], v[158:159], v[164:165]
	ds_bpermute_b32 v163, v153, v121
	ds_bpermute_b32 v164, v153, v117
	v_pk_mul_f32 v[156:157], v[172:173], v[156:157]
	v_mul_f32_e32 v162, v152, v161
	v_pk_fma_f32 v[156:157], v[168:169], v[170:171], v[156:157]
	s_waitcnt lgkmcnt(1)
	v_mul_f32_e32 v165, v152, v163
	s_waitcnt lgkmcnt(0)
	v_mul_f32_e32 v166, v152, v164
	v_mul_f32_e32 v171, v152, v167
	v_mad_i64_i32 v[172:173], s[24:25], v148, s13, v[138:139]
	v_mov_b32_e32 v164, v125
	v_mov_b32_e32 v161, v128
	v_mov_b32_e32 v170, v117
	v_mov_b32_e32 v148, v129
	v_cvt_pk_bf16_f32 v168, v156, v157
	v_cvt_pk_bf16_f32 v169, v158, v159
	v_mov_b32_e32 v163, v121
	v_pk_mul_f32 v[160:161], v[164:165], v[160:161]
	v_mov_b32_e32 v167, v113
	v_pk_mul_f32 v[148:149], v[170:171], v[148:149]
	v_pk_fma_f32 v[160:161], v[150:151], v[162:163], v[160:161]
	v_pk_fma_f32 v[162:163], v[130:131], v[166:167], v[148:149]
	v_cvt_pk_bf16_f32 v128, v160, v161
	global_store_dwordx2 v[182:183], v[168:169], off nt
	global_store_dwordx4 v[184:185], v[156:159], off nt
	v_cvt_pk_bf16_f32 v129, v162, v163
	global_store_dwordx2 v[172:173], v[128:129], off nt
	global_store_dwordx4 v[180:181], v[160:163], off nt
	v_bitop3_b32 v128, v154, 30, 2 bitop3:0xc8
	v_lshlrev_b32_e32 v134, 8, v128
	v_lshl_add_u64 v[150:151], v[142:143], 0, v[134:135]
	v_add_co_u32_e32 v156, vcc, s33, v150
	v_or_b32_e32 v165, v155, v128
	s_nop 0
	v_addc_co_u32_e32 v157, vcc, 0, v151, vcc
	global_load_dwordx3 v[160:162], v[156:157], off offset:256
	v_lshl_add_u64 v[150:151], v[150:151], 0, s[84:85]
	global_load_dwordx4 v[128:131], v[156:157], off offset:268
	global_load_dword v149, v[156:157], off offset:284
	ds_bpermute_b32 v134, v153, v126
	v_mov_b32_e32 v180, v118
	v_or_b32_e32 v148, 2, v154
	v_mad_i64_i32 v[184:185], s[24:25], v148, s14, v[140:141]
	s_waitcnt lgkmcnt(0)
	v_mul_f32_e32 v170, v152, v134
	v_or_b32_e32 v134, 3, v154
	v_and_or_b32 v148, v134, 31, v155
	ds_bpermute_b32 v155, v153, v119
	v_mov_b32_e32 v172, v126
	v_mov_b32_e32 v171, v122
	v_mad_i64_i32 v[182:183], s[24:25], v165, s13, v[138:139]
	v_mov_b32_e32 v165, v115
	s_waitcnt vmcnt(2)
	v_mov_b32_e32 v167, v162
	v_mov_b32_e32 v166, v161
	global_load_dwordx3 v[162:164], v[156:157], off offset:20
	s_nop 0
	global_load_dwordx4 v[156:159], v[156:157], off
	s_nop 0
	global_load_dword v150, v[150:151], off offset:16
	ds_bpermute_b32 v151, v153, v122
	ds_bpermute_b32 v161, v153, v114
	s_waitcnt lgkmcnt(1)
	v_mul_f32_e32 v173, v152, v151
	s_waitcnt lgkmcnt(0)
	v_mul_f32_e32 v181, v152, v161
	ds_bpermute_b32 v161, v153, v115
	s_waitcnt vmcnt(2)
	v_mov_b32_e32 v151, v164
	s_waitcnt vmcnt(1)
	v_mov_b32_e32 v168, v157
	ds_bpermute_b32 v157, v153, v118
	v_mov_b32_e32 v169, v158
	s_waitcnt vmcnt(0)
	v_pk_mul_f32 v[150:151], v[180:181], v[150:151]
	v_mul_f32_e32 v164, v152, v155
	v_mad_i64_i32 v[180:181], s[24:25], v134, s14, v[140:141]
	s_waitcnt lgkmcnt(0)
	v_mul_f32_e32 v158, v152, v157
	v_mov_b32_e32 v157, v159
	v_mov_b32_e32 v159, v114
	v_pk_fma_f32 v[158:159], v[162:163], v[158:159], v[150:151]
	ds_bpermute_b32 v151, v153, v123
	ds_bpermute_b32 v150, v153, v127
	v_pk_mul_f32 v[156:157], v[172:173], v[156:157]
	v_mad_i64_i32 v[172:173], s[24:25], v148, s13, v[138:139]
	v_pk_fma_f32 v[156:157], v[168:169], v[170:171], v[156:157]
	s_waitcnt lgkmcnt(1)
	v_mul_f32_e32 v163, v152, v151
	v_mul_f32_e32 v171, v152, v161
	v_mov_b32_e32 v162, v127
	v_mov_b32_e32 v161, v128
	v_mov_b32_e32 v170, v119
	v_mov_b32_e32 v148, v129
	v_cvt_pk_bf16_f32 v168, v156, v157
	v_cvt_pk_bf16_f32 v169, v158, v159
	s_waitcnt lgkmcnt(0)
	v_mul_f32_e32 v150, v152, v150
	v_mov_b32_e32 v151, v123
	v_pk_mul_f32 v[160:161], v[162:163], v[160:161]
	v_pk_mul_f32 v[148:149], v[170:171], v[148:149]
	v_pk_fma_f32 v[160:161], v[166:167], v[150:151], v[160:161]
	v_pk_fma_f32 v[162:163], v[130:131], v[164:165], v[148:149]
	v_cvt_pk_bf16_f32 v128, v160, v161
	global_store_dwordx2 v[182:183], v[168:169], off nt
	global_store_dwordx4 v[184:185], v[156:159], off nt
	v_cvt_pk_bf16_f32 v129, v162, v163
	global_store_dwordx2 v[172:173], v[128:129], off nt
	global_store_dwordx4 v[180:181], v[160:163], off nt
	v_add_u32_e32 v148, 16, v154
	v_and_b32_e32 v129, 28, v148
	v_lshlrev_b32_e32 v134, 8, v129
	v_lshl_add_u64 v[150:151], v[142:143], 0, v[134:135]
	v_add_co_u32_e32 v156, vcc, s33, v150
	v_lshrrev_b32_e32 v128, 5, v148
	s_nop 0
	v_addc_co_u32_e32 v157, vcc, 0, v151, vcc
	global_load_dwordx3 v[160:162], v[156:157], off offset:256
	v_mul_lo_u32 v128, v128, s12
	v_or_b32_e32 v128, v128, v129
	v_lshl_add_u64 v[150:151], v[150:151], 0, s[84:85]
	v_add_u32_e32 v155, 0x1000, v128
	global_load_dwordx4 v[128:131], v[156:157], off offset:268
	global_load_dword v149, v[156:157], off offset:284
	ds_bpermute_b32 v134, v153, v108
	v_mov_b32_e32 v180, v100
	v_mad_i64_i32 v[182:183], s[24:25], v155, s13, v[138:139]
	v_mad_i64_i32 v[184:185], s[24:25], v148, s14, v[140:141]
	s_waitcnt lgkmcnt(0)
	v_mul_f32_e32 v170, v152, v134
	v_add_u32_e32 v134, 17, v154
	v_lshrrev_b32_e32 v148, 5, v134
	ds_bpermute_b32 v155, v153, v101
	v_mul_lo_u32 v148, v148, s12
	v_mov_b32_e32 v172, v108
	v_and_or_b32 v148, v134, 29, v148
	v_mov_b32_e32 v171, v104
	v_add_u32_e32 v148, 0x1000, v148
	v_mov_b32_e32 v165, v97
	s_waitcnt vmcnt(2)
	v_mov_b32_e32 v167, v162
	v_mov_b32_e32 v166, v161
	global_load_dwordx3 v[162:164], v[156:157], off offset:20
	s_nop 0
	global_load_dwordx4 v[156:159], v[156:157], off
	s_nop 0
	global_load_dword v150, v[150:151], off offset:16
	ds_bpermute_b32 v151, v153, v104
	ds_bpermute_b32 v161, v153, v96
	s_waitcnt lgkmcnt(1)
	v_mul_f32_e32 v173, v152, v151
	s_waitcnt lgkmcnt(0)
	v_mul_f32_e32 v181, v152, v161
	ds_bpermute_b32 v161, v153, v97
	s_waitcnt vmcnt(2)
	v_mov_b32_e32 v151, v164
	s_waitcnt vmcnt(1)
	v_mov_b32_e32 v168, v157
	ds_bpermute_b32 v157, v153, v100
	v_mov_b32_e32 v169, v158
	s_waitcnt vmcnt(0)
	v_pk_mul_f32 v[150:151], v[180:181], v[150:151]
	v_mul_f32_e32 v164, v152, v155
	v_mad_i64_i32 v[180:181], s[24:25], v134, s14, v[140:141]
	s_waitcnt lgkmcnt(0)
	v_mul_f32_e32 v158, v152, v157
	v_mov_b32_e32 v157, v159
	v_mov_b32_e32 v159, v96
	v_pk_fma_f32 v[158:159], v[162:163], v[158:159], v[150:151]
	ds_bpermute_b32 v151, v153, v105
	ds_bpermute_b32 v150, v153, v109
	v_pk_mul_f32 v[156:157], v[172:173], v[156:157]
	v_mad_i64_i32 v[172:173], s[24:25], v148, s13, v[138:139]
	v_pk_fma_f32 v[156:157], v[168:169], v[170:171], v[156:157]
	s_waitcnt lgkmcnt(1)
	v_mul_f32_e32 v163, v152, v151
	v_mul_f32_e32 v171, v152, v161
	v_mov_b32_e32 v162, v109
	v_mov_b32_e32 v161, v128
	v_mov_b32_e32 v170, v101
	v_mov_b32_e32 v148, v129
	v_cvt_pk_bf16_f32 v168, v156, v157
	v_cvt_pk_bf16_f32 v169, v158, v159
	s_waitcnt lgkmcnt(0)
	v_mul_f32_e32 v150, v152, v150
	v_mov_b32_e32 v151, v105
	v_pk_mul_f32 v[160:161], v[162:163], v[160:161]
	v_pk_mul_f32 v[148:149], v[170:171], v[148:149]
	v_pk_fma_f32 v[160:161], v[166:167], v[150:151], v[160:161]
	v_pk_fma_f32 v[162:163], v[130:131], v[164:165], v[148:149]
	v_cvt_pk_bf16_f32 v128, v160, v161
	global_store_dwordx2 v[182:183], v[168:169], off nt
	global_store_dwordx4 v[184:185], v[156:159], off nt
	v_cvt_pk_bf16_f32 v129, v162, v163
	global_store_dwordx2 v[172:173], v[128:129], off nt
	global_store_dwordx4 v[180:181], v[160:163], off nt
	v_add_u32_e32 v148, 18, v154
	v_and_b32_e32 v129, 30, v148
	v_lshlrev_b32_e32 v134, 8, v129
	v_lshl_add_u64 v[150:151], v[142:143], 0, v[134:135]
	v_add_co_u32_e32 v156, vcc, s33, v150
	v_lshrrev_b32_e32 v128, 5, v148
	s_nop 0
	v_addc_co_u32_e32 v157, vcc, 0, v151, vcc
	global_load_dwordx3 v[160:162], v[156:157], off offset:256
	v_mul_lo_u32 v128, v128, s12
	v_or_b32_e32 v128, v128, v129
	v_add_u32_e32 v155, 0x1000, v128
	global_load_dwordx4 v[128:131], v[156:157], off offset:268
	global_load_dword v149, v[156:157], off offset:284
	v_lshl_add_u64 v[150:151], v[150:151], 0, s[84:85]
	ds_bpermute_b32 v134, v153, v110
	v_mov_b32_e32 v182, v102
	v_mad_i64_i32 v[184:185], s[24:25], v155, s13, v[138:139]
	ds_bpermute_b32 v155, v153, v111
	s_waitcnt lgkmcnt(1)
	v_mul_f32_e32 v172, v152, v134
	v_add_u32_e32 v134, 19, v154
	v_mov_b32_e32 v180, v110
	v_mov_b32_e32 v173, v106
	s_waitcnt vmcnt(2)
	v_mov_b32_e32 v167, v162
	v_mov_b32_e32 v166, v161
	global_load_dwordx3 v[162:164], v[156:157], off offset:20
	s_nop 0
	global_load_dwordx4 v[156:159], v[156:157], off
	s_nop 0
	global_load_dword v168, v[150:151], off offset:16
	ds_bpermute_b32 v151, v153, v102
	ds_bpermute_b32 v150, v153, v106
	ds_bpermute_b32 v161, v153, v107
	s_waitcnt lgkmcnt(1)
	v_mul_f32_e32 v181, v152, v150
	s_waitcnt vmcnt(2)
	v_mov_b32_e32 v169, v164
	s_waitcnt vmcnt(1)
	v_mov_b32_e32 v170, v157
	ds_bpermute_b32 v157, v153, v98
	v_mov_b32_e32 v171, v158
	v_mul_f32_e32 v158, v152, v151
	v_mad_i64_i32 v[150:151], s[24:25], v148, s14, v[140:141]
	s_waitcnt lgkmcnt(0)
	v_mul_f32_e32 v183, v152, v157
	v_mov_b32_e32 v157, v159
	v_mov_b32_e32 v159, v98
	s_waitcnt vmcnt(0)
	v_pk_mul_f32 v[164:165], v[182:183], v[168:169]
	v_lshrrev_b32_e32 v148, 5, v134
	v_pk_fma_f32 v[158:159], v[162:163], v[158:159], v[164:165]
	ds_bpermute_b32 v164, v153, v99
	ds_bpermute_b32 v163, v153, v103
	v_mul_lo_u32 v148, v148, s12
	v_and_or_b32 v148, v134, 31, v148
	v_pk_mul_f32 v[156:157], v[180:181], v[156:157]
	v_add_u32_e32 v148, 0x1000, v148
	v_pk_fma_f32 v[156:157], v[170:171], v[172:173], v[156:157]
	v_mul_f32_e32 v165, v152, v161
	s_waitcnt lgkmcnt(1)
	v_mul_f32_e32 v173, v152, v164
	v_mad_i64_i32 v[180:181], s[24:25], v148, s13, v[138:139]
	v_mov_b32_e32 v164, v111
	v_mov_b32_e32 v161, v128
	v_mov_b32_e32 v172, v103
	v_mov_b32_e32 v148, v129
	v_cvt_pk_bf16_f32 v170, v156, v157
	v_cvt_pk_bf16_f32 v171, v158, v159
	v_mul_f32_e32 v162, v152, v155
	s_waitcnt lgkmcnt(0)
	v_mul_f32_e32 v168, v152, v163
	v_mov_b32_e32 v163, v107
	v_pk_mul_f32 v[160:161], v[164:165], v[160:161]
	v_mov_b32_e32 v169, v99
	v_pk_mul_f32 v[148:149], v[172:173], v[148:149]
	v_mad_i64_i32 v[182:183], s[24:25], v134, s14, v[140:141]
	v_pk_fma_f32 v[160:161], v[166:167], v[162:163], v[160:161]
	v_pk_fma_f32 v[162:163], v[130:131], v[168:169], v[148:149]
	v_cvt_pk_bf16_f32 v128, v160, v161
	global_store_dwordx2 v[184:185], v[170:171], off nt
	global_store_dwordx4 v[150:151], v[156:159], off nt
	v_cvt_pk_bf16_f32 v129, v162, v163
	global_store_dwordx2 v[180:181], v[128:129], off nt
	global_store_dwordx4 v[182:183], v[160:163], off nt
	v_add_u32_e32 v134, 32, v154
	global_load_dwordx3 v[160:162], v[146:147], off offset:256
	v_lshrrev_b32_e32 v128, 5, v134
	v_mul_lo_u32 v128, v128, s12
	v_or_b32_e32 v128, v128, v137
	v_add_u32_e32 v148, 0x1000, v128
	ds_bpermute_b32 v155, v153, v92
	v_mov_b32_e32 v180, v84
	v_mad_i64_i32 v[184:185], s[24:25], v134, s14, v[140:141]
	v_add_u32_e32 v134, 33, v154
	s_waitcnt lgkmcnt(0)
	v_mul_f32_e32 v170, v152, v155
	v_mad_i64_i32 v[182:183], s[24:25], v148, s13, v[138:139]
	v_lshrrev_b32_e32 v148, 5, v134
	ds_bpermute_b32 v155, v153, v93
	v_mul_lo_u32 v148, v148, s12
	v_mov_b32_e32 v172, v92
	v_and_or_b32 v148, v134, 29, v148
	v_mov_b32_e32 v171, v88
	v_add_u32_e32 v148, 0x1000, v148
	s_waitcnt vmcnt(0)
	v_mov_b32_e32 v150, v161
	v_mov_b32_e32 v151, v162
	global_load_dwordx4 v[128:131], v[146:147], off offset:268
	global_load_dword v149, v[146:147], off offset:284
	global_load_dwordx3 v[162:164], v[146:147], off offset:20
	global_load_dwordx4 v[156:159], v[146:147], off
	global_load_dword v166, v[144:145], off offset:16
	ds_bpermute_b32 v161, v153, v80
	s_waitcnt lgkmcnt(0)
	v_mul_f32_e32 v181, v152, v161
	ds_bpermute_b32 v161, v153, v89
	s_waitcnt vmcnt(2)
	v_mov_b32_e32 v167, v164
	s_waitcnt vmcnt(1)
	v_mov_b32_e32 v168, v157
	v_mov_b32_e32 v169, v158
	ds_bpermute_b32 v157, v153, v88
	ds_bpermute_b32 v158, v153, v84
	s_waitcnt vmcnt(0)
	v_pk_mul_f32 v[164:165], v[180:181], v[166:167]
	v_mov_b32_e32 v167, v81
	v_mad_i64_i32 v[180:181], s[24:25], v134, s14, v[140:141]
	s_waitcnt lgkmcnt(1)
	v_mul_f32_e32 v173, v152, v157
	s_waitcnt lgkmcnt(0)
	v_mul_f32_e32 v158, v152, v158
	v_mov_b32_e32 v157, v159
	v_mov_b32_e32 v159, v80
	v_pk_fma_f32 v[158:159], v[162:163], v[158:159], v[164:165]
	ds_bpermute_b32 v164, v153, v81
	ds_bpermute_b32 v163, v153, v85
	v_pk_mul_f32 v[156:157], v[172:173], v[156:157]
	v_mul_f32_e32 v165, v152, v161
	v_pk_fma_f32 v[156:157], v[168:169], v[170:171], v[156:157]
	s_waitcnt lgkmcnt(1)
	v_mul_f32_e32 v171, v152, v164
	v_mad_i64_i32 v[172:173], s[24:25], v148, s13, v[138:139]
	v_mov_b32_e32 v164, v93
	v_mov_b32_e32 v161, v128
	v_mov_b32_e32 v170, v85
	v_mov_b32_e32 v148, v129
	v_cvt_pk_bf16_f32 v168, v156, v157
	v_cvt_pk_bf16_f32 v169, v158, v159
	v_mul_f32_e32 v162, v152, v155
	s_waitcnt lgkmcnt(0)
	v_mul_f32_e32 v166, v152, v163
	v_mov_b32_e32 v163, v89
	v_pk_mul_f32 v[160:161], v[164:165], v[160:161]
	v_pk_mul_f32 v[148:149], v[170:171], v[148:149]
	v_pk_fma_f32 v[160:161], v[150:151], v[162:163], v[160:161]
	v_pk_fma_f32 v[162:163], v[130:131], v[166:167], v[148:149]
	v_cvt_pk_bf16_f32 v128, v160, v161
	global_store_dwordx2 v[182:183], v[168:169], off nt
	global_store_dwordx4 v[184:185], v[156:159], off nt
	v_cvt_pk_bf16_f32 v129, v162, v163
	global_store_dwordx2 v[172:173], v[128:129], off nt
	global_store_dwordx4 v[180:181], v[160:163], off nt
	v_add_u32_e32 v148, 34, v154
	v_and_b32_e32 v129, 30, v148
	v_lshlrev_b32_e32 v134, 8, v129
	v_lshl_add_u64 v[150:151], v[142:143], 0, v[134:135]
	v_add_co_u32_e32 v156, vcc, s33, v150
	v_lshrrev_b32_e32 v128, 5, v148
	s_nop 0
	v_addc_co_u32_e32 v157, vcc, 0, v151, vcc
	global_load_dwordx3 v[160:162], v[156:157], off offset:256
	v_mul_lo_u32 v128, v128, s12
	v_or_b32_e32 v128, v128, v129
	v_add_u32_e32 v155, 0x1000, v128
	global_load_dwordx4 v[128:131], v[156:157], off offset:268
	global_load_dword v149, v[156:157], off offset:284
	v_lshl_add_u64 v[150:151], v[150:151], 0, s[84:85]
	ds_bpermute_b32 v134, v153, v94
	v_mov_b32_e32 v182, v86
	v_mad_i64_i32 v[184:185], s[24:25], v155, s13, v[138:139]
	ds_bpermute_b32 v155, v153, v95
	s_waitcnt lgkmcnt(1)
	v_mul_f32_e32 v172, v152, v134
	v_add_u32_e32 v134, 35, v154
	v_mov_b32_e32 v180, v94
	v_mov_b32_e32 v173, v90
	s_waitcnt vmcnt(2)
	v_mov_b32_e32 v167, v162
	v_mov_b32_e32 v166, v161
	global_load_dwordx3 v[162:164], v[156:157], off offset:20
	s_nop 0
	global_load_dwordx4 v[156:159], v[156:157], off
	s_nop 0
	global_load_dword v168, v[150:151], off offset:16
	ds_bpermute_b32 v151, v153, v86
	ds_bpermute_b32 v150, v153, v90
	ds_bpermute_b32 v161, v153, v91
	s_waitcnt lgkmcnt(1)
	v_mul_f32_e32 v181, v152, v150
	s_waitcnt vmcnt(2)
	v_mov_b32_e32 v169, v164
	s_waitcnt vmcnt(1)
	v_mov_b32_e32 v170, v157
	ds_bpermute_b32 v157, v153, v82
	v_mov_b32_e32 v171, v158
	v_mul_f32_e32 v158, v152, v151
	v_mad_i64_i32 v[150:151], s[24:25], v148, s14, v[140:141]
	s_waitcnt lgkmcnt(0)
	v_mul_f32_e32 v183, v152, v157
	v_mov_b32_e32 v157, v159
	v_mov_b32_e32 v159, v82
	s_waitcnt vmcnt(0)
	v_pk_mul_f32 v[164:165], v[182:183], v[168:169]
	v_lshrrev_b32_e32 v148, 5, v134
	v_pk_fma_f32 v[158:159], v[162:163], v[158:159], v[164:165]
	ds_bpermute_b32 v164, v153, v83
	ds_bpermute_b32 v163, v153, v87
	v_mul_lo_u32 v148, v148, s12
	v_and_or_b32 v148, v134, 31, v148
	v_pk_mul_f32 v[156:157], v[180:181], v[156:157]
	v_add_u32_e32 v148, 0x1000, v148
	v_pk_fma_f32 v[156:157], v[170:171], v[172:173], v[156:157]
	v_mul_f32_e32 v165, v152, v161
	s_waitcnt lgkmcnt(1)
	v_mul_f32_e32 v173, v152, v164
	v_mad_i64_i32 v[180:181], s[24:25], v148, s13, v[138:139]
	v_mov_b32_e32 v164, v95
	v_mov_b32_e32 v161, v128
	v_mov_b32_e32 v172, v87
	v_mov_b32_e32 v148, v129
	v_cvt_pk_bf16_f32 v170, v156, v157
	v_cvt_pk_bf16_f32 v171, v158, v159
	v_mul_f32_e32 v162, v152, v155
	s_waitcnt lgkmcnt(0)
	v_mul_f32_e32 v168, v152, v163
	v_mov_b32_e32 v163, v91
	v_pk_mul_f32 v[160:161], v[164:165], v[160:161]
	v_mov_b32_e32 v169, v83
	v_pk_mul_f32 v[148:149], v[172:173], v[148:149]
	v_mad_i64_i32 v[182:183], s[24:25], v134, s14, v[140:141]
	v_pk_fma_f32 v[160:161], v[166:167], v[162:163], v[160:161]
	v_pk_fma_f32 v[162:163], v[130:131], v[168:169], v[148:149]
	v_cvt_pk_bf16_f32 v128, v160, v161
	global_store_dwordx2 v[184:185], v[170:171], off nt
	global_store_dwordx4 v[150:151], v[156:159], off nt
	v_cvt_pk_bf16_f32 v129, v162, v163
	global_store_dwordx2 v[180:181], v[128:129], off nt
	global_store_dwordx4 v[182:183], v[160:163], off nt
	v_add_u32_e32 v148, 48, v154
	v_and_b32_e32 v129, 28, v148
	v_lshlrev_b32_e32 v134, 8, v129
	v_lshl_add_u64 v[150:151], v[142:143], 0, v[134:135]
	v_add_co_u32_e32 v156, vcc, s33, v150
	v_lshrrev_b32_e32 v128, 5, v148
	s_nop 0
	v_addc_co_u32_e32 v157, vcc, 0, v151, vcc
	global_load_dwordx3 v[160:162], v[156:157], off offset:256
	v_mul_lo_u32 v128, v128, s12
	v_or_b32_e32 v128, v128, v129
	v_lshl_add_u64 v[150:151], v[150:151], 0, s[84:85]
	v_add_u32_e32 v155, 0x1000, v128
	global_load_dwordx4 v[128:131], v[156:157], off offset:268
	global_load_dword v149, v[156:157], off offset:284
	ds_bpermute_b32 v134, v153, v76
	v_mov_b32_e32 v180, v68
	v_mad_i64_i32 v[182:183], s[24:25], v155, s13, v[138:139]
	v_mad_i64_i32 v[184:185], s[24:25], v148, s14, v[140:141]
	s_waitcnt lgkmcnt(0)
	v_mul_f32_e32 v170, v152, v134
	v_add_u32_e32 v134, 49, v154
	v_lshrrev_b32_e32 v148, 5, v134
	ds_bpermute_b32 v155, v153, v69
	v_mul_lo_u32 v148, v148, s12
	v_mov_b32_e32 v172, v76
	v_and_or_b32 v148, v134, 29, v148
	v_mov_b32_e32 v171, v72
	v_add_u32_e32 v148, 0x1000, v148
	v_mov_b32_e32 v165, v65
	s_waitcnt vmcnt(2)
	v_mov_b32_e32 v167, v162
	v_mov_b32_e32 v166, v161
	global_load_dwordx3 v[162:164], v[156:157], off offset:20
	s_nop 0
	global_load_dwordx4 v[156:159], v[156:157], off
	s_nop 0
	global_load_dword v150, v[150:151], off offset:16
	ds_bpermute_b32 v151, v153, v72
	ds_bpermute_b32 v161, v153, v64
	s_waitcnt lgkmcnt(1)
	v_mul_f32_e32 v173, v152, v151
	s_waitcnt lgkmcnt(0)
	v_mul_f32_e32 v181, v152, v161
	ds_bpermute_b32 v161, v153, v65
	s_waitcnt vmcnt(2)
	v_mov_b32_e32 v151, v164
	s_waitcnt vmcnt(1)
	v_mov_b32_e32 v168, v157
	ds_bpermute_b32 v157, v153, v68
	v_mov_b32_e32 v169, v158
	s_waitcnt vmcnt(0)
	v_pk_mul_f32 v[150:151], v[180:181], v[150:151]
	v_mul_f32_e32 v164, v152, v155
	v_mad_i64_i32 v[180:181], s[24:25], v134, s14, v[140:141]
	s_waitcnt lgkmcnt(0)
	v_mul_f32_e32 v158, v152, v157
	v_mov_b32_e32 v157, v159
	v_mov_b32_e32 v159, v64
	v_pk_fma_f32 v[158:159], v[162:163], v[158:159], v[150:151]
	ds_bpermute_b32 v151, v153, v73
	ds_bpermute_b32 v150, v153, v77
	v_pk_mul_f32 v[156:157], v[172:173], v[156:157]
	v_mad_i64_i32 v[172:173], s[24:25], v148, s13, v[138:139]
	v_pk_fma_f32 v[156:157], v[168:169], v[170:171], v[156:157]
	s_waitcnt lgkmcnt(1)
	v_mul_f32_e32 v163, v152, v151
	v_mul_f32_e32 v171, v152, v161
	v_mov_b32_e32 v162, v77
	v_mov_b32_e32 v161, v128
	v_mov_b32_e32 v170, v69
	v_mov_b32_e32 v148, v129
	v_cvt_pk_bf16_f32 v168, v156, v157
	v_cvt_pk_bf16_f32 v169, v158, v159
	s_waitcnt lgkmcnt(0)
	v_mul_f32_e32 v150, v152, v150
	v_mov_b32_e32 v151, v73
	v_pk_mul_f32 v[160:161], v[162:163], v[160:161]
	v_pk_mul_f32 v[148:149], v[170:171], v[148:149]
	v_pk_fma_f32 v[160:161], v[166:167], v[150:151], v[160:161]
	v_pk_fma_f32 v[162:163], v[130:131], v[164:165], v[148:149]
	v_cvt_pk_bf16_f32 v128, v160, v161
	global_store_dwordx2 v[182:183], v[168:169], off nt
	global_store_dwordx4 v[184:185], v[156:159], off nt
	v_cvt_pk_bf16_f32 v129, v162, v163
	global_store_dwordx2 v[172:173], v[128:129], off nt
	global_store_dwordx4 v[180:181], v[160:163], off nt
	v_add_u32_e32 v148, 50, v154
	v_and_b32_e32 v129, 30, v148
	v_lshlrev_b32_e32 v134, 8, v129
	v_lshl_add_u64 v[150:151], v[142:143], 0, v[134:135]
	v_add_co_u32_e32 v156, vcc, s33, v150
	v_lshrrev_b32_e32 v128, 5, v148
	s_nop 0
	v_addc_co_u32_e32 v157, vcc, 0, v151, vcc
	global_load_dwordx3 v[160:162], v[156:157], off offset:256
	v_mul_lo_u32 v128, v128, s12
	v_or_b32_e32 v128, v128, v129
	v_add_u32_e32 v155, 0x1000, v128
	global_load_dwordx4 v[128:131], v[156:157], off offset:268
	global_load_dword v149, v[156:157], off offset:284
	v_lshl_add_u64 v[150:151], v[150:151], 0, s[84:85]
	ds_bpermute_b32 v134, v153, v78
	v_mov_b32_e32 v182, v70
	v_mad_i64_i32 v[184:185], s[24:25], v155, s13, v[138:139]
	ds_bpermute_b32 v155, v153, v79
	s_waitcnt lgkmcnt(1)
	v_mul_f32_e32 v172, v152, v134
	v_add_u32_e32 v134, 51, v154
	v_mov_b32_e32 v180, v78
	v_mov_b32_e32 v173, v74
	s_waitcnt vmcnt(2)
	v_mov_b32_e32 v167, v162
	v_mov_b32_e32 v166, v161
	global_load_dwordx3 v[162:164], v[156:157], off offset:20
	s_nop 0
	global_load_dwordx4 v[156:159], v[156:157], off
	s_nop 0
	global_load_dword v168, v[150:151], off offset:16
	ds_bpermute_b32 v151, v153, v70
	ds_bpermute_b32 v150, v153, v74
	ds_bpermute_b32 v161, v153, v75
	s_waitcnt lgkmcnt(1)
	v_mul_f32_e32 v181, v152, v150
	s_waitcnt vmcnt(2)
	v_mov_b32_e32 v169, v164
	s_waitcnt vmcnt(1)
	v_mov_b32_e32 v170, v157
	ds_bpermute_b32 v157, v153, v66
	v_mov_b32_e32 v171, v158
	v_mul_f32_e32 v158, v152, v151
	v_mad_i64_i32 v[150:151], s[24:25], v148, s14, v[140:141]
	s_waitcnt lgkmcnt(0)
	v_mul_f32_e32 v183, v152, v157
	v_mov_b32_e32 v157, v159
	v_mov_b32_e32 v159, v66
	s_waitcnt vmcnt(0)
	v_pk_mul_f32 v[164:165], v[182:183], v[168:169]
	v_lshrrev_b32_e32 v148, 5, v134
	v_pk_fma_f32 v[158:159], v[162:163], v[158:159], v[164:165]
	ds_bpermute_b32 v164, v153, v67
	ds_bpermute_b32 v163, v153, v71
	v_mul_lo_u32 v148, v148, s12
	v_and_or_b32 v148, v134, 31, v148
	v_pk_mul_f32 v[156:157], v[180:181], v[156:157]
	v_add_u32_e32 v148, 0x1000, v148
	v_pk_fma_f32 v[156:157], v[170:171], v[172:173], v[156:157]
	v_mul_f32_e32 v165, v152, v161
	s_waitcnt lgkmcnt(1)
	v_mul_f32_e32 v173, v152, v164
	v_mad_i64_i32 v[180:181], s[24:25], v148, s13, v[138:139]
	v_mov_b32_e32 v164, v79
	v_mov_b32_e32 v161, v128
	v_mov_b32_e32 v172, v71
	v_mov_b32_e32 v148, v129
	v_cvt_pk_bf16_f32 v170, v156, v157
	v_cvt_pk_bf16_f32 v171, v158, v159
	v_mul_f32_e32 v162, v152, v155
	s_waitcnt lgkmcnt(0)
	v_mul_f32_e32 v168, v152, v163
	v_mov_b32_e32 v163, v75
	v_pk_mul_f32 v[160:161], v[164:165], v[160:161]
	v_mov_b32_e32 v169, v67
	v_pk_mul_f32 v[148:149], v[172:173], v[148:149]
	v_mad_i64_i32 v[182:183], s[24:25], v134, s14, v[140:141]
	v_pk_fma_f32 v[160:161], v[166:167], v[162:163], v[160:161]
	v_pk_fma_f32 v[162:163], v[130:131], v[168:169], v[148:149]
	v_cvt_pk_bf16_f32 v128, v160, v161
	global_store_dwordx2 v[184:185], v[170:171], off nt
	global_store_dwordx4 v[150:151], v[156:159], off nt
	v_cvt_pk_bf16_f32 v129, v162, v163
	global_store_dwordx2 v[180:181], v[128:129], off nt
	global_store_dwordx4 v[182:183], v[160:163], off nt
	v_add_u32_e32 v134, 64, v154
	global_load_dwordx3 v[160:162], v[146:147], off offset:256
	v_lshrrev_b32_e32 v128, 5, v134
	v_mul_lo_u32 v128, v128, s12
	v_or_b32_e32 v128, v128, v137
	v_add_u32_e32 v148, 0x1000, v128
	ds_bpermute_b32 v155, v153, v60
	v_mov_b32_e32 v180, v52
	v_mad_i64_i32 v[184:185], s[24:25], v134, s14, v[140:141]
	v_add_u32_e32 v134, 0x41, v154
	s_waitcnt lgkmcnt(0)
	v_mul_f32_e32 v170, v152, v155
	v_mad_i64_i32 v[182:183], s[24:25], v148, s13, v[138:139]
	v_lshrrev_b32_e32 v148, 5, v134
	ds_bpermute_b32 v155, v153, v61
	v_mul_lo_u32 v148, v148, s12
	v_mov_b32_e32 v172, v60
	v_and_or_b32 v148, v134, 29, v148
	v_mov_b32_e32 v171, v56
	v_add_u32_e32 v148, 0x1000, v148
	s_waitcnt vmcnt(0)
	v_mov_b32_e32 v150, v161
	v_mov_b32_e32 v151, v162
	global_load_dwordx4 v[128:131], v[146:147], off offset:268
	global_load_dword v149, v[146:147], off offset:284
	global_load_dwordx3 v[162:164], v[146:147], off offset:20
	global_load_dwordx4 v[156:159], v[146:147], off
	global_load_dword v166, v[144:145], off offset:16
	ds_bpermute_b32 v161, v153, v48
	s_waitcnt lgkmcnt(0)
	v_mul_f32_e32 v181, v152, v161
	ds_bpermute_b32 v161, v153, v57
	s_waitcnt vmcnt(2)
	v_mov_b32_e32 v167, v164
	s_waitcnt vmcnt(1)
	v_mov_b32_e32 v168, v157
	v_mov_b32_e32 v169, v158
	ds_bpermute_b32 v157, v153, v56
	ds_bpermute_b32 v158, v153, v52
	s_waitcnt vmcnt(0)
	v_pk_mul_f32 v[164:165], v[180:181], v[166:167]
	v_mov_b32_e32 v167, v49
	v_mad_i64_i32 v[180:181], s[24:25], v134, s14, v[140:141]
	s_waitcnt lgkmcnt(1)
	v_mul_f32_e32 v173, v152, v157
	s_waitcnt lgkmcnt(0)
	v_mul_f32_e32 v158, v152, v158
	v_mov_b32_e32 v157, v159
	v_mov_b32_e32 v159, v48
	v_pk_fma_f32 v[158:159], v[162:163], v[158:159], v[164:165]
	ds_bpermute_b32 v164, v153, v49
	ds_bpermute_b32 v163, v153, v53
	v_pk_mul_f32 v[156:157], v[172:173], v[156:157]
	v_mul_f32_e32 v165, v152, v161
	v_pk_fma_f32 v[156:157], v[168:169], v[170:171], v[156:157]
	s_waitcnt lgkmcnt(1)
	v_mul_f32_e32 v171, v152, v164
	v_mad_i64_i32 v[172:173], s[24:25], v148, s13, v[138:139]
	v_mov_b32_e32 v164, v61
	v_mov_b32_e32 v161, v128
	v_mov_b32_e32 v170, v53
	v_mov_b32_e32 v148, v129
	v_cvt_pk_bf16_f32 v168, v156, v157
	v_cvt_pk_bf16_f32 v169, v158, v159
	v_mul_f32_e32 v162, v152, v155
	s_waitcnt lgkmcnt(0)
	v_mul_f32_e32 v166, v152, v163
	v_mov_b32_e32 v163, v57
	v_pk_mul_f32 v[160:161], v[164:165], v[160:161]
	v_pk_mul_f32 v[148:149], v[170:171], v[148:149]
	v_pk_fma_f32 v[160:161], v[150:151], v[162:163], v[160:161]
	v_pk_fma_f32 v[162:163], v[130:131], v[166:167], v[148:149]
	v_cvt_pk_bf16_f32 v128, v160, v161
	global_store_dwordx2 v[182:183], v[168:169], off nt
	global_store_dwordx4 v[184:185], v[156:159], off nt
	v_cvt_pk_bf16_f32 v129, v162, v163
	global_store_dwordx2 v[172:173], v[128:129], off nt
	global_store_dwordx4 v[180:181], v[160:163], off nt
	v_add_u32_e32 v148, 0x42, v154
	v_and_b32_e32 v129, 30, v148
	v_lshlrev_b32_e32 v134, 8, v129
	v_lshl_add_u64 v[150:151], v[142:143], 0, v[134:135]
	v_add_co_u32_e32 v156, vcc, s33, v150
	v_lshrrev_b32_e32 v128, 5, v148
	s_nop 0
	v_addc_co_u32_e32 v157, vcc, 0, v151, vcc
	global_load_dwordx3 v[160:162], v[156:157], off offset:256
	v_mul_lo_u32 v128, v128, s12
	v_or_b32_e32 v128, v128, v129
	v_add_u32_e32 v155, 0x1000, v128
	global_load_dwordx4 v[128:131], v[156:157], off offset:268
	global_load_dword v149, v[156:157], off offset:284
	v_lshl_add_u64 v[150:151], v[150:151], 0, s[84:85]
	ds_bpermute_b32 v134, v153, v62
	v_mov_b32_e32 v182, v54
	v_mad_i64_i32 v[184:185], s[24:25], v155, s13, v[138:139]
	ds_bpermute_b32 v155, v153, v63
	s_waitcnt lgkmcnt(1)
	v_mul_f32_e32 v172, v152, v134
	v_add_u32_e32 v134, 0x43, v154
	v_mov_b32_e32 v180, v62
	v_mov_b32_e32 v173, v58
	s_waitcnt vmcnt(2)
	v_mov_b32_e32 v167, v162
	v_mov_b32_e32 v166, v161
	global_load_dwordx3 v[162:164], v[156:157], off offset:20
	s_nop 0
	global_load_dwordx4 v[156:159], v[156:157], off
	s_nop 0
	global_load_dword v168, v[150:151], off offset:16
	ds_bpermute_b32 v151, v153, v54
	ds_bpermute_b32 v150, v153, v58
	ds_bpermute_b32 v161, v153, v59
	s_waitcnt lgkmcnt(1)
	v_mul_f32_e32 v181, v152, v150
	s_waitcnt vmcnt(2)
	v_mov_b32_e32 v169, v164
	s_waitcnt vmcnt(1)
	v_mov_b32_e32 v170, v157
	ds_bpermute_b32 v157, v153, v50
	v_mov_b32_e32 v171, v158
	v_mul_f32_e32 v158, v152, v151
	v_mad_i64_i32 v[150:151], s[24:25], v148, s14, v[140:141]
	s_waitcnt lgkmcnt(0)
	v_mul_f32_e32 v183, v152, v157
	v_mov_b32_e32 v157, v159
	v_mov_b32_e32 v159, v50
	s_waitcnt vmcnt(0)
	v_pk_mul_f32 v[164:165], v[182:183], v[168:169]
	v_lshrrev_b32_e32 v148, 5, v134
	v_pk_fma_f32 v[158:159], v[162:163], v[158:159], v[164:165]
	ds_bpermute_b32 v164, v153, v51
	ds_bpermute_b32 v163, v153, v55
	v_mul_lo_u32 v148, v148, s12
	v_and_or_b32 v148, v134, 31, v148
	v_pk_mul_f32 v[156:157], v[180:181], v[156:157]
	v_add_u32_e32 v148, 0x1000, v148
	v_pk_fma_f32 v[156:157], v[170:171], v[172:173], v[156:157]
	v_mul_f32_e32 v165, v152, v161
	s_waitcnt lgkmcnt(1)
	v_mul_f32_e32 v173, v152, v164
	v_mad_i64_i32 v[180:181], s[24:25], v148, s13, v[138:139]
	v_mov_b32_e32 v164, v63
	v_mov_b32_e32 v161, v128
	v_mov_b32_e32 v172, v55
	v_mov_b32_e32 v148, v129
	v_cvt_pk_bf16_f32 v170, v156, v157
	v_cvt_pk_bf16_f32 v171, v158, v159
	v_mul_f32_e32 v162, v152, v155
	s_waitcnt lgkmcnt(0)
	v_mul_f32_e32 v168, v152, v163
	v_mov_b32_e32 v163, v59
	v_pk_mul_f32 v[160:161], v[164:165], v[160:161]
	v_mov_b32_e32 v169, v51
	v_pk_mul_f32 v[148:149], v[172:173], v[148:149]
	v_mad_i64_i32 v[182:183], s[24:25], v134, s14, v[140:141]
	v_pk_fma_f32 v[160:161], v[166:167], v[162:163], v[160:161]
	v_pk_fma_f32 v[162:163], v[130:131], v[168:169], v[148:149]
	v_cvt_pk_bf16_f32 v128, v160, v161
	global_store_dwordx2 v[184:185], v[170:171], off nt
	global_store_dwordx4 v[150:151], v[156:159], off nt
	v_cvt_pk_bf16_f32 v129, v162, v163
	global_store_dwordx2 v[180:181], v[128:129], off nt
	global_store_dwordx4 v[182:183], v[160:163], off nt
	v_add_u32_e32 v148, 0x50, v154
	v_and_b32_e32 v129, 28, v148
	v_lshlrev_b32_e32 v134, 8, v129
	v_lshl_add_u64 v[150:151], v[142:143], 0, v[134:135]
	v_add_co_u32_e32 v156, vcc, s33, v150
	v_lshrrev_b32_e32 v128, 5, v148
	s_nop 0
	v_addc_co_u32_e32 v157, vcc, 0, v151, vcc
	global_load_dwordx3 v[160:162], v[156:157], off offset:256
	v_mul_lo_u32 v128, v128, s12
	v_or_b32_e32 v128, v128, v129
	v_lshl_add_u64 v[150:151], v[150:151], 0, s[84:85]
	v_add_u32_e32 v155, 0x1000, v128
	global_load_dwordx4 v[128:131], v[156:157], off offset:268
	global_load_dword v149, v[156:157], off offset:284
	ds_bpermute_b32 v134, v153, v44
	v_mov_b32_e32 v180, v36
	v_mad_i64_i32 v[182:183], s[24:25], v155, s13, v[138:139]
	v_mad_i64_i32 v[184:185], s[24:25], v148, s14, v[140:141]
	s_waitcnt lgkmcnt(0)
	v_mul_f32_e32 v170, v152, v134
	v_add_u32_e32 v134, 0x51, v154
	v_lshrrev_b32_e32 v148, 5, v134
	ds_bpermute_b32 v155, v153, v37
	v_mul_lo_u32 v148, v148, s12
	v_mov_b32_e32 v172, v44
	v_and_or_b32 v148, v134, 29, v148
	v_mov_b32_e32 v171, v40
	v_add_u32_e32 v148, 0x1000, v148
	v_mov_b32_e32 v165, v33
	s_waitcnt vmcnt(2)
	v_mov_b32_e32 v167, v162
	v_mov_b32_e32 v166, v161
	global_load_dwordx3 v[162:164], v[156:157], off offset:20
	s_nop 0
	global_load_dwordx4 v[156:159], v[156:157], off
	s_nop 0
	global_load_dword v150, v[150:151], off offset:16
	ds_bpermute_b32 v151, v153, v40
	ds_bpermute_b32 v161, v153, v32
	s_waitcnt lgkmcnt(1)
	v_mul_f32_e32 v173, v152, v151
	s_waitcnt lgkmcnt(0)
	v_mul_f32_e32 v181, v152, v161
	ds_bpermute_b32 v161, v153, v33
	s_waitcnt vmcnt(2)
	v_mov_b32_e32 v151, v164
	s_waitcnt vmcnt(1)
	v_mov_b32_e32 v168, v157
	ds_bpermute_b32 v157, v153, v36
	v_mov_b32_e32 v169, v158
	s_waitcnt vmcnt(0)
	v_pk_mul_f32 v[150:151], v[180:181], v[150:151]
	v_mul_f32_e32 v164, v152, v155
	v_mad_i64_i32 v[180:181], s[24:25], v134, s14, v[140:141]
	s_waitcnt lgkmcnt(0)
	v_mul_f32_e32 v158, v152, v157
	v_mov_b32_e32 v157, v159
	v_mov_b32_e32 v159, v32
	v_pk_fma_f32 v[158:159], v[162:163], v[158:159], v[150:151]
	ds_bpermute_b32 v151, v153, v41
	ds_bpermute_b32 v150, v153, v45
	v_pk_mul_f32 v[156:157], v[172:173], v[156:157]
	v_mad_i64_i32 v[172:173], s[24:25], v148, s13, v[138:139]
	v_pk_fma_f32 v[156:157], v[168:169], v[170:171], v[156:157]
	s_waitcnt lgkmcnt(1)
	v_mul_f32_e32 v163, v152, v151
	v_mul_f32_e32 v171, v152, v161
	v_mov_b32_e32 v162, v45
	v_mov_b32_e32 v161, v128
	v_mov_b32_e32 v170, v37
	v_mov_b32_e32 v148, v129
	v_cvt_pk_bf16_f32 v168, v156, v157
	v_cvt_pk_bf16_f32 v169, v158, v159
	s_waitcnt lgkmcnt(0)
	v_mul_f32_e32 v150, v152, v150
	v_mov_b32_e32 v151, v41
	v_pk_mul_f32 v[160:161], v[162:163], v[160:161]
	v_pk_mul_f32 v[148:149], v[170:171], v[148:149]
	v_pk_fma_f32 v[160:161], v[166:167], v[150:151], v[160:161]
	v_pk_fma_f32 v[162:163], v[130:131], v[164:165], v[148:149]
	v_cvt_pk_bf16_f32 v128, v160, v161
	global_store_dwordx2 v[182:183], v[168:169], off nt
	global_store_dwordx4 v[184:185], v[156:159], off nt
	v_cvt_pk_bf16_f32 v129, v162, v163
	global_store_dwordx2 v[172:173], v[128:129], off nt
	global_store_dwordx4 v[180:181], v[160:163], off nt
	v_add_u32_e32 v148, 0x52, v154
	v_and_b32_e32 v129, 30, v148
	v_lshlrev_b32_e32 v134, 8, v129
	v_lshl_add_u64 v[150:151], v[142:143], 0, v[134:135]
	v_add_co_u32_e32 v156, vcc, s33, v150
	v_lshrrev_b32_e32 v128, 5, v148
	s_nop 0
	v_addc_co_u32_e32 v157, vcc, 0, v151, vcc
	global_load_dwordx3 v[160:162], v[156:157], off offset:256
	v_mul_lo_u32 v128, v128, s12
	v_or_b32_e32 v128, v128, v129
	v_add_u32_e32 v155, 0x1000, v128
	global_load_dwordx4 v[128:131], v[156:157], off offset:268
	global_load_dword v149, v[156:157], off offset:284
	v_lshl_add_u64 v[150:151], v[150:151], 0, s[84:85]
	ds_bpermute_b32 v134, v153, v46
	v_mov_b32_e32 v182, v38
	v_mad_i64_i32 v[184:185], s[24:25], v155, s13, v[138:139]
	ds_bpermute_b32 v155, v153, v47
	s_waitcnt lgkmcnt(1)
	v_mul_f32_e32 v172, v152, v134
	v_add_u32_e32 v134, 0x53, v154
	v_mov_b32_e32 v180, v46
	v_mov_b32_e32 v173, v42
	s_waitcnt vmcnt(2)
	v_mov_b32_e32 v167, v162
	v_mov_b32_e32 v166, v161
	global_load_dwordx3 v[162:164], v[156:157], off offset:20
	s_nop 0
	global_load_dwordx4 v[156:159], v[156:157], off
	s_nop 0
	global_load_dword v168, v[150:151], off offset:16
	ds_bpermute_b32 v151, v153, v38
	ds_bpermute_b32 v150, v153, v42
	ds_bpermute_b32 v161, v153, v43
	s_waitcnt lgkmcnt(1)
	v_mul_f32_e32 v181, v152, v150
	s_waitcnt vmcnt(2)
	v_mov_b32_e32 v169, v164
	s_waitcnt vmcnt(1)
	v_mov_b32_e32 v170, v157
	ds_bpermute_b32 v157, v153, v34
	v_mov_b32_e32 v171, v158
	v_mul_f32_e32 v158, v152, v151
	v_mad_i64_i32 v[150:151], s[24:25], v148, s14, v[140:141]
	s_waitcnt lgkmcnt(0)
	v_mul_f32_e32 v183, v152, v157
	v_mov_b32_e32 v157, v159
	v_mov_b32_e32 v159, v34
	s_waitcnt vmcnt(0)
	v_pk_mul_f32 v[164:165], v[182:183], v[168:169]
	v_lshrrev_b32_e32 v148, 5, v134
	v_pk_fma_f32 v[158:159], v[162:163], v[158:159], v[164:165]
	ds_bpermute_b32 v164, v153, v35
	ds_bpermute_b32 v163, v153, v39
	v_mul_lo_u32 v148, v148, s12
	v_and_or_b32 v148, v134, 31, v148
	v_pk_mul_f32 v[156:157], v[180:181], v[156:157]
	v_add_u32_e32 v148, 0x1000, v148
	v_pk_fma_f32 v[156:157], v[170:171], v[172:173], v[156:157]
	v_mul_f32_e32 v165, v152, v161
	s_waitcnt lgkmcnt(1)
	v_mul_f32_e32 v173, v152, v164
	v_mad_i64_i32 v[180:181], s[24:25], v148, s13, v[138:139]
	v_mov_b32_e32 v164, v47
	v_mov_b32_e32 v161, v128
	v_mov_b32_e32 v172, v39
	v_mov_b32_e32 v148, v129
	v_cvt_pk_bf16_f32 v170, v156, v157
	v_cvt_pk_bf16_f32 v171, v158, v159
	v_mul_f32_e32 v162, v152, v155
	s_waitcnt lgkmcnt(0)
	v_mul_f32_e32 v168, v152, v163
	v_mov_b32_e32 v163, v43
	v_pk_mul_f32 v[160:161], v[164:165], v[160:161]
	v_mov_b32_e32 v169, v35
	v_pk_mul_f32 v[148:149], v[172:173], v[148:149]
	v_mad_i64_i32 v[182:183], s[24:25], v134, s14, v[140:141]
	v_pk_fma_f32 v[160:161], v[166:167], v[162:163], v[160:161]
	v_pk_fma_f32 v[162:163], v[130:131], v[168:169], v[148:149]
	v_cvt_pk_bf16_f32 v128, v160, v161
	global_store_dwordx2 v[184:185], v[170:171], off nt
	global_store_dwordx4 v[150:151], v[156:159], off nt
	v_cvt_pk_bf16_f32 v129, v162, v163
	global_store_dwordx2 v[180:181], v[128:129], off nt
	global_store_dwordx4 v[182:183], v[160:163], off nt
	v_add_u32_e32 v134, 0x60, v154
	global_load_dwordx3 v[160:162], v[146:147], off offset:256
	v_lshrrev_b32_e32 v128, 5, v134
	v_mul_lo_u32 v128, v128, s12
	v_or_b32_e32 v128, v128, v137
	v_add_u32_e32 v137, 0x1000, v128
	ds_bpermute_b32 v148, v153, v24
	ds_bpermute_b32 v155, v153, v20
	v_mov_b32_e32 v170, v20
	v_mov_b32_e32 v168, v28
	v_mov_b32_e32 v167, v24
	s_waitcnt lgkmcnt(1)
	v_mul_f32_e32 v169, v152, v148
	ds_bpermute_b32 v148, v153, v29
	v_mad_i64_i32 v[180:181], s[24:25], v134, s14, v[140:141]
	v_add_u32_e32 v134, 0x61, v154
	v_mad_i64_i32 v[172:173], s[24:25], v137, s13, v[138:139]
	v_lshrrev_b32_e32 v137, 5, v134
	v_mul_lo_u32 v137, v137, s12
	v_and_or_b32 v137, v134, 29, v137
	v_add_u32_e32 v137, 0x1000, v137
	s_waitcnt vmcnt(0)
	v_mov_b32_e32 v150, v161
	v_mov_b32_e32 v151, v162
	global_load_dwordx4 v[128:131], v[146:147], off offset:268
	global_load_dword v149, v[146:147], off offset:284
	global_load_dwordx3 v[162:164], v[146:147], off offset:20
	global_load_dwordx4 v[156:159], v[146:147], off
	s_nop 0
	global_load_dword v146, v[144:145], off offset:16
	ds_bpermute_b32 v147, v153, v28
	s_waitcnt lgkmcnt(0)
	v_mul_f32_e32 v166, v152, v147
	s_waitcnt vmcnt(4)
	v_mov_b32_e32 v161, v128
	s_waitcnt vmcnt(2)
	v_mov_b32_e32 v147, v164
	s_waitcnt vmcnt(1)
	v_mov_b32_e32 v144, v157
	ds_bpermute_b32 v157, v153, v16
	v_mov_b32_e32 v145, v158
	v_mul_f32_e32 v158, v152, v155
	ds_bpermute_b32 v155, v153, v25
	v_mov_b32_e32 v164, v21
	s_waitcnt lgkmcnt(1)
	v_mul_f32_e32 v171, v152, v157
	v_mov_b32_e32 v157, v159
	v_mov_b32_e32 v159, v16
	s_waitcnt vmcnt(0)
	v_pk_mul_f32 v[146:147], v[170:171], v[146:147]
	v_pk_mul_f32 v[156:157], v[168:169], v[156:157]
	v_pk_fma_f32 v[146:147], v[162:163], v[158:159], v[146:147]
	ds_bpermute_b32 v158, v153, v17
	v_pk_fma_f32 v[144:145], v[144:145], v[166:167], v[156:157]
	ds_bpermute_b32 v157, v153, v21
	v_mul_f32_e32 v156, v152, v148
	s_waitcnt lgkmcnt(2)
	v_mul_f32_e32 v159, v152, v155
	s_waitcnt lgkmcnt(1)
	v_mul_f32_e32 v165, v152, v158
	v_mov_b32_e32 v158, v29
	v_mov_b32_e32 v148, v129
	v_cvt_pk_bf16_f32 v166, v144, v145
	v_cvt_pk_bf16_f32 v167, v146, v147
	s_waitcnt lgkmcnt(0)
	v_mul_f32_e32 v162, v152, v157
	v_mov_b32_e32 v157, v25
	v_pk_mul_f32 v[158:159], v[158:159], v[160:161]
	v_mov_b32_e32 v163, v17
	v_pk_mul_f32 v[148:149], v[164:165], v[148:149]
	v_mad_i64_i32 v[168:169], s[24:25], v137, s13, v[138:139]
	v_mad_i64_i32 v[170:171], s[24:25], v134, s14, v[140:141]
	v_pk_fma_f32 v[156:157], v[150:151], v[156:157], v[158:159]
	v_pk_fma_f32 v[158:159], v[130:131], v[162:163], v[148:149]
	v_cvt_pk_bf16_f32 v128, v156, v157
	global_store_dwordx2 v[172:173], v[166:167], off nt
	global_store_dwordx4 v[180:181], v[144:147], off nt
	v_cvt_pk_bf16_f32 v129, v158, v159
	global_store_dwordx2 v[168:169], v[128:129], off nt
	global_store_dwordx4 v[170:171], v[156:159], off nt
	v_add_u32_e32 v137, 0x62, v154
	v_and_b32_e32 v129, 30, v137
	v_lshlrev_b32_e32 v134, 8, v129
	v_lshl_add_u64 v[146:147], v[142:143], 0, v[134:135]
	v_add_co_u32_e32 v148, vcc, s33, v146
	v_lshrrev_b32_e32 v128, 5, v137
	s_nop 0
	v_addc_co_u32_e32 v149, vcc, 0, v147, vcc
	global_load_dwordx3 v[156:158], v[148:149], off offset:256
	v_mul_lo_u32 v128, v128, s12
	v_or_b32_e32 v128, v128, v129
	v_add_u32_e32 v144, 0x1000, v128
	global_load_dwordx4 v[128:131], v[148:149], off offset:268
	global_load_dword v145, v[148:149], off offset:284
	v_lshl_add_u64 v[146:147], v[146:147], 0, s[84:85]
	ds_bpermute_b32 v134, v153, v30
	v_mov_b32_e32 v172, v22
	v_mad_i64_i32 v[180:181], s[24:25], v144, s13, v[138:139]
	ds_bpermute_b32 v144, v153, v31
	ds_bpermute_b32 v155, v153, v27
	s_waitcnt lgkmcnt(2)
	v_mul_f32_e32 v168, v152, v134
	v_add_u32_e32 v134, 0x63, v154
	v_mov_b32_e32 v170, v30
	v_mov_b32_e32 v169, v26
	s_waitcnt vmcnt(2)
	v_mov_b32_e32 v163, v158
	v_mov_b32_e32 v162, v157
	global_load_dwordx3 v[158:160], v[148:149], off offset:20
	s_nop 0
	global_load_dwordx4 v[148:151], v[148:149], off
	s_nop 0
	global_load_dword v164, v[146:147], off offset:16
	ds_bpermute_b32 v147, v153, v22
	ds_bpermute_b32 v146, v153, v26
	ds_bpermute_b32 v157, v153, v23
	s_waitcnt lgkmcnt(1)
	v_mul_f32_e32 v171, v152, v146
	s_waitcnt vmcnt(2)
	v_mov_b32_e32 v165, v160
	s_waitcnt vmcnt(1)
	v_mov_b32_e32 v166, v149
	ds_bpermute_b32 v149, v153, v18
	v_mov_b32_e32 v167, v150
	v_mul_f32_e32 v150, v152, v147
	v_mad_i64_i32 v[146:147], s[24:25], v137, s14, v[140:141]
	s_waitcnt lgkmcnt(0)
	v_mul_f32_e32 v173, v152, v149
	v_mov_b32_e32 v149, v151
	v_mov_b32_e32 v151, v18
	s_waitcnt vmcnt(0)
	v_pk_mul_f32 v[160:161], v[172:173], v[164:165]
	v_lshrrev_b32_e32 v137, 5, v134
	v_pk_fma_f32 v[150:151], v[158:159], v[150:151], v[160:161]
	ds_bpermute_b32 v159, v153, v19
	v_pk_mul_f32 v[148:149], v[170:171], v[148:149]
	v_mul_lo_u32 v137, v137, s12
	v_pk_fma_f32 v[148:149], v[166:167], v[168:169], v[148:149]
	v_and_or_b32 v137, v134, 31, v137
	v_mul_f32_e32 v158, v152, v144
	v_mul_f32_e32 v161, v152, v155
	v_mul_f32_e32 v164, v152, v157
	s_waitcnt lgkmcnt(0)
	v_mul_f32_e32 v169, v152, v159
	v_mov_b32_e32 v160, v31
	v_mov_b32_e32 v157, v128
	v_mov_b32_e32 v168, v23
	v_mov_b32_e32 v144, v129
	v_cvt_pk_bf16_f32 v166, v148, v149
	v_cvt_pk_bf16_f32 v167, v150, v151
	v_add_u32_e32 v137, 0x1000, v137
	v_mov_b32_e32 v159, v27
	v_pk_mul_f32 v[156:157], v[160:161], v[156:157]
	v_mov_b32_e32 v165, v19
	v_pk_mul_f32 v[144:145], v[168:169], v[144:145]
	v_mad_i64_i32 v[170:171], s[24:25], v137, s13, v[138:139]
	v_mad_i64_i32 v[172:173], s[24:25], v134, s14, v[140:141]
	v_pk_fma_f32 v[156:157], v[162:163], v[158:159], v[156:157]
	v_pk_fma_f32 v[158:159], v[130:131], v[164:165], v[144:145]
	v_cvt_pk_bf16_f32 v128, v156, v157
	global_store_dwordx2 v[180:181], v[166:167], off nt
	global_store_dwordx4 v[146:147], v[148:151], off nt
	v_cvt_pk_bf16_f32 v129, v158, v159
	global_store_dwordx2 v[170:171], v[128:129], off nt
	global_store_dwordx4 v[172:173], v[156:159], off nt
	v_add_u32_e32 v137, 0x70, v154
	v_and_b32_e32 v129, 28, v137
	v_lshlrev_b32_e32 v134, 8, v129
	v_lshl_add_u64 v[146:147], v[142:143], 0, v[134:135]
	v_add_co_u32_e32 v148, vcc, s33, v146
	v_lshrrev_b32_e32 v128, 5, v137
	s_nop 0
	v_addc_co_u32_e32 v149, vcc, 0, v147, vcc
	global_load_dwordx3 v[156:158], v[148:149], off offset:256
	v_mul_lo_u32 v128, v128, s12
	v_or_b32_e32 v128, v128, v129
	v_lshl_add_u64 v[162:163], v[146:147], 0, s[84:85]
	v_add_u32_e32 v144, 0x1000, v128
	global_load_dwordx4 v[128:131], v[148:149], off offset:268
	global_load_dword v145, v[148:149], off offset:284
	ds_bpermute_b32 v155, v153, v0
	ds_bpermute_b32 v134, v153, v12
	v_mov_b32_e32 v170, v4
	v_mad_i64_i32 v[172:173], s[24:25], v144, s13, v[138:139]
	s_waitcnt lgkmcnt(1)
	v_mul_f32_e32 v171, v152, v155
	ds_bpermute_b32 v144, v153, v13
	ds_bpermute_b32 v155, v153, v9
	s_waitcnt lgkmcnt(2)
	v_mul_f32_e32 v166, v152, v134
	v_add_u32_e32 v134, 0x71, v154
	v_mad_i64_i32 v[180:181], s[24:25], v137, s14, v[140:141]
	v_mov_b32_e32 v168, v12
	v_lshrrev_b32_e32 v137, 5, v134
	v_mov_b32_e32 v167, v8
	v_mul_lo_u32 v137, v137, s12
	v_and_or_b32 v137, v134, 29, v137
	v_add_u32_e32 v137, 0x1000, v137
	s_waitcnt vmcnt(2)
	v_mov_b32_e32 v150, v157
	v_mov_b32_e32 v151, v158
	global_load_dwordx3 v[158:160], v[148:149], off offset:20
	s_nop 0
	global_load_dwordx4 v[146:149], v[148:149], off
	s_nop 0
	global_load_dword v162, v[162:163], off offset:16
	ds_bpermute_b32 v157, v153, v5
	s_waitcnt vmcnt(2)
	v_mov_b32_e32 v163, v160
	s_waitcnt vmcnt(1)
	v_mov_b32_e32 v164, v147
	v_mov_b32_e32 v165, v148
	ds_bpermute_b32 v147, v153, v8
	ds_bpermute_b32 v148, v153, v4
	s_waitcnt vmcnt(0)
	v_pk_mul_f32 v[160:161], v[170:171], v[162:163]
	s_waitcnt lgkmcnt(2)
	v_mul_f32_e32 v162, v152, v157
	v_mov_b32_e32 v157, v128
	s_waitcnt lgkmcnt(1)
	v_mul_f32_e32 v169, v152, v147
	s_waitcnt lgkmcnt(0)
	v_mul_f32_e32 v148, v152, v148
	v_mov_b32_e32 v147, v149
	v_mov_b32_e32 v149, v0
	v_pk_fma_f32 v[148:149], v[158:159], v[148:149], v[160:161]
	ds_bpermute_b32 v159, v153, v1
	v_pk_mul_f32 v[146:147], v[168:169], v[146:147]
	v_mul_f32_e32 v158, v152, v144
	v_pk_fma_f32 v[146:147], v[164:165], v[166:167], v[146:147]
	v_mul_f32_e32 v161, v152, v155
	s_waitcnt lgkmcnt(0)
	v_mul_f32_e32 v167, v152, v159
	v_mov_b32_e32 v160, v13
	v_mov_b32_e32 v166, v5
	v_mov_b32_e32 v144, v129
	v_cvt_pk_bf16_f32 v164, v146, v147
	v_cvt_pk_bf16_f32 v165, v148, v149
	v_mov_b32_e32 v159, v9
	v_pk_mul_f32 v[156:157], v[160:161], v[156:157]
	v_mov_b32_e32 v163, v1
	v_pk_mul_f32 v[144:145], v[166:167], v[144:145]
	v_mad_i64_i32 v[168:169], s[24:25], v137, s13, v[138:139]
	v_mad_i64_i32 v[170:171], s[24:25], v134, s14, v[140:141]
	v_pk_fma_f32 v[156:157], v[150:151], v[158:159], v[156:157]
	v_pk_fma_f32 v[158:159], v[130:131], v[162:163], v[144:145]
	v_cvt_pk_bf16_f32 v128, v156, v157
	global_store_dwordx2 v[172:173], v[164:165], off nt
	global_store_dwordx4 v[180:181], v[146:149], off nt
	v_cvt_pk_bf16_f32 v129, v158, v159
	global_store_dwordx2 v[168:169], v[128:129], off nt
	global_store_dwordx4 v[170:171], v[156:159], off nt
	v_add_u32_e32 v137, 0x72, v154
	v_and_b32_e32 v129, 30, v137
	v_lshlrev_b32_e32 v134, 8, v129
	v_lshl_add_u64 v[144:145], v[142:143], 0, v[134:135]
	v_add_co_u32_e32 v146, vcc, s33, v144
	v_lshrrev_b32_e32 v128, 5, v137
	s_nop 0
	v_addc_co_u32_e32 v147, vcc, 0, v145, vcc
	global_load_dwordx3 v[156:158], v[146:147], off offset:256
	v_mul_lo_u32 v128, v128, s12
	v_or_b32_e32 v128, v128, v129
	v_add_u32_e32 v155, 0x1000, v128
	global_load_dwordx4 v[128:131], v[146:147], off offset:268
	global_load_dword v143, v[146:147], off offset:284
	v_lshl_add_u64 v[144:145], v[144:145], 0, s[84:85]
	ds_bpermute_b32 v142, v153, v10
	ds_bpermute_b32 v134, v153, v14
	v_mov_b32_e32 v170, v6
	v_mad_i64_i32 v[172:173], s[24:25], v155, s13, v[138:139]
	s_waitcnt lgkmcnt(1)
	v_mul_f32_e32 v169, v152, v142
	ds_bpermute_b32 v142, v153, v15
	ds_bpermute_b32 v155, v153, v11
	s_waitcnt lgkmcnt(2)
	v_mul_f32_e32 v166, v152, v134
	v_add_u32_e32 v134, 0x73, v154
	v_mov_b32_e32 v168, v14
	v_mov_b32_e32 v167, v10
	s_waitcnt lgkmcnt(1)
	v_mul_f32_e32 v154, v152, v142
	s_waitcnt vmcnt(2)
	v_mov_b32_e32 v150, v157
	v_mov_b32_e32 v151, v158
	global_load_dwordx3 v[158:160], v[146:147], off offset:20
	s_nop 0
	global_load_dwordx4 v[146:149], v[146:147], off
	s_nop 0
	global_load_dword v162, v[144:145], off offset:16
	ds_bpermute_b32 v145, v153, v2
	ds_bpermute_b32 v144, v153, v6
	ds_bpermute_b32 v157, v153, v7
	s_waitcnt vmcnt(4)
	v_mov_b32_e32 v142, v129
	s_waitcnt lgkmcnt(2)
	v_mul_f32_e32 v171, v152, v145
	s_waitcnt vmcnt(2)
	v_mov_b32_e32 v163, v160
	s_waitcnt vmcnt(1)
	v_mov_b32_e32 v164, v147
	v_mov_b32_e32 v165, v148
	s_waitcnt lgkmcnt(1)
	v_mul_f32_e32 v148, v152, v144
	v_mov_b32_e32 v147, v149
	v_mov_b32_e32 v149, v2
	s_waitcnt vmcnt(0)
	v_pk_mul_f32 v[160:161], v[170:171], v[162:163]
	v_mad_i64_i32 v[144:145], s[24:25], v137, s14, v[140:141]
	v_pk_fma_f32 v[148:149], v[158:159], v[148:149], v[160:161]
	ds_bpermute_b32 v159, v153, v3
	v_lshrrev_b32_e32 v137, 5, v134
	v_mul_lo_u32 v137, v137, s12
	v_and_or_b32 v137, v134, 31, v137
	v_pk_mul_f32 v[146:147], v[168:169], v[146:147]
	v_add_u32_e32 v137, 0x1000, v137
	v_mul_f32_e32 v153, v152, v155
	s_waitcnt lgkmcnt(1)
	v_mul_f32_e32 v158, v152, v157
	s_waitcnt lgkmcnt(0)
	v_mul_f32_e32 v161, v152, v159
	v_mov_b32_e32 v152, v15
	v_mov_b32_e32 v157, v128
	v_mov_b32_e32 v160, v7
	v_pk_fma_f32 v[146:147], v[164:165], v[166:167], v[146:147]
	v_cvt_pk_bf16_f32 v165, v148, v149
	v_mad_i64_i32 v[162:163], s[24:25], v137, s13, v[138:139]
	v_cvt_pk_bf16_f32 v164, v146, v147
	v_mad_i64_i32 v[166:167], s[24:25], v134, s14, v[140:141]
	v_mov_b32_e32 v155, v11
	v_pk_mul_f32 v[138:139], v[152:153], v[156:157]
	v_mov_b32_e32 v159, v3
	v_pk_mul_f32 v[140:141], v[160:161], v[142:143]
	v_pk_fma_f32 v[138:139], v[150:151], v[154:155], v[138:139]
	v_pk_fma_f32 v[140:141], v[130:131], v[158:159], v[140:141]
	v_cvt_pk_bf16_f32 v128, v138, v139
	global_store_dwordx2 v[172:173], v[164:165], off nt
	global_store_dwordx4 v[144:145], v[146:149], off nt
	v_cvt_pk_bf16_f32 v129, v140, v141
	global_store_dwordx2 v[162:163], v[128:129], off nt
	global_store_dwordx4 v[166:167], v[138:141], off nt

.LBB0_242:
	s_or_saveexec_b64 s[8:9], s[8:9]
	s_mov_b64 s[68:69], 0
	s_xor_b64 exec, exec, s[8:9]
	s_cbranch_execz .LBB0_250
	v_cmp_lt_i32_e32 vcc, 1, v177
	s_mov_b64 s[72:73], 0
	s_mov_b64 s[68:69], -1
	s_mov_b64 s[74:75], s[66:67]
	s_and_saveexec_b64 s[0:1], vcc
	s_cbranch_execz .LBB0_249
	v_cmp_lt_i32_e32 vcc, 2, v177
	s_mov_b64 s[72:73], -1
	s_mov_b64 s[74:75], s[66:67]
	s_and_saveexec_b64 s[68:69], vcc
	s_cbranch_execz .LBB0_248
	v_cmp_lt_i32_e32 vcc, 3, v177
	s_mov_b64 s[74:75], -1
	s_and_saveexec_b64 s[72:73], vcc
	s_cbranch_execz .LBB0_247
	v_mbcnt_hi_u32_b32 v128, -1, v204
	v_and_b32_e32 v130, 64, v128
	v_xor_b32_e32 v129, 8, v128
	v_add_u32_e32 v130, 64, v130
	v_cmp_lt_i32_e32 vcc, v129, v130
	v_readlane_b32 s36, v253, 26
	v_ashrrev_i32_e32 v137, 31, v136
	v_cndmask_b32_e32 v128, v128, v129, vcc
	v_cmp_gt_u32_e32 vcc, 8, v176
	v_readlane_b32 s37, v253, 27
	v_lshl_add_u32 v149, v178, 2, v211
	v_lshlrev_b32_e32 v150, 2, v128
	v_cndmask_b32_e64 v148, 1.0, -1.0, vcc
	v_readlane_b32 s38, v253, 28
	v_readlane_b32 s39, v253, 29
	v_readlane_b32 s40, v253, 30
	v_readlane_b32 s41, v253, 31
	v_readlane_b32 s42, v253, 32
	v_readlane_b32 s43, v253, 33
	v_readlane_b32 s44, v253, 34
	v_readlane_b32 s45, v253, 35
	v_readlane_b32 s46, v253, 36
	v_readlane_b32 s47, v253, 37
	v_readlane_b32 s48, v253, 38
	v_readlane_b32 s49, v253, 39
	v_readlane_b32 s50, v253, 40
	v_readlane_b32 s51, v253, 41
	v_lshl_add_u64 v[128:129], v[136:137], 1, s[36:37]
	v_lshlrev_b32_e32 v130, 5, v174
	v_and_b32_e32 v134, 0xe0, v130
	v_lshl_add_u64 v[130:131], s[58:59], 0, v[134:135]
	v_lshlrev_b32_e32 v134, 10, v178
	v_and_b32_e32 v134, 0x1c00, v134
	v_lshl_add_u64 v[140:141], v[130:131], 0, v[134:135]
	s_mov_b64 s[26:27], 0x80100
	v_lshl_add_u64 v[138:139], v[140:141], 0, s[26:27]
	v_lshl_add_u64 v[142:143], v[140:141], 0, s[84:85]
	v_add_co_u32_e32 v140, vcc, s33, v140
	ds_bpermute_b32 v134, v150, v124
	s_nop 0
	v_addc_co_u32_e32 v141, vcc, 0, v141, vcc
	global_load_dwordx4 v[144:147], v[140:141], off
	global_load_dwordx4 v[152:155], v[142:143], off offset:16
	ds_bpermute_b32 v137, v150, v120
	ds_bpermute_b32 v151, v150, v116
	s_waitcnt lgkmcnt(2)
	v_mul_f32_e32 v157, v148, v134
	v_mov_b32_e32 v156, v124
	ds_bpermute_b32 v158, v150, v112
	ds_bpermute_b32 v162, v150, v117
	v_mov_b32_e32 v160, v125
	ds_bpermute_b32 v163, v150, v113
	s_waitcnt vmcnt(1)
	v_pk_mul_f32 v[144:145], v[156:157], v[144:145]
	s_nop 0
	v_add_f32_e32 v134, v144, v145
	s_waitcnt lgkmcnt(4)
	v_mul_f32_e32 v145, v148, v137
	v_mov_b32_e32 v144, v120
	v_pk_mul_f32 v[144:145], v[144:145], v[146:147]
	v_mul_f32_e32 v134, 0x3e38aa3b, v134
	v_add_f32_e32 v137, v144, v145
	s_waitcnt lgkmcnt(3)
	v_mul_f32_e32 v145, v148, v151
	v_mov_b32_e32 v144, v116
	s_waitcnt vmcnt(0)
	v_pk_mul_f32 v[144:145], v[144:145], v[152:153]
	v_mul_f32_e32 v137, 0x3e38aa3b, v137
	v_add_f32_e32 v146, v144, v145
	s_waitcnt lgkmcnt(2)
	v_mul_f32_e32 v145, v148, v158
	v_mov_b32_e32 v144, v112
	v_pk_mul_f32 v[144:145], v[144:145], v[154:155]
	global_load_dwordx4 v[152:155], v[140:141], off offset:256
	global_load_dwordx4 v[156:159], v[138:139], off offset:16
	v_add_f32_e32 v147, v144, v145
	v_mul_f32_e32 v151, 0x3e38aa3b, v146
	v_cvt_pk_bf16_f32 v146, v134, v137
	ds_bpermute_b32 v137, v150, v125
	v_mul_f32_e32 v147, 0x3e38aa3b, v147
	v_cvt_pk_bf16_f32 v147, v151, v147
	ds_bpermute_b32 v151, v150, v121
	v_mad_i64_i32 v[144:145], s[24:25], v149, s13, v[128:129]
	s_waitcnt lgkmcnt(1)
	v_mul_f32_e32 v161, v148, v137
	v_or_b32_e32 v134, 1, v149
	global_store_dwordx2 v[144:145], v[146:147], off nt
	s_waitcnt vmcnt(2)
	v_pk_mul_f32 v[152:153], v[160:161], v[152:153]
	s_nop 0
	v_add_f32_e32 v137, v152, v153
	s_waitcnt lgkmcnt(0)
	v_mul_f32_e32 v153, v148, v151
	v_mov_b32_e32 v152, v121
	v_pk_mul_f32 v[152:153], v[152:153], v[154:155]
	s_nop 0
	v_add_f32_e32 v151, v152, v153
	v_mul_f32_e32 v153, v148, v162
	v_mov_b32_e32 v152, v117
	s_waitcnt vmcnt(1)
	v_pk_mul_f32 v[152:153], v[152:153], v[156:157]
	s_nop 0
	v_add_f32_e32 v154, v152, v153
	v_mul_f32_e32 v153, v148, v163
	v_mov_b32_e32 v152, v113
	v_pk_mul_f32 v[144:145], v[152:153], v[158:159]
	v_mul_f32_e32 v147, 0x3e38aa3b, v154
	v_add_f32_e32 v146, v144, v145
	v_mad_i64_i32 v[144:145], s[24:25], v134, s13, v[128:129]
	v_mul_f32_e32 v134, 0x3e38aa3b, v137
	v_mul_f32_e32 v137, 0x3e38aa3b, v151
	v_mul_f32_e32 v151, 0x3e38aa3b, v146
	v_cvt_pk_bf16_f32 v146, v134, v137
	v_cvt_pk_bf16_f32 v147, v147, v151
	global_store_dwordx2 v[144:145], v[146:147], off nt
	v_or_b32_e32 v137, 2, v149
	v_lshlrev_b32_e32 v134, 8, v137
	v_and_b32_e32 v134, 0x1e00, v134
	v_lshl_add_u64 v[144:145], v[130:131], 0, v[134:135]
	v_add_co_u32_e32 v160, vcc, s33, v144
	v_lshl_add_u64 v[152:153], v[144:145], 0, s[84:85]
	s_nop 0
	v_addc_co_u32_e32 v161, vcc, 0, v145, vcc
	v_lshl_add_u64 v[156:157], v[144:145], 0, s[26:27]
	global_load_dwordx4 v[144:147], v[160:161], off
	s_nop 0
	global_load_dwordx4 v[152:155], v[152:153], off offset:16
	ds_bpermute_b32 v134, v150, v126
	ds_bpermute_b32 v151, v150, v122
	ds_bpermute_b32 v162, v150, v118
	v_mov_b32_e32 v158, v126
	ds_bpermute_b32 v163, v150, v114
	s_waitcnt lgkmcnt(3)
	v_mul_f32_e32 v159, v148, v134
	ds_bpermute_b32 v164, v150, v119
	ds_bpermute_b32 v165, v150, v115
	s_waitcnt vmcnt(1)
	v_pk_mul_f32 v[144:145], v[158:159], v[144:145]
	s_nop 0
	v_add_f32_e32 v134, v144, v145
	s_waitcnt lgkmcnt(4)
	v_mul_f32_e32 v145, v148, v151
	v_mov_b32_e32 v144, v122
	v_pk_mul_f32 v[144:145], v[144:145], v[146:147]
	v_mul_f32_e32 v134, 0x3e38aa3b, v134
	v_add_f32_e32 v146, v144, v145
	s_waitcnt lgkmcnt(3)
	v_mul_f32_e32 v145, v148, v162
	v_mov_b32_e32 v144, v118
	s_waitcnt vmcnt(0)
	v_pk_mul_f32 v[144:145], v[144:145], v[152:153]
	v_mov_b32_e32 v162, v127
	v_add_f32_e32 v147, v144, v145
	s_waitcnt lgkmcnt(2)
	v_mul_f32_e32 v145, v148, v163
	v_mov_b32_e32 v144, v114
	v_pk_mul_f32 v[144:145], v[144:145], v[154:155]
	global_load_dwordx4 v[152:155], v[160:161], off offset:256
	s_nop 0
	global_load_dwordx4 v[156:159], v[156:157], off offset:16
	v_add_f32_e32 v151, v144, v145
	v_mad_i64_i32 v[144:145], s[24:25], v137, s13, v[128:129]
	v_mul_f32_e32 v137, 0x3e38aa3b, v146
	v_cvt_pk_bf16_f32 v146, v134, v137
	ds_bpermute_b32 v137, v150, v127
	v_mul_f32_e32 v147, 0x3e38aa3b, v147
	v_mul_f32_e32 v151, 0x3e38aa3b, v151
	v_cvt_pk_bf16_f32 v147, v147, v151
	ds_bpermute_b32 v151, v150, v123
	s_waitcnt lgkmcnt(1)
	v_mul_f32_e32 v163, v148, v137
	v_or_b32_e32 v134, 3, v149
	global_store_dwordx2 v[144:145], v[146:147], off nt
	s_waitcnt vmcnt(2)
	v_pk_mul_f32 v[152:153], v[162:163], v[152:153]
	s_nop 0
	v_add_f32_e32 v137, v152, v153
	s_waitcnt lgkmcnt(0)
	v_mul_f32_e32 v153, v148, v151
	v_mov_b32_e32 v152, v123
	v_pk_mul_f32 v[152:153], v[152:153], v[154:155]
	s_nop 0
	v_add_f32_e32 v151, v152, v153
	v_mul_f32_e32 v153, v148, v164
	v_mov_b32_e32 v152, v119
	s_waitcnt vmcnt(1)
	v_pk_mul_f32 v[152:153], v[152:153], v[156:157]
	s_nop 0
	v_add_f32_e32 v154, v152, v153
	v_mul_f32_e32 v153, v148, v165
	v_mov_b32_e32 v152, v115
	v_pk_mul_f32 v[144:145], v[152:153], v[158:159]
	v_mul_f32_e32 v147, 0x3e38aa3b, v154
	v_add_f32_e32 v146, v144, v145
	v_mad_i64_i32 v[144:145], s[24:25], v134, s13, v[128:129]
	v_mul_f32_e32 v134, 0x3e38aa3b, v137
	v_mul_f32_e32 v137, 0x3e38aa3b, v151
	v_mul_f32_e32 v151, 0x3e38aa3b, v146
	v_cvt_pk_bf16_f32 v146, v134, v137
	v_cvt_pk_bf16_f32 v147, v147, v151
	global_store_dwordx2 v[144:145], v[146:147], off nt
	v_add_u32_e32 v137, 16, v149
	v_lshlrev_b32_e32 v134, 8, v137
	v_and_b32_e32 v134, 0x1c00, v134
	v_lshl_add_u64 v[144:145], v[130:131], 0, v[134:135]
	v_add_co_u32_e32 v160, vcc, s33, v144
	v_lshl_add_u64 v[152:153], v[144:145], 0, s[84:85]
	s_nop 0
	v_addc_co_u32_e32 v161, vcc, 0, v145, vcc
	v_lshl_add_u64 v[156:157], v[144:145], 0, s[26:27]
	global_load_dwordx4 v[144:147], v[160:161], off
	s_nop 0
	global_load_dwordx4 v[152:155], v[152:153], off offset:16
	ds_bpermute_b32 v134, v150, v108
	ds_bpermute_b32 v151, v150, v104
	ds_bpermute_b32 v162, v150, v100
	v_mov_b32_e32 v158, v108
	ds_bpermute_b32 v163, v150, v96
	s_waitcnt lgkmcnt(3)
	v_mul_f32_e32 v159, v148, v134
	ds_bpermute_b32 v164, v150, v101
	ds_bpermute_b32 v165, v150, v97
	s_waitcnt vmcnt(1)
	v_pk_mul_f32 v[144:145], v[158:159], v[144:145]
	s_nop 0
	v_add_f32_e32 v134, v144, v145
	s_waitcnt lgkmcnt(4)
	v_mul_f32_e32 v145, v148, v151
	v_mov_b32_e32 v144, v104
	v_pk_mul_f32 v[144:145], v[144:145], v[146:147]
	v_mul_f32_e32 v134, 0x3e38aa3b, v134
	v_add_f32_e32 v146, v144, v145
	s_waitcnt lgkmcnt(3)
	v_mul_f32_e32 v145, v148, v162
	v_mov_b32_e32 v144, v100
	s_waitcnt vmcnt(0)
	v_pk_mul_f32 v[144:145], v[144:145], v[152:153]
	v_mov_b32_e32 v162, v109
	v_add_f32_e32 v147, v144, v145
	s_waitcnt lgkmcnt(2)
	v_mul_f32_e32 v145, v148, v163
	v_mov_b32_e32 v144, v96
	v_pk_mul_f32 v[144:145], v[144:145], v[154:155]
	global_load_dwordx4 v[152:155], v[160:161], off offset:256
	s_nop 0
	global_load_dwordx4 v[156:159], v[156:157], off offset:16
	v_add_f32_e32 v151, v144, v145
	v_mad_i64_i32 v[144:145], s[24:25], v137, s13, v[128:129]
	v_mul_f32_e32 v137, 0x3e38aa3b, v146
	v_cvt_pk_bf16_f32 v146, v134, v137
	ds_bpermute_b32 v137, v150, v109
	v_mul_f32_e32 v147, 0x3e38aa3b, v147
	v_mul_f32_e32 v151, 0x3e38aa3b, v151
	v_cvt_pk_bf16_f32 v147, v147, v151
	ds_bpermute_b32 v151, v150, v105
	s_waitcnt lgkmcnt(1)
	v_mul_f32_e32 v163, v148, v137
	v_add_u32_e32 v134, 17, v149
	global_store_dwordx2 v[144:145], v[146:147], off nt
	s_waitcnt vmcnt(2)
	v_pk_mul_f32 v[152:153], v[162:163], v[152:153]
	s_nop 0
	v_add_f32_e32 v137, v152, v153
	s_waitcnt lgkmcnt(0)
	v_mul_f32_e32 v153, v148, v151
	v_mov_b32_e32 v152, v105
	v_pk_mul_f32 v[152:153], v[152:153], v[154:155]
	s_nop 0
	v_add_f32_e32 v151, v152, v153
	v_mul_f32_e32 v153, v148, v164
	v_mov_b32_e32 v152, v101
	s_waitcnt vmcnt(1)
	v_pk_mul_f32 v[152:153], v[152:153], v[156:157]
	s_nop 0
	v_add_f32_e32 v154, v152, v153
	v_mul_f32_e32 v153, v148, v165
	v_mov_b32_e32 v152, v97
	v_pk_mul_f32 v[144:145], v[152:153], v[158:159]
	v_mul_f32_e32 v147, 0x3e38aa3b, v154
	v_add_f32_e32 v146, v144, v145
	v_mad_i64_i32 v[144:145], s[24:25], v134, s13, v[128:129]
	v_mul_f32_e32 v134, 0x3e38aa3b, v137
	v_mul_f32_e32 v137, 0x3e38aa3b, v151
	v_mul_f32_e32 v151, 0x3e38aa3b, v146
	v_cvt_pk_bf16_f32 v146, v134, v137
	v_cvt_pk_bf16_f32 v147, v147, v151
	global_store_dwordx2 v[144:145], v[146:147], off nt
	v_add_u32_e32 v137, 18, v149
	v_lshlrev_b32_e32 v134, 8, v137
	v_and_b32_e32 v134, 0x1e00, v134
	v_lshl_add_u64 v[144:145], v[130:131], 0, v[134:135]
	v_add_co_u32_e32 v160, vcc, s33, v144
	v_lshl_add_u64 v[152:153], v[144:145], 0, s[84:85]
	s_nop 0
	v_addc_co_u32_e32 v161, vcc, 0, v145, vcc
	v_lshl_add_u64 v[156:157], v[144:145], 0, s[26:27]
	global_load_dwordx4 v[144:147], v[160:161], off
	s_nop 0
	global_load_dwordx4 v[152:155], v[152:153], off offset:16
	ds_bpermute_b32 v134, v150, v110
	ds_bpermute_b32 v151, v150, v106
	ds_bpermute_b32 v162, v150, v102
	v_mov_b32_e32 v158, v110
	ds_bpermute_b32 v163, v150, v98
	s_waitcnt lgkmcnt(3)
	v_mul_f32_e32 v159, v148, v134
	ds_bpermute_b32 v164, v150, v103
	ds_bpermute_b32 v165, v150, v99
	s_waitcnt vmcnt(1)
	v_pk_mul_f32 v[144:145], v[158:159], v[144:145]
	s_nop 0
	v_add_f32_e32 v134, v144, v145
	s_waitcnt lgkmcnt(4)
	v_mul_f32_e32 v145, v148, v151
	v_mov_b32_e32 v144, v106
	v_pk_mul_f32 v[144:145], v[144:145], v[146:147]
	v_mul_f32_e32 v134, 0x3e38aa3b, v134
	v_add_f32_e32 v146, v144, v145
	s_waitcnt lgkmcnt(3)
	v_mul_f32_e32 v145, v148, v162
	v_mov_b32_e32 v144, v102
	s_waitcnt vmcnt(0)
	v_pk_mul_f32 v[144:145], v[144:145], v[152:153]
	v_mov_b32_e32 v162, v111
	v_add_f32_e32 v147, v144, v145
	s_waitcnt lgkmcnt(2)
	v_mul_f32_e32 v145, v148, v163
	v_mov_b32_e32 v144, v98
	v_pk_mul_f32 v[144:145], v[144:145], v[154:155]
	global_load_dwordx4 v[152:155], v[160:161], off offset:256
	s_nop 0
	global_load_dwordx4 v[156:159], v[156:157], off offset:16
	v_add_f32_e32 v151, v144, v145
	v_mad_i64_i32 v[144:145], s[24:25], v137, s13, v[128:129]
	v_mul_f32_e32 v137, 0x3e38aa3b, v146
	v_cvt_pk_bf16_f32 v146, v134, v137
	ds_bpermute_b32 v137, v150, v111
	v_mul_f32_e32 v147, 0x3e38aa3b, v147
	v_mul_f32_e32 v151, 0x3e38aa3b, v151
	v_cvt_pk_bf16_f32 v147, v147, v151
	ds_bpermute_b32 v151, v150, v107
	s_waitcnt lgkmcnt(1)
	v_mul_f32_e32 v163, v148, v137
	v_add_u32_e32 v134, 19, v149
	global_store_dwordx2 v[144:145], v[146:147], off nt
	s_waitcnt vmcnt(2)
	v_pk_mul_f32 v[152:153], v[162:163], v[152:153]
	s_nop 0
	v_add_f32_e32 v137, v152, v153
	s_waitcnt lgkmcnt(0)
	v_mul_f32_e32 v153, v148, v151
	v_mov_b32_e32 v152, v107
	v_pk_mul_f32 v[152:153], v[152:153], v[154:155]
	s_nop 0
	v_add_f32_e32 v151, v152, v153
	v_mul_f32_e32 v153, v148, v164
	v_mov_b32_e32 v152, v103
	s_waitcnt vmcnt(1)
	v_pk_mul_f32 v[152:153], v[152:153], v[156:157]
	s_nop 0
	v_add_f32_e32 v154, v152, v153
	v_mul_f32_e32 v153, v148, v165
	v_mov_b32_e32 v152, v99
	v_pk_mul_f32 v[144:145], v[152:153], v[158:159]
	v_mul_f32_e32 v147, 0x3e38aa3b, v154
	v_add_f32_e32 v146, v144, v145
	v_mad_i64_i32 v[144:145], s[24:25], v134, s13, v[128:129]
	v_mul_f32_e32 v134, 0x3e38aa3b, v137
	v_mul_f32_e32 v137, 0x3e38aa3b, v151
	v_mul_f32_e32 v151, 0x3e38aa3b, v146
	v_cvt_pk_bf16_f32 v146, v134, v137
	v_cvt_pk_bf16_f32 v147, v147, v151
	global_store_dwordx2 v[144:145], v[146:147], off nt
	v_add_u32_e32 v134, 32, v149
	global_load_dwordx4 v[144:147], v[140:141], off
	global_load_dwordx4 v[152:155], v[142:143], off offset:16
	ds_bpermute_b32 v137, v150, v92
	ds_bpermute_b32 v151, v150, v88
	ds_bpermute_b32 v158, v150, v84
	v_mov_b32_e32 v156, v92
	ds_bpermute_b32 v159, v150, v80
	s_waitcnt lgkmcnt(3)
	v_mul_f32_e32 v157, v148, v137
	ds_bpermute_b32 v162, v150, v85
	v_mov_b32_e32 v160, v93
	ds_bpermute_b32 v163, v150, v81
	s_waitcnt vmcnt(1)
	v_pk_mul_f32 v[144:145], v[156:157], v[144:145]
	s_nop 0
	v_add_f32_e32 v137, v144, v145
	s_waitcnt lgkmcnt(4)
	v_mul_f32_e32 v145, v148, v151
	v_mov_b32_e32 v144, v88
	v_pk_mul_f32 v[144:145], v[144:145], v[146:147]
	s_nop 0
	v_add_f32_e32 v146, v144, v145
	s_waitcnt lgkmcnt(3)
	v_mul_f32_e32 v145, v148, v158
	v_mov_b32_e32 v144, v84
	s_waitcnt vmcnt(0)
	v_pk_mul_f32 v[144:145], v[144:145], v[152:153]
	s_nop 0
	v_add_f32_e32 v147, v144, v145
	s_waitcnt lgkmcnt(2)
	v_mul_f32_e32 v145, v148, v159
	v_mov_b32_e32 v144, v80
	v_pk_mul_f32 v[144:145], v[144:145], v[154:155]
	global_load_dwordx4 v[152:155], v[140:141], off offset:256
	global_load_dwordx4 v[156:159], v[138:139], off offset:16
	v_add_f32_e32 v151, v144, v145
	v_mad_i64_i32 v[144:145], s[24:25], v134, s13, v[128:129]
	v_mul_f32_e32 v134, 0x3e38aa3b, v137
	v_mul_f32_e32 v137, 0x3e38aa3b, v146
	v_cvt_pk_bf16_f32 v146, v134, v137
	ds_bpermute_b32 v137, v150, v93
	v_mul_f32_e32 v147, 0x3e38aa3b, v147
	v_mul_f32_e32 v151, 0x3e38aa3b, v151
	v_cvt_pk_bf16_f32 v147, v147, v151
	ds_bpermute_b32 v151, v150, v89
	s_waitcnt lgkmcnt(1)
	v_mul_f32_e32 v161, v148, v137
	v_add_u32_e32 v134, 33, v149
	global_store_dwordx2 v[144:145], v[146:147], off nt
	s_waitcnt vmcnt(2)
	v_pk_mul_f32 v[152:153], v[160:161], v[152:153]
	s_nop 0
	v_add_f32_e32 v137, v152, v153
	s_waitcnt lgkmcnt(0)
	v_mul_f32_e32 v153, v148, v151
	v_mov_b32_e32 v152, v89
	v_pk_mul_f32 v[152:153], v[152:153], v[154:155]
	s_nop 0
	v_add_f32_e32 v151, v152, v153
	v_mul_f32_e32 v153, v148, v162
	v_mov_b32_e32 v152, v85
	s_waitcnt vmcnt(1)
	v_pk_mul_f32 v[152:153], v[152:153], v[156:157]
	s_nop 0
	v_add_f32_e32 v154, v152, v153
	v_mul_f32_e32 v153, v148, v163
	v_mov_b32_e32 v152, v81
	v_pk_mul_f32 v[144:145], v[152:153], v[158:159]
	v_mul_f32_e32 v147, 0x3e38aa3b, v154
	v_add_f32_e32 v146, v144, v145
	v_mad_i64_i32 v[144:145], s[24:25], v134, s13, v[128:129]
	v_mul_f32_e32 v134, 0x3e38aa3b, v137
	v_mul_f32_e32 v137, 0x3e38aa3b, v151
	v_mul_f32_e32 v151, 0x3e38aa3b, v146
	v_cvt_pk_bf16_f32 v146, v134, v137
	v_cvt_pk_bf16_f32 v147, v147, v151
	global_store_dwordx2 v[144:145], v[146:147], off nt
	v_add_u32_e32 v137, 34, v149
	v_lshlrev_b32_e32 v134, 8, v137
	v_and_b32_e32 v134, 0x1e00, v134
	v_lshl_add_u64 v[144:145], v[130:131], 0, v[134:135]
	v_add_co_u32_e32 v160, vcc, s33, v144
	v_lshl_add_u64 v[152:153], v[144:145], 0, s[84:85]
	s_nop 0
	v_addc_co_u32_e32 v161, vcc, 0, v145, vcc
	v_lshl_add_u64 v[156:157], v[144:145], 0, s[26:27]
	global_load_dwordx4 v[144:147], v[160:161], off
	s_nop 0
	global_load_dwordx4 v[152:155], v[152:153], off offset:16
	ds_bpermute_b32 v134, v150, v94
	ds_bpermute_b32 v151, v150, v90
	ds_bpermute_b32 v162, v150, v86
	v_mov_b32_e32 v158, v94
	ds_bpermute_b32 v163, v150, v82
	s_waitcnt lgkmcnt(3)
	v_mul_f32_e32 v159, v148, v134
	ds_bpermute_b32 v164, v150, v87
	ds_bpermute_b32 v165, v150, v83
	s_waitcnt vmcnt(1)
	v_pk_mul_f32 v[144:145], v[158:159], v[144:145]
	s_nop 0
	v_add_f32_e32 v134, v144, v145
	s_waitcnt lgkmcnt(4)
	v_mul_f32_e32 v145, v148, v151
	v_mov_b32_e32 v144, v90
	v_pk_mul_f32 v[144:145], v[144:145], v[146:147]
	v_mul_f32_e32 v134, 0x3e38aa3b, v134
	v_add_f32_e32 v146, v144, v145
	s_waitcnt lgkmcnt(3)
	v_mul_f32_e32 v145, v148, v162
	v_mov_b32_e32 v144, v86
	s_waitcnt vmcnt(0)
	v_pk_mul_f32 v[144:145], v[144:145], v[152:153]
	v_mov_b32_e32 v162, v95
	v_add_f32_e32 v147, v144, v145
	s_waitcnt lgkmcnt(2)
	v_mul_f32_e32 v145, v148, v163
	v_mov_b32_e32 v144, v82
	v_pk_mul_f32 v[144:145], v[144:145], v[154:155]
	global_load_dwordx4 v[152:155], v[160:161], off offset:256
	s_nop 0
	global_load_dwordx4 v[156:159], v[156:157], off offset:16
	v_add_f32_e32 v151, v144, v145
	v_mad_i64_i32 v[144:145], s[24:25], v137, s13, v[128:129]
	v_mul_f32_e32 v137, 0x3e38aa3b, v146
	v_cvt_pk_bf16_f32 v146, v134, v137
	ds_bpermute_b32 v137, v150, v95
	v_mul_f32_e32 v147, 0x3e38aa3b, v147
	v_mul_f32_e32 v151, 0x3e38aa3b, v151
	v_cvt_pk_bf16_f32 v147, v147, v151
	ds_bpermute_b32 v151, v150, v91
	s_waitcnt lgkmcnt(1)
	v_mul_f32_e32 v163, v148, v137
	v_add_u32_e32 v134, 35, v149
	global_store_dwordx2 v[144:145], v[146:147], off nt
	s_waitcnt vmcnt(2)
	v_pk_mul_f32 v[152:153], v[162:163], v[152:153]
	s_nop 0
	v_add_f32_e32 v137, v152, v153
	s_waitcnt lgkmcnt(0)
	v_mul_f32_e32 v153, v148, v151
	v_mov_b32_e32 v152, v91
	v_pk_mul_f32 v[152:153], v[152:153], v[154:155]
	s_nop 0
	v_add_f32_e32 v151, v152, v153
	v_mul_f32_e32 v153, v148, v164
	v_mov_b32_e32 v152, v87
	s_waitcnt vmcnt(1)
	v_pk_mul_f32 v[152:153], v[152:153], v[156:157]
	s_nop 0
	v_add_f32_e32 v154, v152, v153
	v_mul_f32_e32 v153, v148, v165
	v_mov_b32_e32 v152, v83
	v_pk_mul_f32 v[144:145], v[152:153], v[158:159]
	v_mul_f32_e32 v147, 0x3e38aa3b, v154
	v_add_f32_e32 v146, v144, v145
	v_mad_i64_i32 v[144:145], s[24:25], v134, s13, v[128:129]
	v_mul_f32_e32 v134, 0x3e38aa3b, v137
	v_mul_f32_e32 v137, 0x3e38aa3b, v151
	v_mul_f32_e32 v151, 0x3e38aa3b, v146
	v_cvt_pk_bf16_f32 v146, v134, v137
	v_cvt_pk_bf16_f32 v147, v147, v151
	global_store_dwordx2 v[144:145], v[146:147], off nt
	v_add_u32_e32 v137, 48, v149
	v_lshlrev_b32_e32 v134, 8, v137
	v_and_b32_e32 v134, 0x1c00, v134
	v_lshl_add_u64 v[144:145], v[130:131], 0, v[134:135]
	v_add_co_u32_e32 v160, vcc, s33, v144
	v_lshl_add_u64 v[152:153], v[144:145], 0, s[84:85]
	s_nop 0
	v_addc_co_u32_e32 v161, vcc, 0, v145, vcc
	v_lshl_add_u64 v[156:157], v[144:145], 0, s[26:27]
	global_load_dwordx4 v[144:147], v[160:161], off
	s_nop 0
	global_load_dwordx4 v[152:155], v[152:153], off offset:16
	ds_bpermute_b32 v134, v150, v76
	ds_bpermute_b32 v151, v150, v72
	ds_bpermute_b32 v162, v150, v68
	v_mov_b32_e32 v158, v76
	ds_bpermute_b32 v163, v150, v64
	s_waitcnt lgkmcnt(3)
	v_mul_f32_e32 v159, v148, v134
	ds_bpermute_b32 v164, v150, v69
	ds_bpermute_b32 v165, v150, v65
	s_waitcnt vmcnt(1)
	v_pk_mul_f32 v[144:145], v[158:159], v[144:145]
	s_nop 0
	v_add_f32_e32 v134, v144, v145
	s_waitcnt lgkmcnt(4)
	v_mul_f32_e32 v145, v148, v151
	v_mov_b32_e32 v144, v72
	v_pk_mul_f32 v[144:145], v[144:145], v[146:147]
	v_mul_f32_e32 v134, 0x3e38aa3b, v134
	v_add_f32_e32 v146, v144, v145
	s_waitcnt lgkmcnt(3)
	v_mul_f32_e32 v145, v148, v162
	v_mov_b32_e32 v144, v68
	s_waitcnt vmcnt(0)
	v_pk_mul_f32 v[144:145], v[144:145], v[152:153]
	v_mov_b32_e32 v162, v77
	v_add_f32_e32 v147, v144, v145
	s_waitcnt lgkmcnt(2)
	v_mul_f32_e32 v145, v148, v163
	v_mov_b32_e32 v144, v64
	v_pk_mul_f32 v[144:145], v[144:145], v[154:155]
	global_load_dwordx4 v[152:155], v[160:161], off offset:256
	s_nop 0
	global_load_dwordx4 v[156:159], v[156:157], off offset:16
	v_add_f32_e32 v151, v144, v145
	v_mad_i64_i32 v[144:145], s[24:25], v137, s13, v[128:129]
	v_mul_f32_e32 v137, 0x3e38aa3b, v146
	v_cvt_pk_bf16_f32 v146, v134, v137
	ds_bpermute_b32 v137, v150, v77
	v_mul_f32_e32 v147, 0x3e38aa3b, v147
	v_mul_f32_e32 v151, 0x3e38aa3b, v151
	v_cvt_pk_bf16_f32 v147, v147, v151
	ds_bpermute_b32 v151, v150, v73
	s_waitcnt lgkmcnt(1)
	v_mul_f32_e32 v163, v148, v137
	v_add_u32_e32 v134, 49, v149
	global_store_dwordx2 v[144:145], v[146:147], off nt
	s_waitcnt vmcnt(2)
	v_pk_mul_f32 v[152:153], v[162:163], v[152:153]
	s_nop 0
	v_add_f32_e32 v137, v152, v153
	s_waitcnt lgkmcnt(0)
	v_mul_f32_e32 v153, v148, v151
	v_mov_b32_e32 v152, v73
	v_pk_mul_f32 v[152:153], v[152:153], v[154:155]
	s_nop 0
	v_add_f32_e32 v151, v152, v153
	v_mul_f32_e32 v153, v148, v164
	v_mov_b32_e32 v152, v69
	s_waitcnt vmcnt(1)
	v_pk_mul_f32 v[152:153], v[152:153], v[156:157]
	s_nop 0
	v_add_f32_e32 v154, v152, v153
	v_mul_f32_e32 v153, v148, v165
	v_mov_b32_e32 v152, v65
	v_pk_mul_f32 v[144:145], v[152:153], v[158:159]
	v_mul_f32_e32 v147, 0x3e38aa3b, v154
	v_add_f32_e32 v146, v144, v145
	v_mad_i64_i32 v[144:145], s[24:25], v134, s13, v[128:129]
	v_mul_f32_e32 v134, 0x3e38aa3b, v137
	v_mul_f32_e32 v137, 0x3e38aa3b, v151
	v_mul_f32_e32 v151, 0x3e38aa3b, v146
	v_cvt_pk_bf16_f32 v146, v134, v137
	v_cvt_pk_bf16_f32 v147, v147, v151
	global_store_dwordx2 v[144:145], v[146:147], off nt
	v_add_u32_e32 v137, 50, v149
	v_lshlrev_b32_e32 v134, 8, v137
	v_and_b32_e32 v134, 0x1e00, v134
	v_lshl_add_u64 v[144:145], v[130:131], 0, v[134:135]
	v_add_co_u32_e32 v160, vcc, s33, v144
	v_lshl_add_u64 v[152:153], v[144:145], 0, s[84:85]
	s_nop 0
	v_addc_co_u32_e32 v161, vcc, 0, v145, vcc
	v_lshl_add_u64 v[156:157], v[144:145], 0, s[26:27]
	global_load_dwordx4 v[144:147], v[160:161], off
	s_nop 0
	global_load_dwordx4 v[152:155], v[152:153], off offset:16
	ds_bpermute_b32 v134, v150, v78
	ds_bpermute_b32 v151, v150, v74
	ds_bpermute_b32 v162, v150, v70
	v_mov_b32_e32 v158, v78
	ds_bpermute_b32 v163, v150, v66
	s_waitcnt lgkmcnt(3)
	v_mul_f32_e32 v159, v148, v134
	ds_bpermute_b32 v164, v150, v71
	ds_bpermute_b32 v165, v150, v67
	s_waitcnt vmcnt(1)
	v_pk_mul_f32 v[144:145], v[158:159], v[144:145]
	s_nop 0
	v_add_f32_e32 v134, v144, v145
	s_waitcnt lgkmcnt(4)
	v_mul_f32_e32 v145, v148, v151
	v_mov_b32_e32 v144, v74
	v_pk_mul_f32 v[144:145], v[144:145], v[146:147]
	v_mul_f32_e32 v134, 0x3e38aa3b, v134
	v_add_f32_e32 v146, v144, v145
	s_waitcnt lgkmcnt(3)
	v_mul_f32_e32 v145, v148, v162
	v_mov_b32_e32 v144, v70
	s_waitcnt vmcnt(0)
	v_pk_mul_f32 v[144:145], v[144:145], v[152:153]
	v_mov_b32_e32 v162, v79
	v_add_f32_e32 v147, v144, v145
	s_waitcnt lgkmcnt(2)
	v_mul_f32_e32 v145, v148, v163
	v_mov_b32_e32 v144, v66
	v_pk_mul_f32 v[144:145], v[144:145], v[154:155]
	global_load_dwordx4 v[152:155], v[160:161], off offset:256
	s_nop 0
	global_load_dwordx4 v[156:159], v[156:157], off offset:16
	v_add_f32_e32 v151, v144, v145
	v_mad_i64_i32 v[144:145], s[24:25], v137, s13, v[128:129]
	v_mul_f32_e32 v137, 0x3e38aa3b, v146
	v_cvt_pk_bf16_f32 v146, v134, v137
	ds_bpermute_b32 v137, v150, v79
	v_mul_f32_e32 v147, 0x3e38aa3b, v147
	v_mul_f32_e32 v151, 0x3e38aa3b, v151
	v_cvt_pk_bf16_f32 v147, v147, v151
	ds_bpermute_b32 v151, v150, v75
	s_waitcnt lgkmcnt(1)
	v_mul_f32_e32 v163, v148, v137
	v_add_u32_e32 v134, 51, v149
	global_store_dwordx2 v[144:145], v[146:147], off nt
	s_waitcnt vmcnt(2)
	v_pk_mul_f32 v[152:153], v[162:163], v[152:153]
	s_nop 0
	v_add_f32_e32 v137, v152, v153
	s_waitcnt lgkmcnt(0)
	v_mul_f32_e32 v153, v148, v151
	v_mov_b32_e32 v152, v75
	v_pk_mul_f32 v[152:153], v[152:153], v[154:155]
	s_nop 0
	v_add_f32_e32 v151, v152, v153
	v_mul_f32_e32 v153, v148, v164
	v_mov_b32_e32 v152, v71
	s_waitcnt vmcnt(1)
	v_pk_mul_f32 v[152:153], v[152:153], v[156:157]
	s_nop 0
	v_add_f32_e32 v154, v152, v153
	v_mul_f32_e32 v153, v148, v165
	v_mov_b32_e32 v152, v67
	v_pk_mul_f32 v[144:145], v[152:153], v[158:159]
	v_mul_f32_e32 v147, 0x3e38aa3b, v154
	v_add_f32_e32 v146, v144, v145
	v_mad_i64_i32 v[144:145], s[24:25], v134, s13, v[128:129]
	v_mul_f32_e32 v134, 0x3e38aa3b, v137
	v_mul_f32_e32 v137, 0x3e38aa3b, v151
	v_mul_f32_e32 v151, 0x3e38aa3b, v146
	v_cvt_pk_bf16_f32 v146, v134, v137
	v_cvt_pk_bf16_f32 v147, v147, v151
	global_store_dwordx2 v[144:145], v[146:147], off nt
	v_add_u32_e32 v134, 64, v149
	global_load_dwordx4 v[144:147], v[140:141], off
	global_load_dwordx4 v[152:155], v[142:143], off offset:16
	ds_bpermute_b32 v137, v150, v60
	ds_bpermute_b32 v151, v150, v56
	ds_bpermute_b32 v158, v150, v52
	v_mov_b32_e32 v156, v60
	ds_bpermute_b32 v159, v150, v48
	s_waitcnt lgkmcnt(3)
	v_mul_f32_e32 v157, v148, v137
	ds_bpermute_b32 v162, v150, v53
	v_mov_b32_e32 v160, v61
	ds_bpermute_b32 v163, v150, v49
	s_waitcnt vmcnt(1)
	v_pk_mul_f32 v[144:145], v[156:157], v[144:145]
	s_nop 0
	v_add_f32_e32 v137, v144, v145
	s_waitcnt lgkmcnt(4)
	v_mul_f32_e32 v145, v148, v151
	v_mov_b32_e32 v144, v56
	v_pk_mul_f32 v[144:145], v[144:145], v[146:147]
	s_nop 0
	v_add_f32_e32 v146, v144, v145
	s_waitcnt lgkmcnt(3)
	v_mul_f32_e32 v145, v148, v158
	v_mov_b32_e32 v144, v52
	s_waitcnt vmcnt(0)
	v_pk_mul_f32 v[144:145], v[144:145], v[152:153]
	s_nop 0
	v_add_f32_e32 v147, v144, v145
	s_waitcnt lgkmcnt(2)
	v_mul_f32_e32 v145, v148, v159
	v_mov_b32_e32 v144, v48
	v_pk_mul_f32 v[144:145], v[144:145], v[154:155]
	global_load_dwordx4 v[152:155], v[140:141], off offset:256
	global_load_dwordx4 v[156:159], v[138:139], off offset:16
	v_add_f32_e32 v151, v144, v145
	v_mad_i64_i32 v[144:145], s[24:25], v134, s13, v[128:129]
	v_mul_f32_e32 v134, 0x3e38aa3b, v137
	v_mul_f32_e32 v137, 0x3e38aa3b, v146
	v_cvt_pk_bf16_f32 v146, v134, v137
	ds_bpermute_b32 v137, v150, v61
	v_mul_f32_e32 v147, 0x3e38aa3b, v147
	v_mul_f32_e32 v151, 0x3e38aa3b, v151
	v_cvt_pk_bf16_f32 v147, v147, v151
	ds_bpermute_b32 v151, v150, v57
	s_waitcnt lgkmcnt(1)
	v_mul_f32_e32 v161, v148, v137
	v_add_u32_e32 v134, 0x41, v149
	global_store_dwordx2 v[144:145], v[146:147], off nt
	s_waitcnt vmcnt(2)
	v_pk_mul_f32 v[152:153], v[160:161], v[152:153]
	s_nop 0
	v_add_f32_e32 v137, v152, v153
	s_waitcnt lgkmcnt(0)
	v_mul_f32_e32 v153, v148, v151
	v_mov_b32_e32 v152, v57
	v_pk_mul_f32 v[152:153], v[152:153], v[154:155]
	s_nop 0
	v_add_f32_e32 v151, v152, v153
	v_mul_f32_e32 v153, v148, v162
	v_mov_b32_e32 v152, v53
	s_waitcnt vmcnt(1)
	v_pk_mul_f32 v[152:153], v[152:153], v[156:157]
	s_nop 0
	v_add_f32_e32 v154, v152, v153
	v_mul_f32_e32 v153, v148, v163
	v_mov_b32_e32 v152, v49
	v_pk_mul_f32 v[144:145], v[152:153], v[158:159]
	v_mul_f32_e32 v147, 0x3e38aa3b, v154
	v_add_f32_e32 v146, v144, v145
	v_mad_i64_i32 v[144:145], s[24:25], v134, s13, v[128:129]
	v_mul_f32_e32 v134, 0x3e38aa3b, v137
	v_mul_f32_e32 v137, 0x3e38aa3b, v151
	v_mul_f32_e32 v151, 0x3e38aa3b, v146
	v_cvt_pk_bf16_f32 v146, v134, v137
	v_cvt_pk_bf16_f32 v147, v147, v151
	global_store_dwordx2 v[144:145], v[146:147], off nt
	v_add_u32_e32 v137, 0x42, v149
	v_lshlrev_b32_e32 v134, 8, v137
	v_and_b32_e32 v134, 0x1e00, v134
	v_lshl_add_u64 v[144:145], v[130:131], 0, v[134:135]
	v_add_co_u32_e32 v160, vcc, s33, v144
	v_lshl_add_u64 v[152:153], v[144:145], 0, s[84:85]
	s_nop 0
	v_addc_co_u32_e32 v161, vcc, 0, v145, vcc
	v_lshl_add_u64 v[156:157], v[144:145], 0, s[26:27]
	global_load_dwordx4 v[144:147], v[160:161], off
	s_nop 0
	global_load_dwordx4 v[152:155], v[152:153], off offset:16
	ds_bpermute_b32 v134, v150, v62
	ds_bpermute_b32 v151, v150, v58
	ds_bpermute_b32 v162, v150, v54
	v_mov_b32_e32 v158, v62
	ds_bpermute_b32 v163, v150, v50
	s_waitcnt lgkmcnt(3)
	v_mul_f32_e32 v159, v148, v134
	ds_bpermute_b32 v164, v150, v55
	ds_bpermute_b32 v165, v150, v51
	s_waitcnt vmcnt(1)
	v_pk_mul_f32 v[144:145], v[158:159], v[144:145]
	s_nop 0
	v_add_f32_e32 v134, v144, v145
	s_waitcnt lgkmcnt(4)
	v_mul_f32_e32 v145, v148, v151
	v_mov_b32_e32 v144, v58
	v_pk_mul_f32 v[144:145], v[144:145], v[146:147]
	v_mul_f32_e32 v134, 0x3e38aa3b, v134
	v_add_f32_e32 v146, v144, v145
	s_waitcnt lgkmcnt(3)
	v_mul_f32_e32 v145, v148, v162
	v_mov_b32_e32 v144, v54
	s_waitcnt vmcnt(0)
	v_pk_mul_f32 v[144:145], v[144:145], v[152:153]
	v_mov_b32_e32 v162, v63
	v_add_f32_e32 v147, v144, v145
	s_waitcnt lgkmcnt(2)
	v_mul_f32_e32 v145, v148, v163
	v_mov_b32_e32 v144, v50
	v_pk_mul_f32 v[144:145], v[144:145], v[154:155]
	global_load_dwordx4 v[152:155], v[160:161], off offset:256
	s_nop 0
	global_load_dwordx4 v[156:159], v[156:157], off offset:16
	v_add_f32_e32 v151, v144, v145
	v_mad_i64_i32 v[144:145], s[24:25], v137, s13, v[128:129]
	v_mul_f32_e32 v137, 0x3e38aa3b, v146
	v_cvt_pk_bf16_f32 v146, v134, v137
	ds_bpermute_b32 v137, v150, v63
	v_mul_f32_e32 v147, 0x3e38aa3b, v147
	v_mul_f32_e32 v151, 0x3e38aa3b, v151
	v_cvt_pk_bf16_f32 v147, v147, v151
	ds_bpermute_b32 v151, v150, v59
	s_waitcnt lgkmcnt(1)
	v_mul_f32_e32 v163, v148, v137
	v_add_u32_e32 v134, 0x43, v149
	global_store_dwordx2 v[144:145], v[146:147], off nt
	s_waitcnt vmcnt(2)
	v_pk_mul_f32 v[152:153], v[162:163], v[152:153]
	s_nop 0
	v_add_f32_e32 v137, v152, v153
	s_waitcnt lgkmcnt(0)
	v_mul_f32_e32 v153, v148, v151
	v_mov_b32_e32 v152, v59
	v_pk_mul_f32 v[152:153], v[152:153], v[154:155]
	s_nop 0
	v_add_f32_e32 v151, v152, v153
	v_mul_f32_e32 v153, v148, v164
	v_mov_b32_e32 v152, v55
	s_waitcnt vmcnt(1)
	v_pk_mul_f32 v[152:153], v[152:153], v[156:157]
	s_nop 0
	v_add_f32_e32 v154, v152, v153
	v_mul_f32_e32 v153, v148, v165
	v_mov_b32_e32 v152, v51
	v_pk_mul_f32 v[144:145], v[152:153], v[158:159]
	v_mul_f32_e32 v147, 0x3e38aa3b, v154
	v_add_f32_e32 v146, v144, v145
	v_mad_i64_i32 v[144:145], s[24:25], v134, s13, v[128:129]
	v_mul_f32_e32 v134, 0x3e38aa3b, v137
	v_mul_f32_e32 v137, 0x3e38aa3b, v151
	v_mul_f32_e32 v151, 0x3e38aa3b, v146
	v_cvt_pk_bf16_f32 v146, v134, v137
	v_cvt_pk_bf16_f32 v147, v147, v151
	global_store_dwordx2 v[144:145], v[146:147], off nt
	v_add_u32_e32 v137, 0x50, v149
	v_lshlrev_b32_e32 v134, 8, v137
	v_and_b32_e32 v134, 0x1c00, v134
	v_lshl_add_u64 v[144:145], v[130:131], 0, v[134:135]
	v_add_co_u32_e32 v160, vcc, s33, v144
	v_lshl_add_u64 v[152:153], v[144:145], 0, s[84:85]
	s_nop 0
	v_addc_co_u32_e32 v161, vcc, 0, v145, vcc
	v_lshl_add_u64 v[156:157], v[144:145], 0, s[26:27]
	global_load_dwordx4 v[144:147], v[160:161], off
	s_nop 0
	global_load_dwordx4 v[152:155], v[152:153], off offset:16
	ds_bpermute_b32 v134, v150, v44
	ds_bpermute_b32 v151, v150, v40
	ds_bpermute_b32 v162, v150, v36
	v_mov_b32_e32 v158, v44
	ds_bpermute_b32 v163, v150, v32
	s_waitcnt lgkmcnt(3)
	v_mul_f32_e32 v159, v148, v134
	ds_bpermute_b32 v164, v150, v37
	ds_bpermute_b32 v165, v150, v33
	s_waitcnt vmcnt(1)
	v_pk_mul_f32 v[144:145], v[158:159], v[144:145]
	s_nop 0
	v_add_f32_e32 v134, v144, v145
	s_waitcnt lgkmcnt(4)
	v_mul_f32_e32 v145, v148, v151
	v_mov_b32_e32 v144, v40
	v_pk_mul_f32 v[144:145], v[144:145], v[146:147]
	v_mul_f32_e32 v134, 0x3e38aa3b, v134
	v_add_f32_e32 v146, v144, v145
	s_waitcnt lgkmcnt(3)
	v_mul_f32_e32 v145, v148, v162
	v_mov_b32_e32 v144, v36
	s_waitcnt vmcnt(0)
	v_pk_mul_f32 v[144:145], v[144:145], v[152:153]
	v_mov_b32_e32 v162, v45
	v_add_f32_e32 v147, v144, v145
	s_waitcnt lgkmcnt(2)
	v_mul_f32_e32 v145, v148, v163
	v_mov_b32_e32 v144, v32
	v_pk_mul_f32 v[144:145], v[144:145], v[154:155]
	global_load_dwordx4 v[152:155], v[160:161], off offset:256
	s_nop 0
	global_load_dwordx4 v[156:159], v[156:157], off offset:16
	v_add_f32_e32 v151, v144, v145
	v_mad_i64_i32 v[144:145], s[24:25], v137, s13, v[128:129]
	v_mul_f32_e32 v137, 0x3e38aa3b, v146
	v_cvt_pk_bf16_f32 v146, v134, v137
	ds_bpermute_b32 v137, v150, v45
	v_mul_f32_e32 v147, 0x3e38aa3b, v147
	v_mul_f32_e32 v151, 0x3e38aa3b, v151
	v_cvt_pk_bf16_f32 v147, v147, v151
	ds_bpermute_b32 v151, v150, v41
	s_waitcnt lgkmcnt(1)
	v_mul_f32_e32 v163, v148, v137
	v_add_u32_e32 v134, 0x51, v149
	global_store_dwordx2 v[144:145], v[146:147], off nt
	s_waitcnt vmcnt(2)
	v_pk_mul_f32 v[152:153], v[162:163], v[152:153]
	s_nop 0
	v_add_f32_e32 v137, v152, v153
	s_waitcnt lgkmcnt(0)
	v_mul_f32_e32 v153, v148, v151
	v_mov_b32_e32 v152, v41
	v_pk_mul_f32 v[152:153], v[152:153], v[154:155]
	s_nop 0
	v_add_f32_e32 v151, v152, v153
	v_mul_f32_e32 v153, v148, v164
	v_mov_b32_e32 v152, v37
	s_waitcnt vmcnt(1)
	v_pk_mul_f32 v[152:153], v[152:153], v[156:157]
	s_nop 0
	v_add_f32_e32 v154, v152, v153
	v_mul_f32_e32 v153, v148, v165
	v_mov_b32_e32 v152, v33
	v_pk_mul_f32 v[144:145], v[152:153], v[158:159]
	v_mul_f32_e32 v147, 0x3e38aa3b, v154
	v_add_f32_e32 v146, v144, v145
	v_mad_i64_i32 v[144:145], s[24:25], v134, s13, v[128:129]
	v_mul_f32_e32 v134, 0x3e38aa3b, v137
	v_mul_f32_e32 v137, 0x3e38aa3b, v151
	v_mul_f32_e32 v151, 0x3e38aa3b, v146
	v_cvt_pk_bf16_f32 v146, v134, v137
	v_cvt_pk_bf16_f32 v147, v147, v151
	global_store_dwordx2 v[144:145], v[146:147], off nt
	v_add_u32_e32 v137, 0x52, v149
	v_lshlrev_b32_e32 v134, 8, v137
	v_and_b32_e32 v134, 0x1e00, v134
	v_lshl_add_u64 v[144:145], v[130:131], 0, v[134:135]
	v_add_co_u32_e32 v160, vcc, s33, v144
	v_lshl_add_u64 v[152:153], v[144:145], 0, s[84:85]
	s_nop 0
	v_addc_co_u32_e32 v161, vcc, 0, v145, vcc
	v_lshl_add_u64 v[156:157], v[144:145], 0, s[26:27]
	global_load_dwordx4 v[144:147], v[160:161], off
	s_nop 0
	global_load_dwordx4 v[152:155], v[152:153], off offset:16
	ds_bpermute_b32 v134, v150, v46
	ds_bpermute_b32 v151, v150, v42
	ds_bpermute_b32 v162, v150, v38
	v_mov_b32_e32 v158, v46
	ds_bpermute_b32 v163, v150, v34
	s_waitcnt lgkmcnt(3)
	v_mul_f32_e32 v159, v148, v134
	ds_bpermute_b32 v164, v150, v39
	ds_bpermute_b32 v165, v150, v35
	s_waitcnt vmcnt(1)
	v_pk_mul_f32 v[144:145], v[158:159], v[144:145]
	s_nop 0
	v_add_f32_e32 v134, v144, v145
	s_waitcnt lgkmcnt(4)
	v_mul_f32_e32 v145, v148, v151
	v_mov_b32_e32 v144, v42
	v_pk_mul_f32 v[144:145], v[144:145], v[146:147]
	v_mul_f32_e32 v134, 0x3e38aa3b, v134
	v_add_f32_e32 v146, v144, v145
	s_waitcnt lgkmcnt(3)
	v_mul_f32_e32 v145, v148, v162
	v_mov_b32_e32 v144, v38
	s_waitcnt vmcnt(0)
	v_pk_mul_f32 v[144:145], v[144:145], v[152:153]
	v_mov_b32_e32 v162, v47
	v_add_f32_e32 v147, v144, v145
	s_waitcnt lgkmcnt(2)
	v_mul_f32_e32 v145, v148, v163
	v_mov_b32_e32 v144, v34
	v_pk_mul_f32 v[144:145], v[144:145], v[154:155]
	global_load_dwordx4 v[152:155], v[160:161], off offset:256
	s_nop 0
	global_load_dwordx4 v[156:159], v[156:157], off offset:16
	v_add_f32_e32 v151, v144, v145
	v_mad_i64_i32 v[144:145], s[24:25], v137, s13, v[128:129]
	v_mul_f32_e32 v137, 0x3e38aa3b, v146
	v_cvt_pk_bf16_f32 v146, v134, v137
	ds_bpermute_b32 v137, v150, v47
	v_mul_f32_e32 v147, 0x3e38aa3b, v147
	v_mul_f32_e32 v151, 0x3e38aa3b, v151
	v_cvt_pk_bf16_f32 v147, v147, v151
	ds_bpermute_b32 v151, v150, v43
	s_waitcnt lgkmcnt(1)
	v_mul_f32_e32 v163, v148, v137
	v_add_u32_e32 v134, 0x53, v149
	global_store_dwordx2 v[144:145], v[146:147], off nt
	s_waitcnt vmcnt(2)
	v_pk_mul_f32 v[152:153], v[162:163], v[152:153]
	s_nop 0
	v_add_f32_e32 v137, v152, v153
	s_waitcnt lgkmcnt(0)
	v_mul_f32_e32 v153, v148, v151
	v_mov_b32_e32 v152, v43
	v_pk_mul_f32 v[152:153], v[152:153], v[154:155]
	s_nop 0
	v_add_f32_e32 v151, v152, v153
	v_mul_f32_e32 v153, v148, v164
	v_mov_b32_e32 v152, v39
	s_waitcnt vmcnt(1)
	v_pk_mul_f32 v[152:153], v[152:153], v[156:157]
	s_nop 0
	v_add_f32_e32 v154, v152, v153
	v_mul_f32_e32 v153, v148, v165
	v_mov_b32_e32 v152, v35
	v_pk_mul_f32 v[144:145], v[152:153], v[158:159]
	v_mul_f32_e32 v147, 0x3e38aa3b, v154
	v_add_f32_e32 v146, v144, v145
	v_mad_i64_i32 v[144:145], s[24:25], v134, s13, v[128:129]
	v_mul_f32_e32 v134, 0x3e38aa3b, v137
	v_mul_f32_e32 v137, 0x3e38aa3b, v151
	v_mul_f32_e32 v151, 0x3e38aa3b, v146
	v_cvt_pk_bf16_f32 v146, v134, v137
	v_cvt_pk_bf16_f32 v147, v147, v151
	global_store_dwordx2 v[144:145], v[146:147], off nt
	v_add_u32_e32 v134, 0x60, v149
	global_load_dwordx4 v[144:147], v[140:141], off
	global_load_dwordx4 v[152:155], v[142:143], off offset:16
	ds_bpermute_b32 v137, v150, v28
	ds_bpermute_b32 v151, v150, v24
	ds_bpermute_b32 v158, v150, v20
	v_mov_b32_e32 v156, v28
	ds_bpermute_b32 v159, v150, v16
	s_waitcnt lgkmcnt(3)
	v_mul_f32_e32 v157, v148, v137
	s_waitcnt vmcnt(1)
	v_pk_mul_f32 v[142:143], v[156:157], v[144:145]
	s_nop 0
	v_add_f32_e32 v137, v142, v143
	s_waitcnt lgkmcnt(2)
	v_mul_f32_e32 v143, v148, v151
	v_mov_b32_e32 v142, v24
	v_pk_mul_f32 v[142:143], v[142:143], v[146:147]
	ds_bpermute_b32 v151, v150, v25
	v_add_f32_e32 v144, v142, v143
	s_waitcnt lgkmcnt(2)
	v_mul_f32_e32 v143, v148, v158
	v_mov_b32_e32 v142, v20
	s_waitcnt vmcnt(0)
	v_pk_mul_f32 v[142:143], v[142:143], v[152:153]
	ds_bpermute_b32 v156, v150, v21
	v_add_f32_e32 v145, v142, v143
	s_waitcnt lgkmcnt(2)
	v_mul_f32_e32 v143, v148, v159
	v_mov_b32_e32 v142, v16
	v_pk_mul_f32 v[142:143], v[142:143], v[154:155]
	global_load_dwordx4 v[152:155], v[140:141], off offset:256
	s_nop 0
	global_load_dwordx4 v[138:141], v[138:139], off offset:16
	v_add_f32_e32 v146, v142, v143
	v_mad_i64_i32 v[142:143], s[24:25], v134, s13, v[128:129]
	v_mul_f32_e32 v134, 0x3e38aa3b, v137
	v_mul_f32_e32 v137, 0x3e38aa3b, v144
	v_cvt_pk_bf16_f32 v144, v134, v137
	ds_bpermute_b32 v137, v150, v29
	v_mul_f32_e32 v145, 0x3e38aa3b, v145
	v_mul_f32_e32 v146, 0x3e38aa3b, v146
	v_cvt_pk_bf16_f32 v145, v145, v146
	v_mov_b32_e32 v146, v29
	s_waitcnt lgkmcnt(0)
	v_mul_f32_e32 v147, v148, v137
	ds_bpermute_b32 v157, v150, v17
	v_add_u32_e32 v134, 0x61, v149
	global_store_dwordx2 v[142:143], v[144:145], off nt
	s_waitcnt vmcnt(2)
	v_pk_mul_f32 v[146:147], v[146:147], v[152:153]
	s_nop 0
	v_add_f32_e32 v137, v146, v147
	v_mul_f32_e32 v147, v148, v151
	v_mov_b32_e32 v146, v25
	v_pk_mul_f32 v[146:147], v[146:147], v[154:155]
	s_nop 0
	v_add_f32_e32 v151, v146, v147
	v_mul_f32_e32 v147, v148, v156
	v_mov_b32_e32 v146, v21
	s_waitcnt vmcnt(1)
	v_pk_mul_f32 v[138:139], v[146:147], v[138:139]
	s_nop 0
	v_add_f32_e32 v146, v138, v139
	s_waitcnt lgkmcnt(0)
	v_mul_f32_e32 v139, v148, v157
	v_mov_b32_e32 v138, v17
	v_pk_mul_f32 v[138:139], v[138:139], v[140:141]
	v_mul_f32_e32 v141, 0x3e38aa3b, v146
	v_add_f32_e32 v140, v138, v139
	v_mad_i64_i32 v[138:139], s[24:25], v134, s13, v[128:129]
	v_mul_f32_e32 v134, 0x3e38aa3b, v137
	v_mul_f32_e32 v137, 0x3e38aa3b, v151
	v_mul_f32_e32 v142, 0x3e38aa3b, v140
	v_cvt_pk_bf16_f32 v140, v134, v137
	v_cvt_pk_bf16_f32 v141, v141, v142
	global_store_dwordx2 v[138:139], v[140:141], off nt
	v_add_u32_e32 v137, 0x62, v149
	v_lshlrev_b32_e32 v134, 8, v137
	v_and_b32_e32 v134, 0x1e00, v134
	v_lshl_add_u64 v[138:139], v[130:131], 0, v[134:135]
	v_add_co_u32_e32 v154, vcc, s33, v138
	v_lshl_add_u64 v[142:143], v[138:139], 0, s[84:85]
	s_nop 0
	v_addc_co_u32_e32 v155, vcc, 0, v139, vcc
	v_lshl_add_u64 v[146:147], v[138:139], 0, s[26:27]
	global_load_dwordx4 v[138:141], v[154:155], off
	s_nop 0
	global_load_dwordx4 v[142:145], v[142:143], off offset:16
	ds_bpermute_b32 v134, v150, v30
	ds_bpermute_b32 v151, v150, v26
	ds_bpermute_b32 v156, v150, v22
	v_mov_b32_e32 v152, v30
	ds_bpermute_b32 v157, v150, v18
	s_waitcnt lgkmcnt(3)
	v_mul_f32_e32 v153, v148, v134
	ds_bpermute_b32 v158, v150, v23
	ds_bpermute_b32 v159, v150, v19
	s_waitcnt vmcnt(1)
	v_pk_mul_f32 v[138:139], v[152:153], v[138:139]
	s_nop 0
	v_add_f32_e32 v134, v138, v139
	s_waitcnt lgkmcnt(4)
	v_mul_f32_e32 v139, v148, v151
	v_mov_b32_e32 v138, v26
	v_pk_mul_f32 v[138:139], v[138:139], v[140:141]
	v_mul_f32_e32 v134, 0x3e38aa3b, v134
	v_add_f32_e32 v140, v138, v139
	s_waitcnt lgkmcnt(3)
	v_mul_f32_e32 v139, v148, v156
	v_mov_b32_e32 v138, v22
	s_waitcnt vmcnt(0)
	v_pk_mul_f32 v[138:139], v[138:139], v[142:143]
	ds_bpermute_b32 v151, v150, v27
	v_add_f32_e32 v141, v138, v139
	s_waitcnt lgkmcnt(3)
	v_mul_f32_e32 v139, v148, v157
	v_mov_b32_e32 v138, v18
	v_pk_mul_f32 v[138:139], v[138:139], v[144:145]
	v_mul_f32_e32 v141, 0x3e38aa3b, v141
	v_add_f32_e32 v142, v138, v139
	v_mul_f32_e32 v142, 0x3e38aa3b, v142
	v_cvt_pk_bf16_f32 v141, v141, v142
	global_load_dwordx4 v[142:145], v[154:155], off offset:256
	s_nop 0
	global_load_dwordx4 v[152:155], v[146:147], off offset:16
	v_mad_i64_i32 v[138:139], s[24:25], v137, s13, v[128:129]
	v_mul_f32_e32 v137, 0x3e38aa3b, v140
	v_cvt_pk_bf16_f32 v140, v134, v137
	ds_bpermute_b32 v137, v150, v31
	v_mov_b32_e32 v156, v31
	v_add_u32_e32 v134, 0x63, v149
	global_store_dwordx2 v[138:139], v[140:141], off nt
	s_waitcnt lgkmcnt(0)
	v_mul_f32_e32 v157, v148, v137
	s_waitcnt vmcnt(2)
	v_pk_mul_f32 v[142:143], v[156:157], v[142:143]
	s_nop 0
	v_add_f32_e32 v137, v142, v143
	v_mul_f32_e32 v143, v148, v151
	v_mov_b32_e32 v142, v27
	v_pk_mul_f32 v[142:143], v[142:143], v[144:145]
	s_nop 0
	v_add_f32_e32 v144, v142, v143
	v_mul_f32_e32 v143, v148, v158
	v_mov_b32_e32 v142, v23
	s_waitcnt vmcnt(1)
	v_pk_mul_f32 v[142:143], v[142:143], v[152:153]
	s_nop 0
	v_add_f32_e32 v145, v142, v143
	v_mul_f32_e32 v143, v148, v159
	v_mov_b32_e32 v142, v19
	v_pk_mul_f32 v[138:139], v[142:143], v[154:155]
	v_mul_f32_e32 v141, 0x3e38aa3b, v145
	v_add_f32_e32 v140, v138, v139
	v_mad_i64_i32 v[138:139], s[24:25], v134, s13, v[128:129]
	v_mul_f32_e32 v134, 0x3e38aa3b, v137
	v_mul_f32_e32 v137, 0x3e38aa3b, v144
	v_mul_f32_e32 v142, 0x3e38aa3b, v140
	v_cvt_pk_bf16_f32 v140, v134, v137
	v_cvt_pk_bf16_f32 v141, v141, v142
	global_store_dwordx2 v[138:139], v[140:141], off nt
	v_add_u32_e32 v137, 0x70, v149
	v_lshlrev_b32_e32 v134, 8, v137
	v_and_b32_e32 v134, 0x1c00, v134
	v_lshl_add_u64 v[138:139], v[130:131], 0, v[134:135]
	v_add_co_u32_e32 v154, vcc, s33, v138
	v_lshl_add_u64 v[142:143], v[138:139], 0, s[84:85]
	s_nop 0
	v_addc_co_u32_e32 v155, vcc, 0, v139, vcc
	v_lshl_add_u64 v[146:147], v[138:139], 0, s[26:27]
	global_load_dwordx4 v[138:141], v[154:155], off
	s_nop 0
	global_load_dwordx4 v[142:145], v[142:143], off offset:16
	ds_bpermute_b32 v134, v150, v12
	ds_bpermute_b32 v151, v150, v8
	ds_bpermute_b32 v156, v150, v4
	v_mov_b32_e32 v152, v12
	ds_bpermute_b32 v157, v150, v0
	s_waitcnt lgkmcnt(3)
	v_mul_f32_e32 v153, v148, v134
	ds_bpermute_b32 v158, v150, v5
	ds_bpermute_b32 v159, v150, v1
	s_waitcnt vmcnt(1)
	v_pk_mul_f32 v[138:139], v[152:153], v[138:139]
	s_nop 0
	v_add_f32_e32 v134, v138, v139
	s_waitcnt lgkmcnt(4)
	v_mul_f32_e32 v139, v148, v151
	v_mov_b32_e32 v138, v8
	v_pk_mul_f32 v[138:139], v[138:139], v[140:141]
	v_mul_f32_e32 v134, 0x3e38aa3b, v134
	v_add_f32_e32 v140, v138, v139
	s_waitcnt lgkmcnt(3)
	v_mul_f32_e32 v139, v148, v156
	v_mov_b32_e32 v138, v4
	s_waitcnt vmcnt(0)
	v_pk_mul_f32 v[138:139], v[138:139], v[142:143]
	ds_bpermute_b32 v151, v150, v9
	v_add_f32_e32 v141, v138, v139
	s_waitcnt lgkmcnt(3)
	v_mul_f32_e32 v139, v148, v157
	v_mov_b32_e32 v138, v0
	v_pk_mul_f32 v[138:139], v[138:139], v[144:145]
	v_mul_f32_e32 v141, 0x3e38aa3b, v141
	v_add_f32_e32 v142, v138, v139
	v_mul_f32_e32 v142, 0x3e38aa3b, v142
	v_cvt_pk_bf16_f32 v141, v141, v142
	global_load_dwordx4 v[142:145], v[154:155], off offset:256
	s_nop 0
	global_load_dwordx4 v[152:155], v[146:147], off offset:16
	v_mad_i64_i32 v[138:139], s[24:25], v137, s13, v[128:129]
	v_mul_f32_e32 v137, 0x3e38aa3b, v140
	v_cvt_pk_bf16_f32 v140, v134, v137
	ds_bpermute_b32 v137, v150, v13
	v_mov_b32_e32 v156, v13
	v_add_u32_e32 v134, 0x71, v149
	global_store_dwordx2 v[138:139], v[140:141], off nt
	s_waitcnt lgkmcnt(0)
	v_mul_f32_e32 v157, v148, v137
	s_waitcnt vmcnt(2)
	v_pk_mul_f32 v[142:143], v[156:157], v[142:143]
	s_nop 0
	v_add_f32_e32 v137, v142, v143
	v_mul_f32_e32 v143, v148, v151
	v_mov_b32_e32 v142, v9
	v_pk_mul_f32 v[142:143], v[142:143], v[144:145]
	s_nop 0
	v_add_f32_e32 v144, v142, v143
	v_mul_f32_e32 v143, v148, v158
	v_mov_b32_e32 v142, v5
	s_waitcnt vmcnt(1)
	v_pk_mul_f32 v[142:143], v[142:143], v[152:153]
	s_nop 0
	v_add_f32_e32 v145, v142, v143
	v_mul_f32_e32 v143, v148, v159
	v_mov_b32_e32 v142, v1
	v_pk_mul_f32 v[138:139], v[142:143], v[154:155]
	v_mul_f32_e32 v141, 0x3e38aa3b, v145
	v_add_f32_e32 v140, v138, v139
	v_mad_i64_i32 v[138:139], s[24:25], v134, s13, v[128:129]
	v_mul_f32_e32 v134, 0x3e38aa3b, v137
	v_mul_f32_e32 v137, 0x3e38aa3b, v144
	v_mul_f32_e32 v142, 0x3e38aa3b, v140
	v_cvt_pk_bf16_f32 v140, v134, v137
	v_cvt_pk_bf16_f32 v141, v141, v142
	global_store_dwordx2 v[138:139], v[140:141], off nt
	v_add_u32_e32 v137, 0x72, v149
	v_lshlrev_b32_e32 v134, 8, v137
	v_and_b32_e32 v134, 0x1e00, v134
	v_lshl_add_u64 v[130:131], v[130:131], 0, v[134:135]
	v_add_co_u32_e32 v154, vcc, s33, v130
	v_lshl_add_u64 v[142:143], v[130:131], 0, s[84:85]
	s_nop 0
	v_addc_co_u32_e32 v155, vcc, 0, v131, vcc
	global_load_dwordx4 v[138:141], v[154:155], off
	s_nop 0
	global_load_dwordx4 v[142:145], v[142:143], off offset:16
	ds_bpermute_b32 v134, v150, v14
	ds_bpermute_b32 v151, v150, v10
	ds_bpermute_b32 v156, v150, v6
	v_mov_b32_e32 v152, v14
	v_lshl_add_u64 v[146:147], v[130:131], 0, s[26:27]
	s_waitcnt lgkmcnt(2)
	v_mul_f32_e32 v153, v148, v134
	ds_bpermute_b32 v157, v150, v2
	s_waitcnt vmcnt(1)
	v_pk_mul_f32 v[130:131], v[152:153], v[138:139]
	s_nop 0
	v_add_f32_e32 v134, v130, v131
	s_waitcnt lgkmcnt(2)
	v_mul_f32_e32 v131, v148, v151
	v_mov_b32_e32 v130, v10
	v_pk_mul_f32 v[130:131], v[130:131], v[140:141]
	v_mul_f32_e32 v134, 0x3e38aa3b, v134
	v_add_f32_e32 v138, v130, v131
	s_waitcnt lgkmcnt(1)
	v_mul_f32_e32 v131, v148, v156
	v_mov_b32_e32 v130, v6
	s_waitcnt vmcnt(0)
	v_pk_mul_f32 v[130:131], v[130:131], v[142:143]
	ds_bpermute_b32 v152, v150, v7
	v_add_f32_e32 v139, v130, v131
	s_waitcnt lgkmcnt(1)
	v_mul_f32_e32 v131, v148, v157
	v_mov_b32_e32 v130, v2
	v_pk_mul_f32 v[130:131], v[130:131], v[144:145]
	v_mul_f32_e32 v139, 0x3e38aa3b, v139
	v_add_f32_e32 v140, v130, v131
	v_mul_f32_e32 v140, 0x3e38aa3b, v140
	v_cvt_pk_bf16_f32 v139, v139, v140
	global_load_dwordx4 v[140:143], v[154:155], off offset:256
	s_nop 0
	global_load_dwordx4 v[144:147], v[146:147], off offset:16
	v_mad_i64_i32 v[130:131], s[24:25], v137, s13, v[128:129]
	v_mul_f32_e32 v137, 0x3e38aa3b, v138
	v_cvt_pk_bf16_f32 v138, v134, v137
	ds_bpermute_b32 v137, v150, v15
	v_add_u32_e32 v134, 0x73, v149
	ds_bpermute_b32 v149, v150, v11
	ds_bpermute_b32 v153, v150, v3
	v_mov_b32_e32 v150, v15
	s_waitcnt lgkmcnt(2)
	v_mul_f32_e32 v151, v148, v137
	global_store_dwordx2 v[130:131], v[138:139], off nt
	s_waitcnt vmcnt(2)
	v_pk_mul_f32 v[140:141], v[150:151], v[140:141]
	s_nop 0
	v_add_f32_e32 v137, v140, v141
	s_waitcnt lgkmcnt(1)
	v_mul_f32_e32 v141, v148, v149
	v_mov_b32_e32 v140, v11
	v_pk_mul_f32 v[140:141], v[140:141], v[142:143]
	s_nop 0
	v_add_f32_e32 v142, v140, v141
	v_mul_f32_e32 v141, v148, v152
	v_mov_b32_e32 v140, v7
	s_waitcnt vmcnt(1)
	v_pk_mul_f32 v[140:141], v[140:141], v[144:145]
	s_nop 0
	v_add_f32_e32 v143, v140, v141
	s_waitcnt lgkmcnt(0)
	v_mul_f32_e32 v141, v148, v153
	v_mov_b32_e32 v140, v3
	v_pk_mul_f32 v[130:131], v[140:141], v[146:147]
	v_mad_i64_i32 v[128:129], s[24:25], v134, s13, v[128:129]
	v_add_f32_e32 v130, v130, v131
	v_mul_f32_e32 v131, 0x3e38aa3b, v137
	s_xor_b64 s[74:75], exec, -1
	v_mul_f32_e32 v134, 0x3e38aa3b, v142
	v_mul_f32_e32 v137, 0x3e38aa3b, v143
	v_mul_f32_e32 v138, 0x3e38aa3b, v130
	v_cvt_pk_bf16_f32 v130, v131, v134
	v_cvt_pk_bf16_f32 v131, v137, v138
	global_store_dwordx2 v[128:129], v[130:131], off nt

.LBB0_250:
	s_or_b64 exec, exec, s[8:9]
	v_lshl_add_u32 v128, v178, 2, v211
	v_ashrrev_i32_e32 v137, 31, v136
	v_or_b32_e32 v166, 1, v128
	v_or_b32_e32 v164, 2, v128
	v_or_b32_e32 v162, 3, v128
	v_add_u32_e32 v160, 16, v128
	v_add_u32_e32 v158, 17, v128
	v_add_u32_e32 v156, 18, v128
	v_add_u32_e32 v154, 19, v128
	v_add_u32_e32 v152, 32, v128
	v_add_u32_e32 v150, 33, v128
	v_add_u32_e32 v148, 34, v128
	v_add_u32_e32 v146, 35, v128
	v_add_u32_e32 v144, 48, v128
	v_add_u32_e32 v142, 49, v128
	v_add_u32_e32 v140, 50, v128
	v_add_u32_e32 v138, 51, v128
	v_add_u32_e32 v130, 64, v128
	s_and_saveexec_b64 s[8:9], s[66:67]
	s_cbranch_execz .LBB0_252
	v_cmp_eq_u32_e32 vcc, 7, v177
	v_mov_b32_e32 v129, 0x180
	v_readlane_b32 s36, v253, 26
	v_cndmask_b32_e32 v129, v252, v129, vcc
	v_cmp_ne_u32_e32 vcc, 3, v177
	v_readlane_b32 s42, v253, 32
	v_readlane_b32 s43, v253, 33
	v_cndmask_b32_e32 v129, 0, v129, vcc
	v_lshlrev_b32_e32 v134, 1, v129
	v_lshl_add_u64 v[168:169], s[42:43], 0, v[134:135]
	v_readlane_b32 s37, v253, 27
	v_readlane_b32 s38, v253, 28
	v_readlane_b32 s39, v253, 29
	v_readlane_b32 s40, v253, 30
	v_readlane_b32 s41, v253, 31
	v_readlane_b32 s44, v253, 34
	v_readlane_b32 s45, v253, 35
	v_readlane_b32 s46, v253, 36
	v_readlane_b32 s47, v253, 37
	v_readlane_b32 s48, v253, 38
	v_readlane_b32 s49, v253, 39
	v_readlane_b32 s50, v253, 40
	v_readlane_b32 s51, v253, 41
	v_lshl_add_u64 v[168:169], v[136:137], 1, v[168:169]
	v_ashrrev_i32_e32 v129, 31, v128
	v_lshlrev_b64 v[170:171], 11, v[128:129]
	v_mul_f32_e32 v129, 0xbfb8aa3b, v124
	v_mul_f32_e32 v131, 0xbfb8aa3b, v120
	v_mul_f32_e32 v134, 0xbfb8aa3b, v116
	v_mul_f32_e32 v139, 0xbfb8aa3b, v112
	v_exp_f32_e32 v129, v129
	v_exp_f32_e32 v131, v131
	v_exp_f32_e32 v134, v134
	v_exp_f32_e32 v139, v139
	v_add_f32_e32 v129, 1.0, v129
	v_add_f32_e32 v131, 1.0, v131
	v_add_f32_e32 v134, 1.0, v134
	v_add_f32_e32 v139, 1.0, v139
	v_rcp_f32_e32 v129, v129
	v_rcp_f32_e32 v131, v131
	v_rcp_f32_e32 v134, v134
	v_rcp_f32_e32 v139, v139
	v_lshl_add_u64 v[170:171], v[168:169], 0, v[170:171]
	v_mul_f32_e32 v129, v124, v129
	v_mul_f32_e32 v131, v120, v131
	v_mul_f32_e32 v134, v116, v134
	v_mul_f32_e32 v139, v112, v139
	v_cvt_pk_bf16_f32 v172, v129, v131
	v_cvt_pk_bf16_f32 v173, v134, v139
	global_store_dwordx2 v[170:171], v[172:173], off nt
	v_mul_f32_e32 v129, 0xbfb8aa3b, v125
	v_mul_f32_e32 v131, 0xbfb8aa3b, v121
	v_mul_f32_e32 v134, 0xbfb8aa3b, v117
	v_mul_f32_e32 v139, 0xbfb8aa3b, v113
	v_exp_f32_e32 v129, v129
	v_exp_f32_e32 v131, v131
	v_exp_f32_e32 v134, v134
	v_exp_f32_e32 v139, v139
	v_add_f32_e32 v129, 1.0, v129
	v_add_f32_e32 v131, 1.0, v131
	v_add_f32_e32 v134, 1.0, v134
	v_add_f32_e32 v139, 1.0, v139
	v_rcp_f32_e32 v129, v129
	v_rcp_f32_e32 v131, v131
	v_rcp_f32_e32 v134, v134
	v_rcp_f32_e32 v139, v139
	v_ashrrev_i32_e32 v167, 31, v166
	v_lshlrev_b64 v[170:171], 11, v[166:167]
	v_lshl_add_u64 v[170:171], v[168:169], 0, v[170:171]
	v_mul_f32_e32 v129, v125, v129
	v_mul_f32_e32 v131, v121, v131
	v_mul_f32_e32 v134, v117, v134
	v_mul_f32_e32 v139, v113, v139
	v_cvt_pk_bf16_f32 v172, v129, v131
	v_cvt_pk_bf16_f32 v173, v134, v139
	global_store_dwordx2 v[170:171], v[172:173], off nt
	v_mul_f32_e32 v129, 0xbfb8aa3b, v126
	v_mul_f32_e32 v131, 0xbfb8aa3b, v122
	v_mul_f32_e32 v134, 0xbfb8aa3b, v118
	v_mul_f32_e32 v139, 0xbfb8aa3b, v114
	v_exp_f32_e32 v129, v129
	v_exp_f32_e32 v131, v131
	v_exp_f32_e32 v134, v134
	v_exp_f32_e32 v139, v139
	v_add_f32_e32 v129, 1.0, v129
	v_add_f32_e32 v131, 1.0, v131
	v_add_f32_e32 v134, 1.0, v134
	v_add_f32_e32 v139, 1.0, v139
	v_rcp_f32_e32 v129, v129
	v_rcp_f32_e32 v131, v131
	v_rcp_f32_e32 v134, v134
	v_rcp_f32_e32 v139, v139
	v_ashrrev_i32_e32 v165, 31, v164
	v_lshlrev_b64 v[170:171], 11, v[164:165]
	v_lshl_add_u64 v[170:171], v[168:169], 0, v[170:171]
	v_mul_f32_e32 v129, v126, v129
	v_mul_f32_e32 v131, v122, v131
	v_mul_f32_e32 v134, v118, v134
	v_mul_f32_e32 v139, v114, v139
	v_cvt_pk_bf16_f32 v172, v129, v131
	v_cvt_pk_bf16_f32 v173, v134, v139
	global_store_dwordx2 v[170:171], v[172:173], off nt
	v_mul_f32_e32 v129, 0xbfb8aa3b, v127
	v_mul_f32_e32 v131, 0xbfb8aa3b, v123
	v_mul_f32_e32 v134, 0xbfb8aa3b, v119
	v_mul_f32_e32 v139, 0xbfb8aa3b, v115
	v_exp_f32_e32 v129, v129
	v_exp_f32_e32 v131, v131
	v_exp_f32_e32 v134, v134
	v_exp_f32_e32 v139, v139
	v_add_f32_e32 v129, 1.0, v129
	v_add_f32_e32 v131, 1.0, v131
	v_add_f32_e32 v134, 1.0, v134
	v_add_f32_e32 v139, 1.0, v139
	v_rcp_f32_e32 v129, v129
	v_rcp_f32_e32 v131, v131
	v_rcp_f32_e32 v134, v134
	v_rcp_f32_e32 v139, v139
	v_ashrrev_i32_e32 v163, 31, v162
	v_lshlrev_b64 v[170:171], 11, v[162:163]
	v_lshl_add_u64 v[170:171], v[168:169], 0, v[170:171]
	v_mul_f32_e32 v129, v127, v129
	v_mul_f32_e32 v131, v123, v131
	v_mul_f32_e32 v134, v119, v134
	v_mul_f32_e32 v139, v115, v139
	v_cvt_pk_bf16_f32 v172, v129, v131
	v_cvt_pk_bf16_f32 v173, v134, v139
	global_store_dwordx2 v[170:171], v[172:173], off nt
	v_mul_f32_e32 v129, 0xbfb8aa3b, v108
	v_mul_f32_e32 v131, 0xbfb8aa3b, v104
	v_mul_f32_e32 v134, 0xbfb8aa3b, v100
	v_mul_f32_e32 v139, 0xbfb8aa3b, v96
	v_exp_f32_e32 v129, v129
	v_exp_f32_e32 v131, v131
	v_exp_f32_e32 v134, v134
	v_exp_f32_e32 v139, v139
	v_add_f32_e32 v129, 1.0, v129
	v_add_f32_e32 v131, 1.0, v131
	v_add_f32_e32 v134, 1.0, v134
	v_add_f32_e32 v139, 1.0, v139
	v_rcp_f32_e32 v129, v129
	v_rcp_f32_e32 v131, v131
	v_rcp_f32_e32 v134, v134
	v_rcp_f32_e32 v139, v139
	v_ashrrev_i32_e32 v161, 31, v160
	v_lshlrev_b64 v[170:171], 11, v[160:161]
	v_lshl_add_u64 v[170:171], v[168:169], 0, v[170:171]
	v_mul_f32_e32 v129, v108, v129
	v_mul_f32_e32 v131, v104, v131
	v_mul_f32_e32 v134, v100, v134
	v_mul_f32_e32 v139, v96, v139
	v_cvt_pk_bf16_f32 v172, v129, v131
	v_cvt_pk_bf16_f32 v173, v134, v139
	global_store_dwordx2 v[170:171], v[172:173], off nt
	v_mul_f32_e32 v129, 0xbfb8aa3b, v109
	v_mul_f32_e32 v131, 0xbfb8aa3b, v105
	v_mul_f32_e32 v134, 0xbfb8aa3b, v101
	v_mul_f32_e32 v139, 0xbfb8aa3b, v97
	v_exp_f32_e32 v129, v129
	v_exp_f32_e32 v131, v131
	v_exp_f32_e32 v134, v134
	v_exp_f32_e32 v139, v139
	v_add_f32_e32 v129, 1.0, v129
	v_add_f32_e32 v131, 1.0, v131
	v_add_f32_e32 v134, 1.0, v134
	v_add_f32_e32 v139, 1.0, v139
	v_rcp_f32_e32 v129, v129
	v_rcp_f32_e32 v131, v131
	v_rcp_f32_e32 v134, v134
	v_rcp_f32_e32 v139, v139
	v_ashrrev_i32_e32 v159, 31, v158
	v_lshlrev_b64 v[170:171], 11, v[158:159]
	v_lshl_add_u64 v[170:171], v[168:169], 0, v[170:171]
	v_mul_f32_e32 v129, v109, v129
	v_mul_f32_e32 v131, v105, v131
	v_mul_f32_e32 v134, v101, v134
	v_mul_f32_e32 v139, v97, v139
	v_cvt_pk_bf16_f32 v172, v129, v131
	v_cvt_pk_bf16_f32 v173, v134, v139
	global_store_dwordx2 v[170:171], v[172:173], off nt
	v_mul_f32_e32 v129, 0xbfb8aa3b, v110
	v_mul_f32_e32 v131, 0xbfb8aa3b, v106
	v_mul_f32_e32 v134, 0xbfb8aa3b, v102
	v_mul_f32_e32 v139, 0xbfb8aa3b, v98
	v_exp_f32_e32 v129, v129
	v_exp_f32_e32 v131, v131
	v_exp_f32_e32 v134, v134
	v_exp_f32_e32 v139, v139
	v_add_f32_e32 v129, 1.0, v129
	v_add_f32_e32 v131, 1.0, v131
	v_add_f32_e32 v134, 1.0, v134
	v_add_f32_e32 v139, 1.0, v139
	v_rcp_f32_e32 v129, v129
	v_rcp_f32_e32 v131, v131
	v_rcp_f32_e32 v134, v134
	v_rcp_f32_e32 v139, v139
	v_ashrrev_i32_e32 v157, 31, v156
	v_lshlrev_b64 v[170:171], 11, v[156:157]
	v_lshl_add_u64 v[170:171], v[168:169], 0, v[170:171]
	v_mul_f32_e32 v129, v110, v129
	v_mul_f32_e32 v131, v106, v131
	v_mul_f32_e32 v134, v102, v134
	v_mul_f32_e32 v139, v98, v139
	v_cvt_pk_bf16_f32 v172, v129, v131
	v_cvt_pk_bf16_f32 v173, v134, v139
	global_store_dwordx2 v[170:171], v[172:173], off nt
	v_mul_f32_e32 v129, 0xbfb8aa3b, v111
	v_mul_f32_e32 v131, 0xbfb8aa3b, v107
	v_mul_f32_e32 v134, 0xbfb8aa3b, v103
	v_mul_f32_e32 v139, 0xbfb8aa3b, v99
	v_exp_f32_e32 v129, v129
	v_exp_f32_e32 v131, v131
	v_exp_f32_e32 v134, v134
	v_exp_f32_e32 v139, v139
	v_add_f32_e32 v129, 1.0, v129
	v_add_f32_e32 v131, 1.0, v131
	v_add_f32_e32 v134, 1.0, v134
	v_add_f32_e32 v139, 1.0, v139
	v_rcp_f32_e32 v129, v129
	v_rcp_f32_e32 v131, v131
	v_rcp_f32_e32 v134, v134
	v_rcp_f32_e32 v139, v139
	v_ashrrev_i32_e32 v155, 31, v154
	v_lshlrev_b64 v[170:171], 11, v[154:155]
	v_lshl_add_u64 v[170:171], v[168:169], 0, v[170:171]
	v_mul_f32_e32 v129, v111, v129
	v_mul_f32_e32 v131, v107, v131
	v_mul_f32_e32 v134, v103, v134
	v_mul_f32_e32 v139, v99, v139
	v_cvt_pk_bf16_f32 v172, v129, v131
	v_cvt_pk_bf16_f32 v173, v134, v139
	global_store_dwordx2 v[170:171], v[172:173], off nt
	v_mul_f32_e32 v129, 0xbfb8aa3b, v92
	v_mul_f32_e32 v131, 0xbfb8aa3b, v88
	v_mul_f32_e32 v134, 0xbfb8aa3b, v84
	v_mul_f32_e32 v139, 0xbfb8aa3b, v80
	v_exp_f32_e32 v129, v129
	v_exp_f32_e32 v131, v131
	v_exp_f32_e32 v134, v134
	v_exp_f32_e32 v139, v139
	v_add_f32_e32 v129, 1.0, v129
	v_add_f32_e32 v131, 1.0, v131
	v_add_f32_e32 v134, 1.0, v134
	v_add_f32_e32 v139, 1.0, v139
	v_rcp_f32_e32 v129, v129
	v_rcp_f32_e32 v131, v131
	v_rcp_f32_e32 v134, v134
	v_rcp_f32_e32 v139, v139
	v_ashrrev_i32_e32 v153, 31, v152
	v_lshlrev_b64 v[170:171], 11, v[152:153]
	v_lshl_add_u64 v[170:171], v[168:169], 0, v[170:171]
	v_mul_f32_e32 v129, v92, v129
	v_mul_f32_e32 v131, v88, v131
	v_mul_f32_e32 v134, v84, v134
	v_mul_f32_e32 v139, v80, v139
	v_cvt_pk_bf16_f32 v172, v129, v131
	v_cvt_pk_bf16_f32 v173, v134, v139
	global_store_dwordx2 v[170:171], v[172:173], off nt
	v_mul_f32_e32 v129, 0xbfb8aa3b, v93
	v_mul_f32_e32 v131, 0xbfb8aa3b, v89
	v_mul_f32_e32 v134, 0xbfb8aa3b, v85
	v_mul_f32_e32 v139, 0xbfb8aa3b, v81
	v_exp_f32_e32 v129, v129
	v_exp_f32_e32 v131, v131
	v_exp_f32_e32 v134, v134
	v_exp_f32_e32 v139, v139
	v_add_f32_e32 v129, 1.0, v129
	v_add_f32_e32 v131, 1.0, v131
	v_add_f32_e32 v134, 1.0, v134
	v_add_f32_e32 v139, 1.0, v139
	v_rcp_f32_e32 v129, v129
	v_rcp_f32_e32 v131, v131
	v_rcp_f32_e32 v134, v134
	v_rcp_f32_e32 v139, v139
	v_ashrrev_i32_e32 v151, 31, v150
	v_lshlrev_b64 v[170:171], 11, v[150:151]
	v_lshl_add_u64 v[170:171], v[168:169], 0, v[170:171]
	v_mul_f32_e32 v129, v93, v129
	v_mul_f32_e32 v131, v89, v131
	v_mul_f32_e32 v134, v85, v134
	v_mul_f32_e32 v139, v81, v139
	v_cvt_pk_bf16_f32 v172, v129, v131
	v_cvt_pk_bf16_f32 v173, v134, v139
	global_store_dwordx2 v[170:171], v[172:173], off nt
	v_mul_f32_e32 v129, 0xbfb8aa3b, v94
	v_mul_f32_e32 v131, 0xbfb8aa3b, v90
	v_mul_f32_e32 v134, 0xbfb8aa3b, v86
	v_mul_f32_e32 v139, 0xbfb8aa3b, v82
	v_exp_f32_e32 v129, v129
	v_exp_f32_e32 v131, v131
	v_exp_f32_e32 v134, v134
	v_exp_f32_e32 v139, v139
	v_add_f32_e32 v129, 1.0, v129
	v_add_f32_e32 v131, 1.0, v131
	v_add_f32_e32 v134, 1.0, v134
	v_add_f32_e32 v139, 1.0, v139
	v_rcp_f32_e32 v129, v129
	v_rcp_f32_e32 v131, v131
	v_rcp_f32_e32 v134, v134
	v_rcp_f32_e32 v139, v139
	v_ashrrev_i32_e32 v149, 31, v148
	v_lshlrev_b64 v[170:171], 11, v[148:149]
	v_lshl_add_u64 v[170:171], v[168:169], 0, v[170:171]
	v_mul_f32_e32 v129, v94, v129
	v_mul_f32_e32 v131, v90, v131
	v_mul_f32_e32 v134, v86, v134
	v_mul_f32_e32 v139, v82, v139
	v_cvt_pk_bf16_f32 v172, v129, v131
	v_cvt_pk_bf16_f32 v173, v134, v139
	global_store_dwordx2 v[170:171], v[172:173], off nt
	v_mul_f32_e32 v129, 0xbfb8aa3b, v95
	v_mul_f32_e32 v131, 0xbfb8aa3b, v91
	v_mul_f32_e32 v134, 0xbfb8aa3b, v87
	v_mul_f32_e32 v139, 0xbfb8aa3b, v83
	v_exp_f32_e32 v129, v129
	v_exp_f32_e32 v131, v131
	v_exp_f32_e32 v134, v134
	v_exp_f32_e32 v139, v139
	v_add_f32_e32 v129, 1.0, v129
	v_add_f32_e32 v131, 1.0, v131
	v_add_f32_e32 v134, 1.0, v134
	v_add_f32_e32 v139, 1.0, v139
	v_rcp_f32_e32 v129, v129
	v_rcp_f32_e32 v131, v131
	v_rcp_f32_e32 v134, v134
	v_rcp_f32_e32 v139, v139
	v_ashrrev_i32_e32 v147, 31, v146
	v_lshlrev_b64 v[170:171], 11, v[146:147]
	v_lshl_add_u64 v[170:171], v[168:169], 0, v[170:171]
	v_mul_f32_e32 v129, v95, v129
	v_mul_f32_e32 v131, v91, v131
	v_mul_f32_e32 v134, v87, v134
	v_mul_f32_e32 v139, v83, v139
	v_cvt_pk_bf16_f32 v172, v129, v131
	v_cvt_pk_bf16_f32 v173, v134, v139
	global_store_dwordx2 v[170:171], v[172:173], off nt
	v_mul_f32_e32 v129, 0xbfb8aa3b, v76
	v_mul_f32_e32 v131, 0xbfb8aa3b, v72
	v_mul_f32_e32 v134, 0xbfb8aa3b, v68
	v_mul_f32_e32 v139, 0xbfb8aa3b, v64
	v_exp_f32_e32 v129, v129
	v_exp_f32_e32 v131, v131
	v_exp_f32_e32 v134, v134
	v_exp_f32_e32 v139, v139
	v_add_f32_e32 v129, 1.0, v129
	v_add_f32_e32 v131, 1.0, v131
	v_add_f32_e32 v134, 1.0, v134
	v_add_f32_e32 v139, 1.0, v139
	v_rcp_f32_e32 v129, v129
	v_rcp_f32_e32 v131, v131
	v_rcp_f32_e32 v134, v134
	v_rcp_f32_e32 v139, v139
	v_ashrrev_i32_e32 v145, 31, v144
	v_lshlrev_b64 v[170:171], 11, v[144:145]
	v_lshl_add_u64 v[170:171], v[168:169], 0, v[170:171]
	v_mul_f32_e32 v129, v76, v129
	v_mul_f32_e32 v131, v72, v131
	v_mul_f32_e32 v134, v68, v134
	v_mul_f32_e32 v139, v64, v139
	v_cvt_pk_bf16_f32 v172, v129, v131
	v_cvt_pk_bf16_f32 v173, v134, v139
	global_store_dwordx2 v[170:171], v[172:173], off nt
	v_mul_f32_e32 v129, 0xbfb8aa3b, v77
	v_mul_f32_e32 v131, 0xbfb8aa3b, v73
	v_mul_f32_e32 v134, 0xbfb8aa3b, v69
	v_mul_f32_e32 v139, 0xbfb8aa3b, v65
	v_exp_f32_e32 v129, v129
	v_exp_f32_e32 v131, v131
	v_exp_f32_e32 v134, v134
	v_exp_f32_e32 v139, v139
	v_add_f32_e32 v129, 1.0, v129
	v_add_f32_e32 v131, 1.0, v131
	v_add_f32_e32 v134, 1.0, v134
	v_add_f32_e32 v139, 1.0, v139
	v_rcp_f32_e32 v129, v129
	v_rcp_f32_e32 v131, v131
	v_rcp_f32_e32 v134, v134
	v_rcp_f32_e32 v139, v139
	v_ashrrev_i32_e32 v143, 31, v142
	v_lshlrev_b64 v[170:171], 11, v[142:143]
	v_lshl_add_u64 v[170:171], v[168:169], 0, v[170:171]
	v_mul_f32_e32 v129, v77, v129
	v_mul_f32_e32 v131, v73, v131
	v_mul_f32_e32 v134, v69, v134
	v_mul_f32_e32 v139, v65, v139
	v_cvt_pk_bf16_f32 v172, v129, v131
	v_cvt_pk_bf16_f32 v173, v134, v139
	global_store_dwordx2 v[170:171], v[172:173], off nt
	v_mul_f32_e32 v129, 0xbfb8aa3b, v78
	v_mul_f32_e32 v131, 0xbfb8aa3b, v74
	v_mul_f32_e32 v134, 0xbfb8aa3b, v70
	v_mul_f32_e32 v139, 0xbfb8aa3b, v66
	v_exp_f32_e32 v129, v129
	v_exp_f32_e32 v131, v131
	v_exp_f32_e32 v134, v134
	v_exp_f32_e32 v139, v139
	v_add_f32_e32 v129, 1.0, v129
	v_add_f32_e32 v131, 1.0, v131
	v_add_f32_e32 v134, 1.0, v134
	v_add_f32_e32 v139, 1.0, v139
	v_rcp_f32_e32 v129, v129
	v_rcp_f32_e32 v131, v131
	v_rcp_f32_e32 v134, v134
	v_rcp_f32_e32 v139, v139
	v_ashrrev_i32_e32 v141, 31, v140
	v_lshlrev_b64 v[170:171], 11, v[140:141]
	v_lshl_add_u64 v[170:171], v[168:169], 0, v[170:171]
	v_mul_f32_e32 v129, v78, v129
	v_mul_f32_e32 v131, v74, v131
	v_mul_f32_e32 v134, v70, v134
	v_mul_f32_e32 v139, v66, v139
	v_cvt_pk_bf16_f32 v172, v129, v131
	v_cvt_pk_bf16_f32 v173, v134, v139
	global_store_dwordx2 v[170:171], v[172:173], off nt
	v_ashrrev_i32_e32 v139, 31, v138
	v_lshlrev_b64 v[170:171], 11, v[138:139]
	v_mul_f32_e32 v129, 0xbfb8aa3b, v79
	v_mul_f32_e32 v131, 0xbfb8aa3b, v75
	v_mul_f32_e32 v134, 0xbfb8aa3b, v71
	v_mul_f32_e32 v139, 0xbfb8aa3b, v67
	v_exp_f32_e32 v129, v129
	v_exp_f32_e32 v131, v131
	v_exp_f32_e32 v134, v134
	v_exp_f32_e32 v139, v139
	v_add_f32_e32 v129, 1.0, v129
	v_add_f32_e32 v131, 1.0, v131
	v_add_f32_e32 v134, 1.0, v134
	v_add_f32_e32 v139, 1.0, v139
	v_rcp_f32_e32 v129, v129
	v_rcp_f32_e32 v131, v131
	v_rcp_f32_e32 v134, v134
	v_rcp_f32_e32 v139, v139
	v_lshl_add_u64 v[170:171], v[168:169], 0, v[170:171]
	v_mul_f32_e32 v129, v79, v129
	v_mul_f32_e32 v131, v75, v131
	v_mul_f32_e32 v134, v71, v134
	v_mul_f32_e32 v139, v67, v139
	v_cvt_pk_bf16_f32 v172, v129, v131
	v_cvt_pk_bf16_f32 v173, v134, v139
	global_store_dwordx2 v[170:171], v[172:173], off nt
	v_ashrrev_i32_e32 v131, 31, v130
	v_lshlrev_b64 v[170:171], 11, v[130:131]
	v_mul_f32_e32 v129, 0xbfb8aa3b, v60
	v_mul_f32_e32 v131, 0xbfb8aa3b, v56
	v_mul_f32_e32 v134, 0xbfb8aa3b, v52
	v_mul_f32_e32 v139, 0xbfb8aa3b, v48
	v_exp_f32_e32 v129, v129
	v_exp_f32_e32 v131, v131
	v_exp_f32_e32 v134, v134
	v_exp_f32_e32 v139, v139
	v_add_f32_e32 v129, 1.0, v129
	v_add_f32_e32 v131, 1.0, v131
	v_add_f32_e32 v134, 1.0, v134
	v_add_f32_e32 v139, 1.0, v139
	v_rcp_f32_e32 v129, v129
	v_rcp_f32_e32 v131, v131
	v_rcp_f32_e32 v134, v134
	v_rcp_f32_e32 v139, v139
	v_lshl_add_u64 v[170:171], v[168:169], 0, v[170:171]
	v_mul_f32_e32 v129, v60, v129
	v_mul_f32_e32 v131, v56, v131
	v_mul_f32_e32 v134, v52, v134
	v_mul_f32_e32 v139, v48, v139
	v_cvt_pk_bf16_f32 v172, v129, v131
	v_cvt_pk_bf16_f32 v173, v134, v139
	global_store_dwordx2 v[170:171], v[172:173], off nt
	v_mul_f32_e32 v129, 0xbfb8aa3b, v61
	v_mul_f32_e32 v131, 0xbfb8aa3b, v57
	v_mul_f32_e32 v134, 0xbfb8aa3b, v53
	v_mul_f32_e32 v139, 0xbfb8aa3b, v49
	v_exp_f32_e32 v129, v129
	v_exp_f32_e32 v131, v131
	v_exp_f32_e32 v134, v134
	v_exp_f32_e32 v139, v139
	v_add_f32_e32 v129, 1.0, v129
	v_add_f32_e32 v131, 1.0, v131
	v_add_f32_e32 v134, 1.0, v134
	v_add_f32_e32 v139, 1.0, v139
	v_add_u32_e32 v170, 0x41, v128
	v_rcp_f32_e32 v129, v129
	v_rcp_f32_e32 v131, v131
	v_rcp_f32_e32 v134, v134
	v_rcp_f32_e32 v139, v139
	v_ashrrev_i32_e32 v171, 31, v170
	v_lshlrev_b64 v[170:171], 11, v[170:171]
	v_lshl_add_u64 v[170:171], v[168:169], 0, v[170:171]
	v_mul_f32_e32 v129, v61, v129
	v_mul_f32_e32 v131, v57, v131
	v_mul_f32_e32 v134, v53, v134
	v_mul_f32_e32 v139, v49, v139
	v_cvt_pk_bf16_f32 v172, v129, v131
	v_cvt_pk_bf16_f32 v173, v134, v139
	global_store_dwordx2 v[170:171], v[172:173], off nt
	v_mul_f32_e32 v129, 0xbfb8aa3b, v62
	v_mul_f32_e32 v131, 0xbfb8aa3b, v58
	v_mul_f32_e32 v134, 0xbfb8aa3b, v54
	v_mul_f32_e32 v139, 0xbfb8aa3b, v50
	v_exp_f32_e32 v129, v129
	v_exp_f32_e32 v131, v131
	v_exp_f32_e32 v134, v134
	v_exp_f32_e32 v139, v139
	v_add_f32_e32 v129, 1.0, v129
	v_add_f32_e32 v131, 1.0, v131
	v_add_f32_e32 v134, 1.0, v134
	v_add_f32_e32 v139, 1.0, v139
	v_add_u32_e32 v170, 0x42, v128
	v_rcp_f32_e32 v129, v129
	v_rcp_f32_e32 v131, v131
	v_rcp_f32_e32 v134, v134
	v_rcp_f32_e32 v139, v139
	v_ashrrev_i32_e32 v171, 31, v170
	v_lshlrev_b64 v[170:171], 11, v[170:171]
	v_lshl_add_u64 v[170:171], v[168:169], 0, v[170:171]
	v_mul_f32_e32 v129, v62, v129
	v_mul_f32_e32 v131, v58, v131
	v_mul_f32_e32 v134, v54, v134
	v_mul_f32_e32 v139, v50, v139
	v_cvt_pk_bf16_f32 v172, v129, v131
	v_cvt_pk_bf16_f32 v173, v134, v139
	global_store_dwordx2 v[170:171], v[172:173], off nt
	v_mul_f32_e32 v129, 0xbfb8aa3b, v63
	v_mul_f32_e32 v131, 0xbfb8aa3b, v59
	v_mul_f32_e32 v134, 0xbfb8aa3b, v55
	v_mul_f32_e32 v139, 0xbfb8aa3b, v51
	v_exp_f32_e32 v129, v129
	v_exp_f32_e32 v131, v131
	v_exp_f32_e32 v134, v134
	v_exp_f32_e32 v139, v139
	v_add_f32_e32 v129, 1.0, v129
	v_add_f32_e32 v131, 1.0, v131
	v_add_f32_e32 v134, 1.0, v134
	v_add_f32_e32 v139, 1.0, v139
	v_add_u32_e32 v170, 0x43, v128
	v_rcp_f32_e32 v129, v129
	v_rcp_f32_e32 v131, v131
	v_rcp_f32_e32 v134, v134
	v_rcp_f32_e32 v139, v139
	v_ashrrev_i32_e32 v171, 31, v170
	v_lshlrev_b64 v[170:171], 11, v[170:171]
	v_lshl_add_u64 v[170:171], v[168:169], 0, v[170:171]
	v_mul_f32_e32 v129, v63, v129
	v_mul_f32_e32 v131, v59, v131
	v_mul_f32_e32 v134, v55, v134
	v_mul_f32_e32 v139, v51, v139
	v_cvt_pk_bf16_f32 v172, v129, v131
	v_cvt_pk_bf16_f32 v173, v134, v139
	global_store_dwordx2 v[170:171], v[172:173], off nt
	v_add_u32_e32 v170, 0x50, v128
	v_mul_f32_e32 v129, 0xbfb8aa3b, v44
	v_mul_f32_e32 v131, 0xbfb8aa3b, v40
	v_mul_f32_e32 v134, 0xbfb8aa3b, v36
	v_mul_f32_e32 v139, 0xbfb8aa3b, v32
	v_exp_f32_e32 v129, v129
	v_exp_f32_e32 v131, v131
	v_exp_f32_e32 v134, v134
	v_exp_f32_e32 v139, v139
	v_add_f32_e32 v129, 1.0, v129
	v_add_f32_e32 v131, 1.0, v131
	v_add_f32_e32 v134, 1.0, v134
	v_add_f32_e32 v139, 1.0, v139
	v_rcp_f32_e32 v129, v129
	v_rcp_f32_e32 v131, v131
	v_rcp_f32_e32 v134, v134
	v_rcp_f32_e32 v139, v139
	v_ashrrev_i32_e32 v171, 31, v170
	v_lshlrev_b64 v[170:171], 11, v[170:171]
	v_lshl_add_u64 v[170:171], v[168:169], 0, v[170:171]
	v_mul_f32_e32 v129, v44, v129
	v_mul_f32_e32 v131, v40, v131
	v_mul_f32_e32 v134, v36, v134
	v_mul_f32_e32 v139, v32, v139
	v_cvt_pk_bf16_f32 v172, v129, v131
	v_cvt_pk_bf16_f32 v173, v134, v139
	global_store_dwordx2 v[170:171], v[172:173], off nt
	v_mul_f32_e32 v129, 0xbfb8aa3b, v45
	v_mul_f32_e32 v131, 0xbfb8aa3b, v41
	v_mul_f32_e32 v134, 0xbfb8aa3b, v37
	v_mul_f32_e32 v139, 0xbfb8aa3b, v33
	v_exp_f32_e32 v129, v129
	v_exp_f32_e32 v131, v131
	v_exp_f32_e32 v134, v134
	v_exp_f32_e32 v139, v139
	v_add_f32_e32 v129, 1.0, v129
	v_add_f32_e32 v131, 1.0, v131
	v_add_f32_e32 v134, 1.0, v134
	v_add_f32_e32 v139, 1.0, v139
	v_add_u32_e32 v170, 0x51, v128
	v_rcp_f32_e32 v129, v129
	v_rcp_f32_e32 v131, v131
	v_rcp_f32_e32 v134, v134
	v_rcp_f32_e32 v139, v139
	v_ashrrev_i32_e32 v171, 31, v170
	v_lshlrev_b64 v[170:171], 11, v[170:171]
	v_lshl_add_u64 v[170:171], v[168:169], 0, v[170:171]
	v_mul_f32_e32 v129, v45, v129
	v_mul_f32_e32 v131, v41, v131
	v_mul_f32_e32 v134, v37, v134
	v_mul_f32_e32 v139, v33, v139
	v_cvt_pk_bf16_f32 v172, v129, v131
	v_cvt_pk_bf16_f32 v173, v134, v139
	global_store_dwordx2 v[170:171], v[172:173], off nt
	v_mul_f32_e32 v129, 0xbfb8aa3b, v46
	v_mul_f32_e32 v131, 0xbfb8aa3b, v42
	v_mul_f32_e32 v134, 0xbfb8aa3b, v38
	v_mul_f32_e32 v139, 0xbfb8aa3b, v34
	v_exp_f32_e32 v129, v129
	v_exp_f32_e32 v131, v131
	v_exp_f32_e32 v134, v134
	v_exp_f32_e32 v139, v139
	v_add_f32_e32 v129, 1.0, v129
	v_add_f32_e32 v131, 1.0, v131
	v_add_f32_e32 v134, 1.0, v134
	v_add_f32_e32 v139, 1.0, v139
	v_add_u32_e32 v170, 0x52, v128
	v_rcp_f32_e32 v129, v129
	v_rcp_f32_e32 v131, v131
	v_rcp_f32_e32 v134, v134
	v_rcp_f32_e32 v139, v139
	v_ashrrev_i32_e32 v171, 31, v170
	v_lshlrev_b64 v[170:171], 11, v[170:171]
	v_lshl_add_u64 v[170:171], v[168:169], 0, v[170:171]
	v_mul_f32_e32 v129, v46, v129
	v_mul_f32_e32 v131, v42, v131
	v_mul_f32_e32 v134, v38, v134
	v_mul_f32_e32 v139, v34, v139
	v_cvt_pk_bf16_f32 v172, v129, v131
	v_cvt_pk_bf16_f32 v173, v134, v139
	global_store_dwordx2 v[170:171], v[172:173], off nt
	v_mul_f32_e32 v129, 0xbfb8aa3b, v47
	v_mul_f32_e32 v131, 0xbfb8aa3b, v43
	v_mul_f32_e32 v134, 0xbfb8aa3b, v39
	v_mul_f32_e32 v139, 0xbfb8aa3b, v35
	v_exp_f32_e32 v129, v129
	v_exp_f32_e32 v131, v131
	v_exp_f32_e32 v134, v134
	v_exp_f32_e32 v139, v139
	v_add_f32_e32 v129, 1.0, v129
	v_add_f32_e32 v131, 1.0, v131
	v_add_f32_e32 v134, 1.0, v134
	v_add_f32_e32 v139, 1.0, v139
	v_add_u32_e32 v170, 0x53, v128
	v_rcp_f32_e32 v129, v129
	v_rcp_f32_e32 v131, v131
	v_rcp_f32_e32 v134, v134
	v_rcp_f32_e32 v139, v139
	v_ashrrev_i32_e32 v171, 31, v170
	v_lshlrev_b64 v[170:171], 11, v[170:171]
	v_lshl_add_u64 v[170:171], v[168:169], 0, v[170:171]
	v_mul_f32_e32 v129, v47, v129
	v_mul_f32_e32 v131, v43, v131
	v_mul_f32_e32 v134, v39, v134
	v_mul_f32_e32 v139, v35, v139
	v_cvt_pk_bf16_f32 v172, v129, v131
	v_cvt_pk_bf16_f32 v173, v134, v139
	global_store_dwordx2 v[170:171], v[172:173], off nt
	v_add_u32_e32 v170, 0x60, v128
	v_mul_f32_e32 v129, 0xbfb8aa3b, v28
	v_mul_f32_e32 v131, 0xbfb8aa3b, v24
	v_mul_f32_e32 v134, 0xbfb8aa3b, v20
	v_mul_f32_e32 v139, 0xbfb8aa3b, v16
	v_exp_f32_e32 v129, v129
	v_exp_f32_e32 v131, v131
	v_exp_f32_e32 v134, v134
	v_exp_f32_e32 v139, v139
	v_add_f32_e32 v129, 1.0, v129
	v_add_f32_e32 v131, 1.0, v131
	v_add_f32_e32 v134, 1.0, v134
	v_add_f32_e32 v139, 1.0, v139
	v_rcp_f32_e32 v129, v129
	v_rcp_f32_e32 v131, v131
	v_rcp_f32_e32 v134, v134
	v_rcp_f32_e32 v139, v139
	v_ashrrev_i32_e32 v171, 31, v170
	v_lshlrev_b64 v[170:171], 11, v[170:171]
	v_lshl_add_u64 v[170:171], v[168:169], 0, v[170:171]
	v_mul_f32_e32 v129, v28, v129
	v_mul_f32_e32 v131, v24, v131
	v_mul_f32_e32 v134, v20, v134
	v_mul_f32_e32 v139, v16, v139
	v_cvt_pk_bf16_f32 v172, v129, v131
	v_cvt_pk_bf16_f32 v173, v134, v139
	global_store_dwordx2 v[170:171], v[172:173], off nt
	v_mul_f32_e32 v129, 0xbfb8aa3b, v29
	v_mul_f32_e32 v131, 0xbfb8aa3b, v25
	v_mul_f32_e32 v134, 0xbfb8aa3b, v21
	v_mul_f32_e32 v139, 0xbfb8aa3b, v17
	v_exp_f32_e32 v129, v129
	v_exp_f32_e32 v131, v131
	v_exp_f32_e32 v134, v134
	v_exp_f32_e32 v139, v139
	v_add_f32_e32 v129, 1.0, v129
	v_add_f32_e32 v131, 1.0, v131
	v_add_f32_e32 v134, 1.0, v134
	v_add_f32_e32 v139, 1.0, v139
	v_add_u32_e32 v170, 0x61, v128
	v_rcp_f32_e32 v129, v129
	v_rcp_f32_e32 v131, v131
	v_rcp_f32_e32 v134, v134
	v_rcp_f32_e32 v139, v139
	v_ashrrev_i32_e32 v171, 31, v170
	v_lshlrev_b64 v[170:171], 11, v[170:171]
	v_lshl_add_u64 v[170:171], v[168:169], 0, v[170:171]
	v_mul_f32_e32 v129, v29, v129
	v_mul_f32_e32 v131, v25, v131
	v_mul_f32_e32 v134, v21, v134
	v_mul_f32_e32 v139, v17, v139
	v_cvt_pk_bf16_f32 v172, v129, v131
	v_cvt_pk_bf16_f32 v173, v134, v139
	global_store_dwordx2 v[170:171], v[172:173], off nt
	v_mul_f32_e32 v129, 0xbfb8aa3b, v30
	v_mul_f32_e32 v131, 0xbfb8aa3b, v26
	v_mul_f32_e32 v134, 0xbfb8aa3b, v22
	v_mul_f32_e32 v139, 0xbfb8aa3b, v18
	v_exp_f32_e32 v129, v129
	v_exp_f32_e32 v131, v131
	v_exp_f32_e32 v134, v134
	v_exp_f32_e32 v139, v139
	v_add_f32_e32 v129, 1.0, v129
	v_add_f32_e32 v131, 1.0, v131
	v_add_f32_e32 v134, 1.0, v134
	v_add_f32_e32 v139, 1.0, v139
	v_add_u32_e32 v170, 0x62, v128
	v_rcp_f32_e32 v129, v129
	v_rcp_f32_e32 v131, v131
	v_rcp_f32_e32 v134, v134
	v_rcp_f32_e32 v139, v139
	v_ashrrev_i32_e32 v171, 31, v170
	v_lshlrev_b64 v[170:171], 11, v[170:171]
	v_lshl_add_u64 v[170:171], v[168:169], 0, v[170:171]
	v_mul_f32_e32 v129, v30, v129
	v_mul_f32_e32 v131, v26, v131
	v_mul_f32_e32 v134, v22, v134
	v_mul_f32_e32 v139, v18, v139
	v_cvt_pk_bf16_f32 v172, v129, v131
	v_cvt_pk_bf16_f32 v173, v134, v139
	global_store_dwordx2 v[170:171], v[172:173], off nt
	v_mul_f32_e32 v129, 0xbfb8aa3b, v31
	v_mul_f32_e32 v131, 0xbfb8aa3b, v27
	v_mul_f32_e32 v134, 0xbfb8aa3b, v23
	v_mul_f32_e32 v139, 0xbfb8aa3b, v19
	v_exp_f32_e32 v129, v129
	v_exp_f32_e32 v131, v131
	v_exp_f32_e32 v134, v134
	v_exp_f32_e32 v139, v139
	v_add_f32_e32 v129, 1.0, v129
	v_add_f32_e32 v131, 1.0, v131
	v_add_f32_e32 v134, 1.0, v134
	v_add_f32_e32 v139, 1.0, v139
	v_add_u32_e32 v170, 0x63, v128
	v_rcp_f32_e32 v129, v129
	v_rcp_f32_e32 v131, v131
	v_rcp_f32_e32 v134, v134
	v_rcp_f32_e32 v139, v139
	v_ashrrev_i32_e32 v171, 31, v170
	v_lshlrev_b64 v[170:171], 11, v[170:171]
	v_lshl_add_u64 v[170:171], v[168:169], 0, v[170:171]
	v_mul_f32_e32 v129, v31, v129
	v_mul_f32_e32 v131, v27, v131
	v_mul_f32_e32 v134, v23, v134
	v_mul_f32_e32 v139, v19, v139
	v_cvt_pk_bf16_f32 v172, v129, v131
	v_cvt_pk_bf16_f32 v173, v134, v139
	global_store_dwordx2 v[170:171], v[172:173], off nt
	v_add_u32_e32 v170, 0x70, v128
	v_mul_f32_e32 v129, 0xbfb8aa3b, v12
	v_mul_f32_e32 v131, 0xbfb8aa3b, v8
	v_mul_f32_e32 v134, 0xbfb8aa3b, v4
	v_mul_f32_e32 v139, 0xbfb8aa3b, v0
	v_exp_f32_e32 v129, v129
	v_exp_f32_e32 v131, v131
	v_exp_f32_e32 v134, v134
	v_exp_f32_e32 v139, v139
	v_add_f32_e32 v129, 1.0, v129
	v_add_f32_e32 v131, 1.0, v131
	v_add_f32_e32 v134, 1.0, v134
	v_add_f32_e32 v139, 1.0, v139
	v_rcp_f32_e32 v129, v129
	v_rcp_f32_e32 v131, v131
	v_rcp_f32_e32 v134, v134
	v_rcp_f32_e32 v139, v139
	v_ashrrev_i32_e32 v171, 31, v170
	v_lshlrev_b64 v[170:171], 11, v[170:171]
	v_lshl_add_u64 v[170:171], v[168:169], 0, v[170:171]
	v_mul_f32_e32 v129, v12, v129
	v_mul_f32_e32 v131, v8, v131
	v_mul_f32_e32 v134, v4, v134
	v_mul_f32_e32 v139, v0, v139
	v_cvt_pk_bf16_f32 v172, v129, v131
	v_cvt_pk_bf16_f32 v173, v134, v139
	global_store_dwordx2 v[170:171], v[172:173], off nt
	v_mul_f32_e32 v129, 0xbfb8aa3b, v13
	v_mul_f32_e32 v131, 0xbfb8aa3b, v9
	v_mul_f32_e32 v134, 0xbfb8aa3b, v5
	v_mul_f32_e32 v139, 0xbfb8aa3b, v1
	v_exp_f32_e32 v129, v129
	v_exp_f32_e32 v131, v131
	v_exp_f32_e32 v134, v134
	v_exp_f32_e32 v139, v139
	v_add_f32_e32 v129, 1.0, v129
	v_add_f32_e32 v131, 1.0, v131
	v_add_f32_e32 v134, 1.0, v134
	v_add_f32_e32 v139, 1.0, v139
	v_add_u32_e32 v170, 0x71, v128
	v_rcp_f32_e32 v129, v129
	v_rcp_f32_e32 v131, v131
	v_rcp_f32_e32 v134, v134
	v_rcp_f32_e32 v139, v139
	v_ashrrev_i32_e32 v171, 31, v170
	v_lshlrev_b64 v[170:171], 11, v[170:171]
	v_lshl_add_u64 v[170:171], v[168:169], 0, v[170:171]
	v_mul_f32_e32 v129, v13, v129
	v_mul_f32_e32 v131, v9, v131
	v_mul_f32_e32 v134, v5, v134
	v_mul_f32_e32 v139, v1, v139
	v_cvt_pk_bf16_f32 v172, v129, v131
	v_cvt_pk_bf16_f32 v173, v134, v139
	global_store_dwordx2 v[170:171], v[172:173], off nt
	v_mul_f32_e32 v129, 0xbfb8aa3b, v14
	v_mul_f32_e32 v131, 0xbfb8aa3b, v10
	v_mul_f32_e32 v134, 0xbfb8aa3b, v6
	v_mul_f32_e32 v139, 0xbfb8aa3b, v2
	v_exp_f32_e32 v129, v129
	v_exp_f32_e32 v131, v131
	v_exp_f32_e32 v134, v134
	v_exp_f32_e32 v139, v139
	v_add_f32_e32 v129, 1.0, v129
	v_add_f32_e32 v131, 1.0, v131
	v_add_f32_e32 v134, 1.0, v134
	v_add_f32_e32 v139, 1.0, v139
	v_add_u32_e32 v170, 0x72, v128
	v_rcp_f32_e32 v129, v129
	v_rcp_f32_e32 v131, v131
	v_rcp_f32_e32 v134, v134
	v_rcp_f32_e32 v139, v139
	v_ashrrev_i32_e32 v171, 31, v170
	v_lshlrev_b64 v[170:171], 11, v[170:171]
	v_lshl_add_u64 v[170:171], v[168:169], 0, v[170:171]
	v_mul_f32_e32 v129, v14, v129
	v_mul_f32_e32 v131, v10, v131
	v_mul_f32_e32 v134, v6, v134
	v_mul_f32_e32 v139, v2, v139
	v_cvt_pk_bf16_f32 v172, v129, v131
	v_cvt_pk_bf16_f32 v173, v134, v139
	global_store_dwordx2 v[170:171], v[172:173], off nt
	v_mul_f32_e32 v129, 0xbfb8aa3b, v15
	v_mul_f32_e32 v131, 0xbfb8aa3b, v11
	v_mul_f32_e32 v134, 0xbfb8aa3b, v7
	v_mul_f32_e32 v139, 0xbfb8aa3b, v3
	v_exp_f32_e32 v129, v129
	v_exp_f32_e32 v131, v131
	v_exp_f32_e32 v134, v134
	v_exp_f32_e32 v139, v139
	v_add_f32_e32 v129, 1.0, v129
	v_add_f32_e32 v131, 1.0, v131
	v_add_f32_e32 v134, 1.0, v134
	v_add_f32_e32 v139, 1.0, v139
	v_add_u32_e32 v170, 0x73, v128
	v_rcp_f32_e32 v129, v129
	v_rcp_f32_e32 v131, v131
	v_rcp_f32_e32 v134, v134
	v_rcp_f32_e32 v139, v139
	v_ashrrev_i32_e32 v171, 31, v170
	v_lshlrev_b64 v[170:171], 11, v[170:171]
	v_lshl_add_u64 v[168:169], v[168:169], 0, v[170:171]
	v_mul_f32_e32 v129, v15, v129
	v_mul_f32_e32 v131, v11, v131
	v_mul_f32_e32 v134, v7, v134
	v_mul_f32_e32 v139, v3, v139
	v_cvt_pk_bf16_f32 v170, v129, v131
	v_cvt_pk_bf16_f32 v171, v134, v139
	global_store_dwordx2 v[168:169], v[170:171], off nt

.LBB0_260:
	v_readlane_b32 s0, v253, 42
	v_readlane_b32 s1, v253, 43
	s_load_dwordx2 s[0:1], s[0:1], 0x130
	s_waitcnt lgkmcnt(0)
	v_lshl_add_u64 v[136:137], v[136:137], 1, s[0:1]
	v_mad_i64_i32 v[168:169], s[0:1], v128, s13, v[136:137]
	v_mul_f32_e32 v129, 0x3e38aa3b, v124
	v_mul_f32_e32 v131, 0x3e38aa3b, v120
	v_mul_f32_e32 v134, 0x3e38aa3b, v116
	v_mul_f32_e32 v139, 0x3e38aa3b, v112
	v_cvt_pk_bf16_f32 v170, v129, v131
	v_cvt_pk_bf16_f32 v171, v134, v139
	global_store_dwordx2 v[168:169], v[170:171], off nt
	v_mad_i64_i32 v[166:167], s[0:1], v166, s13, v[136:137]
	v_mul_f32_e32 v129, 0x3e38aa3b, v125
	v_mul_f32_e32 v131, 0x3e38aa3b, v121
	v_mul_f32_e32 v134, 0x3e38aa3b, v117
	v_mul_f32_e32 v139, 0x3e38aa3b, v113
	v_cvt_pk_bf16_f32 v168, v129, v131
	v_cvt_pk_bf16_f32 v169, v134, v139
	global_store_dwordx2 v[166:167], v[168:169], off nt
	v_mad_i64_i32 v[164:165], s[0:1], v164, s13, v[136:137]
	v_mul_f32_e32 v129, 0x3e38aa3b, v126
	v_mul_f32_e32 v131, 0x3e38aa3b, v122
	v_mul_f32_e32 v134, 0x3e38aa3b, v118
	v_mul_f32_e32 v139, 0x3e38aa3b, v114
	v_cvt_pk_bf16_f32 v166, v129, v131
	v_cvt_pk_bf16_f32 v167, v134, v139
	global_store_dwordx2 v[164:165], v[166:167], off nt
	v_mad_i64_i32 v[162:163], s[0:1], v162, s13, v[136:137]
	v_mul_f32_e32 v129, 0x3e38aa3b, v127
	v_mul_f32_e32 v131, 0x3e38aa3b, v123
	v_mul_f32_e32 v134, 0x3e38aa3b, v119
	v_mul_f32_e32 v139, 0x3e38aa3b, v115
	v_cvt_pk_bf16_f32 v164, v129, v131
	v_cvt_pk_bf16_f32 v165, v134, v139
	global_store_dwordx2 v[162:163], v[164:165], off nt
	v_mad_i64_i32 v[160:161], s[0:1], v160, s13, v[136:137]
	v_mul_f32_e32 v129, 0x3e38aa3b, v108
	v_mul_f32_e32 v131, 0x3e38aa3b, v104
	v_mul_f32_e32 v134, 0x3e38aa3b, v100
	v_mul_f32_e32 v139, 0x3e38aa3b, v96
	v_cvt_pk_bf16_f32 v162, v129, v131
	v_cvt_pk_bf16_f32 v163, v134, v139
	global_store_dwordx2 v[160:161], v[162:163], off nt
	v_mad_i64_i32 v[158:159], s[0:1], v158, s13, v[136:137]
	v_mul_f32_e32 v129, 0x3e38aa3b, v109
	v_mul_f32_e32 v131, 0x3e38aa3b, v105
	v_mul_f32_e32 v134, 0x3e38aa3b, v101
	v_mul_f32_e32 v139, 0x3e38aa3b, v97
	v_cvt_pk_bf16_f32 v160, v129, v131
	v_cvt_pk_bf16_f32 v161, v134, v139
	global_store_dwordx2 v[158:159], v[160:161], off nt
	v_mad_i64_i32 v[156:157], s[0:1], v156, s13, v[136:137]
	v_mul_f32_e32 v129, 0x3e38aa3b, v110
	v_mul_f32_e32 v131, 0x3e38aa3b, v106
	v_mul_f32_e32 v134, 0x3e38aa3b, v102
	v_mul_f32_e32 v139, 0x3e38aa3b, v98
	v_cvt_pk_bf16_f32 v158, v129, v131
	v_cvt_pk_bf16_f32 v159, v134, v139
	global_store_dwordx2 v[156:157], v[158:159], off nt
	v_mad_i64_i32 v[154:155], s[0:1], v154, s13, v[136:137]
	v_mul_f32_e32 v129, 0x3e38aa3b, v111
	v_mul_f32_e32 v131, 0x3e38aa3b, v107
	v_mul_f32_e32 v134, 0x3e38aa3b, v103
	v_mul_f32_e32 v139, 0x3e38aa3b, v99
	v_cvt_pk_bf16_f32 v156, v129, v131
	v_cvt_pk_bf16_f32 v157, v134, v139
	global_store_dwordx2 v[154:155], v[156:157], off nt
	v_mad_i64_i32 v[152:153], s[0:1], v152, s13, v[136:137]
	v_mul_f32_e32 v129, 0x3e38aa3b, v92
	v_mul_f32_e32 v131, 0x3e38aa3b, v88
	v_mul_f32_e32 v134, 0x3e38aa3b, v84
	v_mul_f32_e32 v139, 0x3e38aa3b, v80
	v_cvt_pk_bf16_f32 v154, v129, v131
	v_cvt_pk_bf16_f32 v155, v134, v139
	global_store_dwordx2 v[152:153], v[154:155], off nt
	v_mad_i64_i32 v[150:151], s[0:1], v150, s13, v[136:137]
	v_mul_f32_e32 v129, 0x3e38aa3b, v93
	v_mul_f32_e32 v131, 0x3e38aa3b, v89
	v_mul_f32_e32 v134, 0x3e38aa3b, v85
	v_mul_f32_e32 v139, 0x3e38aa3b, v81
	v_cvt_pk_bf16_f32 v152, v129, v131
	v_cvt_pk_bf16_f32 v153, v134, v139
	global_store_dwordx2 v[150:151], v[152:153], off nt
	v_mad_i64_i32 v[148:149], s[0:1], v148, s13, v[136:137]
	v_mul_f32_e32 v129, 0x3e38aa3b, v94
	v_mul_f32_e32 v131, 0x3e38aa3b, v90
	v_mul_f32_e32 v134, 0x3e38aa3b, v86
	v_mul_f32_e32 v139, 0x3e38aa3b, v82
	v_cvt_pk_bf16_f32 v150, v129, v131
	v_cvt_pk_bf16_f32 v151, v134, v139
	global_store_dwordx2 v[148:149], v[150:151], off nt
	v_mad_i64_i32 v[146:147], s[0:1], v146, s13, v[136:137]
	v_mul_f32_e32 v129, 0x3e38aa3b, v95
	v_mul_f32_e32 v131, 0x3e38aa3b, v91
	v_mul_f32_e32 v134, 0x3e38aa3b, v87
	v_mul_f32_e32 v139, 0x3e38aa3b, v83
	v_cvt_pk_bf16_f32 v148, v129, v131
	v_cvt_pk_bf16_f32 v149, v134, v139
	global_store_dwordx2 v[146:147], v[148:149], off nt
	v_mad_i64_i32 v[144:145], s[0:1], v144, s13, v[136:137]
	v_mul_f32_e32 v129, 0x3e38aa3b, v76
	v_mul_f32_e32 v131, 0x3e38aa3b, v72
	v_mul_f32_e32 v134, 0x3e38aa3b, v68
	v_mul_f32_e32 v139, 0x3e38aa3b, v64
	v_cvt_pk_bf16_f32 v146, v129, v131
	v_cvt_pk_bf16_f32 v147, v134, v139
	global_store_dwordx2 v[144:145], v[146:147], off nt
	v_mad_i64_i32 v[142:143], s[0:1], v142, s13, v[136:137]
	v_mul_f32_e32 v129, 0x3e38aa3b, v77
	v_mul_f32_e32 v131, 0x3e38aa3b, v73
	v_mul_f32_e32 v134, 0x3e38aa3b, v69
	v_mul_f32_e32 v139, 0x3e38aa3b, v65
	v_cvt_pk_bf16_f32 v144, v129, v131
	v_cvt_pk_bf16_f32 v145, v134, v139
	global_store_dwordx2 v[142:143], v[144:145], off nt
	v_mad_i64_i32 v[140:141], s[0:1], v140, s13, v[136:137]
	v_mul_f32_e32 v129, 0x3e38aa3b, v78
	v_mul_f32_e32 v131, 0x3e38aa3b, v74
	v_mul_f32_e32 v134, 0x3e38aa3b, v70
	v_mul_f32_e32 v139, 0x3e38aa3b, v66
	v_cvt_pk_bf16_f32 v142, v129, v131
	v_cvt_pk_bf16_f32 v143, v134, v139
	global_store_dwordx2 v[140:141], v[142:143], off nt
	v_mad_i64_i32 v[138:139], s[0:1], v138, s13, v[136:137]
	v_mul_f32_e32 v141, 0x3e38aa3b, v67
	v_mul_f32_e32 v129, 0x3e38aa3b, v79
	v_mul_f32_e32 v131, 0x3e38aa3b, v75
	v_mul_f32_e32 v134, 0x3e38aa3b, v71
	v_cvt_pk_bf16_f32 v140, v129, v131
	v_cvt_pk_bf16_f32 v141, v134, v141
	global_store_dwordx2 v[138:139], v[140:141], off nt
	v_mad_i64_i32 v[130:131], s[0:1], v130, s13, v[136:137]
	v_mul_f32_e32 v139, 0x3e38aa3b, v52
	v_mul_f32_e32 v129, 0x3e38aa3b, v60
	v_mul_f32_e32 v134, 0x3e38aa3b, v56
	v_mul_f32_e32 v140, 0x3e38aa3b, v48
	v_cvt_pk_bf16_f32 v138, v129, v134
	v_cvt_pk_bf16_f32 v139, v139, v140
	global_store_dwordx2 v[130:131], v[138:139], off nt
	v_add_u32_e32 v129, 0x41, v128
	v_mad_i64_i32 v[130:131], s[0:1], v129, s13, v[136:137]
	v_mul_f32_e32 v139, 0x3e38aa3b, v53
	v_mul_f32_e32 v129, 0x3e38aa3b, v61
	v_mul_f32_e32 v134, 0x3e38aa3b, v57
	v_mul_f32_e32 v140, 0x3e38aa3b, v49
	v_cvt_pk_bf16_f32 v138, v129, v134
	v_cvt_pk_bf16_f32 v139, v139, v140
	global_store_dwordx2 v[130:131], v[138:139], off nt
	v_add_u32_e32 v129, 0x42, v128
	v_mad_i64_i32 v[130:131], s[0:1], v129, s13, v[136:137]
	v_mul_f32_e32 v139, 0x3e38aa3b, v54
	v_mul_f32_e32 v129, 0x3e38aa3b, v62
	v_mul_f32_e32 v134, 0x3e38aa3b, v58
	v_mul_f32_e32 v140, 0x3e38aa3b, v50
	v_cvt_pk_bf16_f32 v138, v129, v134
	v_cvt_pk_bf16_f32 v139, v139, v140
	global_store_dwordx2 v[130:131], v[138:139], off nt
	v_add_u32_e32 v129, 0x43, v128
	v_mad_i64_i32 v[130:131], s[0:1], v129, s13, v[136:137]
	v_mul_f32_e32 v129, 0x3e38aa3b, v63
	v_mul_f32_e32 v139, 0x3e38aa3b, v55
	v_mul_f32_e32 v134, 0x3e38aa3b, v59
	v_mul_f32_e32 v140, 0x3e38aa3b, v51
	v_cvt_pk_bf16_f32 v138, v129, v134
	v_cvt_pk_bf16_f32 v139, v139, v140
	global_store_dwordx2 v[130:131], v[138:139], off nt
	v_add_u32_e32 v129, 0x50, v128
	v_mad_i64_i32 v[130:131], s[0:1], v129, s13, v[136:137]
	v_mul_f32_e32 v139, 0x3e38aa3b, v36
	v_mul_f32_e32 v129, 0x3e38aa3b, v44
	v_mul_f32_e32 v134, 0x3e38aa3b, v40
	v_mul_f32_e32 v140, 0x3e38aa3b, v32
	v_cvt_pk_bf16_f32 v138, v129, v134
	v_cvt_pk_bf16_f32 v139, v139, v140
	global_store_dwordx2 v[130:131], v[138:139], off nt
	v_add_u32_e32 v129, 0x51, v128
	v_mad_i64_i32 v[130:131], s[0:1], v129, s13, v[136:137]
	v_mul_f32_e32 v139, 0x3e38aa3b, v37
	v_mul_f32_e32 v129, 0x3e38aa3b, v45
	v_mul_f32_e32 v134, 0x3e38aa3b, v41
	v_mul_f32_e32 v140, 0x3e38aa3b, v33
	v_cvt_pk_bf16_f32 v138, v129, v134
	v_cvt_pk_bf16_f32 v139, v139, v140
	global_store_dwordx2 v[130:131], v[138:139], off nt
	v_add_u32_e32 v129, 0x52, v128
	v_mad_i64_i32 v[130:131], s[0:1], v129, s13, v[136:137]
	v_mul_f32_e32 v139, 0x3e38aa3b, v38
	v_mul_f32_e32 v129, 0x3e38aa3b, v46
	v_mul_f32_e32 v134, 0x3e38aa3b, v42
	v_mul_f32_e32 v140, 0x3e38aa3b, v34
	v_cvt_pk_bf16_f32 v138, v129, v134
	v_cvt_pk_bf16_f32 v139, v139, v140
	global_store_dwordx2 v[130:131], v[138:139], off nt
	v_add_u32_e32 v129, 0x53, v128
	v_mad_i64_i32 v[130:131], s[0:1], v129, s13, v[136:137]
	v_mul_f32_e32 v129, 0x3e38aa3b, v47
	v_mul_f32_e32 v139, 0x3e38aa3b, v39
	v_mul_f32_e32 v134, 0x3e38aa3b, v43
	v_mul_f32_e32 v140, 0x3e38aa3b, v35
	v_cvt_pk_bf16_f32 v138, v129, v134
	v_cvt_pk_bf16_f32 v139, v139, v140
	global_store_dwordx2 v[130:131], v[138:139], off nt
	v_add_u32_e32 v129, 0x60, v128
	v_mad_i64_i32 v[130:131], s[0:1], v129, s13, v[136:137]
	v_mul_f32_e32 v139, 0x3e38aa3b, v20
	v_mul_f32_e32 v129, 0x3e38aa3b, v28
	v_mul_f32_e32 v134, 0x3e38aa3b, v24
	v_mul_f32_e32 v140, 0x3e38aa3b, v16
	v_cvt_pk_bf16_f32 v138, v129, v134
	v_cvt_pk_bf16_f32 v139, v139, v140
	global_store_dwordx2 v[130:131], v[138:139], off nt
	v_add_u32_e32 v129, 0x61, v128
	v_mad_i64_i32 v[130:131], s[0:1], v129, s13, v[136:137]
	v_mul_f32_e32 v139, 0x3e38aa3b, v21
	v_mul_f32_e32 v129, 0x3e38aa3b, v29
	v_mul_f32_e32 v134, 0x3e38aa3b, v25
	v_mul_f32_e32 v140, 0x3e38aa3b, v17
	v_cvt_pk_bf16_f32 v138, v129, v134
	v_cvt_pk_bf16_f32 v139, v139, v140
	global_store_dwordx2 v[130:131], v[138:139], off nt
	v_add_u32_e32 v129, 0x62, v128
	v_mad_i64_i32 v[130:131], s[0:1], v129, s13, v[136:137]
	v_mul_f32_e32 v139, 0x3e38aa3b, v22
	v_mul_f32_e32 v129, 0x3e38aa3b, v30
	v_mul_f32_e32 v134, 0x3e38aa3b, v26
	v_mul_f32_e32 v140, 0x3e38aa3b, v18
	v_cvt_pk_bf16_f32 v138, v129, v134
	v_cvt_pk_bf16_f32 v139, v139, v140
	global_store_dwordx2 v[130:131], v[138:139], off nt
	v_add_u32_e32 v129, 0x63, v128
	v_mad_i64_i32 v[130:131], s[0:1], v129, s13, v[136:137]
	v_mul_f32_e32 v129, 0x3e38aa3b, v31
	v_mul_f32_e32 v139, 0x3e38aa3b, v23
	v_mul_f32_e32 v134, 0x3e38aa3b, v27
	v_mul_f32_e32 v140, 0x3e38aa3b, v19
	v_cvt_pk_bf16_f32 v138, v129, v134
	v_cvt_pk_bf16_f32 v139, v139, v140
	global_store_dwordx2 v[130:131], v[138:139], off nt
	v_add_u32_e32 v129, 0x70, v128
	v_mad_i64_i32 v[130:131], s[0:1], v129, s13, v[136:137]
	v_mul_f32_e32 v139, 0x3e38aa3b, v4
	v_mul_f32_e32 v129, 0x3e38aa3b, v12
	v_mul_f32_e32 v134, 0x3e38aa3b, v8
	v_mul_f32_e32 v140, 0x3e38aa3b, v0
	v_cvt_pk_bf16_f32 v138, v129, v134
	v_cvt_pk_bf16_f32 v139, v139, v140
	global_store_dwordx2 v[130:131], v[138:139], off nt
	v_add_u32_e32 v129, 0x71, v128
	v_mad_i64_i32 v[130:131], s[0:1], v129, s13, v[136:137]
	v_mul_f32_e32 v139, 0x3e38aa3b, v5
	v_mul_f32_e32 v129, 0x3e38aa3b, v13
	v_mul_f32_e32 v134, 0x3e38aa3b, v9
	v_mul_f32_e32 v140, 0x3e38aa3b, v1
	v_cvt_pk_bf16_f32 v138, v129, v134
	v_cvt_pk_bf16_f32 v139, v139, v140
	global_store_dwordx2 v[130:131], v[138:139], off nt
	v_add_u32_e32 v129, 0x72, v128
	v_mad_i64_i32 v[130:131], s[0:1], v129, s13, v[136:137]
	v_mul_f32_e32 v139, 0x3e38aa3b, v6
	v_mul_f32_e32 v129, 0x3e38aa3b, v14
	v_mul_f32_e32 v134, 0x3e38aa3b, v10
	v_mul_f32_e32 v140, 0x3e38aa3b, v2
	v_cvt_pk_bf16_f32 v138, v129, v134
	v_cvt_pk_bf16_f32 v139, v139, v140
	global_store_dwordx2 v[130:131], v[138:139], off nt
	v_add_u32_e32 v128, 0x73, v128
	v_mad_i64_i32 v[128:129], s[0:1], v128, s13, v[136:137]
	v_mul_f32_e32 v130, 0x3e38aa3b, v15
	v_mul_f32_e32 v131, 0x3e38aa3b, v11
	v_mul_f32_e32 v134, 0x3e38aa3b, v7
	v_mul_f32_e32 v136, 0x3e38aa3b, v3
	v_cvt_pk_bf16_f32 v130, v130, v131
	v_cvt_pk_bf16_f32 v131, v134, v136
	global_store_dwordx2 v[128:129], v[130:131], off nt

.LBB0_269:
	global_load_dwordx2 v[172:173], v[172:173], off
	v_lshlrev_b32_e32 v134, 2, v170
	v_lshl_add_u64 v[170:171], s[4:5], 0, v[134:135]
	v_lshl_add_u64 v[170:171], v[136:137], 2, v[170:171]
	s_waitcnt vmcnt(0)
	v_lshl_add_u64 v[172:173], v[136:137], 1, v[172:173]
	v_lshrrev_b32_e32 v129, 5, v168
	v_mul_lo_u32 v129, v129, s16
	v_add_u32_e32 v129, 0x200, v129
	v_or_b32_e32 v131, v129, v139
	v_mad_i64_i32 v[178:179], s[24:25], v131, s13, v[172:173]
	v_cvt_pk_bf16_f32 v180, v124, v120
	v_cvt_pk_bf16_f32 v181, v116, v112
	global_store_dwordx2 v[178:179], v[180:181], off nt
	v_mad_i64_i32 v[182:183], s[24:25], v168, s14, v[170:171]
	v_mov_b32_e32 v178, v124
	v_mov_b32_e32 v179, v120
	v_mov_b32_e32 v180, v116
	v_mov_b32_e32 v181, v112
	global_store_dwordx4 v[182:183], v[178:181], off nt
	v_or_b32_e32 v131, 1, v168
	v_and_or_b32 v134, v131, 29, v129
	v_mad_i64_i32 v[178:179], s[24:25], v134, s13, v[172:173]
	v_cvt_pk_bf16_f32 v180, v125, v121
	v_cvt_pk_bf16_f32 v181, v117, v113
	global_store_dwordx2 v[178:179], v[180:181], off nt
	v_mad_i64_i32 v[182:183], s[24:25], v131, s14, v[170:171]
	v_mov_b32_e32 v178, v125
	v_mov_b32_e32 v179, v121
	v_mov_b32_e32 v180, v117
	v_mov_b32_e32 v181, v113
	global_store_dwordx4 v[182:183], v[178:181], off nt
	v_or_b32_e32 v131, 2, v168
	v_and_or_b32 v134, v131, 30, v129
	v_mad_i64_i32 v[178:179], s[24:25], v134, s13, v[172:173]
	v_cvt_pk_bf16_f32 v180, v126, v122
	v_cvt_pk_bf16_f32 v181, v118, v114
	global_store_dwordx2 v[178:179], v[180:181], off nt
	v_mad_i64_i32 v[182:183], s[24:25], v131, s14, v[170:171]
	v_mov_b32_e32 v178, v126
	v_mov_b32_e32 v179, v122
	v_mov_b32_e32 v180, v118
	v_mov_b32_e32 v181, v114
	global_store_dwordx4 v[182:183], v[178:181], off nt
	v_or_b32_e32 v131, 3, v168
	v_and_or_b32 v129, v131, 31, v129
	v_mad_i64_i32 v[178:179], s[24:25], v129, s13, v[172:173]
	v_cvt_pk_bf16_f32 v180, v127, v123
	v_cvt_pk_bf16_f32 v181, v119, v115
	global_store_dwordx2 v[178:179], v[180:181], off nt
	v_mad_i64_i32 v[182:183], s[24:25], v131, s14, v[170:171]
	v_mov_b32_e32 v178, v127
	v_mov_b32_e32 v179, v123
	v_mov_b32_e32 v180, v119
	v_mov_b32_e32 v181, v115
	global_store_dwordx4 v[182:183], v[178:181], off nt
	v_add_u32_e32 v129, 16, v168
	v_lshrrev_b32_e32 v131, 5, v129
	v_mul_lo_u32 v131, v131, s16
	v_and_or_b32 v131, v129, 28, v131
	v_add_u32_e32 v131, 0x200, v131
	v_mad_i64_i32 v[178:179], s[24:25], v131, s13, v[172:173]
	v_cvt_pk_bf16_f32 v180, v108, v104
	v_cvt_pk_bf16_f32 v181, v100, v96
	global_store_dwordx2 v[178:179], v[180:181], off nt
	v_mad_i64_i32 v[182:183], s[24:25], v129, s14, v[170:171]
	v_mov_b32_e32 v178, v108
	v_mov_b32_e32 v179, v104
	v_mov_b32_e32 v180, v100
	v_mov_b32_e32 v181, v96
	global_store_dwordx4 v[182:183], v[178:181], off nt
	v_add_u32_e32 v129, 17, v168
	v_lshrrev_b32_e32 v131, 5, v129
	v_mul_lo_u32 v131, v131, s16
	v_and_or_b32 v131, v129, 29, v131
	v_add_u32_e32 v131, 0x200, v131
	v_mad_i64_i32 v[178:179], s[24:25], v131, s13, v[172:173]
	v_cvt_pk_bf16_f32 v180, v109, v105
	v_cvt_pk_bf16_f32 v181, v101, v97
	global_store_dwordx2 v[178:179], v[180:181], off nt
	v_mad_i64_i32 v[182:183], s[24:25], v129, s14, v[170:171]
	v_mov_b32_e32 v178, v109
	v_mov_b32_e32 v179, v105
	v_mov_b32_e32 v180, v101
	v_mov_b32_e32 v181, v97
	global_store_dwordx4 v[182:183], v[178:181], off nt
	v_add_u32_e32 v129, 18, v168
	v_lshrrev_b32_e32 v131, 5, v129
	v_mul_lo_u32 v131, v131, s16
	v_and_or_b32 v131, v129, 30, v131
	v_add_u32_e32 v131, 0x200, v131
	v_mad_i64_i32 v[178:179], s[24:25], v131, s13, v[172:173]
	v_cvt_pk_bf16_f32 v180, v110, v106
	v_cvt_pk_bf16_f32 v181, v102, v98
	global_store_dwordx2 v[178:179], v[180:181], off nt
	v_mad_i64_i32 v[182:183], s[24:25], v129, s14, v[170:171]
	v_mov_b32_e32 v178, v110
	v_mov_b32_e32 v179, v106
	v_mov_b32_e32 v180, v102
	v_mov_b32_e32 v181, v98
	global_store_dwordx4 v[182:183], v[178:181], off nt
	v_add_u32_e32 v129, 19, v168
	v_lshrrev_b32_e32 v131, 5, v129
	v_mul_lo_u32 v131, v131, s16
	v_and_or_b32 v131, v129, 31, v131
	v_add_u32_e32 v131, 0x200, v131
	v_mad_i64_i32 v[178:179], s[24:25], v131, s13, v[172:173]
	v_cvt_pk_bf16_f32 v180, v111, v107
	v_cvt_pk_bf16_f32 v181, v103, v99
	global_store_dwordx2 v[178:179], v[180:181], off nt
	v_mad_i64_i32 v[182:183], s[24:25], v129, s14, v[170:171]
	v_mov_b32_e32 v178, v111
	v_mov_b32_e32 v179, v107
	v_mov_b32_e32 v180, v103
	v_mov_b32_e32 v181, v99
	global_store_dwordx4 v[182:183], v[178:181], off nt
	v_add_u32_e32 v129, 32, v168
	v_lshrrev_b32_e32 v131, 5, v129
	v_mul_lo_u32 v131, v131, s16
	v_or_b32_e32 v131, v131, v139
	v_add_u32_e32 v131, 0x200, v131
	v_mad_i64_i32 v[178:179], s[24:25], v131, s13, v[172:173]
	v_cvt_pk_bf16_f32 v180, v92, v88
	v_cvt_pk_bf16_f32 v181, v84, v80
	global_store_dwordx2 v[178:179], v[180:181], off nt
	v_mad_i64_i32 v[182:183], s[24:25], v129, s14, v[170:171]
	v_mov_b32_e32 v178, v92
	v_mov_b32_e32 v179, v88
	v_mov_b32_e32 v180, v84
	v_mov_b32_e32 v181, v80
	global_store_dwordx4 v[182:183], v[178:181], off nt
	v_add_u32_e32 v129, 33, v168
	v_lshrrev_b32_e32 v131, 5, v129
	v_mul_lo_u32 v131, v131, s16
	v_and_or_b32 v131, v129, 29, v131
	v_add_u32_e32 v131, 0x200, v131
	v_mad_i64_i32 v[178:179], s[24:25], v131, s13, v[172:173]
	v_cvt_pk_bf16_f32 v180, v93, v89
	v_cvt_pk_bf16_f32 v181, v85, v81
	global_store_dwordx2 v[178:179], v[180:181], off nt
	v_mad_i64_i32 v[182:183], s[24:25], v129, s14, v[170:171]
	v_mov_b32_e32 v178, v93
	v_mov_b32_e32 v179, v89
	v_mov_b32_e32 v180, v85
	v_mov_b32_e32 v181, v81
	global_store_dwordx4 v[182:183], v[178:181], off nt
	v_add_u32_e32 v129, 34, v168
	v_lshrrev_b32_e32 v131, 5, v129
	v_mul_lo_u32 v131, v131, s16
	v_and_or_b32 v131, v129, 30, v131
	v_add_u32_e32 v131, 0x200, v131
	v_mad_i64_i32 v[178:179], s[24:25], v131, s13, v[172:173]
	v_cvt_pk_bf16_f32 v180, v94, v90
	v_cvt_pk_bf16_f32 v181, v86, v82
	global_store_dwordx2 v[178:179], v[180:181], off nt
	v_mad_i64_i32 v[182:183], s[24:25], v129, s14, v[170:171]
	v_mov_b32_e32 v178, v94
	v_mov_b32_e32 v179, v90
	v_mov_b32_e32 v180, v86
	v_mov_b32_e32 v181, v82
	global_store_dwordx4 v[182:183], v[178:181], off nt
	v_add_u32_e32 v129, 35, v168
	v_lshrrev_b32_e32 v131, 5, v129
	v_mul_lo_u32 v131, v131, s16
	v_and_or_b32 v131, v129, 31, v131
	v_add_u32_e32 v131, 0x200, v131
	v_mad_i64_i32 v[178:179], s[24:25], v131, s13, v[172:173]
	v_cvt_pk_bf16_f32 v180, v95, v91
	v_cvt_pk_bf16_f32 v181, v87, v83
	global_store_dwordx2 v[178:179], v[180:181], off nt
	v_mad_i64_i32 v[182:183], s[24:25], v129, s14, v[170:171]
	v_mov_b32_e32 v178, v95
	v_mov_b32_e32 v179, v91
	v_mov_b32_e32 v180, v87
	v_mov_b32_e32 v181, v83
	global_store_dwordx4 v[182:183], v[178:181], off nt
	v_add_u32_e32 v129, 48, v168
	v_lshrrev_b32_e32 v131, 5, v129
	v_mul_lo_u32 v131, v131, s16
	v_and_or_b32 v131, v129, 28, v131
	v_add_u32_e32 v131, 0x200, v131
	v_mad_i64_i32 v[178:179], s[24:25], v131, s13, v[172:173]
	v_cvt_pk_bf16_f32 v180, v76, v72
	v_cvt_pk_bf16_f32 v181, v68, v64
	global_store_dwordx2 v[178:179], v[180:181], off nt
	v_mad_i64_i32 v[182:183], s[24:25], v129, s14, v[170:171]
	v_mov_b32_e32 v178, v76
	v_mov_b32_e32 v179, v72
	v_mov_b32_e32 v180, v68
	v_mov_b32_e32 v181, v64
	global_store_dwordx4 v[182:183], v[178:181], off nt
	v_add_u32_e32 v129, 49, v168
	v_lshrrev_b32_e32 v131, 5, v129
	v_mul_lo_u32 v131, v131, s16
	v_and_or_b32 v131, v129, 29, v131
	v_add_u32_e32 v131, 0x200, v131
	v_mad_i64_i32 v[178:179], s[24:25], v131, s13, v[172:173]
	v_cvt_pk_bf16_f32 v180, v77, v73
	v_cvt_pk_bf16_f32 v181, v69, v65
	global_store_dwordx2 v[178:179], v[180:181], off nt
	v_mad_i64_i32 v[182:183], s[24:25], v129, s14, v[170:171]
	v_mov_b32_e32 v178, v77
	v_mov_b32_e32 v179, v73
	v_mov_b32_e32 v180, v69
	v_mov_b32_e32 v181, v65
	global_store_dwordx4 v[182:183], v[178:181], off nt
	v_add_u32_e32 v129, 50, v168
	v_lshrrev_b32_e32 v131, 5, v129
	v_mul_lo_u32 v131, v131, s16
	v_and_or_b32 v131, v129, 30, v131
	v_add_u32_e32 v131, 0x200, v131
	v_mad_i64_i32 v[178:179], s[24:25], v131, s13, v[172:173]
	v_cvt_pk_bf16_f32 v180, v78, v74
	v_cvt_pk_bf16_f32 v181, v70, v66
	global_store_dwordx2 v[178:179], v[180:181], off nt
	v_mad_i64_i32 v[182:183], s[24:25], v129, s14, v[170:171]
	v_mov_b32_e32 v178, v78
	v_mov_b32_e32 v179, v74
	v_mov_b32_e32 v180, v70
	v_mov_b32_e32 v181, v66
	global_store_dwordx4 v[182:183], v[178:181], off nt
	v_add_u32_e32 v129, 51, v168
	v_lshrrev_b32_e32 v131, 5, v129
	v_mul_lo_u32 v131, v131, s16
	v_and_or_b32 v131, v129, 31, v131
	v_add_u32_e32 v131, 0x200, v131
	v_mad_i64_i32 v[178:179], s[24:25], v131, s13, v[172:173]
	v_cvt_pk_bf16_f32 v180, v79, v75
	v_cvt_pk_bf16_f32 v181, v71, v67
	global_store_dwordx2 v[178:179], v[180:181], off nt
	v_mad_i64_i32 v[182:183], s[24:25], v129, s14, v[170:171]
	v_mov_b32_e32 v178, v79
	v_mov_b32_e32 v179, v75
	v_mov_b32_e32 v180, v71
	v_mov_b32_e32 v181, v67
	global_store_dwordx4 v[182:183], v[178:181], off nt
	v_add_u32_e32 v129, 64, v168
	v_lshrrev_b32_e32 v131, 5, v129
	v_mul_lo_u32 v131, v131, s16
	v_or_b32_e32 v131, v131, v139
	v_add_u32_e32 v131, 0x200, v131
	v_mad_i64_i32 v[178:179], s[24:25], v131, s13, v[172:173]
	v_cvt_pk_bf16_f32 v180, v60, v56
	v_cvt_pk_bf16_f32 v181, v52, v48
	global_store_dwordx2 v[178:179], v[180:181], off nt
	v_mad_i64_i32 v[182:183], s[24:25], v129, s14, v[170:171]
	v_mov_b32_e32 v178, v60
	v_mov_b32_e32 v179, v56
	v_mov_b32_e32 v180, v52
	v_mov_b32_e32 v181, v48
	global_store_dwordx4 v[182:183], v[178:181], off nt
	v_add_u32_e32 v129, 0x41, v168
	v_lshrrev_b32_e32 v131, 5, v129
	v_mul_lo_u32 v131, v131, s16
	v_and_or_b32 v131, v129, 29, v131
	v_add_u32_e32 v131, 0x200, v131
	v_mad_i64_i32 v[178:179], s[24:25], v131, s13, v[172:173]
	v_cvt_pk_bf16_f32 v180, v61, v57
	v_cvt_pk_bf16_f32 v181, v53, v49
	global_store_dwordx2 v[178:179], v[180:181], off nt
	v_mad_i64_i32 v[182:183], s[24:25], v129, s14, v[170:171]
	v_mov_b32_e32 v178, v61
	v_mov_b32_e32 v179, v57
	v_mov_b32_e32 v180, v53
	v_mov_b32_e32 v181, v49
	global_store_dwordx4 v[182:183], v[178:181], off nt
	v_add_u32_e32 v129, 0x42, v168
	v_lshrrev_b32_e32 v131, 5, v129
	v_mul_lo_u32 v131, v131, s16
	v_and_or_b32 v131, v129, 30, v131
	v_add_u32_e32 v131, 0x200, v131
	v_mad_i64_i32 v[178:179], s[24:25], v131, s13, v[172:173]
	v_cvt_pk_bf16_f32 v180, v62, v58
	v_cvt_pk_bf16_f32 v181, v54, v50
	global_store_dwordx2 v[178:179], v[180:181], off nt
	v_mad_i64_i32 v[182:183], s[24:25], v129, s14, v[170:171]
	v_mov_b32_e32 v178, v62
	v_mov_b32_e32 v179, v58
	v_mov_b32_e32 v180, v54
	v_mov_b32_e32 v181, v50
	global_store_dwordx4 v[182:183], v[178:181], off nt
	v_add_u32_e32 v129, 0x43, v168
	v_lshrrev_b32_e32 v131, 5, v129
	v_mul_lo_u32 v131, v131, s16
	v_and_or_b32 v131, v129, 31, v131
	v_add_u32_e32 v131, 0x200, v131
	v_mad_i64_i32 v[178:179], s[24:25], v131, s13, v[172:173]
	v_cvt_pk_bf16_f32 v180, v63, v59
	v_cvt_pk_bf16_f32 v181, v55, v51
	global_store_dwordx2 v[178:179], v[180:181], off nt
	v_mad_i64_i32 v[182:183], s[24:25], v129, s14, v[170:171]
	v_mov_b32_e32 v178, v63
	v_mov_b32_e32 v179, v59
	v_mov_b32_e32 v180, v55
	v_mov_b32_e32 v181, v51
	global_store_dwordx4 v[182:183], v[178:181], off nt
	v_add_u32_e32 v129, 0x50, v168
	v_lshrrev_b32_e32 v131, 5, v129
	v_mul_lo_u32 v131, v131, s16
	v_and_or_b32 v131, v129, 28, v131
	v_add_u32_e32 v131, 0x200, v131
	v_mad_i64_i32 v[178:179], s[24:25], v131, s13, v[172:173]
	v_cvt_pk_bf16_f32 v180, v44, v40
	v_cvt_pk_bf16_f32 v181, v36, v32
	global_store_dwordx2 v[178:179], v[180:181], off nt
	v_mad_i64_i32 v[182:183], s[24:25], v129, s14, v[170:171]
	v_mov_b32_e32 v178, v44
	v_mov_b32_e32 v179, v40
	v_mov_b32_e32 v180, v36
	v_mov_b32_e32 v181, v32
	global_store_dwordx4 v[182:183], v[178:181], off nt
	v_add_u32_e32 v129, 0x51, v168
	v_lshrrev_b32_e32 v131, 5, v129
	v_mul_lo_u32 v131, v131, s16
	v_and_or_b32 v131, v129, 29, v131
	v_add_u32_e32 v131, 0x200, v131
	v_mad_i64_i32 v[178:179], s[24:25], v131, s13, v[172:173]
	v_cvt_pk_bf16_f32 v180, v45, v41
	v_cvt_pk_bf16_f32 v181, v37, v33
	global_store_dwordx2 v[178:179], v[180:181], off nt
	v_mad_i64_i32 v[182:183], s[24:25], v129, s14, v[170:171]
	v_mov_b32_e32 v178, v45
	v_mov_b32_e32 v179, v41
	v_mov_b32_e32 v180, v37
	v_mov_b32_e32 v181, v33
	global_store_dwordx4 v[182:183], v[178:181], off nt
	v_add_u32_e32 v129, 0x52, v168
	v_lshrrev_b32_e32 v131, 5, v129
	v_mul_lo_u32 v131, v131, s16
	v_and_or_b32 v131, v129, 30, v131
	v_add_u32_e32 v131, 0x200, v131
	v_mad_i64_i32 v[178:179], s[24:25], v131, s13, v[172:173]
	v_cvt_pk_bf16_f32 v180, v46, v42
	v_cvt_pk_bf16_f32 v181, v38, v34
	global_store_dwordx2 v[178:179], v[180:181], off nt
	v_mad_i64_i32 v[182:183], s[24:25], v129, s14, v[170:171]
	v_mov_b32_e32 v178, v46
	v_mov_b32_e32 v179, v42
	v_mov_b32_e32 v180, v38
	v_mov_b32_e32 v181, v34
	global_store_dwordx4 v[182:183], v[178:181], off nt
	v_add_u32_e32 v129, 0x53, v168
	v_lshrrev_b32_e32 v131, 5, v129
	v_mul_lo_u32 v131, v131, s16
	v_and_or_b32 v131, v129, 31, v131
	v_add_u32_e32 v131, 0x200, v131
	v_mad_i64_i32 v[178:179], s[24:25], v131, s13, v[172:173]
	v_cvt_pk_bf16_f32 v180, v47, v43
	v_cvt_pk_bf16_f32 v181, v39, v35
	global_store_dwordx2 v[178:179], v[180:181], off nt
	v_mad_i64_i32 v[182:183], s[24:25], v129, s14, v[170:171]
	v_mov_b32_e32 v178, v47
	v_mov_b32_e32 v179, v43
	v_mov_b32_e32 v180, v39
	v_mov_b32_e32 v181, v35
	global_store_dwordx4 v[182:183], v[178:181], off nt
	v_add_u32_e32 v129, 0x60, v168
	v_lshrrev_b32_e32 v131, 5, v129
	v_mul_lo_u32 v131, v131, s16
	v_or_b32_e32 v131, v131, v139
	v_add_u32_e32 v131, 0x200, v131
	v_mad_i64_i32 v[178:179], s[24:25], v131, s13, v[172:173]
	v_cvt_pk_bf16_f32 v180, v28, v24
	v_cvt_pk_bf16_f32 v181, v20, v16
	global_store_dwordx2 v[178:179], v[180:181], off nt
	v_mad_i64_i32 v[182:183], s[24:25], v129, s14, v[170:171]
	v_mov_b32_e32 v178, v28
	v_mov_b32_e32 v179, v24
	v_mov_b32_e32 v180, v20
	v_mov_b32_e32 v181, v16
	global_store_dwordx4 v[182:183], v[178:181], off nt
	v_add_u32_e32 v129, 0x61, v168
	v_lshrrev_b32_e32 v131, 5, v129
	v_mul_lo_u32 v131, v131, s16
	v_and_or_b32 v131, v129, 29, v131
	v_add_u32_e32 v131, 0x200, v131
	v_mad_i64_i32 v[178:179], s[24:25], v131, s13, v[172:173]
	v_cvt_pk_bf16_f32 v180, v29, v25
	v_cvt_pk_bf16_f32 v181, v21, v17
	global_store_dwordx2 v[178:179], v[180:181], off nt
	v_mad_i64_i32 v[182:183], s[24:25], v129, s14, v[170:171]
	v_mov_b32_e32 v178, v29
	v_mov_b32_e32 v179, v25
	v_mov_b32_e32 v180, v21
	v_mov_b32_e32 v181, v17
	global_store_dwordx4 v[182:183], v[178:181], off nt
	v_add_u32_e32 v129, 0x62, v168
	v_lshrrev_b32_e32 v131, 5, v129
	v_mul_lo_u32 v131, v131, s16
	v_and_or_b32 v131, v129, 30, v131
	v_add_u32_e32 v131, 0x200, v131
	v_mad_i64_i32 v[178:179], s[24:25], v131, s13, v[172:173]
	v_cvt_pk_bf16_f32 v180, v30, v26
	v_cvt_pk_bf16_f32 v181, v22, v18
	global_store_dwordx2 v[178:179], v[180:181], off nt
	v_mad_i64_i32 v[182:183], s[24:25], v129, s14, v[170:171]
	v_mov_b32_e32 v178, v30
	v_mov_b32_e32 v179, v26
	v_mov_b32_e32 v180, v22
	v_mov_b32_e32 v181, v18
	global_store_dwordx4 v[182:183], v[178:181], off nt
	v_add_u32_e32 v129, 0x63, v168
	v_lshrrev_b32_e32 v131, 5, v129
	v_mul_lo_u32 v131, v131, s16
	v_and_or_b32 v131, v129, 31, v131
	v_add_u32_e32 v131, 0x200, v131
	v_mad_i64_i32 v[178:179], s[24:25], v131, s13, v[172:173]
	v_cvt_pk_bf16_f32 v180, v31, v27
	v_cvt_pk_bf16_f32 v181, v23, v19
	global_store_dwordx2 v[178:179], v[180:181], off nt
	v_mad_i64_i32 v[182:183], s[24:25], v129, s14, v[170:171]
	v_mov_b32_e32 v178, v31
	v_mov_b32_e32 v179, v27
	v_mov_b32_e32 v180, v23
	v_mov_b32_e32 v181, v19
	global_store_dwordx4 v[182:183], v[178:181], off nt
	v_add_u32_e32 v129, 0x70, v168
	v_lshrrev_b32_e32 v131, 5, v129
	v_mul_lo_u32 v131, v131, s16
	v_and_or_b32 v131, v129, 28, v131
	v_add_u32_e32 v131, 0x200, v131
	v_mad_i64_i32 v[178:179], s[24:25], v131, s13, v[172:173]
	v_cvt_pk_bf16_f32 v180, v12, v8
	v_cvt_pk_bf16_f32 v181, v4, v0
	global_store_dwordx2 v[178:179], v[180:181], off nt
	v_mad_i64_i32 v[182:183], s[24:25], v129, s14, v[170:171]
	v_mov_b32_e32 v178, v12
	v_mov_b32_e32 v179, v8
	v_mov_b32_e32 v180, v4
	v_mov_b32_e32 v181, v0
	global_store_dwordx4 v[182:183], v[178:181], off nt
	v_add_u32_e32 v129, 0x71, v168
	v_lshrrev_b32_e32 v131, 5, v129
	v_mul_lo_u32 v131, v131, s16
	v_and_or_b32 v131, v129, 29, v131
	v_add_u32_e32 v131, 0x200, v131
	v_mad_i64_i32 v[178:179], s[24:25], v131, s13, v[172:173]
	v_cvt_pk_bf16_f32 v180, v13, v9
	v_cvt_pk_bf16_f32 v181, v5, v1
	global_store_dwordx2 v[178:179], v[180:181], off nt
	v_mad_i64_i32 v[182:183], s[24:25], v129, s14, v[170:171]
	v_mov_b32_e32 v178, v13
	v_mov_b32_e32 v179, v9
	v_mov_b32_e32 v180, v5
	v_mov_b32_e32 v181, v1
	global_store_dwordx4 v[182:183], v[178:181], off nt
	v_add_u32_e32 v129, 0x72, v168
	v_lshrrev_b32_e32 v131, 5, v129
	v_mul_lo_u32 v131, v131, s16
	v_and_or_b32 v131, v129, 30, v131
	v_add_u32_e32 v131, 0x200, v131
	v_mad_i64_i32 v[178:179], s[24:25], v131, s13, v[172:173]
	v_cvt_pk_bf16_f32 v180, v14, v10
	v_cvt_pk_bf16_f32 v181, v6, v2
	global_store_dwordx2 v[178:179], v[180:181], off nt
	v_mad_i64_i32 v[182:183], s[24:25], v129, s14, v[170:171]
	v_mov_b32_e32 v178, v14
	v_mov_b32_e32 v179, v10
	v_mov_b32_e32 v180, v6
	v_mov_b32_e32 v181, v2
	global_store_dwordx4 v[182:183], v[178:181], off nt
	v_add_u32_e32 v129, 0x73, v168
	v_lshrrev_b32_e32 v131, 5, v129
	v_mul_lo_u32 v131, v131, s16
	v_and_or_b32 v131, v129, 31, v131
	v_add_u32_e32 v131, 0x200, v131
	v_mad_i64_i32 v[172:173], s[24:25], v131, s13, v[172:173]
	v_cvt_pk_bf16_f32 v178, v15, v11
	v_cvt_pk_bf16_f32 v179, v7, v3
	global_store_dwordx2 v[172:173], v[178:179], off nt
	v_mad_i64_i32 v[178:179], s[24:25], v129, s14, v[170:171]
	v_mov_b32_e32 v170, v15
	v_mov_b32_e32 v171, v11
	v_mov_b32_e32 v172, v7
	v_mov_b32_e32 v173, v3
	global_store_dwordx4 v[178:179], v[170:173], off nt
	s_andn2_b64 s[8:9], s[8:9], exec
	s_or_b64 exec, exec, s[0:1]
	s_mov_b64 s[66:67], 0
	s_and_saveexec_b64 s[0:1], s[8:9]
	s_cbranch_execz .LBB0_258

.LBB0_271:
	v_mbcnt_hi_u32_b32 v129, -1, v204
	v_and_b32_e32 v134, 64, v129
	v_xor_b32_e32 v131, 4, v129
	v_add_u32_e32 v134, 64, v134
	v_cmp_lt_i32_e32 vcc, v131, v134
	v_readlane_b32 s36, v253, 26
	v_lshlrev_b32_e32 v134, 2, v175
	v_cndmask_b32_e32 v129, v129, v131, vcc
	v_lshlrev_b32_e32 v131, 3, v174
	v_readlane_b32 s50, v253, 40
	v_readlane_b32 s51, v253, 41
	v_and_b32_e32 v141, 4, v174
	v_lshlrev_b32_e32 v129, 2, v129
	v_cmp_lt_u32_e64 s[10:11], 7, v176
	v_and_b32_e32 v131, 24, v131
	v_cmp_gt_u32_e64 s[8:9], 10, v176
	v_lshl_add_u64 v[170:171], s[50:51], 0, v[134:135]
	v_cmp_eq_u32_e64 s[0:1], 0, v141
	v_readlane_b32 s37, v253, 27
	v_readlane_b32 s38, v253, 28
	v_readlane_b32 s39, v253, 29
	v_readlane_b32 s40, v253, 30
	v_readlane_b32 s41, v253, 31
	v_readlane_b32 s42, v253, 32
	v_readlane_b32 s43, v253, 33
	v_readlane_b32 s44, v253, 34
	v_readlane_b32 s45, v253, 35
	v_readlane_b32 s46, v253, 36
	v_readlane_b32 s47, v253, 37
	v_readlane_b32 s48, v253, 38
	v_readlane_b32 s49, v253, 39
	v_lshlrev_b32_e32 v131, 3, v131
	v_lshl_or_b32 v172, v139, 8, v131
	v_mov_b32_e32 v173, v135
	v_lshl_add_u64 v[178:179], s[58:59], 0, v[172:173]
	v_add_co_u32_e32 v172, vcc, s33, v178
	ds_bpermute_b32 v190, v129, v124
	s_nop 0
	v_addc_co_u32_e32 v173, vcc, 0, v179, vcc
	global_load_dwordx2 v[186:187], v[172:173], off offset:256
	global_load_dwordx2 v[184:185], v[172:173], off offset:272
	global_load_dwordx2 v[182:183], v[172:173], off offset:288
	global_load_dwordx2 v[180:181], v[172:173], off offset:304
	ds_bpermute_b32 v191, v129, v120
	ds_bpermute_b32 v188, v129, v116
	ds_bpermute_b32 v189, v129, v112
	s_and_saveexec_b64 s[24:25], s[10:11]
	s_xor_b64 s[72:73], exec, s[24:25]
	s_cbranch_execz .LBB0_275
	s_and_saveexec_b64 s[74:75], s[8:9]
	s_cbranch_execz .LBB0_274
	v_ashrrev_i32_e32 v169, 31, v168
	v_mov_b32_e32 v176, v124
	v_mov_b32_e32 v177, v120
	v_lshlrev_b64 v[172:173], 5, v[168:169]
	s_waitcnt lgkmcnt(0)
	v_pk_mul_f32 v[188:189], v[176:177], s[88:89] op_sel_hi:[1,0]
	v_mov_b32_e32 v176, v116
	v_mov_b32_e32 v177, v112
	v_lshl_add_u64 v[172:173], v[170:171], 0, v[172:173]
	v_pk_mul_f32 v[190:191], v[176:177], s[88:89] op_sel_hi:[1,0]
	global_store_dwordx4 v[172:173], v[188:191], off offset:-128 nt

.LBB0_275:
	s_or_saveexec_b64 s[72:73], s[72:73]
	v_cndmask_b32_e64 v172, 1.0, -1.0, s[0:1]
	v_readlane_b32 s36, v253, 26
	v_readlane_b32 s0, v253, 20
	v_lshlrev_b32_e32 v174, 1, v175
	v_mov_b32_e32 v175, v135
	v_readlane_b32 s48, v253, 38
	v_readlane_b32 s49, v253, 39
	v_readlane_b32 s1, v253, 21
	v_readlane_b32 s37, v253, 27
	v_lshl_add_u64 v[176:177], s[48:49], 0, v[174:175]
	v_lshl_add_u64 v[174:175], s[0:1], 0, v[134:135]
	v_lshrrev_b32_e32 v134, 5, v168
	v_mul_lo_u32 v141, v134, s12
	v_readlane_b32 s38, v253, 28
	v_readlane_b32 s39, v253, 29
	v_readlane_b32 s40, v253, 30
	v_readlane_b32 s41, v253, 31
	v_readlane_b32 s42, v253, 32
	v_readlane_b32 s43, v253, 33
	v_readlane_b32 s44, v253, 34
	v_readlane_b32 s45, v253, 35
	v_readlane_b32 s46, v253, 36
	v_readlane_b32 s47, v253, 37
	v_readlane_b32 s50, v253, 40
	v_readlane_b32 s51, v253, 41
	s_xor_b64 exec, exec, s[72:73]
	s_cbranch_execz .LBB0_277
	v_or_b32_e32 v134, v141, v139
	v_add_u32_e32 v192, 0x1000, v134
	v_ashrrev_i32_e32 v193, 31, v192
	v_lshlrev_b64 v[192:193], 6, v[192:193]
	v_ashrrev_i32_e32 v169, 31, v168
	v_lshl_add_u64 v[194:195], v[176:177], 0, v[192:193]
	v_lshlrev_b64 v[192:193], 7, v[168:169]
	v_lshl_add_u64 v[196:197], v[174:175], 0, v[192:193]
	v_add_co_u32_e32 v192, vcc, 0x80000, v178
	v_mov_b32_e32 v202, v124
	s_nop 0
	v_addc_co_u32_e32 v193, vcc, 0, v179, vcc
	global_load_dwordx2 v[198:199], v[192:193], off offset:16
	global_load_dwordx2 v[200:201], v[192:193], off
	v_mov_b32_e32 v203, v120
	s_waitcnt lgkmcnt(2)
	v_pk_mul_f32 v[190:191], v[172:173], v[190:191] op_sel_hi:[0,1]
	s_waitcnt lgkmcnt(0)
	v_pk_mul_f32 v[188:189], v[172:173], v[188:189] op_sel_hi:[0,1]
	s_waitcnt vmcnt(1)
	v_mov_b32_e32 v207, v198
	s_waitcnt vmcnt(0)
	v_mov_b32_e32 v206, v200
	v_mov_b32_e32 v198, v201
	global_load_dwordx2 v[200:201], v[192:193], off offset:48
	s_nop 0
	global_load_dwordx2 v[192:193], v[192:193], off offset:32
	v_pk_mul_f32 v[202:203], v[202:203], v[206:207]
	s_waitcnt vmcnt(1)
	v_mov_b32_e32 v207, v200
	v_pk_fma_f32 v[190:191], v[190:191], v[198:199], v[202:203]
	v_mov_b32_e32 v202, v116
	v_mov_b32_e32 v203, v112
	s_waitcnt vmcnt(0)
	v_mov_b32_e32 v206, v192
	v_pk_mul_f32 v[202:203], v[202:203], v[206:207]
	v_mov_b32_e32 v200, v193
	v_cvt_pk_bf16_f32 v198, v190, v191
	v_pk_fma_f32 v[192:193], v[188:189], v[200:201], v[202:203]
	s_nop 0
	v_cvt_pk_bf16_f32 v199, v192, v193
	global_store_dwordx2 v[194:195], v[198:199], off nt
	global_store_dwordx4 v[196:197], v[190:193], off nt
.LBB0_277:
	s_or_b64 exec, exec, s[72:73]
	ds_bpermute_b32 v192, v129, v125
	ds_bpermute_b32 v193, v129, v121
	s_waitcnt lgkmcnt(3)
	ds_bpermute_b32 v188, v129, v117
	s_waitcnt lgkmcnt(3)
	ds_bpermute_b32 v189, v129, v113
	v_or_b32_e32 v190, 1, v168
	s_and_saveexec_b64 s[0:1], s[10:11]
	s_xor_b64 s[0:1], exec, s[0:1]
	s_cbranch_execz .LBB0_281
	s_and_saveexec_b64 s[72:73], s[8:9]
	s_cbranch_execz .LBB0_280
	v_ashrrev_i32_e32 v191, 31, v190
	s_waitcnt vmcnt(0)
	v_lshlrev_b64 v[180:181], 5, v[190:191]
	v_lshl_add_u64 v[184:185], v[170:171], 0, v[180:181]
	v_mov_b32_e32 v180, v125
	v_mov_b32_e32 v181, v121
	v_mov_b32_e32 v182, v117
	v_mov_b32_e32 v183, v113
	v_pk_mul_f32 v[180:181], v[180:181], s[88:89] op_sel_hi:[1,0]
	v_pk_mul_f32 v[182:183], v[182:183], s[88:89] op_sel_hi:[1,0]
	global_store_dwordx4 v[184:185], v[180:183], off offset:-128 nt

.LBB0_281:
	s_andn2_saveexec_b64 s[0:1], s[0:1]
	s_cbranch_execz .LBB0_283
	v_and_or_b32 v134, v190, 29, v141
	v_add_u32_e32 v194, 0x1000, v134
	v_ashrrev_i32_e32 v195, 31, v194
	s_waitcnt vmcnt(0)
	v_mov_b32_e32 v199, v180
	v_mov_b32_e32 v202, v186
	v_mov_b32_e32 v203, v184
	s_waitcnt lgkmcnt(2)
	v_pk_mul_f32 v[192:193], v[172:173], v[192:193] op_sel_hi:[0,1]
	v_mov_b32_e32 v184, v187
	s_waitcnt lgkmcnt(0)
	v_pk_mul_f32 v[186:187], v[172:173], v[188:189] op_sel_hi:[0,1]
	v_mov_b32_e32 v180, v183
	v_mov_b32_e32 v196, v117
	v_mov_b32_e32 v197, v113
	v_mov_b32_e32 v198, v182
	v_mov_b32_e32 v200, v125
	v_mov_b32_e32 v201, v121
	v_lshlrev_b64 v[194:195], 6, v[194:195]
	v_ashrrev_i32_e32 v191, 31, v190
	v_pk_mul_f32 v[184:185], v[184:185], v[192:193]
	v_pk_mul_f32 v[180:181], v[180:181], v[186:187]
	v_lshl_add_u64 v[194:195], v[176:177], 0, v[194:195]
	v_lshlrev_b64 v[190:191], 7, v[190:191]
	v_pk_fma_f32 v[184:185], v[200:201], v[202:203], v[184:185]
	v_pk_fma_f32 v[186:187], v[196:197], v[198:199], v[180:181]
	v_cvt_pk_bf16_f32 v182, v184, v185
	v_lshl_add_u64 v[190:191], v[174:175], 0, v[190:191]
	v_cvt_pk_bf16_f32 v183, v186, v187
	global_store_dwordx2 v[194:195], v[182:183], off nt
	global_store_dwordx4 v[190:191], v[184:187], off nt
.LBB0_283:
	s_or_b64 exec, exec, s[0:1]
	v_bitop3_b32 v143, v168, 30, 2 bitop3:0xc8
	v_lshl_or_b32 v134, v143, 8, v131
	s_waitcnt lgkmcnt(2)
	v_lshl_add_u64 v[192:193], s[58:59], 0, v[134:135]
	s_waitcnt vmcnt(0)
	v_add_co_u32_e32 v180, vcc, 0x80000, v192
	ds_bpermute_b32 v190, v129, v126
	s_nop 0
	v_addc_co_u32_e32 v181, vcc, 0, v193, vcc
	global_load_dwordx2 v[186:187], v[180:181], off offset:256
	global_load_dwordx2 v[184:185], v[180:181], off offset:272
	global_load_dwordx2 v[182:183], v[180:181], off offset:288
	s_nop 0
	global_load_dwordx2 v[180:181], v[180:181], off offset:304
	ds_bpermute_b32 v191, v129, v122
	s_waitcnt lgkmcnt(3)
	ds_bpermute_b32 v188, v129, v118
	s_waitcnt lgkmcnt(3)
	ds_bpermute_b32 v189, v129, v114
	v_or_b32_e32 v194, 2, v168
	s_and_saveexec_b64 s[0:1], s[10:11]
	s_xor_b64 s[0:1], exec, s[0:1]
	s_cbranch_execz .LBB0_287
	s_and_saveexec_b64 s[72:73], s[8:9]
	s_cbranch_execz .LBB0_286
	v_ashrrev_i32_e32 v195, 31, v194
	s_waitcnt lgkmcnt(0)
	v_lshlrev_b64 v[188:189], 5, v[194:195]
	v_lshl_add_u64 v[192:193], v[170:171], 0, v[188:189]
	v_mov_b32_e32 v188, v126
	v_mov_b32_e32 v189, v122
	v_mov_b32_e32 v190, v118
	v_mov_b32_e32 v191, v114
	v_pk_mul_f32 v[188:189], v[188:189], s[88:89] op_sel_hi:[1,0]
	v_pk_mul_f32 v[190:191], v[190:191], s[88:89] op_sel_hi:[1,0]
	global_store_dwordx4 v[192:193], v[188:191], off offset:-128 nt

.LBB0_287:
	s_andn2_saveexec_b64 s[0:1], s[0:1]
	s_cbranch_execz .LBB0_289
	v_add_co_u32_e32 v192, vcc, 0x80000, v192
	v_or_b32_e32 v134, v141, v143
	s_nop 0
	v_addc_co_u32_e32 v193, vcc, 0, v193, vcc
	global_load_dwordx2 v[198:199], v[192:193], off offset:16
	global_load_dwordx2 v[200:201], v[192:193], off
	v_mov_b32_e32 v202, v126
	v_mov_b32_e32 v203, v122
	v_add_u32_e32 v196, 0x1000, v134
	s_waitcnt lgkmcnt(2)
	v_pk_mul_f32 v[190:191], v[172:173], v[190:191] op_sel_hi:[0,1]
	v_ashrrev_i32_e32 v197, 31, v196
	v_lshlrev_b64 v[196:197], 6, v[196:197]
	v_ashrrev_i32_e32 v195, 31, v194
	s_waitcnt lgkmcnt(0)
	v_pk_mul_f32 v[188:189], v[172:173], v[188:189] op_sel_hi:[0,1]
	v_lshl_add_u64 v[196:197], v[176:177], 0, v[196:197]
	v_lshlrev_b64 v[194:195], 7, v[194:195]
	v_lshl_add_u64 v[194:195], v[174:175], 0, v[194:195]
	s_waitcnt vmcnt(1)
	v_mov_b32_e32 v207, v198
	s_waitcnt vmcnt(0)
	v_mov_b32_e32 v206, v200
	v_mov_b32_e32 v198, v201
	global_load_dwordx2 v[200:201], v[192:193], off offset:48
	s_nop 0
	global_load_dwordx2 v[192:193], v[192:193], off offset:32
	v_pk_mul_f32 v[202:203], v[202:203], v[206:207]
	s_waitcnt vmcnt(1)
	v_mov_b32_e32 v207, v200
	v_pk_fma_f32 v[190:191], v[190:191], v[198:199], v[202:203]
	v_mov_b32_e32 v202, v118
	v_mov_b32_e32 v203, v114
	s_waitcnt vmcnt(0)
	v_mov_b32_e32 v206, v192
	v_pk_mul_f32 v[202:203], v[202:203], v[206:207]
	v_mov_b32_e32 v200, v193
	v_cvt_pk_bf16_f32 v198, v190, v191
	v_pk_fma_f32 v[192:193], v[188:189], v[200:201], v[202:203]
	s_nop 0
	v_cvt_pk_bf16_f32 v199, v192, v193
	global_store_dwordx2 v[196:197], v[198:199], off nt
	global_store_dwordx4 v[194:195], v[190:193], off nt
.LBB0_289:
	s_or_b64 exec, exec, s[0:1]
	ds_bpermute_b32 v192, v129, v127
	ds_bpermute_b32 v193, v129, v123
	s_waitcnt lgkmcnt(3)
	ds_bpermute_b32 v188, v129, v119
	s_waitcnt lgkmcnt(3)
	ds_bpermute_b32 v189, v129, v115
	v_or_b32_e32 v190, 3, v168
	s_and_saveexec_b64 s[0:1], s[10:11]
	s_xor_b64 s[0:1], exec, s[0:1]
	s_cbranch_execz .LBB0_293
	s_and_saveexec_b64 s[72:73], s[8:9]
	s_cbranch_execz .LBB0_292
	v_ashrrev_i32_e32 v191, 31, v190
	s_waitcnt vmcnt(0)
	v_lshlrev_b64 v[180:181], 5, v[190:191]
	v_lshl_add_u64 v[184:185], v[170:171], 0, v[180:181]
	v_mov_b32_e32 v180, v127
	v_mov_b32_e32 v181, v123
	v_mov_b32_e32 v182, v119
	v_mov_b32_e32 v183, v115
	v_pk_mul_f32 v[180:181], v[180:181], s[88:89] op_sel_hi:[1,0]
	v_pk_mul_f32 v[182:183], v[182:183], s[88:89] op_sel_hi:[1,0]
	global_store_dwordx4 v[184:185], v[180:183], off offset:-128 nt

.LBB0_293:
	s_andn2_saveexec_b64 s[0:1], s[0:1]
	s_cbranch_execz .LBB0_295
	v_and_or_b32 v134, v190, 31, v141
	v_add_u32_e32 v194, 0x1000, v134
	v_ashrrev_i32_e32 v195, 31, v194
	s_waitcnt vmcnt(0)
	v_mov_b32_e32 v199, v180
	v_mov_b32_e32 v202, v186
	v_mov_b32_e32 v203, v184
	s_waitcnt lgkmcnt(2)
	v_pk_mul_f32 v[192:193], v[172:173], v[192:193] op_sel_hi:[0,1]
	v_mov_b32_e32 v184, v187
	s_waitcnt lgkmcnt(0)
	v_pk_mul_f32 v[186:187], v[172:173], v[188:189] op_sel_hi:[0,1]
	v_mov_b32_e32 v180, v183
	v_mov_b32_e32 v196, v119
	v_mov_b32_e32 v197, v115
	v_mov_b32_e32 v198, v182
	v_mov_b32_e32 v200, v127
	v_mov_b32_e32 v201, v123
	v_lshlrev_b64 v[194:195], 6, v[194:195]
	v_ashrrev_i32_e32 v191, 31, v190
	v_pk_mul_f32 v[184:185], v[184:185], v[192:193]
	v_pk_mul_f32 v[180:181], v[180:181], v[186:187]
	v_lshl_add_u64 v[194:195], v[176:177], 0, v[194:195]
	v_lshlrev_b64 v[190:191], 7, v[190:191]
	v_pk_fma_f32 v[184:185], v[200:201], v[202:203], v[184:185]
	v_pk_fma_f32 v[186:187], v[196:197], v[198:199], v[180:181]
	v_cvt_pk_bf16_f32 v182, v184, v185
	v_lshl_add_u64 v[190:191], v[174:175], 0, v[190:191]
	v_cvt_pk_bf16_f32 v183, v186, v187
	global_store_dwordx2 v[194:195], v[182:183], off nt
	global_store_dwordx4 v[190:191], v[184:187], off nt
.LBB0_295:
	s_or_b64 exec, exec, s[0:1]
	v_add_u32_e32 v194, 16, v168
	v_and_b32_e32 v141, 28, v194
	v_lshl_or_b32 v134, v141, 8, v131
	s_waitcnt lgkmcnt(2)
	v_lshl_add_u64 v[192:193], s[58:59], 0, v[134:135]
	s_waitcnt vmcnt(0)
	v_add_co_u32_e32 v180, vcc, 0x80000, v192
	ds_bpermute_b32 v190, v129, v108
	s_nop 0
	v_addc_co_u32_e32 v181, vcc, 0, v193, vcc
	global_load_dwordx2 v[186:187], v[180:181], off offset:256
	global_load_dwordx2 v[184:185], v[180:181], off offset:272
	global_load_dwordx2 v[182:183], v[180:181], off offset:288
	s_nop 0
	global_load_dwordx2 v[180:181], v[180:181], off offset:304
	ds_bpermute_b32 v191, v129, v104
	s_waitcnt lgkmcnt(3)
	ds_bpermute_b32 v188, v129, v100
	s_waitcnt lgkmcnt(3)
	ds_bpermute_b32 v189, v129, v96
	s_and_saveexec_b64 s[0:1], s[10:11]
	s_xor_b64 s[0:1], exec, s[0:1]
	s_cbranch_execz .LBB0_299
	s_and_saveexec_b64 s[72:73], s[8:9]
	s_cbranch_execz .LBB0_298
	v_ashrrev_i32_e32 v195, 31, v194
	s_waitcnt lgkmcnt(0)
	v_lshlrev_b64 v[188:189], 5, v[194:195]
	v_lshl_add_u64 v[192:193], v[170:171], 0, v[188:189]
	v_mov_b32_e32 v188, v108
	v_mov_b32_e32 v189, v104
	v_mov_b32_e32 v190, v100
	v_mov_b32_e32 v191, v96
	v_pk_mul_f32 v[188:189], v[188:189], s[88:89] op_sel_hi:[1,0]
	v_pk_mul_f32 v[190:191], v[190:191], s[88:89] op_sel_hi:[1,0]
	global_store_dwordx4 v[192:193], v[188:191], off offset:-128 nt

.LBB0_299:
	s_andn2_saveexec_b64 s[0:1], s[0:1]
	s_cbranch_execz .LBB0_301
	v_add_co_u32_e32 v192, vcc, 0x80000, v192
	v_lshrrev_b32_e32 v134, 5, v194
	s_nop 0
	v_addc_co_u32_e32 v193, vcc, 0, v193, vcc
	global_load_dwordx2 v[198:199], v[192:193], off offset:16
	global_load_dwordx2 v[200:201], v[192:193], off
	v_mul_lo_u32 v134, v134, s12
	v_or_b32_e32 v134, v134, v141
	v_mov_b32_e32 v202, v108
	v_mov_b32_e32 v203, v104
	v_add_u32_e32 v196, 0x1000, v134
	s_waitcnt lgkmcnt(2)
	v_pk_mul_f32 v[190:191], v[172:173], v[190:191] op_sel_hi:[0,1]
	v_ashrrev_i32_e32 v197, 31, v196
	v_lshlrev_b64 v[196:197], 6, v[196:197]
	v_ashrrev_i32_e32 v195, 31, v194
	s_waitcnt lgkmcnt(0)
	v_pk_mul_f32 v[188:189], v[172:173], v[188:189] op_sel_hi:[0,1]
	v_lshl_add_u64 v[196:197], v[176:177], 0, v[196:197]
	v_lshlrev_b64 v[194:195], 7, v[194:195]
	v_lshl_add_u64 v[194:195], v[174:175], 0, v[194:195]
	s_waitcnt vmcnt(1)
	v_mov_b32_e32 v207, v198
	s_waitcnt vmcnt(0)
	v_mov_b32_e32 v206, v200
	v_mov_b32_e32 v198, v201
	global_load_dwordx2 v[200:201], v[192:193], off offset:48
	s_nop 0
	global_load_dwordx2 v[192:193], v[192:193], off offset:32
	v_pk_mul_f32 v[202:203], v[202:203], v[206:207]
	s_waitcnt vmcnt(1)
	v_mov_b32_e32 v207, v200
	v_pk_fma_f32 v[190:191], v[190:191], v[198:199], v[202:203]
	v_mov_b32_e32 v202, v100
	v_mov_b32_e32 v203, v96
	s_waitcnt vmcnt(0)
	v_mov_b32_e32 v206, v192
	v_pk_mul_f32 v[202:203], v[202:203], v[206:207]
	v_mov_b32_e32 v200, v193
	v_cvt_pk_bf16_f32 v198, v190, v191
	v_pk_fma_f32 v[192:193], v[188:189], v[200:201], v[202:203]
	s_nop 0
	v_cvt_pk_bf16_f32 v199, v192, v193
	global_store_dwordx2 v[196:197], v[198:199], off nt
	global_store_dwordx4 v[194:195], v[190:193], off nt
.LBB0_301:
	s_or_b64 exec, exec, s[0:1]
	ds_bpermute_b32 v192, v129, v109
	ds_bpermute_b32 v193, v129, v105
	s_waitcnt lgkmcnt(3)
	ds_bpermute_b32 v188, v129, v101
	s_waitcnt lgkmcnt(3)
	ds_bpermute_b32 v189, v129, v97
	v_add_u32_e32 v190, 17, v168
	s_and_saveexec_b64 s[0:1], s[10:11]
	s_xor_b64 s[0:1], exec, s[0:1]
	s_cbranch_execz .LBB0_305
	s_and_saveexec_b64 s[72:73], s[8:9]
	s_cbranch_execz .LBB0_304
	v_ashrrev_i32_e32 v191, 31, v190
	s_waitcnt vmcnt(0)
	v_lshlrev_b64 v[180:181], 5, v[190:191]
	v_lshl_add_u64 v[184:185], v[170:171], 0, v[180:181]
	v_mov_b32_e32 v180, v109
	v_mov_b32_e32 v181, v105
	v_mov_b32_e32 v182, v101
	v_mov_b32_e32 v183, v97
	v_pk_mul_f32 v[180:181], v[180:181], s[88:89] op_sel_hi:[1,0]
	v_pk_mul_f32 v[182:183], v[182:183], s[88:89] op_sel_hi:[1,0]
	global_store_dwordx4 v[184:185], v[180:183], off offset:-128 nt

.LBB0_305:
	s_andn2_saveexec_b64 s[0:1], s[0:1]
	s_cbranch_execz .LBB0_307
	v_lshrrev_b32_e32 v134, 5, v190
	v_mul_lo_u32 v134, v134, s12
	v_and_or_b32 v134, v190, 29, v134
	v_add_u32_e32 v194, 0x1000, v134
	v_ashrrev_i32_e32 v195, 31, v194
	s_waitcnt vmcnt(0)
	v_mov_b32_e32 v199, v180
	v_mov_b32_e32 v202, v186
	v_mov_b32_e32 v203, v184
	s_waitcnt lgkmcnt(2)
	v_pk_mul_f32 v[192:193], v[172:173], v[192:193] op_sel_hi:[0,1]
	v_mov_b32_e32 v184, v187
	s_waitcnt lgkmcnt(0)
	v_pk_mul_f32 v[186:187], v[172:173], v[188:189] op_sel_hi:[0,1]
	v_mov_b32_e32 v180, v183
	v_mov_b32_e32 v196, v101
	v_mov_b32_e32 v197, v97
	v_mov_b32_e32 v198, v182
	v_mov_b32_e32 v200, v109
	v_mov_b32_e32 v201, v105
	v_lshlrev_b64 v[194:195], 6, v[194:195]
	v_ashrrev_i32_e32 v191, 31, v190
	v_pk_mul_f32 v[184:185], v[184:185], v[192:193]
	v_pk_mul_f32 v[180:181], v[180:181], v[186:187]
	v_lshl_add_u64 v[194:195], v[176:177], 0, v[194:195]
	v_lshlrev_b64 v[190:191], 7, v[190:191]
	v_pk_fma_f32 v[184:185], v[200:201], v[202:203], v[184:185]
	v_pk_fma_f32 v[186:187], v[196:197], v[198:199], v[180:181]
	v_cvt_pk_bf16_f32 v182, v184, v185
	v_lshl_add_u64 v[190:191], v[174:175], 0, v[190:191]
	v_cvt_pk_bf16_f32 v183, v186, v187
	global_store_dwordx2 v[194:195], v[182:183], off nt
	global_store_dwordx4 v[190:191], v[184:187], off nt
.LBB0_307:
	s_or_b64 exec, exec, s[0:1]
	v_add_u32_e32 v194, 18, v168
	v_and_b32_e32 v141, 30, v194
	v_lshl_or_b32 v134, v141, 8, v131
	s_waitcnt lgkmcnt(2)
	v_lshl_add_u64 v[192:193], s[58:59], 0, v[134:135]
	s_waitcnt vmcnt(0)
	v_add_co_u32_e32 v180, vcc, 0x80000, v192
	ds_bpermute_b32 v190, v129, v110
	s_nop 0
	v_addc_co_u32_e32 v181, vcc, 0, v193, vcc
	global_load_dwordx2 v[186:187], v[180:181], off offset:256
	global_load_dwordx2 v[184:185], v[180:181], off offset:272
	global_load_dwordx2 v[182:183], v[180:181], off offset:288
	s_nop 0
	global_load_dwordx2 v[180:181], v[180:181], off offset:304
	ds_bpermute_b32 v191, v129, v106
	s_waitcnt lgkmcnt(3)
	ds_bpermute_b32 v188, v129, v102
	s_waitcnt lgkmcnt(3)
	ds_bpermute_b32 v189, v129, v98
	s_and_saveexec_b64 s[0:1], s[10:11]
	s_xor_b64 s[0:1], exec, s[0:1]
	s_cbranch_execz .LBB0_311
	s_and_saveexec_b64 s[72:73], s[8:9]
	s_cbranch_execz .LBB0_310
	v_ashrrev_i32_e32 v195, 31, v194
	s_waitcnt lgkmcnt(0)
	v_lshlrev_b64 v[188:189], 5, v[194:195]
	v_lshl_add_u64 v[192:193], v[170:171], 0, v[188:189]
	v_mov_b32_e32 v188, v110
	v_mov_b32_e32 v189, v106
	v_mov_b32_e32 v190, v102
	v_mov_b32_e32 v191, v98
	v_pk_mul_f32 v[188:189], v[188:189], s[88:89] op_sel_hi:[1,0]
	v_pk_mul_f32 v[190:191], v[190:191], s[88:89] op_sel_hi:[1,0]
	global_store_dwordx4 v[192:193], v[188:191], off offset:-128 nt

.LBB0_311:
	s_andn2_saveexec_b64 s[0:1], s[0:1]
	s_cbranch_execz .LBB0_313
	v_add_co_u32_e32 v192, vcc, 0x80000, v192
	v_lshrrev_b32_e32 v134, 5, v194
	s_nop 0
	v_addc_co_u32_e32 v193, vcc, 0, v193, vcc
	global_load_dwordx2 v[198:199], v[192:193], off offset:16
	global_load_dwordx2 v[200:201], v[192:193], off
	v_mul_lo_u32 v134, v134, s12
	v_or_b32_e32 v134, v134, v141
	v_mov_b32_e32 v202, v110
	v_mov_b32_e32 v203, v106
	v_add_u32_e32 v196, 0x1000, v134
	s_waitcnt lgkmcnt(2)
	v_pk_mul_f32 v[190:191], v[172:173], v[190:191] op_sel_hi:[0,1]
	v_ashrrev_i32_e32 v197, 31, v196
	v_lshlrev_b64 v[196:197], 6, v[196:197]
	v_ashrrev_i32_e32 v195, 31, v194
	s_waitcnt lgkmcnt(0)
	v_pk_mul_f32 v[188:189], v[172:173], v[188:189] op_sel_hi:[0,1]
	v_lshl_add_u64 v[196:197], v[176:177], 0, v[196:197]
	v_lshlrev_b64 v[194:195], 7, v[194:195]
	v_lshl_add_u64 v[194:195], v[174:175], 0, v[194:195]
	s_waitcnt vmcnt(1)
	v_mov_b32_e32 v207, v198
	s_waitcnt vmcnt(0)
	v_mov_b32_e32 v206, v200
	v_mov_b32_e32 v198, v201
	global_load_dwordx2 v[200:201], v[192:193], off offset:48
	s_nop 0
	global_load_dwordx2 v[192:193], v[192:193], off offset:32
	v_pk_mul_f32 v[202:203], v[202:203], v[206:207]
	s_waitcnt vmcnt(1)
	v_mov_b32_e32 v207, v200
	v_pk_fma_f32 v[190:191], v[190:191], v[198:199], v[202:203]
	v_mov_b32_e32 v202, v102
	v_mov_b32_e32 v203, v98
	s_waitcnt vmcnt(0)
	v_mov_b32_e32 v206, v192
	v_pk_mul_f32 v[202:203], v[202:203], v[206:207]
	v_mov_b32_e32 v200, v193
	v_cvt_pk_bf16_f32 v198, v190, v191
	v_pk_fma_f32 v[192:193], v[188:189], v[200:201], v[202:203]
	s_nop 0
	v_cvt_pk_bf16_f32 v199, v192, v193
	global_store_dwordx2 v[196:197], v[198:199], off nt
	global_store_dwordx4 v[194:195], v[190:193], off nt
.LBB0_313:
	s_or_b64 exec, exec, s[0:1]
	ds_bpermute_b32 v192, v129, v111
	ds_bpermute_b32 v193, v129, v107
	s_waitcnt lgkmcnt(3)
	ds_bpermute_b32 v188, v129, v103
	s_waitcnt lgkmcnt(3)
	ds_bpermute_b32 v189, v129, v99
	v_add_u32_e32 v190, 19, v168
	s_and_saveexec_b64 s[0:1], s[10:11]
	s_xor_b64 s[0:1], exec, s[0:1]
	s_cbranch_execz .LBB0_317
	s_and_saveexec_b64 s[72:73], s[8:9]
	s_cbranch_execz .LBB0_316
	v_ashrrev_i32_e32 v191, 31, v190
	s_waitcnt vmcnt(0)
	v_lshlrev_b64 v[180:181], 5, v[190:191]
	v_lshl_add_u64 v[184:185], v[170:171], 0, v[180:181]
	v_mov_b32_e32 v180, v111
	v_mov_b32_e32 v181, v107
	v_mov_b32_e32 v182, v103
	v_mov_b32_e32 v183, v99
	v_pk_mul_f32 v[180:181], v[180:181], s[88:89] op_sel_hi:[1,0]
	v_pk_mul_f32 v[182:183], v[182:183], s[88:89] op_sel_hi:[1,0]
	global_store_dwordx4 v[184:185], v[180:183], off offset:-128 nt

.LBB0_317:
	s_andn2_saveexec_b64 s[0:1], s[0:1]
	s_cbranch_execz .LBB0_319
	v_lshrrev_b32_e32 v134, 5, v190
	v_mul_lo_u32 v134, v134, s12
	v_and_or_b32 v134, v190, 31, v134
	v_add_u32_e32 v194, 0x1000, v134
	v_ashrrev_i32_e32 v195, 31, v194
	s_waitcnt vmcnt(0)
	v_mov_b32_e32 v199, v180
	v_mov_b32_e32 v202, v186
	v_mov_b32_e32 v203, v184
	s_waitcnt lgkmcnt(2)
	v_pk_mul_f32 v[192:193], v[172:173], v[192:193] op_sel_hi:[0,1]
	v_mov_b32_e32 v184, v187
	s_waitcnt lgkmcnt(0)
	v_pk_mul_f32 v[186:187], v[172:173], v[188:189] op_sel_hi:[0,1]
	v_mov_b32_e32 v180, v183
	v_mov_b32_e32 v196, v103
	v_mov_b32_e32 v197, v99
	v_mov_b32_e32 v198, v182
	v_mov_b32_e32 v200, v111
	v_mov_b32_e32 v201, v107
	v_lshlrev_b64 v[194:195], 6, v[194:195]
	v_ashrrev_i32_e32 v191, 31, v190
	v_pk_mul_f32 v[184:185], v[184:185], v[192:193]
	v_pk_mul_f32 v[180:181], v[180:181], v[186:187]
	v_lshl_add_u64 v[194:195], v[176:177], 0, v[194:195]
	v_lshlrev_b64 v[190:191], 7, v[190:191]
	v_pk_fma_f32 v[184:185], v[200:201], v[202:203], v[184:185]
	v_pk_fma_f32 v[186:187], v[196:197], v[198:199], v[180:181]
	v_cvt_pk_bf16_f32 v182, v184, v185
	v_lshl_add_u64 v[190:191], v[174:175], 0, v[190:191]
	v_cvt_pk_bf16_f32 v183, v186, v187
	global_store_dwordx2 v[194:195], v[182:183], off nt
	global_store_dwordx4 v[190:191], v[184:187], off nt
.LBB0_319:
	s_or_b64 exec, exec, s[0:1]
	s_mov_b64 s[0:1], 0x80100
	s_waitcnt vmcnt(0)
	v_lshl_add_u64 v[180:181], v[178:179], 0, s[0:1]
	s_mov_b64 s[0:1], 0x80110
	v_lshl_add_u64 v[182:183], v[178:179], 0, s[0:1]
	s_mov_b64 s[0:1], 0x80120
	v_lshl_add_u64 v[184:185], v[178:179], 0, s[0:1]
	s_mov_b64 s[0:1], 0x80130
	v_lshl_add_u64 v[186:187], v[178:179], 0, s[0:1]
	v_add_u32_e32 v200, 32, v168
	global_load_dwordx2 v[194:195], v[180:181], off
	s_waitcnt lgkmcnt(2)
	global_load_dwordx2 v[192:193], v[182:183], off
	global_load_dwordx2 v[190:191], v[184:185], off
	s_waitcnt lgkmcnt(0)
	global_load_dwordx2 v[188:189], v[186:187], off
	ds_bpermute_b32 v198, v129, v92
	ds_bpermute_b32 v199, v129, v88
	ds_bpermute_b32 v196, v129, v84
	ds_bpermute_b32 v197, v129, v80
	s_and_saveexec_b64 s[0:1], s[10:11]
	s_xor_b64 s[0:1], exec, s[0:1]
	s_cbranch_execz .LBB0_323
	s_and_saveexec_b64 s[72:73], s[8:9]
	s_cbranch_execz .LBB0_322
	v_ashrrev_i32_e32 v201, 31, v200
	s_waitcnt lgkmcnt(0)
	v_lshlrev_b64 v[196:197], 5, v[200:201]
	v_lshl_add_u64 v[200:201], v[170:171], 0, v[196:197]
	v_mov_b32_e32 v196, v92
	v_mov_b32_e32 v197, v88
	v_mov_b32_e32 v198, v84
	v_mov_b32_e32 v199, v80
	v_pk_mul_f32 v[196:197], v[196:197], s[88:89] op_sel_hi:[1,0]
	v_pk_mul_f32 v[198:199], v[198:199], s[88:89] op_sel_hi:[1,0]
	global_store_dwordx4 v[200:201], v[196:199], off offset:-128 nt

.LBB0_323:
	s_andn2_saveexec_b64 s[0:1], s[0:1]
	s_cbranch_execz .LBB0_325
	v_ashrrev_i32_e32 v201, 31, v200
	v_lshrrev_b32_e32 v134, 5, v200
	v_lshlrev_b64 v[200:201], 7, v[200:201]
	v_lshl_add_u64 v[206:207], v[174:175], 0, v[200:201]
	v_add_co_u32_e32 v200, vcc, 0x80000, v178
	v_mul_lo_u32 v134, v134, s12
	s_nop 0
	v_addc_co_u32_e32 v201, vcc, 0, v179, vcc
	global_load_dwordx2 v[208:209], v[200:201], off offset:16
	global_load_dwordx2 v[214:215], v[200:201], off
	v_or_b32_e32 v134, v134, v139
	v_mov_b32_e32 v216, v92
	v_mov_b32_e32 v217, v88
	v_add_u32_e32 v202, 0x1000, v134
	s_waitcnt lgkmcnt(2)
	v_pk_mul_f32 v[198:199], v[172:173], v[198:199] op_sel_hi:[0,1]
	v_ashrrev_i32_e32 v203, 31, v202
	v_lshlrev_b64 v[202:203], 6, v[202:203]
	s_waitcnt lgkmcnt(0)
	v_pk_mul_f32 v[196:197], v[172:173], v[196:197] op_sel_hi:[0,1]
	v_lshl_add_u64 v[202:203], v[176:177], 0, v[202:203]
	s_waitcnt vmcnt(1)
	v_mov_b32_e32 v219, v208
	s_waitcnt vmcnt(0)
	v_mov_b32_e32 v218, v214
	v_mov_b32_e32 v208, v215
	global_load_dwordx2 v[214:215], v[200:201], off offset:48
	s_nop 0
	global_load_dwordx2 v[200:201], v[200:201], off offset:32
	v_pk_mul_f32 v[216:217], v[216:217], v[218:219]
	s_waitcnt vmcnt(1)
	v_mov_b32_e32 v219, v214
	v_pk_fma_f32 v[198:199], v[198:199], v[208:209], v[216:217]
	v_mov_b32_e32 v216, v84
	v_mov_b32_e32 v217, v80
	s_waitcnt vmcnt(0)
	v_mov_b32_e32 v218, v200
	v_pk_mul_f32 v[216:217], v[216:217], v[218:219]
	v_mov_b32_e32 v214, v201
	v_cvt_pk_bf16_f32 v208, v198, v199
	v_pk_fma_f32 v[200:201], v[196:197], v[214:215], v[216:217]
	s_nop 0
	v_cvt_pk_bf16_f32 v209, v200, v201
	global_store_dwordx2 v[202:203], v[208:209], off nt
	global_store_dwordx4 v[206:207], v[198:201], off nt
.LBB0_325:
	s_or_b64 exec, exec, s[0:1]
	ds_bpermute_b32 v200, v129, v93
	ds_bpermute_b32 v201, v129, v89
	s_waitcnt lgkmcnt(3)
	ds_bpermute_b32 v196, v129, v85
	s_waitcnt lgkmcnt(3)
	ds_bpermute_b32 v197, v129, v81
	v_add_u32_e32 v198, 33, v168
	s_and_saveexec_b64 s[0:1], s[10:11]
	s_xor_b64 s[0:1], exec, s[0:1]
	s_cbranch_execz .LBB0_329
	s_and_saveexec_b64 s[72:73], s[8:9]
	s_cbranch_execz .LBB0_328
	v_ashrrev_i32_e32 v199, 31, v198
	s_waitcnt vmcnt(0)
	v_lshlrev_b64 v[188:189], 5, v[198:199]
	v_lshl_add_u64 v[192:193], v[170:171], 0, v[188:189]
	v_mov_b32_e32 v188, v93
	v_mov_b32_e32 v189, v89
	v_mov_b32_e32 v190, v85
	v_mov_b32_e32 v191, v81
	v_pk_mul_f32 v[188:189], v[188:189], s[88:89] op_sel_hi:[1,0]
	v_pk_mul_f32 v[190:191], v[190:191], s[88:89] op_sel_hi:[1,0]
	global_store_dwordx4 v[192:193], v[188:191], off offset:-128 nt

.LBB0_329:
	s_andn2_saveexec_b64 s[0:1], s[0:1]
	s_cbranch_execz .LBB0_331
	v_lshrrev_b32_e32 v134, 5, v198
	v_mul_lo_u32 v134, v134, s12
	v_and_or_b32 v134, v198, 29, v134
	v_add_u32_e32 v202, 0x1000, v134
	v_ashrrev_i32_e32 v203, 31, v202
	s_waitcnt vmcnt(0)
	v_mov_b32_e32 v209, v188
	v_mov_b32_e32 v216, v194
	v_mov_b32_e32 v217, v192
	s_waitcnt lgkmcnt(2)
	v_pk_mul_f32 v[200:201], v[172:173], v[200:201] op_sel_hi:[0,1]
	v_mov_b32_e32 v192, v195
	s_waitcnt lgkmcnt(0)
	v_pk_mul_f32 v[194:195], v[172:173], v[196:197] op_sel_hi:[0,1]
	v_mov_b32_e32 v188, v191
	v_mov_b32_e32 v206, v85
	v_mov_b32_e32 v207, v81
	v_mov_b32_e32 v208, v190
	v_mov_b32_e32 v214, v93
	v_mov_b32_e32 v215, v89
	v_lshlrev_b64 v[202:203], 6, v[202:203]
	v_ashrrev_i32_e32 v199, 31, v198
	v_pk_mul_f32 v[192:193], v[192:193], v[200:201]
	v_pk_mul_f32 v[188:189], v[188:189], v[194:195]
	v_lshl_add_u64 v[202:203], v[176:177], 0, v[202:203]
	v_lshlrev_b64 v[198:199], 7, v[198:199]
	v_pk_fma_f32 v[192:193], v[214:215], v[216:217], v[192:193]
	v_pk_fma_f32 v[194:195], v[206:207], v[208:209], v[188:189]
	v_cvt_pk_bf16_f32 v190, v192, v193
	v_lshl_add_u64 v[198:199], v[174:175], 0, v[198:199]
	v_cvt_pk_bf16_f32 v191, v194, v195
	global_store_dwordx2 v[202:203], v[190:191], off nt
	global_store_dwordx4 v[198:199], v[192:195], off nt
.LBB0_331:
	s_or_b64 exec, exec, s[0:1]
	v_add_u32_e32 v202, 34, v168
	v_and_b32_e32 v141, 30, v202
	v_lshl_or_b32 v134, v141, 8, v131
	s_waitcnt lgkmcnt(2)
	v_lshl_add_u64 v[200:201], s[58:59], 0, v[134:135]
	s_waitcnt vmcnt(0)
	v_add_co_u32_e32 v188, vcc, 0x80000, v200
	ds_bpermute_b32 v198, v129, v94
	s_nop 0
	v_addc_co_u32_e32 v189, vcc, 0, v201, vcc
	global_load_dwordx2 v[194:195], v[188:189], off offset:256
	global_load_dwordx2 v[192:193], v[188:189], off offset:272
	global_load_dwordx2 v[190:191], v[188:189], off offset:288
	s_nop 0
	global_load_dwordx2 v[188:189], v[188:189], off offset:304
	ds_bpermute_b32 v199, v129, v90
	s_waitcnt lgkmcnt(3)
	ds_bpermute_b32 v196, v129, v86
	s_waitcnt lgkmcnt(3)
	ds_bpermute_b32 v197, v129, v82
	s_and_saveexec_b64 s[0:1], s[10:11]
	s_xor_b64 s[0:1], exec, s[0:1]
	s_cbranch_execz .LBB0_335
	s_and_saveexec_b64 s[72:73], s[8:9]
	s_cbranch_execz .LBB0_334
	v_ashrrev_i32_e32 v203, 31, v202
	s_waitcnt lgkmcnt(0)
	v_lshlrev_b64 v[196:197], 5, v[202:203]
	v_lshl_add_u64 v[200:201], v[170:171], 0, v[196:197]
	v_mov_b32_e32 v196, v94
	v_mov_b32_e32 v197, v90
	v_mov_b32_e32 v198, v86
	v_mov_b32_e32 v199, v82
	v_pk_mul_f32 v[196:197], v[196:197], s[88:89] op_sel_hi:[1,0]
	v_pk_mul_f32 v[198:199], v[198:199], s[88:89] op_sel_hi:[1,0]
	global_store_dwordx4 v[200:201], v[196:199], off offset:-128 nt

.LBB0_335:
	s_andn2_saveexec_b64 s[0:1], s[0:1]
	s_cbranch_execz .LBB0_337
	v_add_co_u32_e32 v200, vcc, 0x80000, v200
	v_lshrrev_b32_e32 v134, 5, v202
	s_nop 0
	v_addc_co_u32_e32 v201, vcc, 0, v201, vcc
	global_load_dwordx2 v[208:209], v[200:201], off offset:16
	global_load_dwordx2 v[214:215], v[200:201], off
	v_mul_lo_u32 v134, v134, s12
	v_or_b32_e32 v134, v134, v141
	v_mov_b32_e32 v216, v94
	v_mov_b32_e32 v217, v90
	v_add_u32_e32 v206, 0x1000, v134
	s_waitcnt lgkmcnt(2)
	v_pk_mul_f32 v[198:199], v[172:173], v[198:199] op_sel_hi:[0,1]
	v_ashrrev_i32_e32 v207, 31, v206
	v_lshlrev_b64 v[206:207], 6, v[206:207]
	v_ashrrev_i32_e32 v203, 31, v202
	s_waitcnt lgkmcnt(0)
	v_pk_mul_f32 v[196:197], v[172:173], v[196:197] op_sel_hi:[0,1]
	v_lshl_add_u64 v[206:207], v[176:177], 0, v[206:207]
	v_lshlrev_b64 v[202:203], 7, v[202:203]
	v_lshl_add_u64 v[202:203], v[174:175], 0, v[202:203]
	s_waitcnt vmcnt(1)
	v_mov_b32_e32 v219, v208
	s_waitcnt vmcnt(0)
	v_mov_b32_e32 v218, v214
	v_mov_b32_e32 v208, v215
	global_load_dwordx2 v[214:215], v[200:201], off offset:48
	s_nop 0
	global_load_dwordx2 v[200:201], v[200:201], off offset:32
	v_pk_mul_f32 v[216:217], v[216:217], v[218:219]
	s_waitcnt vmcnt(1)
	v_mov_b32_e32 v219, v214
	v_pk_fma_f32 v[198:199], v[198:199], v[208:209], v[216:217]
	v_mov_b32_e32 v216, v86
	v_mov_b32_e32 v217, v82
	s_waitcnt vmcnt(0)
	v_mov_b32_e32 v218, v200
	v_pk_mul_f32 v[216:217], v[216:217], v[218:219]
	v_mov_b32_e32 v214, v201
	v_cvt_pk_bf16_f32 v208, v198, v199
	v_pk_fma_f32 v[200:201], v[196:197], v[214:215], v[216:217]
	s_nop 0
	v_cvt_pk_bf16_f32 v209, v200, v201
	global_store_dwordx2 v[206:207], v[208:209], off nt
	global_store_dwordx4 v[202:203], v[198:201], off nt
.LBB0_337:
	s_or_b64 exec, exec, s[0:1]
	ds_bpermute_b32 v200, v129, v95
	ds_bpermute_b32 v201, v129, v91
	s_waitcnt lgkmcnt(3)
	ds_bpermute_b32 v196, v129, v87
	s_waitcnt lgkmcnt(3)
	ds_bpermute_b32 v197, v129, v83
	v_add_u32_e32 v198, 35, v168
	s_and_saveexec_b64 s[0:1], s[10:11]
	s_xor_b64 s[0:1], exec, s[0:1]
	s_cbranch_execz .LBB0_341
	s_and_saveexec_b64 s[72:73], s[8:9]
	s_cbranch_execz .LBB0_340
	v_ashrrev_i32_e32 v199, 31, v198
	s_waitcnt vmcnt(0)
	v_lshlrev_b64 v[188:189], 5, v[198:199]
	v_lshl_add_u64 v[192:193], v[170:171], 0, v[188:189]
	v_mov_b32_e32 v188, v95
	v_mov_b32_e32 v189, v91
	v_mov_b32_e32 v190, v87
	v_mov_b32_e32 v191, v83
	v_pk_mul_f32 v[188:189], v[188:189], s[88:89] op_sel_hi:[1,0]
	v_pk_mul_f32 v[190:191], v[190:191], s[88:89] op_sel_hi:[1,0]
	global_store_dwordx4 v[192:193], v[188:191], off offset:-128 nt

.LBB0_341:
	s_andn2_saveexec_b64 s[0:1], s[0:1]
	s_cbranch_execz .LBB0_343
	v_lshrrev_b32_e32 v134, 5, v198
	v_mul_lo_u32 v134, v134, s12
	v_and_or_b32 v134, v198, 31, v134
	v_add_u32_e32 v202, 0x1000, v134
	v_ashrrev_i32_e32 v203, 31, v202
	s_waitcnt vmcnt(0)
	v_mov_b32_e32 v209, v188
	v_mov_b32_e32 v216, v194
	v_mov_b32_e32 v217, v192
	s_waitcnt lgkmcnt(2)
	v_pk_mul_f32 v[200:201], v[172:173], v[200:201] op_sel_hi:[0,1]
	v_mov_b32_e32 v192, v195
	s_waitcnt lgkmcnt(0)
	v_pk_mul_f32 v[194:195], v[172:173], v[196:197] op_sel_hi:[0,1]
	v_mov_b32_e32 v188, v191
	v_mov_b32_e32 v206, v87
	v_mov_b32_e32 v207, v83
	v_mov_b32_e32 v208, v190
	v_mov_b32_e32 v214, v95
	v_mov_b32_e32 v215, v91
	v_lshlrev_b64 v[202:203], 6, v[202:203]
	v_ashrrev_i32_e32 v199, 31, v198
	v_pk_mul_f32 v[192:193], v[192:193], v[200:201]
	v_pk_mul_f32 v[188:189], v[188:189], v[194:195]
	v_lshl_add_u64 v[202:203], v[176:177], 0, v[202:203]
	v_lshlrev_b64 v[198:199], 7, v[198:199]
	v_pk_fma_f32 v[192:193], v[214:215], v[216:217], v[192:193]
	v_pk_fma_f32 v[194:195], v[206:207], v[208:209], v[188:189]
	v_cvt_pk_bf16_f32 v190, v192, v193
	v_lshl_add_u64 v[198:199], v[174:175], 0, v[198:199]
	v_cvt_pk_bf16_f32 v191, v194, v195
	global_store_dwordx2 v[202:203], v[190:191], off nt
	global_store_dwordx4 v[198:199], v[192:195], off nt
.LBB0_343:
	s_or_b64 exec, exec, s[0:1]
	v_add_u32_e32 v202, 48, v168
	v_and_b32_e32 v141, 28, v202
	v_lshl_or_b32 v134, v141, 8, v131
	s_waitcnt lgkmcnt(2)
	v_lshl_add_u64 v[200:201], s[58:59], 0, v[134:135]
	s_waitcnt vmcnt(0)
	v_add_co_u32_e32 v188, vcc, 0x80000, v200
	ds_bpermute_b32 v198, v129, v76
	s_nop 0
	v_addc_co_u32_e32 v189, vcc, 0, v201, vcc
	global_load_dwordx2 v[194:195], v[188:189], off offset:256
	global_load_dwordx2 v[192:193], v[188:189], off offset:272
	global_load_dwordx2 v[190:191], v[188:189], off offset:288
	s_nop 0
	global_load_dwordx2 v[188:189], v[188:189], off offset:304
	ds_bpermute_b32 v199, v129, v72
	s_waitcnt lgkmcnt(3)
	ds_bpermute_b32 v196, v129, v68
	s_waitcnt lgkmcnt(3)
	ds_bpermute_b32 v197, v129, v64
	s_and_saveexec_b64 s[0:1], s[10:11]
	s_xor_b64 s[0:1], exec, s[0:1]
	s_cbranch_execz .LBB0_347
	s_and_saveexec_b64 s[72:73], s[8:9]
	s_cbranch_execz .LBB0_346
	v_ashrrev_i32_e32 v203, 31, v202
	s_waitcnt lgkmcnt(0)
	v_lshlrev_b64 v[196:197], 5, v[202:203]
	v_lshl_add_u64 v[200:201], v[170:171], 0, v[196:197]
	v_mov_b32_e32 v196, v76
	v_mov_b32_e32 v197, v72
	v_mov_b32_e32 v198, v68
	v_mov_b32_e32 v199, v64
	v_pk_mul_f32 v[196:197], v[196:197], s[88:89] op_sel_hi:[1,0]
	v_pk_mul_f32 v[198:199], v[198:199], s[88:89] op_sel_hi:[1,0]
	global_store_dwordx4 v[200:201], v[196:199], off offset:-128 nt

.LBB0_347:
	s_andn2_saveexec_b64 s[0:1], s[0:1]
	s_cbranch_execz .LBB0_349
	v_add_co_u32_e32 v200, vcc, 0x80000, v200
	v_lshrrev_b32_e32 v134, 5, v202
	s_nop 0
	v_addc_co_u32_e32 v201, vcc, 0, v201, vcc
	global_load_dwordx2 v[208:209], v[200:201], off offset:16
	global_load_dwordx2 v[214:215], v[200:201], off
	v_mul_lo_u32 v134, v134, s12
	v_or_b32_e32 v134, v134, v141
	v_mov_b32_e32 v216, v76
	v_mov_b32_e32 v217, v72
	v_add_u32_e32 v206, 0x1000, v134
	s_waitcnt lgkmcnt(2)
	v_pk_mul_f32 v[198:199], v[172:173], v[198:199] op_sel_hi:[0,1]
	v_ashrrev_i32_e32 v207, 31, v206
	v_lshlrev_b64 v[206:207], 6, v[206:207]
	v_ashrrev_i32_e32 v203, 31, v202
	s_waitcnt lgkmcnt(0)
	v_pk_mul_f32 v[196:197], v[172:173], v[196:197] op_sel_hi:[0,1]
	v_lshl_add_u64 v[206:207], v[176:177], 0, v[206:207]
	v_lshlrev_b64 v[202:203], 7, v[202:203]
	v_lshl_add_u64 v[202:203], v[174:175], 0, v[202:203]
	s_waitcnt vmcnt(1)
	v_mov_b32_e32 v219, v208
	s_waitcnt vmcnt(0)
	v_mov_b32_e32 v218, v214
	v_mov_b32_e32 v208, v215
	global_load_dwordx2 v[214:215], v[200:201], off offset:48
	s_nop 0
	global_load_dwordx2 v[200:201], v[200:201], off offset:32
	v_pk_mul_f32 v[216:217], v[216:217], v[218:219]
	s_waitcnt vmcnt(1)
	v_mov_b32_e32 v219, v214
	v_pk_fma_f32 v[198:199], v[198:199], v[208:209], v[216:217]
	v_mov_b32_e32 v216, v68
	v_mov_b32_e32 v217, v64
	s_waitcnt vmcnt(0)
	v_mov_b32_e32 v218, v200
	v_pk_mul_f32 v[216:217], v[216:217], v[218:219]
	v_mov_b32_e32 v214, v201
	v_cvt_pk_bf16_f32 v208, v198, v199
	v_pk_fma_f32 v[200:201], v[196:197], v[214:215], v[216:217]
	s_nop 0
	v_cvt_pk_bf16_f32 v209, v200, v201
	global_store_dwordx2 v[206:207], v[208:209], off nt
	global_store_dwordx4 v[202:203], v[198:201], off nt
.LBB0_349:
	s_or_b64 exec, exec, s[0:1]
	ds_bpermute_b32 v200, v129, v77
	ds_bpermute_b32 v201, v129, v73
	s_waitcnt lgkmcnt(3)
	ds_bpermute_b32 v196, v129, v69
	s_waitcnt lgkmcnt(3)
	ds_bpermute_b32 v197, v129, v65
	v_add_u32_e32 v198, 49, v168
	s_and_saveexec_b64 s[0:1], s[10:11]
	s_xor_b64 s[0:1], exec, s[0:1]
	s_cbranch_execz .LBB0_353
	s_and_saveexec_b64 s[72:73], s[8:9]
	s_cbranch_execz .LBB0_352
	v_ashrrev_i32_e32 v199, 31, v198
	s_waitcnt vmcnt(0)
	v_lshlrev_b64 v[188:189], 5, v[198:199]
	v_lshl_add_u64 v[192:193], v[170:171], 0, v[188:189]
	v_mov_b32_e32 v188, v77
	v_mov_b32_e32 v189, v73
	v_mov_b32_e32 v190, v69
	v_mov_b32_e32 v191, v65
	v_pk_mul_f32 v[188:189], v[188:189], s[88:89] op_sel_hi:[1,0]
	v_pk_mul_f32 v[190:191], v[190:191], s[88:89] op_sel_hi:[1,0]
	global_store_dwordx4 v[192:193], v[188:191], off offset:-128 nt

.LBB0_353:
	s_andn2_saveexec_b64 s[0:1], s[0:1]
	s_cbranch_execz .LBB0_355
	v_lshrrev_b32_e32 v134, 5, v198
	v_mul_lo_u32 v134, v134, s12
	v_and_or_b32 v134, v198, 29, v134
	v_add_u32_e32 v202, 0x1000, v134
	v_ashrrev_i32_e32 v203, 31, v202
	s_waitcnt vmcnt(0)
	v_mov_b32_e32 v209, v188
	v_mov_b32_e32 v216, v194
	v_mov_b32_e32 v217, v192
	s_waitcnt lgkmcnt(2)
	v_pk_mul_f32 v[200:201], v[172:173], v[200:201] op_sel_hi:[0,1]
	v_mov_b32_e32 v192, v195
	s_waitcnt lgkmcnt(0)
	v_pk_mul_f32 v[194:195], v[172:173], v[196:197] op_sel_hi:[0,1]
	v_mov_b32_e32 v188, v191
	v_mov_b32_e32 v206, v69
	v_mov_b32_e32 v207, v65
	v_mov_b32_e32 v208, v190
	v_mov_b32_e32 v214, v77
	v_mov_b32_e32 v215, v73
	v_lshlrev_b64 v[202:203], 6, v[202:203]
	v_ashrrev_i32_e32 v199, 31, v198
	v_pk_mul_f32 v[192:193], v[192:193], v[200:201]
	v_pk_mul_f32 v[188:189], v[188:189], v[194:195]
	v_lshl_add_u64 v[202:203], v[176:177], 0, v[202:203]
	v_lshlrev_b64 v[198:199], 7, v[198:199]
	v_pk_fma_f32 v[192:193], v[214:215], v[216:217], v[192:193]
	v_pk_fma_f32 v[194:195], v[206:207], v[208:209], v[188:189]
	v_cvt_pk_bf16_f32 v190, v192, v193
	v_lshl_add_u64 v[198:199], v[174:175], 0, v[198:199]
	v_cvt_pk_bf16_f32 v191, v194, v195
	global_store_dwordx2 v[202:203], v[190:191], off nt
	global_store_dwordx4 v[198:199], v[192:195], off nt
.LBB0_355:
	s_or_b64 exec, exec, s[0:1]
	v_add_u32_e32 v202, 50, v168
	v_and_b32_e32 v141, 30, v202
	v_lshl_or_b32 v134, v141, 8, v131
	s_waitcnt lgkmcnt(2)
	v_lshl_add_u64 v[200:201], s[58:59], 0, v[134:135]
	s_waitcnt vmcnt(0)
	v_add_co_u32_e32 v188, vcc, 0x80000, v200
	ds_bpermute_b32 v198, v129, v78
	s_nop 0
	v_addc_co_u32_e32 v189, vcc, 0, v201, vcc
	global_load_dwordx2 v[194:195], v[188:189], off offset:256
	global_load_dwordx2 v[192:193], v[188:189], off offset:272
	global_load_dwordx2 v[190:191], v[188:189], off offset:288
	s_nop 0
	global_load_dwordx2 v[188:189], v[188:189], off offset:304
	ds_bpermute_b32 v199, v129, v74
	s_waitcnt lgkmcnt(3)
	ds_bpermute_b32 v196, v129, v70
	s_waitcnt lgkmcnt(3)
	ds_bpermute_b32 v197, v129, v66
	s_and_saveexec_b64 s[0:1], s[10:11]
	s_xor_b64 s[0:1], exec, s[0:1]
	s_cbranch_execz .LBB0_359
	s_and_saveexec_b64 s[72:73], s[8:9]
	s_cbranch_execz .LBB0_358
	v_ashrrev_i32_e32 v203, 31, v202
	s_waitcnt lgkmcnt(0)
	v_lshlrev_b64 v[196:197], 5, v[202:203]
	v_lshl_add_u64 v[200:201], v[170:171], 0, v[196:197]
	v_mov_b32_e32 v196, v78
	v_mov_b32_e32 v197, v74
	v_mov_b32_e32 v198, v70
	v_mov_b32_e32 v199, v66
	v_pk_mul_f32 v[196:197], v[196:197], s[88:89] op_sel_hi:[1,0]
	v_pk_mul_f32 v[198:199], v[198:199], s[88:89] op_sel_hi:[1,0]
	global_store_dwordx4 v[200:201], v[196:199], off offset:-128 nt

.LBB0_359:
	s_andn2_saveexec_b64 s[0:1], s[0:1]
	s_cbranch_execz .LBB0_361
	v_add_co_u32_e32 v200, vcc, 0x80000, v200
	v_lshrrev_b32_e32 v134, 5, v202
	s_nop 0
	v_addc_co_u32_e32 v201, vcc, 0, v201, vcc
	global_load_dwordx2 v[208:209], v[200:201], off offset:16
	global_load_dwordx2 v[214:215], v[200:201], off
	v_mul_lo_u32 v134, v134, s12
	v_or_b32_e32 v134, v134, v141
	v_mov_b32_e32 v216, v78
	v_mov_b32_e32 v217, v74
	v_add_u32_e32 v206, 0x1000, v134
	s_waitcnt lgkmcnt(2)
	v_pk_mul_f32 v[198:199], v[172:173], v[198:199] op_sel_hi:[0,1]
	v_ashrrev_i32_e32 v207, 31, v206
	v_lshlrev_b64 v[206:207], 6, v[206:207]
	v_ashrrev_i32_e32 v203, 31, v202
	s_waitcnt lgkmcnt(0)
	v_pk_mul_f32 v[196:197], v[172:173], v[196:197] op_sel_hi:[0,1]
	v_lshl_add_u64 v[206:207], v[176:177], 0, v[206:207]
	v_lshlrev_b64 v[202:203], 7, v[202:203]
	v_lshl_add_u64 v[202:203], v[174:175], 0, v[202:203]
	s_waitcnt vmcnt(1)
	v_mov_b32_e32 v219, v208
	s_waitcnt vmcnt(0)
	v_mov_b32_e32 v218, v214
	v_mov_b32_e32 v208, v215
	global_load_dwordx2 v[214:215], v[200:201], off offset:48
	s_nop 0
	global_load_dwordx2 v[200:201], v[200:201], off offset:32
	v_pk_mul_f32 v[216:217], v[216:217], v[218:219]
	s_waitcnt vmcnt(1)
	v_mov_b32_e32 v219, v214
	v_pk_fma_f32 v[198:199], v[198:199], v[208:209], v[216:217]
	v_mov_b32_e32 v216, v70
	v_mov_b32_e32 v217, v66
	s_waitcnt vmcnt(0)
	v_mov_b32_e32 v218, v200
	v_pk_mul_f32 v[216:217], v[216:217], v[218:219]
	v_mov_b32_e32 v214, v201
	v_cvt_pk_bf16_f32 v208, v198, v199
	v_pk_fma_f32 v[200:201], v[196:197], v[214:215], v[216:217]
	s_nop 0
	v_cvt_pk_bf16_f32 v209, v200, v201
	global_store_dwordx2 v[206:207], v[208:209], off nt
	global_store_dwordx4 v[202:203], v[198:201], off nt
.LBB0_361:
	s_or_b64 exec, exec, s[0:1]
	ds_bpermute_b32 v200, v129, v79
	ds_bpermute_b32 v201, v129, v75
	s_waitcnt lgkmcnt(3)
	ds_bpermute_b32 v196, v129, v71
	s_waitcnt lgkmcnt(3)
	ds_bpermute_b32 v197, v129, v67
	v_add_u32_e32 v198, 51, v168
	s_and_saveexec_b64 s[0:1], s[10:11]
	s_xor_b64 s[0:1], exec, s[0:1]
	s_cbranch_execz .LBB0_365
	s_and_saveexec_b64 s[72:73], s[8:9]
	s_cbranch_execz .LBB0_364
	v_ashrrev_i32_e32 v199, 31, v198
	s_waitcnt vmcnt(0)
	v_lshlrev_b64 v[188:189], 5, v[198:199]
	v_lshl_add_u64 v[192:193], v[170:171], 0, v[188:189]
	v_mov_b32_e32 v188, v79
	v_mov_b32_e32 v189, v75
	v_mov_b32_e32 v190, v71
	v_mov_b32_e32 v191, v67
	v_pk_mul_f32 v[188:189], v[188:189], s[88:89] op_sel_hi:[1,0]
	v_pk_mul_f32 v[190:191], v[190:191], s[88:89] op_sel_hi:[1,0]
	global_store_dwordx4 v[192:193], v[188:191], off offset:-128 nt

.LBB0_365:
	s_andn2_saveexec_b64 s[0:1], s[0:1]
	s_cbranch_execz .LBB0_367
	v_lshrrev_b32_e32 v134, 5, v198
	v_mul_lo_u32 v134, v134, s12
	v_and_or_b32 v134, v198, 31, v134
	v_add_u32_e32 v202, 0x1000, v134
	v_ashrrev_i32_e32 v203, 31, v202
	s_waitcnt vmcnt(0)
	v_mov_b32_e32 v209, v188
	v_mov_b32_e32 v216, v194
	v_mov_b32_e32 v217, v192
	s_waitcnt lgkmcnt(2)
	v_pk_mul_f32 v[200:201], v[172:173], v[200:201] op_sel_hi:[0,1]
	v_mov_b32_e32 v192, v195
	s_waitcnt lgkmcnt(0)
	v_pk_mul_f32 v[194:195], v[172:173], v[196:197] op_sel_hi:[0,1]
	v_mov_b32_e32 v188, v191
	v_mov_b32_e32 v206, v71
	v_mov_b32_e32 v207, v67
	v_mov_b32_e32 v208, v190
	v_mov_b32_e32 v214, v79
	v_mov_b32_e32 v215, v75
	v_lshlrev_b64 v[202:203], 6, v[202:203]
	v_ashrrev_i32_e32 v199, 31, v198
	v_pk_mul_f32 v[192:193], v[192:193], v[200:201]
	v_pk_mul_f32 v[188:189], v[188:189], v[194:195]
	v_lshl_add_u64 v[202:203], v[176:177], 0, v[202:203]
	v_lshlrev_b64 v[198:199], 7, v[198:199]
	v_pk_fma_f32 v[192:193], v[214:215], v[216:217], v[192:193]
	v_pk_fma_f32 v[194:195], v[206:207], v[208:209], v[188:189]
	v_cvt_pk_bf16_f32 v190, v192, v193
	v_lshl_add_u64 v[198:199], v[174:175], 0, v[198:199]
	v_cvt_pk_bf16_f32 v191, v194, v195
	global_store_dwordx2 v[202:203], v[190:191], off nt
	global_store_dwordx4 v[198:199], v[192:195], off nt
.LBB0_367:
	s_or_b64 exec, exec, s[0:1]
	s_waitcnt lgkmcnt(3)
	v_add_u32_e32 v200, 64, v168
	global_load_dwordx2 v[194:195], v[180:181], off
	global_load_dwordx2 v[192:193], v[182:183], off
	global_load_dwordx2 v[190:191], v[184:185], off
	global_load_dwordx2 v[188:189], v[186:187], off
	ds_bpermute_b32 v198, v129, v60
	ds_bpermute_b32 v199, v129, v56
	s_waitcnt lgkmcnt(3)
	ds_bpermute_b32 v196, v129, v52
	s_waitcnt lgkmcnt(3)
	ds_bpermute_b32 v197, v129, v48
	s_and_saveexec_b64 s[0:1], s[10:11]
	s_xor_b64 s[0:1], exec, s[0:1]
	s_cbranch_execz .LBB0_371
	s_and_saveexec_b64 s[72:73], s[8:9]
	s_cbranch_execz .LBB0_370
	v_ashrrev_i32_e32 v201, 31, v200
	s_waitcnt lgkmcnt(0)
	v_lshlrev_b64 v[196:197], 5, v[200:201]
	v_lshl_add_u64 v[200:201], v[170:171], 0, v[196:197]
	v_mov_b32_e32 v196, v60
	v_mov_b32_e32 v197, v56
	v_mov_b32_e32 v198, v52
	v_mov_b32_e32 v199, v48
	v_pk_mul_f32 v[196:197], v[196:197], s[88:89] op_sel_hi:[1,0]
	v_pk_mul_f32 v[198:199], v[198:199], s[88:89] op_sel_hi:[1,0]
	global_store_dwordx4 v[200:201], v[196:199], off offset:-128 nt

.LBB0_371:
	s_andn2_saveexec_b64 s[0:1], s[0:1]
	s_cbranch_execz .LBB0_373
	v_ashrrev_i32_e32 v201, 31, v200
	v_lshrrev_b32_e32 v134, 5, v200
	v_lshlrev_b64 v[200:201], 7, v[200:201]
	v_lshl_add_u64 v[206:207], v[174:175], 0, v[200:201]
	v_add_co_u32_e32 v200, vcc, 0x80000, v178
	v_mul_lo_u32 v134, v134, s12
	s_nop 0
	v_addc_co_u32_e32 v201, vcc, 0, v179, vcc
	global_load_dwordx2 v[208:209], v[200:201], off offset:16
	global_load_dwordx2 v[214:215], v[200:201], off
	v_or_b32_e32 v134, v134, v139
	v_mov_b32_e32 v216, v60
	v_mov_b32_e32 v217, v56
	v_add_u32_e32 v202, 0x1000, v134
	s_waitcnt lgkmcnt(2)
	v_pk_mul_f32 v[198:199], v[172:173], v[198:199] op_sel_hi:[0,1]
	v_ashrrev_i32_e32 v203, 31, v202
	v_lshlrev_b64 v[202:203], 6, v[202:203]
	s_waitcnt lgkmcnt(0)
	v_pk_mul_f32 v[196:197], v[172:173], v[196:197] op_sel_hi:[0,1]
	v_lshl_add_u64 v[202:203], v[176:177], 0, v[202:203]
	s_waitcnt vmcnt(1)
	v_mov_b32_e32 v219, v208
	s_waitcnt vmcnt(0)
	v_mov_b32_e32 v218, v214
	v_mov_b32_e32 v208, v215
	global_load_dwordx2 v[214:215], v[200:201], off offset:48
	s_nop 0
	global_load_dwordx2 v[200:201], v[200:201], off offset:32
	v_pk_mul_f32 v[216:217], v[216:217], v[218:219]
	s_waitcnt vmcnt(1)
	v_mov_b32_e32 v219, v214
	v_pk_fma_f32 v[198:199], v[198:199], v[208:209], v[216:217]
	v_mov_b32_e32 v216, v52
	v_mov_b32_e32 v217, v48
	s_waitcnt vmcnt(0)
	v_mov_b32_e32 v218, v200
	v_pk_mul_f32 v[216:217], v[216:217], v[218:219]
	v_mov_b32_e32 v214, v201
	v_cvt_pk_bf16_f32 v208, v198, v199
	v_pk_fma_f32 v[200:201], v[196:197], v[214:215], v[216:217]
	s_nop 0
	v_cvt_pk_bf16_f32 v209, v200, v201
	global_store_dwordx2 v[202:203], v[208:209], off nt
	global_store_dwordx4 v[206:207], v[198:201], off nt
.LBB0_373:
	s_or_b64 exec, exec, s[0:1]
	ds_bpermute_b32 v200, v129, v61
	ds_bpermute_b32 v201, v129, v57
	s_waitcnt lgkmcnt(3)
	ds_bpermute_b32 v196, v129, v53
	s_waitcnt lgkmcnt(3)
	ds_bpermute_b32 v197, v129, v49
	v_add_u32_e32 v198, 0x41, v168
	s_and_saveexec_b64 s[0:1], s[10:11]
	s_xor_b64 s[0:1], exec, s[0:1]
	s_cbranch_execz .LBB0_377
	s_and_saveexec_b64 s[72:73], s[8:9]
	s_cbranch_execz .LBB0_376
	v_ashrrev_i32_e32 v199, 31, v198
	s_waitcnt vmcnt(0)
	v_lshlrev_b64 v[188:189], 5, v[198:199]
	v_lshl_add_u64 v[192:193], v[170:171], 0, v[188:189]
	v_mov_b32_e32 v188, v61
	v_mov_b32_e32 v189, v57
	v_mov_b32_e32 v190, v53
	v_mov_b32_e32 v191, v49
	v_pk_mul_f32 v[188:189], v[188:189], s[88:89] op_sel_hi:[1,0]
	v_pk_mul_f32 v[190:191], v[190:191], s[88:89] op_sel_hi:[1,0]
	global_store_dwordx4 v[192:193], v[188:191], off offset:-128 nt

.LBB0_377:
	s_andn2_saveexec_b64 s[0:1], s[0:1]
	s_cbranch_execz .LBB0_379
	v_lshrrev_b32_e32 v134, 5, v198
	v_mul_lo_u32 v134, v134, s12
	v_and_or_b32 v134, v198, 29, v134
	v_add_u32_e32 v202, 0x1000, v134
	v_ashrrev_i32_e32 v203, 31, v202
	s_waitcnt vmcnt(0)
	v_mov_b32_e32 v209, v188
	v_mov_b32_e32 v216, v194
	v_mov_b32_e32 v217, v192
	s_waitcnt lgkmcnt(2)
	v_pk_mul_f32 v[200:201], v[172:173], v[200:201] op_sel_hi:[0,1]
	v_mov_b32_e32 v192, v195
	s_waitcnt lgkmcnt(0)
	v_pk_mul_f32 v[194:195], v[172:173], v[196:197] op_sel_hi:[0,1]
	v_mov_b32_e32 v188, v191
	v_mov_b32_e32 v206, v53
	v_mov_b32_e32 v207, v49
	v_mov_b32_e32 v208, v190
	v_mov_b32_e32 v214, v61
	v_mov_b32_e32 v215, v57
	v_lshlrev_b64 v[202:203], 6, v[202:203]
	v_ashrrev_i32_e32 v199, 31, v198
	v_pk_mul_f32 v[192:193], v[192:193], v[200:201]
	v_pk_mul_f32 v[188:189], v[188:189], v[194:195]
	v_lshl_add_u64 v[202:203], v[176:177], 0, v[202:203]
	v_lshlrev_b64 v[198:199], 7, v[198:199]
	v_pk_fma_f32 v[192:193], v[214:215], v[216:217], v[192:193]
	v_pk_fma_f32 v[194:195], v[206:207], v[208:209], v[188:189]
	v_cvt_pk_bf16_f32 v190, v192, v193
	v_lshl_add_u64 v[198:199], v[174:175], 0, v[198:199]
	v_cvt_pk_bf16_f32 v191, v194, v195
	global_store_dwordx2 v[202:203], v[190:191], off nt
	global_store_dwordx4 v[198:199], v[192:195], off nt
.LBB0_379:
	s_or_b64 exec, exec, s[0:1]
	v_add_u32_e32 v202, 0x42, v168
	v_and_b32_e32 v141, 30, v202
	v_lshl_or_b32 v134, v141, 8, v131
	s_waitcnt lgkmcnt(2)
	v_lshl_add_u64 v[200:201], s[58:59], 0, v[134:135]
	s_waitcnt vmcnt(0)
	v_add_co_u32_e32 v188, vcc, 0x80000, v200
	ds_bpermute_b32 v198, v129, v62
	s_nop 0
	v_addc_co_u32_e32 v189, vcc, 0, v201, vcc
	global_load_dwordx2 v[194:195], v[188:189], off offset:256
	global_load_dwordx2 v[192:193], v[188:189], off offset:272
	global_load_dwordx2 v[190:191], v[188:189], off offset:288
	s_nop 0
	global_load_dwordx2 v[188:189], v[188:189], off offset:304
	ds_bpermute_b32 v199, v129, v58
	s_waitcnt lgkmcnt(3)
	ds_bpermute_b32 v196, v129, v54
	s_waitcnt lgkmcnt(3)
	ds_bpermute_b32 v197, v129, v50
	s_and_saveexec_b64 s[0:1], s[10:11]
	s_xor_b64 s[0:1], exec, s[0:1]
	s_cbranch_execz .LBB0_383
	s_and_saveexec_b64 s[72:73], s[8:9]
	s_cbranch_execz .LBB0_382
	v_ashrrev_i32_e32 v203, 31, v202
	s_waitcnt lgkmcnt(0)
	v_lshlrev_b64 v[196:197], 5, v[202:203]
	v_lshl_add_u64 v[200:201], v[170:171], 0, v[196:197]
	v_mov_b32_e32 v196, v62
	v_mov_b32_e32 v197, v58
	v_mov_b32_e32 v198, v54
	v_mov_b32_e32 v199, v50
	v_pk_mul_f32 v[196:197], v[196:197], s[88:89] op_sel_hi:[1,0]
	v_pk_mul_f32 v[198:199], v[198:199], s[88:89] op_sel_hi:[1,0]
	global_store_dwordx4 v[200:201], v[196:199], off offset:-128 nt

.LBB0_383:
	s_andn2_saveexec_b64 s[0:1], s[0:1]
	s_cbranch_execz .LBB0_385
	v_add_co_u32_e32 v200, vcc, 0x80000, v200
	v_lshrrev_b32_e32 v134, 5, v202
	s_nop 0
	v_addc_co_u32_e32 v201, vcc, 0, v201, vcc
	global_load_dwordx2 v[208:209], v[200:201], off offset:16
	global_load_dwordx2 v[214:215], v[200:201], off
	v_mul_lo_u32 v134, v134, s12
	v_or_b32_e32 v134, v134, v141
	v_mov_b32_e32 v216, v62
	v_mov_b32_e32 v217, v58
	v_add_u32_e32 v206, 0x1000, v134
	s_waitcnt lgkmcnt(2)
	v_pk_mul_f32 v[198:199], v[172:173], v[198:199] op_sel_hi:[0,1]
	v_ashrrev_i32_e32 v207, 31, v206
	v_lshlrev_b64 v[206:207], 6, v[206:207]
	v_ashrrev_i32_e32 v203, 31, v202
	s_waitcnt lgkmcnt(0)
	v_pk_mul_f32 v[196:197], v[172:173], v[196:197] op_sel_hi:[0,1]
	v_lshl_add_u64 v[206:207], v[176:177], 0, v[206:207]
	v_lshlrev_b64 v[202:203], 7, v[202:203]
	v_lshl_add_u64 v[202:203], v[174:175], 0, v[202:203]
	s_waitcnt vmcnt(1)
	v_mov_b32_e32 v219, v208
	s_waitcnt vmcnt(0)
	v_mov_b32_e32 v218, v214
	v_mov_b32_e32 v208, v215
	global_load_dwordx2 v[214:215], v[200:201], off offset:48
	s_nop 0
	global_load_dwordx2 v[200:201], v[200:201], off offset:32
	v_pk_mul_f32 v[216:217], v[216:217], v[218:219]
	s_waitcnt vmcnt(1)
	v_mov_b32_e32 v219, v214
	v_pk_fma_f32 v[198:199], v[198:199], v[208:209], v[216:217]
	v_mov_b32_e32 v216, v54
	v_mov_b32_e32 v217, v50
	s_waitcnt vmcnt(0)
	v_mov_b32_e32 v218, v200
	v_pk_mul_f32 v[216:217], v[216:217], v[218:219]
	v_mov_b32_e32 v214, v201
	v_cvt_pk_bf16_f32 v208, v198, v199
	v_pk_fma_f32 v[200:201], v[196:197], v[214:215], v[216:217]
	s_nop 0
	v_cvt_pk_bf16_f32 v209, v200, v201
	global_store_dwordx2 v[206:207], v[208:209], off nt
	global_store_dwordx4 v[202:203], v[198:201], off nt
.LBB0_385:
	s_or_b64 exec, exec, s[0:1]
	ds_bpermute_b32 v200, v129, v63
	ds_bpermute_b32 v201, v129, v59
	s_waitcnt lgkmcnt(3)
	ds_bpermute_b32 v196, v129, v55
	s_waitcnt lgkmcnt(3)
	ds_bpermute_b32 v197, v129, v51
	v_add_u32_e32 v198, 0x43, v168
	s_and_saveexec_b64 s[0:1], s[10:11]
	s_xor_b64 s[0:1], exec, s[0:1]
	s_cbranch_execz .LBB0_389
	s_and_saveexec_b64 s[72:73], s[8:9]
	s_cbranch_execz .LBB0_388
	v_ashrrev_i32_e32 v199, 31, v198
	s_waitcnt vmcnt(0)
	v_lshlrev_b64 v[188:189], 5, v[198:199]
	v_lshl_add_u64 v[192:193], v[170:171], 0, v[188:189]
	v_mov_b32_e32 v188, v63
	v_mov_b32_e32 v189, v59
	v_mov_b32_e32 v190, v55
	v_mov_b32_e32 v191, v51
	v_pk_mul_f32 v[188:189], v[188:189], s[88:89] op_sel_hi:[1,0]
	v_pk_mul_f32 v[190:191], v[190:191], s[88:89] op_sel_hi:[1,0]
	global_store_dwordx4 v[192:193], v[188:191], off offset:-128 nt

.LBB0_389:
	s_andn2_saveexec_b64 s[0:1], s[0:1]
	s_cbranch_execz .LBB0_391
	v_lshrrev_b32_e32 v134, 5, v198
	v_mul_lo_u32 v134, v134, s12
	v_and_or_b32 v134, v198, 31, v134
	v_add_u32_e32 v202, 0x1000, v134
	v_ashrrev_i32_e32 v203, 31, v202
	s_waitcnt vmcnt(0)
	v_mov_b32_e32 v209, v188
	v_mov_b32_e32 v216, v194
	v_mov_b32_e32 v217, v192
	s_waitcnt lgkmcnt(2)
	v_pk_mul_f32 v[200:201], v[172:173], v[200:201] op_sel_hi:[0,1]
	v_mov_b32_e32 v192, v195
	s_waitcnt lgkmcnt(0)
	v_pk_mul_f32 v[194:195], v[172:173], v[196:197] op_sel_hi:[0,1]
	v_mov_b32_e32 v188, v191
	v_mov_b32_e32 v206, v55
	v_mov_b32_e32 v207, v51
	v_mov_b32_e32 v208, v190
	v_mov_b32_e32 v214, v63
	v_mov_b32_e32 v215, v59
	v_lshlrev_b64 v[202:203], 6, v[202:203]
	v_ashrrev_i32_e32 v199, 31, v198
	v_pk_mul_f32 v[192:193], v[192:193], v[200:201]
	v_pk_mul_f32 v[188:189], v[188:189], v[194:195]
	v_lshl_add_u64 v[202:203], v[176:177], 0, v[202:203]
	v_lshlrev_b64 v[198:199], 7, v[198:199]
	v_pk_fma_f32 v[192:193], v[214:215], v[216:217], v[192:193]
	v_pk_fma_f32 v[194:195], v[206:207], v[208:209], v[188:189]
	v_cvt_pk_bf16_f32 v190, v192, v193
	v_lshl_add_u64 v[198:199], v[174:175], 0, v[198:199]
	v_cvt_pk_bf16_f32 v191, v194, v195
	global_store_dwordx2 v[202:203], v[190:191], off nt
	global_store_dwordx4 v[198:199], v[192:195], off nt
.LBB0_391:
	s_or_b64 exec, exec, s[0:1]
	v_add_u32_e32 v202, 0x50, v168
	v_and_b32_e32 v141, 28, v202
	v_lshl_or_b32 v134, v141, 8, v131
	s_waitcnt lgkmcnt(2)
	v_lshl_add_u64 v[200:201], s[58:59], 0, v[134:135]
	s_waitcnt vmcnt(0)
	v_add_co_u32_e32 v188, vcc, 0x80000, v200
	ds_bpermute_b32 v198, v129, v44
	s_nop 0
	v_addc_co_u32_e32 v189, vcc, 0, v201, vcc
	global_load_dwordx2 v[194:195], v[188:189], off offset:256
	global_load_dwordx2 v[192:193], v[188:189], off offset:272
	global_load_dwordx2 v[190:191], v[188:189], off offset:288
	s_nop 0
	global_load_dwordx2 v[188:189], v[188:189], off offset:304
	ds_bpermute_b32 v199, v129, v40
	s_waitcnt lgkmcnt(3)
	ds_bpermute_b32 v196, v129, v36
	s_waitcnt lgkmcnt(3)
	ds_bpermute_b32 v197, v129, v32
	s_and_saveexec_b64 s[0:1], s[10:11]
	s_xor_b64 s[0:1], exec, s[0:1]
	s_cbranch_execz .LBB0_395
	s_and_saveexec_b64 s[72:73], s[8:9]
	s_cbranch_execz .LBB0_394
	v_ashrrev_i32_e32 v203, 31, v202
	s_waitcnt lgkmcnt(0)
	v_lshlrev_b64 v[196:197], 5, v[202:203]
	v_lshl_add_u64 v[200:201], v[170:171], 0, v[196:197]
	v_mov_b32_e32 v196, v44
	v_mov_b32_e32 v197, v40
	v_mov_b32_e32 v198, v36
	v_mov_b32_e32 v199, v32
	v_pk_mul_f32 v[196:197], v[196:197], s[88:89] op_sel_hi:[1,0]
	v_pk_mul_f32 v[198:199], v[198:199], s[88:89] op_sel_hi:[1,0]
	global_store_dwordx4 v[200:201], v[196:199], off offset:-128 nt

.LBB0_395:
	s_andn2_saveexec_b64 s[0:1], s[0:1]
	s_cbranch_execz .LBB0_397
	v_add_co_u32_e32 v200, vcc, 0x80000, v200
	v_lshrrev_b32_e32 v134, 5, v202
	s_nop 0
	v_addc_co_u32_e32 v201, vcc, 0, v201, vcc
	global_load_dwordx2 v[208:209], v[200:201], off offset:16
	global_load_dwordx2 v[214:215], v[200:201], off
	v_mul_lo_u32 v134, v134, s12
	v_or_b32_e32 v134, v134, v141
	v_mov_b32_e32 v216, v44
	v_mov_b32_e32 v217, v40
	v_add_u32_e32 v206, 0x1000, v134
	s_waitcnt lgkmcnt(2)
	v_pk_mul_f32 v[198:199], v[172:173], v[198:199] op_sel_hi:[0,1]
	v_ashrrev_i32_e32 v207, 31, v206
	v_lshlrev_b64 v[206:207], 6, v[206:207]
	v_ashrrev_i32_e32 v203, 31, v202
	s_waitcnt lgkmcnt(0)
	v_pk_mul_f32 v[196:197], v[172:173], v[196:197] op_sel_hi:[0,1]
	v_lshl_add_u64 v[206:207], v[176:177], 0, v[206:207]
	v_lshlrev_b64 v[202:203], 7, v[202:203]
	v_lshl_add_u64 v[202:203], v[174:175], 0, v[202:203]
	s_waitcnt vmcnt(1)
	v_mov_b32_e32 v219, v208
	s_waitcnt vmcnt(0)
	v_mov_b32_e32 v218, v214
	v_mov_b32_e32 v208, v215
	global_load_dwordx2 v[214:215], v[200:201], off offset:48
	s_nop 0
	global_load_dwordx2 v[200:201], v[200:201], off offset:32
	v_pk_mul_f32 v[216:217], v[216:217], v[218:219]
	s_waitcnt vmcnt(1)
	v_mov_b32_e32 v219, v214
	v_pk_fma_f32 v[198:199], v[198:199], v[208:209], v[216:217]
	v_mov_b32_e32 v216, v36
	v_mov_b32_e32 v217, v32
	s_waitcnt vmcnt(0)
	v_mov_b32_e32 v218, v200
	v_pk_mul_f32 v[216:217], v[216:217], v[218:219]
	v_mov_b32_e32 v214, v201
	v_cvt_pk_bf16_f32 v208, v198, v199
	v_pk_fma_f32 v[200:201], v[196:197], v[214:215], v[216:217]
	s_nop 0
	v_cvt_pk_bf16_f32 v209, v200, v201
	global_store_dwordx2 v[206:207], v[208:209], off nt
	global_store_dwordx4 v[202:203], v[198:201], off nt
.LBB0_397:
	s_or_b64 exec, exec, s[0:1]
	ds_bpermute_b32 v200, v129, v45
	ds_bpermute_b32 v201, v129, v41
	s_waitcnt lgkmcnt(3)
	ds_bpermute_b32 v196, v129, v37
	s_waitcnt lgkmcnt(3)
	ds_bpermute_b32 v197, v129, v33
	v_add_u32_e32 v198, 0x51, v168
	s_and_saveexec_b64 s[0:1], s[10:11]
	s_xor_b64 s[0:1], exec, s[0:1]
	s_cbranch_execz .LBB0_401
	s_and_saveexec_b64 s[72:73], s[8:9]
	s_cbranch_execz .LBB0_400
	v_ashrrev_i32_e32 v199, 31, v198
	s_waitcnt vmcnt(0)
	v_lshlrev_b64 v[188:189], 5, v[198:199]
	v_lshl_add_u64 v[192:193], v[170:171], 0, v[188:189]
	v_mov_b32_e32 v188, v45
	v_mov_b32_e32 v189, v41
	v_mov_b32_e32 v190, v37
	v_mov_b32_e32 v191, v33
	v_pk_mul_f32 v[188:189], v[188:189], s[88:89] op_sel_hi:[1,0]
	v_pk_mul_f32 v[190:191], v[190:191], s[88:89] op_sel_hi:[1,0]
	global_store_dwordx4 v[192:193], v[188:191], off offset:-128 nt

.LBB0_401:
	s_andn2_saveexec_b64 s[0:1], s[0:1]
	s_cbranch_execz .LBB0_403
	v_lshrrev_b32_e32 v134, 5, v198
	v_mul_lo_u32 v134, v134, s12
	v_and_or_b32 v134, v198, 29, v134
	v_add_u32_e32 v202, 0x1000, v134
	v_ashrrev_i32_e32 v203, 31, v202
	s_waitcnt vmcnt(0)
	v_mov_b32_e32 v209, v188
	v_mov_b32_e32 v216, v194
	v_mov_b32_e32 v217, v192
	s_waitcnt lgkmcnt(2)
	v_pk_mul_f32 v[200:201], v[172:173], v[200:201] op_sel_hi:[0,1]
	v_mov_b32_e32 v192, v195
	s_waitcnt lgkmcnt(0)
	v_pk_mul_f32 v[194:195], v[172:173], v[196:197] op_sel_hi:[0,1]
	v_mov_b32_e32 v188, v191
	v_mov_b32_e32 v206, v37
	v_mov_b32_e32 v207, v33
	v_mov_b32_e32 v208, v190
	v_mov_b32_e32 v214, v45
	v_mov_b32_e32 v215, v41
	v_lshlrev_b64 v[202:203], 6, v[202:203]
	v_ashrrev_i32_e32 v199, 31, v198
	v_pk_mul_f32 v[192:193], v[192:193], v[200:201]
	v_pk_mul_f32 v[188:189], v[188:189], v[194:195]
	v_lshl_add_u64 v[202:203], v[176:177], 0, v[202:203]
	v_lshlrev_b64 v[198:199], 7, v[198:199]
	v_pk_fma_f32 v[192:193], v[214:215], v[216:217], v[192:193]
	v_pk_fma_f32 v[194:195], v[206:207], v[208:209], v[188:189]
	v_cvt_pk_bf16_f32 v190, v192, v193
	v_lshl_add_u64 v[198:199], v[174:175], 0, v[198:199]
	v_cvt_pk_bf16_f32 v191, v194, v195
	global_store_dwordx2 v[202:203], v[190:191], off nt
	global_store_dwordx4 v[198:199], v[192:195], off nt
.LBB0_403:
	s_or_b64 exec, exec, s[0:1]
	v_add_u32_e32 v202, 0x52, v168
	v_and_b32_e32 v141, 30, v202
	v_lshl_or_b32 v134, v141, 8, v131
	s_waitcnt lgkmcnt(2)
	v_lshl_add_u64 v[200:201], s[58:59], 0, v[134:135]
	s_waitcnt vmcnt(0)
	v_add_co_u32_e32 v188, vcc, 0x80000, v200
	ds_bpermute_b32 v198, v129, v46
	s_nop 0
	v_addc_co_u32_e32 v189, vcc, 0, v201, vcc
	global_load_dwordx2 v[194:195], v[188:189], off offset:256
	global_load_dwordx2 v[192:193], v[188:189], off offset:272
	global_load_dwordx2 v[190:191], v[188:189], off offset:288
	s_nop 0
	global_load_dwordx2 v[188:189], v[188:189], off offset:304
	ds_bpermute_b32 v199, v129, v42
	s_waitcnt lgkmcnt(3)
	ds_bpermute_b32 v196, v129, v38
	s_waitcnt lgkmcnt(3)
	ds_bpermute_b32 v197, v129, v34
	s_and_saveexec_b64 s[0:1], s[10:11]
	s_xor_b64 s[0:1], exec, s[0:1]
	s_cbranch_execz .LBB0_407
	s_and_saveexec_b64 s[72:73], s[8:9]
	s_cbranch_execz .LBB0_406
	v_ashrrev_i32_e32 v203, 31, v202
	s_waitcnt lgkmcnt(0)
	v_lshlrev_b64 v[196:197], 5, v[202:203]
	v_lshl_add_u64 v[200:201], v[170:171], 0, v[196:197]
	v_mov_b32_e32 v196, v46
	v_mov_b32_e32 v197, v42
	v_mov_b32_e32 v198, v38
	v_mov_b32_e32 v199, v34
	v_pk_mul_f32 v[196:197], v[196:197], s[88:89] op_sel_hi:[1,0]
	v_pk_mul_f32 v[198:199], v[198:199], s[88:89] op_sel_hi:[1,0]
	global_store_dwordx4 v[200:201], v[196:199], off offset:-128 nt

.LBB0_407:
	s_andn2_saveexec_b64 s[0:1], s[0:1]
	s_cbranch_execz .LBB0_409
	v_add_co_u32_e32 v200, vcc, 0x80000, v200
	v_lshrrev_b32_e32 v134, 5, v202
	s_nop 0
	v_addc_co_u32_e32 v201, vcc, 0, v201, vcc
	global_load_dwordx2 v[208:209], v[200:201], off offset:16
	global_load_dwordx2 v[214:215], v[200:201], off
	v_mul_lo_u32 v134, v134, s12
	v_or_b32_e32 v134, v134, v141
	v_mov_b32_e32 v216, v46
	v_mov_b32_e32 v217, v42
	v_add_u32_e32 v206, 0x1000, v134
	s_waitcnt lgkmcnt(2)
	v_pk_mul_f32 v[198:199], v[172:173], v[198:199] op_sel_hi:[0,1]
	v_ashrrev_i32_e32 v207, 31, v206
	v_lshlrev_b64 v[206:207], 6, v[206:207]
	v_ashrrev_i32_e32 v203, 31, v202
	s_waitcnt lgkmcnt(0)
	v_pk_mul_f32 v[196:197], v[172:173], v[196:197] op_sel_hi:[0,1]
	v_lshl_add_u64 v[206:207], v[176:177], 0, v[206:207]
	v_lshlrev_b64 v[202:203], 7, v[202:203]
	v_lshl_add_u64 v[202:203], v[174:175], 0, v[202:203]
	s_waitcnt vmcnt(1)
	v_mov_b32_e32 v219, v208
	s_waitcnt vmcnt(0)
	v_mov_b32_e32 v218, v214
	v_mov_b32_e32 v208, v215
	global_load_dwordx2 v[214:215], v[200:201], off offset:48
	s_nop 0
	global_load_dwordx2 v[200:201], v[200:201], off offset:32
	v_pk_mul_f32 v[216:217], v[216:217], v[218:219]
	s_waitcnt vmcnt(1)
	v_mov_b32_e32 v219, v214
	v_pk_fma_f32 v[198:199], v[198:199], v[208:209], v[216:217]
	v_mov_b32_e32 v216, v38
	v_mov_b32_e32 v217, v34
	s_waitcnt vmcnt(0)
	v_mov_b32_e32 v218, v200
	v_pk_mul_f32 v[216:217], v[216:217], v[218:219]
	v_mov_b32_e32 v214, v201
	v_cvt_pk_bf16_f32 v208, v198, v199
	v_pk_fma_f32 v[200:201], v[196:197], v[214:215], v[216:217]
	s_nop 0
	v_cvt_pk_bf16_f32 v209, v200, v201
	global_store_dwordx2 v[206:207], v[208:209], off nt
	global_store_dwordx4 v[202:203], v[198:201], off nt
.LBB0_409:
	s_or_b64 exec, exec, s[0:1]
	ds_bpermute_b32 v200, v129, v47
	ds_bpermute_b32 v201, v129, v43
	s_waitcnt lgkmcnt(3)
	ds_bpermute_b32 v196, v129, v39
	s_waitcnt lgkmcnt(3)
	ds_bpermute_b32 v197, v129, v35
	v_add_u32_e32 v198, 0x53, v168
	s_and_saveexec_b64 s[0:1], s[10:11]
	s_xor_b64 s[0:1], exec, s[0:1]
	s_cbranch_execz .LBB0_413
	s_and_saveexec_b64 s[72:73], s[8:9]
	s_cbranch_execz .LBB0_412
	v_ashrrev_i32_e32 v199, 31, v198
	s_waitcnt vmcnt(0)
	v_lshlrev_b64 v[188:189], 5, v[198:199]
	v_lshl_add_u64 v[192:193], v[170:171], 0, v[188:189]
	v_mov_b32_e32 v188, v47
	v_mov_b32_e32 v189, v43
	v_mov_b32_e32 v190, v39
	v_mov_b32_e32 v191, v35
	v_pk_mul_f32 v[188:189], v[188:189], s[88:89] op_sel_hi:[1,0]
	v_pk_mul_f32 v[190:191], v[190:191], s[88:89] op_sel_hi:[1,0]
	global_store_dwordx4 v[192:193], v[188:191], off offset:-128 nt

.LBB0_413:
	s_andn2_saveexec_b64 s[0:1], s[0:1]
	s_cbranch_execz .LBB0_415
	v_lshrrev_b32_e32 v134, 5, v198
	v_mul_lo_u32 v134, v134, s12
	v_and_or_b32 v134, v198, 31, v134
	v_add_u32_e32 v202, 0x1000, v134
	v_ashrrev_i32_e32 v203, 31, v202
	s_waitcnt vmcnt(0)
	v_mov_b32_e32 v209, v188
	v_mov_b32_e32 v216, v194
	v_mov_b32_e32 v217, v192
	s_waitcnt lgkmcnt(2)
	v_pk_mul_f32 v[200:201], v[172:173], v[200:201] op_sel_hi:[0,1]
	v_mov_b32_e32 v192, v195
	s_waitcnt lgkmcnt(0)
	v_pk_mul_f32 v[194:195], v[172:173], v[196:197] op_sel_hi:[0,1]
	v_mov_b32_e32 v188, v191
	v_mov_b32_e32 v206, v39
	v_mov_b32_e32 v207, v35
	v_mov_b32_e32 v208, v190
	v_mov_b32_e32 v214, v47
	v_mov_b32_e32 v215, v43
	v_lshlrev_b64 v[202:203], 6, v[202:203]
	v_ashrrev_i32_e32 v199, 31, v198
	v_pk_mul_f32 v[192:193], v[192:193], v[200:201]
	v_pk_mul_f32 v[188:189], v[188:189], v[194:195]
	v_lshl_add_u64 v[202:203], v[176:177], 0, v[202:203]
	v_lshlrev_b64 v[198:199], 7, v[198:199]
	v_pk_fma_f32 v[192:193], v[214:215], v[216:217], v[192:193]
	v_pk_fma_f32 v[194:195], v[206:207], v[208:209], v[188:189]
	v_cvt_pk_bf16_f32 v190, v192, v193
	v_lshl_add_u64 v[198:199], v[174:175], 0, v[198:199]
	v_cvt_pk_bf16_f32 v191, v194, v195
	global_store_dwordx2 v[202:203], v[190:191], off nt
	global_store_dwordx4 v[198:199], v[192:195], off nt
.LBB0_415:
	s_or_b64 exec, exec, s[0:1]
	s_waitcnt vmcnt(2)
	v_add_u32_e32 v192, 0x60, v168
	global_load_dwordx2 v[190:191], v[180:181], off
	global_load_dwordx2 v[188:189], v[182:183], off
	s_nop 0
	global_load_dwordx2 v[182:183], v[184:185], off
	global_load_dwordx2 v[180:181], v[186:187], off
	ds_bpermute_b32 v186, v129, v28
	ds_bpermute_b32 v187, v129, v24
	ds_bpermute_b32 v184, v129, v20
	ds_bpermute_b32 v185, v129, v16
	s_and_saveexec_b64 s[0:1], s[10:11]
	s_xor_b64 s[0:1], exec, s[0:1]
	s_cbranch_execz .LBB0_419
	s_and_saveexec_b64 s[72:73], s[8:9]
	s_cbranch_execz .LBB0_418
	v_ashrrev_i32_e32 v193, 31, v192
	v_lshlrev_b64 v[178:179], 5, v[192:193]
	s_waitcnt lgkmcnt(1)
	v_mov_b32_e32 v184, v28
	s_waitcnt lgkmcnt(0)
	v_mov_b32_e32 v185, v24
	v_mov_b32_e32 v186, v20
	v_mov_b32_e32 v187, v16
	v_lshl_add_u64 v[178:179], v[170:171], 0, v[178:179]
	v_pk_mul_f32 v[184:185], v[184:185], s[88:89] op_sel_hi:[1,0]
	v_pk_mul_f32 v[186:187], v[186:187], s[88:89] op_sel_hi:[1,0]
	global_store_dwordx4 v[178:179], v[184:187], off offset:-128 nt

.LBB0_419:
	s_andn2_saveexec_b64 s[0:1], s[0:1]
	s_cbranch_execz .LBB0_421
	v_lshrrev_b32_e32 v134, 5, v192
	v_mul_lo_u32 v134, v134, s12
	v_or_b32_e32 v134, v134, v139
	v_add_u32_e32 v194, 0x1000, v134
	v_ashrrev_i32_e32 v195, 31, v194
	v_ashrrev_i32_e32 v193, 31, v192
	v_add_co_u32_e32 v178, vcc, 0x80000, v178
	v_lshlrev_b64 v[194:195], 6, v[194:195]
	v_lshlrev_b64 v[192:193], 7, v[192:193]
	v_addc_co_u32_e32 v179, vcc, 0, v179, vcc
	s_waitcnt lgkmcnt(4)
	v_lshl_add_u64 v[196:197], v[176:177], 0, v[194:195]
	v_lshl_add_u64 v[198:199], v[174:175], 0, v[192:193]
	global_load_dwordx2 v[192:193], v[178:179], off offset:16
	global_load_dwordx2 v[194:195], v[178:179], off
	v_mov_b32_e32 v200, v28
	v_mov_b32_e32 v201, v24
	s_waitcnt lgkmcnt(2)
	v_pk_mul_f32 v[186:187], v[172:173], v[186:187] op_sel_hi:[0,1]
	s_waitcnt lgkmcnt(0)
	v_pk_mul_f32 v[184:185], v[172:173], v[184:185] op_sel_hi:[0,1]
	s_waitcnt vmcnt(1)
	v_mov_b32_e32 v203, v192
	s_waitcnt vmcnt(0)
	v_mov_b32_e32 v202, v194
	v_mov_b32_e32 v192, v195
	global_load_dwordx2 v[194:195], v[178:179], off offset:48
	s_nop 0
	global_load_dwordx2 v[178:179], v[178:179], off offset:32
	v_pk_mul_f32 v[200:201], v[200:201], v[202:203]
	s_waitcnt vmcnt(1)
	v_mov_b32_e32 v203, v194
	v_pk_fma_f32 v[192:193], v[186:187], v[192:193], v[200:201]
	v_mov_b32_e32 v200, v20
	v_mov_b32_e32 v201, v16
	s_waitcnt vmcnt(0)
	v_mov_b32_e32 v202, v178
	v_pk_mul_f32 v[200:201], v[200:201], v[202:203]
	v_mov_b32_e32 v194, v179
	v_cvt_pk_bf16_f32 v186, v192, v193
	v_pk_fma_f32 v[194:195], v[184:185], v[194:195], v[200:201]
	s_nop 0
	v_cvt_pk_bf16_f32 v187, v194, v195
	global_store_dwordx2 v[196:197], v[186:187], off nt
	global_store_dwordx4 v[198:199], v[192:195], off nt
.LBB0_421:
	s_or_b64 exec, exec, s[0:1]
	s_waitcnt lgkmcnt(3)
	ds_bpermute_b32 v186, v129, v29
	s_waitcnt lgkmcnt(3)
	ds_bpermute_b32 v187, v129, v25
	ds_bpermute_b32 v178, v129, v21
	ds_bpermute_b32 v179, v129, v17
	s_waitcnt lgkmcnt(5)
	v_add_u32_e32 v184, 0x61, v168
	s_and_saveexec_b64 s[0:1], s[10:11]
	s_xor_b64 s[0:1], exec, s[0:1]
	s_cbranch_execz .LBB0_425
	s_and_saveexec_b64 s[72:73], s[8:9]
	s_cbranch_execz .LBB0_424
	s_waitcnt lgkmcnt(4)
	v_ashrrev_i32_e32 v185, 31, v184
	s_waitcnt lgkmcnt(0)
	v_lshlrev_b64 v[178:179], 5, v[184:185]
	s_waitcnt vmcnt(1)
	v_lshl_add_u64 v[182:183], v[170:171], 0, v[178:179]
	v_mov_b32_e32 v178, v29
	v_mov_b32_e32 v179, v25
	s_waitcnt vmcnt(0)
	v_mov_b32_e32 v180, v21
	v_mov_b32_e32 v181, v17
	v_pk_mul_f32 v[178:179], v[178:179], s[88:89] op_sel_hi:[1,0]
	v_pk_mul_f32 v[180:181], v[180:181], s[88:89] op_sel_hi:[1,0]
	global_store_dwordx4 v[182:183], v[178:181], off offset:-128 nt

.LBB0_425:
	s_andn2_saveexec_b64 s[0:1], s[0:1]
	s_cbranch_execz .LBB0_427
	v_lshrrev_b32_e32 v134, 5, v184
	v_mul_lo_u32 v134, v134, s12
	v_and_or_b32 v134, v184, 29, v134
	s_waitcnt lgkmcnt(4)
	v_ashrrev_i32_e32 v185, 31, v184
	v_add_u32_e32 v192, 0x1000, v134
	v_lshlrev_b64 v[184:185], 7, v[184:185]
	v_ashrrev_i32_e32 v193, 31, v192
	s_waitcnt vmcnt(0)
	v_mov_b32_e32 v197, v180
	v_mov_b32_e32 v201, v188
	v_lshl_add_u64 v[202:203], v[174:175], 0, v[184:185]
	s_waitcnt lgkmcnt(2)
	v_pk_mul_f32 v[184:185], v[172:173], v[186:187] op_sel_hi:[0,1]
	v_mov_b32_e32 v188, v191
	s_waitcnt lgkmcnt(0)
	v_pk_mul_f32 v[178:179], v[172:173], v[178:179] op_sel_hi:[0,1]
	v_mov_b32_e32 v180, v183
	v_mov_b32_e32 v194, v21
	v_mov_b32_e32 v195, v17
	v_mov_b32_e32 v196, v182
	v_mov_b32_e32 v198, v29
	v_mov_b32_e32 v199, v25
	v_mov_b32_e32 v200, v190
	v_lshlrev_b64 v[192:193], 6, v[192:193]
	v_pk_mul_f32 v[184:185], v[188:189], v[184:185]
	v_pk_mul_f32 v[178:179], v[180:181], v[178:179]
	v_lshl_add_u64 v[192:193], v[176:177], 0, v[192:193]
	v_pk_fma_f32 v[184:185], v[198:199], v[200:201], v[184:185]
	v_pk_fma_f32 v[186:187], v[194:195], v[196:197], v[178:179]
	v_cvt_pk_bf16_f32 v182, v184, v185
	s_nop 0
	v_cvt_pk_bf16_f32 v183, v186, v187
	global_store_dwordx2 v[192:193], v[182:183], off nt
	global_store_dwordx4 v[202:203], v[184:187], off nt
.LBB0_427:
	s_or_b64 exec, exec, s[0:1]
	v_add_u32_e32 v192, 0x62, v168
	v_and_b32_e32 v139, 30, v192
	v_lshl_or_b32 v134, v139, 8, v131
	s_waitcnt vmcnt(3)
	v_lshl_add_u64 v[190:191], s[58:59], 0, v[134:135]
	s_waitcnt lgkmcnt(1)
	v_add_co_u32_e32 v178, vcc, 0x80000, v190
	s_waitcnt vmcnt(2)
	ds_bpermute_b32 v188, v129, v30
	s_waitcnt lgkmcnt(1)
	v_addc_co_u32_e32 v179, vcc, 0, v191, vcc
	global_load_dwordx2 v[184:185], v[178:179], off offset:256
	global_load_dwordx2 v[182:183], v[178:179], off offset:272
	global_load_dwordx2 v[180:181], v[178:179], off offset:288
	s_nop 0
	global_load_dwordx2 v[178:179], v[178:179], off offset:304
	ds_bpermute_b32 v189, v129, v26
	ds_bpermute_b32 v186, v129, v22
	ds_bpermute_b32 v187, v129, v18
	s_and_saveexec_b64 s[0:1], s[10:11]
	s_xor_b64 s[0:1], exec, s[0:1]
	s_cbranch_execz .LBB0_431
	s_and_saveexec_b64 s[72:73], s[8:9]
	s_cbranch_execz .LBB0_430
	v_ashrrev_i32_e32 v193, 31, v192
	s_waitcnt lgkmcnt(0)
	v_lshlrev_b64 v[186:187], 5, v[192:193]
	v_lshl_add_u64 v[190:191], v[170:171], 0, v[186:187]
	v_mov_b32_e32 v186, v30
	v_mov_b32_e32 v187, v26
	v_mov_b32_e32 v188, v22
	v_mov_b32_e32 v189, v18
	v_pk_mul_f32 v[186:187], v[186:187], s[88:89] op_sel_hi:[1,0]
	v_pk_mul_f32 v[188:189], v[188:189], s[88:89] op_sel_hi:[1,0]
	global_store_dwordx4 v[190:191], v[186:189], off offset:-128 nt

.LBB0_431:
	s_andn2_saveexec_b64 s[0:1], s[0:1]
	s_cbranch_execz .LBB0_433
	v_add_co_u32_e32 v190, vcc, 0x80000, v190
	v_lshrrev_b32_e32 v134, 5, v192
	s_nop 0
	v_addc_co_u32_e32 v191, vcc, 0, v191, vcc
	global_load_dwordx2 v[196:197], v[190:191], off offset:16
	global_load_dwordx2 v[198:199], v[190:191], off
	v_mul_lo_u32 v134, v134, s12
	v_or_b32_e32 v134, v134, v139
	v_mov_b32_e32 v200, v30
	v_mov_b32_e32 v201, v26
	v_add_u32_e32 v194, 0x1000, v134
	s_waitcnt lgkmcnt(2)
	v_pk_mul_f32 v[188:189], v[172:173], v[188:189] op_sel_hi:[0,1]
	v_ashrrev_i32_e32 v195, 31, v194
	v_lshlrev_b64 v[194:195], 6, v[194:195]
	v_ashrrev_i32_e32 v193, 31, v192
	s_waitcnt lgkmcnt(0)
	v_pk_mul_f32 v[186:187], v[172:173], v[186:187] op_sel_hi:[0,1]
	v_lshl_add_u64 v[194:195], v[176:177], 0, v[194:195]
	v_lshlrev_b64 v[192:193], 7, v[192:193]
	v_lshl_add_u64 v[192:193], v[174:175], 0, v[192:193]
	s_waitcnt vmcnt(1)
	v_mov_b32_e32 v203, v196
	s_waitcnt vmcnt(0)
	v_mov_b32_e32 v202, v198
	v_mov_b32_e32 v196, v199
	global_load_dwordx2 v[198:199], v[190:191], off offset:48
	s_nop 0
	global_load_dwordx2 v[190:191], v[190:191], off offset:32
	v_pk_mul_f32 v[200:201], v[200:201], v[202:203]
	s_waitcnt vmcnt(1)
	v_mov_b32_e32 v203, v198
	v_pk_fma_f32 v[188:189], v[188:189], v[196:197], v[200:201]
	v_mov_b32_e32 v200, v22
	v_mov_b32_e32 v201, v18
	s_waitcnt vmcnt(0)
	v_mov_b32_e32 v202, v190
	v_pk_mul_f32 v[200:201], v[200:201], v[202:203]
	v_mov_b32_e32 v198, v191
	v_cvt_pk_bf16_f32 v196, v188, v189
	v_pk_fma_f32 v[190:191], v[186:187], v[198:199], v[200:201]
	s_nop 0
	v_cvt_pk_bf16_f32 v197, v190, v191
	global_store_dwordx2 v[194:195], v[196:197], off nt
	global_store_dwordx4 v[192:193], v[188:191], off nt
.LBB0_433:
	s_or_b64 exec, exec, s[0:1]
	ds_bpermute_b32 v190, v129, v31
	ds_bpermute_b32 v191, v129, v27
	s_waitcnt lgkmcnt(3)
	ds_bpermute_b32 v186, v129, v23
	s_waitcnt lgkmcnt(3)
	ds_bpermute_b32 v187, v129, v19
	v_add_u32_e32 v188, 0x63, v168
	s_and_saveexec_b64 s[0:1], s[10:11]
	s_xor_b64 s[0:1], exec, s[0:1]
	s_cbranch_execz .LBB0_437
	s_and_saveexec_b64 s[72:73], s[8:9]
	s_cbranch_execz .LBB0_436
	v_ashrrev_i32_e32 v189, 31, v188
	s_waitcnt vmcnt(0)
	v_lshlrev_b64 v[178:179], 5, v[188:189]
	v_lshl_add_u64 v[182:183], v[170:171], 0, v[178:179]
	v_mov_b32_e32 v178, v31
	v_mov_b32_e32 v179, v27
	v_mov_b32_e32 v180, v23
	v_mov_b32_e32 v181, v19
	v_pk_mul_f32 v[178:179], v[178:179], s[88:89] op_sel_hi:[1,0]
	v_pk_mul_f32 v[180:181], v[180:181], s[88:89] op_sel_hi:[1,0]
	global_store_dwordx4 v[182:183], v[178:181], off offset:-128 nt

.LBB0_437:
	s_andn2_saveexec_b64 s[0:1], s[0:1]
	s_cbranch_execz .LBB0_439
	v_lshrrev_b32_e32 v134, 5, v188
	v_mul_lo_u32 v134, v134, s12
	v_and_or_b32 v134, v188, 31, v134
	v_add_u32_e32 v192, 0x1000, v134
	v_ashrrev_i32_e32 v193, 31, v192
	s_waitcnt vmcnt(0)
	v_mov_b32_e32 v197, v178
	v_mov_b32_e32 v200, v184
	v_mov_b32_e32 v201, v182
	s_waitcnt lgkmcnt(2)
	v_pk_mul_f32 v[190:191], v[172:173], v[190:191] op_sel_hi:[0,1]
	v_mov_b32_e32 v182, v185
	s_waitcnt lgkmcnt(0)
	v_pk_mul_f32 v[184:185], v[172:173], v[186:187] op_sel_hi:[0,1]
	v_mov_b32_e32 v178, v181
	v_mov_b32_e32 v194, v23
	v_mov_b32_e32 v195, v19
	v_mov_b32_e32 v196, v180
	v_mov_b32_e32 v198, v31
	v_mov_b32_e32 v199, v27
	v_lshlrev_b64 v[192:193], 6, v[192:193]
	v_ashrrev_i32_e32 v189, 31, v188
	v_pk_mul_f32 v[182:183], v[182:183], v[190:191]
	v_pk_mul_f32 v[178:179], v[178:179], v[184:185]
	v_lshl_add_u64 v[192:193], v[176:177], 0, v[192:193]
	v_lshlrev_b64 v[188:189], 7, v[188:189]
	v_pk_fma_f32 v[182:183], v[198:199], v[200:201], v[182:183]
	v_pk_fma_f32 v[184:185], v[194:195], v[196:197], v[178:179]
	v_cvt_pk_bf16_f32 v180, v182, v183
	v_lshl_add_u64 v[188:189], v[174:175], 0, v[188:189]
	v_cvt_pk_bf16_f32 v181, v184, v185
	global_store_dwordx2 v[192:193], v[180:181], off nt
	global_store_dwordx4 v[188:189], v[182:185], off nt
.LBB0_439:
	s_or_b64 exec, exec, s[0:1]
	v_add_u32_e32 v192, 0x70, v168
	v_and_b32_e32 v139, 28, v192
	v_lshl_or_b32 v134, v139, 8, v131
	s_waitcnt lgkmcnt(2)
	v_lshl_add_u64 v[190:191], s[58:59], 0, v[134:135]
	s_waitcnt vmcnt(0)
	v_add_co_u32_e32 v178, vcc, 0x80000, v190
	ds_bpermute_b32 v188, v129, v12
	s_nop 0
	v_addc_co_u32_e32 v179, vcc, 0, v191, vcc
	global_load_dwordx2 v[184:185], v[178:179], off offset:256
	global_load_dwordx2 v[182:183], v[178:179], off offset:272
	global_load_dwordx2 v[180:181], v[178:179], off offset:288
	s_nop 0
	global_load_dwordx2 v[178:179], v[178:179], off offset:304
	ds_bpermute_b32 v189, v129, v8
	s_waitcnt lgkmcnt(3)
	ds_bpermute_b32 v186, v129, v4
	s_waitcnt lgkmcnt(3)
	ds_bpermute_b32 v187, v129, v0
	s_and_saveexec_b64 s[0:1], s[10:11]
	s_xor_b64 s[0:1], exec, s[0:1]
	s_cbranch_execz .LBB0_443
	s_and_saveexec_b64 s[72:73], s[8:9]
	s_cbranch_execz .LBB0_442
	v_ashrrev_i32_e32 v193, 31, v192
	s_waitcnt lgkmcnt(0)
	v_lshlrev_b64 v[186:187], 5, v[192:193]
	v_lshl_add_u64 v[190:191], v[170:171], 0, v[186:187]
	v_mov_b32_e32 v186, v12
	v_mov_b32_e32 v187, v8
	v_mov_b32_e32 v188, v4
	v_mov_b32_e32 v189, v0
	v_pk_mul_f32 v[186:187], v[186:187], s[88:89] op_sel_hi:[1,0]
	v_pk_mul_f32 v[188:189], v[188:189], s[88:89] op_sel_hi:[1,0]
	global_store_dwordx4 v[190:191], v[186:189], off offset:-128 nt

.LBB0_443:
	s_andn2_saveexec_b64 s[0:1], s[0:1]
	s_cbranch_execz .LBB0_445
	v_add_co_u32_e32 v190, vcc, 0x80000, v190
	v_lshrrev_b32_e32 v134, 5, v192
	s_nop 0
	v_addc_co_u32_e32 v191, vcc, 0, v191, vcc
	global_load_dwordx2 v[196:197], v[190:191], off offset:16
	global_load_dwordx2 v[198:199], v[190:191], off
	v_mul_lo_u32 v134, v134, s12
	v_or_b32_e32 v134, v134, v139
	v_mov_b32_e32 v200, v12
	v_mov_b32_e32 v201, v8
	v_add_u32_e32 v194, 0x1000, v134
	s_waitcnt lgkmcnt(2)
	v_pk_mul_f32 v[188:189], v[172:173], v[188:189] op_sel_hi:[0,1]
	v_ashrrev_i32_e32 v195, 31, v194
	v_lshlrev_b64 v[194:195], 6, v[194:195]
	v_ashrrev_i32_e32 v193, 31, v192
	s_waitcnt lgkmcnt(0)
	v_pk_mul_f32 v[186:187], v[172:173], v[186:187] op_sel_hi:[0,1]
	v_lshl_add_u64 v[194:195], v[176:177], 0, v[194:195]
	v_lshlrev_b64 v[192:193], 7, v[192:193]
	v_lshl_add_u64 v[192:193], v[174:175], 0, v[192:193]
	s_waitcnt vmcnt(1)
	v_mov_b32_e32 v203, v196
	s_waitcnt vmcnt(0)
	v_mov_b32_e32 v202, v198
	v_mov_b32_e32 v196, v199
	global_load_dwordx2 v[198:199], v[190:191], off offset:48
	s_nop 0
	global_load_dwordx2 v[190:191], v[190:191], off offset:32
	v_pk_mul_f32 v[200:201], v[200:201], v[202:203]
	s_waitcnt vmcnt(1)
	v_mov_b32_e32 v203, v198
	v_pk_fma_f32 v[188:189], v[188:189], v[196:197], v[200:201]
	v_mov_b32_e32 v200, v4
	v_mov_b32_e32 v201, v0
	s_waitcnt vmcnt(0)
	v_mov_b32_e32 v202, v190
	v_pk_mul_f32 v[200:201], v[200:201], v[202:203]
	v_mov_b32_e32 v198, v191
	v_cvt_pk_bf16_f32 v196, v188, v189
	v_pk_fma_f32 v[190:191], v[186:187], v[198:199], v[200:201]
	s_nop 0
	v_cvt_pk_bf16_f32 v197, v190, v191
	global_store_dwordx2 v[194:195], v[196:197], off nt
	global_store_dwordx4 v[192:193], v[188:191], off nt
.LBB0_445:
	s_or_b64 exec, exec, s[0:1]
	ds_bpermute_b32 v190, v129, v13
	ds_bpermute_b32 v191, v129, v9
	s_waitcnt lgkmcnt(3)
	ds_bpermute_b32 v186, v129, v5
	s_waitcnt lgkmcnt(3)
	ds_bpermute_b32 v187, v129, v1
	v_add_u32_e32 v188, 0x71, v168
	s_and_saveexec_b64 s[0:1], s[10:11]
	s_xor_b64 s[0:1], exec, s[0:1]
	s_cbranch_execz .LBB0_449
	s_and_saveexec_b64 s[72:73], s[8:9]
	s_cbranch_execz .LBB0_448
	v_ashrrev_i32_e32 v189, 31, v188
	s_waitcnt vmcnt(0)
	v_lshlrev_b64 v[178:179], 5, v[188:189]
	v_lshl_add_u64 v[182:183], v[170:171], 0, v[178:179]
	v_mov_b32_e32 v178, v13
	v_mov_b32_e32 v179, v9
	v_mov_b32_e32 v180, v5
	v_mov_b32_e32 v181, v1
	v_pk_mul_f32 v[178:179], v[178:179], s[88:89] op_sel_hi:[1,0]
	v_pk_mul_f32 v[180:181], v[180:181], s[88:89] op_sel_hi:[1,0]
	global_store_dwordx4 v[182:183], v[178:181], off offset:-128 nt

.LBB0_449:
	s_andn2_saveexec_b64 s[0:1], s[0:1]
	s_cbranch_execz .LBB0_451
	v_lshrrev_b32_e32 v134, 5, v188
	v_mul_lo_u32 v134, v134, s12
	v_and_or_b32 v134, v188, 29, v134
	v_add_u32_e32 v192, 0x1000, v134
	v_ashrrev_i32_e32 v193, 31, v192
	s_waitcnt vmcnt(0)
	v_mov_b32_e32 v197, v178
	v_mov_b32_e32 v200, v184
	v_mov_b32_e32 v201, v182
	s_waitcnt lgkmcnt(2)
	v_pk_mul_f32 v[190:191], v[172:173], v[190:191] op_sel_hi:[0,1]
	v_mov_b32_e32 v182, v185
	s_waitcnt lgkmcnt(0)
	v_pk_mul_f32 v[184:185], v[172:173], v[186:187] op_sel_hi:[0,1]
	v_mov_b32_e32 v178, v181
	v_mov_b32_e32 v194, v5
	v_mov_b32_e32 v195, v1
	v_mov_b32_e32 v196, v180
	v_mov_b32_e32 v198, v13
	v_mov_b32_e32 v199, v9
	v_lshlrev_b64 v[192:193], 6, v[192:193]
	v_ashrrev_i32_e32 v189, 31, v188
	v_pk_mul_f32 v[182:183], v[182:183], v[190:191]
	v_pk_mul_f32 v[178:179], v[178:179], v[184:185]
	v_lshl_add_u64 v[192:193], v[176:177], 0, v[192:193]
	v_lshlrev_b64 v[188:189], 7, v[188:189]
	v_pk_fma_f32 v[182:183], v[198:199], v[200:201], v[182:183]
	v_pk_fma_f32 v[184:185], v[194:195], v[196:197], v[178:179]
	v_cvt_pk_bf16_f32 v180, v182, v183
	v_lshl_add_u64 v[188:189], v[174:175], 0, v[188:189]
	v_cvt_pk_bf16_f32 v181, v184, v185
	global_store_dwordx2 v[192:193], v[180:181], off nt
	global_store_dwordx4 v[188:189], v[182:185], off nt
.LBB0_451:
	s_or_b64 exec, exec, s[0:1]
	v_add_u32_e32 v192, 0x72, v168
	v_and_b32_e32 v139, 30, v192
	v_lshl_or_b32 v134, v139, 8, v131
	s_waitcnt lgkmcnt(2)
	v_lshl_add_u64 v[190:191], s[58:59], 0, v[134:135]
	s_waitcnt vmcnt(0)
	v_add_co_u32_e32 v178, vcc, 0x80000, v190
	ds_bpermute_b32 v188, v129, v14
	s_nop 0
	v_addc_co_u32_e32 v179, vcc, 0, v191, vcc
	global_load_dwordx2 v[184:185], v[178:179], off offset:256
	global_load_dwordx2 v[182:183], v[178:179], off offset:272
	global_load_dwordx2 v[180:181], v[178:179], off offset:288
	s_nop 0
	global_load_dwordx2 v[178:179], v[178:179], off offset:304
	ds_bpermute_b32 v189, v129, v10
	s_waitcnt lgkmcnt(3)
	ds_bpermute_b32 v186, v129, v6
	s_waitcnt lgkmcnt(3)
	ds_bpermute_b32 v187, v129, v2
	s_and_saveexec_b64 s[0:1], s[10:11]
	s_xor_b64 s[0:1], exec, s[0:1]
	s_cbranch_execz .LBB0_455
	s_and_saveexec_b64 s[72:73], s[8:9]
	s_cbranch_execz .LBB0_454
	v_ashrrev_i32_e32 v193, 31, v192
	s_waitcnt lgkmcnt(0)
	v_lshlrev_b64 v[186:187], 5, v[192:193]
	v_lshl_add_u64 v[190:191], v[170:171], 0, v[186:187]
	v_mov_b32_e32 v186, v14
	v_mov_b32_e32 v187, v10
	v_mov_b32_e32 v188, v6
	v_mov_b32_e32 v189, v2
	v_pk_mul_f32 v[186:187], v[186:187], s[88:89] op_sel_hi:[1,0]
	v_pk_mul_f32 v[188:189], v[188:189], s[88:89] op_sel_hi:[1,0]
	global_store_dwordx4 v[190:191], v[186:189], off offset:-128 nt

.LBB0_455:
	s_andn2_saveexec_b64 s[0:1], s[0:1]
	s_cbranch_execz .LBB0_457
	v_add_co_u32_e32 v190, vcc, 0x80000, v190
	v_lshrrev_b32_e32 v131, 5, v192
	s_nop 0
	v_addc_co_u32_e32 v191, vcc, 0, v191, vcc
	global_load_dwordx2 v[196:197], v[190:191], off offset:16
	global_load_dwordx2 v[198:199], v[190:191], off
	v_mul_lo_u32 v131, v131, s12
	v_or_b32_e32 v131, v131, v139
	v_mov_b32_e32 v200, v14
	v_mov_b32_e32 v201, v10
	v_add_u32_e32 v194, 0x1000, v131
	s_waitcnt lgkmcnt(2)
	v_pk_mul_f32 v[188:189], v[172:173], v[188:189] op_sel_hi:[0,1]
	v_ashrrev_i32_e32 v195, 31, v194
	v_lshlrev_b64 v[194:195], 6, v[194:195]
	v_ashrrev_i32_e32 v193, 31, v192
	s_waitcnt lgkmcnt(0)
	v_pk_mul_f32 v[186:187], v[172:173], v[186:187] op_sel_hi:[0,1]
	v_lshl_add_u64 v[194:195], v[176:177], 0, v[194:195]
	v_lshlrev_b64 v[192:193], 7, v[192:193]
	v_lshl_add_u64 v[192:193], v[174:175], 0, v[192:193]
	s_waitcnt vmcnt(1)
	v_mov_b32_e32 v203, v196
	s_waitcnt vmcnt(0)
	v_mov_b32_e32 v202, v198
	v_mov_b32_e32 v196, v199
	global_load_dwordx2 v[198:199], v[190:191], off offset:48
	s_nop 0
	global_load_dwordx2 v[190:191], v[190:191], off offset:32
	v_pk_mul_f32 v[200:201], v[200:201], v[202:203]
	s_waitcnt vmcnt(1)
	v_mov_b32_e32 v203, v198
	v_pk_fma_f32 v[188:189], v[188:189], v[196:197], v[200:201]
	v_mov_b32_e32 v200, v6
	v_mov_b32_e32 v201, v2
	s_waitcnt vmcnt(0)
	v_mov_b32_e32 v202, v190
	v_pk_mul_f32 v[200:201], v[200:201], v[202:203]
	v_mov_b32_e32 v198, v191
	v_cvt_pk_bf16_f32 v196, v188, v189
	v_pk_fma_f32 v[190:191], v[186:187], v[198:199], v[200:201]
	s_nop 0
	v_cvt_pk_bf16_f32 v197, v190, v191
	global_store_dwordx2 v[194:195], v[196:197], off nt
	global_store_dwordx4 v[192:193], v[188:191], off nt
.LBB0_457:
	s_or_b64 exec, exec, s[0:1]
	s_waitcnt lgkmcnt(3)
	ds_bpermute_b32 v188, v129, v15
	s_waitcnt lgkmcnt(3)
	ds_bpermute_b32 v189, v129, v11
	s_waitcnt lgkmcnt(3)
	ds_bpermute_b32 v186, v129, v7
	s_waitcnt lgkmcnt(3)
	ds_bpermute_b32 v187, v129, v3
	v_add_u32_e32 v168, 0x73, v168
	s_and_saveexec_b64 s[0:1], s[10:11]
	s_xor_b64 s[0:1], exec, s[0:1]
	s_cbranch_execz .LBB0_461
	s_and_saveexec_b64 s[10:11], s[8:9]
	s_cbranch_execz .LBB0_460
	v_ashrrev_i32_e32 v169, 31, v168
	v_lshlrev_b64 v[168:169], 5, v[168:169]
	v_lshl_add_u64 v[172:173], v[170:171], 0, v[168:169]
	v_mov_b32_e32 v168, v15
	v_mov_b32_e32 v169, v11
	v_mov_b32_e32 v170, v7
	v_mov_b32_e32 v171, v3
	v_pk_mul_f32 v[168:169], v[168:169], s[88:89] op_sel_hi:[1,0]
	v_pk_mul_f32 v[170:171], v[170:171], s[88:89] op_sel_hi:[1,0]
	global_store_dwordx4 v[172:173], v[168:171], off offset:-128 nt

.LBB0_461:
	s_andn2_saveexec_b64 s[0:1], s[0:1]
	s_cbranch_execz .LBB0_463
	v_lshrrev_b32_e32 v129, 5, v168
	v_mul_lo_u32 v129, v129, s12
	v_and_or_b32 v129, v168, 31, v129
	v_add_u32_e32 v170, 0x1000, v129
	v_ashrrev_i32_e32 v171, 31, v170
	v_ashrrev_i32_e32 v169, 31, v168
	v_lshlrev_b64 v[170:171], 6, v[170:171]
	v_lshlrev_b64 v[168:169], 7, v[168:169]
	s_waitcnt vmcnt(0)
	v_mov_b32_e32 v193, v178
	v_mov_b32_e32 v197, v182
	v_lshl_add_u64 v[176:177], v[176:177], 0, v[170:171]
	v_lshl_add_u64 v[174:175], v[174:175], 0, v[168:169]
	s_waitcnt lgkmcnt(2)
	v_pk_mul_f32 v[168:169], v[172:173], v[188:189] op_sel_hi:[0,1]
	v_mov_b32_e32 v182, v185
	s_waitcnt lgkmcnt(0)
	v_pk_mul_f32 v[170:171], v[172:173], v[186:187] op_sel_hi:[0,1]
	v_mov_b32_e32 v178, v181
	v_mov_b32_e32 v190, v7
	v_mov_b32_e32 v191, v3
	v_mov_b32_e32 v192, v180
	v_mov_b32_e32 v194, v15
	v_mov_b32_e32 v195, v11
	v_mov_b32_e32 v196, v184
	v_pk_mul_f32 v[168:169], v[182:183], v[168:169]
	v_pk_mul_f32 v[170:171], v[178:179], v[170:171]
	v_pk_fma_f32 v[168:169], v[194:195], v[196:197], v[168:169]
	v_pk_fma_f32 v[170:171], v[190:191], v[192:193], v[170:171]
	v_cvt_pk_bf16_f32 v180, v168, v169
	s_nop 0
	v_cvt_pk_bf16_f32 v181, v170, v171
	global_store_dwordx2 v[176:177], v[180:181], off nt
	global_store_dwordx4 v[174:175], v[168:171], off nt

.LBB0_469:
.LBB0_470:
	s_or_saveexec_b64 s[0:1], s[0:1]
	v_mov_b32_e32 v176, s23
	s_xor_b64 exec, exec, s[0:1]
	s_mov_b32 s8, 0x2aaaaaab
	v_mul_hi_i32 v128, v212, s8
	v_lshrrev_b32_e32 v129, 31, v128
	v_ashrrev_i32_e32 v128, 6, v128
	v_add_u32_e32 v176, v128, v129
	s_movk_i32 s8, 0xfe80
	v_mad_i32_i24 v128, v176, s8, v212
	s_or_b64 exec, exec, s[0:1]
	v_and_b32_e32 v175, 15, v210
	v_lshlrev_b32_e32 v174, 2, v175
	v_add_u32_e32 v136, v128, v174
	v_ashrrev_i32_e32 v146, 4, v210
	v_cmp_lt_i32_e32 vcc, 4, v176
	s_mov_b64 s[0:1], 0
	s_mov_b64 s[66:67], 0
	s_mov_b64 s[94:95], 0
	s_and_saveexec_b64 s[8:9], vcc
	s_xor_b64 s[8:9], exec, s[8:9]
	s_cbranch_execz .LBB0_492
	v_cmp_lt_i32_e32 vcc, 7, v176
	s_mov_b64 s[96:97], 0
	s_mov_b64 s[68:69], 0
	s_and_saveexec_b64 s[24:25], vcc
	s_xor_b64 s[66:67], exec, s[24:25]
	s_cbranch_execz .LBB0_483
	v_cmp_lt_i32_e32 vcc, 8, v176
	s_mov_b64 s[72:73], 0
	s_mov_b64 s[74:75], 0
	s_and_saveexec_b64 s[24:25], vcc
	s_xor_b64 s[68:69], exec, s[24:25]
	s_cbranch_execz .LBB0_480
	v_cmp_lt_i32_e32 vcc, 9, v176
	s_mov_b64 s[94:95], -1
	s_and_saveexec_b64 s[72:73], vcc
	s_cbranch_execz .LBB0_479
	v_cmp_eq_u32_e32 vcc, 10, v176
	s_mov_b64 s[34:35], -1
	s_and_saveexec_b64 s[74:75], vcc
	s_cbranch_execz .LBB0_478
	v_mbcnt_hi_u32_b32 v128, -1, v204
	v_and_b32_e32 v131, 64, v128
	v_xor_b32_e32 v129, 4, v128
	v_add_u32_e32 v131, 64, v131
	v_cmp_lt_i32_e32 vcc, v129, v131
	v_readlane_b32 s36, v253, 44
	v_ashrrev_i32_e32 v137, 31, v136
	v_cndmask_b32_e32 v128, v128, v129, vcc
	v_lshlrev_b32_e32 v138, 2, v128
	v_and_b32_e32 v128, 4, v210
	v_cmp_eq_u32_e32 vcc, 0, v128
	v_readlane_b32 s46, v253, 54
	v_readlane_b32 s47, v253, 55
	v_lshlrev_b32_e32 v131, 3, v210
	v_lshl_add_u32 v130, v146, 2, v211
	v_cndmask_b32_e64 v134, 1.0, -1.0, vcc
	v_readlane_b32 s37, v253, 45
	v_readlane_b32 s38, v253, 46
	v_readlane_b32 s39, v253, 47
	v_readlane_b32 s40, v253, 48
	v_readlane_b32 s41, v253, 49
	v_readlane_b32 s42, v253, 50
	v_readlane_b32 s43, v253, 51
	v_readlane_b32 s44, v253, 52
	v_readlane_b32 s45, v253, 53
	v_readlane_b32 s48, v253, 56
	v_readlane_b32 s49, v253, 57
	v_readlane_b32 s50, v253, 58
	v_readlane_b32 s51, v253, 59
	v_lshl_add_u64 v[128:129], v[136:137], 1, s[46:47]
	v_and_b32_e32 v137, 24, v131
	v_lshlrev_b32_e32 v131, 5, v130
	v_and_or_b32 v131, v131, s17, v137
	v_lshlrev_b32_e32 v139, 3, v131
	global_load_dwordx2 v[142:143], v139, s[58:59]
	global_load_dwordx2 v[150:151], v139, s[58:59] offset:256
	ds_bpermute_b32 v131, v138, v124
	v_mov_b32_e32 v140, v124
	ds_bpermute_b32 v144, v138, v120
	ds_bpermute_b32 v145, v138, v116
	ds_bpermute_b32 v147, v138, v112
	s_waitcnt lgkmcnt(3)
	v_mul_f32_e32 v141, v134, v131
	v_ashrrev_i32_e32 v131, 31, v130
	ds_bpermute_b32 v152, v138, v113
	s_waitcnt vmcnt(1)
	v_pk_mul_f32 v[140:141], v[140:141], v[142:143]
	global_load_dwordx2 v[142:143], v139, s[58:59] offset:16
	v_add_f32_e32 v148, v140, v141
	s_waitcnt lgkmcnt(3)
	v_mul_f32_e32 v141, v134, v144
	v_mov_b32_e32 v140, v120
	s_waitcnt vmcnt(0)
	v_pk_mul_f32 v[140:141], v[140:141], v[142:143]
	global_load_dwordx2 v[142:143], v139, s[58:59] offset:32
	v_add_f32_e32 v144, v140, v141
	s_waitcnt lgkmcnt(2)
	v_mul_f32_e32 v141, v134, v145
	v_mov_b32_e32 v140, v116
	s_waitcnt vmcnt(0)
	v_pk_mul_f32 v[140:141], v[140:141], v[142:143]
	global_load_dwordx2 v[142:143], v139, s[58:59] offset:48
	v_add_f32_e32 v145, v140, v141
	s_waitcnt lgkmcnt(1)
	v_mul_f32_e32 v141, v134, v147
	v_mov_b32_e32 v140, v112
	ds_bpermute_b32 v147, v138, v117
	s_waitcnt vmcnt(0)
	v_pk_mul_f32 v[140:141], v[140:141], v[142:143]
	s_nop 0
	v_add_f32_e32 v143, v140, v141
	v_lshlrev_b64 v[140:141], 9, v[130:131]
	ds_bpermute_b32 v131, v138, v125
	v_cvt_pk_bf16_f32 v142, v148, v144
	v_mov_b32_e32 v148, v125
	v_cvt_pk_bf16_f32 v143, v145, v143
	ds_bpermute_b32 v145, v138, v121
	s_waitcnt lgkmcnt(1)
	v_mul_f32_e32 v149, v134, v131
	v_pk_mul_f32 v[148:149], v[148:149], v[150:151]
	global_load_dwordx2 v[150:151], v139, s[58:59] offset:272
	v_add_f32_e32 v131, v148, v149
	s_waitcnt lgkmcnt(0)
	v_mul_f32_e32 v149, v134, v145
	v_mov_b32_e32 v148, v121
	v_lshl_add_u64 v[140:141], v[128:129], 0, v[140:141]
	v_or_b32_e32 v144, 1, v130
	s_waitcnt vmcnt(0)
	v_pk_mul_f32 v[148:149], v[148:149], v[150:151]
	global_load_dwordx2 v[150:151], v139, s[58:59] offset:288
	v_add_f32_e32 v153, v148, v149
	v_mul_f32_e32 v149, v134, v147
	v_mov_b32_e32 v148, v117
	s_waitcnt vmcnt(0)
	v_pk_mul_f32 v[148:149], v[148:149], v[150:151]
	global_load_dwordx2 v[150:151], v139, s[58:59] offset:304
	v_add_f32_e32 v147, v148, v149
	v_mul_f32_e32 v149, v134, v152
	global_store_dwordx2 v[140:141], v[142:143], off nt
	v_mov_b32_e32 v148, v113
	s_waitcnt vmcnt(1)
	v_pk_mul_f32 v[140:141], v[148:149], v[150:151]
	v_ashrrev_i32_e32 v145, 31, v144
	v_add_f32_e32 v139, v140, v141
	v_lshlrev_b64 v[140:141], 9, v[144:145]
	v_lshl_add_u64 v[140:141], v[128:129], 0, v[140:141]
	v_cvt_pk_bf16_f32 v142, v131, v153
	v_cvt_pk_bf16_f32 v143, v147, v139
	global_store_dwordx2 v[140:141], v[142:143], off nt
	v_or_b32_e32 v140, 2, v130
	v_lshlrev_b32_e32 v131, 5, v140
	v_and_or_b32 v131, v131, s18, v137
	v_lshlrev_b32_e32 v131, 3, v131
	global_load_dwordx2 v[144:145], v131, s[58:59]
	global_load_dwordx2 v[150:151], v131, s[58:59] offset:256
	ds_bpermute_b32 v139, v138, v126
	v_mov_b32_e32 v142, v126
	ds_bpermute_b32 v141, v138, v122
	ds_bpermute_b32 v147, v138, v118
	ds_bpermute_b32 v148, v138, v114
	s_waitcnt lgkmcnt(3)
	v_mul_f32_e32 v143, v134, v139
	ds_bpermute_b32 v152, v138, v115
	s_waitcnt vmcnt(1)
	v_pk_mul_f32 v[142:143], v[142:143], v[144:145]
	global_load_dwordx2 v[144:145], v131, s[58:59] offset:16
	v_add_f32_e32 v139, v142, v143
	s_waitcnt lgkmcnt(3)
	v_mul_f32_e32 v143, v134, v141
	v_mov_b32_e32 v142, v122
	v_ashrrev_i32_e32 v141, 31, v140
	v_lshlrev_b64 v[140:141], 9, v[140:141]
	v_lshl_add_u64 v[140:141], v[128:129], 0, v[140:141]
	s_waitcnt vmcnt(0)
	v_pk_mul_f32 v[142:143], v[142:143], v[144:145]
	global_load_dwordx2 v[144:145], v131, s[58:59] offset:32
	v_add_f32_e32 v149, v142, v143
	s_waitcnt lgkmcnt(2)
	v_mul_f32_e32 v143, v134, v147
	v_mov_b32_e32 v142, v118
	s_waitcnt vmcnt(0)
	v_pk_mul_f32 v[142:143], v[142:143], v[144:145]
	global_load_dwordx2 v[144:145], v131, s[58:59] offset:48
	v_add_f32_e32 v147, v142, v143
	s_waitcnt lgkmcnt(1)
	v_mul_f32_e32 v143, v134, v148
	v_mov_b32_e32 v142, v114
	v_mov_b32_e32 v148, v127
	s_waitcnt vmcnt(0)
	v_pk_mul_f32 v[142:143], v[142:143], v[144:145]
	s_nop 0
	v_add_f32_e32 v143, v142, v143
	v_cvt_pk_bf16_f32 v142, v139, v149
	ds_bpermute_b32 v139, v138, v127
	ds_bpermute_b32 v145, v138, v123
	v_cvt_pk_bf16_f32 v143, v147, v143
	ds_bpermute_b32 v147, v138, v119
	v_or_b32_e32 v144, 3, v130
	s_waitcnt lgkmcnt(2)
	v_mul_f32_e32 v149, v134, v139
	v_pk_mul_f32 v[148:149], v[148:149], v[150:151]
	global_load_dwordx2 v[150:151], v131, s[58:59] offset:272
	v_add_f32_e32 v139, v148, v149
	s_waitcnt lgkmcnt(1)
	v_mul_f32_e32 v149, v134, v145
	v_mov_b32_e32 v148, v123
	s_waitcnt vmcnt(0)
	v_pk_mul_f32 v[148:149], v[148:149], v[150:151]
	global_load_dwordx2 v[150:151], v131, s[58:59] offset:288
	v_add_f32_e32 v153, v148, v149
	s_waitcnt lgkmcnt(0)
	v_mul_f32_e32 v149, v134, v147
	v_mov_b32_e32 v148, v119
	s_waitcnt vmcnt(0)
	v_pk_mul_f32 v[148:149], v[148:149], v[150:151]
	global_load_dwordx2 v[150:151], v131, s[58:59] offset:304
	v_add_f32_e32 v147, v148, v149
	v_mul_f32_e32 v149, v134, v152
	global_store_dwordx2 v[140:141], v[142:143], off nt
	v_mov_b32_e32 v148, v115
	s_waitcnt vmcnt(1)
	v_pk_mul_f32 v[140:141], v[148:149], v[150:151]
	v_ashrrev_i32_e32 v145, 31, v144
	v_add_f32_e32 v131, v140, v141
	v_lshlrev_b64 v[140:141], 9, v[144:145]
	v_lshl_add_u64 v[140:141], v[128:129], 0, v[140:141]
	v_cvt_pk_bf16_f32 v142, v139, v153
	v_cvt_pk_bf16_f32 v143, v147, v131
	global_store_dwordx2 v[140:141], v[142:143], off nt
	v_add_u32_e32 v140, 16, v130
	v_lshlrev_b32_e32 v131, 5, v140
	v_and_or_b32 v131, v131, s17, v137
	v_lshlrev_b32_e32 v131, 3, v131
	global_load_dwordx2 v[144:145], v131, s[58:59]
	global_load_dwordx2 v[150:151], v131, s[58:59] offset:256
	ds_bpermute_b32 v139, v138, v108
	v_mov_b32_e32 v142, v108
	ds_bpermute_b32 v141, v138, v104
	ds_bpermute_b32 v147, v138, v100
	ds_bpermute_b32 v148, v138, v96
	s_waitcnt lgkmcnt(3)
	v_mul_f32_e32 v143, v134, v139
	ds_bpermute_b32 v152, v138, v97
	s_waitcnt vmcnt(1)
	v_pk_mul_f32 v[142:143], v[142:143], v[144:145]
	global_load_dwordx2 v[144:145], v131, s[58:59] offset:16
	v_add_f32_e32 v139, v142, v143
	s_waitcnt lgkmcnt(3)
	v_mul_f32_e32 v143, v134, v141
	v_mov_b32_e32 v142, v104
	v_ashrrev_i32_e32 v141, 31, v140
	v_lshlrev_b64 v[140:141], 9, v[140:141]
	v_lshl_add_u64 v[140:141], v[128:129], 0, v[140:141]
	s_waitcnt vmcnt(0)
	v_pk_mul_f32 v[142:143], v[142:143], v[144:145]
	global_load_dwordx2 v[144:145], v131, s[58:59] offset:32
	v_add_f32_e32 v149, v142, v143
	s_waitcnt lgkmcnt(2)
	v_mul_f32_e32 v143, v134, v147
	v_mov_b32_e32 v142, v100
	s_waitcnt vmcnt(0)
	v_pk_mul_f32 v[142:143], v[142:143], v[144:145]
	global_load_dwordx2 v[144:145], v131, s[58:59] offset:48
	v_add_f32_e32 v147, v142, v143
	s_waitcnt lgkmcnt(1)
	v_mul_f32_e32 v143, v134, v148
	v_mov_b32_e32 v142, v96
	v_mov_b32_e32 v148, v109
	s_waitcnt vmcnt(0)
	v_pk_mul_f32 v[142:143], v[142:143], v[144:145]
	s_nop 0
	v_add_f32_e32 v143, v142, v143
	v_cvt_pk_bf16_f32 v142, v139, v149
	ds_bpermute_b32 v139, v138, v109
	ds_bpermute_b32 v145, v138, v105
	v_cvt_pk_bf16_f32 v143, v147, v143
	ds_bpermute_b32 v147, v138, v101
	v_add_u32_e32 v144, 17, v130
	s_waitcnt lgkmcnt(2)
	v_mul_f32_e32 v149, v134, v139
	v_pk_mul_f32 v[148:149], v[148:149], v[150:151]
	global_load_dwordx2 v[150:151], v131, s[58:59] offset:272
	v_add_f32_e32 v139, v148, v149
	s_waitcnt lgkmcnt(1)
	v_mul_f32_e32 v149, v134, v145
	v_mov_b32_e32 v148, v105
	s_waitcnt vmcnt(0)
	v_pk_mul_f32 v[148:149], v[148:149], v[150:151]
	global_load_dwordx2 v[150:151], v131, s[58:59] offset:288
	v_add_f32_e32 v153, v148, v149
	s_waitcnt lgkmcnt(0)
	v_mul_f32_e32 v149, v134, v147
	v_mov_b32_e32 v148, v101
	s_waitcnt vmcnt(0)
	v_pk_mul_f32 v[148:149], v[148:149], v[150:151]
	global_load_dwordx2 v[150:151], v131, s[58:59] offset:304
	v_add_f32_e32 v147, v148, v149
	v_mul_f32_e32 v149, v134, v152
	global_store_dwordx2 v[140:141], v[142:143], off nt
	v_mov_b32_e32 v148, v97
	s_waitcnt vmcnt(1)
	v_pk_mul_f32 v[140:141], v[148:149], v[150:151]
	v_ashrrev_i32_e32 v145, 31, v144
	v_add_f32_e32 v131, v140, v141
	v_lshlrev_b64 v[140:141], 9, v[144:145]
	v_lshl_add_u64 v[140:141], v[128:129], 0, v[140:141]
	v_cvt_pk_bf16_f32 v142, v139, v153
	v_cvt_pk_bf16_f32 v143, v147, v131
	global_store_dwordx2 v[140:141], v[142:143], off nt
	v_add_u32_e32 v140, 18, v130
	v_lshlrev_b32_e32 v131, 5, v140
	v_and_or_b32 v131, v131, s18, v137
	v_lshlrev_b32_e32 v131, 3, v131
	global_load_dwordx2 v[144:145], v131, s[58:59]
	global_load_dwordx2 v[150:151], v131, s[58:59] offset:256
	ds_bpermute_b32 v139, v138, v110
	v_mov_b32_e32 v142, v110
	ds_bpermute_b32 v141, v138, v106
	ds_bpermute_b32 v147, v138, v102
	ds_bpermute_b32 v148, v138, v98
	s_waitcnt lgkmcnt(3)
	v_mul_f32_e32 v143, v134, v139
	ds_bpermute_b32 v152, v138, v99
	s_waitcnt vmcnt(1)
	v_pk_mul_f32 v[142:143], v[142:143], v[144:145]
	global_load_dwordx2 v[144:145], v131, s[58:59] offset:16
	v_add_f32_e32 v139, v142, v143
	s_waitcnt lgkmcnt(3)
	v_mul_f32_e32 v143, v134, v141
	v_mov_b32_e32 v142, v106
	v_ashrrev_i32_e32 v141, 31, v140
	v_lshlrev_b64 v[140:141], 9, v[140:141]
	v_lshl_add_u64 v[140:141], v[128:129], 0, v[140:141]
	s_waitcnt vmcnt(0)
	v_pk_mul_f32 v[142:143], v[142:143], v[144:145]
	global_load_dwordx2 v[144:145], v131, s[58:59] offset:32
	v_add_f32_e32 v149, v142, v143
	s_waitcnt lgkmcnt(2)
	v_mul_f32_e32 v143, v134, v147
	v_mov_b32_e32 v142, v102
	s_waitcnt vmcnt(0)
	v_pk_mul_f32 v[142:143], v[142:143], v[144:145]
	global_load_dwordx2 v[144:145], v131, s[58:59] offset:48
	v_add_f32_e32 v147, v142, v143
	s_waitcnt lgkmcnt(1)
	v_mul_f32_e32 v143, v134, v148
	v_mov_b32_e32 v142, v98
	v_mov_b32_e32 v148, v111
	s_waitcnt vmcnt(0)
	v_pk_mul_f32 v[142:143], v[142:143], v[144:145]
	s_nop 0
	v_add_f32_e32 v143, v142, v143
	v_cvt_pk_bf16_f32 v142, v139, v149
	ds_bpermute_b32 v139, v138, v111
	ds_bpermute_b32 v145, v138, v107
	v_cvt_pk_bf16_f32 v143, v147, v143
	ds_bpermute_b32 v147, v138, v103
	v_add_u32_e32 v144, 19, v130
	s_waitcnt lgkmcnt(2)
	v_mul_f32_e32 v149, v134, v139
	v_pk_mul_f32 v[148:149], v[148:149], v[150:151]
	global_load_dwordx2 v[150:151], v131, s[58:59] offset:272
	v_add_f32_e32 v139, v148, v149
	s_waitcnt lgkmcnt(1)
	v_mul_f32_e32 v149, v134, v145
	v_mov_b32_e32 v148, v107
	s_waitcnt vmcnt(0)
	v_pk_mul_f32 v[148:149], v[148:149], v[150:151]
	global_load_dwordx2 v[150:151], v131, s[58:59] offset:288
	v_add_f32_e32 v153, v148, v149
	s_waitcnt lgkmcnt(0)
	v_mul_f32_e32 v149, v134, v147
	v_mov_b32_e32 v148, v103
	s_waitcnt vmcnt(0)
	v_pk_mul_f32 v[148:149], v[148:149], v[150:151]
	global_load_dwordx2 v[150:151], v131, s[58:59] offset:304
	v_add_f32_e32 v147, v148, v149
	v_mul_f32_e32 v149, v134, v152
	global_store_dwordx2 v[140:141], v[142:143], off nt
	v_mov_b32_e32 v148, v99
	s_waitcnt vmcnt(1)
	v_pk_mul_f32 v[140:141], v[148:149], v[150:151]
	v_ashrrev_i32_e32 v145, 31, v144
	v_add_f32_e32 v131, v140, v141
	v_lshlrev_b64 v[140:141], 9, v[144:145]
	v_lshl_add_u64 v[140:141], v[128:129], 0, v[140:141]
	v_cvt_pk_bf16_f32 v142, v139, v153
	v_cvt_pk_bf16_f32 v143, v147, v131
	global_store_dwordx2 v[140:141], v[142:143], off nt
	v_add_u32_e32 v140, 32, v130
	v_lshlrev_b32_e32 v131, 5, v140
	v_and_or_b32 v131, v131, s17, v137
	v_lshlrev_b32_e32 v131, 3, v131
	global_load_dwordx2 v[144:145], v131, s[58:59]
	global_load_dwordx2 v[150:151], v131, s[58:59] offset:256
	ds_bpermute_b32 v139, v138, v92
	v_mov_b32_e32 v142, v92
	ds_bpermute_b32 v141, v138, v88
	ds_bpermute_b32 v147, v138, v84
	ds_bpermute_b32 v148, v138, v80
	s_waitcnt lgkmcnt(3)
	v_mul_f32_e32 v143, v134, v139
	ds_bpermute_b32 v152, v138, v81
	s_waitcnt vmcnt(1)
	v_pk_mul_f32 v[142:143], v[142:143], v[144:145]
	global_load_dwordx2 v[144:145], v131, s[58:59] offset:16
	v_add_f32_e32 v139, v142, v143
	s_waitcnt lgkmcnt(3)
	v_mul_f32_e32 v143, v134, v141
	v_mov_b32_e32 v142, v88
	v_ashrrev_i32_e32 v141, 31, v140
	v_lshlrev_b64 v[140:141], 9, v[140:141]
	v_lshl_add_u64 v[140:141], v[128:129], 0, v[140:141]
	s_waitcnt vmcnt(0)
	v_pk_mul_f32 v[142:143], v[142:143], v[144:145]
	global_load_dwordx2 v[144:145], v131, s[58:59] offset:32
	v_add_f32_e32 v149, v142, v143
	s_waitcnt lgkmcnt(2)
	v_mul_f32_e32 v143, v134, v147
	v_mov_b32_e32 v142, v84
	s_waitcnt vmcnt(0)
	v_pk_mul_f32 v[142:143], v[142:143], v[144:145]
	global_load_dwordx2 v[144:145], v131, s[58:59] offset:48
	v_add_f32_e32 v147, v142, v143
	s_waitcnt lgkmcnt(1)
	v_mul_f32_e32 v143, v134, v148
	v_mov_b32_e32 v142, v80
	v_mov_b32_e32 v148, v93
	s_waitcnt vmcnt(0)
	v_pk_mul_f32 v[142:143], v[142:143], v[144:145]
	s_nop 0
	v_add_f32_e32 v143, v142, v143
	v_cvt_pk_bf16_f32 v142, v139, v149
	ds_bpermute_b32 v139, v138, v93
	ds_bpermute_b32 v145, v138, v89
	v_cvt_pk_bf16_f32 v143, v147, v143
	ds_bpermute_b32 v147, v138, v85
	v_add_u32_e32 v144, 33, v130
	s_waitcnt lgkmcnt(2)
	v_mul_f32_e32 v149, v134, v139
	v_pk_mul_f32 v[148:149], v[148:149], v[150:151]
	global_load_dwordx2 v[150:151], v131, s[58:59] offset:272
	v_add_f32_e32 v139, v148, v149
	s_waitcnt lgkmcnt(1)
	v_mul_f32_e32 v149, v134, v145
	v_mov_b32_e32 v148, v89
	s_waitcnt vmcnt(0)
	v_pk_mul_f32 v[148:149], v[148:149], v[150:151]
	global_load_dwordx2 v[150:151], v131, s[58:59] offset:288
	v_add_f32_e32 v153, v148, v149
	s_waitcnt lgkmcnt(0)
	v_mul_f32_e32 v149, v134, v147
	v_mov_b32_e32 v148, v85
	s_waitcnt vmcnt(0)
	v_pk_mul_f32 v[148:149], v[148:149], v[150:151]
	global_load_dwordx2 v[150:151], v131, s[58:59] offset:304
	v_add_f32_e32 v147, v148, v149
	v_mul_f32_e32 v149, v134, v152
	global_store_dwordx2 v[140:141], v[142:143], off nt
	v_mov_b32_e32 v148, v81
	s_waitcnt vmcnt(1)
	v_pk_mul_f32 v[140:141], v[148:149], v[150:151]
	v_ashrrev_i32_e32 v145, 31, v144
	v_add_f32_e32 v131, v140, v141
	v_lshlrev_b64 v[140:141], 9, v[144:145]
	v_lshl_add_u64 v[140:141], v[128:129], 0, v[140:141]
	v_cvt_pk_bf16_f32 v142, v139, v153
	v_cvt_pk_bf16_f32 v143, v147, v131
	global_store_dwordx2 v[140:141], v[142:143], off nt
	v_add_u32_e32 v140, 34, v130
	v_lshlrev_b32_e32 v131, 5, v140
	v_and_or_b32 v131, v131, s18, v137
	v_lshlrev_b32_e32 v131, 3, v131
	global_load_dwordx2 v[144:145], v131, s[58:59]
	global_load_dwordx2 v[150:151], v131, s[58:59] offset:256
	ds_bpermute_b32 v139, v138, v94
	v_mov_b32_e32 v142, v94
	ds_bpermute_b32 v141, v138, v90
	ds_bpermute_b32 v147, v138, v86
	ds_bpermute_b32 v148, v138, v82
	s_waitcnt lgkmcnt(3)
	v_mul_f32_e32 v143, v134, v139
	ds_bpermute_b32 v152, v138, v83
	s_waitcnt vmcnt(1)
	v_pk_mul_f32 v[142:143], v[142:143], v[144:145]
	global_load_dwordx2 v[144:145], v131, s[58:59] offset:16
	v_add_f32_e32 v139, v142, v143
	s_waitcnt lgkmcnt(3)
	v_mul_f32_e32 v143, v134, v141
	v_mov_b32_e32 v142, v90
	v_ashrrev_i32_e32 v141, 31, v140
	v_lshlrev_b64 v[140:141], 9, v[140:141]
	v_lshl_add_u64 v[140:141], v[128:129], 0, v[140:141]
	s_waitcnt vmcnt(0)
	v_pk_mul_f32 v[142:143], v[142:143], v[144:145]
	global_load_dwordx2 v[144:145], v131, s[58:59] offset:32
	v_add_f32_e32 v149, v142, v143
	s_waitcnt lgkmcnt(2)
	v_mul_f32_e32 v143, v134, v147
	v_mov_b32_e32 v142, v86
	s_waitcnt vmcnt(0)
	v_pk_mul_f32 v[142:143], v[142:143], v[144:145]
	global_load_dwordx2 v[144:145], v131, s[58:59] offset:48
	v_add_f32_e32 v147, v142, v143
	s_waitcnt lgkmcnt(1)
	v_mul_f32_e32 v143, v134, v148
	v_mov_b32_e32 v142, v82
	v_mov_b32_e32 v148, v95
	s_waitcnt vmcnt(0)
	v_pk_mul_f32 v[142:143], v[142:143], v[144:145]
	s_nop 0
	v_add_f32_e32 v143, v142, v143
	v_cvt_pk_bf16_f32 v142, v139, v149
	ds_bpermute_b32 v139, v138, v95
	ds_bpermute_b32 v145, v138, v91
	v_cvt_pk_bf16_f32 v143, v147, v143
	ds_bpermute_b32 v147, v138, v87
	v_add_u32_e32 v144, 35, v130
	s_waitcnt lgkmcnt(2)
	v_mul_f32_e32 v149, v134, v139
	v_pk_mul_f32 v[148:149], v[148:149], v[150:151]
	global_load_dwordx2 v[150:151], v131, s[58:59] offset:272
	v_add_f32_e32 v139, v148, v149
	s_waitcnt lgkmcnt(1)
	v_mul_f32_e32 v149, v134, v145
	v_mov_b32_e32 v148, v91
	s_waitcnt vmcnt(0)
	v_pk_mul_f32 v[148:149], v[148:149], v[150:151]
	global_load_dwordx2 v[150:151], v131, s[58:59] offset:288
	v_add_f32_e32 v153, v148, v149
	s_waitcnt lgkmcnt(0)
	v_mul_f32_e32 v149, v134, v147
	v_mov_b32_e32 v148, v87
	s_waitcnt vmcnt(0)
	v_pk_mul_f32 v[148:149], v[148:149], v[150:151]
	global_load_dwordx2 v[150:151], v131, s[58:59] offset:304
	v_add_f32_e32 v147, v148, v149
	v_mul_f32_e32 v149, v134, v152
	global_store_dwordx2 v[140:141], v[142:143], off nt
	v_mov_b32_e32 v148, v83
	s_waitcnt vmcnt(1)
	v_pk_mul_f32 v[140:141], v[148:149], v[150:151]
	v_ashrrev_i32_e32 v145, 31, v144
	v_add_f32_e32 v131, v140, v141
	v_lshlrev_b64 v[140:141], 9, v[144:145]
	v_lshl_add_u64 v[140:141], v[128:129], 0, v[140:141]
	v_cvt_pk_bf16_f32 v142, v139, v153
	v_cvt_pk_bf16_f32 v143, v147, v131
	global_store_dwordx2 v[140:141], v[142:143], off nt
	v_add_u32_e32 v140, 48, v130
	v_lshlrev_b32_e32 v131, 5, v140
	v_and_or_b32 v131, v131, s17, v137
	v_lshlrev_b32_e32 v131, 3, v131
	global_load_dwordx2 v[144:145], v131, s[58:59]
	global_load_dwordx2 v[150:151], v131, s[58:59] offset:256
	ds_bpermute_b32 v139, v138, v76
	v_mov_b32_e32 v142, v76
	ds_bpermute_b32 v141, v138, v72
	ds_bpermute_b32 v147, v138, v68
	ds_bpermute_b32 v148, v138, v64
	s_waitcnt lgkmcnt(3)
	v_mul_f32_e32 v143, v134, v139
	ds_bpermute_b32 v152, v138, v65
	s_waitcnt vmcnt(1)
	v_pk_mul_f32 v[142:143], v[142:143], v[144:145]
	global_load_dwordx2 v[144:145], v131, s[58:59] offset:16
	v_add_f32_e32 v139, v142, v143
	s_waitcnt lgkmcnt(3)
	v_mul_f32_e32 v143, v134, v141
	v_mov_b32_e32 v142, v72
	v_ashrrev_i32_e32 v141, 31, v140
	v_lshlrev_b64 v[140:141], 9, v[140:141]
	v_lshl_add_u64 v[140:141], v[128:129], 0, v[140:141]
	s_waitcnt vmcnt(0)
	v_pk_mul_f32 v[142:143], v[142:143], v[144:145]
	global_load_dwordx2 v[144:145], v131, s[58:59] offset:32
	v_add_f32_e32 v149, v142, v143
	s_waitcnt lgkmcnt(2)
	v_mul_f32_e32 v143, v134, v147
	v_mov_b32_e32 v142, v68
	s_waitcnt vmcnt(0)
	v_pk_mul_f32 v[142:143], v[142:143], v[144:145]
	global_load_dwordx2 v[144:145], v131, s[58:59] offset:48
	v_add_f32_e32 v147, v142, v143
	s_waitcnt lgkmcnt(1)
	v_mul_f32_e32 v143, v134, v148
	v_mov_b32_e32 v142, v64
	v_mov_b32_e32 v148, v77
	s_waitcnt vmcnt(0)
	v_pk_mul_f32 v[142:143], v[142:143], v[144:145]
	s_nop 0
	v_add_f32_e32 v143, v142, v143
	v_cvt_pk_bf16_f32 v142, v139, v149
	ds_bpermute_b32 v139, v138, v77
	ds_bpermute_b32 v145, v138, v73
	v_cvt_pk_bf16_f32 v143, v147, v143
	ds_bpermute_b32 v147, v138, v69
	v_add_u32_e32 v144, 49, v130
	s_waitcnt lgkmcnt(2)
	v_mul_f32_e32 v149, v134, v139
	v_pk_mul_f32 v[148:149], v[148:149], v[150:151]
	global_load_dwordx2 v[150:151], v131, s[58:59] offset:272
	v_add_f32_e32 v139, v148, v149
	s_waitcnt lgkmcnt(1)
	v_mul_f32_e32 v149, v134, v145
	v_mov_b32_e32 v148, v73
	s_waitcnt vmcnt(0)
	v_pk_mul_f32 v[148:149], v[148:149], v[150:151]
	global_load_dwordx2 v[150:151], v131, s[58:59] offset:288
	v_add_f32_e32 v153, v148, v149
	s_waitcnt lgkmcnt(0)
	v_mul_f32_e32 v149, v134, v147
	v_mov_b32_e32 v148, v69
	s_waitcnt vmcnt(0)
	v_pk_mul_f32 v[148:149], v[148:149], v[150:151]
	global_load_dwordx2 v[150:151], v131, s[58:59] offset:304
	v_add_f32_e32 v147, v148, v149
	v_mul_f32_e32 v149, v134, v152
	global_store_dwordx2 v[140:141], v[142:143], off nt
	v_mov_b32_e32 v148, v65
	s_waitcnt vmcnt(1)
	v_pk_mul_f32 v[140:141], v[148:149], v[150:151]
	v_ashrrev_i32_e32 v145, 31, v144
	v_add_f32_e32 v131, v140, v141
	v_lshlrev_b64 v[140:141], 9, v[144:145]
	v_lshl_add_u64 v[140:141], v[128:129], 0, v[140:141]
	v_cvt_pk_bf16_f32 v142, v139, v153
	v_cvt_pk_bf16_f32 v143, v147, v131
	global_store_dwordx2 v[140:141], v[142:143], off nt
	v_add_u32_e32 v140, 50, v130
	v_lshlrev_b32_e32 v131, 5, v140
	v_and_or_b32 v131, v131, s18, v137
	v_lshlrev_b32_e32 v131, 3, v131
	global_load_dwordx2 v[144:145], v131, s[58:59]
	global_load_dwordx2 v[150:151], v131, s[58:59] offset:256
	ds_bpermute_b32 v139, v138, v78
	v_mov_b32_e32 v142, v78
	ds_bpermute_b32 v141, v138, v74
	ds_bpermute_b32 v147, v138, v70
	ds_bpermute_b32 v148, v138, v66
	s_waitcnt lgkmcnt(3)
	v_mul_f32_e32 v143, v134, v139
	ds_bpermute_b32 v152, v138, v67
	s_waitcnt vmcnt(1)
	v_pk_mul_f32 v[142:143], v[142:143], v[144:145]
	global_load_dwordx2 v[144:145], v131, s[58:59] offset:16
	v_add_f32_e32 v139, v142, v143
	s_waitcnt lgkmcnt(3)
	v_mul_f32_e32 v143, v134, v141
	v_mov_b32_e32 v142, v74
	v_ashrrev_i32_e32 v141, 31, v140
	v_lshlrev_b64 v[140:141], 9, v[140:141]
	v_lshl_add_u64 v[140:141], v[128:129], 0, v[140:141]
	s_waitcnt vmcnt(0)
	v_pk_mul_f32 v[142:143], v[142:143], v[144:145]
	global_load_dwordx2 v[144:145], v131, s[58:59] offset:32
	v_add_f32_e32 v149, v142, v143
	s_waitcnt lgkmcnt(2)
	v_mul_f32_e32 v143, v134, v147
	v_mov_b32_e32 v142, v70
	s_waitcnt vmcnt(0)
	v_pk_mul_f32 v[142:143], v[142:143], v[144:145]
	global_load_dwordx2 v[144:145], v131, s[58:59] offset:48
	v_add_f32_e32 v147, v142, v143
	s_waitcnt lgkmcnt(1)
	v_mul_f32_e32 v143, v134, v148
	v_mov_b32_e32 v142, v66
	v_mov_b32_e32 v148, v79
	s_waitcnt vmcnt(0)
	v_pk_mul_f32 v[142:143], v[142:143], v[144:145]
	s_nop 0
	v_add_f32_e32 v143, v142, v143
	v_cvt_pk_bf16_f32 v142, v139, v149
	ds_bpermute_b32 v139, v138, v79
	ds_bpermute_b32 v145, v138, v75
	v_cvt_pk_bf16_f32 v143, v147, v143
	ds_bpermute_b32 v147, v138, v71
	v_add_u32_e32 v144, 51, v130
	s_waitcnt lgkmcnt(2)
	v_mul_f32_e32 v149, v134, v139
	v_pk_mul_f32 v[148:149], v[148:149], v[150:151]
	global_load_dwordx2 v[150:151], v131, s[58:59] offset:272
	v_add_f32_e32 v139, v148, v149
	s_waitcnt lgkmcnt(1)
	v_mul_f32_e32 v149, v134, v145
	v_mov_b32_e32 v148, v75
	s_waitcnt vmcnt(0)
	v_pk_mul_f32 v[148:149], v[148:149], v[150:151]
	global_load_dwordx2 v[150:151], v131, s[58:59] offset:288
	v_add_f32_e32 v153, v148, v149
	s_waitcnt lgkmcnt(0)
	v_mul_f32_e32 v149, v134, v147
	v_mov_b32_e32 v148, v71
	s_waitcnt vmcnt(0)
	v_pk_mul_f32 v[148:149], v[148:149], v[150:151]
	global_load_dwordx2 v[150:151], v131, s[58:59] offset:304
	v_add_f32_e32 v147, v148, v149
	v_mul_f32_e32 v149, v134, v152
	global_store_dwordx2 v[140:141], v[142:143], off nt
	v_mov_b32_e32 v148, v67
	s_waitcnt vmcnt(1)
	v_pk_mul_f32 v[140:141], v[148:149], v[150:151]
	v_ashrrev_i32_e32 v145, 31, v144
	v_add_f32_e32 v131, v140, v141
	v_lshlrev_b64 v[140:141], 9, v[144:145]
	v_lshl_add_u64 v[140:141], v[128:129], 0, v[140:141]
	v_cvt_pk_bf16_f32 v142, v139, v153
	v_cvt_pk_bf16_f32 v143, v147, v131
	global_store_dwordx2 v[140:141], v[142:143], off nt
	v_add_u32_e32 v140, 64, v130
	v_lshlrev_b32_e32 v131, 5, v140
	v_and_or_b32 v131, v131, s17, v137
	v_lshlrev_b32_e32 v131, 3, v131
	global_load_dwordx2 v[144:145], v131, s[58:59]
	global_load_dwordx2 v[150:151], v131, s[58:59] offset:256
	ds_bpermute_b32 v139, v138, v60
	v_mov_b32_e32 v142, v60
	ds_bpermute_b32 v141, v138, v56
	ds_bpermute_b32 v147, v138, v52
	ds_bpermute_b32 v148, v138, v48
	s_waitcnt lgkmcnt(3)
	v_mul_f32_e32 v143, v134, v139
	ds_bpermute_b32 v152, v138, v49
	s_waitcnt vmcnt(1)
	v_pk_mul_f32 v[142:143], v[142:143], v[144:145]
	global_load_dwordx2 v[144:145], v131, s[58:59] offset:16
	v_add_f32_e32 v139, v142, v143
	s_waitcnt lgkmcnt(3)
	v_mul_f32_e32 v143, v134, v141
	v_mov_b32_e32 v142, v56
	v_ashrrev_i32_e32 v141, 31, v140
	v_lshlrev_b64 v[140:141], 9, v[140:141]
	v_lshl_add_u64 v[140:141], v[128:129], 0, v[140:141]
	s_waitcnt vmcnt(0)
	v_pk_mul_f32 v[142:143], v[142:143], v[144:145]
	global_load_dwordx2 v[144:145], v131, s[58:59] offset:32
	v_add_f32_e32 v149, v142, v143
	s_waitcnt lgkmcnt(2)
	v_mul_f32_e32 v143, v134, v147
	v_mov_b32_e32 v142, v52
	s_waitcnt vmcnt(0)
	v_pk_mul_f32 v[142:143], v[142:143], v[144:145]
	global_load_dwordx2 v[144:145], v131, s[58:59] offset:48
	v_add_f32_e32 v147, v142, v143
	s_waitcnt lgkmcnt(1)
	v_mul_f32_e32 v143, v134, v148
	v_mov_b32_e32 v142, v48
	v_mov_b32_e32 v148, v61
	s_waitcnt vmcnt(0)
	v_pk_mul_f32 v[142:143], v[142:143], v[144:145]
	s_nop 0
	v_add_f32_e32 v143, v142, v143
	v_cvt_pk_bf16_f32 v142, v139, v149
	ds_bpermute_b32 v139, v138, v61
	ds_bpermute_b32 v145, v138, v57
	v_cvt_pk_bf16_f32 v143, v147, v143
	ds_bpermute_b32 v147, v138, v53
	v_add_u32_e32 v144, 0x41, v130
	s_waitcnt lgkmcnt(2)
	v_mul_f32_e32 v149, v134, v139
	v_pk_mul_f32 v[148:149], v[148:149], v[150:151]
	global_load_dwordx2 v[150:151], v131, s[58:59] offset:272
	v_add_f32_e32 v139, v148, v149
	s_waitcnt lgkmcnt(1)
	v_mul_f32_e32 v149, v134, v145
	v_mov_b32_e32 v148, v57
	s_waitcnt vmcnt(0)
	v_pk_mul_f32 v[148:149], v[148:149], v[150:151]
	global_load_dwordx2 v[150:151], v131, s[58:59] offset:288
	v_add_f32_e32 v153, v148, v149
	s_waitcnt lgkmcnt(0)
	v_mul_f32_e32 v149, v134, v147
	v_mov_b32_e32 v148, v53
	s_waitcnt vmcnt(0)
	v_pk_mul_f32 v[148:149], v[148:149], v[150:151]
	global_load_dwordx2 v[150:151], v131, s[58:59] offset:304
	v_add_f32_e32 v147, v148, v149
	v_mul_f32_e32 v149, v134, v152
	global_store_dwordx2 v[140:141], v[142:143], off nt
	v_mov_b32_e32 v148, v49
	s_waitcnt vmcnt(1)
	v_pk_mul_f32 v[140:141], v[148:149], v[150:151]
	v_ashrrev_i32_e32 v145, 31, v144
	v_add_f32_e32 v131, v140, v141
	v_lshlrev_b64 v[140:141], 9, v[144:145]
	v_lshl_add_u64 v[140:141], v[128:129], 0, v[140:141]
	v_cvt_pk_bf16_f32 v142, v139, v153
	v_cvt_pk_bf16_f32 v143, v147, v131
	global_store_dwordx2 v[140:141], v[142:143], off nt
	v_add_u32_e32 v140, 0x42, v130
	v_lshlrev_b32_e32 v131, 5, v140
	v_and_or_b32 v131, v131, s18, v137
	v_lshlrev_b32_e32 v131, 3, v131
	global_load_dwordx2 v[144:145], v131, s[58:59]
	global_load_dwordx2 v[150:151], v131, s[58:59] offset:256
	ds_bpermute_b32 v139, v138, v62
	v_mov_b32_e32 v142, v62
	ds_bpermute_b32 v141, v138, v58
	ds_bpermute_b32 v147, v138, v54
	ds_bpermute_b32 v148, v138, v50
	s_waitcnt lgkmcnt(3)
	v_mul_f32_e32 v143, v134, v139
	ds_bpermute_b32 v152, v138, v51
	s_waitcnt vmcnt(1)
	v_pk_mul_f32 v[142:143], v[142:143], v[144:145]
	global_load_dwordx2 v[144:145], v131, s[58:59] offset:16
	v_add_f32_e32 v139, v142, v143
	s_waitcnt lgkmcnt(3)
	v_mul_f32_e32 v143, v134, v141
	v_mov_b32_e32 v142, v58
	v_ashrrev_i32_e32 v141, 31, v140
	v_lshlrev_b64 v[140:141], 9, v[140:141]
	v_lshl_add_u64 v[140:141], v[128:129], 0, v[140:141]
	s_waitcnt vmcnt(0)
	v_pk_mul_f32 v[142:143], v[142:143], v[144:145]
	global_load_dwordx2 v[144:145], v131, s[58:59] offset:32
	v_add_f32_e32 v149, v142, v143
	s_waitcnt lgkmcnt(2)
	v_mul_f32_e32 v143, v134, v147
	v_mov_b32_e32 v142, v54
	s_waitcnt vmcnt(0)
	v_pk_mul_f32 v[142:143], v[142:143], v[144:145]
	global_load_dwordx2 v[144:145], v131, s[58:59] offset:48
	v_add_f32_e32 v147, v142, v143
	s_waitcnt lgkmcnt(1)
	v_mul_f32_e32 v143, v134, v148
	v_mov_b32_e32 v142, v50
	v_mov_b32_e32 v148, v63
	s_waitcnt vmcnt(0)
	v_pk_mul_f32 v[142:143], v[142:143], v[144:145]
	s_nop 0
	v_add_f32_e32 v143, v142, v143
	v_cvt_pk_bf16_f32 v142, v139, v149
	ds_bpermute_b32 v139, v138, v63
	ds_bpermute_b32 v145, v138, v59
	v_cvt_pk_bf16_f32 v143, v147, v143
	ds_bpermute_b32 v147, v138, v55
	v_add_u32_e32 v144, 0x43, v130
	s_waitcnt lgkmcnt(2)
	v_mul_f32_e32 v149, v134, v139
	v_pk_mul_f32 v[148:149], v[148:149], v[150:151]
	global_load_dwordx2 v[150:151], v131, s[58:59] offset:272
	v_add_f32_e32 v139, v148, v149
	s_waitcnt lgkmcnt(1)
	v_mul_f32_e32 v149, v134, v145
	v_mov_b32_e32 v148, v59
	s_waitcnt vmcnt(0)
	v_pk_mul_f32 v[148:149], v[148:149], v[150:151]
	global_load_dwordx2 v[150:151], v131, s[58:59] offset:288
	v_add_f32_e32 v153, v148, v149
	s_waitcnt lgkmcnt(0)
	v_mul_f32_e32 v149, v134, v147
	v_mov_b32_e32 v148, v55
	s_waitcnt vmcnt(0)
	v_pk_mul_f32 v[148:149], v[148:149], v[150:151]
	global_load_dwordx2 v[150:151], v131, s[58:59] offset:304
	v_add_f32_e32 v147, v148, v149
	v_mul_f32_e32 v149, v134, v152
	global_store_dwordx2 v[140:141], v[142:143], off nt
	v_mov_b32_e32 v148, v51
	s_waitcnt vmcnt(1)
	v_pk_mul_f32 v[140:141], v[148:149], v[150:151]
	v_ashrrev_i32_e32 v145, 31, v144
	v_add_f32_e32 v131, v140, v141
	v_lshlrev_b64 v[140:141], 9, v[144:145]
	v_lshl_add_u64 v[140:141], v[128:129], 0, v[140:141]
	v_cvt_pk_bf16_f32 v142, v139, v153
	v_cvt_pk_bf16_f32 v143, v147, v131
	global_store_dwordx2 v[140:141], v[142:143], off nt
	v_add_u32_e32 v140, 0x50, v130
	v_lshlrev_b32_e32 v131, 5, v140
	v_and_or_b32 v131, v131, s17, v137
	v_lshlrev_b32_e32 v131, 3, v131
	global_load_dwordx2 v[144:145], v131, s[58:59]
	global_load_dwordx2 v[150:151], v131, s[58:59] offset:256
	ds_bpermute_b32 v139, v138, v44
	v_mov_b32_e32 v142, v44
	ds_bpermute_b32 v141, v138, v40
	ds_bpermute_b32 v147, v138, v36
	ds_bpermute_b32 v148, v138, v32
	s_waitcnt lgkmcnt(3)
	v_mul_f32_e32 v143, v134, v139
	ds_bpermute_b32 v152, v138, v33
	s_waitcnt vmcnt(1)
	v_pk_mul_f32 v[142:143], v[142:143], v[144:145]
	global_load_dwordx2 v[144:145], v131, s[58:59] offset:16
	v_add_f32_e32 v139, v142, v143
	s_waitcnt lgkmcnt(3)
	v_mul_f32_e32 v143, v134, v141
	v_mov_b32_e32 v142, v40
	v_ashrrev_i32_e32 v141, 31, v140
	v_lshlrev_b64 v[140:141], 9, v[140:141]
	v_lshl_add_u64 v[140:141], v[128:129], 0, v[140:141]
	s_waitcnt vmcnt(0)
	v_pk_mul_f32 v[142:143], v[142:143], v[144:145]
	global_load_dwordx2 v[144:145], v131, s[58:59] offset:32
	v_add_f32_e32 v149, v142, v143
	s_waitcnt lgkmcnt(2)
	v_mul_f32_e32 v143, v134, v147
	v_mov_b32_e32 v142, v36
	s_waitcnt vmcnt(0)
	v_pk_mul_f32 v[142:143], v[142:143], v[144:145]
	global_load_dwordx2 v[144:145], v131, s[58:59] offset:48
	v_add_f32_e32 v147, v142, v143
	s_waitcnt lgkmcnt(1)
	v_mul_f32_e32 v143, v134, v148
	v_mov_b32_e32 v142, v32
	v_mov_b32_e32 v148, v45
	s_waitcnt vmcnt(0)
	v_pk_mul_f32 v[142:143], v[142:143], v[144:145]
	s_nop 0
	v_add_f32_e32 v143, v142, v143
	v_cvt_pk_bf16_f32 v142, v139, v149
	ds_bpermute_b32 v139, v138, v45
	ds_bpermute_b32 v145, v138, v41
	v_cvt_pk_bf16_f32 v143, v147, v143
	ds_bpermute_b32 v147, v138, v37
	v_add_u32_e32 v144, 0x51, v130
	s_waitcnt lgkmcnt(2)
	v_mul_f32_e32 v149, v134, v139
	v_pk_mul_f32 v[148:149], v[148:149], v[150:151]
	global_load_dwordx2 v[150:151], v131, s[58:59] offset:272
	v_add_f32_e32 v139, v148, v149
	s_waitcnt lgkmcnt(1)
	v_mul_f32_e32 v149, v134, v145
	v_mov_b32_e32 v148, v41
	s_waitcnt vmcnt(0)
	v_pk_mul_f32 v[148:149], v[148:149], v[150:151]
	global_load_dwordx2 v[150:151], v131, s[58:59] offset:288
	v_add_f32_e32 v153, v148, v149
	s_waitcnt lgkmcnt(0)
	v_mul_f32_e32 v149, v134, v147
	v_mov_b32_e32 v148, v37
	s_waitcnt vmcnt(0)
	v_pk_mul_f32 v[148:149], v[148:149], v[150:151]
	global_load_dwordx2 v[150:151], v131, s[58:59] offset:304
	v_add_f32_e32 v147, v148, v149
	v_mul_f32_e32 v149, v134, v152
	global_store_dwordx2 v[140:141], v[142:143], off nt
	v_mov_b32_e32 v148, v33
	s_waitcnt vmcnt(1)
	v_pk_mul_f32 v[140:141], v[148:149], v[150:151]
	v_ashrrev_i32_e32 v145, 31, v144
	v_add_f32_e32 v131, v140, v141
	v_lshlrev_b64 v[140:141], 9, v[144:145]
	v_lshl_add_u64 v[140:141], v[128:129], 0, v[140:141]
	v_cvt_pk_bf16_f32 v142, v139, v153
	v_cvt_pk_bf16_f32 v143, v147, v131
	global_store_dwordx2 v[140:141], v[142:143], off nt
	v_add_u32_e32 v140, 0x52, v130
	v_lshlrev_b32_e32 v131, 5, v140
	v_and_or_b32 v131, v131, s18, v137
	v_lshlrev_b32_e32 v131, 3, v131
	global_load_dwordx2 v[144:145], v131, s[58:59]
	global_load_dwordx2 v[150:151], v131, s[58:59] offset:256
	ds_bpermute_b32 v139, v138, v46
	v_mov_b32_e32 v142, v46
	ds_bpermute_b32 v141, v138, v42
	ds_bpermute_b32 v147, v138, v38
	ds_bpermute_b32 v148, v138, v34
	s_waitcnt lgkmcnt(3)
	v_mul_f32_e32 v143, v134, v139
	ds_bpermute_b32 v152, v138, v35
	s_waitcnt vmcnt(1)
	v_pk_mul_f32 v[142:143], v[142:143], v[144:145]
	global_load_dwordx2 v[144:145], v131, s[58:59] offset:16
	v_add_f32_e32 v139, v142, v143
	s_waitcnt lgkmcnt(3)
	v_mul_f32_e32 v143, v134, v141
	v_mov_b32_e32 v142, v42
	v_ashrrev_i32_e32 v141, 31, v140
	v_lshlrev_b64 v[140:141], 9, v[140:141]
	v_lshl_add_u64 v[140:141], v[128:129], 0, v[140:141]
	s_waitcnt vmcnt(0)
	v_pk_mul_f32 v[142:143], v[142:143], v[144:145]
	global_load_dwordx2 v[144:145], v131, s[58:59] offset:32
	v_add_f32_e32 v149, v142, v143
	s_waitcnt lgkmcnt(2)
	v_mul_f32_e32 v143, v134, v147
	v_mov_b32_e32 v142, v38
	s_waitcnt vmcnt(0)
	v_pk_mul_f32 v[142:143], v[142:143], v[144:145]
	global_load_dwordx2 v[144:145], v131, s[58:59] offset:48
	v_add_f32_e32 v147, v142, v143
	s_waitcnt lgkmcnt(1)
	v_mul_f32_e32 v143, v134, v148
	v_mov_b32_e32 v142, v34
	v_mov_b32_e32 v148, v47
	s_waitcnt vmcnt(0)
	v_pk_mul_f32 v[142:143], v[142:143], v[144:145]
	s_nop 0
	v_add_f32_e32 v143, v142, v143
	v_cvt_pk_bf16_f32 v142, v139, v149
	ds_bpermute_b32 v139, v138, v47
	ds_bpermute_b32 v145, v138, v43
	v_cvt_pk_bf16_f32 v143, v147, v143
	ds_bpermute_b32 v147, v138, v39
	v_add_u32_e32 v144, 0x53, v130
	s_waitcnt lgkmcnt(2)
	v_mul_f32_e32 v149, v134, v139
	v_pk_mul_f32 v[148:149], v[148:149], v[150:151]
	global_load_dwordx2 v[150:151], v131, s[58:59] offset:272
	v_add_f32_e32 v139, v148, v149
	s_waitcnt lgkmcnt(1)
	v_mul_f32_e32 v149, v134, v145
	v_mov_b32_e32 v148, v43
	s_waitcnt vmcnt(0)
	v_pk_mul_f32 v[148:149], v[148:149], v[150:151]
	global_load_dwordx2 v[150:151], v131, s[58:59] offset:288
	v_add_f32_e32 v153, v148, v149
	s_waitcnt lgkmcnt(0)
	v_mul_f32_e32 v149, v134, v147
	v_mov_b32_e32 v148, v39
	s_waitcnt vmcnt(0)
	v_pk_mul_f32 v[148:149], v[148:149], v[150:151]
	global_load_dwordx2 v[150:151], v131, s[58:59] offset:304
	v_add_f32_e32 v147, v148, v149
	v_mul_f32_e32 v149, v134, v152
	global_store_dwordx2 v[140:141], v[142:143], off nt
	v_mov_b32_e32 v148, v35
	s_waitcnt vmcnt(1)
	v_pk_mul_f32 v[140:141], v[148:149], v[150:151]
	v_ashrrev_i32_e32 v145, 31, v144
	v_add_f32_e32 v131, v140, v141
	v_lshlrev_b64 v[140:141], 9, v[144:145]
	v_lshl_add_u64 v[140:141], v[128:129], 0, v[140:141]
	v_cvt_pk_bf16_f32 v142, v139, v153
	v_cvt_pk_bf16_f32 v143, v147, v131
	global_store_dwordx2 v[140:141], v[142:143], off nt
	v_add_u32_e32 v140, 0x60, v130
	v_lshlrev_b32_e32 v131, 5, v140
	v_and_or_b32 v131, v131, s17, v137
	v_lshlrev_b32_e32 v131, 3, v131
	global_load_dwordx2 v[144:145], v131, s[58:59]
	global_load_dwordx2 v[150:151], v131, s[58:59] offset:256
	ds_bpermute_b32 v139, v138, v28
	v_mov_b32_e32 v142, v28
	ds_bpermute_b32 v141, v138, v24
	ds_bpermute_b32 v147, v138, v20
	ds_bpermute_b32 v148, v138, v16
	s_waitcnt lgkmcnt(3)
	v_mul_f32_e32 v143, v134, v139
	ds_bpermute_b32 v152, v138, v17
	s_waitcnt vmcnt(1)
	v_pk_mul_f32 v[142:143], v[142:143], v[144:145]
	global_load_dwordx2 v[144:145], v131, s[58:59] offset:16
	v_add_f32_e32 v139, v142, v143
	s_waitcnt lgkmcnt(3)
	v_mul_f32_e32 v143, v134, v141
	v_mov_b32_e32 v142, v24
	v_ashrrev_i32_e32 v141, 31, v140
	v_lshlrev_b64 v[140:141], 9, v[140:141]
	v_lshl_add_u64 v[140:141], v[128:129], 0, v[140:141]
	s_waitcnt vmcnt(0)
	v_pk_mul_f32 v[142:143], v[142:143], v[144:145]
	global_load_dwordx2 v[144:145], v131, s[58:59] offset:32
	v_add_f32_e32 v149, v142, v143
	s_waitcnt lgkmcnt(2)
	v_mul_f32_e32 v143, v134, v147
	v_mov_b32_e32 v142, v20
	s_waitcnt vmcnt(0)
	v_pk_mul_f32 v[142:143], v[142:143], v[144:145]
	global_load_dwordx2 v[144:145], v131, s[58:59] offset:48
	v_add_f32_e32 v147, v142, v143
	s_waitcnt lgkmcnt(1)
	v_mul_f32_e32 v143, v134, v148
	v_mov_b32_e32 v142, v16
	v_mov_b32_e32 v148, v29
	s_waitcnt vmcnt(0)
	v_pk_mul_f32 v[142:143], v[142:143], v[144:145]
	s_nop 0
	v_add_f32_e32 v143, v142, v143
	v_cvt_pk_bf16_f32 v142, v139, v149
	ds_bpermute_b32 v139, v138, v29
	ds_bpermute_b32 v145, v138, v25
	v_cvt_pk_bf16_f32 v143, v147, v143
	ds_bpermute_b32 v147, v138, v21
	v_add_u32_e32 v144, 0x61, v130
	s_waitcnt lgkmcnt(2)
	v_mul_f32_e32 v149, v134, v139
	v_pk_mul_f32 v[148:149], v[148:149], v[150:151]
	global_load_dwordx2 v[150:151], v131, s[58:59] offset:272
	v_add_f32_e32 v139, v148, v149
	s_waitcnt lgkmcnt(1)
	v_mul_f32_e32 v149, v134, v145
	v_mov_b32_e32 v148, v25
	s_waitcnt vmcnt(0)
	v_pk_mul_f32 v[148:149], v[148:149], v[150:151]
	global_load_dwordx2 v[150:151], v131, s[58:59] offset:288
	v_add_f32_e32 v153, v148, v149
	s_waitcnt lgkmcnt(0)
	v_mul_f32_e32 v149, v134, v147
	v_mov_b32_e32 v148, v21
	s_waitcnt vmcnt(0)
	v_pk_mul_f32 v[148:149], v[148:149], v[150:151]
	global_load_dwordx2 v[150:151], v131, s[58:59] offset:304
	v_add_f32_e32 v147, v148, v149
	v_mul_f32_e32 v149, v134, v152
	global_store_dwordx2 v[140:141], v[142:143], off nt
	v_mov_b32_e32 v148, v17
	s_waitcnt vmcnt(1)
	v_pk_mul_f32 v[140:141], v[148:149], v[150:151]
	v_ashrrev_i32_e32 v145, 31, v144
	v_add_f32_e32 v131, v140, v141
	v_lshlrev_b64 v[140:141], 9, v[144:145]
	v_lshl_add_u64 v[140:141], v[128:129], 0, v[140:141]
	v_cvt_pk_bf16_f32 v142, v139, v153
	v_cvt_pk_bf16_f32 v143, v147, v131
	global_store_dwordx2 v[140:141], v[142:143], off nt
	v_add_u32_e32 v140, 0x62, v130
	v_lshlrev_b32_e32 v131, 5, v140
	v_and_or_b32 v131, v131, s18, v137
	v_lshlrev_b32_e32 v131, 3, v131
	global_load_dwordx2 v[144:145], v131, s[58:59]
	global_load_dwordx2 v[150:151], v131, s[58:59] offset:256
	ds_bpermute_b32 v139, v138, v30
	v_mov_b32_e32 v142, v30
	ds_bpermute_b32 v141, v138, v26
	ds_bpermute_b32 v147, v138, v22
	ds_bpermute_b32 v148, v138, v18
	s_waitcnt lgkmcnt(3)
	v_mul_f32_e32 v143, v134, v139
	ds_bpermute_b32 v152, v138, v19
	s_waitcnt vmcnt(1)
	v_pk_mul_f32 v[142:143], v[142:143], v[144:145]
	global_load_dwordx2 v[144:145], v131, s[58:59] offset:16
	v_add_f32_e32 v139, v142, v143
	s_waitcnt lgkmcnt(3)
	v_mul_f32_e32 v143, v134, v141
	v_mov_b32_e32 v142, v26
	v_ashrrev_i32_e32 v141, 31, v140
	v_lshlrev_b64 v[140:141], 9, v[140:141]
	v_lshl_add_u64 v[140:141], v[128:129], 0, v[140:141]
	s_waitcnt vmcnt(0)
	v_pk_mul_f32 v[142:143], v[142:143], v[144:145]
	global_load_dwordx2 v[144:145], v131, s[58:59] offset:32
	v_add_f32_e32 v149, v142, v143
	s_waitcnt lgkmcnt(2)
	v_mul_f32_e32 v143, v134, v147
	v_mov_b32_e32 v142, v22
	s_waitcnt vmcnt(0)
	v_pk_mul_f32 v[142:143], v[142:143], v[144:145]
	global_load_dwordx2 v[144:145], v131, s[58:59] offset:48
	v_add_f32_e32 v147, v142, v143
	s_waitcnt lgkmcnt(1)
	v_mul_f32_e32 v143, v134, v148
	v_mov_b32_e32 v142, v18
	v_mov_b32_e32 v148, v31
	s_waitcnt vmcnt(0)
	v_pk_mul_f32 v[142:143], v[142:143], v[144:145]
	s_nop 0
	v_add_f32_e32 v143, v142, v143
	v_cvt_pk_bf16_f32 v142, v139, v149
	ds_bpermute_b32 v139, v138, v31
	ds_bpermute_b32 v145, v138, v27
	v_cvt_pk_bf16_f32 v143, v147, v143
	ds_bpermute_b32 v147, v138, v23
	v_add_u32_e32 v144, 0x63, v130
	s_waitcnt lgkmcnt(2)
	v_mul_f32_e32 v149, v134, v139
	v_pk_mul_f32 v[148:149], v[148:149], v[150:151]
	global_load_dwordx2 v[150:151], v131, s[58:59] offset:272
	v_add_f32_e32 v139, v148, v149
	s_waitcnt lgkmcnt(1)
	v_mul_f32_e32 v149, v134, v145
	v_mov_b32_e32 v148, v27
	s_waitcnt vmcnt(0)
	v_pk_mul_f32 v[148:149], v[148:149], v[150:151]
	global_load_dwordx2 v[150:151], v131, s[58:59] offset:288
	v_add_f32_e32 v153, v148, v149
	s_waitcnt lgkmcnt(0)
	v_mul_f32_e32 v149, v134, v147
	v_mov_b32_e32 v148, v23
	s_waitcnt vmcnt(0)
	v_pk_mul_f32 v[148:149], v[148:149], v[150:151]
	global_load_dwordx2 v[150:151], v131, s[58:59] offset:304
	v_add_f32_e32 v147, v148, v149
	v_mul_f32_e32 v149, v134, v152
	global_store_dwordx2 v[140:141], v[142:143], off nt
	v_mov_b32_e32 v148, v19
	s_waitcnt vmcnt(1)
	v_pk_mul_f32 v[140:141], v[148:149], v[150:151]
	v_ashrrev_i32_e32 v145, 31, v144
	v_add_f32_e32 v131, v140, v141
	v_lshlrev_b64 v[140:141], 9, v[144:145]
	v_lshl_add_u64 v[140:141], v[128:129], 0, v[140:141]
	v_cvt_pk_bf16_f32 v142, v139, v153
	v_cvt_pk_bf16_f32 v143, v147, v131
	global_store_dwordx2 v[140:141], v[142:143], off nt
	v_add_u32_e32 v140, 0x70, v130
	v_lshlrev_b32_e32 v131, 5, v140
	v_and_or_b32 v131, v131, s17, v137
	v_lshlrev_b32_e32 v131, 3, v131
	global_load_dwordx2 v[144:145], v131, s[58:59]
	global_load_dwordx2 v[150:151], v131, s[58:59] offset:256
	ds_bpermute_b32 v139, v138, v12
	v_mov_b32_e32 v142, v12
	ds_bpermute_b32 v141, v138, v8
	ds_bpermute_b32 v147, v138, v4
	ds_bpermute_b32 v148, v138, v0
	s_waitcnt lgkmcnt(3)
	v_mul_f32_e32 v143, v134, v139
	ds_bpermute_b32 v152, v138, v1
	s_waitcnt vmcnt(1)
	v_pk_mul_f32 v[142:143], v[142:143], v[144:145]
	global_load_dwordx2 v[144:145], v131, s[58:59] offset:16
	v_add_f32_e32 v139, v142, v143
	s_waitcnt lgkmcnt(3)
	v_mul_f32_e32 v143, v134, v141
	v_mov_b32_e32 v142, v8
	v_ashrrev_i32_e32 v141, 31, v140
	v_lshlrev_b64 v[140:141], 9, v[140:141]
	v_lshl_add_u64 v[140:141], v[128:129], 0, v[140:141]
	s_waitcnt vmcnt(0)
	v_pk_mul_f32 v[142:143], v[142:143], v[144:145]
	global_load_dwordx2 v[144:145], v131, s[58:59] offset:32
	v_add_f32_e32 v149, v142, v143
	s_waitcnt lgkmcnt(2)
	v_mul_f32_e32 v143, v134, v147
	v_mov_b32_e32 v142, v4
	s_waitcnt vmcnt(0)
	v_pk_mul_f32 v[142:143], v[142:143], v[144:145]
	global_load_dwordx2 v[144:145], v131, s[58:59] offset:48
	v_add_f32_e32 v147, v142, v143
	s_waitcnt lgkmcnt(1)
	v_mul_f32_e32 v143, v134, v148
	v_mov_b32_e32 v142, v0
	v_mov_b32_e32 v148, v13
	s_waitcnt vmcnt(0)
	v_pk_mul_f32 v[142:143], v[142:143], v[144:145]
	s_nop 0
	v_add_f32_e32 v143, v142, v143
	v_cvt_pk_bf16_f32 v142, v139, v149
	ds_bpermute_b32 v139, v138, v13
	ds_bpermute_b32 v145, v138, v9
	v_cvt_pk_bf16_f32 v143, v147, v143
	ds_bpermute_b32 v147, v138, v5
	v_add_u32_e32 v144, 0x71, v130
	s_waitcnt lgkmcnt(2)
	v_mul_f32_e32 v149, v134, v139
	v_pk_mul_f32 v[148:149], v[148:149], v[150:151]
	global_load_dwordx2 v[150:151], v131, s[58:59] offset:272
	v_add_f32_e32 v139, v148, v149
	s_waitcnt lgkmcnt(1)
	v_mul_f32_e32 v149, v134, v145
	v_mov_b32_e32 v148, v9
	s_waitcnt vmcnt(0)
	v_pk_mul_f32 v[148:149], v[148:149], v[150:151]
	global_load_dwordx2 v[150:151], v131, s[58:59] offset:288
	v_add_f32_e32 v153, v148, v149
	s_waitcnt lgkmcnt(0)
	v_mul_f32_e32 v149, v134, v147
	v_mov_b32_e32 v148, v5
	s_waitcnt vmcnt(0)
	v_pk_mul_f32 v[148:149], v[148:149], v[150:151]
	global_load_dwordx2 v[150:151], v131, s[58:59] offset:304
	v_add_f32_e32 v147, v148, v149
	v_mul_f32_e32 v149, v134, v152
	global_store_dwordx2 v[140:141], v[142:143], off nt
	v_mov_b32_e32 v148, v1
	s_waitcnt vmcnt(1)
	v_pk_mul_f32 v[140:141], v[148:149], v[150:151]
	v_ashrrev_i32_e32 v145, 31, v144
	v_add_f32_e32 v131, v140, v141
	v_lshlrev_b64 v[140:141], 9, v[144:145]
	v_lshl_add_u64 v[140:141], v[128:129], 0, v[140:141]
	v_cvt_pk_bf16_f32 v142, v139, v153
	v_cvt_pk_bf16_f32 v143, v147, v131
	global_store_dwordx2 v[140:141], v[142:143], off nt
	v_add_u32_e32 v140, 0x72, v130
	v_lshlrev_b32_e32 v131, 5, v140
	v_and_or_b32 v131, v131, s18, v137
	v_lshlrev_b32_e32 v131, 3, v131
	global_load_dwordx2 v[144:145], v131, s[58:59]
	ds_bpermute_b32 v137, v138, v14
	v_mov_b32_e32 v142, v14
	ds_bpermute_b32 v139, v138, v10
	ds_bpermute_b32 v141, v138, v6
	ds_bpermute_b32 v147, v138, v2
	s_waitcnt lgkmcnt(3)
	v_mul_f32_e32 v143, v134, v137
	ds_bpermute_b32 v149, v138, v3
	v_add_u32_e32 v130, 0x73, v130
	s_waitcnt vmcnt(0)
	v_pk_mul_f32 v[142:143], v[142:143], v[144:145]
	global_load_dwordx2 v[144:145], v131, s[58:59] offset:16
	v_add_f32_e32 v137, v142, v143
	s_waitcnt lgkmcnt(3)
	v_mul_f32_e32 v143, v134, v139
	v_mov_b32_e32 v142, v10
	s_waitcnt vmcnt(0)
	v_pk_mul_f32 v[142:143], v[142:143], v[144:145]
	global_load_dwordx2 v[144:145], v131, s[58:59] offset:32
	v_add_f32_e32 v139, v142, v143
	s_waitcnt lgkmcnt(2)
	v_mul_f32_e32 v143, v134, v141
	v_mov_b32_e32 v142, v6
	v_ashrrev_i32_e32 v141, 31, v140
	v_lshlrev_b64 v[140:141], 9, v[140:141]
	v_lshl_add_u64 v[140:141], v[128:129], 0, v[140:141]
	s_waitcnt vmcnt(0)
	v_pk_mul_f32 v[142:143], v[142:143], v[144:145]
	global_load_dwordx2 v[144:145], v131, s[58:59] offset:48
	v_add_f32_e32 v148, v142, v143
	s_waitcnt lgkmcnt(1)
	v_mul_f32_e32 v143, v134, v147
	v_mov_b32_e32 v142, v2
	ds_bpermute_b32 v147, v138, v11
	s_waitcnt vmcnt(0)
	v_pk_mul_f32 v[142:143], v[142:143], v[144:145]
	global_load_dwordx2 v[144:145], v131, s[58:59] offset:256
	v_add_f32_e32 v143, v142, v143
	v_cvt_pk_bf16_f32 v142, v137, v139
	ds_bpermute_b32 v137, v138, v15
	v_cvt_pk_bf16_f32 v143, v148, v143
	ds_bpermute_b32 v148, v138, v7
	v_mov_b32_e32 v138, v15
	s_waitcnt lgkmcnt(1)
	v_mul_f32_e32 v139, v134, v137
	s_waitcnt vmcnt(0)
	v_pk_mul_f32 v[138:139], v[138:139], v[144:145]
	global_load_dwordx2 v[144:145], v131, s[58:59] offset:272
	v_add_f32_e32 v137, v138, v139
	v_mul_f32_e32 v139, v134, v147
	v_mov_b32_e32 v138, v11
	s_waitcnt vmcnt(0)
	v_pk_mul_f32 v[138:139], v[138:139], v[144:145]
	global_load_dwordx2 v[144:145], v131, s[58:59] offset:288
	v_add_f32_e32 v147, v138, v139
	s_waitcnt lgkmcnt(0)
	v_mul_f32_e32 v139, v134, v148
	v_mov_b32_e32 v138, v7
	s_waitcnt vmcnt(0)
	v_pk_mul_f32 v[138:139], v[138:139], v[144:145]
	global_load_dwordx2 v[144:145], v131, s[58:59] offset:304
	v_add_f32_e32 v148, v138, v139
	v_mul_f32_e32 v139, v134, v149
	global_store_dwordx2 v[140:141], v[142:143], off nt
	v_ashrrev_i32_e32 v131, 31, v130
	v_mov_b32_e32 v138, v3
	v_lshlrev_b64 v[130:131], 9, v[130:131]
	s_waitcnt vmcnt(1)
	v_pk_mul_f32 v[138:139], v[138:139], v[144:145]
	v_lshl_add_u64 v[128:129], v[128:129], 0, v[130:131]
	v_add_f32_e32 v134, v138, v139
	v_cvt_pk_bf16_f32 v130, v137, v147
	v_cvt_pk_bf16_f32 v131, v148, v134
	global_store_dwordx2 v[128:129], v[130:131], off nt
	s_xor_b64 s[34:35], exec, -1

.LBB0_480:
	s_andn2_saveexec_b64 s[68:69], s[68:69]
	s_cbranch_execz .LBB0_482
	v_readlane_b32 s36, v253, 44
	v_ashrrev_i32_e32 v137, 31, v136
	v_readlane_b32 s44, v253, 52
	v_readlane_b32 s45, v253, 53
	v_lshl_add_u32 v128, v146, 2, v211
	v_readlane_b32 s37, v253, 45
	v_readlane_b32 s38, v253, 46
	v_readlane_b32 s39, v253, 47
	v_readlane_b32 s40, v253, 48
	v_readlane_b32 s41, v253, 49
	v_readlane_b32 s42, v253, 50
	v_readlane_b32 s43, v253, 51
	v_readlane_b32 s46, v253, 54
	v_readlane_b32 s47, v253, 55
	v_readlane_b32 s48, v253, 56
	v_readlane_b32 s49, v253, 57
	v_readlane_b32 s50, v253, 58
	v_readlane_b32 s51, v253, 59
	v_lshl_add_u64 v[130:131], v[136:137], 1, s[44:45]
	v_ashrrev_i32_e32 v129, 31, v128
	v_lshlrev_b64 v[138:139], 9, v[128:129]
	v_lshl_add_u64 v[138:139], v[130:131], 0, v[138:139]
	v_mul_f32_e32 v141, 0x3e38aa3b, v112
	v_mul_f32_e32 v129, 0x3e38aa3b, v124
	v_mul_f32_e32 v134, 0x3e38aa3b, v120
	v_mul_f32_e32 v137, 0x3e38aa3b, v116
	v_cvt_pk_bf16_f32 v140, v129, v134
	v_cvt_pk_bf16_f32 v141, v137, v141
	global_store_dwordx2 v[138:139], v[140:141], off nt
	v_or_b32_e32 v138, 1, v128
	v_ashrrev_i32_e32 v139, 31, v138
	v_lshlrev_b64 v[138:139], 9, v[138:139]
	v_lshl_add_u64 v[138:139], v[130:131], 0, v[138:139]
	v_mul_f32_e32 v141, 0x3e38aa3b, v113
	v_mul_f32_e32 v129, 0x3e38aa3b, v125
	v_mul_f32_e32 v134, 0x3e38aa3b, v121
	v_mul_f32_e32 v137, 0x3e38aa3b, v117
	v_cvt_pk_bf16_f32 v140, v129, v134
	v_cvt_pk_bf16_f32 v141, v137, v141
	global_store_dwordx2 v[138:139], v[140:141], off nt
	v_or_b32_e32 v138, 2, v128
	v_ashrrev_i32_e32 v139, 31, v138
	v_lshlrev_b64 v[138:139], 9, v[138:139]
	v_lshl_add_u64 v[138:139], v[130:131], 0, v[138:139]
	v_mul_f32_e32 v141, 0x3e38aa3b, v114
	v_mul_f32_e32 v129, 0x3e38aa3b, v126
	v_mul_f32_e32 v134, 0x3e38aa3b, v122
	v_mul_f32_e32 v137, 0x3e38aa3b, v118
	v_cvt_pk_bf16_f32 v140, v129, v134
	v_cvt_pk_bf16_f32 v141, v137, v141
	global_store_dwordx2 v[138:139], v[140:141], off nt
	v_or_b32_e32 v138, 3, v128
	v_ashrrev_i32_e32 v139, 31, v138
	v_lshlrev_b64 v[138:139], 9, v[138:139]
	v_lshl_add_u64 v[138:139], v[130:131], 0, v[138:139]
	v_mul_f32_e32 v141, 0x3e38aa3b, v115
	v_mul_f32_e32 v129, 0x3e38aa3b, v127
	v_mul_f32_e32 v134, 0x3e38aa3b, v123
	v_mul_f32_e32 v137, 0x3e38aa3b, v119
	v_cvt_pk_bf16_f32 v140, v129, v134
	v_cvt_pk_bf16_f32 v141, v137, v141
	global_store_dwordx2 v[138:139], v[140:141], off nt
	v_add_u32_e32 v138, 16, v128
	v_ashrrev_i32_e32 v139, 31, v138
	v_lshlrev_b64 v[138:139], 9, v[138:139]
	v_lshl_add_u64 v[138:139], v[130:131], 0, v[138:139]
	v_mul_f32_e32 v141, 0x3e38aa3b, v96
	v_mul_f32_e32 v129, 0x3e38aa3b, v108
	v_mul_f32_e32 v134, 0x3e38aa3b, v104
	v_mul_f32_e32 v137, 0x3e38aa3b, v100
	v_cvt_pk_bf16_f32 v140, v129, v134
	v_cvt_pk_bf16_f32 v141, v137, v141
	global_store_dwordx2 v[138:139], v[140:141], off nt
	v_add_u32_e32 v138, 17, v128
	v_ashrrev_i32_e32 v139, 31, v138
	v_lshlrev_b64 v[138:139], 9, v[138:139]
	v_lshl_add_u64 v[138:139], v[130:131], 0, v[138:139]
	v_mul_f32_e32 v141, 0x3e38aa3b, v97
	v_mul_f32_e32 v129, 0x3e38aa3b, v109
	v_mul_f32_e32 v134, 0x3e38aa3b, v105
	v_mul_f32_e32 v137, 0x3e38aa3b, v101
	v_cvt_pk_bf16_f32 v140, v129, v134
	v_cvt_pk_bf16_f32 v141, v137, v141
	global_store_dwordx2 v[138:139], v[140:141], off nt
	v_add_u32_e32 v138, 18, v128
	v_ashrrev_i32_e32 v139, 31, v138
	v_lshlrev_b64 v[138:139], 9, v[138:139]
	v_lshl_add_u64 v[138:139], v[130:131], 0, v[138:139]
	v_mul_f32_e32 v141, 0x3e38aa3b, v98
	v_mul_f32_e32 v129, 0x3e38aa3b, v110
	v_mul_f32_e32 v134, 0x3e38aa3b, v106
	v_mul_f32_e32 v137, 0x3e38aa3b, v102
	v_cvt_pk_bf16_f32 v140, v129, v134
	v_cvt_pk_bf16_f32 v141, v137, v141
	global_store_dwordx2 v[138:139], v[140:141], off nt
	v_add_u32_e32 v138, 19, v128
	v_ashrrev_i32_e32 v139, 31, v138
	v_lshlrev_b64 v[138:139], 9, v[138:139]
	v_lshl_add_u64 v[138:139], v[130:131], 0, v[138:139]
	v_mul_f32_e32 v141, 0x3e38aa3b, v99
	v_mul_f32_e32 v129, 0x3e38aa3b, v111
	v_mul_f32_e32 v134, 0x3e38aa3b, v107
	v_mul_f32_e32 v137, 0x3e38aa3b, v103
	v_cvt_pk_bf16_f32 v140, v129, v134
	v_cvt_pk_bf16_f32 v141, v137, v141
	global_store_dwordx2 v[138:139], v[140:141], off nt
	v_add_u32_e32 v138, 32, v128
	v_ashrrev_i32_e32 v139, 31, v138
	v_lshlrev_b64 v[138:139], 9, v[138:139]
	v_lshl_add_u64 v[138:139], v[130:131], 0, v[138:139]
	v_mul_f32_e32 v141, 0x3e38aa3b, v80
	v_mul_f32_e32 v129, 0x3e38aa3b, v92
	v_mul_f32_e32 v134, 0x3e38aa3b, v88
	v_mul_f32_e32 v137, 0x3e38aa3b, v84
	v_cvt_pk_bf16_f32 v140, v129, v134
	v_cvt_pk_bf16_f32 v141, v137, v141
	global_store_dwordx2 v[138:139], v[140:141], off nt
	v_add_u32_e32 v138, 33, v128
	v_ashrrev_i32_e32 v139, 31, v138
	v_lshlrev_b64 v[138:139], 9, v[138:139]
	v_lshl_add_u64 v[138:139], v[130:131], 0, v[138:139]
	v_mul_f32_e32 v141, 0x3e38aa3b, v81
	v_mul_f32_e32 v129, 0x3e38aa3b, v93
	v_mul_f32_e32 v134, 0x3e38aa3b, v89
	v_mul_f32_e32 v137, 0x3e38aa3b, v85
	v_cvt_pk_bf16_f32 v140, v129, v134
	v_cvt_pk_bf16_f32 v141, v137, v141
	global_store_dwordx2 v[138:139], v[140:141], off nt
	v_add_u32_e32 v138, 34, v128
	v_ashrrev_i32_e32 v139, 31, v138
	v_lshlrev_b64 v[138:139], 9, v[138:139]
	v_lshl_add_u64 v[138:139], v[130:131], 0, v[138:139]
	v_mul_f32_e32 v141, 0x3e38aa3b, v82
	v_mul_f32_e32 v129, 0x3e38aa3b, v94
	v_mul_f32_e32 v134, 0x3e38aa3b, v90
	v_mul_f32_e32 v137, 0x3e38aa3b, v86
	v_cvt_pk_bf16_f32 v140, v129, v134
	v_cvt_pk_bf16_f32 v141, v137, v141
	global_store_dwordx2 v[138:139], v[140:141], off nt
	v_add_u32_e32 v138, 35, v128
	v_ashrrev_i32_e32 v139, 31, v138
	v_lshlrev_b64 v[138:139], 9, v[138:139]
	v_lshl_add_u64 v[138:139], v[130:131], 0, v[138:139]
	v_mul_f32_e32 v141, 0x3e38aa3b, v83
	v_mul_f32_e32 v129, 0x3e38aa3b, v95
	v_mul_f32_e32 v134, 0x3e38aa3b, v91
	v_mul_f32_e32 v137, 0x3e38aa3b, v87
	v_cvt_pk_bf16_f32 v140, v129, v134
	v_cvt_pk_bf16_f32 v141, v137, v141
	global_store_dwordx2 v[138:139], v[140:141], off nt
	v_add_u32_e32 v138, 48, v128
	v_ashrrev_i32_e32 v139, 31, v138
	v_lshlrev_b64 v[138:139], 9, v[138:139]
	v_lshl_add_u64 v[138:139], v[130:131], 0, v[138:139]
	v_mul_f32_e32 v141, 0x3e38aa3b, v64
	v_mul_f32_e32 v129, 0x3e38aa3b, v76
	v_mul_f32_e32 v134, 0x3e38aa3b, v72
	v_mul_f32_e32 v137, 0x3e38aa3b, v68
	v_cvt_pk_bf16_f32 v140, v129, v134
	v_cvt_pk_bf16_f32 v141, v137, v141
	global_store_dwordx2 v[138:139], v[140:141], off nt
	v_add_u32_e32 v138, 49, v128
	v_ashrrev_i32_e32 v139, 31, v138
	v_lshlrev_b64 v[138:139], 9, v[138:139]
	v_lshl_add_u64 v[138:139], v[130:131], 0, v[138:139]
	v_mul_f32_e32 v141, 0x3e38aa3b, v65
	v_mul_f32_e32 v129, 0x3e38aa3b, v77
	v_mul_f32_e32 v134, 0x3e38aa3b, v73
	v_mul_f32_e32 v137, 0x3e38aa3b, v69
	v_cvt_pk_bf16_f32 v140, v129, v134
	v_cvt_pk_bf16_f32 v141, v137, v141
	global_store_dwordx2 v[138:139], v[140:141], off nt
	v_add_u32_e32 v138, 50, v128
	v_ashrrev_i32_e32 v139, 31, v138
	v_lshlrev_b64 v[138:139], 9, v[138:139]
	v_lshl_add_u64 v[138:139], v[130:131], 0, v[138:139]
	v_mul_f32_e32 v141, 0x3e38aa3b, v66
	v_mul_f32_e32 v129, 0x3e38aa3b, v78
	v_mul_f32_e32 v134, 0x3e38aa3b, v74
	v_mul_f32_e32 v137, 0x3e38aa3b, v70
	v_cvt_pk_bf16_f32 v140, v129, v134
	v_cvt_pk_bf16_f32 v141, v137, v141
	global_store_dwordx2 v[138:139], v[140:141], off nt
	v_add_u32_e32 v138, 51, v128
	v_ashrrev_i32_e32 v139, 31, v138
	v_lshlrev_b64 v[138:139], 9, v[138:139]
	v_lshl_add_u64 v[138:139], v[130:131], 0, v[138:139]
	v_mul_f32_e32 v141, 0x3e38aa3b, v67
	v_mul_f32_e32 v129, 0x3e38aa3b, v79
	v_mul_f32_e32 v134, 0x3e38aa3b, v75
	v_mul_f32_e32 v137, 0x3e38aa3b, v71
	v_cvt_pk_bf16_f32 v140, v129, v134
	v_cvt_pk_bf16_f32 v141, v137, v141
	global_store_dwordx2 v[138:139], v[140:141], off nt
	v_add_u32_e32 v138, 64, v128
	v_ashrrev_i32_e32 v139, 31, v138
	v_lshlrev_b64 v[138:139], 9, v[138:139]
	v_lshl_add_u64 v[138:139], v[130:131], 0, v[138:139]
	v_mul_f32_e32 v141, 0x3e38aa3b, v48
	v_mul_f32_e32 v129, 0x3e38aa3b, v60
	v_mul_f32_e32 v134, 0x3e38aa3b, v56
	v_mul_f32_e32 v137, 0x3e38aa3b, v52
	v_cvt_pk_bf16_f32 v140, v129, v134
	v_cvt_pk_bf16_f32 v141, v137, v141
	global_store_dwordx2 v[138:139], v[140:141], off nt
	v_add_u32_e32 v138, 0x41, v128
	v_ashrrev_i32_e32 v139, 31, v138
	v_lshlrev_b64 v[138:139], 9, v[138:139]
	v_lshl_add_u64 v[138:139], v[130:131], 0, v[138:139]
	v_mul_f32_e32 v141, 0x3e38aa3b, v49
	v_mul_f32_e32 v129, 0x3e38aa3b, v61
	v_mul_f32_e32 v134, 0x3e38aa3b, v57
	v_mul_f32_e32 v137, 0x3e38aa3b, v53
	v_cvt_pk_bf16_f32 v140, v129, v134
	v_cvt_pk_bf16_f32 v141, v137, v141
	global_store_dwordx2 v[138:139], v[140:141], off nt
	v_add_u32_e32 v138, 0x42, v128
	v_ashrrev_i32_e32 v139, 31, v138
	v_lshlrev_b64 v[138:139], 9, v[138:139]
	v_lshl_add_u64 v[138:139], v[130:131], 0, v[138:139]
	v_mul_f32_e32 v141, 0x3e38aa3b, v50
	v_mul_f32_e32 v129, 0x3e38aa3b, v62
	v_mul_f32_e32 v134, 0x3e38aa3b, v58
	v_mul_f32_e32 v137, 0x3e38aa3b, v54
	v_cvt_pk_bf16_f32 v140, v129, v134
	v_cvt_pk_bf16_f32 v141, v137, v141
	global_store_dwordx2 v[138:139], v[140:141], off nt
	v_add_u32_e32 v138, 0x43, v128
	v_ashrrev_i32_e32 v139, 31, v138
	v_lshlrev_b64 v[138:139], 9, v[138:139]
	v_lshl_add_u64 v[138:139], v[130:131], 0, v[138:139]
	v_mul_f32_e32 v141, 0x3e38aa3b, v51
	v_mul_f32_e32 v129, 0x3e38aa3b, v63
	v_mul_f32_e32 v134, 0x3e38aa3b, v59
	v_mul_f32_e32 v137, 0x3e38aa3b, v55
	v_cvt_pk_bf16_f32 v140, v129, v134
	v_cvt_pk_bf16_f32 v141, v137, v141
	global_store_dwordx2 v[138:139], v[140:141], off nt
	v_add_u32_e32 v138, 0x50, v128
	v_ashrrev_i32_e32 v139, 31, v138
	v_lshlrev_b64 v[138:139], 9, v[138:139]
	v_lshl_add_u64 v[138:139], v[130:131], 0, v[138:139]
	v_mul_f32_e32 v141, 0x3e38aa3b, v32
	v_mul_f32_e32 v129, 0x3e38aa3b, v44
	v_mul_f32_e32 v134, 0x3e38aa3b, v40
	v_mul_f32_e32 v137, 0x3e38aa3b, v36
	v_cvt_pk_bf16_f32 v140, v129, v134
	v_cvt_pk_bf16_f32 v141, v137, v141
	global_store_dwordx2 v[138:139], v[140:141], off nt
	v_add_u32_e32 v138, 0x51, v128
	v_ashrrev_i32_e32 v139, 31, v138
	v_lshlrev_b64 v[138:139], 9, v[138:139]
	v_lshl_add_u64 v[138:139], v[130:131], 0, v[138:139]
	v_mul_f32_e32 v141, 0x3e38aa3b, v33
	v_mul_f32_e32 v129, 0x3e38aa3b, v45
	v_mul_f32_e32 v134, 0x3e38aa3b, v41
	v_mul_f32_e32 v137, 0x3e38aa3b, v37
	v_cvt_pk_bf16_f32 v140, v129, v134
	v_cvt_pk_bf16_f32 v141, v137, v141
	global_store_dwordx2 v[138:139], v[140:141], off nt
	v_add_u32_e32 v138, 0x52, v128
	v_ashrrev_i32_e32 v139, 31, v138
	v_lshlrev_b64 v[138:139], 9, v[138:139]
	v_lshl_add_u64 v[138:139], v[130:131], 0, v[138:139]
	v_mul_f32_e32 v141, 0x3e38aa3b, v34
	v_mul_f32_e32 v129, 0x3e38aa3b, v46
	v_mul_f32_e32 v134, 0x3e38aa3b, v42
	v_mul_f32_e32 v137, 0x3e38aa3b, v38
	v_cvt_pk_bf16_f32 v140, v129, v134
	v_cvt_pk_bf16_f32 v141, v137, v141
	global_store_dwordx2 v[138:139], v[140:141], off nt
	v_add_u32_e32 v138, 0x53, v128
	v_ashrrev_i32_e32 v139, 31, v138
	v_lshlrev_b64 v[138:139], 9, v[138:139]
	v_lshl_add_u64 v[138:139], v[130:131], 0, v[138:139]
	v_mul_f32_e32 v141, 0x3e38aa3b, v35
	v_mul_f32_e32 v129, 0x3e38aa3b, v47
	v_mul_f32_e32 v134, 0x3e38aa3b, v43
	v_mul_f32_e32 v137, 0x3e38aa3b, v39
	v_cvt_pk_bf16_f32 v140, v129, v134
	v_cvt_pk_bf16_f32 v141, v137, v141
	global_store_dwordx2 v[138:139], v[140:141], off nt
	v_add_u32_e32 v138, 0x60, v128
	v_ashrrev_i32_e32 v139, 31, v138
	v_lshlrev_b64 v[138:139], 9, v[138:139]
	v_lshl_add_u64 v[138:139], v[130:131], 0, v[138:139]
	v_mul_f32_e32 v141, 0x3e38aa3b, v16
	v_mul_f32_e32 v129, 0x3e38aa3b, v28
	v_mul_f32_e32 v134, 0x3e38aa3b, v24
	v_mul_f32_e32 v137, 0x3e38aa3b, v20
	v_cvt_pk_bf16_f32 v140, v129, v134
	v_cvt_pk_bf16_f32 v141, v137, v141
	global_store_dwordx2 v[138:139], v[140:141], off nt
	v_add_u32_e32 v138, 0x61, v128
	v_ashrrev_i32_e32 v139, 31, v138
	v_lshlrev_b64 v[138:139], 9, v[138:139]
	v_lshl_add_u64 v[138:139], v[130:131], 0, v[138:139]
	v_mul_f32_e32 v141, 0x3e38aa3b, v17
	v_mul_f32_e32 v129, 0x3e38aa3b, v29
	v_mul_f32_e32 v134, 0x3e38aa3b, v25
	v_mul_f32_e32 v137, 0x3e38aa3b, v21
	v_cvt_pk_bf16_f32 v140, v129, v134
	v_cvt_pk_bf16_f32 v141, v137, v141
	global_store_dwordx2 v[138:139], v[140:141], off nt
	v_add_u32_e32 v138, 0x62, v128
	v_ashrrev_i32_e32 v139, 31, v138
	v_lshlrev_b64 v[138:139], 9, v[138:139]
	v_lshl_add_u64 v[138:139], v[130:131], 0, v[138:139]
	v_mul_f32_e32 v141, 0x3e38aa3b, v18
	v_mul_f32_e32 v129, 0x3e38aa3b, v30
	v_mul_f32_e32 v134, 0x3e38aa3b, v26
	v_mul_f32_e32 v137, 0x3e38aa3b, v22
	v_cvt_pk_bf16_f32 v140, v129, v134
	v_cvt_pk_bf16_f32 v141, v137, v141
	global_store_dwordx2 v[138:139], v[140:141], off nt
	v_add_u32_e32 v138, 0x63, v128
	v_ashrrev_i32_e32 v139, 31, v138
	v_lshlrev_b64 v[138:139], 9, v[138:139]
	v_lshl_add_u64 v[138:139], v[130:131], 0, v[138:139]
	v_mul_f32_e32 v141, 0x3e38aa3b, v19
	v_mul_f32_e32 v129, 0x3e38aa3b, v31
	v_mul_f32_e32 v134, 0x3e38aa3b, v27
	v_mul_f32_e32 v137, 0x3e38aa3b, v23
	v_cvt_pk_bf16_f32 v140, v129, v134
	v_cvt_pk_bf16_f32 v141, v137, v141
	global_store_dwordx2 v[138:139], v[140:141], off nt
	v_add_u32_e32 v138, 0x70, v128
	v_ashrrev_i32_e32 v139, 31, v138
	v_lshlrev_b64 v[138:139], 9, v[138:139]
	v_lshl_add_u64 v[138:139], v[130:131], 0, v[138:139]
	v_mul_f32_e32 v141, 0x3e38aa3b, v0
	v_mul_f32_e32 v129, 0x3e38aa3b, v12
	v_mul_f32_e32 v134, 0x3e38aa3b, v8
	v_mul_f32_e32 v137, 0x3e38aa3b, v4
	v_cvt_pk_bf16_f32 v140, v129, v134
	v_cvt_pk_bf16_f32 v141, v137, v141
	global_store_dwordx2 v[138:139], v[140:141], off nt
	v_add_u32_e32 v138, 0x71, v128
	v_ashrrev_i32_e32 v139, 31, v138
	v_lshlrev_b64 v[138:139], 9, v[138:139]
	v_lshl_add_u64 v[138:139], v[130:131], 0, v[138:139]
	v_mul_f32_e32 v141, 0x3e38aa3b, v1
	v_mul_f32_e32 v129, 0x3e38aa3b, v13
	v_mul_f32_e32 v134, 0x3e38aa3b, v9
	v_mul_f32_e32 v137, 0x3e38aa3b, v5
	v_cvt_pk_bf16_f32 v140, v129, v134
	v_cvt_pk_bf16_f32 v141, v137, v141
	global_store_dwordx2 v[138:139], v[140:141], off nt
	v_add_u32_e32 v138, 0x72, v128
	v_ashrrev_i32_e32 v139, 31, v138
	v_lshlrev_b64 v[138:139], 9, v[138:139]
	v_lshl_add_u64 v[138:139], v[130:131], 0, v[138:139]
	v_mul_f32_e32 v141, 0x3e38aa3b, v2
	v_mul_f32_e32 v129, 0x3e38aa3b, v14
	v_mul_f32_e32 v134, 0x3e38aa3b, v10
	v_mul_f32_e32 v137, 0x3e38aa3b, v6
	v_cvt_pk_bf16_f32 v140, v129, v134
	v_cvt_pk_bf16_f32 v141, v137, v141
	global_store_dwordx2 v[138:139], v[140:141], off nt
	v_add_u32_e32 v128, 0x73, v128
	v_ashrrev_i32_e32 v129, 31, v128
	v_lshlrev_b64 v[128:129], 9, v[128:129]
	v_lshl_add_u64 v[128:129], v[130:131], 0, v[128:129]
	v_mul_f32_e32 v130, 0x3e38aa3b, v15
	v_mul_f32_e32 v131, 0x3e38aa3b, v11
	v_mul_f32_e32 v134, 0x3e38aa3b, v7
	v_mul_f32_e32 v137, 0x3e38aa3b, v3
	v_cvt_pk_bf16_f32 v130, v130, v131
	v_cvt_pk_bf16_f32 v131, v134, v137
	global_store_dwordx2 v[128:129], v[130:131], off nt

.LBB0_483:
	s_andn2_saveexec_b64 s[66:67], s[66:67]
	s_cbranch_execz .LBB0_491
	v_cmp_lt_i32_e32 vcc, 5, v176
	s_mov_b64 s[72:73], s[96:97]
	s_and_saveexec_b64 s[24:25], vcc
	s_xor_b64 s[74:75], exec, s[24:25]
	s_cbranch_execz .LBB0_488
	v_cmp_gt_i32_e32 vcc, 7, v176
	s_mov_b64 s[94:95], -1
	s_and_saveexec_b64 s[72:73], vcc
	s_cbranch_execz .LBB0_487
	v_readlane_b32 s36, v253, 44
	v_readlane_b32 s24, v253, 22
	v_ashrrev_i32_e32 v137, 31, v136
	v_readlane_b32 s40, v253, 48
	v_readlane_b32 s41, v253, 49
	v_readlane_b32 s25, v253, 23
	v_lshl_add_u32 v134, v146, 2, v211
	v_readlane_b32 s37, v253, 45
	v_readlane_b32 s38, v253, 46
	v_readlane_b32 s39, v253, 47
	v_readlane_b32 s42, v253, 50
	v_readlane_b32 s43, v253, 51
	v_readlane_b32 s44, v253, 52
	v_readlane_b32 s45, v253, 53
	v_readlane_b32 s46, v253, 54
	v_readlane_b32 s47, v253, 55
	v_readlane_b32 s48, v253, 56
	v_readlane_b32 s49, v253, 57
	v_readlane_b32 s50, v253, 58
	v_readlane_b32 s51, v253, 59
	v_lshl_add_u64 v[130:131], v[136:137], 1, s[40:41]
	v_lshl_add_u64 v[128:129], v[136:137], 2, s[24:25]
	v_mad_i64_i32 v[138:139], s[24:25], v134, s15, 0
	v_lshl_add_u64 v[140:141], v[138:139], 1, v[130:131]
	v_cvt_pk_bf16_f32 v142, v124, v120
	v_cvt_pk_bf16_f32 v143, v116, v112
	global_store_dwordx2 v[140:141], v[142:143], off nt
	v_lshl_add_u64 v[142:143], v[138:139], 2, v[128:129]
	v_mov_b32_e32 v138, v124
	v_mov_b32_e32 v139, v120
	v_mov_b32_e32 v140, v116
	v_mov_b32_e32 v141, v112
	global_store_dwordx4 v[142:143], v[138:141], off nt
	v_or_b32_e32 v137, 1, v134
	s_nop 0
	v_mad_i64_i32 v[138:139], s[24:25], v137, s15, 0
	v_lshl_add_u64 v[140:141], v[138:139], 1, v[130:131]
	v_cvt_pk_bf16_f32 v142, v125, v121
	v_cvt_pk_bf16_f32 v143, v117, v113
	global_store_dwordx2 v[140:141], v[142:143], off nt
	v_lshl_add_u64 v[142:143], v[138:139], 2, v[128:129]
	v_mov_b32_e32 v138, v125
	v_mov_b32_e32 v139, v121
	v_mov_b32_e32 v140, v117
	v_mov_b32_e32 v141, v113
	global_store_dwordx4 v[142:143], v[138:141], off nt
	v_or_b32_e32 v137, 2, v134
	s_nop 0
	v_mad_i64_i32 v[138:139], s[24:25], v137, s15, 0
	v_lshl_add_u64 v[140:141], v[138:139], 1, v[130:131]
	v_cvt_pk_bf16_f32 v142, v126, v122
	v_cvt_pk_bf16_f32 v143, v118, v114
	global_store_dwordx2 v[140:141], v[142:143], off nt
	v_lshl_add_u64 v[142:143], v[138:139], 2, v[128:129]
	v_mov_b32_e32 v138, v126
	v_mov_b32_e32 v139, v122
	v_mov_b32_e32 v140, v118
	v_mov_b32_e32 v141, v114
	global_store_dwordx4 v[142:143], v[138:141], off nt
	v_or_b32_e32 v137, 3, v134
	s_nop 0
	v_mad_i64_i32 v[138:139], s[24:25], v137, s15, 0
	v_lshl_add_u64 v[140:141], v[138:139], 1, v[130:131]
	v_cvt_pk_bf16_f32 v142, v127, v123
	v_cvt_pk_bf16_f32 v143, v119, v115
	global_store_dwordx2 v[140:141], v[142:143], off nt
	v_lshl_add_u64 v[142:143], v[138:139], 2, v[128:129]
	v_mov_b32_e32 v138, v127
	v_mov_b32_e32 v139, v123
	v_mov_b32_e32 v140, v119
	v_mov_b32_e32 v141, v115
	global_store_dwordx4 v[142:143], v[138:141], off nt
	v_add_u32_e32 v137, 16, v134
	s_nop 0
	v_mad_i64_i32 v[138:139], s[24:25], v137, s15, 0
	v_lshl_add_u64 v[140:141], v[138:139], 1, v[130:131]
	v_cvt_pk_bf16_f32 v142, v108, v104
	v_cvt_pk_bf16_f32 v143, v100, v96
	global_store_dwordx2 v[140:141], v[142:143], off nt
	v_lshl_add_u64 v[142:143], v[138:139], 2, v[128:129]
	v_mov_b32_e32 v138, v108
	v_mov_b32_e32 v139, v104
	v_mov_b32_e32 v140, v100
	v_mov_b32_e32 v141, v96
	global_store_dwordx4 v[142:143], v[138:141], off nt
	v_add_u32_e32 v137, 17, v134
	s_nop 0
	v_mad_i64_i32 v[138:139], s[24:25], v137, s15, 0
	v_lshl_add_u64 v[140:141], v[138:139], 1, v[130:131]
	v_cvt_pk_bf16_f32 v142, v109, v105
	v_cvt_pk_bf16_f32 v143, v101, v97
	global_store_dwordx2 v[140:141], v[142:143], off nt
	v_lshl_add_u64 v[142:143], v[138:139], 2, v[128:129]
	v_mov_b32_e32 v138, v109
	v_mov_b32_e32 v139, v105
	v_mov_b32_e32 v140, v101
	v_mov_b32_e32 v141, v97
	global_store_dwordx4 v[142:143], v[138:141], off nt
	v_add_u32_e32 v137, 18, v134
	s_nop 0
	v_mad_i64_i32 v[138:139], s[24:25], v137, s15, 0
	v_lshl_add_u64 v[140:141], v[138:139], 1, v[130:131]
	v_cvt_pk_bf16_f32 v142, v110, v106
	v_cvt_pk_bf16_f32 v143, v102, v98
	global_store_dwordx2 v[140:141], v[142:143], off nt
	v_lshl_add_u64 v[142:143], v[138:139], 2, v[128:129]
	v_mov_b32_e32 v138, v110
	v_mov_b32_e32 v139, v106
	v_mov_b32_e32 v140, v102
	v_mov_b32_e32 v141, v98
	global_store_dwordx4 v[142:143], v[138:141], off nt
	v_add_u32_e32 v137, 19, v134
	s_nop 0
	v_mad_i64_i32 v[138:139], s[24:25], v137, s15, 0
	v_lshl_add_u64 v[140:141], v[138:139], 1, v[130:131]
	v_cvt_pk_bf16_f32 v142, v111, v107
	v_cvt_pk_bf16_f32 v143, v103, v99
	global_store_dwordx2 v[140:141], v[142:143], off nt
	v_lshl_add_u64 v[142:143], v[138:139], 2, v[128:129]
	v_mov_b32_e32 v138, v111
	v_mov_b32_e32 v139, v107
	v_mov_b32_e32 v140, v103
	v_mov_b32_e32 v141, v99
	global_store_dwordx4 v[142:143], v[138:141], off nt
	v_add_u32_e32 v137, 32, v134
	s_nop 0
	v_mad_i64_i32 v[138:139], s[24:25], v137, s15, 0
	v_lshl_add_u64 v[140:141], v[138:139], 1, v[130:131]
	v_cvt_pk_bf16_f32 v142, v92, v88
	v_cvt_pk_bf16_f32 v143, v84, v80
	global_store_dwordx2 v[140:141], v[142:143], off nt
	v_lshl_add_u64 v[142:143], v[138:139], 2, v[128:129]
	v_mov_b32_e32 v138, v92
	v_mov_b32_e32 v139, v88
	v_mov_b32_e32 v140, v84
	v_mov_b32_e32 v141, v80
	global_store_dwordx4 v[142:143], v[138:141], off nt
	v_add_u32_e32 v137, 33, v134
	s_nop 0
	v_mad_i64_i32 v[138:139], s[24:25], v137, s15, 0
	v_lshl_add_u64 v[140:141], v[138:139], 1, v[130:131]
	v_cvt_pk_bf16_f32 v142, v93, v89
	v_cvt_pk_bf16_f32 v143, v85, v81
	global_store_dwordx2 v[140:141], v[142:143], off nt
	v_lshl_add_u64 v[142:143], v[138:139], 2, v[128:129]
	v_mov_b32_e32 v138, v93
	v_mov_b32_e32 v139, v89
	v_mov_b32_e32 v140, v85
	v_mov_b32_e32 v141, v81
	global_store_dwordx4 v[142:143], v[138:141], off nt
	v_add_u32_e32 v137, 34, v134
	s_nop 0
	v_mad_i64_i32 v[138:139], s[24:25], v137, s15, 0
	v_lshl_add_u64 v[140:141], v[138:139], 1, v[130:131]
	v_cvt_pk_bf16_f32 v142, v94, v90
	v_cvt_pk_bf16_f32 v143, v86, v82
	global_store_dwordx2 v[140:141], v[142:143], off nt
	v_lshl_add_u64 v[142:143], v[138:139], 2, v[128:129]
	v_mov_b32_e32 v138, v94
	v_mov_b32_e32 v139, v90
	v_mov_b32_e32 v140, v86
	v_mov_b32_e32 v141, v82
	global_store_dwordx4 v[142:143], v[138:141], off nt
	v_add_u32_e32 v137, 35, v134
	s_nop 0
	v_mad_i64_i32 v[138:139], s[24:25], v137, s15, 0
	v_lshl_add_u64 v[140:141], v[138:139], 1, v[130:131]
	v_cvt_pk_bf16_f32 v142, v95, v91
	v_cvt_pk_bf16_f32 v143, v87, v83
	global_store_dwordx2 v[140:141], v[142:143], off nt
	v_lshl_add_u64 v[142:143], v[138:139], 2, v[128:129]
	v_mov_b32_e32 v138, v95
	v_mov_b32_e32 v139, v91
	v_mov_b32_e32 v140, v87
	v_mov_b32_e32 v141, v83
	global_store_dwordx4 v[142:143], v[138:141], off nt
	v_add_u32_e32 v137, 48, v134
	s_nop 0
	v_mad_i64_i32 v[138:139], s[24:25], v137, s15, 0
	v_lshl_add_u64 v[140:141], v[138:139], 1, v[130:131]
	v_cvt_pk_bf16_f32 v142, v76, v72
	v_cvt_pk_bf16_f32 v143, v68, v64
	global_store_dwordx2 v[140:141], v[142:143], off nt
	v_lshl_add_u64 v[142:143], v[138:139], 2, v[128:129]
	v_mov_b32_e32 v138, v76
	v_mov_b32_e32 v139, v72
	v_mov_b32_e32 v140, v68
	v_mov_b32_e32 v141, v64
	global_store_dwordx4 v[142:143], v[138:141], off nt
	v_add_u32_e32 v137, 49, v134
	s_nop 0
	v_mad_i64_i32 v[138:139], s[24:25], v137, s15, 0
	v_lshl_add_u64 v[140:141], v[138:139], 1, v[130:131]
	v_cvt_pk_bf16_f32 v142, v77, v73
	v_cvt_pk_bf16_f32 v143, v69, v65
	global_store_dwordx2 v[140:141], v[142:143], off nt
	v_lshl_add_u64 v[142:143], v[138:139], 2, v[128:129]
	v_mov_b32_e32 v138, v77
	v_mov_b32_e32 v139, v73
	v_mov_b32_e32 v140, v69
	v_mov_b32_e32 v141, v65
	global_store_dwordx4 v[142:143], v[138:141], off nt
	v_add_u32_e32 v137, 50, v134
	s_nop 0
	v_mad_i64_i32 v[138:139], s[24:25], v137, s15, 0
	v_lshl_add_u64 v[140:141], v[138:139], 1, v[130:131]
	v_cvt_pk_bf16_f32 v142, v78, v74
	v_cvt_pk_bf16_f32 v143, v70, v66
	global_store_dwordx2 v[140:141], v[142:143], off nt
	v_lshl_add_u64 v[142:143], v[138:139], 2, v[128:129]
	v_mov_b32_e32 v138, v78
	v_mov_b32_e32 v139, v74
	v_mov_b32_e32 v140, v70
	v_mov_b32_e32 v141, v66
	global_store_dwordx4 v[142:143], v[138:141], off nt
	v_add_u32_e32 v137, 51, v134
	s_nop 0
	v_mad_i64_i32 v[138:139], s[24:25], v137, s15, 0
	v_lshl_add_u64 v[140:141], v[138:139], 1, v[130:131]
	v_cvt_pk_bf16_f32 v142, v79, v75
	v_cvt_pk_bf16_f32 v143, v71, v67
	global_store_dwordx2 v[140:141], v[142:143], off nt
	v_lshl_add_u64 v[142:143], v[138:139], 2, v[128:129]
	v_mov_b32_e32 v138, v79
	v_mov_b32_e32 v139, v75
	v_mov_b32_e32 v140, v71
	v_mov_b32_e32 v141, v67
	global_store_dwordx4 v[142:143], v[138:141], off nt
	v_add_u32_e32 v137, 64, v134
	s_nop 0
	v_mad_i64_i32 v[138:139], s[24:25], v137, s15, 0
	v_lshl_add_u64 v[140:141], v[138:139], 1, v[130:131]
	v_cvt_pk_bf16_f32 v142, v60, v56
	v_cvt_pk_bf16_f32 v143, v52, v48
	global_store_dwordx2 v[140:141], v[142:143], off nt
	v_lshl_add_u64 v[142:143], v[138:139], 2, v[128:129]
	v_mov_b32_e32 v138, v60
	v_mov_b32_e32 v139, v56
	v_mov_b32_e32 v140, v52
	v_mov_b32_e32 v141, v48
	global_store_dwordx4 v[142:143], v[138:141], off nt
	v_add_u32_e32 v137, 0x41, v134
	s_nop 0
	v_mad_i64_i32 v[138:139], s[24:25], v137, s15, 0
	v_lshl_add_u64 v[140:141], v[138:139], 1, v[130:131]
	v_cvt_pk_bf16_f32 v142, v61, v57
	v_cvt_pk_bf16_f32 v143, v53, v49
	global_store_dwordx2 v[140:141], v[142:143], off nt
	v_lshl_add_u64 v[142:143], v[138:139], 2, v[128:129]
	v_mov_b32_e32 v138, v61
	v_mov_b32_e32 v139, v57
	v_mov_b32_e32 v140, v53
	v_mov_b32_e32 v141, v49
	global_store_dwordx4 v[142:143], v[138:141], off nt
	v_add_u32_e32 v137, 0x42, v134
	s_nop 0
	v_mad_i64_i32 v[138:139], s[24:25], v137, s15, 0
	v_lshl_add_u64 v[140:141], v[138:139], 1, v[130:131]
	v_cvt_pk_bf16_f32 v142, v62, v58
	v_cvt_pk_bf16_f32 v143, v54, v50
	global_store_dwordx2 v[140:141], v[142:143], off nt
	v_lshl_add_u64 v[142:143], v[138:139], 2, v[128:129]
	v_mov_b32_e32 v138, v62
	v_mov_b32_e32 v139, v58
	v_mov_b32_e32 v140, v54
	v_mov_b32_e32 v141, v50
	global_store_dwordx4 v[142:143], v[138:141], off nt
	v_add_u32_e32 v137, 0x43, v134
	s_nop 0
	v_mad_i64_i32 v[138:139], s[24:25], v137, s15, 0
	v_lshl_add_u64 v[140:141], v[138:139], 1, v[130:131]
	v_cvt_pk_bf16_f32 v142, v63, v59
	v_cvt_pk_bf16_f32 v143, v55, v51
	global_store_dwordx2 v[140:141], v[142:143], off nt
	v_lshl_add_u64 v[142:143], v[138:139], 2, v[128:129]
	v_mov_b32_e32 v138, v63
	v_mov_b32_e32 v139, v59
	v_mov_b32_e32 v140, v55
	v_mov_b32_e32 v141, v51
	global_store_dwordx4 v[142:143], v[138:141], off nt
	v_add_u32_e32 v137, 0x50, v134
	s_nop 0
	v_mad_i64_i32 v[138:139], s[24:25], v137, s15, 0
	v_lshl_add_u64 v[140:141], v[138:139], 1, v[130:131]
	v_cvt_pk_bf16_f32 v142, v44, v40
	v_cvt_pk_bf16_f32 v143, v36, v32
	global_store_dwordx2 v[140:141], v[142:143], off nt
	v_lshl_add_u64 v[142:143], v[138:139], 2, v[128:129]
	v_mov_b32_e32 v138, v44
	v_mov_b32_e32 v139, v40
	v_mov_b32_e32 v140, v36
	v_mov_b32_e32 v141, v32
	global_store_dwordx4 v[142:143], v[138:141], off nt
	v_add_u32_e32 v137, 0x51, v134
	s_nop 0
	v_mad_i64_i32 v[138:139], s[24:25], v137, s15, 0
	v_lshl_add_u64 v[140:141], v[138:139], 1, v[130:131]
	v_cvt_pk_bf16_f32 v142, v45, v41
	v_cvt_pk_bf16_f32 v143, v37, v33
	global_store_dwordx2 v[140:141], v[142:143], off nt
	v_lshl_add_u64 v[142:143], v[138:139], 2, v[128:129]
	v_mov_b32_e32 v138, v45
	v_mov_b32_e32 v139, v41
	v_mov_b32_e32 v140, v37
	v_mov_b32_e32 v141, v33
	global_store_dwordx4 v[142:143], v[138:141], off nt
	v_add_u32_e32 v137, 0x52, v134
	s_nop 0
	v_mad_i64_i32 v[138:139], s[24:25], v137, s15, 0
	v_lshl_add_u64 v[140:141], v[138:139], 1, v[130:131]
	v_cvt_pk_bf16_f32 v142, v46, v42
	v_cvt_pk_bf16_f32 v143, v38, v34
	global_store_dwordx2 v[140:141], v[142:143], off nt
	v_lshl_add_u64 v[142:143], v[138:139], 2, v[128:129]
	v_mov_b32_e32 v138, v46
	v_mov_b32_e32 v139, v42
	v_mov_b32_e32 v140, v38
	v_mov_b32_e32 v141, v34
	global_store_dwordx4 v[142:143], v[138:141], off nt
	v_add_u32_e32 v137, 0x53, v134
	s_nop 0
	v_mad_i64_i32 v[138:139], s[24:25], v137, s15, 0
	v_lshl_add_u64 v[140:141], v[138:139], 1, v[130:131]
	v_cvt_pk_bf16_f32 v142, v47, v43
	v_cvt_pk_bf16_f32 v143, v39, v35
	global_store_dwordx2 v[140:141], v[142:143], off nt
	v_lshl_add_u64 v[142:143], v[138:139], 2, v[128:129]
	v_mov_b32_e32 v138, v47
	v_mov_b32_e32 v139, v43
	v_mov_b32_e32 v140, v39
	v_mov_b32_e32 v141, v35
	global_store_dwordx4 v[142:143], v[138:141], off nt
	v_add_u32_e32 v137, 0x60, v134
	s_nop 0
	v_mad_i64_i32 v[138:139], s[24:25], v137, s15, 0
	v_lshl_add_u64 v[140:141], v[138:139], 1, v[130:131]
	v_cvt_pk_bf16_f32 v142, v28, v24
	v_cvt_pk_bf16_f32 v143, v20, v16
	global_store_dwordx2 v[140:141], v[142:143], off nt
	v_lshl_add_u64 v[142:143], v[138:139], 2, v[128:129]
	v_mov_b32_e32 v138, v28
	v_mov_b32_e32 v139, v24
	v_mov_b32_e32 v140, v20
	v_mov_b32_e32 v141, v16
	global_store_dwordx4 v[142:143], v[138:141], off nt
	v_add_u32_e32 v137, 0x61, v134
	s_nop 0
	v_mad_i64_i32 v[138:139], s[24:25], v137, s15, 0
	v_lshl_add_u64 v[140:141], v[138:139], 1, v[130:131]
	v_cvt_pk_bf16_f32 v142, v29, v25
	v_cvt_pk_bf16_f32 v143, v21, v17
	global_store_dwordx2 v[140:141], v[142:143], off nt
	v_lshl_add_u64 v[142:143], v[138:139], 2, v[128:129]
	v_mov_b32_e32 v138, v29
	v_mov_b32_e32 v139, v25
	v_mov_b32_e32 v140, v21
	v_mov_b32_e32 v141, v17
	global_store_dwordx4 v[142:143], v[138:141], off nt
	v_add_u32_e32 v137, 0x62, v134
	s_nop 0
	v_mad_i64_i32 v[138:139], s[24:25], v137, s15, 0
	v_lshl_add_u64 v[140:141], v[138:139], 1, v[130:131]
	v_cvt_pk_bf16_f32 v142, v30, v26
	v_cvt_pk_bf16_f32 v143, v22, v18
	global_store_dwordx2 v[140:141], v[142:143], off nt
	v_lshl_add_u64 v[142:143], v[138:139], 2, v[128:129]
	v_mov_b32_e32 v138, v30
	v_mov_b32_e32 v139, v26
	v_mov_b32_e32 v140, v22
	v_mov_b32_e32 v141, v18
	global_store_dwordx4 v[142:143], v[138:141], off nt
	v_add_u32_e32 v137, 0x63, v134
	s_nop 0
	v_mad_i64_i32 v[138:139], s[24:25], v137, s15, 0
	v_lshl_add_u64 v[140:141], v[138:139], 1, v[130:131]
	v_cvt_pk_bf16_f32 v142, v31, v27
	v_cvt_pk_bf16_f32 v143, v23, v19
	global_store_dwordx2 v[140:141], v[142:143], off nt
	v_lshl_add_u64 v[142:143], v[138:139], 2, v[128:129]
	v_mov_b32_e32 v138, v31
	v_mov_b32_e32 v139, v27
	v_mov_b32_e32 v140, v23
	v_mov_b32_e32 v141, v19
	global_store_dwordx4 v[142:143], v[138:141], off nt
	v_add_u32_e32 v137, 0x70, v134
	s_nop 0
	v_mad_i64_i32 v[138:139], s[24:25], v137, s15, 0
	v_lshl_add_u64 v[140:141], v[138:139], 1, v[130:131]
	v_cvt_pk_bf16_f32 v142, v12, v8
	v_cvt_pk_bf16_f32 v143, v4, v0
	global_store_dwordx2 v[140:141], v[142:143], off nt
	v_lshl_add_u64 v[142:143], v[138:139], 2, v[128:129]
	v_mov_b32_e32 v138, v12
	v_mov_b32_e32 v139, v8
	v_mov_b32_e32 v140, v4
	v_mov_b32_e32 v141, v0
	global_store_dwordx4 v[142:143], v[138:141], off nt
	v_add_u32_e32 v137, 0x71, v134
	s_nop 0
	v_mad_i64_i32 v[138:139], s[24:25], v137, s15, 0
	v_lshl_add_u64 v[140:141], v[138:139], 1, v[130:131]
	v_cvt_pk_bf16_f32 v142, v13, v9
	v_cvt_pk_bf16_f32 v143, v5, v1
	global_store_dwordx2 v[140:141], v[142:143], off nt
	v_lshl_add_u64 v[142:143], v[138:139], 2, v[128:129]
	v_mov_b32_e32 v138, v13
	v_mov_b32_e32 v139, v9
	v_mov_b32_e32 v140, v5
	v_mov_b32_e32 v141, v1
	global_store_dwordx4 v[142:143], v[138:141], off nt
	v_add_u32_e32 v137, 0x72, v134
	s_nop 0
	v_mad_i64_i32 v[138:139], s[24:25], v137, s15, 0
	v_lshl_add_u64 v[140:141], v[138:139], 1, v[130:131]
	v_cvt_pk_bf16_f32 v142, v14, v10
	v_cvt_pk_bf16_f32 v143, v6, v2
	global_store_dwordx2 v[140:141], v[142:143], off nt
	v_lshl_add_u64 v[142:143], v[138:139], 2, v[128:129]
	v_mov_b32_e32 v138, v14
	v_mov_b32_e32 v139, v10
	v_mov_b32_e32 v140, v6
	v_mov_b32_e32 v141, v2
	global_store_dwordx4 v[142:143], v[138:141], off nt
	v_add_u32_e32 v134, 0x73, v134
	s_nop 0
	v_mad_i64_i32 v[138:139], s[24:25], v134, s15, 0
	v_lshl_add_u64 v[130:131], v[138:139], 1, v[130:131]
	v_cvt_pk_bf16_f32 v140, v15, v11
	v_cvt_pk_bf16_f32 v141, v7, v3
	global_store_dwordx2 v[130:131], v[140:141], off nt
	v_lshl_add_u64 v[138:139], v[138:139], 2, v[128:129]
	v_mov_b32_e32 v128, v15
	v_mov_b32_e32 v129, v11
	v_mov_b32_e32 v130, v7
	v_mov_b32_e32 v131, v3
	global_store_dwordx4 v[138:139], v[128:131], off nt
	s_xor_b64 s[94:95], exec, -1

.LBB0_488:
	s_andn2_saveexec_b64 s[74:75], s[74:75]
	s_cbranch_execz .LBB0_490
	v_mbcnt_hi_u32_b32 v128, -1, v204
	v_and_b32_e32 v130, 64, v128
	v_xor_b32_e32 v129, 8, v128
	v_add_u32_e32 v130, 64, v130
	v_cmp_lt_i32_e32 vcc, v129, v130
	v_readlane_b32 s36, v253, 44
	v_readlane_b32 s24, v253, 24
	v_cndmask_b32_e32 v128, v128, v129, vcc
	v_cmp_gt_u32_e32 vcc, 8, v175
	v_ashrrev_i32_e32 v137, 31, v136
	v_readlane_b32 s38, v253, 46
	v_readlane_b32 s39, v253, 47
	v_readlane_b32 s25, v253, 25
	v_lshl_add_u32 v147, v146, 2, v211
	v_lshlrev_b32_e32 v149, 2, v128
	v_cndmask_b32_e64 v148, 1.0, -1.0, vcc
	v_readlane_b32 s37, v253, 45
	v_readlane_b32 s40, v253, 48
	v_readlane_b32 s41, v253, 49
	v_readlane_b32 s42, v253, 50
	v_readlane_b32 s43, v253, 51
	v_readlane_b32 s44, v253, 52
	v_readlane_b32 s45, v253, 53
	v_readlane_b32 s46, v253, 54
	v_readlane_b32 s47, v253, 55
	v_readlane_b32 s48, v253, 56
	v_readlane_b32 s49, v253, 57
	v_readlane_b32 s50, v253, 58
	v_readlane_b32 s51, v253, 59
	v_lshl_add_u64 v[138:139], v[136:137], 1, s[38:39]
	v_lshl_add_u64 v[140:141], v[136:137], 2, s[24:25]
	v_lshlrev_b32_e32 v128, 5, v210
	v_and_b32_e32 v134, 0xe0, v128
	v_lshlrev_b32_e32 v128, 8, v147
	v_lshl_add_u64 v[142:143], s[58:59], 0, v[134:135]
	v_and_b32_e32 v134, 0x7fc00, v128
	v_lshl_add_u64 v[154:155], v[142:143], 0, v[134:135]
	global_load_dwordx3 v[158:160], v[154:155], off offset:256
	global_load_dwordx4 v[128:131], v[154:155], off offset:268
	global_load_dword v145, v[154:155], off offset:284
	global_load_dwordx4 v[150:153], v[154:155], off offset:16
	ds_bpermute_b32 v144, v149, v116
	global_load_dwordx4 v[154:157], v[154:155], off
	ds_bpermute_b32 v137, v149, v120
	ds_bpermute_b32 v134, v149, v124
	v_mov_b32_e32 v170, v116
	v_mov_b32_e32 v168, v124
	v_mov_b32_e32 v167, v120
	s_waitcnt lgkmcnt(1)
	v_mul_f32_e32 v169, v148, v137
	ds_bpermute_b32 v137, v149, v125
	s_waitcnt lgkmcnt(1)
	v_mul_f32_e32 v166, v148, v134
	v_mad_i64_i32 v[172:173], s[24:25], v147, s15, 0
	v_or_b32_e32 v134, 1, v147
	s_waitcnt vmcnt(5)
	v_lshl_add_u64 v[178:179], v[172:173], 1, v[138:139]
	v_lshl_add_u64 v[172:173], v[172:173], 2, v[140:141]
	s_waitcnt vmcnt(4)
	v_mov_b32_e32 v161, v160
	s_waitcnt vmcnt(1)
	v_mov_b32_e32 v163, v152
	v_mov_b32_e32 v162, v151
	ds_bpermute_b32 v151, v149, v112
	s_waitcnt vmcnt(0)
	v_mov_b32_e32 v164, v155
	v_mov_b32_e32 v165, v156
	v_mul_f32_e32 v156, v148, v144
	v_mov_b32_e32 v155, v157
	s_waitcnt lgkmcnt(0)
	v_mul_f32_e32 v171, v148, v151
	v_mov_b32_e32 v151, v153
	v_mov_b32_e32 v157, v112
	v_pk_mul_f32 v[150:151], v[170:171], v[150:151]
	ds_bpermute_b32 v144, v149, v121
	ds_bpermute_b32 v152, v149, v113
	v_pk_fma_f32 v[156:157], v[162:163], v[156:157], v[150:151]
	ds_bpermute_b32 v151, v149, v117
	v_pk_mul_f32 v[154:155], v[168:169], v[154:155]
	v_mov_b32_e32 v160, v159
	v_pk_fma_f32 v[154:155], v[164:165], v[166:167], v[154:155]
	s_waitcnt lgkmcnt(2)
	v_mul_f32_e32 v153, v148, v144
	s_waitcnt lgkmcnt(1)
	v_mul_f32_e32 v167, v148, v152
	v_mov_b32_e32 v152, v125
	v_mov_b32_e32 v159, v128
	v_mov_b32_e32 v166, v117
	v_mov_b32_e32 v144, v129
	v_cvt_pk_bf16_f32 v164, v154, v155
	v_cvt_pk_bf16_f32 v165, v156, v157
	v_mul_f32_e32 v150, v148, v137
	s_waitcnt lgkmcnt(0)
	v_mul_f32_e32 v162, v148, v151
	v_mad_i64_i32 v[168:169], s[24:25], v134, s15, 0
	v_mov_b32_e32 v151, v121
	v_pk_mul_f32 v[152:153], v[152:153], v[158:159]
	v_mov_b32_e32 v163, v113
	v_pk_mul_f32 v[144:145], v[166:167], v[144:145]
	v_lshl_add_u64 v[170:171], v[168:169], 1, v[138:139]
	v_lshl_add_u64 v[168:169], v[168:169], 2, v[140:141]
	v_pk_fma_f32 v[150:151], v[160:161], v[150:151], v[152:153]
	v_pk_fma_f32 v[152:153], v[130:131], v[162:163], v[144:145]
	v_cvt_pk_bf16_f32 v128, v150, v151
	global_store_dwordx2 v[178:179], v[164:165], off nt
	global_store_dwordx4 v[172:173], v[154:157], off nt
	v_cvt_pk_bf16_f32 v129, v152, v153
	global_store_dwordx2 v[170:171], v[128:129], off nt
	global_store_dwordx4 v[168:169], v[150:153], off nt
	v_or_b32_e32 v137, 2, v147
	v_lshlrev_b32_e32 v128, 8, v137
	v_and_b32_e32 v134, 0x7fe00, v128
	v_lshl_add_u64 v[154:155], v[142:143], 0, v[134:135]
	global_load_dwordx3 v[158:160], v[154:155], off offset:256
	global_load_dwordx4 v[128:131], v[154:155], off offset:268
	global_load_dword v145, v[154:155], off offset:284
	global_load_dwordx4 v[150:153], v[154:155], off offset:16
	ds_bpermute_b32 v144, v149, v122
	global_load_dwordx4 v[154:157], v[154:155], off
	ds_bpermute_b32 v134, v149, v126
	v_mov_b32_e32 v170, v118
	v_mad_i64_i32 v[172:173], s[24:25], v137, s15, 0
	s_waitcnt lgkmcnt(1)
	v_mul_f32_e32 v169, v148, v144
	ds_bpermute_b32 v144, v149, v123
	ds_bpermute_b32 v137, v149, v127
	v_mov_b32_e32 v168, v126
	s_waitcnt lgkmcnt(2)
	v_mul_f32_e32 v166, v148, v134
	v_mov_b32_e32 v167, v122
	v_or_b32_e32 v134, 3, v147
	v_lshl_add_u64 v[178:179], v[172:173], 1, v[138:139]
	v_lshl_add_u64 v[172:173], v[172:173], 2, v[140:141]
	s_waitcnt vmcnt(4)
	v_mov_b32_e32 v161, v160
	s_waitcnt vmcnt(1)
	v_mov_b32_e32 v163, v152
	v_mov_b32_e32 v162, v151
	ds_bpermute_b32 v151, v149, v118
	ds_bpermute_b32 v152, v149, v114
	s_waitcnt vmcnt(0)
	v_mov_b32_e32 v165, v156
	v_mov_b32_e32 v164, v155
	v_mov_b32_e32 v155, v157
	s_waitcnt lgkmcnt(1)
	v_mul_f32_e32 v156, v148, v151
	s_waitcnt lgkmcnt(0)
	v_mul_f32_e32 v171, v148, v152
	v_mov_b32_e32 v151, v153
	v_mov_b32_e32 v157, v114
	v_pk_mul_f32 v[150:151], v[170:171], v[150:151]
	ds_bpermute_b32 v152, v149, v115
	v_pk_fma_f32 v[156:157], v[162:163], v[156:157], v[150:151]
	ds_bpermute_b32 v151, v149, v119
	v_pk_mul_f32 v[154:155], v[168:169], v[154:155]
	v_mov_b32_e32 v160, v159
	v_pk_fma_f32 v[154:155], v[164:165], v[166:167], v[154:155]
	v_mul_f32_e32 v153, v148, v144
	s_waitcnt lgkmcnt(1)
	v_mul_f32_e32 v167, v148, v152
	v_mov_b32_e32 v152, v127
	v_mov_b32_e32 v159, v128
	v_mov_b32_e32 v166, v119
	v_mov_b32_e32 v144, v129
	v_cvt_pk_bf16_f32 v164, v154, v155
	v_cvt_pk_bf16_f32 v165, v156, v157
	v_mul_f32_e32 v150, v148, v137
	s_waitcnt lgkmcnt(0)
	v_mul_f32_e32 v162, v148, v151
	v_mad_i64_i32 v[168:169], s[24:25], v134, s15, 0
	v_mov_b32_e32 v151, v123
	v_pk_mul_f32 v[152:153], v[152:153], v[158:159]
	v_mov_b32_e32 v163, v115
	v_pk_mul_f32 v[144:145], v[166:167], v[144:145]
	v_lshl_add_u64 v[170:171], v[168:169], 1, v[138:139]
	v_lshl_add_u64 v[168:169], v[168:169], 2, v[140:141]
	v_pk_fma_f32 v[150:151], v[160:161], v[150:151], v[152:153]
	v_pk_fma_f32 v[152:153], v[130:131], v[162:163], v[144:145]
	v_cvt_pk_bf16_f32 v128, v150, v151
	global_store_dwordx2 v[178:179], v[164:165], off nt
	global_store_dwordx4 v[172:173], v[154:157], off nt
	v_cvt_pk_bf16_f32 v129, v152, v153
	global_store_dwordx2 v[170:171], v[128:129], off nt
	global_store_dwordx4 v[168:169], v[150:153], off nt
	v_add_u32_e32 v137, 16, v147
	v_lshlrev_b32_e32 v128, 8, v137
	v_and_b32_e32 v134, 0x7fc00, v128
	v_lshl_add_u64 v[154:155], v[142:143], 0, v[134:135]
	global_load_dwordx3 v[158:160], v[154:155], off offset:256
	global_load_dwordx4 v[128:131], v[154:155], off offset:268
	global_load_dword v145, v[154:155], off offset:284
	global_load_dwordx4 v[150:153], v[154:155], off offset:16
	ds_bpermute_b32 v144, v149, v104
	global_load_dwordx4 v[154:157], v[154:155], off
	ds_bpermute_b32 v134, v149, v108
	v_mov_b32_e32 v170, v100
	v_mad_i64_i32 v[172:173], s[24:25], v137, s15, 0
	s_waitcnt lgkmcnt(1)
	v_mul_f32_e32 v169, v148, v144
	ds_bpermute_b32 v144, v149, v105
	ds_bpermute_b32 v137, v149, v109
	v_mov_b32_e32 v168, v108
	s_waitcnt lgkmcnt(2)
	v_mul_f32_e32 v166, v148, v134
	v_mov_b32_e32 v167, v104
	v_add_u32_e32 v134, 17, v147
	v_lshl_add_u64 v[178:179], v[172:173], 1, v[138:139]
	v_lshl_add_u64 v[172:173], v[172:173], 2, v[140:141]
	s_waitcnt vmcnt(4)
	v_mov_b32_e32 v161, v160
	s_waitcnt vmcnt(1)
	v_mov_b32_e32 v163, v152
	v_mov_b32_e32 v162, v151
	ds_bpermute_b32 v151, v149, v100
	ds_bpermute_b32 v152, v149, v96
	s_waitcnt vmcnt(0)
	v_mov_b32_e32 v165, v156
	v_mov_b32_e32 v164, v155
	v_mov_b32_e32 v155, v157
	s_waitcnt lgkmcnt(1)
	v_mul_f32_e32 v156, v148, v151
	s_waitcnt lgkmcnt(0)
	v_mul_f32_e32 v171, v148, v152
	v_mov_b32_e32 v151, v153
	v_mov_b32_e32 v157, v96
	v_pk_mul_f32 v[150:151], v[170:171], v[150:151]
	ds_bpermute_b32 v152, v149, v97
	v_pk_fma_f32 v[156:157], v[162:163], v[156:157], v[150:151]
	ds_bpermute_b32 v151, v149, v101
	v_pk_mul_f32 v[154:155], v[168:169], v[154:155]
	v_mov_b32_e32 v160, v159
	v_pk_fma_f32 v[154:155], v[164:165], v[166:167], v[154:155]
	v_mul_f32_e32 v153, v148, v144
	s_waitcnt lgkmcnt(1)
	v_mul_f32_e32 v167, v148, v152
	v_mov_b32_e32 v152, v109
	v_mov_b32_e32 v159, v128
	v_mov_b32_e32 v166, v101
	v_mov_b32_e32 v144, v129
	v_cvt_pk_bf16_f32 v164, v154, v155
	v_cvt_pk_bf16_f32 v165, v156, v157
	v_mul_f32_e32 v150, v148, v137
	s_waitcnt lgkmcnt(0)
	v_mul_f32_e32 v162, v148, v151
	v_mad_i64_i32 v[168:169], s[24:25], v134, s15, 0
	v_mov_b32_e32 v151, v105
	v_pk_mul_f32 v[152:153], v[152:153], v[158:159]
	v_mov_b32_e32 v163, v97
	v_pk_mul_f32 v[144:145], v[166:167], v[144:145]
	v_lshl_add_u64 v[170:171], v[168:169], 1, v[138:139]
	v_lshl_add_u64 v[168:169], v[168:169], 2, v[140:141]
	v_pk_fma_f32 v[150:151], v[160:161], v[150:151], v[152:153]
	v_pk_fma_f32 v[152:153], v[130:131], v[162:163], v[144:145]
	v_cvt_pk_bf16_f32 v128, v150, v151
	global_store_dwordx2 v[178:179], v[164:165], off nt
	global_store_dwordx4 v[172:173], v[154:157], off nt
	v_cvt_pk_bf16_f32 v129, v152, v153
	global_store_dwordx2 v[170:171], v[128:129], off nt
	global_store_dwordx4 v[168:169], v[150:153], off nt
	v_add_u32_e32 v137, 18, v147
	v_lshlrev_b32_e32 v128, 8, v137
	v_and_b32_e32 v134, 0x7fe00, v128
	v_lshl_add_u64 v[154:155], v[142:143], 0, v[134:135]
	global_load_dwordx3 v[158:160], v[154:155], off offset:256
	global_load_dwordx4 v[128:131], v[154:155], off offset:268
	global_load_dword v145, v[154:155], off offset:284
	global_load_dwordx4 v[150:153], v[154:155], off offset:16
	ds_bpermute_b32 v144, v149, v106
	global_load_dwordx4 v[154:157], v[154:155], off
	ds_bpermute_b32 v134, v149, v110
	v_mov_b32_e32 v170, v102
	v_mad_i64_i32 v[172:173], s[24:25], v137, s15, 0
	s_waitcnt lgkmcnt(1)
	v_mul_f32_e32 v169, v148, v144
	ds_bpermute_b32 v144, v149, v107
	ds_bpermute_b32 v137, v149, v111
	v_mov_b32_e32 v168, v110
	s_waitcnt lgkmcnt(2)
	v_mul_f32_e32 v166, v148, v134
	v_mov_b32_e32 v167, v106
	v_add_u32_e32 v134, 19, v147
	v_lshl_add_u64 v[178:179], v[172:173], 1, v[138:139]
	v_lshl_add_u64 v[172:173], v[172:173], 2, v[140:141]
	s_waitcnt vmcnt(4)
	v_mov_b32_e32 v161, v160
	s_waitcnt vmcnt(1)
	v_mov_b32_e32 v163, v152
	v_mov_b32_e32 v162, v151
	ds_bpermute_b32 v151, v149, v102
	ds_bpermute_b32 v152, v149, v98
	s_waitcnt vmcnt(0)
	v_mov_b32_e32 v165, v156
	v_mov_b32_e32 v164, v155
	v_mov_b32_e32 v155, v157
	s_waitcnt lgkmcnt(1)
	v_mul_f32_e32 v156, v148, v151
	s_waitcnt lgkmcnt(0)
	v_mul_f32_e32 v171, v148, v152
	v_mov_b32_e32 v151, v153
	v_mov_b32_e32 v157, v98
	v_pk_mul_f32 v[150:151], v[170:171], v[150:151]
	ds_bpermute_b32 v152, v149, v99
	v_pk_fma_f32 v[156:157], v[162:163], v[156:157], v[150:151]
	ds_bpermute_b32 v151, v149, v103
	v_pk_mul_f32 v[154:155], v[168:169], v[154:155]
	v_mov_b32_e32 v160, v159
	v_pk_fma_f32 v[154:155], v[164:165], v[166:167], v[154:155]
	v_mul_f32_e32 v153, v148, v144
	s_waitcnt lgkmcnt(1)
	v_mul_f32_e32 v167, v148, v152
	v_mov_b32_e32 v152, v111
	v_mov_b32_e32 v159, v128
	v_mov_b32_e32 v166, v103
	v_mov_b32_e32 v144, v129
	v_cvt_pk_bf16_f32 v164, v154, v155
	v_cvt_pk_bf16_f32 v165, v156, v157
	v_mul_f32_e32 v150, v148, v137
	s_waitcnt lgkmcnt(0)
	v_mul_f32_e32 v162, v148, v151
	v_mad_i64_i32 v[168:169], s[24:25], v134, s15, 0
	v_mov_b32_e32 v151, v107
	v_pk_mul_f32 v[152:153], v[152:153], v[158:159]
	v_mov_b32_e32 v163, v99
	v_pk_mul_f32 v[144:145], v[166:167], v[144:145]
	v_lshl_add_u64 v[170:171], v[168:169], 1, v[138:139]
	v_lshl_add_u64 v[168:169], v[168:169], 2, v[140:141]
	v_pk_fma_f32 v[150:151], v[160:161], v[150:151], v[152:153]
	v_pk_fma_f32 v[152:153], v[130:131], v[162:163], v[144:145]
	v_cvt_pk_bf16_f32 v128, v150, v151
	global_store_dwordx2 v[178:179], v[164:165], off nt
	global_store_dwordx4 v[172:173], v[154:157], off nt
	v_cvt_pk_bf16_f32 v129, v152, v153
	global_store_dwordx2 v[170:171], v[128:129], off nt
	global_store_dwordx4 v[168:169], v[150:153], off nt
	v_add_u32_e32 v137, 32, v147
	v_lshlrev_b32_e32 v128, 8, v137
	v_and_b32_e32 v134, 0x7fc00, v128
	v_lshl_add_u64 v[154:155], v[142:143], 0, v[134:135]
	global_load_dwordx3 v[158:160], v[154:155], off offset:256
	global_load_dwordx4 v[128:131], v[154:155], off offset:268
	global_load_dword v145, v[154:155], off offset:284
	global_load_dwordx4 v[150:153], v[154:155], off offset:16
	ds_bpermute_b32 v144, v149, v88
	global_load_dwordx4 v[154:157], v[154:155], off
	ds_bpermute_b32 v134, v149, v92
	v_mov_b32_e32 v170, v84
	v_mad_i64_i32 v[172:173], s[24:25], v137, s15, 0
	s_waitcnt lgkmcnt(1)
	v_mul_f32_e32 v169, v148, v144
	ds_bpermute_b32 v144, v149, v89
	ds_bpermute_b32 v137, v149, v93
	v_mov_b32_e32 v168, v92
	s_waitcnt lgkmcnt(2)
	v_mul_f32_e32 v166, v148, v134
	v_mov_b32_e32 v167, v88
	v_add_u32_e32 v134, 33, v147
	v_lshl_add_u64 v[178:179], v[172:173], 1, v[138:139]
	v_lshl_add_u64 v[172:173], v[172:173], 2, v[140:141]
	s_waitcnt vmcnt(4)
	v_mov_b32_e32 v161, v160
	s_waitcnt vmcnt(1)
	v_mov_b32_e32 v163, v152
	v_mov_b32_e32 v162, v151
	ds_bpermute_b32 v151, v149, v84
	ds_bpermute_b32 v152, v149, v80
	s_waitcnt vmcnt(0)
	v_mov_b32_e32 v165, v156
	v_mov_b32_e32 v164, v155
	v_mov_b32_e32 v155, v157
	s_waitcnt lgkmcnt(1)
	v_mul_f32_e32 v156, v148, v151
	s_waitcnt lgkmcnt(0)
	v_mul_f32_e32 v171, v148, v152
	v_mov_b32_e32 v151, v153
	v_mov_b32_e32 v157, v80
	v_pk_mul_f32 v[150:151], v[170:171], v[150:151]
	ds_bpermute_b32 v152, v149, v81
	v_pk_fma_f32 v[156:157], v[162:163], v[156:157], v[150:151]
	ds_bpermute_b32 v151, v149, v85
	v_pk_mul_f32 v[154:155], v[168:169], v[154:155]
	v_mov_b32_e32 v160, v159
	v_pk_fma_f32 v[154:155], v[164:165], v[166:167], v[154:155]
	v_mul_f32_e32 v153, v148, v144
	s_waitcnt lgkmcnt(1)
	v_mul_f32_e32 v167, v148, v152
	v_mov_b32_e32 v152, v93
	v_mov_b32_e32 v159, v128
	v_mov_b32_e32 v166, v85
	v_mov_b32_e32 v144, v129
	v_cvt_pk_bf16_f32 v164, v154, v155
	v_cvt_pk_bf16_f32 v165, v156, v157
	v_mul_f32_e32 v150, v148, v137
	s_waitcnt lgkmcnt(0)
	v_mul_f32_e32 v162, v148, v151
	v_mad_i64_i32 v[168:169], s[24:25], v134, s15, 0
	v_mov_b32_e32 v151, v89
	v_pk_mul_f32 v[152:153], v[152:153], v[158:159]
	v_mov_b32_e32 v163, v81
	v_pk_mul_f32 v[144:145], v[166:167], v[144:145]
	v_lshl_add_u64 v[170:171], v[168:169], 1, v[138:139]
	v_lshl_add_u64 v[168:169], v[168:169], 2, v[140:141]
	v_pk_fma_f32 v[150:151], v[160:161], v[150:151], v[152:153]
	v_pk_fma_f32 v[152:153], v[130:131], v[162:163], v[144:145]
	v_cvt_pk_bf16_f32 v128, v150, v151
	global_store_dwordx2 v[178:179], v[164:165], off nt
	global_store_dwordx4 v[172:173], v[154:157], off nt
	v_cvt_pk_bf16_f32 v129, v152, v153
	global_store_dwordx2 v[170:171], v[128:129], off nt
	global_store_dwordx4 v[168:169], v[150:153], off nt
	v_add_u32_e32 v137, 34, v147
	v_lshlrev_b32_e32 v128, 8, v137
	v_and_b32_e32 v134, 0x7fe00, v128
	v_lshl_add_u64 v[154:155], v[142:143], 0, v[134:135]
	global_load_dwordx3 v[158:160], v[154:155], off offset:256
	global_load_dwordx4 v[128:131], v[154:155], off offset:268
	global_load_dword v145, v[154:155], off offset:284
	global_load_dwordx4 v[150:153], v[154:155], off offset:16
	ds_bpermute_b32 v144, v149, v90
	global_load_dwordx4 v[154:157], v[154:155], off
	ds_bpermute_b32 v134, v149, v94
	v_mov_b32_e32 v170, v86
	v_mad_i64_i32 v[172:173], s[24:25], v137, s15, 0
	s_waitcnt lgkmcnt(1)
	v_mul_f32_e32 v169, v148, v144
	ds_bpermute_b32 v144, v149, v91
	ds_bpermute_b32 v137, v149, v95
	v_mov_b32_e32 v168, v94
	s_waitcnt lgkmcnt(2)
	v_mul_f32_e32 v166, v148, v134
	v_mov_b32_e32 v167, v90
	v_add_u32_e32 v134, 35, v147
	v_lshl_add_u64 v[178:179], v[172:173], 1, v[138:139]
	v_lshl_add_u64 v[172:173], v[172:173], 2, v[140:141]
	s_waitcnt vmcnt(4)
	v_mov_b32_e32 v161, v160
	s_waitcnt vmcnt(1)
	v_mov_b32_e32 v163, v152
	v_mov_b32_e32 v162, v151
	ds_bpermute_b32 v151, v149, v86
	ds_bpermute_b32 v152, v149, v82
	s_waitcnt vmcnt(0)
	v_mov_b32_e32 v165, v156
	v_mov_b32_e32 v164, v155
	v_mov_b32_e32 v155, v157
	s_waitcnt lgkmcnt(1)
	v_mul_f32_e32 v156, v148, v151
	s_waitcnt lgkmcnt(0)
	v_mul_f32_e32 v171, v148, v152
	v_mov_b32_e32 v151, v153
	v_mov_b32_e32 v157, v82
	v_pk_mul_f32 v[150:151], v[170:171], v[150:151]
	ds_bpermute_b32 v152, v149, v83
	v_pk_fma_f32 v[156:157], v[162:163], v[156:157], v[150:151]
	ds_bpermute_b32 v151, v149, v87
	v_pk_mul_f32 v[154:155], v[168:169], v[154:155]
	v_mov_b32_e32 v160, v159
	v_pk_fma_f32 v[154:155], v[164:165], v[166:167], v[154:155]
	v_mul_f32_e32 v153, v148, v144
	s_waitcnt lgkmcnt(1)
	v_mul_f32_e32 v167, v148, v152
	v_mov_b32_e32 v152, v95
	v_mov_b32_e32 v159, v128
	v_mov_b32_e32 v166, v87
	v_mov_b32_e32 v144, v129
	v_cvt_pk_bf16_f32 v164, v154, v155
	v_cvt_pk_bf16_f32 v165, v156, v157
	v_mul_f32_e32 v150, v148, v137
	s_waitcnt lgkmcnt(0)
	v_mul_f32_e32 v162, v148, v151
	v_mad_i64_i32 v[168:169], s[24:25], v134, s15, 0
	v_mov_b32_e32 v151, v91
	v_pk_mul_f32 v[152:153], v[152:153], v[158:159]
	v_mov_b32_e32 v163, v83
	v_pk_mul_f32 v[144:145], v[166:167], v[144:145]
	v_lshl_add_u64 v[170:171], v[168:169], 1, v[138:139]
	v_lshl_add_u64 v[168:169], v[168:169], 2, v[140:141]
	v_pk_fma_f32 v[150:151], v[160:161], v[150:151], v[152:153]
	v_pk_fma_f32 v[152:153], v[130:131], v[162:163], v[144:145]
	v_cvt_pk_bf16_f32 v128, v150, v151
	global_store_dwordx2 v[178:179], v[164:165], off nt
	global_store_dwordx4 v[172:173], v[154:157], off nt
	v_cvt_pk_bf16_f32 v129, v152, v153
	global_store_dwordx2 v[170:171], v[128:129], off nt
	global_store_dwordx4 v[168:169], v[150:153], off nt
	v_add_u32_e32 v137, 48, v147
	v_lshlrev_b32_e32 v128, 8, v137
	v_and_b32_e32 v134, 0x7fc00, v128
	v_lshl_add_u64 v[154:155], v[142:143], 0, v[134:135]
	global_load_dwordx3 v[158:160], v[154:155], off offset:256
	global_load_dwordx4 v[128:131], v[154:155], off offset:268
	global_load_dword v145, v[154:155], off offset:284
	global_load_dwordx4 v[150:153], v[154:155], off offset:16
	ds_bpermute_b32 v144, v149, v72
	global_load_dwordx4 v[154:157], v[154:155], off
	ds_bpermute_b32 v134, v149, v76
	v_mov_b32_e32 v170, v68
	v_mad_i64_i32 v[172:173], s[24:25], v137, s15, 0
	s_waitcnt lgkmcnt(1)
	v_mul_f32_e32 v169, v148, v144
	ds_bpermute_b32 v144, v149, v73
	ds_bpermute_b32 v137, v149, v77
	v_mov_b32_e32 v168, v76
	s_waitcnt lgkmcnt(2)
	v_mul_f32_e32 v166, v148, v134
	v_mov_b32_e32 v167, v72
	v_add_u32_e32 v134, 49, v147
	v_lshl_add_u64 v[178:179], v[172:173], 1, v[138:139]
	v_lshl_add_u64 v[172:173], v[172:173], 2, v[140:141]
	s_waitcnt vmcnt(4)
	v_mov_b32_e32 v161, v160
	s_waitcnt vmcnt(1)
	v_mov_b32_e32 v163, v152
	v_mov_b32_e32 v162, v151
	ds_bpermute_b32 v151, v149, v68
	ds_bpermute_b32 v152, v149, v64
	s_waitcnt vmcnt(0)
	v_mov_b32_e32 v165, v156
	v_mov_b32_e32 v164, v155
	v_mov_b32_e32 v155, v157
	s_waitcnt lgkmcnt(1)
	v_mul_f32_e32 v156, v148, v151
	s_waitcnt lgkmcnt(0)
	v_mul_f32_e32 v171, v148, v152
	v_mov_b32_e32 v151, v153
	v_mov_b32_e32 v157, v64
	v_pk_mul_f32 v[150:151], v[170:171], v[150:151]
	ds_bpermute_b32 v152, v149, v65
	v_pk_fma_f32 v[156:157], v[162:163], v[156:157], v[150:151]
	ds_bpermute_b32 v151, v149, v69
	v_pk_mul_f32 v[154:155], v[168:169], v[154:155]
	v_mov_b32_e32 v160, v159
	v_pk_fma_f32 v[154:155], v[164:165], v[166:167], v[154:155]
	v_mul_f32_e32 v153, v148, v144
	s_waitcnt lgkmcnt(1)
	v_mul_f32_e32 v167, v148, v152
	v_mov_b32_e32 v152, v77
	v_mov_b32_e32 v159, v128
	v_mov_b32_e32 v166, v69
	v_mov_b32_e32 v144, v129
	v_cvt_pk_bf16_f32 v164, v154, v155
	v_cvt_pk_bf16_f32 v165, v156, v157
	v_mul_f32_e32 v150, v148, v137
	s_waitcnt lgkmcnt(0)
	v_mul_f32_e32 v162, v148, v151
	v_mad_i64_i32 v[168:169], s[24:25], v134, s15, 0
	v_mov_b32_e32 v151, v73
	v_pk_mul_f32 v[152:153], v[152:153], v[158:159]
	v_mov_b32_e32 v163, v65
	v_pk_mul_f32 v[144:145], v[166:167], v[144:145]
	v_lshl_add_u64 v[170:171], v[168:169], 1, v[138:139]
	v_lshl_add_u64 v[168:169], v[168:169], 2, v[140:141]
	v_pk_fma_f32 v[150:151], v[160:161], v[150:151], v[152:153]
	v_pk_fma_f32 v[152:153], v[130:131], v[162:163], v[144:145]
	v_cvt_pk_bf16_f32 v128, v150, v151
	global_store_dwordx2 v[178:179], v[164:165], off nt
	global_store_dwordx4 v[172:173], v[154:157], off nt
	v_cvt_pk_bf16_f32 v129, v152, v153
	global_store_dwordx2 v[170:171], v[128:129], off nt
	global_store_dwordx4 v[168:169], v[150:153], off nt
	v_add_u32_e32 v137, 50, v147
	v_lshlrev_b32_e32 v128, 8, v137
	v_and_b32_e32 v134, 0x7fe00, v128
	v_lshl_add_u64 v[154:155], v[142:143], 0, v[134:135]
	global_load_dwordx3 v[158:160], v[154:155], off offset:256
	global_load_dwordx4 v[128:131], v[154:155], off offset:268
	global_load_dword v145, v[154:155], off offset:284
	global_load_dwordx4 v[150:153], v[154:155], off offset:16
	ds_bpermute_b32 v144, v149, v74
	global_load_dwordx4 v[154:157], v[154:155], off
	ds_bpermute_b32 v134, v149, v78
	v_mov_b32_e32 v170, v70
	v_mad_i64_i32 v[172:173], s[24:25], v137, s15, 0
	s_waitcnt lgkmcnt(1)
	v_mul_f32_e32 v169, v148, v144
	ds_bpermute_b32 v144, v149, v75
	ds_bpermute_b32 v137, v149, v79
	v_mov_b32_e32 v168, v78
	s_waitcnt lgkmcnt(2)
	v_mul_f32_e32 v166, v148, v134
	v_mov_b32_e32 v167, v74
	v_add_u32_e32 v134, 51, v147
	v_lshl_add_u64 v[178:179], v[172:173], 1, v[138:139]
	v_lshl_add_u64 v[172:173], v[172:173], 2, v[140:141]
	s_waitcnt vmcnt(4)
	v_mov_b32_e32 v161, v160
	s_waitcnt vmcnt(1)
	v_mov_b32_e32 v163, v152
	v_mov_b32_e32 v162, v151
	ds_bpermute_b32 v151, v149, v70
	ds_bpermute_b32 v152, v149, v66
	s_waitcnt vmcnt(0)
	v_mov_b32_e32 v165, v156
	v_mov_b32_e32 v164, v155
	v_mov_b32_e32 v155, v157
	s_waitcnt lgkmcnt(1)
	v_mul_f32_e32 v156, v148, v151
	s_waitcnt lgkmcnt(0)
	v_mul_f32_e32 v171, v148, v152
	v_mov_b32_e32 v151, v153
	v_mov_b32_e32 v157, v66
	v_pk_mul_f32 v[150:151], v[170:171], v[150:151]
	ds_bpermute_b32 v152, v149, v67
	v_pk_fma_f32 v[156:157], v[162:163], v[156:157], v[150:151]
	ds_bpermute_b32 v151, v149, v71
	v_pk_mul_f32 v[154:155], v[168:169], v[154:155]
	v_mov_b32_e32 v160, v159
	v_pk_fma_f32 v[154:155], v[164:165], v[166:167], v[154:155]
	v_mul_f32_e32 v153, v148, v144
	s_waitcnt lgkmcnt(1)
	v_mul_f32_e32 v167, v148, v152
	v_mov_b32_e32 v152, v79
	v_mov_b32_e32 v159, v128
	v_mov_b32_e32 v166, v71
	v_mov_b32_e32 v144, v129
	v_cvt_pk_bf16_f32 v164, v154, v155
	v_cvt_pk_bf16_f32 v165, v156, v157
	v_mul_f32_e32 v150, v148, v137
	s_waitcnt lgkmcnt(0)
	v_mul_f32_e32 v162, v148, v151
	v_mad_i64_i32 v[168:169], s[24:25], v134, s15, 0
	v_mov_b32_e32 v151, v75
	v_pk_mul_f32 v[152:153], v[152:153], v[158:159]
	v_mov_b32_e32 v163, v67
	v_pk_mul_f32 v[144:145], v[166:167], v[144:145]
	v_lshl_add_u64 v[170:171], v[168:169], 1, v[138:139]
	v_lshl_add_u64 v[168:169], v[168:169], 2, v[140:141]
	v_pk_fma_f32 v[150:151], v[160:161], v[150:151], v[152:153]
	v_pk_fma_f32 v[152:153], v[130:131], v[162:163], v[144:145]
	v_cvt_pk_bf16_f32 v128, v150, v151
	global_store_dwordx2 v[178:179], v[164:165], off nt
	global_store_dwordx4 v[172:173], v[154:157], off nt
	v_cvt_pk_bf16_f32 v129, v152, v153
	global_store_dwordx2 v[170:171], v[128:129], off nt
	global_store_dwordx4 v[168:169], v[150:153], off nt
	v_add_u32_e32 v137, 64, v147
	v_lshlrev_b32_e32 v128, 8, v137
	v_and_b32_e32 v134, 0x7fc00, v128
	v_lshl_add_u64 v[154:155], v[142:143], 0, v[134:135]
	global_load_dwordx3 v[158:160], v[154:155], off offset:256
	global_load_dwordx4 v[128:131], v[154:155], off offset:268
	global_load_dword v145, v[154:155], off offset:284
	global_load_dwordx4 v[150:153], v[154:155], off offset:16
	ds_bpermute_b32 v144, v149, v56
	global_load_dwordx4 v[154:157], v[154:155], off
	ds_bpermute_b32 v134, v149, v60
	v_mov_b32_e32 v170, v52
	v_mad_i64_i32 v[172:173], s[24:25], v137, s15, 0
	s_waitcnt lgkmcnt(1)
	v_mul_f32_e32 v169, v148, v144
	ds_bpermute_b32 v144, v149, v57
	ds_bpermute_b32 v137, v149, v61
	v_mov_b32_e32 v168, v60
	s_waitcnt lgkmcnt(2)
	v_mul_f32_e32 v166, v148, v134
	v_mov_b32_e32 v167, v56
	v_add_u32_e32 v134, 0x41, v147
	v_lshl_add_u64 v[178:179], v[172:173], 1, v[138:139]
	v_lshl_add_u64 v[172:173], v[172:173], 2, v[140:141]
	s_waitcnt vmcnt(4)
	v_mov_b32_e32 v161, v160
	s_waitcnt vmcnt(1)
	v_mov_b32_e32 v163, v152
	v_mov_b32_e32 v162, v151
	ds_bpermute_b32 v151, v149, v52
	ds_bpermute_b32 v152, v149, v48
	s_waitcnt vmcnt(0)
	v_mov_b32_e32 v165, v156
	v_mov_b32_e32 v164, v155
	v_mov_b32_e32 v155, v157
	s_waitcnt lgkmcnt(1)
	v_mul_f32_e32 v156, v148, v151
	s_waitcnt lgkmcnt(0)
	v_mul_f32_e32 v171, v148, v152
	v_mov_b32_e32 v151, v153
	v_mov_b32_e32 v157, v48
	v_pk_mul_f32 v[150:151], v[170:171], v[150:151]
	ds_bpermute_b32 v152, v149, v49
	v_pk_fma_f32 v[156:157], v[162:163], v[156:157], v[150:151]
	ds_bpermute_b32 v151, v149, v53
	v_pk_mul_f32 v[154:155], v[168:169], v[154:155]
	v_mov_b32_e32 v160, v159
	v_pk_fma_f32 v[154:155], v[164:165], v[166:167], v[154:155]
	v_mul_f32_e32 v153, v148, v144
	s_waitcnt lgkmcnt(1)
	v_mul_f32_e32 v167, v148, v152
	v_mov_b32_e32 v152, v61
	v_mov_b32_e32 v159, v128
	v_mov_b32_e32 v166, v53
	v_mov_b32_e32 v144, v129
	v_cvt_pk_bf16_f32 v164, v154, v155
	v_cvt_pk_bf16_f32 v165, v156, v157
	v_mul_f32_e32 v150, v148, v137
	s_waitcnt lgkmcnt(0)
	v_mul_f32_e32 v162, v148, v151
	v_mad_i64_i32 v[168:169], s[24:25], v134, s15, 0
	v_mov_b32_e32 v151, v57
	v_pk_mul_f32 v[152:153], v[152:153], v[158:159]
	v_mov_b32_e32 v163, v49
	v_pk_mul_f32 v[144:145], v[166:167], v[144:145]
	v_lshl_add_u64 v[170:171], v[168:169], 1, v[138:139]
	v_lshl_add_u64 v[168:169], v[168:169], 2, v[140:141]
	v_pk_fma_f32 v[150:151], v[160:161], v[150:151], v[152:153]
	v_pk_fma_f32 v[152:153], v[130:131], v[162:163], v[144:145]
	v_cvt_pk_bf16_f32 v128, v150, v151
	global_store_dwordx2 v[178:179], v[164:165], off nt
	global_store_dwordx4 v[172:173], v[154:157], off nt
	v_cvt_pk_bf16_f32 v129, v152, v153
	global_store_dwordx2 v[170:171], v[128:129], off nt
	global_store_dwordx4 v[168:169], v[150:153], off nt
	v_add_u32_e32 v137, 0x42, v147
	v_lshlrev_b32_e32 v128, 8, v137
	v_and_b32_e32 v134, 0x7fe00, v128
	v_lshl_add_u64 v[154:155], v[142:143], 0, v[134:135]
	global_load_dwordx3 v[158:160], v[154:155], off offset:256
	global_load_dwordx4 v[128:131], v[154:155], off offset:268
	global_load_dword v145, v[154:155], off offset:284
	global_load_dwordx4 v[150:153], v[154:155], off offset:16
	ds_bpermute_b32 v144, v149, v58
	global_load_dwordx4 v[154:157], v[154:155], off
	ds_bpermute_b32 v134, v149, v62
	v_mov_b32_e32 v170, v54
	v_mad_i64_i32 v[172:173], s[24:25], v137, s15, 0
	s_waitcnt lgkmcnt(1)
	v_mul_f32_e32 v169, v148, v144
	ds_bpermute_b32 v144, v149, v59
	ds_bpermute_b32 v137, v149, v63
	v_mov_b32_e32 v168, v62
	s_waitcnt lgkmcnt(2)
	v_mul_f32_e32 v166, v148, v134
	v_mov_b32_e32 v167, v58
	v_add_u32_e32 v134, 0x43, v147
	v_lshl_add_u64 v[178:179], v[172:173], 1, v[138:139]
	v_lshl_add_u64 v[172:173], v[172:173], 2, v[140:141]
	s_waitcnt vmcnt(4)
	v_mov_b32_e32 v161, v160
	s_waitcnt vmcnt(1)
	v_mov_b32_e32 v163, v152
	v_mov_b32_e32 v162, v151
	ds_bpermute_b32 v151, v149, v54
	ds_bpermute_b32 v152, v149, v50
	s_waitcnt vmcnt(0)
	v_mov_b32_e32 v165, v156
	v_mov_b32_e32 v164, v155
	v_mov_b32_e32 v155, v157
	s_waitcnt lgkmcnt(1)
	v_mul_f32_e32 v156, v148, v151
	s_waitcnt lgkmcnt(0)
	v_mul_f32_e32 v171, v148, v152
	v_mov_b32_e32 v151, v153
	v_mov_b32_e32 v157, v50
	v_pk_mul_f32 v[150:151], v[170:171], v[150:151]
	ds_bpermute_b32 v152, v149, v51
	v_pk_fma_f32 v[156:157], v[162:163], v[156:157], v[150:151]
	ds_bpermute_b32 v151, v149, v55
	v_pk_mul_f32 v[154:155], v[168:169], v[154:155]
	v_mov_b32_e32 v160, v159
	v_pk_fma_f32 v[154:155], v[164:165], v[166:167], v[154:155]
	v_mul_f32_e32 v153, v148, v144
	s_waitcnt lgkmcnt(1)
	v_mul_f32_e32 v167, v148, v152
	v_mov_b32_e32 v152, v63
	v_mov_b32_e32 v159, v128
	v_mov_b32_e32 v166, v55
	v_mov_b32_e32 v144, v129
	v_cvt_pk_bf16_f32 v164, v154, v155
	v_cvt_pk_bf16_f32 v165, v156, v157
	v_mul_f32_e32 v150, v148, v137
	s_waitcnt lgkmcnt(0)
	v_mul_f32_e32 v162, v148, v151
	v_mad_i64_i32 v[168:169], s[24:25], v134, s15, 0
	v_mov_b32_e32 v151, v59
	v_pk_mul_f32 v[152:153], v[152:153], v[158:159]
	v_mov_b32_e32 v163, v51
	v_pk_mul_f32 v[144:145], v[166:167], v[144:145]
	v_lshl_add_u64 v[170:171], v[168:169], 1, v[138:139]
	v_lshl_add_u64 v[168:169], v[168:169], 2, v[140:141]
	v_pk_fma_f32 v[150:151], v[160:161], v[150:151], v[152:153]
	v_pk_fma_f32 v[152:153], v[130:131], v[162:163], v[144:145]
	v_cvt_pk_bf16_f32 v128, v150, v151
	global_store_dwordx2 v[178:179], v[164:165], off nt
	global_store_dwordx4 v[172:173], v[154:157], off nt
	v_cvt_pk_bf16_f32 v129, v152, v153
	global_store_dwordx2 v[170:171], v[128:129], off nt
	global_store_dwordx4 v[168:169], v[150:153], off nt
	v_add_u32_e32 v137, 0x50, v147
	v_lshlrev_b32_e32 v128, 8, v137
	v_and_b32_e32 v134, 0x7fc00, v128
	v_lshl_add_u64 v[154:155], v[142:143], 0, v[134:135]
	global_load_dwordx3 v[158:160], v[154:155], off offset:256
	global_load_dwordx4 v[128:131], v[154:155], off offset:268
	global_load_dword v145, v[154:155], off offset:284
	global_load_dwordx4 v[150:153], v[154:155], off offset:16
	ds_bpermute_b32 v144, v149, v40
	global_load_dwordx4 v[154:157], v[154:155], off
	ds_bpermute_b32 v134, v149, v44
	v_mov_b32_e32 v170, v36
	v_mad_i64_i32 v[172:173], s[24:25], v137, s15, 0
	s_waitcnt lgkmcnt(1)
	v_mul_f32_e32 v169, v148, v144
	ds_bpermute_b32 v144, v149, v41
	ds_bpermute_b32 v137, v149, v45
	v_mov_b32_e32 v168, v44
	s_waitcnt lgkmcnt(2)
	v_mul_f32_e32 v166, v148, v134
	v_mov_b32_e32 v167, v40
	v_add_u32_e32 v134, 0x51, v147
	v_lshl_add_u64 v[178:179], v[172:173], 1, v[138:139]
	v_lshl_add_u64 v[172:173], v[172:173], 2, v[140:141]
	s_waitcnt vmcnt(4)
	v_mov_b32_e32 v161, v160
	s_waitcnt vmcnt(1)
	v_mov_b32_e32 v163, v152
	v_mov_b32_e32 v162, v151
	ds_bpermute_b32 v151, v149, v36
	ds_bpermute_b32 v152, v149, v32
	s_waitcnt vmcnt(0)
	v_mov_b32_e32 v165, v156
	v_mov_b32_e32 v164, v155
	v_mov_b32_e32 v155, v157
	s_waitcnt lgkmcnt(1)
	v_mul_f32_e32 v156, v148, v151
	s_waitcnt lgkmcnt(0)
	v_mul_f32_e32 v171, v148, v152
	v_mov_b32_e32 v151, v153
	v_mov_b32_e32 v157, v32
	v_pk_mul_f32 v[150:151], v[170:171], v[150:151]
	ds_bpermute_b32 v152, v149, v33
	v_pk_fma_f32 v[156:157], v[162:163], v[156:157], v[150:151]
	ds_bpermute_b32 v151, v149, v37
	v_pk_mul_f32 v[154:155], v[168:169], v[154:155]
	v_mov_b32_e32 v160, v159
	v_pk_fma_f32 v[154:155], v[164:165], v[166:167], v[154:155]
	v_mul_f32_e32 v153, v148, v144
	s_waitcnt lgkmcnt(1)
	v_mul_f32_e32 v167, v148, v152
	v_mov_b32_e32 v152, v45
	v_mov_b32_e32 v159, v128
	v_mov_b32_e32 v166, v37
	v_mov_b32_e32 v144, v129
	v_cvt_pk_bf16_f32 v164, v154, v155
	v_cvt_pk_bf16_f32 v165, v156, v157
	v_mul_f32_e32 v150, v148, v137
	s_waitcnt lgkmcnt(0)
	v_mul_f32_e32 v162, v148, v151
	v_mad_i64_i32 v[168:169], s[24:25], v134, s15, 0
	v_mov_b32_e32 v151, v41
	v_pk_mul_f32 v[152:153], v[152:153], v[158:159]
	v_mov_b32_e32 v163, v33
	v_pk_mul_f32 v[144:145], v[166:167], v[144:145]
	v_lshl_add_u64 v[170:171], v[168:169], 1, v[138:139]
	v_lshl_add_u64 v[168:169], v[168:169], 2, v[140:141]
	v_pk_fma_f32 v[150:151], v[160:161], v[150:151], v[152:153]
	v_pk_fma_f32 v[152:153], v[130:131], v[162:163], v[144:145]
	v_cvt_pk_bf16_f32 v128, v150, v151
	global_store_dwordx2 v[178:179], v[164:165], off nt
	global_store_dwordx4 v[172:173], v[154:157], off nt
	v_cvt_pk_bf16_f32 v129, v152, v153
	global_store_dwordx2 v[170:171], v[128:129], off nt
	global_store_dwordx4 v[168:169], v[150:153], off nt
	v_add_u32_e32 v137, 0x52, v147
	v_lshlrev_b32_e32 v128, 8, v137
	v_and_b32_e32 v134, 0x7fe00, v128
	v_lshl_add_u64 v[154:155], v[142:143], 0, v[134:135]
	global_load_dwordx3 v[158:160], v[154:155], off offset:256
	global_load_dwordx4 v[128:131], v[154:155], off offset:268
	global_load_dword v145, v[154:155], off offset:284
	global_load_dwordx4 v[150:153], v[154:155], off offset:16
	ds_bpermute_b32 v144, v149, v42
	global_load_dwordx4 v[154:157], v[154:155], off
	ds_bpermute_b32 v134, v149, v46
	v_mov_b32_e32 v170, v38
	v_mad_i64_i32 v[172:173], s[24:25], v137, s15, 0
	s_waitcnt lgkmcnt(1)
	v_mul_f32_e32 v169, v148, v144
	ds_bpermute_b32 v144, v149, v43
	ds_bpermute_b32 v137, v149, v47
	v_mov_b32_e32 v168, v46
	s_waitcnt lgkmcnt(2)
	v_mul_f32_e32 v166, v148, v134
	v_mov_b32_e32 v167, v42
	v_add_u32_e32 v134, 0x53, v147
	v_lshl_add_u64 v[178:179], v[172:173], 1, v[138:139]
	v_lshl_add_u64 v[172:173], v[172:173], 2, v[140:141]
	s_waitcnt vmcnt(4)
	v_mov_b32_e32 v161, v160
	s_waitcnt vmcnt(1)
	v_mov_b32_e32 v163, v152
	v_mov_b32_e32 v162, v151
	ds_bpermute_b32 v151, v149, v38
	ds_bpermute_b32 v152, v149, v34
	s_waitcnt vmcnt(0)
	v_mov_b32_e32 v165, v156
	v_mov_b32_e32 v164, v155
	v_mov_b32_e32 v155, v157
	s_waitcnt lgkmcnt(1)
	v_mul_f32_e32 v156, v148, v151
	s_waitcnt lgkmcnt(0)
	v_mul_f32_e32 v171, v148, v152
	v_mov_b32_e32 v151, v153
	v_mov_b32_e32 v157, v34
	v_pk_mul_f32 v[150:151], v[170:171], v[150:151]
	ds_bpermute_b32 v152, v149, v35
	v_pk_fma_f32 v[156:157], v[162:163], v[156:157], v[150:151]
	ds_bpermute_b32 v151, v149, v39
	v_pk_mul_f32 v[154:155], v[168:169], v[154:155]
	v_mov_b32_e32 v160, v159
	v_pk_fma_f32 v[154:155], v[164:165], v[166:167], v[154:155]
	v_mul_f32_e32 v153, v148, v144
	s_waitcnt lgkmcnt(1)
	v_mul_f32_e32 v167, v148, v152
	v_mov_b32_e32 v152, v47
	v_mov_b32_e32 v159, v128
	v_mov_b32_e32 v166, v39
	v_mov_b32_e32 v144, v129
	v_cvt_pk_bf16_f32 v164, v154, v155
	v_cvt_pk_bf16_f32 v165, v156, v157
	v_mul_f32_e32 v150, v148, v137
	s_waitcnt lgkmcnt(0)
	v_mul_f32_e32 v162, v148, v151
	v_mad_i64_i32 v[168:169], s[24:25], v134, s15, 0
	v_mov_b32_e32 v151, v43
	v_pk_mul_f32 v[152:153], v[152:153], v[158:159]
	v_mov_b32_e32 v163, v35
	v_pk_mul_f32 v[144:145], v[166:167], v[144:145]
	v_lshl_add_u64 v[170:171], v[168:169], 1, v[138:139]
	v_lshl_add_u64 v[168:169], v[168:169], 2, v[140:141]
	v_pk_fma_f32 v[150:151], v[160:161], v[150:151], v[152:153]
	v_pk_fma_f32 v[152:153], v[130:131], v[162:163], v[144:145]
	v_cvt_pk_bf16_f32 v128, v150, v151
	global_store_dwordx2 v[178:179], v[164:165], off nt
	global_store_dwordx4 v[172:173], v[154:157], off nt
	v_cvt_pk_bf16_f32 v129, v152, v153
	global_store_dwordx2 v[170:171], v[128:129], off nt
	global_store_dwordx4 v[168:169], v[150:153], off nt
	v_add_u32_e32 v137, 0x60, v147
	v_lshlrev_b32_e32 v128, 8, v137
	v_and_b32_e32 v134, 0x7fc00, v128
	v_lshl_add_u64 v[154:155], v[142:143], 0, v[134:135]
	global_load_dwordx3 v[158:160], v[154:155], off offset:256
	global_load_dwordx4 v[128:131], v[154:155], off offset:268
	global_load_dword v145, v[154:155], off offset:284
	global_load_dwordx4 v[150:153], v[154:155], off offset:16
	ds_bpermute_b32 v144, v149, v24
	global_load_dwordx4 v[154:157], v[154:155], off
	ds_bpermute_b32 v134, v149, v28
	v_mov_b32_e32 v170, v20
	v_mad_i64_i32 v[172:173], s[24:25], v137, s15, 0
	s_waitcnt lgkmcnt(1)
	v_mul_f32_e32 v169, v148, v144
	ds_bpermute_b32 v144, v149, v25
	ds_bpermute_b32 v137, v149, v29
	v_mov_b32_e32 v168, v28
	s_waitcnt lgkmcnt(2)
	v_mul_f32_e32 v166, v148, v134
	v_mov_b32_e32 v167, v24
	v_add_u32_e32 v134, 0x61, v147
	v_lshl_add_u64 v[178:179], v[172:173], 1, v[138:139]
	v_lshl_add_u64 v[172:173], v[172:173], 2, v[140:141]
	s_waitcnt vmcnt(4)
	v_mov_b32_e32 v161, v160
	s_waitcnt vmcnt(1)
	v_mov_b32_e32 v163, v152
	v_mov_b32_e32 v162, v151
	ds_bpermute_b32 v151, v149, v20
	ds_bpermute_b32 v152, v149, v16
	s_waitcnt vmcnt(0)
	v_mov_b32_e32 v165, v156
	v_mov_b32_e32 v164, v155
	v_mov_b32_e32 v155, v157
	s_waitcnt lgkmcnt(1)
	v_mul_f32_e32 v156, v148, v151
	s_waitcnt lgkmcnt(0)
	v_mul_f32_e32 v171, v148, v152
	v_mov_b32_e32 v151, v153
	v_mov_b32_e32 v157, v16
	v_pk_mul_f32 v[150:151], v[170:171], v[150:151]
	ds_bpermute_b32 v152, v149, v17
	v_pk_fma_f32 v[156:157], v[162:163], v[156:157], v[150:151]
	ds_bpermute_b32 v151, v149, v21
	v_pk_mul_f32 v[154:155], v[168:169], v[154:155]
	v_mov_b32_e32 v160, v159
	v_pk_fma_f32 v[154:155], v[164:165], v[166:167], v[154:155]
	v_mul_f32_e32 v153, v148, v144
	s_waitcnt lgkmcnt(1)
	v_mul_f32_e32 v167, v148, v152
	v_mov_b32_e32 v152, v29
	v_mov_b32_e32 v159, v128
	v_mov_b32_e32 v166, v21
	v_mov_b32_e32 v144, v129
	v_cvt_pk_bf16_f32 v164, v154, v155
	v_cvt_pk_bf16_f32 v165, v156, v157
	v_mul_f32_e32 v150, v148, v137
	s_waitcnt lgkmcnt(0)
	v_mul_f32_e32 v162, v148, v151
	v_mad_i64_i32 v[168:169], s[24:25], v134, s15, 0
	v_mov_b32_e32 v151, v25
	v_pk_mul_f32 v[152:153], v[152:153], v[158:159]
	v_mov_b32_e32 v163, v17
	v_pk_mul_f32 v[144:145], v[166:167], v[144:145]
	v_lshl_add_u64 v[170:171], v[168:169], 1, v[138:139]
	v_lshl_add_u64 v[168:169], v[168:169], 2, v[140:141]
	v_pk_fma_f32 v[150:151], v[160:161], v[150:151], v[152:153]
	v_pk_fma_f32 v[152:153], v[130:131], v[162:163], v[144:145]
	v_cvt_pk_bf16_f32 v128, v150, v151
	global_store_dwordx2 v[178:179], v[164:165], off nt
	global_store_dwordx4 v[172:173], v[154:157], off nt
	v_cvt_pk_bf16_f32 v129, v152, v153
	global_store_dwordx2 v[170:171], v[128:129], off nt
	global_store_dwordx4 v[168:169], v[150:153], off nt
	v_add_u32_e32 v137, 0x62, v147
	v_lshlrev_b32_e32 v128, 8, v137
	v_and_b32_e32 v134, 0x7fe00, v128
	v_lshl_add_u64 v[154:155], v[142:143], 0, v[134:135]
	global_load_dwordx3 v[158:160], v[154:155], off offset:256
	global_load_dwordx4 v[128:131], v[154:155], off offset:268
	global_load_dword v145, v[154:155], off offset:284
	global_load_dwordx4 v[150:153], v[154:155], off offset:16
	ds_bpermute_b32 v144, v149, v26
	global_load_dwordx4 v[154:157], v[154:155], off
	ds_bpermute_b32 v134, v149, v30
	v_mov_b32_e32 v170, v22
	v_mad_i64_i32 v[172:173], s[24:25], v137, s15, 0
	s_waitcnt lgkmcnt(1)
	v_mul_f32_e32 v169, v148, v144
	ds_bpermute_b32 v144, v149, v27
	ds_bpermute_b32 v137, v149, v31
	v_mov_b32_e32 v168, v30
	s_waitcnt lgkmcnt(2)
	v_mul_f32_e32 v166, v148, v134
	v_mov_b32_e32 v167, v26
	v_add_u32_e32 v134, 0x63, v147
	v_lshl_add_u64 v[178:179], v[172:173], 1, v[138:139]
	v_lshl_add_u64 v[172:173], v[172:173], 2, v[140:141]
	s_waitcnt vmcnt(4)
	v_mov_b32_e32 v161, v160
	s_waitcnt vmcnt(1)
	v_mov_b32_e32 v163, v152
	v_mov_b32_e32 v162, v151
	ds_bpermute_b32 v151, v149, v22
	ds_bpermute_b32 v152, v149, v18
	s_waitcnt vmcnt(0)
	v_mov_b32_e32 v165, v156
	v_mov_b32_e32 v164, v155
	v_mov_b32_e32 v155, v157
	s_waitcnt lgkmcnt(1)
	v_mul_f32_e32 v156, v148, v151
	s_waitcnt lgkmcnt(0)
	v_mul_f32_e32 v171, v148, v152
	v_mov_b32_e32 v151, v153
	v_mov_b32_e32 v157, v18
	v_pk_mul_f32 v[150:151], v[170:171], v[150:151]
	ds_bpermute_b32 v152, v149, v19
	v_pk_fma_f32 v[156:157], v[162:163], v[156:157], v[150:151]
	ds_bpermute_b32 v151, v149, v23
	v_pk_mul_f32 v[154:155], v[168:169], v[154:155]
	v_mov_b32_e32 v160, v159
	v_pk_fma_f32 v[154:155], v[164:165], v[166:167], v[154:155]
	v_mul_f32_e32 v153, v148, v144
	s_waitcnt lgkmcnt(1)
	v_mul_f32_e32 v167, v148, v152
	v_mov_b32_e32 v152, v31
	v_mov_b32_e32 v159, v128
	v_mov_b32_e32 v166, v23
	v_mov_b32_e32 v144, v129
	v_cvt_pk_bf16_f32 v164, v154, v155
	v_cvt_pk_bf16_f32 v165, v156, v157
	v_mul_f32_e32 v150, v148, v137
	s_waitcnt lgkmcnt(0)
	v_mul_f32_e32 v162, v148, v151
	v_mad_i64_i32 v[168:169], s[24:25], v134, s15, 0
	v_mov_b32_e32 v151, v27
	v_pk_mul_f32 v[152:153], v[152:153], v[158:159]
	v_mov_b32_e32 v163, v19
	v_pk_mul_f32 v[144:145], v[166:167], v[144:145]
	v_lshl_add_u64 v[170:171], v[168:169], 1, v[138:139]
	v_lshl_add_u64 v[168:169], v[168:169], 2, v[140:141]
	v_pk_fma_f32 v[150:151], v[160:161], v[150:151], v[152:153]
	v_pk_fma_f32 v[152:153], v[130:131], v[162:163], v[144:145]
	v_cvt_pk_bf16_f32 v128, v150, v151
	global_store_dwordx2 v[178:179], v[164:165], off nt
	global_store_dwordx4 v[172:173], v[154:157], off nt
	v_cvt_pk_bf16_f32 v129, v152, v153
	global_store_dwordx2 v[170:171], v[128:129], off nt
	global_store_dwordx4 v[168:169], v[150:153], off nt
	v_add_u32_e32 v137, 0x70, v147
	v_lshlrev_b32_e32 v128, 8, v137
	v_and_b32_e32 v134, 0x7fc00, v128
	v_lshl_add_u64 v[154:155], v[142:143], 0, v[134:135]
	global_load_dwordx3 v[158:160], v[154:155], off offset:256
	global_load_dwordx4 v[128:131], v[154:155], off offset:268
	global_load_dword v145, v[154:155], off offset:284
	global_load_dwordx4 v[150:153], v[154:155], off offset:16
	ds_bpermute_b32 v144, v149, v8
	global_load_dwordx4 v[154:157], v[154:155], off
	ds_bpermute_b32 v134, v149, v12
	v_mov_b32_e32 v170, v4
	v_mad_i64_i32 v[172:173], s[24:25], v137, s15, 0
	s_waitcnt lgkmcnt(1)
	v_mul_f32_e32 v169, v148, v144
	ds_bpermute_b32 v144, v149, v9
	ds_bpermute_b32 v137, v149, v13
	v_mov_b32_e32 v168, v12
	s_waitcnt lgkmcnt(2)
	v_mul_f32_e32 v166, v148, v134
	v_mov_b32_e32 v167, v8
	v_add_u32_e32 v134, 0x71, v147
	v_lshl_add_u64 v[178:179], v[172:173], 1, v[138:139]
	v_lshl_add_u64 v[172:173], v[172:173], 2, v[140:141]
	s_waitcnt vmcnt(4)
	v_mov_b32_e32 v161, v160
	s_waitcnt vmcnt(1)
	v_mov_b32_e32 v163, v152
	v_mov_b32_e32 v162, v151
	ds_bpermute_b32 v151, v149, v4
	ds_bpermute_b32 v152, v149, v0
	s_waitcnt vmcnt(0)
	v_mov_b32_e32 v165, v156
	v_mov_b32_e32 v164, v155
	v_mov_b32_e32 v155, v157
	s_waitcnt lgkmcnt(1)
	v_mul_f32_e32 v156, v148, v151
	s_waitcnt lgkmcnt(0)
	v_mul_f32_e32 v171, v148, v152
	v_mov_b32_e32 v151, v153
	v_mov_b32_e32 v157, v0
	v_pk_mul_f32 v[150:151], v[170:171], v[150:151]
	ds_bpermute_b32 v152, v149, v1
	v_pk_fma_f32 v[156:157], v[162:163], v[156:157], v[150:151]
	ds_bpermute_b32 v151, v149, v5
	v_pk_mul_f32 v[154:155], v[168:169], v[154:155]
	v_mov_b32_e32 v160, v159
	v_pk_fma_f32 v[154:155], v[164:165], v[166:167], v[154:155]
	v_mul_f32_e32 v153, v148, v144
	s_waitcnt lgkmcnt(1)
	v_mul_f32_e32 v167, v148, v152
	v_mov_b32_e32 v152, v13
	v_mov_b32_e32 v159, v128
	v_mov_b32_e32 v166, v5
	v_mov_b32_e32 v144, v129
	v_cvt_pk_bf16_f32 v164, v154, v155
	v_cvt_pk_bf16_f32 v165, v156, v157
	v_mul_f32_e32 v150, v148, v137
	s_waitcnt lgkmcnt(0)
	v_mul_f32_e32 v162, v148, v151
	v_mad_i64_i32 v[168:169], s[24:25], v134, s15, 0
	v_mov_b32_e32 v151, v9
	v_pk_mul_f32 v[152:153], v[152:153], v[158:159]
	v_mov_b32_e32 v163, v1
	v_pk_mul_f32 v[144:145], v[166:167], v[144:145]
	v_lshl_add_u64 v[170:171], v[168:169], 1, v[138:139]
	v_lshl_add_u64 v[168:169], v[168:169], 2, v[140:141]
	v_pk_fma_f32 v[150:151], v[160:161], v[150:151], v[152:153]
	v_pk_fma_f32 v[152:153], v[130:131], v[162:163], v[144:145]
	v_cvt_pk_bf16_f32 v128, v150, v151
	global_store_dwordx2 v[178:179], v[164:165], off nt
	global_store_dwordx4 v[172:173], v[154:157], off nt
	v_cvt_pk_bf16_f32 v129, v152, v153
	global_store_dwordx2 v[170:171], v[128:129], off nt
	global_store_dwordx4 v[168:169], v[150:153], off nt
	v_add_u32_e32 v137, 0x72, v147
	v_lshlrev_b32_e32 v128, 8, v137
	v_and_b32_e32 v134, 0x7fe00, v128
	v_lshl_add_u64 v[144:145], v[142:143], 0, v[134:135]
	global_load_dwordx3 v[158:160], v[144:145], off offset:256
	global_load_dwordx4 v[128:131], v[144:145], off offset:268
	global_load_dword v143, v[144:145], off offset:284
	global_load_dwordx4 v[150:153], v[144:145], off offset:16
	global_load_dwordx4 v[154:157], v[144:145], off
	ds_bpermute_b32 v134, v149, v14
	ds_bpermute_b32 v142, v149, v10
	v_mov_b32_e32 v168, v6
	v_mad_i64_i32 v[170:171], s[24:25], v137, s15, 0
	s_waitcnt lgkmcnt(1)
	v_mul_f32_e32 v164, v148, v134
	s_waitcnt lgkmcnt(0)
	v_mul_f32_e32 v167, v148, v142
	v_add_u32_e32 v134, 0x73, v147
	ds_bpermute_b32 v137, v149, v15
	ds_bpermute_b32 v142, v149, v11
	ds_bpermute_b32 v147, v149, v7
	v_mov_b32_e32 v166, v14
	v_mov_b32_e32 v165, v10
	v_lshl_add_u64 v[172:173], v[170:171], 1, v[138:139]
	v_lshl_add_u64 v[170:171], v[170:171], 2, v[140:141]
	s_waitcnt vmcnt(4)
	v_mov_b32_e32 v161, v160
	s_waitcnt vmcnt(1)
	v_mov_b32_e32 v163, v152
	v_mov_b32_e32 v162, v151
	ds_bpermute_b32 v151, v149, v6
	ds_bpermute_b32 v152, v149, v2
	s_waitcnt vmcnt(0)
	v_mov_b32_e32 v145, v156
	v_mov_b32_e32 v144, v155
	v_mov_b32_e32 v155, v157
	s_waitcnt lgkmcnt(1)
	v_mul_f32_e32 v156, v148, v151
	s_waitcnt lgkmcnt(0)
	v_mul_f32_e32 v169, v148, v152
	v_mov_b32_e32 v151, v153
	v_mov_b32_e32 v157, v2
	v_pk_mul_f32 v[150:151], v[168:169], v[150:151]
	v_pk_mul_f32 v[154:155], v[166:167], v[154:155]
	v_pk_fma_f32 v[156:157], v[162:163], v[156:157], v[150:151]
	ds_bpermute_b32 v151, v149, v3
	v_mov_b32_e32 v160, v159
	v_pk_fma_f32 v[154:155], v[144:145], v[164:165], v[154:155]
	v_mul_f32_e32 v150, v148, v137
	v_mul_f32_e32 v149, v148, v142
	v_mul_f32_e32 v152, v148, v147
	s_waitcnt lgkmcnt(0)
	v_mul_f32_e32 v163, v148, v151
	v_mad_i64_i32 v[164:165], s[24:25], v134, s15, 0
	v_mov_b32_e32 v148, v15
	v_mov_b32_e32 v159, v128
	v_mov_b32_e32 v162, v7
	v_mov_b32_e32 v142, v129
	v_cvt_pk_bf16_f32 v144, v154, v155
	v_cvt_pk_bf16_f32 v145, v156, v157
	v_lshl_add_u64 v[166:167], v[164:165], 1, v[138:139]
	v_lshl_add_u64 v[164:165], v[164:165], 2, v[140:141]
	v_mov_b32_e32 v151, v11
	v_pk_mul_f32 v[138:139], v[148:149], v[158:159]
	v_mov_b32_e32 v153, v3
	v_pk_mul_f32 v[140:141], v[162:163], v[142:143]
	v_pk_fma_f32 v[138:139], v[160:161], v[150:151], v[138:139]
	v_pk_fma_f32 v[140:141], v[130:131], v[152:153], v[140:141]
	v_cvt_pk_bf16_f32 v128, v138, v139
	global_store_dwordx2 v[172:173], v[144:145], off nt
	global_store_dwordx4 v[170:171], v[154:157], off nt
	v_cvt_pk_bf16_f32 v129, v140, v141
	global_store_dwordx2 v[166:167], v[128:129], off nt
	global_store_dwordx4 v[164:165], v[138:141], off nt

.LBB0_492:
	s_or_saveexec_b64 s[8:9], s[8:9]
	s_mov_b64 s[68:69], 0
	s_xor_b64 exec, exec, s[8:9]
	s_cbranch_execz .LBB0_500
	v_cmp_lt_i32_e32 vcc, 1, v176
	s_mov_b64 s[72:73], 0
	s_mov_b64 s[68:69], -1
	s_mov_b64 s[74:75], s[66:67]
	s_and_saveexec_b64 s[0:1], vcc
	s_cbranch_execz .LBB0_499
	v_cmp_lt_i32_e32 vcc, 2, v176
	s_mov_b64 s[72:73], -1
	s_mov_b64 s[74:75], s[66:67]
	s_and_saveexec_b64 s[68:69], vcc
	s_cbranch_execz .LBB0_498
	v_cmp_lt_i32_e32 vcc, 3, v176
	s_mov_b64 s[74:75], -1
	s_and_saveexec_b64 s[72:73], vcc
	s_cbranch_execz .LBB0_497
	v_mbcnt_hi_u32_b32 v128, -1, v204
	v_and_b32_e32 v130, 64, v128
	v_xor_b32_e32 v129, 8, v128
	v_add_u32_e32 v130, 64, v130
	v_cmp_lt_i32_e32 vcc, v129, v130
	v_readlane_b32 s36, v253, 44
	v_ashrrev_i32_e32 v137, 31, v136
	v_cndmask_b32_e32 v128, v128, v129, vcc
	v_cmp_gt_u32_e32 vcc, 8, v175
	v_readlane_b32 s37, v253, 45
	v_lshl_add_u32 v148, v146, 2, v211
	v_lshlrev_b32_e32 v149, 2, v128
	v_cndmask_b32_e64 v147, 1.0, -1.0, vcc
	v_readlane_b32 s38, v253, 46
	v_readlane_b32 s39, v253, 47
	v_readlane_b32 s40, v253, 48
	v_readlane_b32 s41, v253, 49
	v_readlane_b32 s42, v253, 50
	v_readlane_b32 s43, v253, 51
	v_readlane_b32 s44, v253, 52
	v_readlane_b32 s45, v253, 53
	v_readlane_b32 s46, v253, 54
	v_readlane_b32 s47, v253, 55
	v_readlane_b32 s48, v253, 56
	v_readlane_b32 s49, v253, 57
	v_readlane_b32 s50, v253, 58
	v_readlane_b32 s51, v253, 59
	v_lshl_add_u64 v[138:139], v[136:137], 1, s[36:37]
	v_lshlrev_b32_e32 v128, 5, v210
	v_and_b32_e32 v134, 0xe0, v128
	v_lshlrev_b32_e32 v128, 8, v148
	v_lshl_add_u64 v[140:141], s[58:59], 0, v[134:135]
	v_and_b32_e32 v134, 0x7fc00, v128
	ds_bpermute_b32 v128, v149, v124
	v_lshl_add_u64 v[150:151], v[140:141], 0, v[134:135]
	ds_bpermute_b32 v134, v149, v120
	ds_bpermute_b32 v137, v149, v116
	v_mov_b32_e32 v152, v124
	s_waitcnt lgkmcnt(2)
	v_mul_f32_e32 v153, v147, v128
	global_load_dwordx4 v[128:131], v[150:151], off offset:16
	global_load_dwordx4 v[142:145], v[150:151], off
	ds_bpermute_b32 v154, v149, v112
	ds_bpermute_b32 v156, v149, v117
	ds_bpermute_b32 v157, v149, v113
	s_waitcnt vmcnt(0)
	v_pk_mul_f32 v[142:143], v[152:153], v[142:143]
	s_nop 0
	v_add_f32_e32 v152, v142, v143
	s_waitcnt lgkmcnt(4)
	v_mul_f32_e32 v143, v147, v134
	v_mov_b32_e32 v142, v120
	v_pk_mul_f32 v[142:143], v[142:143], v[144:145]
	s_nop 0
	v_add_f32_e32 v134, v142, v143
	s_waitcnt lgkmcnt(3)
	v_mul_f32_e32 v143, v147, v137
	v_mov_b32_e32 v142, v116
	v_pk_mul_f32 v[128:129], v[142:143], v[128:129]
	v_mad_i64_i32 v[142:143], s[24:25], v148, s13, v[138:139]
	v_add_f32_e32 v137, v128, v129
	s_waitcnt lgkmcnt(2)
	v_mul_f32_e32 v129, v147, v154
	v_mov_b32_e32 v128, v112
	v_pk_mul_f32 v[128:129], v[128:129], v[130:131]
	v_mul_f32_e32 v131, 0x3e38aa3b, v137
	v_add_f32_e32 v128, v128, v129
	v_mul_f32_e32 v128, 0x3e38aa3b, v128
	v_cvt_pk_bf16_f32 v145, v131, v128
	ds_bpermute_b32 v128, v149, v125
	v_mul_f32_e32 v129, 0x3e38aa3b, v152
	v_mul_f32_e32 v130, 0x3e38aa3b, v134
	v_cvt_pk_bf16_f32 v144, v129, v130
	ds_bpermute_b32 v137, v149, v121
	s_waitcnt lgkmcnt(1)
	v_mul_f32_e32 v155, v147, v128
	global_load_dwordx4 v[128:131], v[150:151], off offset:272
	s_nop 0
	global_load_dwordx4 v[150:153], v[150:151], off offset:256
	v_mov_b32_e32 v154, v125
	v_or_b32_e32 v134, 1, v148
	global_store_dwordx2 v[142:143], v[144:145], off nt
	s_waitcnt vmcnt(1)
	v_pk_mul_f32 v[150:151], v[154:155], v[150:151]
	s_nop 0
	v_add_f32_e32 v154, v150, v151
	s_waitcnt lgkmcnt(0)
	v_mul_f32_e32 v151, v147, v137
	v_mov_b32_e32 v150, v121
	v_pk_mul_f32 v[150:151], v[150:151], v[152:153]
	s_nop 0
	v_add_f32_e32 v137, v150, v151
	v_mul_f32_e32 v151, v147, v156
	v_mov_b32_e32 v150, v117
	v_pk_mul_f32 v[128:129], v[150:151], v[128:129]
	s_nop 0
	v_add_f32_e32 v150, v128, v129
	v_mul_f32_e32 v129, v147, v157
	v_mov_b32_e32 v128, v113
	v_pk_mul_f32 v[128:129], v[128:129], v[130:131]
	v_mul_f32_e32 v131, 0x3e38aa3b, v154
	v_add_f32_e32 v130, v128, v129
	v_mad_i64_i32 v[128:129], s[24:25], v134, s13, v[138:139]
	v_mul_f32_e32 v134, 0x3e38aa3b, v137
	v_mul_f32_e32 v137, 0x3e38aa3b, v150
	v_mul_f32_e32 v142, 0x3e38aa3b, v130
	v_cvt_pk_bf16_f32 v130, v131, v134
	v_cvt_pk_bf16_f32 v131, v137, v142
	global_store_dwordx2 v[128:129], v[130:131], off nt
	v_or_b32_e32 v137, 2, v148
	v_lshlrev_b32_e32 v128, 8, v137
	v_and_b32_e32 v134, 0x7fe00, v128
	ds_bpermute_b32 v128, v149, v126
	v_lshl_add_u64 v[150:151], v[140:141], 0, v[134:135]
	ds_bpermute_b32 v134, v149, v122
	ds_bpermute_b32 v154, v149, v118
	v_mov_b32_e32 v152, v126
	s_waitcnt lgkmcnt(2)
	v_mul_f32_e32 v153, v147, v128
	global_load_dwordx4 v[128:131], v[150:151], off offset:16
	global_load_dwordx4 v[142:145], v[150:151], off
	ds_bpermute_b32 v155, v149, v114
	ds_bpermute_b32 v156, v149, v119
	ds_bpermute_b32 v157, v149, v115
	s_waitcnt vmcnt(0)
	v_pk_mul_f32 v[142:143], v[152:153], v[142:143]
	s_nop 0
	v_add_f32_e32 v152, v142, v143
	s_waitcnt lgkmcnt(4)
	v_mul_f32_e32 v143, v147, v134
	v_mov_b32_e32 v142, v122
	v_pk_mul_f32 v[142:143], v[142:143], v[144:145]
	s_nop 0
	v_add_f32_e32 v134, v142, v143
	s_waitcnt lgkmcnt(3)
	v_mul_f32_e32 v143, v147, v154
	v_mov_b32_e32 v142, v118
	v_pk_mul_f32 v[128:129], v[142:143], v[128:129]
	v_mad_i64_i32 v[142:143], s[24:25], v137, s13, v[138:139]
	v_add_f32_e32 v144, v128, v129
	s_waitcnt lgkmcnt(2)
	v_mul_f32_e32 v129, v147, v155
	v_mov_b32_e32 v128, v114
	v_pk_mul_f32 v[128:129], v[128:129], v[130:131]
	v_mul_f32_e32 v131, 0x3e38aa3b, v144
	v_add_f32_e32 v128, v128, v129
	v_mul_f32_e32 v128, 0x3e38aa3b, v128
	v_cvt_pk_bf16_f32 v145, v131, v128
	ds_bpermute_b32 v128, v149, v127
	v_mul_f32_e32 v129, 0x3e38aa3b, v152
	v_mul_f32_e32 v130, 0x3e38aa3b, v134
	v_cvt_pk_bf16_f32 v144, v129, v130
	ds_bpermute_b32 v137, v149, v123
	s_waitcnt lgkmcnt(1)
	v_mul_f32_e32 v155, v147, v128
	global_load_dwordx4 v[128:131], v[150:151], off offset:272
	s_nop 0
	global_load_dwordx4 v[150:153], v[150:151], off offset:256
	v_mov_b32_e32 v154, v127
	v_or_b32_e32 v134, 3, v148
	global_store_dwordx2 v[142:143], v[144:145], off nt
	s_waitcnt vmcnt(1)
	v_pk_mul_f32 v[150:151], v[154:155], v[150:151]
	s_nop 0
	v_add_f32_e32 v154, v150, v151
	s_waitcnt lgkmcnt(0)
	v_mul_f32_e32 v151, v147, v137
	v_mov_b32_e32 v150, v123
	v_pk_mul_f32 v[150:151], v[150:151], v[152:153]
	s_nop 0
	v_add_f32_e32 v137, v150, v151
	v_mul_f32_e32 v151, v147, v156
	v_mov_b32_e32 v150, v119
	v_pk_mul_f32 v[128:129], v[150:151], v[128:129]
	s_nop 0
	v_add_f32_e32 v150, v128, v129
	v_mul_f32_e32 v129, v147, v157
	v_mov_b32_e32 v128, v115
	v_pk_mul_f32 v[128:129], v[128:129], v[130:131]
	v_mul_f32_e32 v131, 0x3e38aa3b, v154
	v_add_f32_e32 v130, v128, v129
	v_mad_i64_i32 v[128:129], s[24:25], v134, s13, v[138:139]
	v_mul_f32_e32 v134, 0x3e38aa3b, v137
	v_mul_f32_e32 v137, 0x3e38aa3b, v150
	v_mul_f32_e32 v142, 0x3e38aa3b, v130
	v_cvt_pk_bf16_f32 v130, v131, v134
	v_cvt_pk_bf16_f32 v131, v137, v142
	global_store_dwordx2 v[128:129], v[130:131], off nt
	v_add_u32_e32 v137, 16, v148
	v_lshlrev_b32_e32 v128, 8, v137
	v_and_b32_e32 v134, 0x7fc00, v128
	ds_bpermute_b32 v128, v149, v108
	v_lshl_add_u64 v[150:151], v[140:141], 0, v[134:135]
	ds_bpermute_b32 v134, v149, v104
	ds_bpermute_b32 v154, v149, v100
	v_mov_b32_e32 v152, v108
	s_waitcnt lgkmcnt(2)
	v_mul_f32_e32 v153, v147, v128
	global_load_dwordx4 v[128:131], v[150:151], off offset:16
	global_load_dwordx4 v[142:145], v[150:151], off
	ds_bpermute_b32 v155, v149, v96
	ds_bpermute_b32 v156, v149, v101
	ds_bpermute_b32 v157, v149, v97
	s_waitcnt vmcnt(0)
	v_pk_mul_f32 v[142:143], v[152:153], v[142:143]
	s_nop 0
	v_add_f32_e32 v152, v142, v143
	s_waitcnt lgkmcnt(4)
	v_mul_f32_e32 v143, v147, v134
	v_mov_b32_e32 v142, v104
	v_pk_mul_f32 v[142:143], v[142:143], v[144:145]
	s_nop 0
	v_add_f32_e32 v134, v142, v143
	s_waitcnt lgkmcnt(3)
	v_mul_f32_e32 v143, v147, v154
	v_mov_b32_e32 v142, v100
	v_pk_mul_f32 v[128:129], v[142:143], v[128:129]
	v_mad_i64_i32 v[142:143], s[24:25], v137, s13, v[138:139]
	v_add_f32_e32 v144, v128, v129
	s_waitcnt lgkmcnt(2)
	v_mul_f32_e32 v129, v147, v155
	v_mov_b32_e32 v128, v96
	v_pk_mul_f32 v[128:129], v[128:129], v[130:131]
	v_mul_f32_e32 v131, 0x3e38aa3b, v144
	v_add_f32_e32 v128, v128, v129
	v_mul_f32_e32 v128, 0x3e38aa3b, v128
	v_cvt_pk_bf16_f32 v145, v131, v128
	ds_bpermute_b32 v128, v149, v109
	v_mul_f32_e32 v129, 0x3e38aa3b, v152
	v_mul_f32_e32 v130, 0x3e38aa3b, v134
	v_cvt_pk_bf16_f32 v144, v129, v130
	ds_bpermute_b32 v137, v149, v105
	s_waitcnt lgkmcnt(1)
	v_mul_f32_e32 v155, v147, v128
	global_load_dwordx4 v[128:131], v[150:151], off offset:272
	s_nop 0
	global_load_dwordx4 v[150:153], v[150:151], off offset:256
	v_mov_b32_e32 v154, v109
	v_add_u32_e32 v134, 17, v148
	global_store_dwordx2 v[142:143], v[144:145], off nt
	s_waitcnt vmcnt(1)
	v_pk_mul_f32 v[150:151], v[154:155], v[150:151]
	s_nop 0
	v_add_f32_e32 v154, v150, v151
	s_waitcnt lgkmcnt(0)
	v_mul_f32_e32 v151, v147, v137
	v_mov_b32_e32 v150, v105
	v_pk_mul_f32 v[150:151], v[150:151], v[152:153]
	s_nop 0
	v_add_f32_e32 v137, v150, v151
	v_mul_f32_e32 v151, v147, v156
	v_mov_b32_e32 v150, v101
	v_pk_mul_f32 v[128:129], v[150:151], v[128:129]
	s_nop 0
	v_add_f32_e32 v150, v128, v129
	v_mul_f32_e32 v129, v147, v157
	v_mov_b32_e32 v128, v97
	v_pk_mul_f32 v[128:129], v[128:129], v[130:131]
	v_mul_f32_e32 v131, 0x3e38aa3b, v154
	v_add_f32_e32 v130, v128, v129
	v_mad_i64_i32 v[128:129], s[24:25], v134, s13, v[138:139]
	v_mul_f32_e32 v134, 0x3e38aa3b, v137
	v_mul_f32_e32 v137, 0x3e38aa3b, v150
	v_mul_f32_e32 v142, 0x3e38aa3b, v130
	v_cvt_pk_bf16_f32 v130, v131, v134
	v_cvt_pk_bf16_f32 v131, v137, v142
	global_store_dwordx2 v[128:129], v[130:131], off nt
	v_add_u32_e32 v137, 18, v148
	v_lshlrev_b32_e32 v128, 8, v137
	v_and_b32_e32 v134, 0x7fe00, v128
	ds_bpermute_b32 v128, v149, v110
	v_lshl_add_u64 v[150:151], v[140:141], 0, v[134:135]
	ds_bpermute_b32 v134, v149, v106
	ds_bpermute_b32 v154, v149, v102
	v_mov_b32_e32 v152, v110
	s_waitcnt lgkmcnt(2)
	v_mul_f32_e32 v153, v147, v128
	global_load_dwordx4 v[128:131], v[150:151], off offset:16
	global_load_dwordx4 v[142:145], v[150:151], off
	ds_bpermute_b32 v155, v149, v98
	ds_bpermute_b32 v156, v149, v103
	ds_bpermute_b32 v157, v149, v99
	s_waitcnt vmcnt(0)
	v_pk_mul_f32 v[142:143], v[152:153], v[142:143]
	s_nop 0
	v_add_f32_e32 v152, v142, v143
	s_waitcnt lgkmcnt(4)
	v_mul_f32_e32 v143, v147, v134
	v_mov_b32_e32 v142, v106
	v_pk_mul_f32 v[142:143], v[142:143], v[144:145]
	s_nop 0
	v_add_f32_e32 v134, v142, v143
	s_waitcnt lgkmcnt(3)
	v_mul_f32_e32 v143, v147, v154
	v_mov_b32_e32 v142, v102
	v_pk_mul_f32 v[128:129], v[142:143], v[128:129]
	v_mad_i64_i32 v[142:143], s[24:25], v137, s13, v[138:139]
	v_add_f32_e32 v144, v128, v129
	s_waitcnt lgkmcnt(2)
	v_mul_f32_e32 v129, v147, v155
	v_mov_b32_e32 v128, v98
	v_pk_mul_f32 v[128:129], v[128:129], v[130:131]
	v_mul_f32_e32 v131, 0x3e38aa3b, v144
	v_add_f32_e32 v128, v128, v129
	v_mul_f32_e32 v128, 0x3e38aa3b, v128
	v_cvt_pk_bf16_f32 v145, v131, v128
	ds_bpermute_b32 v128, v149, v111
	v_mul_f32_e32 v129, 0x3e38aa3b, v152
	v_mul_f32_e32 v130, 0x3e38aa3b, v134
	v_cvt_pk_bf16_f32 v144, v129, v130
	ds_bpermute_b32 v137, v149, v107
	s_waitcnt lgkmcnt(1)
	v_mul_f32_e32 v155, v147, v128
	global_load_dwordx4 v[128:131], v[150:151], off offset:272
	s_nop 0
	global_load_dwordx4 v[150:153], v[150:151], off offset:256
	v_mov_b32_e32 v154, v111
	v_add_u32_e32 v134, 19, v148
	global_store_dwordx2 v[142:143], v[144:145], off nt
	s_waitcnt vmcnt(1)
	v_pk_mul_f32 v[150:151], v[154:155], v[150:151]
	s_nop 0
	v_add_f32_e32 v154, v150, v151
	s_waitcnt lgkmcnt(0)
	v_mul_f32_e32 v151, v147, v137
	v_mov_b32_e32 v150, v107
	v_pk_mul_f32 v[150:151], v[150:151], v[152:153]
	s_nop 0
	v_add_f32_e32 v137, v150, v151
	v_mul_f32_e32 v151, v147, v156
	v_mov_b32_e32 v150, v103
	v_pk_mul_f32 v[128:129], v[150:151], v[128:129]
	s_nop 0
	v_add_f32_e32 v150, v128, v129
	v_mul_f32_e32 v129, v147, v157
	v_mov_b32_e32 v128, v99
	v_pk_mul_f32 v[128:129], v[128:129], v[130:131]
	v_mul_f32_e32 v131, 0x3e38aa3b, v154
	v_add_f32_e32 v130, v128, v129
	v_mad_i64_i32 v[128:129], s[24:25], v134, s13, v[138:139]
	v_mul_f32_e32 v134, 0x3e38aa3b, v137
	v_mul_f32_e32 v137, 0x3e38aa3b, v150
	v_mul_f32_e32 v142, 0x3e38aa3b, v130
	v_cvt_pk_bf16_f32 v130, v131, v134
	v_cvt_pk_bf16_f32 v131, v137, v142
	global_store_dwordx2 v[128:129], v[130:131], off nt
	v_add_u32_e32 v137, 32, v148
	v_lshlrev_b32_e32 v128, 8, v137
	v_and_b32_e32 v134, 0x7fc00, v128
	ds_bpermute_b32 v128, v149, v92
	v_lshl_add_u64 v[150:151], v[140:141], 0, v[134:135]
	ds_bpermute_b32 v134, v149, v88
	ds_bpermute_b32 v154, v149, v84
	v_mov_b32_e32 v152, v92
	s_waitcnt lgkmcnt(2)
	v_mul_f32_e32 v153, v147, v128
	global_load_dwordx4 v[128:131], v[150:151], off offset:16
	global_load_dwordx4 v[142:145], v[150:151], off
	ds_bpermute_b32 v155, v149, v80
	ds_bpermute_b32 v156, v149, v85
	ds_bpermute_b32 v157, v149, v81
	s_waitcnt vmcnt(0)
	v_pk_mul_f32 v[142:143], v[152:153], v[142:143]
	s_nop 0
	v_add_f32_e32 v152, v142, v143
	s_waitcnt lgkmcnt(4)
	v_mul_f32_e32 v143, v147, v134
	v_mov_b32_e32 v142, v88
	v_pk_mul_f32 v[142:143], v[142:143], v[144:145]
	s_nop 0
	v_add_f32_e32 v134, v142, v143
	s_waitcnt lgkmcnt(3)
	v_mul_f32_e32 v143, v147, v154
	v_mov_b32_e32 v142, v84
	v_pk_mul_f32 v[128:129], v[142:143], v[128:129]
	v_mad_i64_i32 v[142:143], s[24:25], v137, s13, v[138:139]
	v_add_f32_e32 v144, v128, v129
	s_waitcnt lgkmcnt(2)
	v_mul_f32_e32 v129, v147, v155
	v_mov_b32_e32 v128, v80
	v_pk_mul_f32 v[128:129], v[128:129], v[130:131]
	v_mul_f32_e32 v131, 0x3e38aa3b, v144
	v_add_f32_e32 v128, v128, v129
	v_mul_f32_e32 v128, 0x3e38aa3b, v128
	v_cvt_pk_bf16_f32 v145, v131, v128
	ds_bpermute_b32 v128, v149, v93
	v_mul_f32_e32 v129, 0x3e38aa3b, v152
	v_mul_f32_e32 v130, 0x3e38aa3b, v134
	v_cvt_pk_bf16_f32 v144, v129, v130
	ds_bpermute_b32 v137, v149, v89
	s_waitcnt lgkmcnt(1)
	v_mul_f32_e32 v155, v147, v128
	global_load_dwordx4 v[128:131], v[150:151], off offset:272
	s_nop 0
	global_load_dwordx4 v[150:153], v[150:151], off offset:256
	v_mov_b32_e32 v154, v93
	v_add_u32_e32 v134, 33, v148
	global_store_dwordx2 v[142:143], v[144:145], off nt
	s_waitcnt vmcnt(1)
	v_pk_mul_f32 v[150:151], v[154:155], v[150:151]
	s_nop 0
	v_add_f32_e32 v154, v150, v151
	s_waitcnt lgkmcnt(0)
	v_mul_f32_e32 v151, v147, v137
	v_mov_b32_e32 v150, v89
	v_pk_mul_f32 v[150:151], v[150:151], v[152:153]
	s_nop 0
	v_add_f32_e32 v137, v150, v151
	v_mul_f32_e32 v151, v147, v156
	v_mov_b32_e32 v150, v85
	v_pk_mul_f32 v[128:129], v[150:151], v[128:129]
	s_nop 0
	v_add_f32_e32 v150, v128, v129
	v_mul_f32_e32 v129, v147, v157
	v_mov_b32_e32 v128, v81
	v_pk_mul_f32 v[128:129], v[128:129], v[130:131]
	v_mul_f32_e32 v131, 0x3e38aa3b, v154
	v_add_f32_e32 v130, v128, v129
	v_mad_i64_i32 v[128:129], s[24:25], v134, s13, v[138:139]
	v_mul_f32_e32 v134, 0x3e38aa3b, v137
	v_mul_f32_e32 v137, 0x3e38aa3b, v150
	v_mul_f32_e32 v142, 0x3e38aa3b, v130
	v_cvt_pk_bf16_f32 v130, v131, v134
	v_cvt_pk_bf16_f32 v131, v137, v142
	global_store_dwordx2 v[128:129], v[130:131], off nt
	v_add_u32_e32 v137, 34, v148
	v_lshlrev_b32_e32 v128, 8, v137
	v_and_b32_e32 v134, 0x7fe00, v128
	ds_bpermute_b32 v128, v149, v94
	v_lshl_add_u64 v[150:151], v[140:141], 0, v[134:135]
	ds_bpermute_b32 v134, v149, v90
	ds_bpermute_b32 v154, v149, v86
	v_mov_b32_e32 v152, v94
	s_waitcnt lgkmcnt(2)
	v_mul_f32_e32 v153, v147, v128
	global_load_dwordx4 v[128:131], v[150:151], off offset:16
	global_load_dwordx4 v[142:145], v[150:151], off
	ds_bpermute_b32 v155, v149, v82
	ds_bpermute_b32 v156, v149, v87
	ds_bpermute_b32 v157, v149, v83
	s_waitcnt vmcnt(0)
	v_pk_mul_f32 v[142:143], v[152:153], v[142:143]
	s_nop 0
	v_add_f32_e32 v152, v142, v143
	s_waitcnt lgkmcnt(4)
	v_mul_f32_e32 v143, v147, v134
	v_mov_b32_e32 v142, v90
	v_pk_mul_f32 v[142:143], v[142:143], v[144:145]
	s_nop 0
	v_add_f32_e32 v134, v142, v143
	s_waitcnt lgkmcnt(3)
	v_mul_f32_e32 v143, v147, v154
	v_mov_b32_e32 v142, v86
	v_pk_mul_f32 v[128:129], v[142:143], v[128:129]
	v_mad_i64_i32 v[142:143], s[24:25], v137, s13, v[138:139]
	v_add_f32_e32 v144, v128, v129
	s_waitcnt lgkmcnt(2)
	v_mul_f32_e32 v129, v147, v155
	v_mov_b32_e32 v128, v82
	v_pk_mul_f32 v[128:129], v[128:129], v[130:131]
	v_mul_f32_e32 v131, 0x3e38aa3b, v144
	v_add_f32_e32 v128, v128, v129
	v_mul_f32_e32 v128, 0x3e38aa3b, v128
	v_cvt_pk_bf16_f32 v145, v131, v128
	ds_bpermute_b32 v128, v149, v95
	v_mul_f32_e32 v129, 0x3e38aa3b, v152
	v_mul_f32_e32 v130, 0x3e38aa3b, v134
	v_cvt_pk_bf16_f32 v144, v129, v130
	ds_bpermute_b32 v137, v149, v91
	s_waitcnt lgkmcnt(1)
	v_mul_f32_e32 v155, v147, v128
	global_load_dwordx4 v[128:131], v[150:151], off offset:272
	s_nop 0
	global_load_dwordx4 v[150:153], v[150:151], off offset:256
	v_mov_b32_e32 v154, v95
	v_add_u32_e32 v134, 35, v148
	global_store_dwordx2 v[142:143], v[144:145], off nt
	s_waitcnt vmcnt(1)
	v_pk_mul_f32 v[150:151], v[154:155], v[150:151]
	s_nop 0
	v_add_f32_e32 v154, v150, v151
	s_waitcnt lgkmcnt(0)
	v_mul_f32_e32 v151, v147, v137
	v_mov_b32_e32 v150, v91
	v_pk_mul_f32 v[150:151], v[150:151], v[152:153]
	s_nop 0
	v_add_f32_e32 v137, v150, v151
	v_mul_f32_e32 v151, v147, v156
	v_mov_b32_e32 v150, v87
	v_pk_mul_f32 v[128:129], v[150:151], v[128:129]
	s_nop 0
	v_add_f32_e32 v150, v128, v129
	v_mul_f32_e32 v129, v147, v157
	v_mov_b32_e32 v128, v83
	v_pk_mul_f32 v[128:129], v[128:129], v[130:131]
	v_mul_f32_e32 v131, 0x3e38aa3b, v154
	v_add_f32_e32 v130, v128, v129
	v_mad_i64_i32 v[128:129], s[24:25], v134, s13, v[138:139]
	v_mul_f32_e32 v134, 0x3e38aa3b, v137
	v_mul_f32_e32 v137, 0x3e38aa3b, v150
	v_mul_f32_e32 v142, 0x3e38aa3b, v130
	v_cvt_pk_bf16_f32 v130, v131, v134
	v_cvt_pk_bf16_f32 v131, v137, v142
	global_store_dwordx2 v[128:129], v[130:131], off nt
	v_add_u32_e32 v137, 48, v148
	v_lshlrev_b32_e32 v128, 8, v137
	v_and_b32_e32 v134, 0x7fc00, v128
	ds_bpermute_b32 v128, v149, v76
	v_lshl_add_u64 v[150:151], v[140:141], 0, v[134:135]
	ds_bpermute_b32 v134, v149, v72
	ds_bpermute_b32 v154, v149, v68
	v_mov_b32_e32 v152, v76
	s_waitcnt lgkmcnt(2)
	v_mul_f32_e32 v153, v147, v128
	global_load_dwordx4 v[128:131], v[150:151], off offset:16
	global_load_dwordx4 v[142:145], v[150:151], off
	ds_bpermute_b32 v155, v149, v64
	ds_bpermute_b32 v156, v149, v69
	ds_bpermute_b32 v157, v149, v65
	s_waitcnt vmcnt(0)
	v_pk_mul_f32 v[142:143], v[152:153], v[142:143]
	s_nop 0
	v_add_f32_e32 v152, v142, v143
	s_waitcnt lgkmcnt(4)
	v_mul_f32_e32 v143, v147, v134
	v_mov_b32_e32 v142, v72
	v_pk_mul_f32 v[142:143], v[142:143], v[144:145]
	s_nop 0
	v_add_f32_e32 v134, v142, v143
	s_waitcnt lgkmcnt(3)
	v_mul_f32_e32 v143, v147, v154
	v_mov_b32_e32 v142, v68
	v_pk_mul_f32 v[128:129], v[142:143], v[128:129]
	v_mad_i64_i32 v[142:143], s[24:25], v137, s13, v[138:139]
	v_add_f32_e32 v144, v128, v129
	s_waitcnt lgkmcnt(2)
	v_mul_f32_e32 v129, v147, v155
	v_mov_b32_e32 v128, v64
	v_pk_mul_f32 v[128:129], v[128:129], v[130:131]
	v_mul_f32_e32 v131, 0x3e38aa3b, v144
	v_add_f32_e32 v128, v128, v129
	v_mul_f32_e32 v128, 0x3e38aa3b, v128
	v_cvt_pk_bf16_f32 v145, v131, v128
	ds_bpermute_b32 v128, v149, v77
	v_mul_f32_e32 v129, 0x3e38aa3b, v152
	v_mul_f32_e32 v130, 0x3e38aa3b, v134
	v_cvt_pk_bf16_f32 v144, v129, v130
	ds_bpermute_b32 v137, v149, v73
	s_waitcnt lgkmcnt(1)
	v_mul_f32_e32 v155, v147, v128
	global_load_dwordx4 v[128:131], v[150:151], off offset:272
	s_nop 0
	global_load_dwordx4 v[150:153], v[150:151], off offset:256
	v_mov_b32_e32 v154, v77
	v_add_u32_e32 v134, 49, v148
	global_store_dwordx2 v[142:143], v[144:145], off nt
	s_waitcnt vmcnt(1)
	v_pk_mul_f32 v[150:151], v[154:155], v[150:151]
	s_nop 0
	v_add_f32_e32 v154, v150, v151
	s_waitcnt lgkmcnt(0)
	v_mul_f32_e32 v151, v147, v137
	v_mov_b32_e32 v150, v73
	v_pk_mul_f32 v[150:151], v[150:151], v[152:153]
	s_nop 0
	v_add_f32_e32 v137, v150, v151
	v_mul_f32_e32 v151, v147, v156
	v_mov_b32_e32 v150, v69
	v_pk_mul_f32 v[128:129], v[150:151], v[128:129]
	s_nop 0
	v_add_f32_e32 v150, v128, v129
	v_mul_f32_e32 v129, v147, v157
	v_mov_b32_e32 v128, v65
	v_pk_mul_f32 v[128:129], v[128:129], v[130:131]
	v_mul_f32_e32 v131, 0x3e38aa3b, v154
	v_add_f32_e32 v130, v128, v129
	v_mad_i64_i32 v[128:129], s[24:25], v134, s13, v[138:139]
	v_mul_f32_e32 v134, 0x3e38aa3b, v137
	v_mul_f32_e32 v137, 0x3e38aa3b, v150
	v_mul_f32_e32 v142, 0x3e38aa3b, v130
	v_cvt_pk_bf16_f32 v130, v131, v134
	v_cvt_pk_bf16_f32 v131, v137, v142
	global_store_dwordx2 v[128:129], v[130:131], off nt
	v_add_u32_e32 v137, 50, v148
	v_lshlrev_b32_e32 v128, 8, v137
	v_and_b32_e32 v134, 0x7fe00, v128
	ds_bpermute_b32 v128, v149, v78
	v_lshl_add_u64 v[150:151], v[140:141], 0, v[134:135]
	ds_bpermute_b32 v134, v149, v74
	ds_bpermute_b32 v154, v149, v70
	v_mov_b32_e32 v152, v78
	s_waitcnt lgkmcnt(2)
	v_mul_f32_e32 v153, v147, v128
	global_load_dwordx4 v[128:131], v[150:151], off offset:16
	global_load_dwordx4 v[142:145], v[150:151], off
	ds_bpermute_b32 v155, v149, v66
	ds_bpermute_b32 v156, v149, v71
	ds_bpermute_b32 v157, v149, v67
	s_waitcnt vmcnt(0)
	v_pk_mul_f32 v[142:143], v[152:153], v[142:143]
	s_nop 0
	v_add_f32_e32 v152, v142, v143
	s_waitcnt lgkmcnt(4)
	v_mul_f32_e32 v143, v147, v134
	v_mov_b32_e32 v142, v74
	v_pk_mul_f32 v[142:143], v[142:143], v[144:145]
	s_nop 0
	v_add_f32_e32 v134, v142, v143
	s_waitcnt lgkmcnt(3)
	v_mul_f32_e32 v143, v147, v154
	v_mov_b32_e32 v142, v70
	v_pk_mul_f32 v[128:129], v[142:143], v[128:129]
	v_mad_i64_i32 v[142:143], s[24:25], v137, s13, v[138:139]
	v_add_f32_e32 v144, v128, v129
	s_waitcnt lgkmcnt(2)
	v_mul_f32_e32 v129, v147, v155
	v_mov_b32_e32 v128, v66
	v_pk_mul_f32 v[128:129], v[128:129], v[130:131]
	v_mul_f32_e32 v131, 0x3e38aa3b, v144
	v_add_f32_e32 v128, v128, v129
	v_mul_f32_e32 v128, 0x3e38aa3b, v128
	v_cvt_pk_bf16_f32 v145, v131, v128
	ds_bpermute_b32 v128, v149, v79
	v_mul_f32_e32 v129, 0x3e38aa3b, v152
	v_mul_f32_e32 v130, 0x3e38aa3b, v134
	v_cvt_pk_bf16_f32 v144, v129, v130
	ds_bpermute_b32 v137, v149, v75
	s_waitcnt lgkmcnt(1)
	v_mul_f32_e32 v155, v147, v128
	global_load_dwordx4 v[128:131], v[150:151], off offset:272
	s_nop 0
	global_load_dwordx4 v[150:153], v[150:151], off offset:256
	v_mov_b32_e32 v154, v79
	v_add_u32_e32 v134, 51, v148
	global_store_dwordx2 v[142:143], v[144:145], off nt
	s_waitcnt vmcnt(1)
	v_pk_mul_f32 v[150:151], v[154:155], v[150:151]
	s_nop 0
	v_add_f32_e32 v154, v150, v151
	s_waitcnt lgkmcnt(0)
	v_mul_f32_e32 v151, v147, v137
	v_mov_b32_e32 v150, v75
	v_pk_mul_f32 v[150:151], v[150:151], v[152:153]
	s_nop 0
	v_add_f32_e32 v137, v150, v151
	v_mul_f32_e32 v151, v147, v156
	v_mov_b32_e32 v150, v71
	v_pk_mul_f32 v[128:129], v[150:151], v[128:129]
	s_nop 0
	v_add_f32_e32 v150, v128, v129
	v_mul_f32_e32 v129, v147, v157
	v_mov_b32_e32 v128, v67
	v_pk_mul_f32 v[128:129], v[128:129], v[130:131]
	v_mul_f32_e32 v131, 0x3e38aa3b, v154
	v_add_f32_e32 v130, v128, v129
	v_mad_i64_i32 v[128:129], s[24:25], v134, s13, v[138:139]
	v_mul_f32_e32 v134, 0x3e38aa3b, v137
	v_mul_f32_e32 v137, 0x3e38aa3b, v150
	v_mul_f32_e32 v142, 0x3e38aa3b, v130
	v_cvt_pk_bf16_f32 v130, v131, v134
	v_cvt_pk_bf16_f32 v131, v137, v142
	global_store_dwordx2 v[128:129], v[130:131], off nt
	v_add_u32_e32 v137, 64, v148
	v_lshlrev_b32_e32 v128, 8, v137
	v_and_b32_e32 v134, 0x7fc00, v128
	ds_bpermute_b32 v128, v149, v60
	v_lshl_add_u64 v[150:151], v[140:141], 0, v[134:135]
	ds_bpermute_b32 v134, v149, v56
	ds_bpermute_b32 v154, v149, v52
	v_mov_b32_e32 v152, v60
	s_waitcnt lgkmcnt(2)
	v_mul_f32_e32 v153, v147, v128
	global_load_dwordx4 v[128:131], v[150:151], off offset:16
	global_load_dwordx4 v[142:145], v[150:151], off
	ds_bpermute_b32 v155, v149, v48
	ds_bpermute_b32 v156, v149, v53
	ds_bpermute_b32 v157, v149, v49
	s_waitcnt vmcnt(0)
	v_pk_mul_f32 v[142:143], v[152:153], v[142:143]
	s_nop 0
	v_add_f32_e32 v152, v142, v143
	s_waitcnt lgkmcnt(4)
	v_mul_f32_e32 v143, v147, v134
	v_mov_b32_e32 v142, v56
	v_pk_mul_f32 v[142:143], v[142:143], v[144:145]
	s_nop 0
	v_add_f32_e32 v134, v142, v143
	s_waitcnt lgkmcnt(3)
	v_mul_f32_e32 v143, v147, v154
	v_mov_b32_e32 v142, v52
	v_pk_mul_f32 v[128:129], v[142:143], v[128:129]
	v_mad_i64_i32 v[142:143], s[24:25], v137, s13, v[138:139]
	v_add_f32_e32 v144, v128, v129
	s_waitcnt lgkmcnt(2)
	v_mul_f32_e32 v129, v147, v155
	v_mov_b32_e32 v128, v48
	v_pk_mul_f32 v[128:129], v[128:129], v[130:131]
	v_mul_f32_e32 v131, 0x3e38aa3b, v144
	v_add_f32_e32 v128, v128, v129
	v_mul_f32_e32 v128, 0x3e38aa3b, v128
	v_cvt_pk_bf16_f32 v145, v131, v128
	ds_bpermute_b32 v128, v149, v61
	v_mul_f32_e32 v129, 0x3e38aa3b, v152
	v_mul_f32_e32 v130, 0x3e38aa3b, v134
	v_cvt_pk_bf16_f32 v144, v129, v130
	ds_bpermute_b32 v137, v149, v57
	s_waitcnt lgkmcnt(1)
	v_mul_f32_e32 v155, v147, v128
	global_load_dwordx4 v[128:131], v[150:151], off offset:272
	s_nop 0
	global_load_dwordx4 v[150:153], v[150:151], off offset:256
	v_mov_b32_e32 v154, v61
	v_add_u32_e32 v134, 0x41, v148
	global_store_dwordx2 v[142:143], v[144:145], off nt
	s_waitcnt vmcnt(1)
	v_pk_mul_f32 v[150:151], v[154:155], v[150:151]
	s_nop 0
	v_add_f32_e32 v154, v150, v151
	s_waitcnt lgkmcnt(0)
	v_mul_f32_e32 v151, v147, v137
	v_mov_b32_e32 v150, v57
	v_pk_mul_f32 v[150:151], v[150:151], v[152:153]
	s_nop 0
	v_add_f32_e32 v137, v150, v151
	v_mul_f32_e32 v151, v147, v156
	v_mov_b32_e32 v150, v53
	v_pk_mul_f32 v[128:129], v[150:151], v[128:129]
	s_nop 0
	v_add_f32_e32 v150, v128, v129
	v_mul_f32_e32 v129, v147, v157
	v_mov_b32_e32 v128, v49
	v_pk_mul_f32 v[128:129], v[128:129], v[130:131]
	v_mul_f32_e32 v131, 0x3e38aa3b, v154
	v_add_f32_e32 v130, v128, v129
	v_mad_i64_i32 v[128:129], s[24:25], v134, s13, v[138:139]
	v_mul_f32_e32 v134, 0x3e38aa3b, v137
	v_mul_f32_e32 v137, 0x3e38aa3b, v150
	v_mul_f32_e32 v142, 0x3e38aa3b, v130
	v_cvt_pk_bf16_f32 v130, v131, v134
	v_cvt_pk_bf16_f32 v131, v137, v142
	global_store_dwordx2 v[128:129], v[130:131], off nt
	v_add_u32_e32 v137, 0x42, v148
	v_lshlrev_b32_e32 v128, 8, v137
	v_and_b32_e32 v134, 0x7fe00, v128
	ds_bpermute_b32 v128, v149, v62
	v_lshl_add_u64 v[150:151], v[140:141], 0, v[134:135]
	ds_bpermute_b32 v134, v149, v58
	ds_bpermute_b32 v154, v149, v54
	v_mov_b32_e32 v152, v62
	s_waitcnt lgkmcnt(2)
	v_mul_f32_e32 v153, v147, v128
	global_load_dwordx4 v[128:131], v[150:151], off offset:16
	global_load_dwordx4 v[142:145], v[150:151], off
	ds_bpermute_b32 v155, v149, v50
	ds_bpermute_b32 v156, v149, v55
	ds_bpermute_b32 v157, v149, v51
	s_waitcnt vmcnt(0)
	v_pk_mul_f32 v[142:143], v[152:153], v[142:143]
	s_nop 0
	v_add_f32_e32 v152, v142, v143
	s_waitcnt lgkmcnt(4)
	v_mul_f32_e32 v143, v147, v134
	v_mov_b32_e32 v142, v58
	v_pk_mul_f32 v[142:143], v[142:143], v[144:145]
	s_nop 0
	v_add_f32_e32 v134, v142, v143
	s_waitcnt lgkmcnt(3)
	v_mul_f32_e32 v143, v147, v154
	v_mov_b32_e32 v142, v54
	v_pk_mul_f32 v[128:129], v[142:143], v[128:129]
	v_mad_i64_i32 v[142:143], s[24:25], v137, s13, v[138:139]
	v_add_f32_e32 v144, v128, v129
	s_waitcnt lgkmcnt(2)
	v_mul_f32_e32 v129, v147, v155
	v_mov_b32_e32 v128, v50
	v_pk_mul_f32 v[128:129], v[128:129], v[130:131]
	v_mul_f32_e32 v131, 0x3e38aa3b, v144
	v_add_f32_e32 v128, v128, v129
	v_mul_f32_e32 v128, 0x3e38aa3b, v128
	v_cvt_pk_bf16_f32 v145, v131, v128
	ds_bpermute_b32 v128, v149, v63
	v_mul_f32_e32 v129, 0x3e38aa3b, v152
	v_mul_f32_e32 v130, 0x3e38aa3b, v134
	v_cvt_pk_bf16_f32 v144, v129, v130
	ds_bpermute_b32 v137, v149, v59
	s_waitcnt lgkmcnt(1)
	v_mul_f32_e32 v155, v147, v128
	global_load_dwordx4 v[128:131], v[150:151], off offset:272
	s_nop 0
	global_load_dwordx4 v[150:153], v[150:151], off offset:256
	v_mov_b32_e32 v154, v63
	v_add_u32_e32 v134, 0x43, v148
	global_store_dwordx2 v[142:143], v[144:145], off nt
	s_waitcnt vmcnt(1)
	v_pk_mul_f32 v[150:151], v[154:155], v[150:151]
	s_nop 0
	v_add_f32_e32 v154, v150, v151
	s_waitcnt lgkmcnt(0)
	v_mul_f32_e32 v151, v147, v137
	v_mov_b32_e32 v150, v59
	v_pk_mul_f32 v[150:151], v[150:151], v[152:153]
	s_nop 0
	v_add_f32_e32 v137, v150, v151
	v_mul_f32_e32 v151, v147, v156
	v_mov_b32_e32 v150, v55
	v_pk_mul_f32 v[128:129], v[150:151], v[128:129]
	s_nop 0
	v_add_f32_e32 v150, v128, v129
	v_mul_f32_e32 v129, v147, v157
	v_mov_b32_e32 v128, v51
	v_pk_mul_f32 v[128:129], v[128:129], v[130:131]
	v_mul_f32_e32 v131, 0x3e38aa3b, v154
	v_add_f32_e32 v130, v128, v129
	v_mad_i64_i32 v[128:129], s[24:25], v134, s13, v[138:139]
	v_mul_f32_e32 v134, 0x3e38aa3b, v137
	v_mul_f32_e32 v137, 0x3e38aa3b, v150
	v_mul_f32_e32 v142, 0x3e38aa3b, v130
	v_cvt_pk_bf16_f32 v130, v131, v134
	v_cvt_pk_bf16_f32 v131, v137, v142
	global_store_dwordx2 v[128:129], v[130:131], off nt
	v_add_u32_e32 v137, 0x50, v148
	v_lshlrev_b32_e32 v128, 8, v137
	v_and_b32_e32 v134, 0x7fc00, v128
	ds_bpermute_b32 v128, v149, v44
	v_lshl_add_u64 v[150:151], v[140:141], 0, v[134:135]
	ds_bpermute_b32 v134, v149, v40
	ds_bpermute_b32 v154, v149, v36
	v_mov_b32_e32 v152, v44
	s_waitcnt lgkmcnt(2)
	v_mul_f32_e32 v153, v147, v128
	global_load_dwordx4 v[128:131], v[150:151], off offset:16
	global_load_dwordx4 v[142:145], v[150:151], off
	ds_bpermute_b32 v155, v149, v32
	ds_bpermute_b32 v156, v149, v37
	ds_bpermute_b32 v157, v149, v33
	s_waitcnt vmcnt(0)
	v_pk_mul_f32 v[142:143], v[152:153], v[142:143]
	s_nop 0
	v_add_f32_e32 v152, v142, v143
	s_waitcnt lgkmcnt(4)
	v_mul_f32_e32 v143, v147, v134
	v_mov_b32_e32 v142, v40
	v_pk_mul_f32 v[142:143], v[142:143], v[144:145]
	s_nop 0
	v_add_f32_e32 v134, v142, v143
	s_waitcnt lgkmcnt(3)
	v_mul_f32_e32 v143, v147, v154
	v_mov_b32_e32 v142, v36
	v_pk_mul_f32 v[128:129], v[142:143], v[128:129]
	v_mad_i64_i32 v[142:143], s[24:25], v137, s13, v[138:139]
	v_add_f32_e32 v144, v128, v129
	s_waitcnt lgkmcnt(2)
	v_mul_f32_e32 v129, v147, v155
	v_mov_b32_e32 v128, v32
	v_pk_mul_f32 v[128:129], v[128:129], v[130:131]
	v_mul_f32_e32 v131, 0x3e38aa3b, v144
	v_add_f32_e32 v128, v128, v129
	v_mul_f32_e32 v128, 0x3e38aa3b, v128
	v_cvt_pk_bf16_f32 v145, v131, v128
	ds_bpermute_b32 v128, v149, v45
	v_mul_f32_e32 v129, 0x3e38aa3b, v152
	v_mul_f32_e32 v130, 0x3e38aa3b, v134
	v_cvt_pk_bf16_f32 v144, v129, v130
	ds_bpermute_b32 v137, v149, v41
	s_waitcnt lgkmcnt(1)
	v_mul_f32_e32 v155, v147, v128
	global_load_dwordx4 v[128:131], v[150:151], off offset:272
	s_nop 0
	global_load_dwordx4 v[150:153], v[150:151], off offset:256
	v_mov_b32_e32 v154, v45
	v_add_u32_e32 v134, 0x51, v148
	global_store_dwordx2 v[142:143], v[144:145], off nt
	s_waitcnt vmcnt(1)
	v_pk_mul_f32 v[150:151], v[154:155], v[150:151]
	s_nop 0
	v_add_f32_e32 v154, v150, v151
	s_waitcnt lgkmcnt(0)
	v_mul_f32_e32 v151, v147, v137
	v_mov_b32_e32 v150, v41
	v_pk_mul_f32 v[150:151], v[150:151], v[152:153]
	s_nop 0
	v_add_f32_e32 v137, v150, v151
	v_mul_f32_e32 v151, v147, v156
	v_mov_b32_e32 v150, v37
	v_pk_mul_f32 v[128:129], v[150:151], v[128:129]
	s_nop 0
	v_add_f32_e32 v150, v128, v129
	v_mul_f32_e32 v129, v147, v157
	v_mov_b32_e32 v128, v33
	v_pk_mul_f32 v[128:129], v[128:129], v[130:131]
	v_mul_f32_e32 v131, 0x3e38aa3b, v154
	v_add_f32_e32 v130, v128, v129
	v_mad_i64_i32 v[128:129], s[24:25], v134, s13, v[138:139]
	v_mul_f32_e32 v134, 0x3e38aa3b, v137
	v_mul_f32_e32 v137, 0x3e38aa3b, v150
	v_mul_f32_e32 v142, 0x3e38aa3b, v130
	v_cvt_pk_bf16_f32 v130, v131, v134
	v_cvt_pk_bf16_f32 v131, v137, v142
	global_store_dwordx2 v[128:129], v[130:131], off nt
	v_add_u32_e32 v137, 0x52, v148
	v_lshlrev_b32_e32 v128, 8, v137
	v_and_b32_e32 v134, 0x7fe00, v128
	ds_bpermute_b32 v128, v149, v46
	v_lshl_add_u64 v[150:151], v[140:141], 0, v[134:135]
	ds_bpermute_b32 v134, v149, v42
	ds_bpermute_b32 v154, v149, v38
	v_mov_b32_e32 v152, v46
	s_waitcnt lgkmcnt(2)
	v_mul_f32_e32 v153, v147, v128
	global_load_dwordx4 v[128:131], v[150:151], off offset:16
	global_load_dwordx4 v[142:145], v[150:151], off
	ds_bpermute_b32 v155, v149, v34
	ds_bpermute_b32 v156, v149, v39
	ds_bpermute_b32 v157, v149, v35
	s_waitcnt vmcnt(0)
	v_pk_mul_f32 v[142:143], v[152:153], v[142:143]
	s_nop 0
	v_add_f32_e32 v152, v142, v143
	s_waitcnt lgkmcnt(4)
	v_mul_f32_e32 v143, v147, v134
	v_mov_b32_e32 v142, v42
	v_pk_mul_f32 v[142:143], v[142:143], v[144:145]
	s_nop 0
	v_add_f32_e32 v134, v142, v143
	s_waitcnt lgkmcnt(3)
	v_mul_f32_e32 v143, v147, v154
	v_mov_b32_e32 v142, v38
	v_pk_mul_f32 v[128:129], v[142:143], v[128:129]
	v_mad_i64_i32 v[142:143], s[24:25], v137, s13, v[138:139]
	v_add_f32_e32 v144, v128, v129
	s_waitcnt lgkmcnt(2)
	v_mul_f32_e32 v129, v147, v155
	v_mov_b32_e32 v128, v34
	v_pk_mul_f32 v[128:129], v[128:129], v[130:131]
	v_mul_f32_e32 v131, 0x3e38aa3b, v144
	v_add_f32_e32 v128, v128, v129
	v_mul_f32_e32 v128, 0x3e38aa3b, v128
	v_cvt_pk_bf16_f32 v145, v131, v128
	ds_bpermute_b32 v128, v149, v47
	v_mul_f32_e32 v129, 0x3e38aa3b, v152
	v_mul_f32_e32 v130, 0x3e38aa3b, v134
	v_cvt_pk_bf16_f32 v144, v129, v130
	ds_bpermute_b32 v137, v149, v43
	s_waitcnt lgkmcnt(1)
	v_mul_f32_e32 v155, v147, v128
	global_load_dwordx4 v[128:131], v[150:151], off offset:272
	s_nop 0
	global_load_dwordx4 v[150:153], v[150:151], off offset:256
	v_mov_b32_e32 v154, v47
	v_add_u32_e32 v134, 0x53, v148
	global_store_dwordx2 v[142:143], v[144:145], off nt
	s_waitcnt vmcnt(1)
	v_pk_mul_f32 v[150:151], v[154:155], v[150:151]
	s_nop 0
	v_add_f32_e32 v154, v150, v151
	s_waitcnt lgkmcnt(0)
	v_mul_f32_e32 v151, v147, v137
	v_mov_b32_e32 v150, v43
	v_pk_mul_f32 v[150:151], v[150:151], v[152:153]
	s_nop 0
	v_add_f32_e32 v137, v150, v151
	v_mul_f32_e32 v151, v147, v156
	v_mov_b32_e32 v150, v39
	v_pk_mul_f32 v[128:129], v[150:151], v[128:129]
	s_nop 0
	v_add_f32_e32 v150, v128, v129
	v_mul_f32_e32 v129, v147, v157
	v_mov_b32_e32 v128, v35
	v_pk_mul_f32 v[128:129], v[128:129], v[130:131]
	v_mul_f32_e32 v131, 0x3e38aa3b, v154
	v_add_f32_e32 v130, v128, v129
	v_mad_i64_i32 v[128:129], s[24:25], v134, s13, v[138:139]
	v_mul_f32_e32 v134, 0x3e38aa3b, v137
	v_mul_f32_e32 v137, 0x3e38aa3b, v150
	v_mul_f32_e32 v142, 0x3e38aa3b, v130
	v_cvt_pk_bf16_f32 v130, v131, v134
	v_cvt_pk_bf16_f32 v131, v137, v142
	global_store_dwordx2 v[128:129], v[130:131], off nt
	v_add_u32_e32 v137, 0x60, v148
	v_lshlrev_b32_e32 v128, 8, v137
	v_and_b32_e32 v134, 0x7fc00, v128
	ds_bpermute_b32 v128, v149, v28
	v_lshl_add_u64 v[150:151], v[140:141], 0, v[134:135]
	ds_bpermute_b32 v134, v149, v24
	ds_bpermute_b32 v154, v149, v20
	v_mov_b32_e32 v152, v28
	s_waitcnt lgkmcnt(2)
	v_mul_f32_e32 v153, v147, v128
	global_load_dwordx4 v[128:131], v[150:151], off offset:16
	global_load_dwordx4 v[142:145], v[150:151], off
	ds_bpermute_b32 v155, v149, v16
	ds_bpermute_b32 v156, v149, v21
	ds_bpermute_b32 v157, v149, v17
	s_waitcnt vmcnt(0)
	v_pk_mul_f32 v[142:143], v[152:153], v[142:143]
	s_nop 0
	v_add_f32_e32 v152, v142, v143
	s_waitcnt lgkmcnt(4)
	v_mul_f32_e32 v143, v147, v134
	v_mov_b32_e32 v142, v24
	v_pk_mul_f32 v[142:143], v[142:143], v[144:145]
	s_nop 0
	v_add_f32_e32 v134, v142, v143
	s_waitcnt lgkmcnt(3)
	v_mul_f32_e32 v143, v147, v154
	v_mov_b32_e32 v142, v20
	v_pk_mul_f32 v[128:129], v[142:143], v[128:129]
	v_mad_i64_i32 v[142:143], s[24:25], v137, s13, v[138:139]
	v_add_f32_e32 v144, v128, v129
	s_waitcnt lgkmcnt(2)
	v_mul_f32_e32 v129, v147, v155
	v_mov_b32_e32 v128, v16
	v_pk_mul_f32 v[128:129], v[128:129], v[130:131]
	v_mul_f32_e32 v131, 0x3e38aa3b, v144
	v_add_f32_e32 v128, v128, v129
	v_mul_f32_e32 v128, 0x3e38aa3b, v128
	v_cvt_pk_bf16_f32 v145, v131, v128
	ds_bpermute_b32 v128, v149, v29
	v_mul_f32_e32 v129, 0x3e38aa3b, v152
	v_mul_f32_e32 v130, 0x3e38aa3b, v134
	v_cvt_pk_bf16_f32 v144, v129, v130
	ds_bpermute_b32 v137, v149, v25
	s_waitcnt lgkmcnt(1)
	v_mul_f32_e32 v155, v147, v128
	global_load_dwordx4 v[128:131], v[150:151], off offset:272
	s_nop 0
	global_load_dwordx4 v[150:153], v[150:151], off offset:256
	v_mov_b32_e32 v154, v29
	v_add_u32_e32 v134, 0x61, v148
	global_store_dwordx2 v[142:143], v[144:145], off nt
	s_waitcnt vmcnt(1)
	v_pk_mul_f32 v[150:151], v[154:155], v[150:151]
	s_nop 0
	v_add_f32_e32 v154, v150, v151
	s_waitcnt lgkmcnt(0)
	v_mul_f32_e32 v151, v147, v137
	v_mov_b32_e32 v150, v25
	v_pk_mul_f32 v[150:151], v[150:151], v[152:153]
	s_nop 0
	v_add_f32_e32 v137, v150, v151
	v_mul_f32_e32 v151, v147, v156
	v_mov_b32_e32 v150, v21
	v_pk_mul_f32 v[128:129], v[150:151], v[128:129]
	s_nop 0
	v_add_f32_e32 v150, v128, v129
	v_mul_f32_e32 v129, v147, v157
	v_mov_b32_e32 v128, v17
	v_pk_mul_f32 v[128:129], v[128:129], v[130:131]
	v_mul_f32_e32 v131, 0x3e38aa3b, v154
	v_add_f32_e32 v130, v128, v129
	v_mad_i64_i32 v[128:129], s[24:25], v134, s13, v[138:139]
	v_mul_f32_e32 v134, 0x3e38aa3b, v137
	v_mul_f32_e32 v137, 0x3e38aa3b, v150
	v_mul_f32_e32 v142, 0x3e38aa3b, v130
	v_cvt_pk_bf16_f32 v130, v131, v134
	v_cvt_pk_bf16_f32 v131, v137, v142
	global_store_dwordx2 v[128:129], v[130:131], off nt
	v_add_u32_e32 v137, 0x62, v148
	v_lshlrev_b32_e32 v128, 8, v137
	v_and_b32_e32 v134, 0x7fe00, v128
	ds_bpermute_b32 v128, v149, v30
	v_lshl_add_u64 v[150:151], v[140:141], 0, v[134:135]
	ds_bpermute_b32 v134, v149, v26
	ds_bpermute_b32 v154, v149, v22
	v_mov_b32_e32 v152, v30
	s_waitcnt lgkmcnt(2)
	v_mul_f32_e32 v153, v147, v128
	global_load_dwordx4 v[128:131], v[150:151], off offset:16
	global_load_dwordx4 v[142:145], v[150:151], off
	ds_bpermute_b32 v155, v149, v18
	ds_bpermute_b32 v156, v149, v23
	ds_bpermute_b32 v157, v149, v19
	s_waitcnt vmcnt(0)
	v_pk_mul_f32 v[142:143], v[152:153], v[142:143]
	s_nop 0
	v_add_f32_e32 v152, v142, v143
	s_waitcnt lgkmcnt(4)
	v_mul_f32_e32 v143, v147, v134
	v_mov_b32_e32 v142, v26
	v_pk_mul_f32 v[142:143], v[142:143], v[144:145]
	s_nop 0
	v_add_f32_e32 v134, v142, v143
	s_waitcnt lgkmcnt(3)
	v_mul_f32_e32 v143, v147, v154
	v_mov_b32_e32 v142, v22
	v_pk_mul_f32 v[128:129], v[142:143], v[128:129]
	v_mad_i64_i32 v[142:143], s[24:25], v137, s13, v[138:139]
	v_add_f32_e32 v144, v128, v129
	s_waitcnt lgkmcnt(2)
	v_mul_f32_e32 v129, v147, v155
	v_mov_b32_e32 v128, v18
	v_pk_mul_f32 v[128:129], v[128:129], v[130:131]
	v_mul_f32_e32 v131, 0x3e38aa3b, v144
	v_add_f32_e32 v128, v128, v129
	v_mul_f32_e32 v128, 0x3e38aa3b, v128
	v_cvt_pk_bf16_f32 v145, v131, v128
	ds_bpermute_b32 v128, v149, v31
	v_mul_f32_e32 v129, 0x3e38aa3b, v152
	v_mul_f32_e32 v130, 0x3e38aa3b, v134
	v_cvt_pk_bf16_f32 v144, v129, v130
	ds_bpermute_b32 v137, v149, v27
	s_waitcnt lgkmcnt(1)
	v_mul_f32_e32 v155, v147, v128
	global_load_dwordx4 v[128:131], v[150:151], off offset:272
	s_nop 0
	global_load_dwordx4 v[150:153], v[150:151], off offset:256
	v_mov_b32_e32 v154, v31
	v_add_u32_e32 v134, 0x63, v148
	global_store_dwordx2 v[142:143], v[144:145], off nt
	s_waitcnt vmcnt(1)
	v_pk_mul_f32 v[150:151], v[154:155], v[150:151]
	s_nop 0
	v_add_f32_e32 v154, v150, v151
	s_waitcnt lgkmcnt(0)
	v_mul_f32_e32 v151, v147, v137
	v_mov_b32_e32 v150, v27
	v_pk_mul_f32 v[150:151], v[150:151], v[152:153]
	s_nop 0
	v_add_f32_e32 v137, v150, v151
	v_mul_f32_e32 v151, v147, v156
	v_mov_b32_e32 v150, v23
	v_pk_mul_f32 v[128:129], v[150:151], v[128:129]
	s_nop 0
	v_add_f32_e32 v150, v128, v129
	v_mul_f32_e32 v129, v147, v157
	v_mov_b32_e32 v128, v19
	v_pk_mul_f32 v[128:129], v[128:129], v[130:131]
	v_mul_f32_e32 v131, 0x3e38aa3b, v154
	v_add_f32_e32 v130, v128, v129
	v_mad_i64_i32 v[128:129], s[24:25], v134, s13, v[138:139]
	v_mul_f32_e32 v134, 0x3e38aa3b, v137
	v_mul_f32_e32 v137, 0x3e38aa3b, v150
	v_mul_f32_e32 v142, 0x3e38aa3b, v130
	v_cvt_pk_bf16_f32 v130, v131, v134
	v_cvt_pk_bf16_f32 v131, v137, v142
	global_store_dwordx2 v[128:129], v[130:131], off nt
	v_add_u32_e32 v137, 0x70, v148
	v_lshlrev_b32_e32 v128, 8, v137
	v_and_b32_e32 v134, 0x7fc00, v128
	ds_bpermute_b32 v128, v149, v12
	v_lshl_add_u64 v[150:151], v[140:141], 0, v[134:135]
	ds_bpermute_b32 v134, v149, v8
	ds_bpermute_b32 v154, v149, v4
	v_mov_b32_e32 v152, v12
	s_waitcnt lgkmcnt(2)
	v_mul_f32_e32 v153, v147, v128
	global_load_dwordx4 v[128:131], v[150:151], off offset:16
	global_load_dwordx4 v[142:145], v[150:151], off
	ds_bpermute_b32 v155, v149, v0
	ds_bpermute_b32 v156, v149, v5
	ds_bpermute_b32 v157, v149, v1
	s_waitcnt vmcnt(0)
	v_pk_mul_f32 v[142:143], v[152:153], v[142:143]
	s_nop 0
	v_add_f32_e32 v152, v142, v143
	s_waitcnt lgkmcnt(4)
	v_mul_f32_e32 v143, v147, v134
	v_mov_b32_e32 v142, v8
	v_pk_mul_f32 v[142:143], v[142:143], v[144:145]
	s_nop 0
	v_add_f32_e32 v134, v142, v143
	s_waitcnt lgkmcnt(3)
	v_mul_f32_e32 v143, v147, v154
	v_mov_b32_e32 v142, v4
	v_pk_mul_f32 v[128:129], v[142:143], v[128:129]
	v_mad_i64_i32 v[142:143], s[24:25], v137, s13, v[138:139]
	v_add_f32_e32 v144, v128, v129
	s_waitcnt lgkmcnt(2)
	v_mul_f32_e32 v129, v147, v155
	v_mov_b32_e32 v128, v0
	v_pk_mul_f32 v[128:129], v[128:129], v[130:131]
	v_mul_f32_e32 v131, 0x3e38aa3b, v144
	v_add_f32_e32 v128, v128, v129
	v_mul_f32_e32 v128, 0x3e38aa3b, v128
	v_cvt_pk_bf16_f32 v145, v131, v128
	ds_bpermute_b32 v128, v149, v13
	v_mul_f32_e32 v129, 0x3e38aa3b, v152
	v_mul_f32_e32 v130, 0x3e38aa3b, v134
	v_cvt_pk_bf16_f32 v144, v129, v130
	ds_bpermute_b32 v137, v149, v9
	s_waitcnt lgkmcnt(1)
	v_mul_f32_e32 v155, v147, v128
	global_load_dwordx4 v[128:131], v[150:151], off offset:272
	s_nop 0
	global_load_dwordx4 v[150:153], v[150:151], off offset:256
	v_mov_b32_e32 v154, v13
	v_add_u32_e32 v134, 0x71, v148
	global_store_dwordx2 v[142:143], v[144:145], off nt
	s_waitcnt vmcnt(1)
	v_pk_mul_f32 v[150:151], v[154:155], v[150:151]
	s_nop 0
	v_add_f32_e32 v154, v150, v151
	s_waitcnt lgkmcnt(0)
	v_mul_f32_e32 v151, v147, v137
	v_mov_b32_e32 v150, v9
	v_pk_mul_f32 v[150:151], v[150:151], v[152:153]
	s_nop 0
	v_add_f32_e32 v137, v150, v151
	v_mul_f32_e32 v151, v147, v156
	v_mov_b32_e32 v150, v5
	v_pk_mul_f32 v[128:129], v[150:151], v[128:129]
	s_nop 0
	v_add_f32_e32 v150, v128, v129
	v_mul_f32_e32 v129, v147, v157
	v_mov_b32_e32 v128, v1
	v_pk_mul_f32 v[128:129], v[128:129], v[130:131]
	v_mul_f32_e32 v131, 0x3e38aa3b, v154
	v_add_f32_e32 v130, v128, v129
	v_mad_i64_i32 v[128:129], s[24:25], v134, s13, v[138:139]
	v_mul_f32_e32 v134, 0x3e38aa3b, v137
	v_mul_f32_e32 v137, 0x3e38aa3b, v150
	v_mul_f32_e32 v142, 0x3e38aa3b, v130
	v_cvt_pk_bf16_f32 v130, v131, v134
	v_cvt_pk_bf16_f32 v131, v137, v142
	global_store_dwordx2 v[128:129], v[130:131], off nt
	v_add_u32_e32 v137, 0x72, v148
	v_lshlrev_b32_e32 v128, 8, v137
	v_and_b32_e32 v134, 0x7fe00, v128
	ds_bpermute_b32 v128, v149, v14
	v_lshl_add_u64 v[144:145], v[140:141], 0, v[134:135]
	ds_bpermute_b32 v134, v149, v10
	ds_bpermute_b32 v152, v149, v6
	v_mov_b32_e32 v150, v14
	s_waitcnt lgkmcnt(2)
	v_mul_f32_e32 v151, v147, v128
	global_load_dwordx4 v[128:131], v[144:145], off offset:16
	global_load_dwordx4 v[140:143], v[144:145], off
	ds_bpermute_b32 v153, v149, v2
	ds_bpermute_b32 v154, v149, v7
	ds_bpermute_b32 v155, v149, v3
	s_waitcnt vmcnt(0)
	v_pk_mul_f32 v[140:141], v[150:151], v[140:141]
	s_nop 0
	v_add_f32_e32 v150, v140, v141
	s_waitcnt lgkmcnt(4)
	v_mul_f32_e32 v141, v147, v134
	v_mov_b32_e32 v140, v10
	v_pk_mul_f32 v[140:141], v[140:141], v[142:143]
	s_nop 0
	v_add_f32_e32 v134, v140, v141
	s_waitcnt lgkmcnt(3)
	v_mul_f32_e32 v141, v147, v152
	v_mov_b32_e32 v140, v6
	v_pk_mul_f32 v[128:129], v[140:141], v[128:129]
	v_mad_i64_i32 v[140:141], s[24:25], v137, s13, v[138:139]
	v_add_f32_e32 v142, v128, v129
	s_waitcnt lgkmcnt(2)
	v_mul_f32_e32 v129, v147, v153
	v_mov_b32_e32 v128, v2
	v_pk_mul_f32 v[128:129], v[128:129], v[130:131]
	v_mul_f32_e32 v131, 0x3e38aa3b, v142
	v_add_f32_e32 v128, v128, v129
	v_mul_f32_e32 v128, 0x3e38aa3b, v128
	v_cvt_pk_bf16_f32 v143, v131, v128
	ds_bpermute_b32 v128, v149, v15
	v_mul_f32_e32 v129, 0x3e38aa3b, v150
	v_mul_f32_e32 v130, 0x3e38aa3b, v134
	v_cvt_pk_bf16_f32 v142, v129, v130
	v_add_u32_e32 v134, 0x73, v148
	ds_bpermute_b32 v137, v149, v11
	s_waitcnt lgkmcnt(1)
	v_mul_f32_e32 v153, v147, v128
	global_load_dwordx4 v[128:131], v[144:145], off offset:272
	global_load_dwordx4 v[148:151], v[144:145], off offset:256
	v_mov_b32_e32 v152, v15
	global_store_dwordx2 v[140:141], v[142:143], off nt
	s_waitcnt vmcnt(1)
	v_pk_mul_f32 v[144:145], v[152:153], v[148:149]
	s_nop 0
	v_add_f32_e32 v148, v144, v145
	s_waitcnt lgkmcnt(0)
	v_mul_f32_e32 v145, v147, v137
	v_mov_b32_e32 v144, v11
	v_pk_mul_f32 v[144:145], v[144:145], v[150:151]
	s_nop 0
	v_add_f32_e32 v137, v144, v145
	v_mul_f32_e32 v145, v147, v154
	v_mov_b32_e32 v144, v7
	v_pk_mul_f32 v[128:129], v[144:145], v[128:129]
	s_nop 0
	v_add_f32_e32 v144, v128, v129
	v_mul_f32_e32 v129, v147, v155
	v_mov_b32_e32 v128, v3
	v_pk_mul_f32 v[128:129], v[128:129], v[130:131]
	v_mul_f32_e32 v131, 0x3e38aa3b, v148
	v_add_f32_e32 v130, v128, v129
	v_mad_i64_i32 v[128:129], s[24:25], v134, s13, v[138:139]
	s_xor_b64 s[74:75], exec, -1
	v_mul_f32_e32 v134, 0x3e38aa3b, v137
	v_mul_f32_e32 v137, 0x3e38aa3b, v144
	v_mul_f32_e32 v138, 0x3e38aa3b, v130
	v_cvt_pk_bf16_f32 v130, v131, v134
	v_cvt_pk_bf16_f32 v131, v137, v138
	global_store_dwordx2 v[128:129], v[130:131], off nt

.LBB0_500:
	s_or_b64 exec, exec, s[8:9]
	v_lshl_add_u32 v128, v146, 2, v211
	v_ashrrev_i32_e32 v137, 31, v136
	v_ashrrev_i32_e32 v129, 31, v128
	v_or_b32_e32 v166, 1, v128
	v_or_b32_e32 v164, 2, v128
	v_or_b32_e32 v162, 3, v128
	v_add_u32_e32 v160, 16, v128
	v_add_u32_e32 v158, 17, v128
	v_add_u32_e32 v156, 18, v128
	v_add_u32_e32 v154, 19, v128
	v_add_u32_e32 v152, 32, v128
	v_add_u32_e32 v150, 33, v128
	v_add_u32_e32 v148, 34, v128
	v_add_u32_e32 v146, 35, v128
	v_add_u32_e32 v144, 48, v128
	v_add_u32_e32 v142, 49, v128
	v_add_u32_e32 v140, 50, v128
	v_add_u32_e32 v138, 51, v128
	v_add_u32_e32 v130, 64, v128
	s_and_saveexec_b64 s[8:9], s[66:67]
	s_cbranch_execz .LBB0_502
	v_cmp_eq_u32_e32 vcc, 7, v176
	v_mov_b32_e32 v131, 0x180
	v_readlane_b32 s36, v253, 44
	v_cndmask_b32_e32 v131, v252, v131, vcc
	v_cmp_ne_u32_e32 vcc, 3, v176
	v_readlane_b32 s42, v253, 50
	v_readlane_b32 s43, v253, 51
	v_cndmask_b32_e32 v131, 0, v131, vcc
	v_lshlrev_b32_e32 v134, 1, v131
	v_lshl_add_u64 v[168:169], s[42:43], 0, v[134:135]
	v_readlane_b32 s37, v253, 45
	v_readlane_b32 s38, v253, 46
	v_readlane_b32 s39, v253, 47
	v_readlane_b32 s40, v253, 48
	v_readlane_b32 s41, v253, 49
	v_readlane_b32 s44, v253, 52
	v_readlane_b32 s45, v253, 53
	v_readlane_b32 s46, v253, 54
	v_readlane_b32 s47, v253, 55
	v_readlane_b32 s48, v253, 56
	v_readlane_b32 s49, v253, 57
	v_readlane_b32 s50, v253, 58
	v_readlane_b32 s51, v253, 59
	v_lshl_add_u64 v[168:169], v[136:137], 1, v[168:169]
	v_mul_f32_e32 v131, 0xbfb8aa3b, v124
	v_mul_f32_e32 v134, 0xbfb8aa3b, v120
	v_mul_f32_e32 v139, 0xbfb8aa3b, v116
	v_mul_f32_e32 v141, 0xbfb8aa3b, v112
	v_exp_f32_e32 v131, v131
	v_exp_f32_e32 v134, v134
	v_exp_f32_e32 v139, v139
	v_exp_f32_e32 v141, v141
	v_add_f32_e32 v131, 1.0, v131
	v_add_f32_e32 v134, 1.0, v134
	v_add_f32_e32 v139, 1.0, v139
	v_add_f32_e32 v141, 1.0, v141
	v_rcp_f32_e32 v131, v131
	v_rcp_f32_e32 v134, v134
	v_rcp_f32_e32 v139, v139
	v_rcp_f32_e32 v141, v141
	v_lshlrev_b64 v[170:171], 11, v[128:129]
	v_lshl_add_u64 v[170:171], v[168:169], 0, v[170:171]
	v_mul_f32_e32 v131, v124, v131
	v_mul_f32_e32 v134, v120, v134
	v_mul_f32_e32 v139, v116, v139
	v_mul_f32_e32 v141, v112, v141
	v_cvt_pk_bf16_f32 v172, v131, v134
	v_cvt_pk_bf16_f32 v173, v139, v141
	global_store_dwordx2 v[170:171], v[172:173], off nt
	v_mul_f32_e32 v131, 0xbfb8aa3b, v125
	v_mul_f32_e32 v134, 0xbfb8aa3b, v121
	v_mul_f32_e32 v139, 0xbfb8aa3b, v117
	v_mul_f32_e32 v141, 0xbfb8aa3b, v113
	v_exp_f32_e32 v131, v131
	v_exp_f32_e32 v134, v134
	v_exp_f32_e32 v139, v139
	v_exp_f32_e32 v141, v141
	v_add_f32_e32 v131, 1.0, v131
	v_add_f32_e32 v134, 1.0, v134
	v_add_f32_e32 v139, 1.0, v139
	v_add_f32_e32 v141, 1.0, v141
	v_rcp_f32_e32 v131, v131
	v_rcp_f32_e32 v134, v134
	v_rcp_f32_e32 v139, v139
	v_rcp_f32_e32 v141, v141
	v_ashrrev_i32_e32 v167, 31, v166
	v_lshlrev_b64 v[170:171], 11, v[166:167]
	v_lshl_add_u64 v[170:171], v[168:169], 0, v[170:171]
	v_mul_f32_e32 v131, v125, v131
	v_mul_f32_e32 v134, v121, v134
	v_mul_f32_e32 v139, v117, v139
	v_mul_f32_e32 v141, v113, v141
	v_cvt_pk_bf16_f32 v172, v131, v134
	v_cvt_pk_bf16_f32 v173, v139, v141
	global_store_dwordx2 v[170:171], v[172:173], off nt
	v_mul_f32_e32 v131, 0xbfb8aa3b, v126
	v_mul_f32_e32 v134, 0xbfb8aa3b, v122
	v_mul_f32_e32 v139, 0xbfb8aa3b, v118
	v_mul_f32_e32 v141, 0xbfb8aa3b, v114
	v_exp_f32_e32 v131, v131
	v_exp_f32_e32 v134, v134
	v_exp_f32_e32 v139, v139
	v_exp_f32_e32 v141, v141
	v_add_f32_e32 v131, 1.0, v131
	v_add_f32_e32 v134, 1.0, v134
	v_add_f32_e32 v139, 1.0, v139
	v_add_f32_e32 v141, 1.0, v141
	v_rcp_f32_e32 v131, v131
	v_rcp_f32_e32 v134, v134
	v_rcp_f32_e32 v139, v139
	v_rcp_f32_e32 v141, v141
	v_ashrrev_i32_e32 v165, 31, v164
	v_lshlrev_b64 v[170:171], 11, v[164:165]
	v_lshl_add_u64 v[170:171], v[168:169], 0, v[170:171]
	v_mul_f32_e32 v131, v126, v131
	v_mul_f32_e32 v134, v122, v134
	v_mul_f32_e32 v139, v118, v139
	v_mul_f32_e32 v141, v114, v141
	v_cvt_pk_bf16_f32 v172, v131, v134
	v_cvt_pk_bf16_f32 v173, v139, v141
	global_store_dwordx2 v[170:171], v[172:173], off nt
	v_mul_f32_e32 v131, 0xbfb8aa3b, v127
	v_mul_f32_e32 v134, 0xbfb8aa3b, v123
	v_mul_f32_e32 v139, 0xbfb8aa3b, v119
	v_mul_f32_e32 v141, 0xbfb8aa3b, v115
	v_exp_f32_e32 v131, v131
	v_exp_f32_e32 v134, v134
	v_exp_f32_e32 v139, v139
	v_exp_f32_e32 v141, v141
	v_add_f32_e32 v131, 1.0, v131
	v_add_f32_e32 v134, 1.0, v134
	v_add_f32_e32 v139, 1.0, v139
	v_add_f32_e32 v141, 1.0, v141
	v_rcp_f32_e32 v131, v131
	v_rcp_f32_e32 v134, v134
	v_rcp_f32_e32 v139, v139
	v_rcp_f32_e32 v141, v141
	v_ashrrev_i32_e32 v163, 31, v162
	v_lshlrev_b64 v[170:171], 11, v[162:163]
	v_lshl_add_u64 v[170:171], v[168:169], 0, v[170:171]
	v_mul_f32_e32 v131, v127, v131
	v_mul_f32_e32 v134, v123, v134
	v_mul_f32_e32 v139, v119, v139
	v_mul_f32_e32 v141, v115, v141
	v_cvt_pk_bf16_f32 v172, v131, v134
	v_cvt_pk_bf16_f32 v173, v139, v141
	global_store_dwordx2 v[170:171], v[172:173], off nt
	v_mul_f32_e32 v131, 0xbfb8aa3b, v108
	v_mul_f32_e32 v134, 0xbfb8aa3b, v104
	v_mul_f32_e32 v139, 0xbfb8aa3b, v100
	v_mul_f32_e32 v141, 0xbfb8aa3b, v96
	v_exp_f32_e32 v131, v131
	v_exp_f32_e32 v134, v134
	v_exp_f32_e32 v139, v139
	v_exp_f32_e32 v141, v141
	v_add_f32_e32 v131, 1.0, v131
	v_add_f32_e32 v134, 1.0, v134
	v_add_f32_e32 v139, 1.0, v139
	v_add_f32_e32 v141, 1.0, v141
	v_rcp_f32_e32 v131, v131
	v_rcp_f32_e32 v134, v134
	v_rcp_f32_e32 v139, v139
	v_rcp_f32_e32 v141, v141
	v_ashrrev_i32_e32 v161, 31, v160
	v_lshlrev_b64 v[170:171], 11, v[160:161]
	v_lshl_add_u64 v[170:171], v[168:169], 0, v[170:171]
	v_mul_f32_e32 v131, v108, v131
	v_mul_f32_e32 v134, v104, v134
	v_mul_f32_e32 v139, v100, v139
	v_mul_f32_e32 v141, v96, v141
	v_cvt_pk_bf16_f32 v172, v131, v134
	v_cvt_pk_bf16_f32 v173, v139, v141
	global_store_dwordx2 v[170:171], v[172:173], off nt
	v_mul_f32_e32 v131, 0xbfb8aa3b, v109
	v_mul_f32_e32 v134, 0xbfb8aa3b, v105
	v_mul_f32_e32 v139, 0xbfb8aa3b, v101
	v_mul_f32_e32 v141, 0xbfb8aa3b, v97
	v_exp_f32_e32 v131, v131
	v_exp_f32_e32 v134, v134
	v_exp_f32_e32 v139, v139
	v_exp_f32_e32 v141, v141
	v_add_f32_e32 v131, 1.0, v131
	v_add_f32_e32 v134, 1.0, v134
	v_add_f32_e32 v139, 1.0, v139
	v_add_f32_e32 v141, 1.0, v141
	v_rcp_f32_e32 v131, v131
	v_rcp_f32_e32 v134, v134
	v_rcp_f32_e32 v139, v139
	v_rcp_f32_e32 v141, v141
	v_ashrrev_i32_e32 v159, 31, v158
	v_lshlrev_b64 v[170:171], 11, v[158:159]
	v_lshl_add_u64 v[170:171], v[168:169], 0, v[170:171]
	v_mul_f32_e32 v131, v109, v131
	v_mul_f32_e32 v134, v105, v134
	v_mul_f32_e32 v139, v101, v139
	v_mul_f32_e32 v141, v97, v141
	v_cvt_pk_bf16_f32 v172, v131, v134
	v_cvt_pk_bf16_f32 v173, v139, v141
	global_store_dwordx2 v[170:171], v[172:173], off nt
	v_mul_f32_e32 v131, 0xbfb8aa3b, v110
	v_mul_f32_e32 v134, 0xbfb8aa3b, v106
	v_mul_f32_e32 v139, 0xbfb8aa3b, v102
	v_mul_f32_e32 v141, 0xbfb8aa3b, v98
	v_exp_f32_e32 v131, v131
	v_exp_f32_e32 v134, v134
	v_exp_f32_e32 v139, v139
	v_exp_f32_e32 v141, v141
	v_add_f32_e32 v131, 1.0, v131
	v_add_f32_e32 v134, 1.0, v134
	v_add_f32_e32 v139, 1.0, v139
	v_add_f32_e32 v141, 1.0, v141
	v_rcp_f32_e32 v131, v131
	v_rcp_f32_e32 v134, v134
	v_rcp_f32_e32 v139, v139
	v_rcp_f32_e32 v141, v141
	v_ashrrev_i32_e32 v157, 31, v156
	v_lshlrev_b64 v[170:171], 11, v[156:157]
	v_lshl_add_u64 v[170:171], v[168:169], 0, v[170:171]
	v_mul_f32_e32 v131, v110, v131
	v_mul_f32_e32 v134, v106, v134
	v_mul_f32_e32 v139, v102, v139
	v_mul_f32_e32 v141, v98, v141
	v_cvt_pk_bf16_f32 v172, v131, v134
	v_cvt_pk_bf16_f32 v173, v139, v141
	global_store_dwordx2 v[170:171], v[172:173], off nt
	v_mul_f32_e32 v131, 0xbfb8aa3b, v111
	v_mul_f32_e32 v134, 0xbfb8aa3b, v107
	v_mul_f32_e32 v139, 0xbfb8aa3b, v103
	v_mul_f32_e32 v141, 0xbfb8aa3b, v99
	v_exp_f32_e32 v131, v131
	v_exp_f32_e32 v134, v134
	v_exp_f32_e32 v139, v139
	v_exp_f32_e32 v141, v141
	v_add_f32_e32 v131, 1.0, v131
	v_add_f32_e32 v134, 1.0, v134
	v_add_f32_e32 v139, 1.0, v139
	v_add_f32_e32 v141, 1.0, v141
	v_rcp_f32_e32 v131, v131
	v_rcp_f32_e32 v134, v134
	v_rcp_f32_e32 v139, v139
	v_rcp_f32_e32 v141, v141
	v_ashrrev_i32_e32 v155, 31, v154
	v_lshlrev_b64 v[170:171], 11, v[154:155]
	v_lshl_add_u64 v[170:171], v[168:169], 0, v[170:171]
	v_mul_f32_e32 v131, v111, v131
	v_mul_f32_e32 v134, v107, v134
	v_mul_f32_e32 v139, v103, v139
	v_mul_f32_e32 v141, v99, v141
	v_cvt_pk_bf16_f32 v172, v131, v134
	v_cvt_pk_bf16_f32 v173, v139, v141
	global_store_dwordx2 v[170:171], v[172:173], off nt
	v_mul_f32_e32 v131, 0xbfb8aa3b, v92
	v_mul_f32_e32 v134, 0xbfb8aa3b, v88
	v_mul_f32_e32 v139, 0xbfb8aa3b, v84
	v_mul_f32_e32 v141, 0xbfb8aa3b, v80
	v_exp_f32_e32 v131, v131
	v_exp_f32_e32 v134, v134
	v_exp_f32_e32 v139, v139
	v_exp_f32_e32 v141, v141
	v_add_f32_e32 v131, 1.0, v131
	v_add_f32_e32 v134, 1.0, v134
	v_add_f32_e32 v139, 1.0, v139
	v_add_f32_e32 v141, 1.0, v141
	v_rcp_f32_e32 v131, v131
	v_rcp_f32_e32 v134, v134
	v_rcp_f32_e32 v139, v139
	v_rcp_f32_e32 v141, v141
	v_ashrrev_i32_e32 v153, 31, v152
	v_lshlrev_b64 v[170:171], 11, v[152:153]
	v_lshl_add_u64 v[170:171], v[168:169], 0, v[170:171]
	v_mul_f32_e32 v131, v92, v131
	v_mul_f32_e32 v134, v88, v134
	v_mul_f32_e32 v139, v84, v139
	v_mul_f32_e32 v141, v80, v141
	v_cvt_pk_bf16_f32 v172, v131, v134
	v_cvt_pk_bf16_f32 v173, v139, v141
	global_store_dwordx2 v[170:171], v[172:173], off nt
	v_mul_f32_e32 v131, 0xbfb8aa3b, v93
	v_mul_f32_e32 v134, 0xbfb8aa3b, v89
	v_mul_f32_e32 v139, 0xbfb8aa3b, v85
	v_mul_f32_e32 v141, 0xbfb8aa3b, v81
	v_exp_f32_e32 v131, v131
	v_exp_f32_e32 v134, v134
	v_exp_f32_e32 v139, v139
	v_exp_f32_e32 v141, v141
	v_add_f32_e32 v131, 1.0, v131
	v_add_f32_e32 v134, 1.0, v134
	v_add_f32_e32 v139, 1.0, v139
	v_add_f32_e32 v141, 1.0, v141
	v_rcp_f32_e32 v131, v131
	v_rcp_f32_e32 v134, v134
	v_rcp_f32_e32 v139, v139
	v_rcp_f32_e32 v141, v141
	v_ashrrev_i32_e32 v151, 31, v150
	v_lshlrev_b64 v[170:171], 11, v[150:151]
	v_lshl_add_u64 v[170:171], v[168:169], 0, v[170:171]
	v_mul_f32_e32 v131, v93, v131
	v_mul_f32_e32 v134, v89, v134
	v_mul_f32_e32 v139, v85, v139
	v_mul_f32_e32 v141, v81, v141
	v_cvt_pk_bf16_f32 v172, v131, v134
	v_cvt_pk_bf16_f32 v173, v139, v141
	global_store_dwordx2 v[170:171], v[172:173], off nt
	v_mul_f32_e32 v131, 0xbfb8aa3b, v94
	v_mul_f32_e32 v134, 0xbfb8aa3b, v90
	v_mul_f32_e32 v139, 0xbfb8aa3b, v86
	v_mul_f32_e32 v141, 0xbfb8aa3b, v82
	v_exp_f32_e32 v131, v131
	v_exp_f32_e32 v134, v134
	v_exp_f32_e32 v139, v139
	v_exp_f32_e32 v141, v141
	v_add_f32_e32 v131, 1.0, v131
	v_add_f32_e32 v134, 1.0, v134
	v_add_f32_e32 v139, 1.0, v139
	v_add_f32_e32 v141, 1.0, v141
	v_rcp_f32_e32 v131, v131
	v_rcp_f32_e32 v134, v134
	v_rcp_f32_e32 v139, v139
	v_rcp_f32_e32 v141, v141
	v_ashrrev_i32_e32 v149, 31, v148
	v_lshlrev_b64 v[170:171], 11, v[148:149]
	v_lshl_add_u64 v[170:171], v[168:169], 0, v[170:171]
	v_mul_f32_e32 v131, v94, v131
	v_mul_f32_e32 v134, v90, v134
	v_mul_f32_e32 v139, v86, v139
	v_mul_f32_e32 v141, v82, v141
	v_cvt_pk_bf16_f32 v172, v131, v134
	v_cvt_pk_bf16_f32 v173, v139, v141
	global_store_dwordx2 v[170:171], v[172:173], off nt
	v_mul_f32_e32 v131, 0xbfb8aa3b, v95
	v_mul_f32_e32 v134, 0xbfb8aa3b, v91
	v_mul_f32_e32 v139, 0xbfb8aa3b, v87
	v_mul_f32_e32 v141, 0xbfb8aa3b, v83
	v_exp_f32_e32 v131, v131
	v_exp_f32_e32 v134, v134
	v_exp_f32_e32 v139, v139
	v_exp_f32_e32 v141, v141
	v_add_f32_e32 v131, 1.0, v131
	v_add_f32_e32 v134, 1.0, v134
	v_add_f32_e32 v139, 1.0, v139
	v_add_f32_e32 v141, 1.0, v141
	v_rcp_f32_e32 v131, v131
	v_rcp_f32_e32 v134, v134
	v_rcp_f32_e32 v139, v139
	v_rcp_f32_e32 v141, v141
	v_ashrrev_i32_e32 v147, 31, v146
	v_lshlrev_b64 v[170:171], 11, v[146:147]
	v_lshl_add_u64 v[170:171], v[168:169], 0, v[170:171]
	v_mul_f32_e32 v131, v95, v131
	v_mul_f32_e32 v134, v91, v134
	v_mul_f32_e32 v139, v87, v139
	v_mul_f32_e32 v141, v83, v141
	v_cvt_pk_bf16_f32 v172, v131, v134
	v_cvt_pk_bf16_f32 v173, v139, v141
	global_store_dwordx2 v[170:171], v[172:173], off nt
	v_mul_f32_e32 v131, 0xbfb8aa3b, v76
	v_mul_f32_e32 v134, 0xbfb8aa3b, v72
	v_mul_f32_e32 v139, 0xbfb8aa3b, v68
	v_mul_f32_e32 v141, 0xbfb8aa3b, v64
	v_exp_f32_e32 v131, v131
	v_exp_f32_e32 v134, v134
	v_exp_f32_e32 v139, v139
	v_exp_f32_e32 v141, v141
	v_add_f32_e32 v131, 1.0, v131
	v_add_f32_e32 v134, 1.0, v134
	v_add_f32_e32 v139, 1.0, v139
	v_add_f32_e32 v141, 1.0, v141
	v_rcp_f32_e32 v131, v131
	v_rcp_f32_e32 v134, v134
	v_rcp_f32_e32 v139, v139
	v_rcp_f32_e32 v141, v141
	v_ashrrev_i32_e32 v145, 31, v144
	v_lshlrev_b64 v[170:171], 11, v[144:145]
	v_lshl_add_u64 v[170:171], v[168:169], 0, v[170:171]
	v_mul_f32_e32 v131, v76, v131
	v_mul_f32_e32 v134, v72, v134
	v_mul_f32_e32 v139, v68, v139
	v_mul_f32_e32 v141, v64, v141
	v_cvt_pk_bf16_f32 v172, v131, v134
	v_cvt_pk_bf16_f32 v173, v139, v141
	global_store_dwordx2 v[170:171], v[172:173], off nt
	v_mul_f32_e32 v131, 0xbfb8aa3b, v77
	v_mul_f32_e32 v134, 0xbfb8aa3b, v73
	v_mul_f32_e32 v139, 0xbfb8aa3b, v69
	v_mul_f32_e32 v141, 0xbfb8aa3b, v65
	v_exp_f32_e32 v131, v131
	v_exp_f32_e32 v134, v134
	v_exp_f32_e32 v139, v139
	v_exp_f32_e32 v141, v141
	v_add_f32_e32 v131, 1.0, v131
	v_add_f32_e32 v134, 1.0, v134
	v_add_f32_e32 v139, 1.0, v139
	v_add_f32_e32 v141, 1.0, v141
	v_rcp_f32_e32 v131, v131
	v_rcp_f32_e32 v134, v134
	v_rcp_f32_e32 v139, v139
	v_rcp_f32_e32 v141, v141
	v_ashrrev_i32_e32 v143, 31, v142
	v_lshlrev_b64 v[170:171], 11, v[142:143]
	v_lshl_add_u64 v[170:171], v[168:169], 0, v[170:171]
	v_mul_f32_e32 v131, v77, v131
	v_mul_f32_e32 v134, v73, v134
	v_mul_f32_e32 v139, v69, v139
	v_mul_f32_e32 v141, v65, v141
	v_cvt_pk_bf16_f32 v172, v131, v134
	v_cvt_pk_bf16_f32 v173, v139, v141
	global_store_dwordx2 v[170:171], v[172:173], off nt
	v_ashrrev_i32_e32 v141, 31, v140
	v_lshlrev_b64 v[170:171], 11, v[140:141]
	v_mul_f32_e32 v131, 0xbfb8aa3b, v78
	v_mul_f32_e32 v134, 0xbfb8aa3b, v74
	v_mul_f32_e32 v139, 0xbfb8aa3b, v70
	v_mul_f32_e32 v141, 0xbfb8aa3b, v66
	v_exp_f32_e32 v131, v131
	v_exp_f32_e32 v134, v134
	v_exp_f32_e32 v139, v139
	v_exp_f32_e32 v141, v141
	v_add_f32_e32 v131, 1.0, v131
	v_add_f32_e32 v134, 1.0, v134
	v_add_f32_e32 v139, 1.0, v139
	v_add_f32_e32 v141, 1.0, v141
	v_rcp_f32_e32 v131, v131
	v_rcp_f32_e32 v134, v134
	v_rcp_f32_e32 v139, v139
	v_rcp_f32_e32 v141, v141
	v_lshl_add_u64 v[170:171], v[168:169], 0, v[170:171]
	v_mul_f32_e32 v131, v78, v131
	v_mul_f32_e32 v134, v74, v134
	v_mul_f32_e32 v139, v70, v139
	v_mul_f32_e32 v141, v66, v141
	v_cvt_pk_bf16_f32 v172, v131, v134
	v_cvt_pk_bf16_f32 v173, v139, v141
	global_store_dwordx2 v[170:171], v[172:173], off nt
	v_ashrrev_i32_e32 v139, 31, v138
	v_lshlrev_b64 v[170:171], 11, v[138:139]
	v_mul_f32_e32 v131, 0xbfb8aa3b, v79
	v_mul_f32_e32 v134, 0xbfb8aa3b, v75
	v_mul_f32_e32 v139, 0xbfb8aa3b, v71
	v_mul_f32_e32 v141, 0xbfb8aa3b, v67
	v_exp_f32_e32 v131, v131
	v_exp_f32_e32 v134, v134
	v_exp_f32_e32 v139, v139
	v_exp_f32_e32 v141, v141
	v_add_f32_e32 v131, 1.0, v131
	v_add_f32_e32 v134, 1.0, v134
	v_add_f32_e32 v139, 1.0, v139
	v_add_f32_e32 v141, 1.0, v141
	v_rcp_f32_e32 v131, v131
	v_rcp_f32_e32 v134, v134
	v_rcp_f32_e32 v139, v139
	v_rcp_f32_e32 v141, v141
	v_lshl_add_u64 v[170:171], v[168:169], 0, v[170:171]
	v_mul_f32_e32 v131, v79, v131
	v_mul_f32_e32 v134, v75, v134
	v_mul_f32_e32 v139, v71, v139
	v_mul_f32_e32 v141, v67, v141
	v_cvt_pk_bf16_f32 v172, v131, v134
	v_cvt_pk_bf16_f32 v173, v139, v141
	global_store_dwordx2 v[170:171], v[172:173], off nt
	v_ashrrev_i32_e32 v131, 31, v130
	v_lshlrev_b64 v[170:171], 11, v[130:131]
	v_mul_f32_e32 v131, 0xbfb8aa3b, v60
	v_mul_f32_e32 v134, 0xbfb8aa3b, v56
	v_mul_f32_e32 v139, 0xbfb8aa3b, v52
	v_mul_f32_e32 v141, 0xbfb8aa3b, v48
	v_exp_f32_e32 v131, v131
	v_exp_f32_e32 v134, v134
	v_exp_f32_e32 v139, v139
	v_exp_f32_e32 v141, v141
	v_add_f32_e32 v131, 1.0, v131
	v_add_f32_e32 v134, 1.0, v134
	v_add_f32_e32 v139, 1.0, v139
	v_add_f32_e32 v141, 1.0, v141
	v_rcp_f32_e32 v131, v131
	v_rcp_f32_e32 v134, v134
	v_rcp_f32_e32 v139, v139
	v_rcp_f32_e32 v141, v141
	v_lshl_add_u64 v[170:171], v[168:169], 0, v[170:171]
	v_mul_f32_e32 v131, v60, v131
	v_mul_f32_e32 v134, v56, v134
	v_mul_f32_e32 v139, v52, v139
	v_mul_f32_e32 v141, v48, v141
	v_cvt_pk_bf16_f32 v172, v131, v134
	v_cvt_pk_bf16_f32 v173, v139, v141
	global_store_dwordx2 v[170:171], v[172:173], off nt
	v_mul_f32_e32 v131, 0xbfb8aa3b, v61
	v_mul_f32_e32 v134, 0xbfb8aa3b, v57
	v_mul_f32_e32 v139, 0xbfb8aa3b, v53
	v_mul_f32_e32 v141, 0xbfb8aa3b, v49
	v_exp_f32_e32 v131, v131
	v_exp_f32_e32 v134, v134
	v_exp_f32_e32 v139, v139
	v_exp_f32_e32 v141, v141
	v_add_f32_e32 v131, 1.0, v131
	v_add_f32_e32 v134, 1.0, v134
	v_add_f32_e32 v139, 1.0, v139
	v_add_f32_e32 v141, 1.0, v141
	v_add_u32_e32 v170, 0x41, v128
	v_rcp_f32_e32 v131, v131
	v_rcp_f32_e32 v134, v134
	v_rcp_f32_e32 v139, v139
	v_rcp_f32_e32 v141, v141
	v_ashrrev_i32_e32 v171, 31, v170
	v_lshlrev_b64 v[170:171], 11, v[170:171]
	v_lshl_add_u64 v[170:171], v[168:169], 0, v[170:171]
	v_mul_f32_e32 v131, v61, v131
	v_mul_f32_e32 v134, v57, v134
	v_mul_f32_e32 v139, v53, v139
	v_mul_f32_e32 v141, v49, v141
	v_cvt_pk_bf16_f32 v172, v131, v134
	v_cvt_pk_bf16_f32 v173, v139, v141
	global_store_dwordx2 v[170:171], v[172:173], off nt
	v_mul_f32_e32 v131, 0xbfb8aa3b, v62
	v_mul_f32_e32 v134, 0xbfb8aa3b, v58
	v_mul_f32_e32 v139, 0xbfb8aa3b, v54
	v_mul_f32_e32 v141, 0xbfb8aa3b, v50
	v_exp_f32_e32 v131, v131
	v_exp_f32_e32 v134, v134
	v_exp_f32_e32 v139, v139
	v_exp_f32_e32 v141, v141
	v_add_f32_e32 v131, 1.0, v131
	v_add_f32_e32 v134, 1.0, v134
	v_add_f32_e32 v139, 1.0, v139
	v_add_f32_e32 v141, 1.0, v141
	v_add_u32_e32 v170, 0x42, v128
	v_rcp_f32_e32 v131, v131
	v_rcp_f32_e32 v134, v134
	v_rcp_f32_e32 v139, v139
	v_rcp_f32_e32 v141, v141
	v_ashrrev_i32_e32 v171, 31, v170
	v_lshlrev_b64 v[170:171], 11, v[170:171]
	v_lshl_add_u64 v[170:171], v[168:169], 0, v[170:171]
	v_mul_f32_e32 v131, v62, v131
	v_mul_f32_e32 v134, v58, v134
	v_mul_f32_e32 v139, v54, v139
	v_mul_f32_e32 v141, v50, v141
	v_cvt_pk_bf16_f32 v172, v131, v134
	v_cvt_pk_bf16_f32 v173, v139, v141
	global_store_dwordx2 v[170:171], v[172:173], off nt
	v_mul_f32_e32 v131, 0xbfb8aa3b, v63
	v_mul_f32_e32 v134, 0xbfb8aa3b, v59
	v_mul_f32_e32 v139, 0xbfb8aa3b, v55
	v_mul_f32_e32 v141, 0xbfb8aa3b, v51
	v_exp_f32_e32 v131, v131
	v_exp_f32_e32 v134, v134
	v_exp_f32_e32 v139, v139
	v_exp_f32_e32 v141, v141
	v_add_f32_e32 v131, 1.0, v131
	v_add_f32_e32 v134, 1.0, v134
	v_add_f32_e32 v139, 1.0, v139
	v_add_f32_e32 v141, 1.0, v141
	v_add_u32_e32 v170, 0x43, v128
	v_rcp_f32_e32 v131, v131
	v_rcp_f32_e32 v134, v134
	v_rcp_f32_e32 v139, v139
	v_rcp_f32_e32 v141, v141
	v_ashrrev_i32_e32 v171, 31, v170
	v_lshlrev_b64 v[170:171], 11, v[170:171]
	v_lshl_add_u64 v[170:171], v[168:169], 0, v[170:171]
	v_mul_f32_e32 v131, v63, v131
	v_mul_f32_e32 v134, v59, v134
	v_mul_f32_e32 v139, v55, v139
	v_mul_f32_e32 v141, v51, v141
	v_cvt_pk_bf16_f32 v172, v131, v134
	v_cvt_pk_bf16_f32 v173, v139, v141
	global_store_dwordx2 v[170:171], v[172:173], off nt
	v_add_u32_e32 v170, 0x50, v128
	v_mul_f32_e32 v131, 0xbfb8aa3b, v44
	v_mul_f32_e32 v134, 0xbfb8aa3b, v40
	v_mul_f32_e32 v139, 0xbfb8aa3b, v36
	v_mul_f32_e32 v141, 0xbfb8aa3b, v32
	v_exp_f32_e32 v131, v131
	v_exp_f32_e32 v134, v134
	v_exp_f32_e32 v139, v139
	v_exp_f32_e32 v141, v141
	v_add_f32_e32 v131, 1.0, v131
	v_add_f32_e32 v134, 1.0, v134
	v_add_f32_e32 v139, 1.0, v139
	v_add_f32_e32 v141, 1.0, v141
	v_rcp_f32_e32 v131, v131
	v_rcp_f32_e32 v134, v134
	v_rcp_f32_e32 v139, v139
	v_rcp_f32_e32 v141, v141
	v_ashrrev_i32_e32 v171, 31, v170
	v_lshlrev_b64 v[170:171], 11, v[170:171]
	v_lshl_add_u64 v[170:171], v[168:169], 0, v[170:171]
	v_mul_f32_e32 v131, v44, v131
	v_mul_f32_e32 v134, v40, v134
	v_mul_f32_e32 v139, v36, v139
	v_mul_f32_e32 v141, v32, v141
	v_cvt_pk_bf16_f32 v172, v131, v134
	v_cvt_pk_bf16_f32 v173, v139, v141
	global_store_dwordx2 v[170:171], v[172:173], off nt
	v_mul_f32_e32 v131, 0xbfb8aa3b, v45
	v_mul_f32_e32 v134, 0xbfb8aa3b, v41
	v_mul_f32_e32 v139, 0xbfb8aa3b, v37
	v_mul_f32_e32 v141, 0xbfb8aa3b, v33
	v_exp_f32_e32 v131, v131
	v_exp_f32_e32 v134, v134
	v_exp_f32_e32 v139, v139
	v_exp_f32_e32 v141, v141
	v_add_f32_e32 v131, 1.0, v131
	v_add_f32_e32 v134, 1.0, v134
	v_add_f32_e32 v139, 1.0, v139
	v_add_f32_e32 v141, 1.0, v141
	v_add_u32_e32 v170, 0x51, v128
	v_rcp_f32_e32 v131, v131
	v_rcp_f32_e32 v134, v134
	v_rcp_f32_e32 v139, v139
	v_rcp_f32_e32 v141, v141
	v_ashrrev_i32_e32 v171, 31, v170
	v_lshlrev_b64 v[170:171], 11, v[170:171]
	v_lshl_add_u64 v[170:171], v[168:169], 0, v[170:171]
	v_mul_f32_e32 v131, v45, v131
	v_mul_f32_e32 v134, v41, v134
	v_mul_f32_e32 v139, v37, v139
	v_mul_f32_e32 v141, v33, v141
	v_cvt_pk_bf16_f32 v172, v131, v134
	v_cvt_pk_bf16_f32 v173, v139, v141
	global_store_dwordx2 v[170:171], v[172:173], off nt
	v_mul_f32_e32 v131, 0xbfb8aa3b, v46
	v_mul_f32_e32 v134, 0xbfb8aa3b, v42
	v_mul_f32_e32 v139, 0xbfb8aa3b, v38
	v_mul_f32_e32 v141, 0xbfb8aa3b, v34
	v_exp_f32_e32 v131, v131
	v_exp_f32_e32 v134, v134
	v_exp_f32_e32 v139, v139
	v_exp_f32_e32 v141, v141
	v_add_f32_e32 v131, 1.0, v131
	v_add_f32_e32 v134, 1.0, v134
	v_add_f32_e32 v139, 1.0, v139
	v_add_f32_e32 v141, 1.0, v141
	v_add_u32_e32 v170, 0x52, v128
	v_rcp_f32_e32 v131, v131
	v_rcp_f32_e32 v134, v134
	v_rcp_f32_e32 v139, v139
	v_rcp_f32_e32 v141, v141
	v_ashrrev_i32_e32 v171, 31, v170
	v_lshlrev_b64 v[170:171], 11, v[170:171]
	v_lshl_add_u64 v[170:171], v[168:169], 0, v[170:171]
	v_mul_f32_e32 v131, v46, v131
	v_mul_f32_e32 v134, v42, v134
	v_mul_f32_e32 v139, v38, v139
	v_mul_f32_e32 v141, v34, v141
	v_cvt_pk_bf16_f32 v172, v131, v134
	v_cvt_pk_bf16_f32 v173, v139, v141
	global_store_dwordx2 v[170:171], v[172:173], off nt
	v_mul_f32_e32 v131, 0xbfb8aa3b, v47
	v_mul_f32_e32 v134, 0xbfb8aa3b, v43
	v_mul_f32_e32 v139, 0xbfb8aa3b, v39
	v_mul_f32_e32 v141, 0xbfb8aa3b, v35
	v_exp_f32_e32 v131, v131
	v_exp_f32_e32 v134, v134
	v_exp_f32_e32 v139, v139
	v_exp_f32_e32 v141, v141
	v_add_f32_e32 v131, 1.0, v131
	v_add_f32_e32 v134, 1.0, v134
	v_add_f32_e32 v139, 1.0, v139
	v_add_f32_e32 v141, 1.0, v141
	v_add_u32_e32 v170, 0x53, v128
	v_rcp_f32_e32 v131, v131
	v_rcp_f32_e32 v134, v134
	v_rcp_f32_e32 v139, v139
	v_rcp_f32_e32 v141, v141
	v_ashrrev_i32_e32 v171, 31, v170
	v_lshlrev_b64 v[170:171], 11, v[170:171]
	v_lshl_add_u64 v[170:171], v[168:169], 0, v[170:171]
	v_mul_f32_e32 v131, v47, v131
	v_mul_f32_e32 v134, v43, v134
	v_mul_f32_e32 v139, v39, v139
	v_mul_f32_e32 v141, v35, v141
	v_cvt_pk_bf16_f32 v172, v131, v134
	v_cvt_pk_bf16_f32 v173, v139, v141
	global_store_dwordx2 v[170:171], v[172:173], off nt
	v_add_u32_e32 v170, 0x60, v128
	v_mul_f32_e32 v131, 0xbfb8aa3b, v28
	v_mul_f32_e32 v134, 0xbfb8aa3b, v24
	v_mul_f32_e32 v139, 0xbfb8aa3b, v20
	v_mul_f32_e32 v141, 0xbfb8aa3b, v16
	v_exp_f32_e32 v131, v131
	v_exp_f32_e32 v134, v134
	v_exp_f32_e32 v139, v139
	v_exp_f32_e32 v141, v141
	v_add_f32_e32 v131, 1.0, v131
	v_add_f32_e32 v134, 1.0, v134
	v_add_f32_e32 v139, 1.0, v139
	v_add_f32_e32 v141, 1.0, v141
	v_rcp_f32_e32 v131, v131
	v_rcp_f32_e32 v134, v134
	v_rcp_f32_e32 v139, v139
	v_rcp_f32_e32 v141, v141
	v_ashrrev_i32_e32 v171, 31, v170
	v_lshlrev_b64 v[170:171], 11, v[170:171]
	v_lshl_add_u64 v[170:171], v[168:169], 0, v[170:171]
	v_mul_f32_e32 v131, v28, v131
	v_mul_f32_e32 v134, v24, v134
	v_mul_f32_e32 v139, v20, v139
	v_mul_f32_e32 v141, v16, v141
	v_cvt_pk_bf16_f32 v172, v131, v134
	v_cvt_pk_bf16_f32 v173, v139, v141
	global_store_dwordx2 v[170:171], v[172:173], off nt
	v_mul_f32_e32 v131, 0xbfb8aa3b, v29
	v_mul_f32_e32 v134, 0xbfb8aa3b, v25
	v_mul_f32_e32 v139, 0xbfb8aa3b, v21
	v_mul_f32_e32 v141, 0xbfb8aa3b, v17
	v_exp_f32_e32 v131, v131
	v_exp_f32_e32 v134, v134
	v_exp_f32_e32 v139, v139
	v_exp_f32_e32 v141, v141
	v_add_f32_e32 v131, 1.0, v131
	v_add_f32_e32 v134, 1.0, v134
	v_add_f32_e32 v139, 1.0, v139
	v_add_f32_e32 v141, 1.0, v141
	v_add_u32_e32 v170, 0x61, v128
	v_rcp_f32_e32 v131, v131
	v_rcp_f32_e32 v134, v134
	v_rcp_f32_e32 v139, v139
	v_rcp_f32_e32 v141, v141
	v_ashrrev_i32_e32 v171, 31, v170
	v_lshlrev_b64 v[170:171], 11, v[170:171]
	v_lshl_add_u64 v[170:171], v[168:169], 0, v[170:171]
	v_mul_f32_e32 v131, v29, v131
	v_mul_f32_e32 v134, v25, v134
	v_mul_f32_e32 v139, v21, v139
	v_mul_f32_e32 v141, v17, v141
	v_cvt_pk_bf16_f32 v172, v131, v134
	v_cvt_pk_bf16_f32 v173, v139, v141
	global_store_dwordx2 v[170:171], v[172:173], off nt
	v_mul_f32_e32 v131, 0xbfb8aa3b, v30
	v_mul_f32_e32 v134, 0xbfb8aa3b, v26
	v_mul_f32_e32 v139, 0xbfb8aa3b, v22
	v_mul_f32_e32 v141, 0xbfb8aa3b, v18
	v_exp_f32_e32 v131, v131
	v_exp_f32_e32 v134, v134
	v_exp_f32_e32 v139, v139
	v_exp_f32_e32 v141, v141
	v_add_f32_e32 v131, 1.0, v131
	v_add_f32_e32 v134, 1.0, v134
	v_add_f32_e32 v139, 1.0, v139
	v_add_f32_e32 v141, 1.0, v141
	v_add_u32_e32 v170, 0x62, v128
	v_rcp_f32_e32 v131, v131
	v_rcp_f32_e32 v134, v134
	v_rcp_f32_e32 v139, v139
	v_rcp_f32_e32 v141, v141
	v_ashrrev_i32_e32 v171, 31, v170
	v_lshlrev_b64 v[170:171], 11, v[170:171]
	v_lshl_add_u64 v[170:171], v[168:169], 0, v[170:171]
	v_mul_f32_e32 v131, v30, v131
	v_mul_f32_e32 v134, v26, v134
	v_mul_f32_e32 v139, v22, v139
	v_mul_f32_e32 v141, v18, v141
	v_cvt_pk_bf16_f32 v172, v131, v134
	v_cvt_pk_bf16_f32 v173, v139, v141
	global_store_dwordx2 v[170:171], v[172:173], off nt
	v_mul_f32_e32 v131, 0xbfb8aa3b, v31
	v_mul_f32_e32 v134, 0xbfb8aa3b, v27
	v_mul_f32_e32 v139, 0xbfb8aa3b, v23
	v_mul_f32_e32 v141, 0xbfb8aa3b, v19
	v_exp_f32_e32 v131, v131
	v_exp_f32_e32 v134, v134
	v_exp_f32_e32 v139, v139
	v_exp_f32_e32 v141, v141
	v_add_f32_e32 v131, 1.0, v131
	v_add_f32_e32 v134, 1.0, v134
	v_add_f32_e32 v139, 1.0, v139
	v_add_f32_e32 v141, 1.0, v141
	v_add_u32_e32 v170, 0x63, v128
	v_rcp_f32_e32 v131, v131
	v_rcp_f32_e32 v134, v134
	v_rcp_f32_e32 v139, v139
	v_rcp_f32_e32 v141, v141
	v_ashrrev_i32_e32 v171, 31, v170
	v_lshlrev_b64 v[170:171], 11, v[170:171]
	v_lshl_add_u64 v[170:171], v[168:169], 0, v[170:171]
	v_mul_f32_e32 v131, v31, v131
	v_mul_f32_e32 v134, v27, v134
	v_mul_f32_e32 v139, v23, v139
	v_mul_f32_e32 v141, v19, v141
	v_cvt_pk_bf16_f32 v172, v131, v134
	v_cvt_pk_bf16_f32 v173, v139, v141
	global_store_dwordx2 v[170:171], v[172:173], off nt
	v_add_u32_e32 v170, 0x70, v128
	v_mul_f32_e32 v131, 0xbfb8aa3b, v12
	v_mul_f32_e32 v134, 0xbfb8aa3b, v8
	v_mul_f32_e32 v139, 0xbfb8aa3b, v4
	v_mul_f32_e32 v141, 0xbfb8aa3b, v0
	v_exp_f32_e32 v131, v131
	v_exp_f32_e32 v134, v134
	v_exp_f32_e32 v139, v139
	v_exp_f32_e32 v141, v141
	v_add_f32_e32 v131, 1.0, v131
	v_add_f32_e32 v134, 1.0, v134
	v_add_f32_e32 v139, 1.0, v139
	v_add_f32_e32 v141, 1.0, v141
	v_rcp_f32_e32 v131, v131
	v_rcp_f32_e32 v134, v134
	v_rcp_f32_e32 v139, v139
	v_rcp_f32_e32 v141, v141
	v_ashrrev_i32_e32 v171, 31, v170
	v_lshlrev_b64 v[170:171], 11, v[170:171]
	v_lshl_add_u64 v[170:171], v[168:169], 0, v[170:171]
	v_mul_f32_e32 v131, v12, v131
	v_mul_f32_e32 v134, v8, v134
	v_mul_f32_e32 v139, v4, v139
	v_mul_f32_e32 v141, v0, v141
	v_cvt_pk_bf16_f32 v172, v131, v134
	v_cvt_pk_bf16_f32 v173, v139, v141
	global_store_dwordx2 v[170:171], v[172:173], off nt
	v_mul_f32_e32 v131, 0xbfb8aa3b, v13
	v_mul_f32_e32 v134, 0xbfb8aa3b, v9
	v_mul_f32_e32 v139, 0xbfb8aa3b, v5
	v_mul_f32_e32 v141, 0xbfb8aa3b, v1
	v_exp_f32_e32 v131, v131
	v_exp_f32_e32 v134, v134
	v_exp_f32_e32 v139, v139
	v_exp_f32_e32 v141, v141
	v_add_f32_e32 v131, 1.0, v131
	v_add_f32_e32 v134, 1.0, v134
	v_add_f32_e32 v139, 1.0, v139
	v_add_f32_e32 v141, 1.0, v141
	v_add_u32_e32 v170, 0x71, v128
	v_rcp_f32_e32 v131, v131
	v_rcp_f32_e32 v134, v134
	v_rcp_f32_e32 v139, v139
	v_rcp_f32_e32 v141, v141
	v_ashrrev_i32_e32 v171, 31, v170
	v_lshlrev_b64 v[170:171], 11, v[170:171]
	v_lshl_add_u64 v[170:171], v[168:169], 0, v[170:171]
	v_mul_f32_e32 v131, v13, v131
	v_mul_f32_e32 v134, v9, v134
	v_mul_f32_e32 v139, v5, v139
	v_mul_f32_e32 v141, v1, v141
	v_cvt_pk_bf16_f32 v172, v131, v134
	v_cvt_pk_bf16_f32 v173, v139, v141
	global_store_dwordx2 v[170:171], v[172:173], off nt
	v_mul_f32_e32 v131, 0xbfb8aa3b, v14
	v_mul_f32_e32 v134, 0xbfb8aa3b, v10
	v_mul_f32_e32 v139, 0xbfb8aa3b, v6
	v_mul_f32_e32 v141, 0xbfb8aa3b, v2
	v_exp_f32_e32 v131, v131
	v_exp_f32_e32 v134, v134
	v_exp_f32_e32 v139, v139
	v_exp_f32_e32 v141, v141
	v_add_f32_e32 v131, 1.0, v131
	v_add_f32_e32 v134, 1.0, v134
	v_add_f32_e32 v139, 1.0, v139
	v_add_f32_e32 v141, 1.0, v141
	v_add_u32_e32 v170, 0x72, v128
	v_rcp_f32_e32 v131, v131
	v_rcp_f32_e32 v134, v134
	v_rcp_f32_e32 v139, v139
	v_rcp_f32_e32 v141, v141
	v_ashrrev_i32_e32 v171, 31, v170
	v_lshlrev_b64 v[170:171], 11, v[170:171]
	v_lshl_add_u64 v[170:171], v[168:169], 0, v[170:171]
	v_mul_f32_e32 v131, v14, v131
	v_mul_f32_e32 v134, v10, v134
	v_mul_f32_e32 v139, v6, v139
	v_mul_f32_e32 v141, v2, v141
	v_cvt_pk_bf16_f32 v172, v131, v134
	v_cvt_pk_bf16_f32 v173, v139, v141
	global_store_dwordx2 v[170:171], v[172:173], off nt
	v_mul_f32_e32 v131, 0xbfb8aa3b, v15
	v_mul_f32_e32 v134, 0xbfb8aa3b, v11
	v_mul_f32_e32 v139, 0xbfb8aa3b, v7
	v_mul_f32_e32 v141, 0xbfb8aa3b, v3
	v_exp_f32_e32 v131, v131
	v_exp_f32_e32 v134, v134
	v_exp_f32_e32 v139, v139
	v_exp_f32_e32 v141, v141
	v_add_f32_e32 v131, 1.0, v131
	v_add_f32_e32 v134, 1.0, v134
	v_add_f32_e32 v139, 1.0, v139
	v_add_f32_e32 v141, 1.0, v141
	v_add_u32_e32 v170, 0x73, v128
	v_rcp_f32_e32 v131, v131
	v_rcp_f32_e32 v134, v134
	v_rcp_f32_e32 v139, v139
	v_rcp_f32_e32 v141, v141
	v_ashrrev_i32_e32 v171, 31, v170
	v_lshlrev_b64 v[170:171], 11, v[170:171]
	v_lshl_add_u64 v[168:169], v[168:169], 0, v[170:171]
	v_mul_f32_e32 v131, v15, v131
	v_mul_f32_e32 v134, v11, v134
	v_mul_f32_e32 v139, v7, v139
	v_mul_f32_e32 v141, v3, v141
	v_cvt_pk_bf16_f32 v170, v131, v134
	v_cvt_pk_bf16_f32 v171, v139, v141
	global_store_dwordx2 v[168:169], v[170:171], off nt

.LBB0_510:
	global_load_dwordx2 v[170:171], v[170:171], off
	v_lshlrev_b32_e32 v134, 2, v168
	v_lshl_add_u64 v[168:169], s[4:5], 0, v[134:135]
	v_lshl_add_u64 v[168:169], v[136:137], 2, v[168:169]
	s_waitcnt vmcnt(0)
	v_lshl_add_u64 v[170:171], v[136:137], 1, v[170:171]
	v_mad_i64_i32 v[172:173], s[24:25], v128, s13, v[170:171]
	v_and_b32_e32 v131, 0x7fc, v128
	v_cvt_pk_bf16_f32 v178, v124, v120
	v_cvt_pk_bf16_f32 v179, v116, v112
	global_store_dwordx2 v[172:173], v[178:179], off nt
	v_ashrrev_i32_e32 v172, 11, v128
	v_cmp_lt_u32_e32 vcc, s19, v131
	v_ashrrev_i32_e32 v173, 31, v172
	s_and_saveexec_b64 s[66:67], vcc
	s_cbranch_execz .LBB0_512
	v_lshlrev_b64 v[178:179], 9, v[172:173]
	v_add_u32_e32 v134, 0xfffffa00, v131
	v_lshl_add_u64 v[178:179], v[178:179], 0, v[134:135]
	v_mad_u64_u32 v[182:183], s[24:25], v178, s14, v[168:169]
	v_mad_i32_i24 v183, v179, s14, v183
	v_mov_b32_e32 v178, v124
	v_mov_b32_e32 v179, v120
	v_mov_b32_e32 v180, v116
	v_mov_b32_e32 v181, v112
	global_store_dwordx4 v[182:183], v[178:181], off nt
.LBB0_512:
	s_or_b64 exec, exec, s[66:67]
	s_movk_i32 s23, 0x7fd
	v_bitop3_b32 v131, v128, s23, 1 bitop3:0xc8
	v_mad_i64_i32 v[178:179], s[24:25], v166, s13, v[170:171]
	v_cmp_lt_u32_e32 vcc, s19, v131
	v_cvt_pk_bf16_f32 v180, v125, v121
	v_cvt_pk_bf16_f32 v181, v117, v113
	global_store_dwordx2 v[178:179], v[180:181], off nt
	s_and_saveexec_b64 s[66:67], vcc
	s_cbranch_execz .LBB0_514
	v_lshlrev_b64 v[178:179], 9, v[172:173]
	v_add_u32_e32 v134, 0xfffffa00, v131
	v_lshl_add_u64 v[178:179], v[178:179], 0, v[134:135]
	v_mad_u64_u32 v[182:183], s[24:25], v178, s14, v[168:169]
	v_mad_i32_i24 v183, v179, s14, v183
	v_mov_b32_e32 v178, v125
	v_mov_b32_e32 v179, v121
	v_mov_b32_e32 v180, v117
	v_mov_b32_e32 v181, v113
	global_store_dwordx4 v[182:183], v[178:181], off nt
.LBB0_514:
	s_or_b64 exec, exec, s[66:67]
	s_movk_i32 s23, 0x7fe
	v_bitop3_b32 v131, v128, s23, 2 bitop3:0xc8
	v_mad_i64_i32 v[178:179], s[24:25], v164, s13, v[170:171]
	v_cmp_lt_u32_e32 vcc, s19, v131
	v_cvt_pk_bf16_f32 v180, v126, v122
	v_cvt_pk_bf16_f32 v181, v118, v114
	global_store_dwordx2 v[178:179], v[180:181], off nt
	s_and_saveexec_b64 s[66:67], vcc
	s_cbranch_execz .LBB0_516
	v_lshlrev_b64 v[178:179], 9, v[172:173]
	v_add_u32_e32 v134, 0xfffffa00, v131
	v_lshl_add_u64 v[178:179], v[178:179], 0, v[134:135]
	v_mad_u64_u32 v[182:183], s[24:25], v178, s14, v[168:169]
	v_mad_i32_i24 v183, v179, s14, v183
	v_mov_b32_e32 v178, v126
	v_mov_b32_e32 v179, v122
	v_mov_b32_e32 v180, v118
	v_mov_b32_e32 v181, v114
	global_store_dwordx4 v[182:183], v[178:181], off nt
.LBB0_516:
	s_or_b64 exec, exec, s[66:67]
	s_movk_i32 s23, 0x7ff
	v_bitop3_b32 v131, v128, s23, 3 bitop3:0xc8
	v_mad_i64_i32 v[178:179], s[24:25], v162, s13, v[170:171]
	v_cmp_lt_u32_e32 vcc, s19, v131
	v_cvt_pk_bf16_f32 v180, v127, v123
	v_cvt_pk_bf16_f32 v181, v119, v115
	global_store_dwordx2 v[178:179], v[180:181], off nt
	s_and_saveexec_b64 s[66:67], vcc
	s_cbranch_execz .LBB0_518
	v_lshlrev_b64 v[172:173], 9, v[172:173]
	v_add_u32_e32 v134, 0xfffffa00, v131
	v_lshl_add_u64 v[172:173], v[172:173], 0, v[134:135]
	v_mad_u64_u32 v[182:183], s[24:25], v172, s14, v[168:169]
	v_mad_i32_i24 v183, v173, s14, v183
	v_mov_b32_e32 v178, v127
	v_mov_b32_e32 v179, v123
	v_mov_b32_e32 v180, v119
	v_mov_b32_e32 v181, v115
	global_store_dwordx4 v[182:183], v[178:181], off nt
.LBB0_518:
	s_or_b64 exec, exec, s[66:67]
	v_and_b32_e32 v131, 0x7fc, v160
	v_mad_i64_i32 v[172:173], s[24:25], v160, s13, v[170:171]
	v_cmp_lt_u32_e32 vcc, s19, v131
	v_cvt_pk_bf16_f32 v178, v108, v104
	v_cvt_pk_bf16_f32 v179, v100, v96
	global_store_dwordx2 v[172:173], v[178:179], off nt
	s_and_saveexec_b64 s[66:67], vcc
	s_cbranch_execz .LBB0_520
	v_ashrrev_i32_e32 v172, 11, v160
	v_ashrrev_i32_e32 v173, 31, v172
	v_lshlrev_b64 v[172:173], 9, v[172:173]
	v_add_u32_e32 v134, 0xfffffa00, v131
	v_lshl_add_u64 v[172:173], v[172:173], 0, v[134:135]
	v_mad_u64_u32 v[182:183], s[24:25], v172, s14, v[168:169]
	v_mad_i32_i24 v183, v173, s14, v183
	v_mov_b32_e32 v178, v108
	v_mov_b32_e32 v179, v104
	v_mov_b32_e32 v180, v100
	v_mov_b32_e32 v181, v96
	global_store_dwordx4 v[182:183], v[178:181], off nt
.LBB0_520:
	s_or_b64 exec, exec, s[66:67]
	v_and_b32_e32 v131, 0x7fd, v158
	v_mad_i64_i32 v[172:173], s[24:25], v158, s13, v[170:171]
	v_cmp_lt_u32_e32 vcc, s19, v131
	v_cvt_pk_bf16_f32 v178, v109, v105
	v_cvt_pk_bf16_f32 v179, v101, v97
	global_store_dwordx2 v[172:173], v[178:179], off nt
	s_and_saveexec_b64 s[66:67], vcc
	s_cbranch_execz .LBB0_522
	v_ashrrev_i32_e32 v172, 11, v158
	v_ashrrev_i32_e32 v173, 31, v172
	v_lshlrev_b64 v[172:173], 9, v[172:173]
	v_add_u32_e32 v134, 0xfffffa00, v131
	v_lshl_add_u64 v[172:173], v[172:173], 0, v[134:135]
	v_mad_u64_u32 v[182:183], s[24:25], v172, s14, v[168:169]
	v_mad_i32_i24 v183, v173, s14, v183
	v_mov_b32_e32 v178, v109
	v_mov_b32_e32 v179, v105
	v_mov_b32_e32 v180, v101
	v_mov_b32_e32 v181, v97
	global_store_dwordx4 v[182:183], v[178:181], off nt
.LBB0_522:
	s_or_b64 exec, exec, s[66:67]
	v_and_b32_e32 v131, 0x7fe, v156
	v_mad_i64_i32 v[172:173], s[24:25], v156, s13, v[170:171]
	v_cmp_lt_u32_e32 vcc, s19, v131
	v_cvt_pk_bf16_f32 v178, v110, v106
	v_cvt_pk_bf16_f32 v179, v102, v98
	global_store_dwordx2 v[172:173], v[178:179], off nt
	s_and_saveexec_b64 s[66:67], vcc
	s_cbranch_execz .LBB0_524
	v_ashrrev_i32_e32 v172, 11, v156
	v_ashrrev_i32_e32 v173, 31, v172
	v_lshlrev_b64 v[172:173], 9, v[172:173]
	v_add_u32_e32 v134, 0xfffffa00, v131
	v_lshl_add_u64 v[172:173], v[172:173], 0, v[134:135]
	v_mad_u64_u32 v[182:183], s[24:25], v172, s14, v[168:169]
	v_mad_i32_i24 v183, v173, s14, v183
	v_mov_b32_e32 v178, v110
	v_mov_b32_e32 v179, v106
	v_mov_b32_e32 v180, v102
	v_mov_b32_e32 v181, v98
	global_store_dwordx4 v[182:183], v[178:181], off nt
.LBB0_524:
	s_or_b64 exec, exec, s[66:67]
	v_and_b32_e32 v131, 0x7ff, v154
	v_mad_i64_i32 v[172:173], s[24:25], v154, s13, v[170:171]
	v_cmp_lt_u32_e32 vcc, s19, v131
	v_cvt_pk_bf16_f32 v178, v111, v107
	v_cvt_pk_bf16_f32 v179, v103, v99
	global_store_dwordx2 v[172:173], v[178:179], off nt
	s_and_saveexec_b64 s[66:67], vcc
	s_cbranch_execz .LBB0_526
	v_ashrrev_i32_e32 v172, 11, v154
	v_ashrrev_i32_e32 v173, 31, v172
	v_lshlrev_b64 v[172:173], 9, v[172:173]
	v_add_u32_e32 v134, 0xfffffa00, v131
	v_lshl_add_u64 v[172:173], v[172:173], 0, v[134:135]
	v_mad_u64_u32 v[182:183], s[24:25], v172, s14, v[168:169]
	v_mad_i32_i24 v183, v173, s14, v183
	v_mov_b32_e32 v178, v111
	v_mov_b32_e32 v179, v107
	v_mov_b32_e32 v180, v103
	v_mov_b32_e32 v181, v99
	global_store_dwordx4 v[182:183], v[178:181], off nt
.LBB0_526:
	s_or_b64 exec, exec, s[66:67]
	v_and_b32_e32 v131, 0x7fc, v152
	v_mad_i64_i32 v[172:173], s[24:25], v152, s13, v[170:171]
	v_cmp_lt_u32_e32 vcc, s19, v131
	v_cvt_pk_bf16_f32 v178, v92, v88
	v_cvt_pk_bf16_f32 v179, v84, v80
	global_store_dwordx2 v[172:173], v[178:179], off nt
	s_and_saveexec_b64 s[66:67], vcc
	s_cbranch_execz .LBB0_528
	v_ashrrev_i32_e32 v172, 11, v152
	v_ashrrev_i32_e32 v173, 31, v172
	v_lshlrev_b64 v[172:173], 9, v[172:173]
	v_add_u32_e32 v134, 0xfffffa00, v131
	v_lshl_add_u64 v[172:173], v[172:173], 0, v[134:135]
	v_mad_u64_u32 v[182:183], s[24:25], v172, s14, v[168:169]
	v_mad_i32_i24 v183, v173, s14, v183
	v_mov_b32_e32 v178, v92
	v_mov_b32_e32 v179, v88
	v_mov_b32_e32 v180, v84
	v_mov_b32_e32 v181, v80
	global_store_dwordx4 v[182:183], v[178:181], off nt
.LBB0_528:
	s_or_b64 exec, exec, s[66:67]
	v_and_b32_e32 v131, 0x7fd, v150
	v_mad_i64_i32 v[172:173], s[24:25], v150, s13, v[170:171]
	v_cmp_lt_u32_e32 vcc, s19, v131
	v_cvt_pk_bf16_f32 v178, v93, v89
	v_cvt_pk_bf16_f32 v179, v85, v81
	global_store_dwordx2 v[172:173], v[178:179], off nt
	s_and_saveexec_b64 s[66:67], vcc
	s_cbranch_execz .LBB0_530
	v_ashrrev_i32_e32 v172, 11, v150
	v_ashrrev_i32_e32 v173, 31, v172
	v_lshlrev_b64 v[172:173], 9, v[172:173]
	v_add_u32_e32 v134, 0xfffffa00, v131
	v_lshl_add_u64 v[172:173], v[172:173], 0, v[134:135]
	v_mad_u64_u32 v[182:183], s[24:25], v172, s14, v[168:169]
	v_mad_i32_i24 v183, v173, s14, v183
	v_mov_b32_e32 v178, v93
	v_mov_b32_e32 v179, v89
	v_mov_b32_e32 v180, v85
	v_mov_b32_e32 v181, v81
	global_store_dwordx4 v[182:183], v[178:181], off nt
.LBB0_530:
	s_or_b64 exec, exec, s[66:67]
	v_and_b32_e32 v131, 0x7fe, v148
	v_mad_i64_i32 v[172:173], s[24:25], v148, s13, v[170:171]
	v_cmp_lt_u32_e32 vcc, s19, v131
	v_cvt_pk_bf16_f32 v178, v94, v90
	v_cvt_pk_bf16_f32 v179, v86, v82
	global_store_dwordx2 v[172:173], v[178:179], off nt
	s_and_saveexec_b64 s[66:67], vcc
	s_cbranch_execz .LBB0_532
	v_ashrrev_i32_e32 v172, 11, v148
	v_ashrrev_i32_e32 v173, 31, v172
	v_lshlrev_b64 v[172:173], 9, v[172:173]
	v_add_u32_e32 v134, 0xfffffa00, v131
	v_lshl_add_u64 v[172:173], v[172:173], 0, v[134:135]
	v_mad_u64_u32 v[182:183], s[24:25], v172, s14, v[168:169]
	v_mad_i32_i24 v183, v173, s14, v183
	v_mov_b32_e32 v178, v94
	v_mov_b32_e32 v179, v90
	v_mov_b32_e32 v180, v86
	v_mov_b32_e32 v181, v82
	global_store_dwordx4 v[182:183], v[178:181], off nt
.LBB0_532:
	s_or_b64 exec, exec, s[66:67]
	v_and_b32_e32 v131, 0x7ff, v146
	v_mad_i64_i32 v[172:173], s[24:25], v146, s13, v[170:171]
	v_cmp_lt_u32_e32 vcc, s19, v131
	v_cvt_pk_bf16_f32 v178, v95, v91
	v_cvt_pk_bf16_f32 v179, v87, v83
	global_store_dwordx2 v[172:173], v[178:179], off nt
	s_and_saveexec_b64 s[66:67], vcc
	s_cbranch_execz .LBB0_534
	v_ashrrev_i32_e32 v172, 11, v146
	v_ashrrev_i32_e32 v173, 31, v172
	v_lshlrev_b64 v[172:173], 9, v[172:173]
	v_add_u32_e32 v134, 0xfffffa00, v131
	v_lshl_add_u64 v[172:173], v[172:173], 0, v[134:135]
	v_mad_u64_u32 v[182:183], s[24:25], v172, s14, v[168:169]
	v_mad_i32_i24 v183, v173, s14, v183
	v_mov_b32_e32 v178, v95
	v_mov_b32_e32 v179, v91
	v_mov_b32_e32 v180, v87
	v_mov_b32_e32 v181, v83
	global_store_dwordx4 v[182:183], v[178:181], off nt
.LBB0_534:
	s_or_b64 exec, exec, s[66:67]
	v_and_b32_e32 v131, 0x7fc, v144
	v_mad_i64_i32 v[172:173], s[24:25], v144, s13, v[170:171]
	v_cmp_lt_u32_e32 vcc, s19, v131
	v_cvt_pk_bf16_f32 v178, v76, v72
	v_cvt_pk_bf16_f32 v179, v68, v64
	global_store_dwordx2 v[172:173], v[178:179], off nt
	s_and_saveexec_b64 s[66:67], vcc
	s_cbranch_execz .LBB0_536
	v_ashrrev_i32_e32 v172, 11, v144
	v_ashrrev_i32_e32 v173, 31, v172
	v_lshlrev_b64 v[172:173], 9, v[172:173]
	v_add_u32_e32 v134, 0xfffffa00, v131
	v_lshl_add_u64 v[172:173], v[172:173], 0, v[134:135]
	v_mad_u64_u32 v[182:183], s[24:25], v172, s14, v[168:169]
	v_mad_i32_i24 v183, v173, s14, v183
	v_mov_b32_e32 v178, v76
	v_mov_b32_e32 v179, v72
	v_mov_b32_e32 v180, v68
	v_mov_b32_e32 v181, v64
	global_store_dwordx4 v[182:183], v[178:181], off nt
.LBB0_536:
	s_or_b64 exec, exec, s[66:67]
	v_and_b32_e32 v131, 0x7fd, v142
	v_mad_i64_i32 v[172:173], s[24:25], v142, s13, v[170:171]
	v_cmp_lt_u32_e32 vcc, s19, v131
	v_cvt_pk_bf16_f32 v178, v77, v73
	v_cvt_pk_bf16_f32 v179, v69, v65
	global_store_dwordx2 v[172:173], v[178:179], off nt
	s_and_saveexec_b64 s[66:67], vcc
	s_cbranch_execz .LBB0_538
	v_ashrrev_i32_e32 v172, 11, v142
	v_ashrrev_i32_e32 v173, 31, v172
	v_lshlrev_b64 v[172:173], 9, v[172:173]
	v_add_u32_e32 v134, 0xfffffa00, v131
	v_lshl_add_u64 v[172:173], v[172:173], 0, v[134:135]
	v_mad_u64_u32 v[182:183], s[24:25], v172, s14, v[168:169]
	v_mad_i32_i24 v183, v173, s14, v183
	v_mov_b32_e32 v178, v77
	v_mov_b32_e32 v179, v73
	v_mov_b32_e32 v180, v69
	v_mov_b32_e32 v181, v65
	global_store_dwordx4 v[182:183], v[178:181], off nt
.LBB0_538:
	s_or_b64 exec, exec, s[66:67]
	v_and_b32_e32 v131, 0x7fe, v140
	v_mad_i64_i32 v[172:173], s[24:25], v140, s13, v[170:171]
	v_cmp_lt_u32_e32 vcc, s19, v131
	v_cvt_pk_bf16_f32 v178, v78, v74
	v_cvt_pk_bf16_f32 v179, v70, v66
	global_store_dwordx2 v[172:173], v[178:179], off nt
	s_and_saveexec_b64 s[66:67], vcc
	s_cbranch_execz .LBB0_540
	v_ashrrev_i32_e32 v172, 11, v140
	v_ashrrev_i32_e32 v173, 31, v172
	v_lshlrev_b64 v[172:173], 9, v[172:173]
	v_add_u32_e32 v134, 0xfffffa00, v131
	v_lshl_add_u64 v[172:173], v[172:173], 0, v[134:135]
	v_mad_u64_u32 v[182:183], s[24:25], v172, s14, v[168:169]
	v_mad_i32_i24 v183, v173, s14, v183
	v_mov_b32_e32 v178, v78
	v_mov_b32_e32 v179, v74
	v_mov_b32_e32 v180, v70
	v_mov_b32_e32 v181, v66
	global_store_dwordx4 v[182:183], v[178:181], off nt
.LBB0_540:
	s_or_b64 exec, exec, s[66:67]
	v_and_b32_e32 v131, 0x7ff, v138
	v_mad_i64_i32 v[172:173], s[24:25], v138, s13, v[170:171]
	v_cmp_lt_u32_e32 vcc, s19, v131
	v_cvt_pk_bf16_f32 v178, v79, v75
	v_cvt_pk_bf16_f32 v179, v71, v67
	global_store_dwordx2 v[172:173], v[178:179], off nt
	s_and_saveexec_b64 s[66:67], vcc
	s_cbranch_execz .LBB0_542
	v_ashrrev_i32_e32 v172, 11, v138
	v_ashrrev_i32_e32 v173, 31, v172
	v_lshlrev_b64 v[172:173], 9, v[172:173]
	v_add_u32_e32 v134, 0xfffffa00, v131
	v_lshl_add_u64 v[172:173], v[172:173], 0, v[134:135]
	v_mad_u64_u32 v[182:183], s[24:25], v172, s14, v[168:169]
	v_mad_i32_i24 v183, v173, s14, v183
	v_mov_b32_e32 v178, v79
	v_mov_b32_e32 v179, v75
	v_mov_b32_e32 v180, v71
	v_mov_b32_e32 v181, v67
	global_store_dwordx4 v[182:183], v[178:181], off nt
.LBB0_542:
	s_or_b64 exec, exec, s[66:67]
	v_and_b32_e32 v131, 0x7fc, v130
	v_mad_i64_i32 v[172:173], s[24:25], v130, s13, v[170:171]
	v_cmp_lt_u32_e32 vcc, s19, v131
	v_cvt_pk_bf16_f32 v178, v60, v56
	v_cvt_pk_bf16_f32 v179, v52, v48
	global_store_dwordx2 v[172:173], v[178:179], off nt
	s_and_saveexec_b64 s[66:67], vcc
	s_cbranch_execz .LBB0_544
	v_ashrrev_i32_e32 v172, 11, v130
	v_ashrrev_i32_e32 v173, 31, v172
	v_lshlrev_b64 v[172:173], 9, v[172:173]
	v_add_u32_e32 v134, 0xfffffa00, v131
	v_lshl_add_u64 v[172:173], v[172:173], 0, v[134:135]
	v_mad_u64_u32 v[182:183], s[24:25], v172, s14, v[168:169]
	v_mad_i32_i24 v183, v173, s14, v183
	v_mov_b32_e32 v178, v60
	v_mov_b32_e32 v179, v56
	v_mov_b32_e32 v180, v52
	v_mov_b32_e32 v181, v48
	global_store_dwordx4 v[182:183], v[178:181], off nt
.LBB0_544:
	s_or_b64 exec, exec, s[66:67]
	v_add_u32_e32 v134, 0x41, v128
	v_and_b32_e32 v131, 0x7fd, v134
	v_mad_i64_i32 v[172:173], s[24:25], v134, s13, v[170:171]
	v_cmp_lt_u32_e32 vcc, s19, v131
	v_cvt_pk_bf16_f32 v178, v61, v57
	v_cvt_pk_bf16_f32 v179, v53, v49
	global_store_dwordx2 v[172:173], v[178:179], off nt
	s_and_saveexec_b64 s[66:67], vcc
	s_cbranch_execz .LBB0_546
	v_ashrrev_i32_e32 v172, 11, v134
	v_ashrrev_i32_e32 v173, 31, v172
	v_lshlrev_b64 v[172:173], 9, v[172:173]
	v_add_u32_e32 v134, 0xfffffa00, v131
	v_lshl_add_u64 v[172:173], v[172:173], 0, v[134:135]
	v_mad_u64_u32 v[182:183], s[24:25], v172, s14, v[168:169]
	v_mad_i32_i24 v183, v173, s14, v183
	v_mov_b32_e32 v178, v61
	v_mov_b32_e32 v179, v57
	v_mov_b32_e32 v180, v53
	v_mov_b32_e32 v181, v49
	global_store_dwordx4 v[182:183], v[178:181], off nt
.LBB0_546:
	s_or_b64 exec, exec, s[66:67]
	v_add_u32_e32 v134, 0x42, v128
	v_and_b32_e32 v131, 0x7fe, v134
	v_mad_i64_i32 v[172:173], s[24:25], v134, s13, v[170:171]
	v_cmp_lt_u32_e32 vcc, s19, v131
	v_cvt_pk_bf16_f32 v178, v62, v58
	v_cvt_pk_bf16_f32 v179, v54, v50
	global_store_dwordx2 v[172:173], v[178:179], off nt
	s_and_saveexec_b64 s[66:67], vcc
	s_cbranch_execz .LBB0_548
	v_ashrrev_i32_e32 v172, 11, v134
	v_ashrrev_i32_e32 v173, 31, v172
	v_lshlrev_b64 v[172:173], 9, v[172:173]
	v_add_u32_e32 v134, 0xfffffa00, v131
	v_lshl_add_u64 v[172:173], v[172:173], 0, v[134:135]
	v_mad_u64_u32 v[182:183], s[24:25], v172, s14, v[168:169]
	v_mad_i32_i24 v183, v173, s14, v183
	v_mov_b32_e32 v178, v62
	v_mov_b32_e32 v179, v58
	v_mov_b32_e32 v180, v54
	v_mov_b32_e32 v181, v50
	global_store_dwordx4 v[182:183], v[178:181], off nt
.LBB0_548:
	s_or_b64 exec, exec, s[66:67]
	v_add_u32_e32 v134, 0x43, v128
	v_and_b32_e32 v131, 0x7ff, v134
	v_mad_i64_i32 v[172:173], s[24:25], v134, s13, v[170:171]
	v_cmp_lt_u32_e32 vcc, s19, v131
	v_cvt_pk_bf16_f32 v178, v63, v59
	v_cvt_pk_bf16_f32 v179, v55, v51
	global_store_dwordx2 v[172:173], v[178:179], off nt
	s_and_saveexec_b64 s[66:67], vcc
	s_cbranch_execz .LBB0_550
	v_ashrrev_i32_e32 v172, 11, v134
	v_ashrrev_i32_e32 v173, 31, v172
	v_lshlrev_b64 v[172:173], 9, v[172:173]
	v_add_u32_e32 v134, 0xfffffa00, v131
	v_lshl_add_u64 v[172:173], v[172:173], 0, v[134:135]
	v_mad_u64_u32 v[182:183], s[24:25], v172, s14, v[168:169]
	v_mad_i32_i24 v183, v173, s14, v183
	v_mov_b32_e32 v178, v63
	v_mov_b32_e32 v179, v59
	v_mov_b32_e32 v180, v55
	v_mov_b32_e32 v181, v51
	global_store_dwordx4 v[182:183], v[178:181], off nt
.LBB0_550:
	s_or_b64 exec, exec, s[66:67]
	v_add_u32_e32 v134, 0x50, v128
	v_and_b32_e32 v131, 0x7fc, v134
	v_mad_i64_i32 v[172:173], s[24:25], v134, s13, v[170:171]
	v_cmp_lt_u32_e32 vcc, s19, v131
	v_cvt_pk_bf16_f32 v178, v44, v40
	v_cvt_pk_bf16_f32 v179, v36, v32
	global_store_dwordx2 v[172:173], v[178:179], off nt
	s_and_saveexec_b64 s[66:67], vcc
	s_cbranch_execz .LBB0_552
	v_ashrrev_i32_e32 v172, 11, v134
	v_ashrrev_i32_e32 v173, 31, v172
	v_lshlrev_b64 v[172:173], 9, v[172:173]
	v_add_u32_e32 v134, 0xfffffa00, v131
	v_lshl_add_u64 v[172:173], v[172:173], 0, v[134:135]
	v_mad_u64_u32 v[182:183], s[24:25], v172, s14, v[168:169]
	v_mad_i32_i24 v183, v173, s14, v183
	v_mov_b32_e32 v178, v44
	v_mov_b32_e32 v179, v40
	v_mov_b32_e32 v180, v36
	v_mov_b32_e32 v181, v32
	global_store_dwordx4 v[182:183], v[178:181], off nt
.LBB0_552:
	s_or_b64 exec, exec, s[66:67]
	v_add_u32_e32 v134, 0x51, v128
	v_and_b32_e32 v131, 0x7fd, v134
	v_mad_i64_i32 v[172:173], s[24:25], v134, s13, v[170:171]
	v_cmp_lt_u32_e32 vcc, s19, v131
	v_cvt_pk_bf16_f32 v178, v45, v41
	v_cvt_pk_bf16_f32 v179, v37, v33
	global_store_dwordx2 v[172:173], v[178:179], off nt
	s_and_saveexec_b64 s[66:67], vcc
	s_cbranch_execz .LBB0_554
	v_ashrrev_i32_e32 v172, 11, v134
	v_ashrrev_i32_e32 v173, 31, v172
	v_lshlrev_b64 v[172:173], 9, v[172:173]
	v_add_u32_e32 v134, 0xfffffa00, v131
	v_lshl_add_u64 v[172:173], v[172:173], 0, v[134:135]
	v_mad_u64_u32 v[182:183], s[24:25], v172, s14, v[168:169]
	v_mad_i32_i24 v183, v173, s14, v183
	v_mov_b32_e32 v178, v45
	v_mov_b32_e32 v179, v41
	v_mov_b32_e32 v180, v37
	v_mov_b32_e32 v181, v33
	global_store_dwordx4 v[182:183], v[178:181], off nt
.LBB0_554:
	s_or_b64 exec, exec, s[66:67]
	v_add_u32_e32 v134, 0x52, v128
	v_and_b32_e32 v131, 0x7fe, v134
	v_mad_i64_i32 v[172:173], s[24:25], v134, s13, v[170:171]
	v_cmp_lt_u32_e32 vcc, s19, v131
	v_cvt_pk_bf16_f32 v178, v46, v42
	v_cvt_pk_bf16_f32 v179, v38, v34
	global_store_dwordx2 v[172:173], v[178:179], off nt
	s_and_saveexec_b64 s[66:67], vcc
	s_cbranch_execz .LBB0_556
	v_ashrrev_i32_e32 v172, 11, v134
	v_ashrrev_i32_e32 v173, 31, v172
	v_lshlrev_b64 v[172:173], 9, v[172:173]
	v_add_u32_e32 v134, 0xfffffa00, v131
	v_lshl_add_u64 v[172:173], v[172:173], 0, v[134:135]
	v_mad_u64_u32 v[182:183], s[24:25], v172, s14, v[168:169]
	v_mad_i32_i24 v183, v173, s14, v183
	v_mov_b32_e32 v178, v46
	v_mov_b32_e32 v179, v42
	v_mov_b32_e32 v180, v38
	v_mov_b32_e32 v181, v34
	global_store_dwordx4 v[182:183], v[178:181], off nt
.LBB0_556:
	s_or_b64 exec, exec, s[66:67]
	v_add_u32_e32 v134, 0x53, v128
	v_and_b32_e32 v131, 0x7ff, v134
	v_mad_i64_i32 v[172:173], s[24:25], v134, s13, v[170:171]
	v_cmp_lt_u32_e32 vcc, s19, v131
	v_cvt_pk_bf16_f32 v178, v47, v43
	v_cvt_pk_bf16_f32 v179, v39, v35
	global_store_dwordx2 v[172:173], v[178:179], off nt
	s_and_saveexec_b64 s[66:67], vcc
	s_cbranch_execz .LBB0_558
	v_ashrrev_i32_e32 v172, 11, v134
	v_ashrrev_i32_e32 v173, 31, v172
	v_lshlrev_b64 v[172:173], 9, v[172:173]
	v_add_u32_e32 v134, 0xfffffa00, v131
	v_lshl_add_u64 v[172:173], v[172:173], 0, v[134:135]
	v_mad_u64_u32 v[182:183], s[24:25], v172, s14, v[168:169]
	v_mad_i32_i24 v183, v173, s14, v183
	v_mov_b32_e32 v178, v47
	v_mov_b32_e32 v179, v43
	v_mov_b32_e32 v180, v39
	v_mov_b32_e32 v181, v35
	global_store_dwordx4 v[182:183], v[178:181], off nt
.LBB0_558:
	s_or_b64 exec, exec, s[66:67]
	v_add_u32_e32 v134, 0x60, v128
	v_and_b32_e32 v131, 0x7fc, v134
	v_mad_i64_i32 v[172:173], s[24:25], v134, s13, v[170:171]
	v_cmp_lt_u32_e32 vcc, s19, v131
	v_cvt_pk_bf16_f32 v178, v28, v24
	v_cvt_pk_bf16_f32 v179, v20, v16
	global_store_dwordx2 v[172:173], v[178:179], off nt
	s_and_saveexec_b64 s[66:67], vcc
	s_cbranch_execz .LBB0_560
	v_ashrrev_i32_e32 v172, 11, v134
	v_ashrrev_i32_e32 v173, 31, v172
	v_lshlrev_b64 v[172:173], 9, v[172:173]
	v_add_u32_e32 v134, 0xfffffa00, v131
	v_lshl_add_u64 v[172:173], v[172:173], 0, v[134:135]
	v_mad_u64_u32 v[182:183], s[24:25], v172, s14, v[168:169]
	v_mad_i32_i24 v183, v173, s14, v183
	v_mov_b32_e32 v178, v28
	v_mov_b32_e32 v179, v24
	v_mov_b32_e32 v180, v20
	v_mov_b32_e32 v181, v16
	global_store_dwordx4 v[182:183], v[178:181], off nt
.LBB0_560:
	s_or_b64 exec, exec, s[66:67]
	v_add_u32_e32 v134, 0x61, v128
	v_and_b32_e32 v131, 0x7fd, v134
	v_mad_i64_i32 v[172:173], s[24:25], v134, s13, v[170:171]
	v_cmp_lt_u32_e32 vcc, s19, v131
	v_cvt_pk_bf16_f32 v178, v29, v25
	v_cvt_pk_bf16_f32 v179, v21, v17
	global_store_dwordx2 v[172:173], v[178:179], off nt
	s_and_saveexec_b64 s[66:67], vcc
	s_cbranch_execz .LBB0_562
	v_ashrrev_i32_e32 v172, 11, v134
	v_ashrrev_i32_e32 v173, 31, v172
	v_lshlrev_b64 v[172:173], 9, v[172:173]
	v_add_u32_e32 v134, 0xfffffa00, v131
	v_lshl_add_u64 v[172:173], v[172:173], 0, v[134:135]
	v_mad_u64_u32 v[182:183], s[24:25], v172, s14, v[168:169]
	v_mad_i32_i24 v183, v173, s14, v183
	v_mov_b32_e32 v178, v29
	v_mov_b32_e32 v179, v25
	v_mov_b32_e32 v180, v21
	v_mov_b32_e32 v181, v17
	global_store_dwordx4 v[182:183], v[178:181], off nt
.LBB0_562:
	s_or_b64 exec, exec, s[66:67]
	v_add_u32_e32 v134, 0x62, v128
	v_and_b32_e32 v131, 0x7fe, v134
	v_mad_i64_i32 v[172:173], s[24:25], v134, s13, v[170:171]
	v_cmp_lt_u32_e32 vcc, s19, v131
	v_cvt_pk_bf16_f32 v178, v30, v26
	v_cvt_pk_bf16_f32 v179, v22, v18
	global_store_dwordx2 v[172:173], v[178:179], off nt
	s_and_saveexec_b64 s[66:67], vcc
	s_cbranch_execz .LBB0_564
	v_ashrrev_i32_e32 v172, 11, v134
	v_ashrrev_i32_e32 v173, 31, v172
	v_lshlrev_b64 v[172:173], 9, v[172:173]
	v_add_u32_e32 v134, 0xfffffa00, v131
	v_lshl_add_u64 v[172:173], v[172:173], 0, v[134:135]
	v_mad_u64_u32 v[182:183], s[24:25], v172, s14, v[168:169]
	v_mad_i32_i24 v183, v173, s14, v183
	v_mov_b32_e32 v178, v30
	v_mov_b32_e32 v179, v26
	v_mov_b32_e32 v180, v22
	v_mov_b32_e32 v181, v18
	global_store_dwordx4 v[182:183], v[178:181], off nt
.LBB0_564:
	s_or_b64 exec, exec, s[66:67]
	v_add_u32_e32 v134, 0x63, v128
	v_and_b32_e32 v131, 0x7ff, v134
	v_mad_i64_i32 v[172:173], s[24:25], v134, s13, v[170:171]
	v_cmp_lt_u32_e32 vcc, s19, v131
	v_cvt_pk_bf16_f32 v178, v31, v27
	v_cvt_pk_bf16_f32 v179, v23, v19
	global_store_dwordx2 v[172:173], v[178:179], off nt
	s_and_saveexec_b64 s[66:67], vcc
	s_cbranch_execz .LBB0_566
	v_ashrrev_i32_e32 v172, 11, v134
	v_ashrrev_i32_e32 v173, 31, v172
	v_lshlrev_b64 v[172:173], 9, v[172:173]
	v_add_u32_e32 v134, 0xfffffa00, v131
	v_lshl_add_u64 v[172:173], v[172:173], 0, v[134:135]
	v_mad_u64_u32 v[182:183], s[24:25], v172, s14, v[168:169]
	v_mad_i32_i24 v183, v173, s14, v183
	v_mov_b32_e32 v178, v31
	v_mov_b32_e32 v179, v27
	v_mov_b32_e32 v180, v23
	v_mov_b32_e32 v181, v19
	global_store_dwordx4 v[182:183], v[178:181], off nt
.LBB0_566:
	s_or_b64 exec, exec, s[66:67]
	v_add_u32_e32 v134, 0x70, v128
	v_and_b32_e32 v131, 0x7fc, v134
	v_mad_i64_i32 v[172:173], s[24:25], v134, s13, v[170:171]
	v_cmp_lt_u32_e32 vcc, s19, v131
	v_cvt_pk_bf16_f32 v178, v12, v8
	v_cvt_pk_bf16_f32 v179, v4, v0
	global_store_dwordx2 v[172:173], v[178:179], off nt
	s_and_saveexec_b64 s[66:67], vcc
	s_cbranch_execz .LBB0_568
	v_ashrrev_i32_e32 v172, 11, v134
	v_ashrrev_i32_e32 v173, 31, v172
	v_lshlrev_b64 v[172:173], 9, v[172:173]
	v_add_u32_e32 v134, 0xfffffa00, v131
	v_lshl_add_u64 v[172:173], v[172:173], 0, v[134:135]
	v_mad_u64_u32 v[182:183], s[24:25], v172, s14, v[168:169]
	v_mad_i32_i24 v183, v173, s14, v183
	v_mov_b32_e32 v178, v12
	v_mov_b32_e32 v179, v8
	v_mov_b32_e32 v180, v4
	v_mov_b32_e32 v181, v0
	global_store_dwordx4 v[182:183], v[178:181], off nt
.LBB0_568:
	s_or_b64 exec, exec, s[66:67]
	v_add_u32_e32 v134, 0x71, v128
	v_and_b32_e32 v131, 0x7fd, v134
	v_mad_i64_i32 v[172:173], s[24:25], v134, s13, v[170:171]
	v_cmp_lt_u32_e32 vcc, s19, v131
	v_cvt_pk_bf16_f32 v178, v13, v9
	v_cvt_pk_bf16_f32 v179, v5, v1
	global_store_dwordx2 v[172:173], v[178:179], off nt
	s_and_saveexec_b64 s[66:67], vcc
	s_cbranch_execz .LBB0_570
	v_ashrrev_i32_e32 v172, 11, v134
	v_ashrrev_i32_e32 v173, 31, v172
	v_lshlrev_b64 v[172:173], 9, v[172:173]
	v_add_u32_e32 v134, 0xfffffa00, v131
	v_lshl_add_u64 v[172:173], v[172:173], 0, v[134:135]
	v_mad_u64_u32 v[182:183], s[24:25], v172, s14, v[168:169]
	v_mad_i32_i24 v183, v173, s14, v183
	v_mov_b32_e32 v178, v13
	v_mov_b32_e32 v179, v9
	v_mov_b32_e32 v180, v5
	v_mov_b32_e32 v181, v1
	global_store_dwordx4 v[182:183], v[178:181], off nt
.LBB0_570:
	s_or_b64 exec, exec, s[66:67]
	v_add_u32_e32 v134, 0x72, v128
	v_and_b32_e32 v131, 0x7fe, v134
	v_mad_i64_i32 v[172:173], s[24:25], v134, s13, v[170:171]
	v_cmp_lt_u32_e32 vcc, s19, v131
	v_cvt_pk_bf16_f32 v178, v14, v10
	v_cvt_pk_bf16_f32 v179, v6, v2
	global_store_dwordx2 v[172:173], v[178:179], off nt
	s_and_saveexec_b64 s[66:67], vcc
	s_cbranch_execz .LBB0_572
	v_ashrrev_i32_e32 v172, 11, v134
	v_ashrrev_i32_e32 v173, 31, v172
	v_lshlrev_b64 v[172:173], 9, v[172:173]
	v_add_u32_e32 v134, 0xfffffa00, v131
	v_lshl_add_u64 v[172:173], v[172:173], 0, v[134:135]
	v_mad_u64_u32 v[182:183], s[24:25], v172, s14, v[168:169]
	v_mad_i32_i24 v183, v173, s14, v183
	v_mov_b32_e32 v178, v14
	v_mov_b32_e32 v179, v10
	v_mov_b32_e32 v180, v6
	v_mov_b32_e32 v181, v2
	global_store_dwordx4 v[182:183], v[178:181], off nt
.LBB0_572:
	s_or_b64 exec, exec, s[66:67]
	v_add_u32_e32 v134, 0x73, v128
	v_and_b32_e32 v131, 0x7ff, v134
	v_mad_i64_i32 v[170:171], s[24:25], v134, s13, v[170:171]
	v_cmp_lt_u32_e32 vcc, s19, v131
	v_cvt_pk_bf16_f32 v172, v15, v11
	v_cvt_pk_bf16_f32 v173, v7, v3
	global_store_dwordx2 v[170:171], v[172:173], off nt
	s_and_saveexec_b64 s[66:67], vcc
	s_cbranch_execz .LBB0_574
	v_ashrrev_i32_e32 v170, 11, v134
	v_ashrrev_i32_e32 v171, 31, v170
	v_lshlrev_b64 v[170:171], 9, v[170:171]
	v_add_u32_e32 v134, 0xfffffa00, v131
	v_lshl_add_u64 v[170:171], v[170:171], 0, v[134:135]
	v_mad_u64_u32 v[172:173], s[24:25], v170, s14, v[168:169]
	v_mad_i32_i24 v173, v171, s14, v173
	v_mov_b32_e32 v168, v15
	v_mov_b32_e32 v169, v11
	v_mov_b32_e32 v170, v7
	v_mov_b32_e32 v171, v3
	global_store_dwordx4 v[172:173], v[168:171], off nt

.LBB0_576:
	v_mbcnt_hi_u32_b32 v131, -1, v204
	v_and_b32_e32 v139, 64, v131
	v_xor_b32_e32 v134, 4, v131
	v_add_u32_e32 v139, 64, v139
	v_cmp_lt_i32_e32 vcc, v134, v139
	v_readlane_b32 s36, v253, 44
	v_readlane_b32 s50, v253, 58
	v_cndmask_b32_e32 v131, v131, v134, vcc
	v_lshlrev_b32_e32 v134, 3, v210
	v_and_b32_e32 v139, 24, v134
	v_lshlrev_b32_e32 v134, 2, v174
	v_readlane_b32 s51, v253, 59
	v_and_b32_e32 v141, 4, v210
	v_lshlrev_b32_e32 v131, 2, v131
	v_cmp_lt_u32_e64 s[8:9], 7, v175
	v_cmp_gt_u32_e32 vcc, 10, v175
	v_lshl_add_u64 v[168:169], s[50:51], 0, v[134:135]
	v_cmp_eq_u32_e64 s[0:1], 0, v141
	v_readlane_b32 s37, v253, 45
	v_readlane_b32 s38, v253, 46
	v_readlane_b32 s39, v253, 47
	v_readlane_b32 s40, v253, 48
	v_readlane_b32 s41, v253, 49
	v_readlane_b32 s42, v253, 50
	v_readlane_b32 s43, v253, 51
	v_readlane_b32 s44, v253, 52
	v_readlane_b32 s45, v253, 53
	v_readlane_b32 s46, v253, 54
	v_readlane_b32 s47, v253, 55
	v_readlane_b32 s48, v253, 56
	v_readlane_b32 s49, v253, 57
	v_lshlrev_b32_e32 v141, 5, v128
	v_and_or_b32 v141, v141, s17, v139
	s_waitcnt lgkmcnt(3)
	v_lshlrev_b32_e32 v188, 3, v141
	global_load_dwordx2 v[182:183], v188, s[58:59] offset:256
	global_load_dwordx2 v[180:181], v188, s[58:59] offset:272
	global_load_dwordx2 v[178:179], v188, s[58:59] offset:288
	global_load_dwordx2 v[176:177], v188, s[58:59] offset:304
	s_waitcnt lgkmcnt(1)
	ds_bpermute_b32 v186, v131, v124
	s_waitcnt lgkmcnt(1)
	ds_bpermute_b32 v187, v131, v120
	s_waitcnt vmcnt(7)
	ds_bpermute_b32 v184, v131, v116
	ds_bpermute_b32 v185, v131, v112
	s_and_saveexec_b64 s[24:25], s[8:9]
	s_xor_b64 s[72:73], exec, s[24:25]
	s_cbranch_execz .LBB0_580
	s_and_saveexec_b64 s[74:75], vcc
	s_cbranch_execz .LBB0_579
	v_lshlrev_b64 v[170:171], 5, v[128:129]
	s_waitcnt lgkmcnt(0)
	v_lshl_add_u64 v[184:185], v[168:169], 0, v[170:171]
	v_mov_b32_e32 v170, v124
	v_mov_b32_e32 v171, v120
	v_mov_b32_e32 v172, v116
	v_mov_b32_e32 v173, v112
	v_pk_mul_f32 v[170:171], v[170:171], s[88:89] op_sel_hi:[1,0]
	v_pk_mul_f32 v[172:173], v[172:173], s[88:89] op_sel_hi:[1,0]
	global_store_dwordx4 v[184:185], v[170:173], off offset:-128 nt

.LBB0_580:
	s_or_saveexec_b64 s[72:73], s[72:73]
	v_readlane_b32 s36, v253, 44
	v_lshlrev_b32_e32 v172, 1, v174
	v_mov_b32_e32 v173, v135
	v_readlane_b32 s48, v253, 56
	v_readlane_b32 s49, v253, 57
	v_cndmask_b32_e64 v170, 1.0, -1.0, s[0:1]
	v_lshl_add_u64 v[174:175], s[76:77], 0, v[134:135]
	v_lshl_add_u64 v[172:173], s[48:49], 0, v[172:173]
	v_readlane_b32 s37, v253, 45
	v_readlane_b32 s38, v253, 46
	v_readlane_b32 s39, v253, 47
	v_readlane_b32 s40, v253, 48
	v_readlane_b32 s41, v253, 49
	v_readlane_b32 s42, v253, 50
	v_readlane_b32 s43, v253, 51
	v_readlane_b32 s44, v253, 52
	v_readlane_b32 s45, v253, 53
	v_readlane_b32 s46, v253, 54
	v_readlane_b32 s47, v253, 55
	v_readlane_b32 s50, v253, 58
	v_readlane_b32 s51, v253, 59
	s_xor_b64 exec, exec, s[72:73]
	s_cbranch_execz .LBB0_582
	v_mov_b32_e32 v189, v135
	v_lshl_add_u64 v[188:189], s[58:59], 0, v[188:189]
	global_load_dwordx2 v[194:195], v[188:189], off offset:16
	global_load_dwordx2 v[196:197], v[188:189], off
	v_mov_b32_e32 v198, v124
	v_mov_b32_e32 v199, v120
	s_waitcnt lgkmcnt(2)
	v_pk_mul_f32 v[186:187], v[170:171], v[186:187] op_sel_hi:[0,1]
	v_lshlrev_b64 v[190:191], 6, v[128:129]
	s_waitcnt lgkmcnt(0)
	v_pk_mul_f32 v[184:185], v[170:171], v[184:185] op_sel_hi:[0,1]
	v_lshl_add_u64 v[190:191], v[172:173], 0, v[190:191]
	v_lshlrev_b64 v[192:193], 7, v[128:129]
	v_lshl_add_u64 v[192:193], v[174:175], 0, v[192:193]
	s_waitcnt vmcnt(1)
	v_mov_b32_e32 v201, v194
	s_waitcnt vmcnt(0)
	v_mov_b32_e32 v200, v196
	v_mov_b32_e32 v194, v197
	global_load_dwordx2 v[196:197], v[188:189], off offset:48
	s_nop 0
	global_load_dwordx2 v[188:189], v[188:189], off offset:32
	v_pk_mul_f32 v[198:199], v[198:199], v[200:201]
	s_waitcnt vmcnt(1)
	v_mov_b32_e32 v201, v196
	v_pk_fma_f32 v[186:187], v[186:187], v[194:195], v[198:199]
	v_mov_b32_e32 v198, v116
	v_mov_b32_e32 v199, v112
	s_waitcnt vmcnt(0)
	v_mov_b32_e32 v200, v188
	v_pk_mul_f32 v[198:199], v[198:199], v[200:201]
	v_mov_b32_e32 v196, v189
	v_cvt_pk_bf16_f32 v194, v186, v187
	v_pk_fma_f32 v[188:189], v[184:185], v[196:197], v[198:199]
	s_nop 0
	v_cvt_pk_bf16_f32 v195, v188, v189
	global_store_dwordx2 v[190:191], v[194:195], off nt
	global_store_dwordx4 v[192:193], v[186:189], off nt
.LBB0_582:
	s_or_b64 exec, exec, s[72:73]
	s_waitcnt lgkmcnt(3)
	ds_bpermute_b32 v186, v131, v125
	s_waitcnt lgkmcnt(3)
	ds_bpermute_b32 v187, v131, v121
	s_waitcnt lgkmcnt(3)
	ds_bpermute_b32 v184, v131, v117
	s_waitcnt lgkmcnt(3)
	ds_bpermute_b32 v185, v131, v113
	v_or_b32_e32 v188, 1, v128
	v_ashrrev_i32_e32 v189, 31, v188
	s_and_saveexec_b64 s[0:1], s[8:9]
	s_xor_b64 s[0:1], exec, s[0:1]
	s_cbranch_execz .LBB0_586
	s_and_saveexec_b64 s[72:73], vcc
	s_cbranch_execz .LBB0_585
	s_waitcnt vmcnt(0)
	v_lshlrev_b64 v[176:177], 5, v[188:189]
	v_lshl_add_u64 v[180:181], v[168:169], 0, v[176:177]
	v_mov_b32_e32 v176, v125
	v_mov_b32_e32 v177, v121
	v_mov_b32_e32 v178, v117
	v_mov_b32_e32 v179, v113
	v_pk_mul_f32 v[176:177], v[176:177], s[88:89] op_sel_hi:[1,0]
	v_pk_mul_f32 v[178:179], v[178:179], s[88:89] op_sel_hi:[1,0]
	global_store_dwordx4 v[180:181], v[176:179], off offset:-128 nt

.LBB0_586:
	s_andn2_saveexec_b64 s[0:1], s[0:1]
	s_cbranch_execz .LBB0_588
	s_waitcnt vmcnt(0)
	v_mov_b32_e32 v193, v176
	v_mov_b32_e32 v196, v182
	v_mov_b32_e32 v197, v180
	s_waitcnt lgkmcnt(2)
	v_pk_mul_f32 v[186:187], v[170:171], v[186:187] op_sel_hi:[0,1]
	v_mov_b32_e32 v180, v183
	s_waitcnt lgkmcnt(0)
	v_pk_mul_f32 v[182:183], v[170:171], v[184:185] op_sel_hi:[0,1]
	v_mov_b32_e32 v176, v179
	v_mov_b32_e32 v190, v117
	v_mov_b32_e32 v191, v113
	v_mov_b32_e32 v192, v178
	v_mov_b32_e32 v194, v125
	v_mov_b32_e32 v195, v121
	v_lshlrev_b64 v[198:199], 6, v[188:189]
	v_pk_mul_f32 v[180:181], v[180:181], v[186:187]
	v_pk_mul_f32 v[176:177], v[176:177], v[182:183]
	v_lshl_add_u64 v[198:199], v[172:173], 0, v[198:199]
	v_lshlrev_b64 v[188:189], 7, v[188:189]
	v_pk_fma_f32 v[180:181], v[194:195], v[196:197], v[180:181]
	v_pk_fma_f32 v[182:183], v[190:191], v[192:193], v[176:177]
	v_cvt_pk_bf16_f32 v178, v180, v181
	v_lshl_add_u64 v[188:189], v[174:175], 0, v[188:189]
	v_cvt_pk_bf16_f32 v179, v182, v183
	global_store_dwordx2 v[198:199], v[178:179], off nt
	global_store_dwordx4 v[188:189], v[180:183], off nt
.LBB0_588:
	s_or_b64 exec, exec, s[0:1]
	s_waitcnt lgkmcnt(3)
	v_or_b32_e32 v186, 2, v128
	v_lshlrev_b32_e32 v129, 5, v186
	v_and_or_b32 v129, v129, s18, v139
	v_lshlrev_b32_e32 v134, 3, v129
	global_load_dwordx2 v[182:183], v134, s[58:59] offset:256
	global_load_dwordx2 v[180:181], v134, s[58:59] offset:272
	global_load_dwordx2 v[178:179], v134, s[58:59] offset:288
	global_load_dwordx2 v[176:177], v134, s[58:59] offset:304
	ds_bpermute_b32 v188, v131, v126
	ds_bpermute_b32 v189, v131, v122
	s_waitcnt lgkmcnt(3)
	ds_bpermute_b32 v184, v131, v118
	s_waitcnt lgkmcnt(3)
	ds_bpermute_b32 v185, v131, v114
	v_ashrrev_i32_e32 v187, 31, v186
	s_and_saveexec_b64 s[0:1], s[8:9]
	s_xor_b64 s[0:1], exec, s[0:1]
	s_cbranch_execz .LBB0_592
	s_and_saveexec_b64 s[72:73], vcc
	s_cbranch_execz .LBB0_591
	s_waitcnt lgkmcnt(0)
	v_lshlrev_b64 v[184:185], 5, v[186:187]
	v_lshl_add_u64 v[188:189], v[168:169], 0, v[184:185]
	v_mov_b32_e32 v184, v126
	v_mov_b32_e32 v185, v122
	v_mov_b32_e32 v186, v118
	v_mov_b32_e32 v187, v114
	v_pk_mul_f32 v[184:185], v[184:185], s[88:89] op_sel_hi:[1,0]
	v_pk_mul_f32 v[186:187], v[186:187], s[88:89] op_sel_hi:[1,0]
	global_store_dwordx4 v[188:189], v[184:187], off offset:-128 nt

.LBB0_592:
	s_andn2_saveexec_b64 s[0:1], s[0:1]
	s_cbranch_execz .LBB0_594
	v_lshl_add_u64 v[190:191], s[58:59], 0, v[134:135]
	v_lshlrev_b64 v[192:193], 6, v[186:187]
	v_lshlrev_b64 v[186:187], 7, v[186:187]
	v_lshl_add_u64 v[194:195], v[174:175], 0, v[186:187]
	global_load_dwordx2 v[186:187], v[190:191], off offset:16
	global_load_dwordx2 v[196:197], v[190:191], off
	v_mov_b32_e32 v198, v126
	v_mov_b32_e32 v199, v122
	s_waitcnt lgkmcnt(2)
	v_pk_mul_f32 v[188:189], v[170:171], v[188:189] op_sel_hi:[0,1]
	s_waitcnt lgkmcnt(0)
	v_pk_mul_f32 v[184:185], v[170:171], v[184:185] op_sel_hi:[0,1]
	v_lshl_add_u64 v[192:193], v[172:173], 0, v[192:193]
	s_waitcnt vmcnt(1)
	v_mov_b32_e32 v201, v186
	s_waitcnt vmcnt(0)
	v_mov_b32_e32 v200, v196
	v_pk_mul_f32 v[198:199], v[198:199], v[200:201]
	v_mov_b32_e32 v186, v197
	v_pk_fma_f32 v[186:187], v[188:189], v[186:187], v[198:199]
	global_load_dwordx2 v[188:189], v[190:191], off offset:48
	s_nop 0
	global_load_dwordx2 v[190:191], v[190:191], off offset:32
	v_mov_b32_e32 v198, v118
	v_mov_b32_e32 v199, v114
	v_cvt_pk_bf16_f32 v196, v186, v187
	s_waitcnt vmcnt(1)
	v_mov_b32_e32 v201, v188
	s_waitcnt vmcnt(0)
	v_mov_b32_e32 v200, v190
	v_pk_mul_f32 v[198:199], v[198:199], v[200:201]
	v_mov_b32_e32 v188, v191
	v_pk_fma_f32 v[188:189], v[184:185], v[188:189], v[198:199]
	s_nop 0
	v_cvt_pk_bf16_f32 v197, v188, v189
	global_store_dwordx2 v[192:193], v[196:197], off nt
	global_store_dwordx4 v[194:195], v[186:189], off nt
.LBB0_594:
	s_or_b64 exec, exec, s[0:1]
	ds_bpermute_b32 v186, v131, v127
	ds_bpermute_b32 v187, v131, v123
	s_waitcnt lgkmcnt(3)
	ds_bpermute_b32 v184, v131, v119
	s_waitcnt lgkmcnt(3)
	ds_bpermute_b32 v185, v131, v115
	v_or_b32_e32 v188, 3, v128
	v_ashrrev_i32_e32 v189, 31, v188
	s_and_saveexec_b64 s[0:1], s[8:9]
	s_xor_b64 s[0:1], exec, s[0:1]
	s_cbranch_execz .LBB0_598
	s_and_saveexec_b64 s[72:73], vcc
	s_cbranch_execz .LBB0_597
	s_waitcnt vmcnt(0)
	v_lshlrev_b64 v[176:177], 5, v[188:189]
	v_lshl_add_u64 v[180:181], v[168:169], 0, v[176:177]
	v_mov_b32_e32 v176, v127
	v_mov_b32_e32 v177, v123
	v_mov_b32_e32 v178, v119
	v_mov_b32_e32 v179, v115
	v_pk_mul_f32 v[176:177], v[176:177], s[88:89] op_sel_hi:[1,0]
	v_pk_mul_f32 v[178:179], v[178:179], s[88:89] op_sel_hi:[1,0]
	global_store_dwordx4 v[180:181], v[176:179], off offset:-128 nt

.LBB0_598:
	s_andn2_saveexec_b64 s[0:1], s[0:1]
	s_cbranch_execz .LBB0_600
	s_waitcnt vmcnt(0)
	v_mov_b32_e32 v193, v176
	v_mov_b32_e32 v196, v182
	v_mov_b32_e32 v197, v180
	s_waitcnt lgkmcnt(2)
	v_pk_mul_f32 v[186:187], v[170:171], v[186:187] op_sel_hi:[0,1]
	v_mov_b32_e32 v180, v183
	s_waitcnt lgkmcnt(0)
	v_pk_mul_f32 v[182:183], v[170:171], v[184:185] op_sel_hi:[0,1]
	v_mov_b32_e32 v176, v179
	v_mov_b32_e32 v190, v119
	v_mov_b32_e32 v191, v115
	v_mov_b32_e32 v192, v178
	v_mov_b32_e32 v194, v127
	v_mov_b32_e32 v195, v123
	v_lshlrev_b64 v[198:199], 6, v[188:189]
	v_pk_mul_f32 v[180:181], v[180:181], v[186:187]
	v_pk_mul_f32 v[176:177], v[176:177], v[182:183]
	v_lshl_add_u64 v[198:199], v[172:173], 0, v[198:199]
	v_lshlrev_b64 v[188:189], 7, v[188:189]
	v_pk_fma_f32 v[180:181], v[194:195], v[196:197], v[180:181]
	v_pk_fma_f32 v[182:183], v[190:191], v[192:193], v[176:177]
	v_cvt_pk_bf16_f32 v178, v180, v181
	v_lshl_add_u64 v[188:189], v[174:175], 0, v[188:189]
	v_cvt_pk_bf16_f32 v179, v182, v183
	global_store_dwordx2 v[198:199], v[178:179], off nt
	global_store_dwordx4 v[188:189], v[180:183], off nt
.LBB0_600:
	s_or_b64 exec, exec, s[0:1]
	s_waitcnt lgkmcnt(3)
	v_add_u32_e32 v186, 16, v128
	v_lshlrev_b32_e32 v129, 5, v186
	v_and_or_b32 v129, v129, s17, v139
	v_lshlrev_b32_e32 v134, 3, v129
	global_load_dwordx2 v[182:183], v134, s[58:59] offset:256
	global_load_dwordx2 v[180:181], v134, s[58:59] offset:272
	global_load_dwordx2 v[178:179], v134, s[58:59] offset:288
	global_load_dwordx2 v[176:177], v134, s[58:59] offset:304
	ds_bpermute_b32 v188, v131, v108
	ds_bpermute_b32 v189, v131, v104
	s_waitcnt lgkmcnt(3)
	ds_bpermute_b32 v184, v131, v100
	s_waitcnt lgkmcnt(3)
	ds_bpermute_b32 v185, v131, v96
	v_ashrrev_i32_e32 v187, 31, v186
	s_and_saveexec_b64 s[0:1], s[8:9]
	s_xor_b64 s[0:1], exec, s[0:1]
	s_cbranch_execz .LBB0_604
	s_and_saveexec_b64 s[72:73], vcc
	s_cbranch_execz .LBB0_603
	s_waitcnt lgkmcnt(0)
	v_lshlrev_b64 v[184:185], 5, v[186:187]
	v_lshl_add_u64 v[188:189], v[168:169], 0, v[184:185]
	v_mov_b32_e32 v184, v108
	v_mov_b32_e32 v185, v104
	v_mov_b32_e32 v186, v100
	v_mov_b32_e32 v187, v96
	v_pk_mul_f32 v[184:185], v[184:185], s[88:89] op_sel_hi:[1,0]
	v_pk_mul_f32 v[186:187], v[186:187], s[88:89] op_sel_hi:[1,0]
	global_store_dwordx4 v[188:189], v[184:187], off offset:-128 nt

.LBB0_604:
	s_andn2_saveexec_b64 s[0:1], s[0:1]
	s_cbranch_execz .LBB0_606
	v_lshl_add_u64 v[190:191], s[58:59], 0, v[134:135]
	v_lshlrev_b64 v[192:193], 6, v[186:187]
	v_lshlrev_b64 v[186:187], 7, v[186:187]
	v_lshl_add_u64 v[194:195], v[174:175], 0, v[186:187]
	global_load_dwordx2 v[186:187], v[190:191], off offset:16
	global_load_dwordx2 v[196:197], v[190:191], off
	v_mov_b32_e32 v198, v108
	v_mov_b32_e32 v199, v104
	s_waitcnt lgkmcnt(2)
	v_pk_mul_f32 v[188:189], v[170:171], v[188:189] op_sel_hi:[0,1]
	s_waitcnt lgkmcnt(0)
	v_pk_mul_f32 v[184:185], v[170:171], v[184:185] op_sel_hi:[0,1]
	v_lshl_add_u64 v[192:193], v[172:173], 0, v[192:193]
	s_waitcnt vmcnt(1)
	v_mov_b32_e32 v201, v186
	s_waitcnt vmcnt(0)
	v_mov_b32_e32 v200, v196
	v_pk_mul_f32 v[198:199], v[198:199], v[200:201]
	v_mov_b32_e32 v186, v197
	v_pk_fma_f32 v[186:187], v[188:189], v[186:187], v[198:199]
	global_load_dwordx2 v[188:189], v[190:191], off offset:48
	s_nop 0
	global_load_dwordx2 v[190:191], v[190:191], off offset:32
	v_mov_b32_e32 v198, v100
	v_mov_b32_e32 v199, v96
	v_cvt_pk_bf16_f32 v196, v186, v187
	s_waitcnt vmcnt(1)
	v_mov_b32_e32 v201, v188
	s_waitcnt vmcnt(0)
	v_mov_b32_e32 v200, v190
	v_pk_mul_f32 v[198:199], v[198:199], v[200:201]
	v_mov_b32_e32 v188, v191
	v_pk_fma_f32 v[188:189], v[184:185], v[188:189], v[198:199]
	s_nop 0
	v_cvt_pk_bf16_f32 v197, v188, v189
	global_store_dwordx2 v[192:193], v[196:197], off nt
	global_store_dwordx4 v[194:195], v[186:189], off nt
.LBB0_606:
	s_or_b64 exec, exec, s[0:1]
	ds_bpermute_b32 v186, v131, v109
	ds_bpermute_b32 v187, v131, v105
	s_waitcnt lgkmcnt(3)
	ds_bpermute_b32 v184, v131, v101
	s_waitcnt lgkmcnt(3)
	ds_bpermute_b32 v185, v131, v97
	v_add_u32_e32 v188, 17, v128
	v_ashrrev_i32_e32 v189, 31, v188
	s_and_saveexec_b64 s[0:1], s[8:9]
	s_xor_b64 s[0:1], exec, s[0:1]
	s_cbranch_execz .LBB0_610
	s_and_saveexec_b64 s[72:73], vcc
	s_cbranch_execz .LBB0_609
	s_waitcnt vmcnt(0)
	v_lshlrev_b64 v[176:177], 5, v[188:189]
	v_lshl_add_u64 v[180:181], v[168:169], 0, v[176:177]
	v_mov_b32_e32 v176, v109
	v_mov_b32_e32 v177, v105
	v_mov_b32_e32 v178, v101
	v_mov_b32_e32 v179, v97
	v_pk_mul_f32 v[176:177], v[176:177], s[88:89] op_sel_hi:[1,0]
	v_pk_mul_f32 v[178:179], v[178:179], s[88:89] op_sel_hi:[1,0]
	global_store_dwordx4 v[180:181], v[176:179], off offset:-128 nt

.LBB0_610:
	s_andn2_saveexec_b64 s[0:1], s[0:1]
	s_cbranch_execz .LBB0_612
	s_waitcnt vmcnt(0)
	v_mov_b32_e32 v193, v176
	v_mov_b32_e32 v196, v182
	v_mov_b32_e32 v197, v180
	s_waitcnt lgkmcnt(2)
	v_pk_mul_f32 v[186:187], v[170:171], v[186:187] op_sel_hi:[0,1]
	v_mov_b32_e32 v180, v183
	s_waitcnt lgkmcnt(0)
	v_pk_mul_f32 v[182:183], v[170:171], v[184:185] op_sel_hi:[0,1]
	v_mov_b32_e32 v176, v179
	v_mov_b32_e32 v190, v101
	v_mov_b32_e32 v191, v97
	v_mov_b32_e32 v192, v178
	v_mov_b32_e32 v194, v109
	v_mov_b32_e32 v195, v105
	v_lshlrev_b64 v[198:199], 6, v[188:189]
	v_pk_mul_f32 v[180:181], v[180:181], v[186:187]
	v_pk_mul_f32 v[176:177], v[176:177], v[182:183]
	v_lshl_add_u64 v[198:199], v[172:173], 0, v[198:199]
	v_lshlrev_b64 v[188:189], 7, v[188:189]
	v_pk_fma_f32 v[180:181], v[194:195], v[196:197], v[180:181]
	v_pk_fma_f32 v[182:183], v[190:191], v[192:193], v[176:177]
	v_cvt_pk_bf16_f32 v178, v180, v181
	v_lshl_add_u64 v[188:189], v[174:175], 0, v[188:189]
	v_cvt_pk_bf16_f32 v179, v182, v183
	global_store_dwordx2 v[198:199], v[178:179], off nt
	global_store_dwordx4 v[188:189], v[180:183], off nt
.LBB0_612:
	s_or_b64 exec, exec, s[0:1]
	s_waitcnt lgkmcnt(3)
	v_add_u32_e32 v186, 18, v128
	v_lshlrev_b32_e32 v129, 5, v186
	v_and_or_b32 v129, v129, s18, v139
	v_lshlrev_b32_e32 v134, 3, v129
	global_load_dwordx2 v[182:183], v134, s[58:59] offset:256
	global_load_dwordx2 v[180:181], v134, s[58:59] offset:272
	global_load_dwordx2 v[178:179], v134, s[58:59] offset:288
	global_load_dwordx2 v[176:177], v134, s[58:59] offset:304
	ds_bpermute_b32 v188, v131, v110
	ds_bpermute_b32 v189, v131, v106
	s_waitcnt lgkmcnt(3)
	ds_bpermute_b32 v184, v131, v102
	s_waitcnt lgkmcnt(3)
	ds_bpermute_b32 v185, v131, v98
	v_ashrrev_i32_e32 v187, 31, v186
	s_and_saveexec_b64 s[0:1], s[8:9]
	s_xor_b64 s[0:1], exec, s[0:1]
	s_cbranch_execz .LBB0_616
	s_and_saveexec_b64 s[72:73], vcc
	s_cbranch_execz .LBB0_615
	s_waitcnt lgkmcnt(0)
	v_lshlrev_b64 v[184:185], 5, v[186:187]
	v_lshl_add_u64 v[188:189], v[168:169], 0, v[184:185]
	v_mov_b32_e32 v184, v110
	v_mov_b32_e32 v185, v106
	v_mov_b32_e32 v186, v102
	v_mov_b32_e32 v187, v98
	v_pk_mul_f32 v[184:185], v[184:185], s[88:89] op_sel_hi:[1,0]
	v_pk_mul_f32 v[186:187], v[186:187], s[88:89] op_sel_hi:[1,0]
	global_store_dwordx4 v[188:189], v[184:187], off offset:-128 nt

.LBB0_616:
	s_andn2_saveexec_b64 s[0:1], s[0:1]
	s_cbranch_execz .LBB0_618
	v_lshl_add_u64 v[190:191], s[58:59], 0, v[134:135]
	v_lshlrev_b64 v[192:193], 6, v[186:187]
	v_lshlrev_b64 v[186:187], 7, v[186:187]
	v_lshl_add_u64 v[194:195], v[174:175], 0, v[186:187]
	global_load_dwordx2 v[186:187], v[190:191], off offset:16
	global_load_dwordx2 v[196:197], v[190:191], off
	v_mov_b32_e32 v198, v110
	v_mov_b32_e32 v199, v106
	s_waitcnt lgkmcnt(2)
	v_pk_mul_f32 v[188:189], v[170:171], v[188:189] op_sel_hi:[0,1]
	s_waitcnt lgkmcnt(0)
	v_pk_mul_f32 v[184:185], v[170:171], v[184:185] op_sel_hi:[0,1]
	v_lshl_add_u64 v[192:193], v[172:173], 0, v[192:193]
	s_waitcnt vmcnt(1)
	v_mov_b32_e32 v201, v186
	s_waitcnt vmcnt(0)
	v_mov_b32_e32 v200, v196
	v_pk_mul_f32 v[198:199], v[198:199], v[200:201]
	v_mov_b32_e32 v186, v197
	v_pk_fma_f32 v[186:187], v[188:189], v[186:187], v[198:199]
	global_load_dwordx2 v[188:189], v[190:191], off offset:48
	s_nop 0
	global_load_dwordx2 v[190:191], v[190:191], off offset:32
	v_mov_b32_e32 v198, v102
	v_mov_b32_e32 v199, v98
	v_cvt_pk_bf16_f32 v196, v186, v187
	s_waitcnt vmcnt(1)
	v_mov_b32_e32 v201, v188
	s_waitcnt vmcnt(0)
	v_mov_b32_e32 v200, v190
	v_pk_mul_f32 v[198:199], v[198:199], v[200:201]
	v_mov_b32_e32 v188, v191
	v_pk_fma_f32 v[188:189], v[184:185], v[188:189], v[198:199]
	s_nop 0
	v_cvt_pk_bf16_f32 v197, v188, v189
	global_store_dwordx2 v[192:193], v[196:197], off nt
	global_store_dwordx4 v[194:195], v[186:189], off nt
.LBB0_618:
	s_or_b64 exec, exec, s[0:1]
	ds_bpermute_b32 v186, v131, v111
	ds_bpermute_b32 v187, v131, v107
	s_waitcnt lgkmcnt(3)
	ds_bpermute_b32 v184, v131, v103
	s_waitcnt lgkmcnt(3)
	ds_bpermute_b32 v185, v131, v99
	v_add_u32_e32 v188, 19, v128
	v_ashrrev_i32_e32 v189, 31, v188
	s_and_saveexec_b64 s[0:1], s[8:9]
	s_xor_b64 s[0:1], exec, s[0:1]
	s_cbranch_execz .LBB0_622
	s_and_saveexec_b64 s[72:73], vcc
	s_cbranch_execz .LBB0_621
	s_waitcnt vmcnt(0)
	v_lshlrev_b64 v[176:177], 5, v[188:189]
	v_lshl_add_u64 v[180:181], v[168:169], 0, v[176:177]
	v_mov_b32_e32 v176, v111
	v_mov_b32_e32 v177, v107
	v_mov_b32_e32 v178, v103
	v_mov_b32_e32 v179, v99
	v_pk_mul_f32 v[176:177], v[176:177], s[88:89] op_sel_hi:[1,0]
	v_pk_mul_f32 v[178:179], v[178:179], s[88:89] op_sel_hi:[1,0]
	global_store_dwordx4 v[180:181], v[176:179], off offset:-128 nt

.LBB0_622:
	s_andn2_saveexec_b64 s[0:1], s[0:1]
	s_cbranch_execz .LBB0_624
	s_waitcnt vmcnt(0)
	v_mov_b32_e32 v193, v176
	v_mov_b32_e32 v196, v182
	v_mov_b32_e32 v197, v180
	s_waitcnt lgkmcnt(2)
	v_pk_mul_f32 v[186:187], v[170:171], v[186:187] op_sel_hi:[0,1]
	v_mov_b32_e32 v180, v183
	s_waitcnt lgkmcnt(0)
	v_pk_mul_f32 v[182:183], v[170:171], v[184:185] op_sel_hi:[0,1]
	v_mov_b32_e32 v176, v179
	v_mov_b32_e32 v190, v103
	v_mov_b32_e32 v191, v99
	v_mov_b32_e32 v192, v178
	v_mov_b32_e32 v194, v111
	v_mov_b32_e32 v195, v107
	v_lshlrev_b64 v[198:199], 6, v[188:189]
	v_pk_mul_f32 v[180:181], v[180:181], v[186:187]
	v_pk_mul_f32 v[176:177], v[176:177], v[182:183]
	v_lshl_add_u64 v[198:199], v[172:173], 0, v[198:199]
	v_lshlrev_b64 v[188:189], 7, v[188:189]
	v_pk_fma_f32 v[180:181], v[194:195], v[196:197], v[180:181]
	v_pk_fma_f32 v[182:183], v[190:191], v[192:193], v[176:177]
	v_cvt_pk_bf16_f32 v178, v180, v181
	v_lshl_add_u64 v[188:189], v[174:175], 0, v[188:189]
	v_cvt_pk_bf16_f32 v179, v182, v183
	global_store_dwordx2 v[198:199], v[178:179], off nt
	global_store_dwordx4 v[188:189], v[180:183], off nt
.LBB0_624:
	s_or_b64 exec, exec, s[0:1]
	s_waitcnt lgkmcnt(3)
	v_add_u32_e32 v186, 32, v128
	v_lshlrev_b32_e32 v129, 5, v186
	v_and_or_b32 v129, v129, s17, v139
	v_lshlrev_b32_e32 v134, 3, v129
	global_load_dwordx2 v[182:183], v134, s[58:59] offset:256
	global_load_dwordx2 v[180:181], v134, s[58:59] offset:272
	global_load_dwordx2 v[178:179], v134, s[58:59] offset:288
	global_load_dwordx2 v[176:177], v134, s[58:59] offset:304
	ds_bpermute_b32 v188, v131, v92
	ds_bpermute_b32 v189, v131, v88
	s_waitcnt lgkmcnt(3)
	ds_bpermute_b32 v184, v131, v84
	s_waitcnt lgkmcnt(3)
	ds_bpermute_b32 v185, v131, v80
	v_ashrrev_i32_e32 v187, 31, v186
	s_and_saveexec_b64 s[0:1], s[8:9]
	s_xor_b64 s[0:1], exec, s[0:1]
	s_cbranch_execz .LBB0_628
	s_and_saveexec_b64 s[72:73], vcc
	s_cbranch_execz .LBB0_627
	s_waitcnt lgkmcnt(0)
	v_lshlrev_b64 v[184:185], 5, v[186:187]
	v_lshl_add_u64 v[188:189], v[168:169], 0, v[184:185]
	v_mov_b32_e32 v184, v92
	v_mov_b32_e32 v185, v88
	v_mov_b32_e32 v186, v84
	v_mov_b32_e32 v187, v80
	v_pk_mul_f32 v[184:185], v[184:185], s[88:89] op_sel_hi:[1,0]
	v_pk_mul_f32 v[186:187], v[186:187], s[88:89] op_sel_hi:[1,0]
	global_store_dwordx4 v[188:189], v[184:187], off offset:-128 nt

.LBB0_628:
	s_andn2_saveexec_b64 s[0:1], s[0:1]
	s_cbranch_execz .LBB0_630
	v_lshl_add_u64 v[190:191], s[58:59], 0, v[134:135]
	v_lshlrev_b64 v[192:193], 6, v[186:187]
	v_lshlrev_b64 v[186:187], 7, v[186:187]
	v_lshl_add_u64 v[194:195], v[174:175], 0, v[186:187]
	global_load_dwordx2 v[186:187], v[190:191], off offset:16
	global_load_dwordx2 v[196:197], v[190:191], off
	v_mov_b32_e32 v198, v92
	v_mov_b32_e32 v199, v88
	s_waitcnt lgkmcnt(2)
	v_pk_mul_f32 v[188:189], v[170:171], v[188:189] op_sel_hi:[0,1]
	s_waitcnt lgkmcnt(0)
	v_pk_mul_f32 v[184:185], v[170:171], v[184:185] op_sel_hi:[0,1]
	v_lshl_add_u64 v[192:193], v[172:173], 0, v[192:193]
	s_waitcnt vmcnt(1)
	v_mov_b32_e32 v201, v186
	s_waitcnt vmcnt(0)
	v_mov_b32_e32 v200, v196
	v_pk_mul_f32 v[198:199], v[198:199], v[200:201]
	v_mov_b32_e32 v186, v197
	v_pk_fma_f32 v[186:187], v[188:189], v[186:187], v[198:199]
	global_load_dwordx2 v[188:189], v[190:191], off offset:48
	s_nop 0
	global_load_dwordx2 v[190:191], v[190:191], off offset:32
	v_mov_b32_e32 v198, v84
	v_mov_b32_e32 v199, v80
	v_cvt_pk_bf16_f32 v196, v186, v187
	s_waitcnt vmcnt(1)
	v_mov_b32_e32 v201, v188
	s_waitcnt vmcnt(0)
	v_mov_b32_e32 v200, v190
	v_pk_mul_f32 v[198:199], v[198:199], v[200:201]
	v_mov_b32_e32 v188, v191
	v_pk_fma_f32 v[188:189], v[184:185], v[188:189], v[198:199]
	s_nop 0
	v_cvt_pk_bf16_f32 v197, v188, v189
	global_store_dwordx2 v[192:193], v[196:197], off nt
	global_store_dwordx4 v[194:195], v[186:189], off nt
.LBB0_630:
	s_or_b64 exec, exec, s[0:1]
	ds_bpermute_b32 v186, v131, v93
	ds_bpermute_b32 v187, v131, v89
	s_waitcnt lgkmcnt(3)
	ds_bpermute_b32 v184, v131, v85
	s_waitcnt lgkmcnt(3)
	ds_bpermute_b32 v185, v131, v81
	v_add_u32_e32 v188, 33, v128
	v_ashrrev_i32_e32 v189, 31, v188
	s_and_saveexec_b64 s[0:1], s[8:9]
	s_xor_b64 s[0:1], exec, s[0:1]
	s_cbranch_execz .LBB0_634
	s_and_saveexec_b64 s[72:73], vcc
	s_cbranch_execz .LBB0_633
	s_waitcnt vmcnt(0)
	v_lshlrev_b64 v[176:177], 5, v[188:189]
	v_lshl_add_u64 v[180:181], v[168:169], 0, v[176:177]
	v_mov_b32_e32 v176, v93
	v_mov_b32_e32 v177, v89
	v_mov_b32_e32 v178, v85
	v_mov_b32_e32 v179, v81
	v_pk_mul_f32 v[176:177], v[176:177], s[88:89] op_sel_hi:[1,0]
	v_pk_mul_f32 v[178:179], v[178:179], s[88:89] op_sel_hi:[1,0]
	global_store_dwordx4 v[180:181], v[176:179], off offset:-128 nt

.LBB0_634:
	s_andn2_saveexec_b64 s[0:1], s[0:1]
	s_cbranch_execz .LBB0_636
	s_waitcnt vmcnt(0)
	v_mov_b32_e32 v193, v176
	v_mov_b32_e32 v196, v182
	v_mov_b32_e32 v197, v180
	s_waitcnt lgkmcnt(2)
	v_pk_mul_f32 v[186:187], v[170:171], v[186:187] op_sel_hi:[0,1]
	v_mov_b32_e32 v180, v183
	s_waitcnt lgkmcnt(0)
	v_pk_mul_f32 v[182:183], v[170:171], v[184:185] op_sel_hi:[0,1]
	v_mov_b32_e32 v176, v179
	v_mov_b32_e32 v190, v85
	v_mov_b32_e32 v191, v81
	v_mov_b32_e32 v192, v178
	v_mov_b32_e32 v194, v93
	v_mov_b32_e32 v195, v89
	v_lshlrev_b64 v[198:199], 6, v[188:189]
	v_pk_mul_f32 v[180:181], v[180:181], v[186:187]
	v_pk_mul_f32 v[176:177], v[176:177], v[182:183]
	v_lshl_add_u64 v[198:199], v[172:173], 0, v[198:199]
	v_lshlrev_b64 v[188:189], 7, v[188:189]
	v_pk_fma_f32 v[180:181], v[194:195], v[196:197], v[180:181]
	v_pk_fma_f32 v[182:183], v[190:191], v[192:193], v[176:177]
	v_cvt_pk_bf16_f32 v178, v180, v181
	v_lshl_add_u64 v[188:189], v[174:175], 0, v[188:189]
	v_cvt_pk_bf16_f32 v179, v182, v183
	global_store_dwordx2 v[198:199], v[178:179], off nt
	global_store_dwordx4 v[188:189], v[180:183], off nt
.LBB0_636:
	s_or_b64 exec, exec, s[0:1]
	s_waitcnt lgkmcnt(3)
	v_add_u32_e32 v186, 34, v128
	v_lshlrev_b32_e32 v129, 5, v186
	v_and_or_b32 v129, v129, s18, v139
	v_lshlrev_b32_e32 v134, 3, v129
	global_load_dwordx2 v[182:183], v134, s[58:59] offset:256
	global_load_dwordx2 v[180:181], v134, s[58:59] offset:272
	global_load_dwordx2 v[178:179], v134, s[58:59] offset:288
	global_load_dwordx2 v[176:177], v134, s[58:59] offset:304
	ds_bpermute_b32 v188, v131, v94
	ds_bpermute_b32 v189, v131, v90
	s_waitcnt lgkmcnt(3)
	ds_bpermute_b32 v184, v131, v86
	s_waitcnt lgkmcnt(3)
	ds_bpermute_b32 v185, v131, v82
	v_ashrrev_i32_e32 v187, 31, v186
	s_and_saveexec_b64 s[0:1], s[8:9]
	s_xor_b64 s[0:1], exec, s[0:1]
	s_cbranch_execz .LBB0_640
	s_and_saveexec_b64 s[72:73], vcc
	s_cbranch_execz .LBB0_639
	s_waitcnt lgkmcnt(0)
	v_lshlrev_b64 v[184:185], 5, v[186:187]
	v_lshl_add_u64 v[188:189], v[168:169], 0, v[184:185]
	v_mov_b32_e32 v184, v94
	v_mov_b32_e32 v185, v90
	v_mov_b32_e32 v186, v86
	v_mov_b32_e32 v187, v82
	v_pk_mul_f32 v[184:185], v[184:185], s[88:89] op_sel_hi:[1,0]
	v_pk_mul_f32 v[186:187], v[186:187], s[88:89] op_sel_hi:[1,0]
	global_store_dwordx4 v[188:189], v[184:187], off offset:-128 nt

.LBB0_640:
	s_andn2_saveexec_b64 s[0:1], s[0:1]
	s_cbranch_execz .LBB0_642
	v_lshl_add_u64 v[190:191], s[58:59], 0, v[134:135]
	v_lshlrev_b64 v[192:193], 6, v[186:187]
	v_lshlrev_b64 v[186:187], 7, v[186:187]
	v_lshl_add_u64 v[194:195], v[174:175], 0, v[186:187]
	global_load_dwordx2 v[186:187], v[190:191], off offset:16
	global_load_dwordx2 v[196:197], v[190:191], off
	v_mov_b32_e32 v198, v94
	v_mov_b32_e32 v199, v90
	s_waitcnt lgkmcnt(2)
	v_pk_mul_f32 v[188:189], v[170:171], v[188:189] op_sel_hi:[0,1]
	s_waitcnt lgkmcnt(0)
	v_pk_mul_f32 v[184:185], v[170:171], v[184:185] op_sel_hi:[0,1]
	v_lshl_add_u64 v[192:193], v[172:173], 0, v[192:193]
	s_waitcnt vmcnt(1)
	v_mov_b32_e32 v201, v186
	s_waitcnt vmcnt(0)
	v_mov_b32_e32 v200, v196
	v_pk_mul_f32 v[198:199], v[198:199], v[200:201]
	v_mov_b32_e32 v186, v197
	v_pk_fma_f32 v[186:187], v[188:189], v[186:187], v[198:199]
	global_load_dwordx2 v[188:189], v[190:191], off offset:48
	s_nop 0
	global_load_dwordx2 v[190:191], v[190:191], off offset:32
	v_mov_b32_e32 v198, v86
	v_mov_b32_e32 v199, v82
	v_cvt_pk_bf16_f32 v196, v186, v187
	s_waitcnt vmcnt(1)
	v_mov_b32_e32 v201, v188
	s_waitcnt vmcnt(0)
	v_mov_b32_e32 v200, v190
	v_pk_mul_f32 v[198:199], v[198:199], v[200:201]
	v_mov_b32_e32 v188, v191
	v_pk_fma_f32 v[188:189], v[184:185], v[188:189], v[198:199]
	s_nop 0
	v_cvt_pk_bf16_f32 v197, v188, v189
	global_store_dwordx2 v[192:193], v[196:197], off nt
	global_store_dwordx4 v[194:195], v[186:189], off nt
.LBB0_642:
	s_or_b64 exec, exec, s[0:1]
	ds_bpermute_b32 v186, v131, v95
	ds_bpermute_b32 v187, v131, v91
	s_waitcnt lgkmcnt(3)
	ds_bpermute_b32 v184, v131, v87
	s_waitcnt lgkmcnt(3)
	ds_bpermute_b32 v185, v131, v83
	v_add_u32_e32 v188, 35, v128
	v_ashrrev_i32_e32 v189, 31, v188
	s_and_saveexec_b64 s[0:1], s[8:9]
	s_xor_b64 s[0:1], exec, s[0:1]
	s_cbranch_execz .LBB0_646
	s_and_saveexec_b64 s[72:73], vcc
	s_cbranch_execz .LBB0_645
	s_waitcnt vmcnt(0)
	v_lshlrev_b64 v[176:177], 5, v[188:189]
	v_lshl_add_u64 v[180:181], v[168:169], 0, v[176:177]
	v_mov_b32_e32 v176, v95
	v_mov_b32_e32 v177, v91
	v_mov_b32_e32 v178, v87
	v_mov_b32_e32 v179, v83
	v_pk_mul_f32 v[176:177], v[176:177], s[88:89] op_sel_hi:[1,0]
	v_pk_mul_f32 v[178:179], v[178:179], s[88:89] op_sel_hi:[1,0]
	global_store_dwordx4 v[180:181], v[176:179], off offset:-128 nt

.LBB0_646:
	s_andn2_saveexec_b64 s[0:1], s[0:1]
	s_cbranch_execz .LBB0_648
	s_waitcnt vmcnt(0)
	v_mov_b32_e32 v193, v176
	v_mov_b32_e32 v196, v182
	v_mov_b32_e32 v197, v180
	s_waitcnt lgkmcnt(2)
	v_pk_mul_f32 v[186:187], v[170:171], v[186:187] op_sel_hi:[0,1]
	v_mov_b32_e32 v180, v183
	s_waitcnt lgkmcnt(0)
	v_pk_mul_f32 v[182:183], v[170:171], v[184:185] op_sel_hi:[0,1]
	v_mov_b32_e32 v176, v179
	v_mov_b32_e32 v190, v87
	v_mov_b32_e32 v191, v83
	v_mov_b32_e32 v192, v178
	v_mov_b32_e32 v194, v95
	v_mov_b32_e32 v195, v91
	v_lshlrev_b64 v[198:199], 6, v[188:189]
	v_pk_mul_f32 v[180:181], v[180:181], v[186:187]
	v_pk_mul_f32 v[176:177], v[176:177], v[182:183]
	v_lshl_add_u64 v[198:199], v[172:173], 0, v[198:199]
	v_lshlrev_b64 v[188:189], 7, v[188:189]
	v_pk_fma_f32 v[180:181], v[194:195], v[196:197], v[180:181]
	v_pk_fma_f32 v[182:183], v[190:191], v[192:193], v[176:177]
	v_cvt_pk_bf16_f32 v178, v180, v181
	v_lshl_add_u64 v[188:189], v[174:175], 0, v[188:189]
	v_cvt_pk_bf16_f32 v179, v182, v183
	global_store_dwordx2 v[198:199], v[178:179], off nt
	global_store_dwordx4 v[188:189], v[180:183], off nt
.LBB0_648:
	s_or_b64 exec, exec, s[0:1]
	s_waitcnt lgkmcnt(3)
	v_add_u32_e32 v186, 48, v128
	v_lshlrev_b32_e32 v129, 5, v186
	v_and_or_b32 v129, v129, s17, v139
	v_lshlrev_b32_e32 v134, 3, v129
	global_load_dwordx2 v[182:183], v134, s[58:59] offset:256
	global_load_dwordx2 v[180:181], v134, s[58:59] offset:272
	global_load_dwordx2 v[178:179], v134, s[58:59] offset:288
	global_load_dwordx2 v[176:177], v134, s[58:59] offset:304
	ds_bpermute_b32 v188, v131, v76
	ds_bpermute_b32 v189, v131, v72
	s_waitcnt lgkmcnt(3)
	ds_bpermute_b32 v184, v131, v68
	s_waitcnt lgkmcnt(3)
	ds_bpermute_b32 v185, v131, v64
	v_ashrrev_i32_e32 v187, 31, v186
	s_and_saveexec_b64 s[0:1], s[8:9]
	s_xor_b64 s[0:1], exec, s[0:1]
	s_cbranch_execz .LBB0_652
	s_and_saveexec_b64 s[72:73], vcc
	s_cbranch_execz .LBB0_651
	s_waitcnt lgkmcnt(0)
	v_lshlrev_b64 v[184:185], 5, v[186:187]
	v_lshl_add_u64 v[188:189], v[168:169], 0, v[184:185]
	v_mov_b32_e32 v184, v76
	v_mov_b32_e32 v185, v72
	v_mov_b32_e32 v186, v68
	v_mov_b32_e32 v187, v64
	v_pk_mul_f32 v[184:185], v[184:185], s[88:89] op_sel_hi:[1,0]
	v_pk_mul_f32 v[186:187], v[186:187], s[88:89] op_sel_hi:[1,0]
	global_store_dwordx4 v[188:189], v[184:187], off offset:-128 nt

.LBB0_652:
	s_andn2_saveexec_b64 s[0:1], s[0:1]
	s_cbranch_execz .LBB0_654
	v_lshl_add_u64 v[190:191], s[58:59], 0, v[134:135]
	v_lshlrev_b64 v[192:193], 6, v[186:187]
	v_lshlrev_b64 v[186:187], 7, v[186:187]
	v_lshl_add_u64 v[194:195], v[174:175], 0, v[186:187]
	global_load_dwordx2 v[186:187], v[190:191], off offset:16
	global_load_dwordx2 v[196:197], v[190:191], off
	v_mov_b32_e32 v198, v76
	v_mov_b32_e32 v199, v72
	s_waitcnt lgkmcnt(2)
	v_pk_mul_f32 v[188:189], v[170:171], v[188:189] op_sel_hi:[0,1]
	s_waitcnt lgkmcnt(0)
	v_pk_mul_f32 v[184:185], v[170:171], v[184:185] op_sel_hi:[0,1]
	v_lshl_add_u64 v[192:193], v[172:173], 0, v[192:193]
	s_waitcnt vmcnt(1)
	v_mov_b32_e32 v201, v186
	s_waitcnt vmcnt(0)
	v_mov_b32_e32 v200, v196
	v_pk_mul_f32 v[198:199], v[198:199], v[200:201]
	v_mov_b32_e32 v186, v197
	v_pk_fma_f32 v[186:187], v[188:189], v[186:187], v[198:199]
	global_load_dwordx2 v[188:189], v[190:191], off offset:48
	s_nop 0
	global_load_dwordx2 v[190:191], v[190:191], off offset:32
	v_mov_b32_e32 v198, v68
	v_mov_b32_e32 v199, v64
	v_cvt_pk_bf16_f32 v196, v186, v187
	s_waitcnt vmcnt(1)
	v_mov_b32_e32 v201, v188
	s_waitcnt vmcnt(0)
	v_mov_b32_e32 v200, v190
	v_pk_mul_f32 v[198:199], v[198:199], v[200:201]
	v_mov_b32_e32 v188, v191
	v_pk_fma_f32 v[188:189], v[184:185], v[188:189], v[198:199]
	s_nop 0
	v_cvt_pk_bf16_f32 v197, v188, v189
	global_store_dwordx2 v[192:193], v[196:197], off nt
	global_store_dwordx4 v[194:195], v[186:189], off nt
.LBB0_654:
	s_or_b64 exec, exec, s[0:1]
	ds_bpermute_b32 v186, v131, v77
	ds_bpermute_b32 v187, v131, v73
	s_waitcnt lgkmcnt(3)
	ds_bpermute_b32 v184, v131, v69
	s_waitcnt lgkmcnt(3)
	ds_bpermute_b32 v185, v131, v65
	v_add_u32_e32 v188, 49, v128
	v_ashrrev_i32_e32 v189, 31, v188
	s_and_saveexec_b64 s[0:1], s[8:9]
	s_xor_b64 s[0:1], exec, s[0:1]
	s_cbranch_execz .LBB0_658
	s_and_saveexec_b64 s[72:73], vcc
	s_cbranch_execz .LBB0_657
	s_waitcnt vmcnt(0)
	v_lshlrev_b64 v[176:177], 5, v[188:189]
	v_lshl_add_u64 v[180:181], v[168:169], 0, v[176:177]
	v_mov_b32_e32 v176, v77
	v_mov_b32_e32 v177, v73
	v_mov_b32_e32 v178, v69
	v_mov_b32_e32 v179, v65
	v_pk_mul_f32 v[176:177], v[176:177], s[88:89] op_sel_hi:[1,0]
	v_pk_mul_f32 v[178:179], v[178:179], s[88:89] op_sel_hi:[1,0]
	global_store_dwordx4 v[180:181], v[176:179], off offset:-128 nt

.LBB0_658:
	s_andn2_saveexec_b64 s[0:1], s[0:1]
	s_cbranch_execz .LBB0_660
	s_waitcnt vmcnt(0)
	v_mov_b32_e32 v193, v176
	v_mov_b32_e32 v196, v182
	v_mov_b32_e32 v197, v180
	s_waitcnt lgkmcnt(2)
	v_pk_mul_f32 v[186:187], v[170:171], v[186:187] op_sel_hi:[0,1]
	v_mov_b32_e32 v180, v183
	s_waitcnt lgkmcnt(0)
	v_pk_mul_f32 v[182:183], v[170:171], v[184:185] op_sel_hi:[0,1]
	v_mov_b32_e32 v176, v179
	v_mov_b32_e32 v190, v69
	v_mov_b32_e32 v191, v65
	v_mov_b32_e32 v192, v178
	v_mov_b32_e32 v194, v77
	v_mov_b32_e32 v195, v73
	v_lshlrev_b64 v[198:199], 6, v[188:189]
	v_pk_mul_f32 v[180:181], v[180:181], v[186:187]
	v_pk_mul_f32 v[176:177], v[176:177], v[182:183]
	v_lshl_add_u64 v[198:199], v[172:173], 0, v[198:199]
	v_lshlrev_b64 v[188:189], 7, v[188:189]
	v_pk_fma_f32 v[180:181], v[194:195], v[196:197], v[180:181]
	v_pk_fma_f32 v[182:183], v[190:191], v[192:193], v[176:177]
	v_cvt_pk_bf16_f32 v178, v180, v181
	v_lshl_add_u64 v[188:189], v[174:175], 0, v[188:189]
	v_cvt_pk_bf16_f32 v179, v182, v183
	global_store_dwordx2 v[198:199], v[178:179], off nt
	global_store_dwordx4 v[188:189], v[180:183], off nt
.LBB0_660:
	s_or_b64 exec, exec, s[0:1]
	s_waitcnt lgkmcnt(3)
	v_add_u32_e32 v186, 50, v128
	v_lshlrev_b32_e32 v129, 5, v186
	v_and_or_b32 v129, v129, s18, v139
	v_lshlrev_b32_e32 v134, 3, v129
	global_load_dwordx2 v[182:183], v134, s[58:59] offset:256
	global_load_dwordx2 v[180:181], v134, s[58:59] offset:272
	global_load_dwordx2 v[178:179], v134, s[58:59] offset:288
	global_load_dwordx2 v[176:177], v134, s[58:59] offset:304
	ds_bpermute_b32 v188, v131, v78
	ds_bpermute_b32 v189, v131, v74
	s_waitcnt lgkmcnt(3)
	ds_bpermute_b32 v184, v131, v70
	s_waitcnt lgkmcnt(3)
	ds_bpermute_b32 v185, v131, v66
	v_ashrrev_i32_e32 v187, 31, v186
	s_and_saveexec_b64 s[0:1], s[8:9]
	s_xor_b64 s[0:1], exec, s[0:1]
	s_cbranch_execz .LBB0_664
	s_and_saveexec_b64 s[72:73], vcc
	s_cbranch_execz .LBB0_663
	s_waitcnt lgkmcnt(0)
	v_lshlrev_b64 v[184:185], 5, v[186:187]
	v_lshl_add_u64 v[188:189], v[168:169], 0, v[184:185]
	v_mov_b32_e32 v184, v78
	v_mov_b32_e32 v185, v74
	v_mov_b32_e32 v186, v70
	v_mov_b32_e32 v187, v66
	v_pk_mul_f32 v[184:185], v[184:185], s[88:89] op_sel_hi:[1,0]
	v_pk_mul_f32 v[186:187], v[186:187], s[88:89] op_sel_hi:[1,0]
	global_store_dwordx4 v[188:189], v[184:187], off offset:-128 nt

.LBB0_664:
	s_andn2_saveexec_b64 s[0:1], s[0:1]
	s_cbranch_execz .LBB0_666
	v_lshl_add_u64 v[190:191], s[58:59], 0, v[134:135]
	v_lshlrev_b64 v[192:193], 6, v[186:187]
	v_lshlrev_b64 v[186:187], 7, v[186:187]
	v_lshl_add_u64 v[194:195], v[174:175], 0, v[186:187]
	global_load_dwordx2 v[186:187], v[190:191], off offset:16
	global_load_dwordx2 v[196:197], v[190:191], off
	v_mov_b32_e32 v198, v78
	v_mov_b32_e32 v199, v74
	s_waitcnt lgkmcnt(2)
	v_pk_mul_f32 v[188:189], v[170:171], v[188:189] op_sel_hi:[0,1]
	s_waitcnt lgkmcnt(0)
	v_pk_mul_f32 v[184:185], v[170:171], v[184:185] op_sel_hi:[0,1]
	v_lshl_add_u64 v[192:193], v[172:173], 0, v[192:193]
	s_waitcnt vmcnt(1)
	v_mov_b32_e32 v201, v186
	s_waitcnt vmcnt(0)
	v_mov_b32_e32 v200, v196
	v_pk_mul_f32 v[198:199], v[198:199], v[200:201]
	v_mov_b32_e32 v186, v197
	v_pk_fma_f32 v[186:187], v[188:189], v[186:187], v[198:199]
	global_load_dwordx2 v[188:189], v[190:191], off offset:48
	s_nop 0
	global_load_dwordx2 v[190:191], v[190:191], off offset:32
	v_mov_b32_e32 v198, v70
	v_mov_b32_e32 v199, v66
	v_cvt_pk_bf16_f32 v196, v186, v187
	s_waitcnt vmcnt(1)
	v_mov_b32_e32 v201, v188
	s_waitcnt vmcnt(0)
	v_mov_b32_e32 v200, v190
	v_pk_mul_f32 v[198:199], v[198:199], v[200:201]
	v_mov_b32_e32 v188, v191
	v_pk_fma_f32 v[188:189], v[184:185], v[188:189], v[198:199]
	s_nop 0
	v_cvt_pk_bf16_f32 v197, v188, v189
	global_store_dwordx2 v[192:193], v[196:197], off nt
	global_store_dwordx4 v[194:195], v[186:189], off nt
.LBB0_666:
	s_or_b64 exec, exec, s[0:1]
	ds_bpermute_b32 v186, v131, v79
	ds_bpermute_b32 v187, v131, v75
	s_waitcnt lgkmcnt(3)
	ds_bpermute_b32 v184, v131, v71
	s_waitcnt lgkmcnt(3)
	ds_bpermute_b32 v185, v131, v67
	v_add_u32_e32 v188, 51, v128
	v_ashrrev_i32_e32 v189, 31, v188
	s_and_saveexec_b64 s[0:1], s[8:9]
	s_xor_b64 s[0:1], exec, s[0:1]
	s_cbranch_execz .LBB0_670
	s_and_saveexec_b64 s[72:73], vcc
	s_cbranch_execz .LBB0_669
	s_waitcnt vmcnt(0)
	v_lshlrev_b64 v[176:177], 5, v[188:189]
	v_lshl_add_u64 v[180:181], v[168:169], 0, v[176:177]
	v_mov_b32_e32 v176, v79
	v_mov_b32_e32 v177, v75
	v_mov_b32_e32 v178, v71
	v_mov_b32_e32 v179, v67
	v_pk_mul_f32 v[176:177], v[176:177], s[88:89] op_sel_hi:[1,0]
	v_pk_mul_f32 v[178:179], v[178:179], s[88:89] op_sel_hi:[1,0]
	global_store_dwordx4 v[180:181], v[176:179], off offset:-128 nt

.LBB0_670:
	s_andn2_saveexec_b64 s[0:1], s[0:1]
	s_cbranch_execz .LBB0_672
	s_waitcnt vmcnt(0)
	v_mov_b32_e32 v193, v176
	v_mov_b32_e32 v196, v182
	v_mov_b32_e32 v197, v180
	s_waitcnt lgkmcnt(2)
	v_pk_mul_f32 v[186:187], v[170:171], v[186:187] op_sel_hi:[0,1]
	v_mov_b32_e32 v180, v183
	s_waitcnt lgkmcnt(0)
	v_pk_mul_f32 v[182:183], v[170:171], v[184:185] op_sel_hi:[0,1]
	v_mov_b32_e32 v176, v179
	v_mov_b32_e32 v190, v71
	v_mov_b32_e32 v191, v67
	v_mov_b32_e32 v192, v178
	v_mov_b32_e32 v194, v79
	v_mov_b32_e32 v195, v75
	v_lshlrev_b64 v[198:199], 6, v[188:189]
	v_pk_mul_f32 v[180:181], v[180:181], v[186:187]
	v_pk_mul_f32 v[176:177], v[176:177], v[182:183]
	v_lshl_add_u64 v[198:199], v[172:173], 0, v[198:199]
	v_lshlrev_b64 v[188:189], 7, v[188:189]
	v_pk_fma_f32 v[180:181], v[194:195], v[196:197], v[180:181]
	v_pk_fma_f32 v[182:183], v[190:191], v[192:193], v[176:177]
	v_cvt_pk_bf16_f32 v178, v180, v181
	v_lshl_add_u64 v[188:189], v[174:175], 0, v[188:189]
	v_cvt_pk_bf16_f32 v179, v182, v183
	global_store_dwordx2 v[198:199], v[178:179], off nt
	global_store_dwordx4 v[188:189], v[180:183], off nt
.LBB0_672:
	s_or_b64 exec, exec, s[0:1]
	s_waitcnt lgkmcnt(3)
	v_add_u32_e32 v186, 64, v128
	v_lshlrev_b32_e32 v129, 5, v186
	v_and_or_b32 v129, v129, s17, v139
	v_lshlrev_b32_e32 v134, 3, v129
	global_load_dwordx2 v[182:183], v134, s[58:59] offset:256
	global_load_dwordx2 v[180:181], v134, s[58:59] offset:272
	global_load_dwordx2 v[178:179], v134, s[58:59] offset:288
	global_load_dwordx2 v[176:177], v134, s[58:59] offset:304
	ds_bpermute_b32 v188, v131, v60
	ds_bpermute_b32 v189, v131, v56
	s_waitcnt lgkmcnt(3)
	ds_bpermute_b32 v184, v131, v52
	s_waitcnt lgkmcnt(3)
	ds_bpermute_b32 v185, v131, v48
	v_ashrrev_i32_e32 v187, 31, v186
	s_and_saveexec_b64 s[0:1], s[8:9]
	s_xor_b64 s[0:1], exec, s[0:1]
	s_cbranch_execz .LBB0_676
	s_and_saveexec_b64 s[72:73], vcc
	s_cbranch_execz .LBB0_675
	s_waitcnt lgkmcnt(0)
	v_lshlrev_b64 v[184:185], 5, v[186:187]
	v_lshl_add_u64 v[188:189], v[168:169], 0, v[184:185]
	v_mov_b32_e32 v184, v60
	v_mov_b32_e32 v185, v56
	v_mov_b32_e32 v186, v52
	v_mov_b32_e32 v187, v48
	v_pk_mul_f32 v[184:185], v[184:185], s[88:89] op_sel_hi:[1,0]
	v_pk_mul_f32 v[186:187], v[186:187], s[88:89] op_sel_hi:[1,0]
	global_store_dwordx4 v[188:189], v[184:187], off offset:-128 nt

.LBB0_676:
	s_andn2_saveexec_b64 s[0:1], s[0:1]
	s_cbranch_execz .LBB0_678
	v_lshl_add_u64 v[190:191], s[58:59], 0, v[134:135]
	v_lshlrev_b64 v[192:193], 6, v[186:187]
	v_lshlrev_b64 v[186:187], 7, v[186:187]
	v_lshl_add_u64 v[194:195], v[174:175], 0, v[186:187]
	global_load_dwordx2 v[186:187], v[190:191], off offset:16
	global_load_dwordx2 v[196:197], v[190:191], off
	v_mov_b32_e32 v198, v60
	v_mov_b32_e32 v199, v56
	s_waitcnt lgkmcnt(2)
	v_pk_mul_f32 v[188:189], v[170:171], v[188:189] op_sel_hi:[0,1]
	s_waitcnt lgkmcnt(0)
	v_pk_mul_f32 v[184:185], v[170:171], v[184:185] op_sel_hi:[0,1]
	v_lshl_add_u64 v[192:193], v[172:173], 0, v[192:193]
	s_waitcnt vmcnt(1)
	v_mov_b32_e32 v201, v186
	s_waitcnt vmcnt(0)
	v_mov_b32_e32 v200, v196
	v_pk_mul_f32 v[198:199], v[198:199], v[200:201]
	v_mov_b32_e32 v186, v197
	v_pk_fma_f32 v[186:187], v[188:189], v[186:187], v[198:199]
	global_load_dwordx2 v[188:189], v[190:191], off offset:48
	s_nop 0
	global_load_dwordx2 v[190:191], v[190:191], off offset:32
	v_mov_b32_e32 v198, v52
	v_mov_b32_e32 v199, v48
	v_cvt_pk_bf16_f32 v196, v186, v187
	s_waitcnt vmcnt(1)
	v_mov_b32_e32 v201, v188
	s_waitcnt vmcnt(0)
	v_mov_b32_e32 v200, v190
	v_pk_mul_f32 v[198:199], v[198:199], v[200:201]
	v_mov_b32_e32 v188, v191
	v_pk_fma_f32 v[188:189], v[184:185], v[188:189], v[198:199]
	s_nop 0
	v_cvt_pk_bf16_f32 v197, v188, v189
	global_store_dwordx2 v[192:193], v[196:197], off nt
	global_store_dwordx4 v[194:195], v[186:189], off nt
.LBB0_678:
	s_or_b64 exec, exec, s[0:1]
	ds_bpermute_b32 v186, v131, v61
	ds_bpermute_b32 v187, v131, v57
	s_waitcnt lgkmcnt(3)
	ds_bpermute_b32 v184, v131, v53
	s_waitcnt lgkmcnt(3)
	ds_bpermute_b32 v185, v131, v49
	v_add_u32_e32 v188, 0x41, v128
	v_ashrrev_i32_e32 v189, 31, v188
	s_and_saveexec_b64 s[0:1], s[8:9]
	s_xor_b64 s[0:1], exec, s[0:1]
	s_cbranch_execz .LBB0_682
	s_and_saveexec_b64 s[72:73], vcc
	s_cbranch_execz .LBB0_681
	s_waitcnt vmcnt(0)
	v_lshlrev_b64 v[176:177], 5, v[188:189]
	v_lshl_add_u64 v[180:181], v[168:169], 0, v[176:177]
	v_mov_b32_e32 v176, v61
	v_mov_b32_e32 v177, v57
	v_mov_b32_e32 v178, v53
	v_mov_b32_e32 v179, v49
	v_pk_mul_f32 v[176:177], v[176:177], s[88:89] op_sel_hi:[1,0]
	v_pk_mul_f32 v[178:179], v[178:179], s[88:89] op_sel_hi:[1,0]
	global_store_dwordx4 v[180:181], v[176:179], off offset:-128 nt

.LBB0_682:
	s_andn2_saveexec_b64 s[0:1], s[0:1]
	s_cbranch_execz .LBB0_684
	s_waitcnt vmcnt(0)
	v_mov_b32_e32 v193, v176
	v_mov_b32_e32 v196, v182
	v_mov_b32_e32 v197, v180
	s_waitcnt lgkmcnt(2)
	v_pk_mul_f32 v[186:187], v[170:171], v[186:187] op_sel_hi:[0,1]
	v_mov_b32_e32 v180, v183
	s_waitcnt lgkmcnt(0)
	v_pk_mul_f32 v[182:183], v[170:171], v[184:185] op_sel_hi:[0,1]
	v_mov_b32_e32 v176, v179
	v_mov_b32_e32 v190, v53
	v_mov_b32_e32 v191, v49
	v_mov_b32_e32 v192, v178
	v_mov_b32_e32 v194, v61
	v_mov_b32_e32 v195, v57
	v_lshlrev_b64 v[198:199], 6, v[188:189]
	v_pk_mul_f32 v[180:181], v[180:181], v[186:187]
	v_pk_mul_f32 v[176:177], v[176:177], v[182:183]
	v_lshl_add_u64 v[198:199], v[172:173], 0, v[198:199]
	v_lshlrev_b64 v[188:189], 7, v[188:189]
	v_pk_fma_f32 v[180:181], v[194:195], v[196:197], v[180:181]
	v_pk_fma_f32 v[182:183], v[190:191], v[192:193], v[176:177]
	v_cvt_pk_bf16_f32 v178, v180, v181
	v_lshl_add_u64 v[188:189], v[174:175], 0, v[188:189]
	v_cvt_pk_bf16_f32 v179, v182, v183
	global_store_dwordx2 v[198:199], v[178:179], off nt
	global_store_dwordx4 v[188:189], v[180:183], off nt
.LBB0_684:
	s_or_b64 exec, exec, s[0:1]
	s_waitcnt lgkmcnt(3)
	v_add_u32_e32 v186, 0x42, v128
	v_lshlrev_b32_e32 v129, 5, v186
	v_and_or_b32 v129, v129, s18, v139
	v_lshlrev_b32_e32 v134, 3, v129
	global_load_dwordx2 v[182:183], v134, s[58:59] offset:256
	global_load_dwordx2 v[180:181], v134, s[58:59] offset:272
	global_load_dwordx2 v[178:179], v134, s[58:59] offset:288
	global_load_dwordx2 v[176:177], v134, s[58:59] offset:304
	ds_bpermute_b32 v188, v131, v62
	ds_bpermute_b32 v189, v131, v58
	s_waitcnt lgkmcnt(3)
	ds_bpermute_b32 v184, v131, v54
	s_waitcnt lgkmcnt(3)
	ds_bpermute_b32 v185, v131, v50
	v_ashrrev_i32_e32 v187, 31, v186
	s_and_saveexec_b64 s[0:1], s[8:9]
	s_xor_b64 s[0:1], exec, s[0:1]
	s_cbranch_execz .LBB0_688
	s_and_saveexec_b64 s[72:73], vcc
	s_cbranch_execz .LBB0_687
	s_waitcnt lgkmcnt(0)
	v_lshlrev_b64 v[184:185], 5, v[186:187]
	v_lshl_add_u64 v[188:189], v[168:169], 0, v[184:185]
	v_mov_b32_e32 v184, v62
	v_mov_b32_e32 v185, v58
	v_mov_b32_e32 v186, v54
	v_mov_b32_e32 v187, v50
	v_pk_mul_f32 v[184:185], v[184:185], s[88:89] op_sel_hi:[1,0]
	v_pk_mul_f32 v[186:187], v[186:187], s[88:89] op_sel_hi:[1,0]
	global_store_dwordx4 v[188:189], v[184:187], off offset:-128 nt

.LBB0_688:
	s_andn2_saveexec_b64 s[0:1], s[0:1]
	s_cbranch_execz .LBB0_690
	v_lshl_add_u64 v[190:191], s[58:59], 0, v[134:135]
	v_lshlrev_b64 v[192:193], 6, v[186:187]
	v_lshlrev_b64 v[186:187], 7, v[186:187]
	v_lshl_add_u64 v[194:195], v[174:175], 0, v[186:187]
	global_load_dwordx2 v[186:187], v[190:191], off offset:16
	global_load_dwordx2 v[196:197], v[190:191], off
	v_mov_b32_e32 v198, v62
	v_mov_b32_e32 v199, v58
	s_waitcnt lgkmcnt(2)
	v_pk_mul_f32 v[188:189], v[170:171], v[188:189] op_sel_hi:[0,1]
	s_waitcnt lgkmcnt(0)
	v_pk_mul_f32 v[184:185], v[170:171], v[184:185] op_sel_hi:[0,1]
	v_lshl_add_u64 v[192:193], v[172:173], 0, v[192:193]
	s_waitcnt vmcnt(1)
	v_mov_b32_e32 v201, v186
	s_waitcnt vmcnt(0)
	v_mov_b32_e32 v200, v196
	v_pk_mul_f32 v[198:199], v[198:199], v[200:201]
	v_mov_b32_e32 v186, v197
	v_pk_fma_f32 v[186:187], v[188:189], v[186:187], v[198:199]
	global_load_dwordx2 v[188:189], v[190:191], off offset:48
	s_nop 0
	global_load_dwordx2 v[190:191], v[190:191], off offset:32
	v_mov_b32_e32 v198, v54
	v_mov_b32_e32 v199, v50
	v_cvt_pk_bf16_f32 v196, v186, v187
	s_waitcnt vmcnt(1)
	v_mov_b32_e32 v201, v188
	s_waitcnt vmcnt(0)
	v_mov_b32_e32 v200, v190
	v_pk_mul_f32 v[198:199], v[198:199], v[200:201]
	v_mov_b32_e32 v188, v191
	v_pk_fma_f32 v[188:189], v[184:185], v[188:189], v[198:199]
	s_nop 0
	v_cvt_pk_bf16_f32 v197, v188, v189
	global_store_dwordx2 v[192:193], v[196:197], off nt
	global_store_dwordx4 v[194:195], v[186:189], off nt
.LBB0_690:
	s_or_b64 exec, exec, s[0:1]
	ds_bpermute_b32 v186, v131, v63
	ds_bpermute_b32 v187, v131, v59
	s_waitcnt lgkmcnt(3)
	ds_bpermute_b32 v184, v131, v55
	s_waitcnt lgkmcnt(3)
	ds_bpermute_b32 v185, v131, v51
	v_add_u32_e32 v188, 0x43, v128
	v_ashrrev_i32_e32 v189, 31, v188
	s_and_saveexec_b64 s[0:1], s[8:9]
	s_xor_b64 s[0:1], exec, s[0:1]
	s_cbranch_execz .LBB0_694
	s_and_saveexec_b64 s[72:73], vcc
	s_cbranch_execz .LBB0_693
	s_waitcnt vmcnt(0)
	v_lshlrev_b64 v[176:177], 5, v[188:189]
	v_lshl_add_u64 v[180:181], v[168:169], 0, v[176:177]
	v_mov_b32_e32 v176, v63
	v_mov_b32_e32 v177, v59
	v_mov_b32_e32 v178, v55
	v_mov_b32_e32 v179, v51
	v_pk_mul_f32 v[176:177], v[176:177], s[88:89] op_sel_hi:[1,0]
	v_pk_mul_f32 v[178:179], v[178:179], s[88:89] op_sel_hi:[1,0]
	global_store_dwordx4 v[180:181], v[176:179], off offset:-128 nt

.LBB0_694:
	s_andn2_saveexec_b64 s[0:1], s[0:1]
	s_cbranch_execz .LBB0_696
	s_waitcnt vmcnt(0)
	v_mov_b32_e32 v193, v176
	v_mov_b32_e32 v196, v182
	v_mov_b32_e32 v197, v180
	s_waitcnt lgkmcnt(2)
	v_pk_mul_f32 v[186:187], v[170:171], v[186:187] op_sel_hi:[0,1]
	v_mov_b32_e32 v180, v183
	s_waitcnt lgkmcnt(0)
	v_pk_mul_f32 v[182:183], v[170:171], v[184:185] op_sel_hi:[0,1]
	v_mov_b32_e32 v176, v179
	v_mov_b32_e32 v190, v55
	v_mov_b32_e32 v191, v51
	v_mov_b32_e32 v192, v178
	v_mov_b32_e32 v194, v63
	v_mov_b32_e32 v195, v59
	v_lshlrev_b64 v[198:199], 6, v[188:189]
	v_pk_mul_f32 v[180:181], v[180:181], v[186:187]
	v_pk_mul_f32 v[176:177], v[176:177], v[182:183]
	v_lshl_add_u64 v[198:199], v[172:173], 0, v[198:199]
	v_lshlrev_b64 v[188:189], 7, v[188:189]
	v_pk_fma_f32 v[180:181], v[194:195], v[196:197], v[180:181]
	v_pk_fma_f32 v[182:183], v[190:191], v[192:193], v[176:177]
	v_cvt_pk_bf16_f32 v178, v180, v181
	v_lshl_add_u64 v[188:189], v[174:175], 0, v[188:189]
	v_cvt_pk_bf16_f32 v179, v182, v183
	global_store_dwordx2 v[198:199], v[178:179], off nt
	global_store_dwordx4 v[188:189], v[180:183], off nt
.LBB0_696:
	s_or_b64 exec, exec, s[0:1]
	s_waitcnt lgkmcnt(3)
	v_add_u32_e32 v186, 0x50, v128
	v_lshlrev_b32_e32 v129, 5, v186
	v_and_or_b32 v129, v129, s17, v139
	v_lshlrev_b32_e32 v134, 3, v129
	global_load_dwordx2 v[182:183], v134, s[58:59] offset:256
	global_load_dwordx2 v[180:181], v134, s[58:59] offset:272
	global_load_dwordx2 v[178:179], v134, s[58:59] offset:288
	global_load_dwordx2 v[176:177], v134, s[58:59] offset:304
	ds_bpermute_b32 v188, v131, v44
	ds_bpermute_b32 v189, v131, v40
	s_waitcnt lgkmcnt(3)
	ds_bpermute_b32 v184, v131, v36
	s_waitcnt lgkmcnt(3)
	ds_bpermute_b32 v185, v131, v32
	v_ashrrev_i32_e32 v187, 31, v186
	s_and_saveexec_b64 s[0:1], s[8:9]
	s_xor_b64 s[0:1], exec, s[0:1]
	s_cbranch_execz .LBB0_700
	s_and_saveexec_b64 s[72:73], vcc
	s_cbranch_execz .LBB0_699
	s_waitcnt lgkmcnt(0)
	v_lshlrev_b64 v[184:185], 5, v[186:187]
	v_lshl_add_u64 v[188:189], v[168:169], 0, v[184:185]
	v_mov_b32_e32 v184, v44
	v_mov_b32_e32 v185, v40
	v_mov_b32_e32 v186, v36
	v_mov_b32_e32 v187, v32
	v_pk_mul_f32 v[184:185], v[184:185], s[88:89] op_sel_hi:[1,0]
	v_pk_mul_f32 v[186:187], v[186:187], s[88:89] op_sel_hi:[1,0]
	global_store_dwordx4 v[188:189], v[184:187], off offset:-128 nt

.LBB0_700:
	s_andn2_saveexec_b64 s[0:1], s[0:1]
	s_cbranch_execz .LBB0_702
	v_lshl_add_u64 v[190:191], s[58:59], 0, v[134:135]
	v_lshlrev_b64 v[192:193], 6, v[186:187]
	v_lshlrev_b64 v[186:187], 7, v[186:187]
	v_lshl_add_u64 v[194:195], v[174:175], 0, v[186:187]
	global_load_dwordx2 v[186:187], v[190:191], off offset:16
	global_load_dwordx2 v[196:197], v[190:191], off
	v_mov_b32_e32 v198, v44
	v_mov_b32_e32 v199, v40
	s_waitcnt lgkmcnt(2)
	v_pk_mul_f32 v[188:189], v[170:171], v[188:189] op_sel_hi:[0,1]
	s_waitcnt lgkmcnt(0)
	v_pk_mul_f32 v[184:185], v[170:171], v[184:185] op_sel_hi:[0,1]
	v_lshl_add_u64 v[192:193], v[172:173], 0, v[192:193]
	s_waitcnt vmcnt(1)
	v_mov_b32_e32 v201, v186
	s_waitcnt vmcnt(0)
	v_mov_b32_e32 v200, v196
	v_pk_mul_f32 v[198:199], v[198:199], v[200:201]
	v_mov_b32_e32 v186, v197
	v_pk_fma_f32 v[186:187], v[188:189], v[186:187], v[198:199]
	global_load_dwordx2 v[188:189], v[190:191], off offset:48
	s_nop 0
	global_load_dwordx2 v[190:191], v[190:191], off offset:32
	v_mov_b32_e32 v198, v36
	v_mov_b32_e32 v199, v32
	v_cvt_pk_bf16_f32 v196, v186, v187
	s_waitcnt vmcnt(1)
	v_mov_b32_e32 v201, v188
	s_waitcnt vmcnt(0)
	v_mov_b32_e32 v200, v190
	v_pk_mul_f32 v[198:199], v[198:199], v[200:201]
	v_mov_b32_e32 v188, v191
	v_pk_fma_f32 v[188:189], v[184:185], v[188:189], v[198:199]
	s_nop 0
	v_cvt_pk_bf16_f32 v197, v188, v189
	global_store_dwordx2 v[192:193], v[196:197], off nt
	global_store_dwordx4 v[194:195], v[186:189], off nt
.LBB0_702:
	s_or_b64 exec, exec, s[0:1]
	ds_bpermute_b32 v186, v131, v45
	ds_bpermute_b32 v187, v131, v41
	s_waitcnt lgkmcnt(3)
	ds_bpermute_b32 v184, v131, v37
	s_waitcnt lgkmcnt(3)
	ds_bpermute_b32 v185, v131, v33
	v_add_u32_e32 v188, 0x51, v128
	v_ashrrev_i32_e32 v189, 31, v188
	s_and_saveexec_b64 s[0:1], s[8:9]
	s_xor_b64 s[0:1], exec, s[0:1]
	s_cbranch_execz .LBB0_706
	s_and_saveexec_b64 s[72:73], vcc
	s_cbranch_execz .LBB0_705
	s_waitcnt vmcnt(0)
	v_lshlrev_b64 v[176:177], 5, v[188:189]
	v_lshl_add_u64 v[180:181], v[168:169], 0, v[176:177]
	v_mov_b32_e32 v176, v45
	v_mov_b32_e32 v177, v41
	v_mov_b32_e32 v178, v37
	v_mov_b32_e32 v179, v33
	v_pk_mul_f32 v[176:177], v[176:177], s[88:89] op_sel_hi:[1,0]
	v_pk_mul_f32 v[178:179], v[178:179], s[88:89] op_sel_hi:[1,0]
	global_store_dwordx4 v[180:181], v[176:179], off offset:-128 nt

.LBB0_706:
	s_andn2_saveexec_b64 s[0:1], s[0:1]
	s_cbranch_execz .LBB0_708
	s_waitcnt vmcnt(0)
	v_mov_b32_e32 v193, v176
	v_mov_b32_e32 v196, v182
	v_mov_b32_e32 v197, v180
	s_waitcnt lgkmcnt(2)
	v_pk_mul_f32 v[186:187], v[170:171], v[186:187] op_sel_hi:[0,1]
	v_mov_b32_e32 v180, v183
	s_waitcnt lgkmcnt(0)
	v_pk_mul_f32 v[182:183], v[170:171], v[184:185] op_sel_hi:[0,1]
	v_mov_b32_e32 v176, v179
	v_mov_b32_e32 v190, v37
	v_mov_b32_e32 v191, v33
	v_mov_b32_e32 v192, v178
	v_mov_b32_e32 v194, v45
	v_mov_b32_e32 v195, v41
	v_lshlrev_b64 v[198:199], 6, v[188:189]
	v_pk_mul_f32 v[180:181], v[180:181], v[186:187]
	v_pk_mul_f32 v[176:177], v[176:177], v[182:183]
	v_lshl_add_u64 v[198:199], v[172:173], 0, v[198:199]
	v_lshlrev_b64 v[188:189], 7, v[188:189]
	v_pk_fma_f32 v[180:181], v[194:195], v[196:197], v[180:181]
	v_pk_fma_f32 v[182:183], v[190:191], v[192:193], v[176:177]
	v_cvt_pk_bf16_f32 v178, v180, v181
	v_lshl_add_u64 v[188:189], v[174:175], 0, v[188:189]
	v_cvt_pk_bf16_f32 v179, v182, v183
	global_store_dwordx2 v[198:199], v[178:179], off nt
	global_store_dwordx4 v[188:189], v[180:183], off nt
.LBB0_708:
	s_or_b64 exec, exec, s[0:1]
	s_waitcnt lgkmcnt(3)
	v_add_u32_e32 v186, 0x52, v128
	v_lshlrev_b32_e32 v129, 5, v186
	v_and_or_b32 v129, v129, s18, v139
	v_lshlrev_b32_e32 v134, 3, v129
	global_load_dwordx2 v[182:183], v134, s[58:59] offset:256
	global_load_dwordx2 v[180:181], v134, s[58:59] offset:272
	global_load_dwordx2 v[178:179], v134, s[58:59] offset:288
	global_load_dwordx2 v[176:177], v134, s[58:59] offset:304
	ds_bpermute_b32 v188, v131, v46
	ds_bpermute_b32 v189, v131, v42
	s_waitcnt lgkmcnt(3)
	ds_bpermute_b32 v184, v131, v38
	s_waitcnt lgkmcnt(3)
	ds_bpermute_b32 v185, v131, v34
	v_ashrrev_i32_e32 v187, 31, v186
	s_and_saveexec_b64 s[0:1], s[8:9]
	s_xor_b64 s[0:1], exec, s[0:1]
	s_cbranch_execz .LBB0_712
	s_and_saveexec_b64 s[72:73], vcc
	s_cbranch_execz .LBB0_711
	s_waitcnt lgkmcnt(0)
	v_lshlrev_b64 v[184:185], 5, v[186:187]
	v_lshl_add_u64 v[188:189], v[168:169], 0, v[184:185]
	v_mov_b32_e32 v184, v46
	v_mov_b32_e32 v185, v42
	v_mov_b32_e32 v186, v38
	v_mov_b32_e32 v187, v34
	v_pk_mul_f32 v[184:185], v[184:185], s[88:89] op_sel_hi:[1,0]
	v_pk_mul_f32 v[186:187], v[186:187], s[88:89] op_sel_hi:[1,0]
	global_store_dwordx4 v[188:189], v[184:187], off offset:-128 nt

.LBB0_712:
	s_andn2_saveexec_b64 s[0:1], s[0:1]
	s_cbranch_execz .LBB0_714
	v_lshl_add_u64 v[190:191], s[58:59], 0, v[134:135]
	v_lshlrev_b64 v[192:193], 6, v[186:187]
	v_lshlrev_b64 v[186:187], 7, v[186:187]
	v_lshl_add_u64 v[194:195], v[174:175], 0, v[186:187]
	global_load_dwordx2 v[186:187], v[190:191], off offset:16
	global_load_dwordx2 v[196:197], v[190:191], off
	v_mov_b32_e32 v198, v46
	v_mov_b32_e32 v199, v42
	s_waitcnt lgkmcnt(2)
	v_pk_mul_f32 v[188:189], v[170:171], v[188:189] op_sel_hi:[0,1]
	s_waitcnt lgkmcnt(0)
	v_pk_mul_f32 v[184:185], v[170:171], v[184:185] op_sel_hi:[0,1]
	v_lshl_add_u64 v[192:193], v[172:173], 0, v[192:193]
	s_waitcnt vmcnt(1)
	v_mov_b32_e32 v201, v186
	s_waitcnt vmcnt(0)
	v_mov_b32_e32 v200, v196
	v_pk_mul_f32 v[198:199], v[198:199], v[200:201]
	v_mov_b32_e32 v186, v197
	v_pk_fma_f32 v[186:187], v[188:189], v[186:187], v[198:199]
	global_load_dwordx2 v[188:189], v[190:191], off offset:48
	s_nop 0
	global_load_dwordx2 v[190:191], v[190:191], off offset:32
	v_mov_b32_e32 v198, v38
	v_mov_b32_e32 v199, v34
	v_cvt_pk_bf16_f32 v196, v186, v187
	s_waitcnt vmcnt(1)
	v_mov_b32_e32 v201, v188
	s_waitcnt vmcnt(0)
	v_mov_b32_e32 v200, v190
	v_pk_mul_f32 v[198:199], v[198:199], v[200:201]
	v_mov_b32_e32 v188, v191
	v_pk_fma_f32 v[188:189], v[184:185], v[188:189], v[198:199]
	s_nop 0
	v_cvt_pk_bf16_f32 v197, v188, v189
	global_store_dwordx2 v[192:193], v[196:197], off nt
	global_store_dwordx4 v[194:195], v[186:189], off nt
.LBB0_714:
	s_or_b64 exec, exec, s[0:1]
	ds_bpermute_b32 v186, v131, v47
	ds_bpermute_b32 v187, v131, v43
	s_waitcnt lgkmcnt(3)
	ds_bpermute_b32 v184, v131, v39
	s_waitcnt lgkmcnt(3)
	ds_bpermute_b32 v185, v131, v35
	v_add_u32_e32 v188, 0x53, v128
	v_ashrrev_i32_e32 v189, 31, v188
	s_and_saveexec_b64 s[0:1], s[8:9]
	s_xor_b64 s[0:1], exec, s[0:1]
	s_cbranch_execz .LBB0_718
	s_and_saveexec_b64 s[72:73], vcc
	s_cbranch_execz .LBB0_717
	s_waitcnt vmcnt(0)
	v_lshlrev_b64 v[176:177], 5, v[188:189]
	v_lshl_add_u64 v[180:181], v[168:169], 0, v[176:177]
	v_mov_b32_e32 v176, v47
	v_mov_b32_e32 v177, v43
	v_mov_b32_e32 v178, v39
	v_mov_b32_e32 v179, v35
	v_pk_mul_f32 v[176:177], v[176:177], s[88:89] op_sel_hi:[1,0]
	v_pk_mul_f32 v[178:179], v[178:179], s[88:89] op_sel_hi:[1,0]
	global_store_dwordx4 v[180:181], v[176:179], off offset:-128 nt

.LBB0_718:
	s_andn2_saveexec_b64 s[0:1], s[0:1]
	s_cbranch_execz .LBB0_720
	s_waitcnt vmcnt(0)
	v_mov_b32_e32 v193, v176
	v_mov_b32_e32 v196, v182
	v_mov_b32_e32 v197, v180
	s_waitcnt lgkmcnt(2)
	v_pk_mul_f32 v[186:187], v[170:171], v[186:187] op_sel_hi:[0,1]
	v_mov_b32_e32 v180, v183
	s_waitcnt lgkmcnt(0)
	v_pk_mul_f32 v[182:183], v[170:171], v[184:185] op_sel_hi:[0,1]
	v_mov_b32_e32 v176, v179
	v_mov_b32_e32 v190, v39
	v_mov_b32_e32 v191, v35
	v_mov_b32_e32 v192, v178
	v_mov_b32_e32 v194, v47
	v_mov_b32_e32 v195, v43
	v_lshlrev_b64 v[198:199], 6, v[188:189]
	v_pk_mul_f32 v[180:181], v[180:181], v[186:187]
	v_pk_mul_f32 v[176:177], v[176:177], v[182:183]
	v_lshl_add_u64 v[198:199], v[172:173], 0, v[198:199]
	v_lshlrev_b64 v[188:189], 7, v[188:189]
	v_pk_fma_f32 v[180:181], v[194:195], v[196:197], v[180:181]
	v_pk_fma_f32 v[182:183], v[190:191], v[192:193], v[176:177]
	v_cvt_pk_bf16_f32 v178, v180, v181
	v_lshl_add_u64 v[188:189], v[174:175], 0, v[188:189]
	v_cvt_pk_bf16_f32 v179, v182, v183
	global_store_dwordx2 v[198:199], v[178:179], off nt
	global_store_dwordx4 v[188:189], v[180:183], off nt
.LBB0_720:
	s_or_b64 exec, exec, s[0:1]
	s_waitcnt lgkmcnt(3)
	v_add_u32_e32 v186, 0x60, v128
	v_lshlrev_b32_e32 v129, 5, v186
	v_and_or_b32 v129, v129, s17, v139
	v_lshlrev_b32_e32 v134, 3, v129
	global_load_dwordx2 v[182:183], v134, s[58:59] offset:256
	global_load_dwordx2 v[180:181], v134, s[58:59] offset:272
	global_load_dwordx2 v[178:179], v134, s[58:59] offset:288
	global_load_dwordx2 v[176:177], v134, s[58:59] offset:304
	ds_bpermute_b32 v188, v131, v28
	ds_bpermute_b32 v189, v131, v24
	s_waitcnt lgkmcnt(3)
	ds_bpermute_b32 v184, v131, v20
	s_waitcnt lgkmcnt(3)
	ds_bpermute_b32 v185, v131, v16
	v_ashrrev_i32_e32 v187, 31, v186
	s_and_saveexec_b64 s[0:1], s[8:9]
	s_xor_b64 s[0:1], exec, s[0:1]
	s_cbranch_execz .LBB0_724
	s_and_saveexec_b64 s[72:73], vcc
	s_cbranch_execz .LBB0_723
	s_waitcnt lgkmcnt(0)
	v_lshlrev_b64 v[184:185], 5, v[186:187]
	v_lshl_add_u64 v[188:189], v[168:169], 0, v[184:185]
	v_mov_b32_e32 v184, v28
	v_mov_b32_e32 v185, v24
	v_mov_b32_e32 v186, v20
	v_mov_b32_e32 v187, v16
	v_pk_mul_f32 v[184:185], v[184:185], s[88:89] op_sel_hi:[1,0]
	v_pk_mul_f32 v[186:187], v[186:187], s[88:89] op_sel_hi:[1,0]
	global_store_dwordx4 v[188:189], v[184:187], off offset:-128 nt

.LBB0_724:
	s_andn2_saveexec_b64 s[0:1], s[0:1]
	s_cbranch_execz .LBB0_726
	v_lshl_add_u64 v[190:191], s[58:59], 0, v[134:135]
	v_lshlrev_b64 v[192:193], 6, v[186:187]
	v_lshlrev_b64 v[186:187], 7, v[186:187]
	v_lshl_add_u64 v[194:195], v[174:175], 0, v[186:187]
	global_load_dwordx2 v[186:187], v[190:191], off offset:16
	global_load_dwordx2 v[196:197], v[190:191], off
	v_mov_b32_e32 v198, v28
	v_mov_b32_e32 v199, v24
	s_waitcnt lgkmcnt(2)
	v_pk_mul_f32 v[188:189], v[170:171], v[188:189] op_sel_hi:[0,1]
	s_waitcnt lgkmcnt(0)
	v_pk_mul_f32 v[184:185], v[170:171], v[184:185] op_sel_hi:[0,1]
	v_lshl_add_u64 v[192:193], v[172:173], 0, v[192:193]
	s_waitcnt vmcnt(1)
	v_mov_b32_e32 v201, v186
	s_waitcnt vmcnt(0)
	v_mov_b32_e32 v200, v196
	v_pk_mul_f32 v[198:199], v[198:199], v[200:201]
	v_mov_b32_e32 v186, v197
	v_pk_fma_f32 v[186:187], v[188:189], v[186:187], v[198:199]
	global_load_dwordx2 v[188:189], v[190:191], off offset:48
	s_nop 0
	global_load_dwordx2 v[190:191], v[190:191], off offset:32
	v_mov_b32_e32 v198, v20
	v_mov_b32_e32 v199, v16
	v_cvt_pk_bf16_f32 v196, v186, v187
	s_waitcnt vmcnt(1)
	v_mov_b32_e32 v201, v188
	s_waitcnt vmcnt(0)
	v_mov_b32_e32 v200, v190
	v_pk_mul_f32 v[198:199], v[198:199], v[200:201]
	v_mov_b32_e32 v188, v191
	v_pk_fma_f32 v[188:189], v[184:185], v[188:189], v[198:199]
	s_nop 0
	v_cvt_pk_bf16_f32 v197, v188, v189
	global_store_dwordx2 v[192:193], v[196:197], off nt
	global_store_dwordx4 v[194:195], v[186:189], off nt
.LBB0_726:
	s_or_b64 exec, exec, s[0:1]
	ds_bpermute_b32 v186, v131, v29
	ds_bpermute_b32 v187, v131, v25
	s_waitcnt lgkmcnt(3)
	ds_bpermute_b32 v184, v131, v21
	s_waitcnt lgkmcnt(3)
	ds_bpermute_b32 v185, v131, v17
	v_add_u32_e32 v188, 0x61, v128
	v_ashrrev_i32_e32 v189, 31, v188
	s_and_saveexec_b64 s[0:1], s[8:9]
	s_xor_b64 s[0:1], exec, s[0:1]
	s_cbranch_execz .LBB0_730
	s_and_saveexec_b64 s[72:73], vcc
	s_cbranch_execz .LBB0_729
	s_waitcnt vmcnt(0)
	v_lshlrev_b64 v[176:177], 5, v[188:189]
	v_lshl_add_u64 v[180:181], v[168:169], 0, v[176:177]
	v_mov_b32_e32 v176, v29
	v_mov_b32_e32 v177, v25
	v_mov_b32_e32 v178, v21
	v_mov_b32_e32 v179, v17
	v_pk_mul_f32 v[176:177], v[176:177], s[88:89] op_sel_hi:[1,0]
	v_pk_mul_f32 v[178:179], v[178:179], s[88:89] op_sel_hi:[1,0]
	global_store_dwordx4 v[180:181], v[176:179], off offset:-128 nt

.LBB0_730:
	s_andn2_saveexec_b64 s[0:1], s[0:1]
	s_cbranch_execz .LBB0_732
	s_waitcnt vmcnt(0)
	v_mov_b32_e32 v193, v176
	v_mov_b32_e32 v196, v182
	v_mov_b32_e32 v197, v180
	s_waitcnt lgkmcnt(2)
	v_pk_mul_f32 v[186:187], v[170:171], v[186:187] op_sel_hi:[0,1]
	v_mov_b32_e32 v180, v183
	s_waitcnt lgkmcnt(0)
	v_pk_mul_f32 v[182:183], v[170:171], v[184:185] op_sel_hi:[0,1]
	v_mov_b32_e32 v176, v179
	v_mov_b32_e32 v190, v21
	v_mov_b32_e32 v191, v17
	v_mov_b32_e32 v192, v178
	v_mov_b32_e32 v194, v29
	v_mov_b32_e32 v195, v25
	v_lshlrev_b64 v[198:199], 6, v[188:189]
	v_pk_mul_f32 v[180:181], v[180:181], v[186:187]
	v_pk_mul_f32 v[176:177], v[176:177], v[182:183]
	v_lshl_add_u64 v[198:199], v[172:173], 0, v[198:199]
	v_lshlrev_b64 v[188:189], 7, v[188:189]
	v_pk_fma_f32 v[180:181], v[194:195], v[196:197], v[180:181]
	v_pk_fma_f32 v[182:183], v[190:191], v[192:193], v[176:177]
	v_cvt_pk_bf16_f32 v178, v180, v181
	v_lshl_add_u64 v[188:189], v[174:175], 0, v[188:189]
	v_cvt_pk_bf16_f32 v179, v182, v183
	global_store_dwordx2 v[198:199], v[178:179], off nt
	global_store_dwordx4 v[188:189], v[180:183], off nt
.LBB0_732:
	s_or_b64 exec, exec, s[0:1]
	s_waitcnt lgkmcnt(3)
	v_add_u32_e32 v186, 0x62, v128
	v_lshlrev_b32_e32 v129, 5, v186
	v_and_or_b32 v129, v129, s18, v139
	v_lshlrev_b32_e32 v134, 3, v129
	global_load_dwordx2 v[182:183], v134, s[58:59] offset:256
	global_load_dwordx2 v[180:181], v134, s[58:59] offset:272
	global_load_dwordx2 v[178:179], v134, s[58:59] offset:288
	global_load_dwordx2 v[176:177], v134, s[58:59] offset:304
	ds_bpermute_b32 v188, v131, v30
	ds_bpermute_b32 v189, v131, v26
	s_waitcnt lgkmcnt(3)
	ds_bpermute_b32 v184, v131, v22
	s_waitcnt lgkmcnt(3)
	ds_bpermute_b32 v185, v131, v18
	v_ashrrev_i32_e32 v187, 31, v186
	s_and_saveexec_b64 s[0:1], s[8:9]
	s_xor_b64 s[0:1], exec, s[0:1]
	s_cbranch_execz .LBB0_736
	s_and_saveexec_b64 s[72:73], vcc
	s_cbranch_execz .LBB0_735
	s_waitcnt lgkmcnt(0)
	v_lshlrev_b64 v[184:185], 5, v[186:187]
	v_lshl_add_u64 v[188:189], v[168:169], 0, v[184:185]
	v_mov_b32_e32 v184, v30
	v_mov_b32_e32 v185, v26
	v_mov_b32_e32 v186, v22
	v_mov_b32_e32 v187, v18
	v_pk_mul_f32 v[184:185], v[184:185], s[88:89] op_sel_hi:[1,0]
	v_pk_mul_f32 v[186:187], v[186:187], s[88:89] op_sel_hi:[1,0]
	global_store_dwordx4 v[188:189], v[184:187], off offset:-128 nt

.LBB0_736:
	s_andn2_saveexec_b64 s[0:1], s[0:1]
	s_cbranch_execz .LBB0_738
	v_lshl_add_u64 v[190:191], s[58:59], 0, v[134:135]
	v_lshlrev_b64 v[192:193], 6, v[186:187]
	v_lshlrev_b64 v[186:187], 7, v[186:187]
	v_lshl_add_u64 v[194:195], v[174:175], 0, v[186:187]
	global_load_dwordx2 v[186:187], v[190:191], off offset:16
	global_load_dwordx2 v[196:197], v[190:191], off
	v_mov_b32_e32 v198, v30
	v_mov_b32_e32 v199, v26
	s_waitcnt lgkmcnt(2)
	v_pk_mul_f32 v[188:189], v[170:171], v[188:189] op_sel_hi:[0,1]
	s_waitcnt lgkmcnt(0)
	v_pk_mul_f32 v[184:185], v[170:171], v[184:185] op_sel_hi:[0,1]
	v_lshl_add_u64 v[192:193], v[172:173], 0, v[192:193]
	s_waitcnt vmcnt(1)
	v_mov_b32_e32 v201, v186
	s_waitcnt vmcnt(0)
	v_mov_b32_e32 v200, v196
	v_pk_mul_f32 v[198:199], v[198:199], v[200:201]
	v_mov_b32_e32 v186, v197
	v_pk_fma_f32 v[186:187], v[188:189], v[186:187], v[198:199]
	global_load_dwordx2 v[188:189], v[190:191], off offset:48
	s_nop 0
	global_load_dwordx2 v[190:191], v[190:191], off offset:32
	v_mov_b32_e32 v198, v22
	v_mov_b32_e32 v199, v18
	v_cvt_pk_bf16_f32 v196, v186, v187
	s_waitcnt vmcnt(1)
	v_mov_b32_e32 v201, v188
	s_waitcnt vmcnt(0)
	v_mov_b32_e32 v200, v190
	v_pk_mul_f32 v[198:199], v[198:199], v[200:201]
	v_mov_b32_e32 v188, v191
	v_pk_fma_f32 v[188:189], v[184:185], v[188:189], v[198:199]
	s_nop 0
	v_cvt_pk_bf16_f32 v197, v188, v189
	global_store_dwordx2 v[192:193], v[196:197], off nt
	global_store_dwordx4 v[194:195], v[186:189], off nt
.LBB0_738:
	s_or_b64 exec, exec, s[0:1]
	ds_bpermute_b32 v186, v131, v31
	ds_bpermute_b32 v187, v131, v27
	s_waitcnt lgkmcnt(3)
	ds_bpermute_b32 v184, v131, v23
	s_waitcnt lgkmcnt(3)
	ds_bpermute_b32 v185, v131, v19
	v_add_u32_e32 v188, 0x63, v128
	v_ashrrev_i32_e32 v189, 31, v188
	s_and_saveexec_b64 s[0:1], s[8:9]
	s_xor_b64 s[0:1], exec, s[0:1]
	s_cbranch_execz .LBB0_742
	s_and_saveexec_b64 s[72:73], vcc
	s_cbranch_execz .LBB0_741
	s_waitcnt vmcnt(0)
	v_lshlrev_b64 v[176:177], 5, v[188:189]
	v_lshl_add_u64 v[180:181], v[168:169], 0, v[176:177]
	v_mov_b32_e32 v176, v31
	v_mov_b32_e32 v177, v27
	v_mov_b32_e32 v178, v23
	v_mov_b32_e32 v179, v19
	v_pk_mul_f32 v[176:177], v[176:177], s[88:89] op_sel_hi:[1,0]
	v_pk_mul_f32 v[178:179], v[178:179], s[88:89] op_sel_hi:[1,0]
	global_store_dwordx4 v[180:181], v[176:179], off offset:-128 nt

.LBB0_742:
	s_andn2_saveexec_b64 s[0:1], s[0:1]
	s_cbranch_execz .LBB0_744
	s_waitcnt vmcnt(0)
	v_mov_b32_e32 v193, v176
	v_mov_b32_e32 v196, v182
	v_mov_b32_e32 v197, v180
	s_waitcnt lgkmcnt(2)
	v_pk_mul_f32 v[186:187], v[170:171], v[186:187] op_sel_hi:[0,1]
	v_mov_b32_e32 v180, v183
	s_waitcnt lgkmcnt(0)
	v_pk_mul_f32 v[182:183], v[170:171], v[184:185] op_sel_hi:[0,1]
	v_mov_b32_e32 v176, v179
	v_mov_b32_e32 v190, v23
	v_mov_b32_e32 v191, v19
	v_mov_b32_e32 v192, v178
	v_mov_b32_e32 v194, v31
	v_mov_b32_e32 v195, v27
	v_lshlrev_b64 v[198:199], 6, v[188:189]
	v_pk_mul_f32 v[180:181], v[180:181], v[186:187]
	v_pk_mul_f32 v[176:177], v[176:177], v[182:183]
	v_lshl_add_u64 v[198:199], v[172:173], 0, v[198:199]
	v_lshlrev_b64 v[188:189], 7, v[188:189]
	v_pk_fma_f32 v[180:181], v[194:195], v[196:197], v[180:181]
	v_pk_fma_f32 v[182:183], v[190:191], v[192:193], v[176:177]
	v_cvt_pk_bf16_f32 v178, v180, v181
	v_lshl_add_u64 v[188:189], v[174:175], 0, v[188:189]
	v_cvt_pk_bf16_f32 v179, v182, v183
	global_store_dwordx2 v[198:199], v[178:179], off nt
	global_store_dwordx4 v[188:189], v[180:183], off nt
.LBB0_744:
	s_or_b64 exec, exec, s[0:1]
	s_waitcnt lgkmcnt(3)
	v_add_u32_e32 v186, 0x70, v128
	v_lshlrev_b32_e32 v129, 5, v186
	v_and_or_b32 v129, v129, s17, v139
	v_lshlrev_b32_e32 v134, 3, v129
	global_load_dwordx2 v[182:183], v134, s[58:59] offset:256
	global_load_dwordx2 v[180:181], v134, s[58:59] offset:272
	global_load_dwordx2 v[178:179], v134, s[58:59] offset:288
	global_load_dwordx2 v[176:177], v134, s[58:59] offset:304
	ds_bpermute_b32 v188, v131, v12
	ds_bpermute_b32 v189, v131, v8
	s_waitcnt lgkmcnt(3)
	ds_bpermute_b32 v184, v131, v4
	s_waitcnt lgkmcnt(3)
	ds_bpermute_b32 v185, v131, v0
	v_ashrrev_i32_e32 v187, 31, v186
	s_and_saveexec_b64 s[0:1], s[8:9]
	s_xor_b64 s[0:1], exec, s[0:1]
	s_cbranch_execz .LBB0_748
	s_and_saveexec_b64 s[72:73], vcc
	s_cbranch_execz .LBB0_747
	s_waitcnt lgkmcnt(0)
	v_lshlrev_b64 v[184:185], 5, v[186:187]
	v_lshl_add_u64 v[188:189], v[168:169], 0, v[184:185]
	v_mov_b32_e32 v184, v12
	v_mov_b32_e32 v185, v8
	v_mov_b32_e32 v186, v4
	v_mov_b32_e32 v187, v0
	v_pk_mul_f32 v[184:185], v[184:185], s[88:89] op_sel_hi:[1,0]
	v_pk_mul_f32 v[186:187], v[186:187], s[88:89] op_sel_hi:[1,0]
	global_store_dwordx4 v[188:189], v[184:187], off offset:-128 nt

.LBB0_748:
	s_andn2_saveexec_b64 s[0:1], s[0:1]
	s_cbranch_execz .LBB0_750
	v_lshl_add_u64 v[190:191], s[58:59], 0, v[134:135]
	v_lshlrev_b64 v[192:193], 6, v[186:187]
	v_lshlrev_b64 v[186:187], 7, v[186:187]
	v_lshl_add_u64 v[194:195], v[174:175], 0, v[186:187]
	global_load_dwordx2 v[186:187], v[190:191], off offset:16
	global_load_dwordx2 v[196:197], v[190:191], off
	v_mov_b32_e32 v198, v12
	v_mov_b32_e32 v199, v8
	s_waitcnt lgkmcnt(2)
	v_pk_mul_f32 v[188:189], v[170:171], v[188:189] op_sel_hi:[0,1]
	s_waitcnt lgkmcnt(0)
	v_pk_mul_f32 v[184:185], v[170:171], v[184:185] op_sel_hi:[0,1]
	v_lshl_add_u64 v[192:193], v[172:173], 0, v[192:193]
	s_waitcnt vmcnt(1)
	v_mov_b32_e32 v201, v186
	s_waitcnt vmcnt(0)
	v_mov_b32_e32 v200, v196
	v_pk_mul_f32 v[198:199], v[198:199], v[200:201]
	v_mov_b32_e32 v186, v197
	v_pk_fma_f32 v[186:187], v[188:189], v[186:187], v[198:199]
	global_load_dwordx2 v[188:189], v[190:191], off offset:48
	s_nop 0
	global_load_dwordx2 v[190:191], v[190:191], off offset:32
	v_mov_b32_e32 v198, v4
	v_mov_b32_e32 v199, v0
	v_cvt_pk_bf16_f32 v196, v186, v187
	s_waitcnt vmcnt(1)
	v_mov_b32_e32 v201, v188
	s_waitcnt vmcnt(0)
	v_mov_b32_e32 v200, v190
	v_pk_mul_f32 v[198:199], v[198:199], v[200:201]
	v_mov_b32_e32 v188, v191
	v_pk_fma_f32 v[188:189], v[184:185], v[188:189], v[198:199]
	s_nop 0
	v_cvt_pk_bf16_f32 v197, v188, v189
	global_store_dwordx2 v[192:193], v[196:197], off nt
	global_store_dwordx4 v[194:195], v[186:189], off nt
.LBB0_750:
	s_or_b64 exec, exec, s[0:1]
	ds_bpermute_b32 v186, v131, v13
	ds_bpermute_b32 v187, v131, v9
	s_waitcnt lgkmcnt(3)
	ds_bpermute_b32 v184, v131, v5
	s_waitcnt lgkmcnt(3)
	ds_bpermute_b32 v185, v131, v1
	v_add_u32_e32 v188, 0x71, v128
	v_ashrrev_i32_e32 v189, 31, v188
	s_and_saveexec_b64 s[0:1], s[8:9]
	s_xor_b64 s[0:1], exec, s[0:1]
	s_cbranch_execz .LBB0_754
	s_and_saveexec_b64 s[72:73], vcc
	s_cbranch_execz .LBB0_753
	s_waitcnt vmcnt(0)
	v_lshlrev_b64 v[176:177], 5, v[188:189]
	v_lshl_add_u64 v[180:181], v[168:169], 0, v[176:177]
	v_mov_b32_e32 v176, v13
	v_mov_b32_e32 v177, v9
	v_mov_b32_e32 v178, v5
	v_mov_b32_e32 v179, v1
	v_pk_mul_f32 v[176:177], v[176:177], s[88:89] op_sel_hi:[1,0]
	v_pk_mul_f32 v[178:179], v[178:179], s[88:89] op_sel_hi:[1,0]
	global_store_dwordx4 v[180:181], v[176:179], off offset:-128 nt

.LBB0_754:
	s_andn2_saveexec_b64 s[0:1], s[0:1]
	s_cbranch_execz .LBB0_756
	s_waitcnt vmcnt(0)
	v_mov_b32_e32 v193, v176
	v_mov_b32_e32 v196, v182
	v_mov_b32_e32 v197, v180
	s_waitcnt lgkmcnt(2)
	v_pk_mul_f32 v[186:187], v[170:171], v[186:187] op_sel_hi:[0,1]
	v_mov_b32_e32 v180, v183
	s_waitcnt lgkmcnt(0)
	v_pk_mul_f32 v[182:183], v[170:171], v[184:185] op_sel_hi:[0,1]
	v_mov_b32_e32 v176, v179
	v_mov_b32_e32 v190, v5
	v_mov_b32_e32 v191, v1
	v_mov_b32_e32 v192, v178
	v_mov_b32_e32 v194, v13
	v_mov_b32_e32 v195, v9
	v_lshlrev_b64 v[198:199], 6, v[188:189]
	v_pk_mul_f32 v[180:181], v[180:181], v[186:187]
	v_pk_mul_f32 v[176:177], v[176:177], v[182:183]
	v_lshl_add_u64 v[198:199], v[172:173], 0, v[198:199]
	v_lshlrev_b64 v[188:189], 7, v[188:189]
	v_pk_fma_f32 v[180:181], v[194:195], v[196:197], v[180:181]
	v_pk_fma_f32 v[182:183], v[190:191], v[192:193], v[176:177]
	v_cvt_pk_bf16_f32 v178, v180, v181
	v_lshl_add_u64 v[188:189], v[174:175], 0, v[188:189]
	v_cvt_pk_bf16_f32 v179, v182, v183
	global_store_dwordx2 v[198:199], v[178:179], off nt
	global_store_dwordx4 v[188:189], v[180:183], off nt
.LBB0_756:
	s_or_b64 exec, exec, s[0:1]
	s_waitcnt lgkmcnt(3)
	v_add_u32_e32 v186, 0x72, v128
	v_lshlrev_b32_e32 v129, 5, v186
	v_and_or_b32 v129, v129, s18, v139
	v_lshlrev_b32_e32 v134, 3, v129
	global_load_dwordx2 v[182:183], v134, s[58:59] offset:256
	global_load_dwordx2 v[180:181], v134, s[58:59] offset:272
	global_load_dwordx2 v[178:179], v134, s[58:59] offset:288
	global_load_dwordx2 v[176:177], v134, s[58:59] offset:304
	ds_bpermute_b32 v188, v131, v14
	ds_bpermute_b32 v189, v131, v10
	s_waitcnt lgkmcnt(3)
	ds_bpermute_b32 v184, v131, v6
	s_waitcnt lgkmcnt(3)
	ds_bpermute_b32 v185, v131, v2
	v_ashrrev_i32_e32 v187, 31, v186
	s_and_saveexec_b64 s[0:1], s[8:9]
	s_xor_b64 s[0:1], exec, s[0:1]
	s_cbranch_execz .LBB0_760
	s_and_saveexec_b64 s[72:73], vcc
	s_cbranch_execz .LBB0_759
	s_waitcnt lgkmcnt(0)
	v_lshlrev_b64 v[184:185], 5, v[186:187]
	v_lshl_add_u64 v[188:189], v[168:169], 0, v[184:185]
	v_mov_b32_e32 v184, v14
	v_mov_b32_e32 v185, v10
	v_mov_b32_e32 v186, v6
	v_mov_b32_e32 v187, v2
	v_pk_mul_f32 v[184:185], v[184:185], s[88:89] op_sel_hi:[1,0]
	v_pk_mul_f32 v[186:187], v[186:187], s[88:89] op_sel_hi:[1,0]
	global_store_dwordx4 v[188:189], v[184:187], off offset:-128 nt

.LBB0_760:
	s_andn2_saveexec_b64 s[0:1], s[0:1]
	s_cbranch_execz .LBB0_762
	v_lshl_add_u64 v[190:191], s[58:59], 0, v[134:135]
	v_lshlrev_b64 v[192:193], 6, v[186:187]
	v_lshlrev_b64 v[186:187], 7, v[186:187]
	v_lshl_add_u64 v[194:195], v[174:175], 0, v[186:187]
	global_load_dwordx2 v[186:187], v[190:191], off offset:16
	global_load_dwordx2 v[196:197], v[190:191], off
	v_mov_b32_e32 v198, v14
	v_mov_b32_e32 v199, v10
	s_waitcnt lgkmcnt(2)
	v_pk_mul_f32 v[188:189], v[170:171], v[188:189] op_sel_hi:[0,1]
	s_waitcnt lgkmcnt(0)
	v_pk_mul_f32 v[184:185], v[170:171], v[184:185] op_sel_hi:[0,1]
	v_lshl_add_u64 v[192:193], v[172:173], 0, v[192:193]
	s_waitcnt vmcnt(1)
	v_mov_b32_e32 v201, v186
	s_waitcnt vmcnt(0)
	v_mov_b32_e32 v200, v196
	v_pk_mul_f32 v[198:199], v[198:199], v[200:201]
	v_mov_b32_e32 v186, v197
	v_pk_fma_f32 v[186:187], v[188:189], v[186:187], v[198:199]
	global_load_dwordx2 v[188:189], v[190:191], off offset:48
	s_nop 0
	global_load_dwordx2 v[190:191], v[190:191], off offset:32
	v_mov_b32_e32 v198, v6
	v_mov_b32_e32 v199, v2
	v_cvt_pk_bf16_f32 v196, v186, v187
	s_waitcnt vmcnt(1)
	v_mov_b32_e32 v201, v188
	s_waitcnt vmcnt(0)
	v_mov_b32_e32 v200, v190
	v_pk_mul_f32 v[198:199], v[198:199], v[200:201]
	v_mov_b32_e32 v188, v191
	v_pk_fma_f32 v[188:189], v[184:185], v[188:189], v[198:199]
	s_nop 0
	v_cvt_pk_bf16_f32 v197, v188, v189
	global_store_dwordx2 v[192:193], v[196:197], off nt
	global_store_dwordx4 v[194:195], v[186:189], off nt
.LBB0_762:
	s_or_b64 exec, exec, s[0:1]
	ds_bpermute_b32 v186, v131, v15
	ds_bpermute_b32 v187, v131, v11
	s_waitcnt lgkmcnt(3)
	ds_bpermute_b32 v184, v131, v7
	s_waitcnt lgkmcnt(3)
	ds_bpermute_b32 v185, v131, v3
	v_add_u32_e32 v188, 0x73, v128
	v_ashrrev_i32_e32 v189, 31, v188
	s_and_saveexec_b64 s[0:1], s[8:9]
	s_xor_b64 s[0:1], exec, s[0:1]
	s_cbranch_execz .LBB0_766
	s_and_saveexec_b64 s[8:9], vcc
	s_cbranch_execz .LBB0_765
	v_lshlrev_b64 v[170:171], 5, v[188:189]
	v_lshl_add_u64 v[172:173], v[168:169], 0, v[170:171]
	v_mov_b32_e32 v168, v15
	v_mov_b32_e32 v169, v11
	v_mov_b32_e32 v170, v7
	v_mov_b32_e32 v171, v3
	v_pk_mul_f32 v[168:169], v[168:169], s[88:89] op_sel_hi:[1,0]
	v_pk_mul_f32 v[170:171], v[170:171], s[88:89] op_sel_hi:[1,0]
	global_store_dwordx4 v[172:173], v[168:171], off offset:-128 nt

.LBB0_766:
	s_andn2_saveexec_b64 s[0:1], s[0:1]
	s_cbranch_execz .LBB0_768
	s_waitcnt vmcnt(0)
	v_mov_b32_e32 v193, v176
	v_mov_b32_e32 v195, v180
	s_waitcnt lgkmcnt(2)
	v_pk_mul_f32 v[186:187], v[170:171], v[186:187] op_sel_hi:[0,1]
	v_mov_b32_e32 v180, v183
	s_waitcnt lgkmcnt(0)
	v_pk_mul_f32 v[170:171], v[170:171], v[184:185] op_sel_hi:[0,1]
	v_mov_b32_e32 v176, v179
	v_mov_b32_e32 v190, v7
	v_mov_b32_e32 v191, v3
	v_mov_b32_e32 v192, v178
	v_mov_b32_e32 v168, v15
	v_mov_b32_e32 v169, v11
	v_mov_b32_e32 v194, v182
	v_lshlrev_b64 v[196:197], 6, v[188:189]
	v_pk_mul_f32 v[180:181], v[180:181], v[186:187]
	v_pk_mul_f32 v[170:171], v[176:177], v[170:171]
	v_lshl_add_u64 v[172:173], v[172:173], 0, v[196:197]
	v_lshlrev_b64 v[188:189], 7, v[188:189]
	v_pk_fma_f32 v[168:169], v[168:169], v[194:195], v[180:181]
	v_pk_fma_f32 v[170:171], v[190:191], v[192:193], v[170:171]
	v_cvt_pk_bf16_f32 v178, v168, v169
	v_lshl_add_u64 v[174:175], v[174:175], 0, v[188:189]
	v_cvt_pk_bf16_f32 v179, v170, v171
	global_store_dwordx2 v[172:173], v[178:179], off nt
	global_store_dwordx4 v[174:175], v[168:171], off nt

.LBB0_769:
	v_readlane_b32 s0, v253, 42
	v_readlane_b32 s1, v253, 43
	s_load_dwordx2 s[0:1], s[0:1], 0xc8
	s_waitcnt lgkmcnt(0)
	v_lshl_add_u64 v[136:137], v[136:137], 1, s[0:1]
	v_mad_i64_i32 v[168:169], s[0:1], v128, s13, v[136:137]
	v_mul_f32_e32 v124, 0x3e38aa3b, v124
	v_mul_f32_e32 v120, 0x3e38aa3b, v120
	v_mul_f32_e32 v116, 0x3e38aa3b, v116
	v_mul_f32_e32 v112, 0x3e38aa3b, v112
	v_cvt_pk_bf16_f32 v170, v124, v120
	v_cvt_pk_bf16_f32 v171, v116, v112
	global_store_dwordx2 v[168:169], v[170:171], off nt
	v_mad_i64_i32 v[166:167], s[0:1], v166, s13, v[136:137]
	v_mul_f32_e32 v112, 0x3e38aa3b, v125
	v_mul_f32_e32 v113, 0x3e38aa3b, v113
	v_mul_f32_e32 v116, 0x3e38aa3b, v121
	v_mul_f32_e32 v117, 0x3e38aa3b, v117
	v_cvt_pk_bf16_f32 v112, v112, v116
	v_cvt_pk_bf16_f32 v113, v117, v113
	global_store_dwordx2 v[166:167], v[112:113], off nt
	v_mad_i64_i32 v[112:113], s[0:1], v164, s13, v[136:137]
	v_mul_f32_e32 v116, 0x3e38aa3b, v126
	v_mul_f32_e32 v117, 0x3e38aa3b, v122
	v_mul_f32_e32 v118, 0x3e38aa3b, v118
	v_mul_f32_e32 v114, 0x3e38aa3b, v114
	v_cvt_pk_bf16_f32 v116, v116, v117
	v_cvt_pk_bf16_f32 v117, v118, v114
	global_store_dwordx2 v[112:113], v[116:117], off nt
	v_mad_i64_i32 v[112:113], s[0:1], v162, s13, v[136:137]
	v_mul_f32_e32 v114, 0x3e38aa3b, v127
	v_mul_f32_e32 v115, 0x3e38aa3b, v115
	v_mul_f32_e32 v116, 0x3e38aa3b, v123
	v_mul_f32_e32 v117, 0x3e38aa3b, v119
	v_cvt_pk_bf16_f32 v114, v114, v116
	v_cvt_pk_bf16_f32 v115, v117, v115
	global_store_dwordx2 v[112:113], v[114:115], off nt
	v_mad_i64_i32 v[112:113], s[0:1], v160, s13, v[136:137]
	v_mul_f32_e32 v108, 0x3e38aa3b, v108
	v_mul_f32_e32 v104, 0x3e38aa3b, v104
	v_mul_f32_e32 v100, 0x3e38aa3b, v100
	v_mul_f32_e32 v96, 0x3e38aa3b, v96
	v_cvt_pk_bf16_f32 v114, v108, v104
	v_cvt_pk_bf16_f32 v115, v100, v96
	global_store_dwordx2 v[112:113], v[114:115], off nt
	v_mad_i64_i32 v[112:113], s[0:1], v158, s13, v[136:137]
	v_mul_f32_e32 v96, 0x3e38aa3b, v109
	v_mul_f32_e32 v97, 0x3e38aa3b, v97
	v_mul_f32_e32 v100, 0x3e38aa3b, v105
	v_mul_f32_e32 v101, 0x3e38aa3b, v101
	v_cvt_pk_bf16_f32 v96, v96, v100
	v_cvt_pk_bf16_f32 v97, v101, v97
	global_store_dwordx2 v[112:113], v[96:97], off nt
	v_mad_i64_i32 v[96:97], s[0:1], v156, s13, v[136:137]
	v_mul_f32_e32 v100, 0x3e38aa3b, v110
	v_mul_f32_e32 v101, 0x3e38aa3b, v106
	v_mul_f32_e32 v102, 0x3e38aa3b, v102
	v_mul_f32_e32 v98, 0x3e38aa3b, v98
	v_cvt_pk_bf16_f32 v100, v100, v101
	v_cvt_pk_bf16_f32 v101, v102, v98
	global_store_dwordx2 v[96:97], v[100:101], off nt
	v_mad_i64_i32 v[96:97], s[0:1], v154, s13, v[136:137]
	v_mul_f32_e32 v98, 0x3e38aa3b, v111
	v_mul_f32_e32 v99, 0x3e38aa3b, v99
	v_mul_f32_e32 v100, 0x3e38aa3b, v107
	v_mul_f32_e32 v101, 0x3e38aa3b, v103
	v_cvt_pk_bf16_f32 v98, v98, v100
	v_cvt_pk_bf16_f32 v99, v101, v99
	global_store_dwordx2 v[96:97], v[98:99], off nt
	v_mad_i64_i32 v[96:97], s[0:1], v152, s13, v[136:137]
	v_mul_f32_e32 v92, 0x3e38aa3b, v92
	v_mul_f32_e32 v88, 0x3e38aa3b, v88
	v_mul_f32_e32 v84, 0x3e38aa3b, v84
	v_mul_f32_e32 v80, 0x3e38aa3b, v80
	v_cvt_pk_bf16_f32 v98, v92, v88
	v_cvt_pk_bf16_f32 v99, v84, v80
	global_store_dwordx2 v[96:97], v[98:99], off nt
	v_mad_i64_i32 v[96:97], s[0:1], v150, s13, v[136:137]
	v_mul_f32_e32 v80, 0x3e38aa3b, v93
	v_mul_f32_e32 v81, 0x3e38aa3b, v81
	v_mul_f32_e32 v84, 0x3e38aa3b, v89
	v_mul_f32_e32 v85, 0x3e38aa3b, v85
	v_cvt_pk_bf16_f32 v80, v80, v84
	v_cvt_pk_bf16_f32 v81, v85, v81
	global_store_dwordx2 v[96:97], v[80:81], off nt
	v_mad_i64_i32 v[80:81], s[0:1], v148, s13, v[136:137]
	v_mul_f32_e32 v84, 0x3e38aa3b, v94
	v_mul_f32_e32 v85, 0x3e38aa3b, v90
	v_mul_f32_e32 v86, 0x3e38aa3b, v86
	v_mul_f32_e32 v82, 0x3e38aa3b, v82
	v_cvt_pk_bf16_f32 v84, v84, v85
	v_cvt_pk_bf16_f32 v85, v86, v82
	global_store_dwordx2 v[80:81], v[84:85], off nt
	v_mad_i64_i32 v[80:81], s[0:1], v146, s13, v[136:137]
	v_mul_f32_e32 v82, 0x3e38aa3b, v95
	v_mul_f32_e32 v83, 0x3e38aa3b, v83
	v_mul_f32_e32 v84, 0x3e38aa3b, v91
	v_mul_f32_e32 v85, 0x3e38aa3b, v87
	v_cvt_pk_bf16_f32 v82, v82, v84
	v_cvt_pk_bf16_f32 v83, v85, v83
	global_store_dwordx2 v[80:81], v[82:83], off nt
	v_mad_i64_i32 v[80:81], s[0:1], v144, s13, v[136:137]
	v_mul_f32_e32 v76, 0x3e38aa3b, v76
	v_mul_f32_e32 v72, 0x3e38aa3b, v72
	v_mul_f32_e32 v68, 0x3e38aa3b, v68
	v_mul_f32_e32 v64, 0x3e38aa3b, v64
	v_cvt_pk_bf16_f32 v82, v76, v72
	v_cvt_pk_bf16_f32 v83, v68, v64
	global_store_dwordx2 v[80:81], v[82:83], off nt
	v_mad_i64_i32 v[80:81], s[0:1], v142, s13, v[136:137]
	v_mul_f32_e32 v64, 0x3e38aa3b, v77
	v_mul_f32_e32 v65, 0x3e38aa3b, v65
	v_mul_f32_e32 v68, 0x3e38aa3b, v73
	v_mul_f32_e32 v69, 0x3e38aa3b, v69
	v_cvt_pk_bf16_f32 v64, v64, v68
	v_cvt_pk_bf16_f32 v65, v69, v65
	global_store_dwordx2 v[80:81], v[64:65], off nt
	v_mad_i64_i32 v[64:65], s[0:1], v140, s13, v[136:137]
	v_mul_f32_e32 v68, 0x3e38aa3b, v78
	v_mul_f32_e32 v69, 0x3e38aa3b, v74
	v_mul_f32_e32 v70, 0x3e38aa3b, v70
	v_mul_f32_e32 v66, 0x3e38aa3b, v66
	v_cvt_pk_bf16_f32 v68, v68, v69
	v_cvt_pk_bf16_f32 v69, v70, v66
	global_store_dwordx2 v[64:65], v[68:69], off nt
	v_mad_i64_i32 v[64:65], s[0:1], v138, s13, v[136:137]
	v_mul_f32_e32 v66, 0x3e38aa3b, v79
	v_mul_f32_e32 v67, 0x3e38aa3b, v67
	v_mul_f32_e32 v68, 0x3e38aa3b, v75
	v_mul_f32_e32 v69, 0x3e38aa3b, v71
	v_cvt_pk_bf16_f32 v66, v66, v68
	v_cvt_pk_bf16_f32 v67, v69, v67
	global_store_dwordx2 v[64:65], v[66:67], off nt
	v_mad_i64_i32 v[64:65], s[0:1], v130, s13, v[136:137]
	v_mul_f32_e32 v60, 0x3e38aa3b, v60
	v_mul_f32_e32 v56, 0x3e38aa3b, v56
	v_mul_f32_e32 v52, 0x3e38aa3b, v52
	v_mul_f32_e32 v48, 0x3e38aa3b, v48
	v_cvt_pk_bf16_f32 v66, v60, v56
	v_cvt_pk_bf16_f32 v67, v52, v48
	global_store_dwordx2 v[64:65], v[66:67], off nt
	v_add_u32_e32 v48, 0x41, v128
	v_mad_i64_i32 v[64:65], s[0:1], v48, s13, v[136:137]
	v_mul_f32_e32 v48, 0x3e38aa3b, v61
	v_mul_f32_e32 v49, 0x3e38aa3b, v49
	v_mul_f32_e32 v52, 0x3e38aa3b, v57
	v_mul_f32_e32 v53, 0x3e38aa3b, v53
	v_cvt_pk_bf16_f32 v48, v48, v52
	v_cvt_pk_bf16_f32 v49, v53, v49
	global_store_dwordx2 v[64:65], v[48:49], off nt
	v_add_u32_e32 v48, 0x42, v128
	v_mad_i64_i32 v[48:49], s[0:1], v48, s13, v[136:137]
	v_mul_f32_e32 v52, 0x3e38aa3b, v62
	v_mul_f32_e32 v53, 0x3e38aa3b, v58
	v_mul_f32_e32 v54, 0x3e38aa3b, v54
	v_mul_f32_e32 v50, 0x3e38aa3b, v50
	v_cvt_pk_bf16_f32 v52, v52, v53
	v_cvt_pk_bf16_f32 v53, v54, v50
	global_store_dwordx2 v[48:49], v[52:53], off nt
	v_add_u32_e32 v48, 0x43, v128
	v_mad_i64_i32 v[48:49], s[0:1], v48, s13, v[136:137]
	v_mul_f32_e32 v50, 0x3e38aa3b, v63
	v_mul_f32_e32 v51, 0x3e38aa3b, v51
	v_mul_f32_e32 v52, 0x3e38aa3b, v59
	v_mul_f32_e32 v53, 0x3e38aa3b, v55
	v_cvt_pk_bf16_f32 v50, v50, v52
	v_cvt_pk_bf16_f32 v51, v53, v51
	global_store_dwordx2 v[48:49], v[50:51], off nt
	v_add_u32_e32 v48, 0x50, v128
	v_mad_i64_i32 v[48:49], s[0:1], v48, s13, v[136:137]
	v_mul_f32_e32 v44, 0x3e38aa3b, v44
	v_mul_f32_e32 v40, 0x3e38aa3b, v40
	v_mul_f32_e32 v36, 0x3e38aa3b, v36
	v_mul_f32_e32 v32, 0x3e38aa3b, v32
	v_cvt_pk_bf16_f32 v50, v44, v40
	v_cvt_pk_bf16_f32 v51, v36, v32
	global_store_dwordx2 v[48:49], v[50:51], off nt
	v_add_u32_e32 v32, 0x51, v128
	v_mad_i64_i32 v[48:49], s[0:1], v32, s13, v[136:137]
	v_mul_f32_e32 v32, 0x3e38aa3b, v45
	v_mul_f32_e32 v33, 0x3e38aa3b, v33
	v_mul_f32_e32 v36, 0x3e38aa3b, v41
	v_mul_f32_e32 v37, 0x3e38aa3b, v37
	v_cvt_pk_bf16_f32 v32, v32, v36
	v_cvt_pk_bf16_f32 v33, v37, v33
	global_store_dwordx2 v[48:49], v[32:33], off nt
	v_add_u32_e32 v32, 0x52, v128
	v_mad_i64_i32 v[32:33], s[0:1], v32, s13, v[136:137]
	v_mul_f32_e32 v36, 0x3e38aa3b, v46
	v_mul_f32_e32 v37, 0x3e38aa3b, v42
	v_mul_f32_e32 v38, 0x3e38aa3b, v38
	v_mul_f32_e32 v34, 0x3e38aa3b, v34
	v_cvt_pk_bf16_f32 v36, v36, v37
	v_cvt_pk_bf16_f32 v37, v38, v34
	global_store_dwordx2 v[32:33], v[36:37], off nt
	v_add_u32_e32 v32, 0x53, v128
	v_mad_i64_i32 v[32:33], s[0:1], v32, s13, v[136:137]
	v_mul_f32_e32 v34, 0x3e38aa3b, v47
	v_mul_f32_e32 v35, 0x3e38aa3b, v35
	v_mul_f32_e32 v36, 0x3e38aa3b, v43
	v_mul_f32_e32 v37, 0x3e38aa3b, v39
	v_cvt_pk_bf16_f32 v34, v34, v36
	v_cvt_pk_bf16_f32 v35, v37, v35
	global_store_dwordx2 v[32:33], v[34:35], off nt
	v_add_u32_e32 v32, 0x60, v128
	v_mad_i64_i32 v[32:33], s[0:1], v32, s13, v[136:137]
	v_mul_f32_e32 v28, 0x3e38aa3b, v28
	v_mul_f32_e32 v24, 0x3e38aa3b, v24
	v_mul_f32_e32 v20, 0x3e38aa3b, v20
	v_mul_f32_e32 v16, 0x3e38aa3b, v16
	v_cvt_pk_bf16_f32 v34, v28, v24
	v_cvt_pk_bf16_f32 v35, v20, v16
	global_store_dwordx2 v[32:33], v[34:35], off nt
	v_add_u32_e32 v16, 0x61, v128
	v_mad_i64_i32 v[32:33], s[0:1], v16, s13, v[136:137]
	v_mul_f32_e32 v16, 0x3e38aa3b, v29
	v_mul_f32_e32 v17, 0x3e38aa3b, v17
	v_mul_f32_e32 v20, 0x3e38aa3b, v25
	v_mul_f32_e32 v21, 0x3e38aa3b, v21
	v_cvt_pk_bf16_f32 v16, v16, v20
	v_cvt_pk_bf16_f32 v17, v21, v17
	global_store_dwordx2 v[32:33], v[16:17], off nt
	v_add_u32_e32 v16, 0x62, v128
	v_mad_i64_i32 v[16:17], s[0:1], v16, s13, v[136:137]
	v_mul_f32_e32 v20, 0x3e38aa3b, v30
	v_mul_f32_e32 v21, 0x3e38aa3b, v26
	v_mul_f32_e32 v22, 0x3e38aa3b, v22
	v_mul_f32_e32 v18, 0x3e38aa3b, v18
	v_cvt_pk_bf16_f32 v20, v20, v21
	v_cvt_pk_bf16_f32 v21, v22, v18
	global_store_dwordx2 v[16:17], v[20:21], off nt
	v_add_u32_e32 v16, 0x63, v128
	v_mad_i64_i32 v[16:17], s[0:1], v16, s13, v[136:137]
	v_mul_f32_e32 v18, 0x3e38aa3b, v31
	v_mul_f32_e32 v19, 0x3e38aa3b, v19
	v_mul_f32_e32 v20, 0x3e38aa3b, v27
	v_mul_f32_e32 v21, 0x3e38aa3b, v23
	v_cvt_pk_bf16_f32 v18, v18, v20
	v_cvt_pk_bf16_f32 v19, v21, v19
	global_store_dwordx2 v[16:17], v[18:19], off nt
	v_add_u32_e32 v16, 0x70, v128
	v_mad_i64_i32 v[16:17], s[0:1], v16, s13, v[136:137]
	v_mul_f32_e32 v12, 0x3e38aa3b, v12
	v_mul_f32_e32 v8, 0x3e38aa3b, v8
	v_mul_f32_e32 v4, 0x3e38aa3b, v4
	v_mul_f32_e32 v0, 0x3e38aa3b, v0
	v_cvt_pk_bf16_f32 v18, v12, v8
	v_cvt_pk_bf16_f32 v19, v4, v0
	global_store_dwordx2 v[16:17], v[18:19], off nt
	v_add_u32_e32 v0, 0x71, v128
	v_mad_i64_i32 v[16:17], s[0:1], v0, s13, v[136:137]
	v_mul_f32_e32 v0, 0x3e38aa3b, v13
	v_mul_f32_e32 v1, 0x3e38aa3b, v1
	v_mul_f32_e32 v4, 0x3e38aa3b, v9
	v_mul_f32_e32 v5, 0x3e38aa3b, v5
	v_cvt_pk_bf16_f32 v0, v0, v4
	v_cvt_pk_bf16_f32 v1, v5, v1
	global_store_dwordx2 v[16:17], v[0:1], off nt
	v_add_u32_e32 v0, 0x72, v128
	v_mad_i64_i32 v[0:1], s[0:1], v0, s13, v[136:137]
	v_mul_f32_e32 v4, 0x3e38aa3b, v14
	v_mul_f32_e32 v5, 0x3e38aa3b, v10
	v_mul_f32_e32 v6, 0x3e38aa3b, v6
	v_mul_f32_e32 v2, 0x3e38aa3b, v2
	v_cvt_pk_bf16_f32 v4, v4, v5
	v_cvt_pk_bf16_f32 v5, v6, v2
	global_store_dwordx2 v[0:1], v[4:5], off nt
	v_add_u32_e32 v0, 0x73, v128
	v_mad_i64_i32 v[0:1], s[0:1], v0, s13, v[136:137]
	v_mul_f32_e32 v2, 0x3e38aa3b, v15
	v_mul_f32_e32 v3, 0x3e38aa3b, v3
	v_mul_f32_e32 v4, 0x3e38aa3b, v11
	v_mul_f32_e32 v5, 0x3e38aa3b, v7
	v_cvt_pk_bf16_f32 v2, v2, v4
	v_cvt_pk_bf16_f32 v3, v5, v3
	global_store_dwordx2 v[0:1], v[2:3], off nt
	s_branch .LBB0_191

.LBB0_1785:
	s_or_b64 exec, exec, s[24:25]
	v_lshlrev_b64 v[10:11], 2, v[134:135]
	v_lshl_add_u64 v[0:1], s[8:9], 0, v[10:11]
	s_waitcnt lgkmcnt(0)
	s_barrier
	global_load_dwordx4 v[0:3], v[0:1], off
	v_lshl_add_u64 v[10:11], s[10:11], 0, v[10:11]
	s_nop 0
	v_lshl_add_u32 v14, v128, 2, v150
	v_lshl_add_u32 v128, v14, 2, v149
	ds_read_b32 v130, v128
	v_add_u32_e32 v14, s45, v14
	v_ashrrev_i32_e32 v15, 31, v14
	v_lshlrev_b64 v[134:135], 12, v[14:15]
	v_lshl_add_u64 v[144:145], v[10:11], 0, v[134:135]
	s_waitcnt lgkmcnt(0)
	v_pk_mul_f32 v[134:135], v[130:131], v[136:137] op_sel_hi:[0,1]
	v_pk_mul_f32 v[130:131], v[130:131], v[138:139] op_sel_hi:[0,1]
	s_waitcnt vmcnt(0)
	v_pk_mul_f32 v[134:135], v[0:1], v[134:135]
	v_pk_mul_f32 v[136:137], v[2:3], v[130:131]
	global_store_dwordx4 v[144:145], v[134:137], off nt
	ds_read_b32 v130, v128 offset:4
	s_nop 0
	v_add_u32_e32 v134, 1, v14
	v_ashrrev_i32_e32 v135, 31, v134
	v_lshlrev_b64 v[134:135], 12, v[134:135]
	v_lshl_add_u64 v[138:139], v[10:11], 0, v[134:135]
	s_waitcnt lgkmcnt(0)
	v_pk_mul_f32 v[120:121], v[130:131], v[120:121] op_sel_hi:[0,1]
	v_pk_mul_f32 v[134:135], v[0:1], v[120:121]
	v_pk_mul_f32 v[120:121], v[130:131], v[140:141] op_sel_hi:[0,1]
	v_pk_mul_f32 v[136:137], v[2:3], v[120:121]
	global_store_dwordx4 v[138:139], v[134:137], off nt
	ds_read_b32 v120, v128 offset:8
	v_add_u32_e32 v130, 2, v14
	v_ashrrev_i32_e32 v131, 31, v130
	v_lshlrev_b64 v[130:131], 12, v[130:131]
	v_lshl_add_u64 v[130:131], v[10:11], 0, v[130:131]
	s_waitcnt lgkmcnt(0)
	v_pk_mul_f32 v[116:117], v[120:121], v[116:117] op_sel_hi:[0,1]
	v_pk_mul_f32 v[134:135], v[0:1], v[116:117]
	v_pk_mul_f32 v[116:117], v[120:121], v[124:125] op_sel_hi:[0,1]
	v_pk_mul_f32 v[136:137], v[2:3], v[116:117]
	global_store_dwordx4 v[130:131], v[134:137], off nt
	ds_read_b32 v116, v128 offset:12
	v_add_u32_e32 v120, 3, v14
	v_ashrrev_i32_e32 v121, 31, v120
	v_lshlrev_b64 v[120:121], 12, v[120:121]
	v_lshl_add_u64 v[120:121], v[10:11], 0, v[120:121]
	s_waitcnt lgkmcnt(0)
	v_pk_mul_f32 v[112:113], v[116:117], v[112:113] op_sel_hi:[0,1]
	v_pk_mul_f32 v[114:115], v[116:117], v[114:115] op_sel_hi:[0,1]
	v_pk_mul_f32 v[112:113], v[0:1], v[112:113]
	v_pk_mul_f32 v[114:115], v[2:3], v[114:115]
	global_store_dwordx4 v[120:121], v[112:115], off nt
	ds_read_b32 v114, v128 offset:64
	s_nop 0
	v_add_u32_e32 v112, 16, v14
	v_ashrrev_i32_e32 v113, 31, v112
	v_lshlrev_b64 v[112:113], 12, v[112:113]
	v_lshl_add_u64 v[116:117], v[10:11], 0, v[112:113]
	s_waitcnt lgkmcnt(0)
	v_pk_mul_f32 v[112:113], v[114:115], v[118:119] op_sel_hi:[0,1]
	v_pk_mul_f32 v[114:115], v[114:115], v[126:127] op_sel_hi:[0,1]
	v_pk_mul_f32 v[112:113], v[0:1], v[112:113]
	v_pk_mul_f32 v[114:115], v[2:3], v[114:115]
	global_store_dwordx4 v[116:117], v[112:115], off nt
	ds_read_b32 v114, v128 offset:68
	s_nop 0
	v_add_u32_e32 v112, 17, v14
	v_ashrrev_i32_e32 v113, 31, v112
	v_lshlrev_b64 v[112:113], 12, v[112:113]
	v_lshl_add_u64 v[116:117], v[10:11], 0, v[112:113]
	s_waitcnt lgkmcnt(0)
	v_pk_mul_f32 v[104:105], v[114:115], v[104:105] op_sel_hi:[0,1]
	v_pk_mul_f32 v[112:113], v[0:1], v[104:105]
	v_pk_mul_f32 v[104:105], v[114:115], v[122:123] op_sel_hi:[0,1]
	v_pk_mul_f32 v[114:115], v[2:3], v[104:105]
	global_store_dwordx4 v[116:117], v[112:115], off nt
	ds_read_b32 v104, v128 offset:72
	s_nop 0
	v_add_u32_e32 v112, 18, v14
	v_ashrrev_i32_e32 v113, 31, v112
	v_lshlrev_b64 v[112:113], 12, v[112:113]
	v_lshl_add_u64 v[116:117], v[10:11], 0, v[112:113]
	s_waitcnt lgkmcnt(0)
	v_pk_mul_f32 v[100:101], v[104:105], v[100:101] op_sel_hi:[0,1]
	v_pk_mul_f32 v[112:113], v[0:1], v[100:101]
	v_pk_mul_f32 v[100:101], v[104:105], v[108:109] op_sel_hi:[0,1]
	v_pk_mul_f32 v[114:115], v[2:3], v[100:101]
	global_store_dwordx4 v[116:117], v[112:115], off nt
	ds_read_b32 v100, v128 offset:76
	v_add_u32_e32 v104, 19, v14
	v_ashrrev_i32_e32 v105, 31, v104
	v_lshlrev_b64 v[104:105], 12, v[104:105]
	v_lshl_add_u64 v[104:105], v[10:11], 0, v[104:105]
	s_waitcnt lgkmcnt(0)
	v_pk_mul_f32 v[96:97], v[100:101], v[96:97] op_sel_hi:[0,1]
	v_pk_mul_f32 v[98:99], v[100:101], v[98:99] op_sel_hi:[0,1]
	v_pk_mul_f32 v[96:97], v[0:1], v[96:97]
	v_pk_mul_f32 v[98:99], v[2:3], v[98:99]
	global_store_dwordx4 v[104:105], v[96:99], off nt
	ds_read_b32 v98, v128 offset:128
	s_nop 0
	v_add_u32_e32 v96, 32, v14
	v_ashrrev_i32_e32 v97, 31, v96
	v_lshlrev_b64 v[96:97], 12, v[96:97]
	v_lshl_add_u64 v[100:101], v[10:11], 0, v[96:97]
	s_waitcnt lgkmcnt(0)
	v_pk_mul_f32 v[96:97], v[98:99], v[102:103] op_sel_hi:[0,1]
	v_pk_mul_f32 v[98:99], v[98:99], v[110:111] op_sel_hi:[0,1]
	v_pk_mul_f32 v[96:97], v[0:1], v[96:97]
	v_pk_mul_f32 v[98:99], v[2:3], v[98:99]
	global_store_dwordx4 v[100:101], v[96:99], off nt
	ds_read_b32 v98, v128 offset:132
	s_nop 0
	v_add_u32_e32 v96, 33, v14
	v_ashrrev_i32_e32 v97, 31, v96
	v_lshlrev_b64 v[96:97], 12, v[96:97]
	v_lshl_add_u64 v[100:101], v[10:11], 0, v[96:97]
	s_waitcnt lgkmcnt(0)
	v_pk_mul_f32 v[88:89], v[98:99], v[88:89] op_sel_hi:[0,1]
	v_pk_mul_f32 v[96:97], v[0:1], v[88:89]
	v_pk_mul_f32 v[88:89], v[98:99], v[106:107] op_sel_hi:[0,1]
	v_pk_mul_f32 v[98:99], v[2:3], v[88:89]
	global_store_dwordx4 v[100:101], v[96:99], off nt
	ds_read_b32 v88, v128 offset:136
	s_nop 0
	v_add_u32_e32 v96, 34, v14
	v_ashrrev_i32_e32 v97, 31, v96
	v_lshlrev_b64 v[96:97], 12, v[96:97]
	v_lshl_add_u64 v[100:101], v[10:11], 0, v[96:97]
	s_waitcnt lgkmcnt(0)
	v_pk_mul_f32 v[84:85], v[88:89], v[84:85] op_sel_hi:[0,1]
	v_pk_mul_f32 v[96:97], v[0:1], v[84:85]
	v_pk_mul_f32 v[84:85], v[88:89], v[92:93] op_sel_hi:[0,1]
	v_pk_mul_f32 v[98:99], v[2:3], v[84:85]
	global_store_dwordx4 v[100:101], v[96:99], off nt
	ds_read_b32 v84, v128 offset:140
	v_add_u32_e32 v88, 35, v14
	v_ashrrev_i32_e32 v89, 31, v88
	v_lshlrev_b64 v[88:89], 12, v[88:89]
	v_lshl_add_u64 v[88:89], v[10:11], 0, v[88:89]
	s_waitcnt lgkmcnt(0)
	v_pk_mul_f32 v[80:81], v[84:85], v[80:81] op_sel_hi:[0,1]
	v_pk_mul_f32 v[82:83], v[84:85], v[82:83] op_sel_hi:[0,1]
	v_pk_mul_f32 v[80:81], v[0:1], v[80:81]
	v_pk_mul_f32 v[82:83], v[2:3], v[82:83]
	global_store_dwordx4 v[88:89], v[80:83], off nt
	ds_read_b32 v82, v128 offset:192
	s_nop 0
	v_add_u32_e32 v80, 48, v14
	v_ashrrev_i32_e32 v81, 31, v80
	v_lshlrev_b64 v[80:81], 12, v[80:81]
	v_lshl_add_u64 v[84:85], v[10:11], 0, v[80:81]
	s_waitcnt lgkmcnt(0)
	v_pk_mul_f32 v[80:81], v[82:83], v[86:87] op_sel_hi:[0,1]
	v_pk_mul_f32 v[82:83], v[82:83], v[94:95] op_sel_hi:[0,1]
	v_pk_mul_f32 v[80:81], v[0:1], v[80:81]
	v_pk_mul_f32 v[82:83], v[2:3], v[82:83]
	global_store_dwordx4 v[84:85], v[80:83], off nt
	ds_read_b32 v82, v128 offset:196
	s_nop 0
	v_add_u32_e32 v80, 49, v14
	v_ashrrev_i32_e32 v81, 31, v80
	v_lshlrev_b64 v[80:81], 12, v[80:81]
	v_lshl_add_u64 v[84:85], v[10:11], 0, v[80:81]
	s_waitcnt lgkmcnt(0)
	v_pk_mul_f32 v[72:73], v[82:83], v[72:73] op_sel_hi:[0,1]
	v_pk_mul_f32 v[80:81], v[0:1], v[72:73]
	v_pk_mul_f32 v[72:73], v[82:83], v[90:91] op_sel_hi:[0,1]
	v_pk_mul_f32 v[82:83], v[2:3], v[72:73]
	global_store_dwordx4 v[84:85], v[80:83], off nt
	ds_read_b32 v72, v128 offset:200
	s_nop 0
	v_add_u32_e32 v80, 50, v14
	v_ashrrev_i32_e32 v81, 31, v80
	v_lshlrev_b64 v[80:81], 12, v[80:81]
	v_lshl_add_u64 v[84:85], v[10:11], 0, v[80:81]
	s_waitcnt lgkmcnt(0)
	v_pk_mul_f32 v[68:69], v[72:73], v[68:69] op_sel_hi:[0,1]
	v_pk_mul_f32 v[80:81], v[0:1], v[68:69]
	v_pk_mul_f32 v[68:69], v[72:73], v[76:77] op_sel_hi:[0,1]
	v_pk_mul_f32 v[82:83], v[2:3], v[68:69]
	global_store_dwordx4 v[84:85], v[80:83], off nt
	ds_read_b32 v68, v128 offset:204
	v_add_u32_e32 v72, 51, v14
	v_ashrrev_i32_e32 v73, 31, v72
	v_lshlrev_b64 v[72:73], 12, v[72:73]
	v_lshl_add_u64 v[72:73], v[10:11], 0, v[72:73]
	s_waitcnt lgkmcnt(0)
	v_pk_mul_f32 v[64:65], v[68:69], v[64:65] op_sel_hi:[0,1]
	v_pk_mul_f32 v[66:67], v[68:69], v[66:67] op_sel_hi:[0,1]
	v_pk_mul_f32 v[64:65], v[0:1], v[64:65]
	v_pk_mul_f32 v[66:67], v[2:3], v[66:67]
	global_store_dwordx4 v[72:73], v[64:67], off nt
	ds_read_b32 v66, v128 offset:256
	s_nop 0
	v_add_u32_e32 v64, 64, v14
	v_ashrrev_i32_e32 v65, 31, v64
	v_lshlrev_b64 v[64:65], 12, v[64:65]
	v_lshl_add_u64 v[68:69], v[10:11], 0, v[64:65]
	s_waitcnt lgkmcnt(0)
	v_pk_mul_f32 v[64:65], v[66:67], v[70:71] op_sel_hi:[0,1]
	v_pk_mul_f32 v[66:67], v[66:67], v[78:79] op_sel_hi:[0,1]
	v_pk_mul_f32 v[64:65], v[0:1], v[64:65]
	v_pk_mul_f32 v[66:67], v[2:3], v[66:67]
	global_store_dwordx4 v[68:69], v[64:67], off nt
	ds_read_b32 v66, v128 offset:260
	s_nop 0
	v_add_u32_e32 v64, 0x41, v14
	v_ashrrev_i32_e32 v65, 31, v64
	v_lshlrev_b64 v[64:65], 12, v[64:65]
	v_lshl_add_u64 v[68:69], v[10:11], 0, v[64:65]
	s_waitcnt lgkmcnt(0)
	v_pk_mul_f32 v[56:57], v[66:67], v[56:57] op_sel_hi:[0,1]
	v_pk_mul_f32 v[64:65], v[0:1], v[56:57]
	v_pk_mul_f32 v[56:57], v[66:67], v[74:75] op_sel_hi:[0,1]
	v_pk_mul_f32 v[66:67], v[2:3], v[56:57]
	global_store_dwordx4 v[68:69], v[64:67], off nt
	ds_read_b32 v56, v128 offset:264
	s_nop 0
	v_add_u32_e32 v64, 0x42, v14
	v_ashrrev_i32_e32 v65, 31, v64
	v_lshlrev_b64 v[64:65], 12, v[64:65]
	v_lshl_add_u64 v[68:69], v[10:11], 0, v[64:65]
	s_waitcnt lgkmcnt(0)
	v_pk_mul_f32 v[52:53], v[56:57], v[52:53] op_sel_hi:[0,1]
	v_pk_mul_f32 v[64:65], v[0:1], v[52:53]
	v_pk_mul_f32 v[52:53], v[56:57], v[60:61] op_sel_hi:[0,1]
	v_pk_mul_f32 v[66:67], v[2:3], v[52:53]
	global_store_dwordx4 v[68:69], v[64:67], off nt
	ds_read_b32 v52, v128 offset:268
	v_add_u32_e32 v56, 0x43, v14
	v_ashrrev_i32_e32 v57, 31, v56
	v_lshlrev_b64 v[56:57], 12, v[56:57]
	v_lshl_add_u64 v[56:57], v[10:11], 0, v[56:57]
	s_waitcnt lgkmcnt(0)
	v_pk_mul_f32 v[48:49], v[52:53], v[48:49] op_sel_hi:[0,1]
	v_pk_mul_f32 v[50:51], v[52:53], v[50:51] op_sel_hi:[0,1]
	v_pk_mul_f32 v[48:49], v[0:1], v[48:49]
	v_pk_mul_f32 v[50:51], v[2:3], v[50:51]
	global_store_dwordx4 v[56:57], v[48:51], off nt
	ds_read_b32 v50, v128 offset:320
	s_nop 0
	v_add_u32_e32 v48, 0x50, v14
	v_ashrrev_i32_e32 v49, 31, v48
	v_lshlrev_b64 v[48:49], 12, v[48:49]
	v_lshl_add_u64 v[52:53], v[10:11], 0, v[48:49]
	s_waitcnt lgkmcnt(0)
	v_pk_mul_f32 v[48:49], v[50:51], v[54:55] op_sel_hi:[0,1]
	v_pk_mul_f32 v[50:51], v[50:51], v[62:63] op_sel_hi:[0,1]
	v_pk_mul_f32 v[48:49], v[0:1], v[48:49]
	v_pk_mul_f32 v[50:51], v[2:3], v[50:51]
	global_store_dwordx4 v[52:53], v[48:51], off nt
	ds_read_b32 v50, v128 offset:324
	s_nop 0
	v_add_u32_e32 v48, 0x51, v14
	v_ashrrev_i32_e32 v49, 31, v48
	v_lshlrev_b64 v[48:49], 12, v[48:49]
	v_lshl_add_u64 v[52:53], v[10:11], 0, v[48:49]
	s_waitcnt lgkmcnt(0)
	v_pk_mul_f32 v[40:41], v[50:51], v[40:41] op_sel_hi:[0,1]
	v_pk_mul_f32 v[48:49], v[0:1], v[40:41]
	v_pk_mul_f32 v[40:41], v[50:51], v[58:59] op_sel_hi:[0,1]
	v_pk_mul_f32 v[50:51], v[2:3], v[40:41]
	global_store_dwordx4 v[52:53], v[48:51], off nt
	ds_read_b32 v40, v128 offset:328
	s_nop 0
	v_add_u32_e32 v48, 0x52, v14
	v_ashrrev_i32_e32 v49, 31, v48
	v_lshlrev_b64 v[48:49], 12, v[48:49]
	v_lshl_add_u64 v[52:53], v[10:11], 0, v[48:49]
	s_waitcnt lgkmcnt(0)
	v_pk_mul_f32 v[36:37], v[40:41], v[36:37] op_sel_hi:[0,1]
	v_pk_mul_f32 v[48:49], v[0:1], v[36:37]
	v_pk_mul_f32 v[36:37], v[40:41], v[44:45] op_sel_hi:[0,1]
	v_pk_mul_f32 v[50:51], v[2:3], v[36:37]
	global_store_dwordx4 v[52:53], v[48:51], off nt
	ds_read_b32 v36, v128 offset:332
	v_add_u32_e32 v40, 0x53, v14
	v_ashrrev_i32_e32 v41, 31, v40
	v_lshlrev_b64 v[40:41], 12, v[40:41]
	v_lshl_add_u64 v[40:41], v[10:11], 0, v[40:41]
	s_waitcnt lgkmcnt(0)
	v_pk_mul_f32 v[32:33], v[36:37], v[32:33] op_sel_hi:[0,1]
	v_pk_mul_f32 v[34:35], v[36:37], v[34:35] op_sel_hi:[0,1]
	v_pk_mul_f32 v[32:33], v[0:1], v[32:33]
	v_pk_mul_f32 v[34:35], v[2:3], v[34:35]
	global_store_dwordx4 v[40:41], v[32:35], off nt
	ds_read_b32 v34, v128 offset:384
	s_nop 0
	v_add_u32_e32 v32, 0x60, v14
	v_ashrrev_i32_e32 v33, 31, v32
	v_lshlrev_b64 v[32:33], 12, v[32:33]
	v_lshl_add_u64 v[36:37], v[10:11], 0, v[32:33]
	s_waitcnt lgkmcnt(0)
	v_pk_mul_f32 v[32:33], v[34:35], v[38:39] op_sel_hi:[0,1]
	v_pk_mul_f32 v[34:35], v[34:35], v[142:143] op_sel_hi:[0,1]
	v_pk_mul_f32 v[32:33], v[0:1], v[32:33]
	v_pk_mul_f32 v[34:35], v[2:3], v[34:35]
	global_store_dwordx4 v[36:37], v[32:35], off nt
	ds_read_b32 v34, v128 offset:388
	s_nop 0
	v_add_u32_e32 v32, 0x61, v14
	v_ashrrev_i32_e32 v33, 31, v32
	v_lshlrev_b64 v[32:33], 12, v[32:33]
	v_lshl_add_u64 v[36:37], v[10:11], 0, v[32:33]
	s_waitcnt lgkmcnt(0)
	v_pk_mul_f32 v[28:29], v[34:35], v[28:29] op_sel_hi:[0,1]
	v_pk_mul_f32 v[32:33], v[0:1], v[28:29]
	v_pk_mul_f32 v[28:29], v[34:35], v[46:47] op_sel_hi:[0,1]
	v_pk_mul_f32 v[34:35], v[2:3], v[28:29]
	global_store_dwordx4 v[36:37], v[32:35], off nt
	ds_read_b32 v28, v128 offset:392
	s_nop 0
	v_add_u32_e32 v32, 0x62, v14
	v_ashrrev_i32_e32 v33, 31, v32
	v_lshlrev_b64 v[32:33], 12, v[32:33]
	v_lshl_add_u64 v[36:37], v[10:11], 0, v[32:33]
	s_waitcnt lgkmcnt(0)
	v_pk_mul_f32 v[24:25], v[28:29], v[24:25] op_sel_hi:[0,1]
	v_pk_mul_f32 v[32:33], v[0:1], v[24:25]
	v_pk_mul_f32 v[24:25], v[28:29], v[42:43] op_sel_hi:[0,1]
	v_pk_mul_f32 v[34:35], v[2:3], v[24:25]
	global_store_dwordx4 v[36:37], v[32:35], off nt
	ds_read_b32 v24, v128 offset:396
	v_add_u32_e32 v28, 0x63, v14
	v_ashrrev_i32_e32 v29, 31, v28
	v_lshlrev_b64 v[28:29], 12, v[28:29]
	v_lshl_add_u64 v[32:33], v[10:11], 0, v[28:29]
	s_waitcnt lgkmcnt(0)
	v_pk_mul_f32 v[20:21], v[24:25], v[20:21] op_sel_hi:[0,1]
	v_pk_mul_f32 v[28:29], v[0:1], v[20:21]
	v_pk_mul_f32 v[20:21], v[24:25], v[30:31] op_sel_hi:[0,1]
	v_pk_mul_f32 v[30:31], v[2:3], v[20:21]
	global_store_dwordx4 v[32:33], v[28:31], off nt
	ds_read_b32 v20, v128 offset:448
	v_add_u32_e32 v24, 0x70, v14
	v_ashrrev_i32_e32 v25, 31, v24
	v_lshlrev_b64 v[24:25], 12, v[24:25]
	v_lshl_add_u64 v[28:29], v[10:11], 0, v[24:25]
	s_waitcnt lgkmcnt(0)
	v_pk_mul_f32 v[16:17], v[20:21], v[16:17] op_sel_hi:[0,1]
	v_pk_mul_f32 v[24:25], v[0:1], v[16:17]
	v_pk_mul_f32 v[16:17], v[20:21], v[26:27] op_sel_hi:[0,1]
	v_pk_mul_f32 v[26:27], v[2:3], v[16:17]
	global_store_dwordx4 v[28:29], v[24:27], off nt
	ds_read_b32 v16, v128 offset:452
	v_add_u32_e32 v20, 0x71, v14
	v_ashrrev_i32_e32 v21, 31, v20
	v_lshlrev_b64 v[20:21], 12, v[20:21]
	v_lshl_add_u64 v[24:25], v[10:11], 0, v[20:21]
	s_waitcnt lgkmcnt(0)
	v_pk_mul_f32 v[12:13], v[16:17], v[12:13] op_sel_hi:[0,1]
	v_pk_mul_f32 v[20:21], v[0:1], v[12:13]
	v_pk_mul_f32 v[12:13], v[16:17], v[22:23] op_sel_hi:[0,1]
	v_pk_mul_f32 v[22:23], v[2:3], v[12:13]
	global_store_dwordx4 v[24:25], v[20:23], off nt
	ds_read_b32 v12, v128 offset:456
	v_add_u32_e32 v16, 0x72, v14
	v_ashrrev_i32_e32 v17, 31, v16
	v_lshlrev_b64 v[16:17], 12, v[16:17]
	v_lshl_add_u64 v[20:21], v[10:11], 0, v[16:17]
	s_waitcnt lgkmcnt(0)
	v_pk_mul_f32 v[8:9], v[12:13], v[8:9] op_sel_hi:[0,1]
	v_pk_mul_f32 v[16:17], v[0:1], v[8:9]
	v_pk_mul_f32 v[8:9], v[12:13], v[18:19] op_sel_hi:[0,1]
	v_pk_mul_f32 v[18:19], v[2:3], v[8:9]
	global_store_dwordx4 v[20:21], v[16:19], off nt
	ds_read_b32 v8, v128 offset:460
	v_add_u32_e32 v12, 0x73, v14
	v_ashrrev_i32_e32 v13, 31, v12
	v_readlane_b32 s0, v253, 0
	v_lshlrev_b64 v[12:13], 12, v[12:13]
	s_waitcnt lgkmcnt(0)
	v_pk_mul_f32 v[4:5], v[8:9], v[4:5] op_sel_hi:[0,1]
	v_pk_mul_f32 v[0:1], v[0:1], v[4:5]
	v_pk_mul_f32 v[4:5], v[8:9], v[6:7] op_sel_hi:[0,1]
	s_add_i32 s43, s43, s0
	s_add_i32 s42, s42, s50
	v_lshl_add_u64 v[10:11], v[10:11], 0, v[12:13]
	v_pk_mul_f32 v[2:3], v[2:3], v[4:5]
	s_cmpk_gt_i32 s43, 0xff
	v_readlane_b32 s1, v253, 1
	global_store_dwordx4 v[10:11], v[0:3], off nt
	s_cbranch_scc1 .LBB0_1783
